# adds: every GEMM K-loop gets a peeled first iteration (units after the first) whose first two vmcnt waits count past the previous unit's 16 output stores, so MFMAs start while the stores drain
# speedup vs baseline: 1.0014x; 1.0014x over previous
;     __host__ __device__ bool next(int i, Unit& u) const { const bool ok = StaticOrder::next(i, u); u.pm = 0; u.pn = 0; return ok; }
;     __host__ __device__ bool next(int i, Unit& u) const {
;         const long L = (long)i * G + c; if (L >= nwg) return false;
;         int wgid = (int)L; { const int q = nwg / NXCD, r = nwg % NXCD, xcd = wgid % NXCD, off = wgid / NXCD; wgid = (xcd < r ? xcd * (q + 1) : r * (q + 1) + (xcd - r) * q) + off; }
;         const int nig = WGM * nN, gid = wgid / nig, fm = gid * WGM, gsz = (nM - fm) < WGM ? (nM - fm) : WGM;
;         u.pm = fm + ((wgid % nig) % gsz); u.pn = (wgid % nig) / gsz; return true;
; template <class Epi, class Sched, bool ALIGN_EPI = false, bool SP2 = false>
; __device__ __forceinline__ void gemm_phase(PG8_LAS unsigned char* lds, const Gemm g, const Sched& S, const Epi& E, const int wave_in) {
;     ...
;     Unit cur, nxt; int ui = 0;
;     if (!S.next(0, cur)) return;
.LBB0_145:
	s_cmp_gt_i32 s52, 2
	s_cselect_b64 s[0:1], -1, 0
	s_cmp_lt_i32 s53, 3
	s_cselect_b64 s[2:3], -1, 0
	s_or_b64 s[0:1], s[0:1], s[2:3]
	v_writelane_b32 v254, s52, 60
	s_and_b64 vcc, exec, s[0:1]
	s_nop 0
	v_writelane_b32 v254, s53, 61
	s_cbranch_vccnz .LBB0_246
	s_mov_b32 s99, 0
	s_cmpk_lt_i32 s73, 0x1680
	s_cselect_b64 s[0:1], -1, 0
	s_cmpk_gt_i32 s73, 0x167f
	v_mbcnt_lo_u32_b32 v8, -1, 0
	v_mbcnt_hi_u32_b32 v8, -1, v8
	s_cbranch_scc1 .LBB0_149
	s_ashr_i32 s2, s73, 31
	s_lshr_b32 s2, s2, 29
	s_add_i32 s2, s73, s2
	s_ashr_i32 s3, s2, 3
	s_and_b32 s2, s2, -8
	s_sub_i32 s2, s73, s2
	s_cmp_lt_i32 s2, 0
	s_movk_i32 s4, 0x2d1
	s_cselect_b32 s4, s4, 0x2d0
	s_mul_i32 s2, s4, s2
	s_add_i32 s2, s2, s3
	s_mul_hi_i32 s3, s2, 0x66666667
	s_lshr_b32 s4, s3, 31
	s_ashr_i32 s3, s3, 6
	s_add_i32 s3, s3, s4
	s_lshl_b32 s4, s3, 2
	s_mulk_i32 s3, 0xa0
	s_sub_i32 s2, s2, s3
	s_sext_i32_i16 s3, s2
	s_bfe_u32 s3, s3, 0x2001d
	s_add_i32 s3, s2, s3
	s_sext_i32_i16 s5, s3
	s_and_b32 s3, s3, 0xfffc
	s_sub_i32 s2, s2, s3
	s_sext_i32_i16 s2, s2
	s_add_i32 s20, s4, s2
	s_ashr_i32 s4, s5, 2
	s_andn2_b64 vcc, exec, s[0:1]
	s_cbranch_vccz .LBB0_150

;     __host__ __device__ bool next(int i, Unit& u) const { const bool ok = StaticOrder::next(i, u); u.pm = 0; u.pn = 0; return ok; }
; #define PG8_STAGE(bufoff, gbase, voff) do { _Pragma("unroll") for (int _i = 0; _i < 2; ++_i) \
;         __builtin_amdgcn_global_load_lds((const unsigned*)((const char*)(gbase) + (voff)[_i]), (PG8_LAS unsigned*)(lds + (bufoff) + ldsw + _i * 8192), 16, 0, 0); } while (0)
; #define PG8_LDA(dst, b, h) do { _Pragma("unroll") for (int m = 0; m < 4; ++m) _Pragma("unroll") for (int k = 0; k < 2; ++k) dst[m][k] = *(const PG8_LAS bf16x8*)(lds + PG8_SA(b, h) + aoff + m * 2048 + k * 1024); } while (0)
; #define PG8_LDB(dst, b, h) do { _Pragma("unroll") for (int n = 0; n < 2; ++n) _Pragma("unroll") for (int k = 0; k < 2; ++k) dst[n][k] = *(const PG8_LAS bf16x8*)(lds + PG8_SB(b, h) + boff + n * 2048 + k * 1024); } while (0)
; #define PG8_WAIT_V(n) asm volatile("s_waitcnt vmcnt(" #n ")" ::: "memory")
; template <class Epi, class Sched, bool ALIGN_EPI = false, bool SP2 = false>
; __device__ __forceinline__ void gemm_phase(PG8_LAS unsigned char* lds, const Gemm g, const Sched& S, const Epi& E, const int wave_in) {
;     ...
;     f32x4 acc[2][2][4][2];
; #pragma unroll
;     for (int a = 0; a < 2; ++a)
; #pragma unroll
;         for (int b = 0; b < 2; ++b)
; #pragma unroll
;             for (int m = 0; m < 4; ++m)
; #pragma unroll
;                 for (int n = 0; n < 2; ++n) acc[a][b][m][n] = (f32x4){0.f, 0.f, 0.f, 0.f};
;     ...
;     for (;;) {
;         const bool has_next = S.next(ui + 1, nxt);
;         const char* nA = has_next ? (const char*)g.A + (size_t)nxt.pm * tstepA : cA; const char* nB = has_next ? (const char*)g.Bt + (size_t)nxt.pn * tstepB : cB;
;         for (int t = 0; t < nt; t += 2) {
;             const bool last = (t == nt - 2);
;             const char* a1 = cA + (size_t)(t + 1) * kstep;
;             const char* a2 = last ? nA : cA + (size_t)(t + 2) * kstep; const char* b2 = last ? nB : cB + (size_t)(t + 2) * kstep;
;             const char* a3 = a2 + kstep; const char* b3 = b2 + kstep;
;             if (last && has_next) S.a_ready(nxt);
;             if constexpr (SP2) {
;             PG8_LDB(B0, 0, 0); PG8_LDB(B1, 0, 1); PG8_SCHED; PG8_LDA(At, 0, 0); PG8_STAGE(PG8_SA(1, 1), a1 + hstepA, voffA);
;             PG8_WAIT_V(8); PG8_WAIT_L(0); PG8_BAR; PG8_MMA(0, 0, At, B0); PG8_MMA(0, 1, At, B1); PG8_BAR; PG8_SCHED;
.LBB0_157:
	s_ashr_i32 s15, s14, 31
	s_lshl_b64 s[16:17], s[14:15], 20
	s_add_u32 s16, s28, s16
	s_addc_u32 s17, s29, s17
	s_and_b64 s[18:19], s[2:3], exec
	s_cselect_b32 s5, s17, s23
	s_cselect_b32 s15, s16, s22
	s_ashr_i32 s13, s12, 31
	s_lshl_b64 s[18:19], s[12:13], 20
	s_add_u32 s18, s30, s18
	s_addc_u32 s19, s31, s19
	s_and_b64 s[26:27], s[2:3], exec
	s_cselect_b32 s13, s19, s25
	s_cselect_b32 s46, s18, s24
	s_add_u32 s22, s22, 0x80080
	s_addc_u32 s23, s23, 0
	s_add_u32 s47, s24, 0x100
	v_mov_b32_e32 v0, 0
	s_addc_u32 s48, s25, 0
	s_mov_b32 s49, -2
	v_mov_b32_e32 v1, v0
	v_mov_b32_e32 v2, v0
	v_mov_b32_e32 v3, v0
	v_mov_b32_e32 v4, v0
	v_mov_b32_e32 v5, v0
	v_mov_b32_e32 v6, v0
	v_mov_b32_e32 v7, v0
	v_mov_b32_e32 v16, v0
	v_mov_b32_e32 v17, v0
	v_mov_b32_e32 v18, v0
	v_mov_b32_e32 v19, v0
	v_mov_b32_e32 v20, v0
	v_mov_b32_e32 v21, v0
	v_mov_b32_e32 v22, v0
	v_mov_b32_e32 v23, v0
	v_mov_b32_e32 v32, v0
	v_mov_b32_e32 v33, v0
	v_mov_b32_e32 v34, v0
	v_mov_b32_e32 v35, v0
	v_mov_b32_e32 v36, v0
	v_mov_b32_e32 v37, v0
	v_mov_b32_e32 v38, v0
	v_mov_b32_e32 v39, v0
	v_mov_b32_e32 v48, v0
	v_mov_b32_e32 v49, v0
	v_mov_b32_e32 v50, v0
	v_mov_b32_e32 v51, v0
	v_mov_b32_e32 v52, v0
	v_mov_b32_e32 v53, v0
	v_mov_b32_e32 v54, v0
	v_mov_b32_e32 v55, v0
	v_mov_b32_e32 v8, v0
	v_mov_b32_e32 v9, v0
	v_mov_b32_e32 v10, v0
	v_mov_b32_e32 v11, v0
	v_mov_b32_e32 v12, v0
	v_mov_b32_e32 v13, v0
	v_mov_b32_e32 v14, v0
	v_mov_b32_e32 v15, v0
	v_mov_b32_e32 v24, v0
	v_mov_b32_e32 v25, v0
	v_mov_b32_e32 v26, v0
	v_mov_b32_e32 v27, v0
	v_mov_b32_e32 v28, v0
	v_mov_b32_e32 v29, v0
	v_mov_b32_e32 v30, v0
	v_mov_b32_e32 v31, v0
	v_mov_b32_e32 v40, v0
	v_mov_b32_e32 v41, v0
	v_mov_b32_e32 v42, v0
	v_mov_b32_e32 v43, v0
	v_mov_b32_e32 v44, v0
	v_mov_b32_e32 v45, v0
	v_mov_b32_e32 v46, v0
	v_mov_b32_e32 v47, v0
	v_mov_b32_e32 v56, v0
	v_mov_b32_e32 v57, v0
	v_mov_b32_e32 v58, v0
	v_mov_b32_e32 v59, v0
	v_mov_b32_e32 v60, v0
	v_mov_b32_e32 v61, v0
	v_mov_b32_e32 v62, v0
	v_mov_b32_e32 v63, v0
	v_mov_b32_e32 v64, v0
	v_mov_b32_e32 v65, v0
	v_mov_b32_e32 v66, v0
	v_mov_b32_e32 v67, v0
	v_mov_b32_e32 v68, v0
	v_mov_b32_e32 v69, v0
	v_mov_b32_e32 v70, v0
	v_mov_b32_e32 v71, v0
	v_mov_b32_e32 v80, v0
	v_mov_b32_e32 v81, v0
	v_mov_b32_e32 v82, v0
	v_mov_b32_e32 v83, v0
	v_mov_b32_e32 v84, v0
	v_mov_b32_e32 v85, v0
	v_mov_b32_e32 v86, v0
	v_mov_b32_e32 v87, v0
	v_mov_b32_e32 v96, v0
	v_mov_b32_e32 v97, v0
	v_mov_b32_e32 v98, v0
	v_mov_b32_e32 v99, v0
	v_mov_b32_e32 v100, v0
	v_mov_b32_e32 v101, v0
	v_mov_b32_e32 v102, v0
	v_mov_b32_e32 v103, v0
	v_mov_b32_e32 v112, v0
	v_mov_b32_e32 v113, v0
	v_mov_b32_e32 v114, v0
	v_mov_b32_e32 v115, v0
	v_mov_b32_e32 v116, v0
	v_mov_b32_e32 v117, v0
	v_mov_b32_e32 v118, v0
	v_mov_b32_e32 v119, v0
	v_mov_b32_e32 v72, v0
	v_mov_b32_e32 v73, v0
	v_mov_b32_e32 v74, v0
	v_mov_b32_e32 v75, v0
	v_mov_b32_e32 v76, v0
	v_mov_b32_e32 v77, v0
	v_mov_b32_e32 v78, v0
	v_mov_b32_e32 v79, v0
	v_mov_b32_e32 v88, v0
	v_mov_b32_e32 v89, v0
	v_mov_b32_e32 v90, v0
	v_mov_b32_e32 v91, v0
	v_mov_b32_e32 v92, v0
	v_mov_b32_e32 v93, v0
	v_mov_b32_e32 v94, v0
	v_mov_b32_e32 v95, v0
	v_mov_b32_e32 v104, v0
	v_mov_b32_e32 v105, v0
	v_mov_b32_e32 v106, v0
	v_mov_b32_e32 v107, v0
	v_mov_b32_e32 v108, v0
	v_mov_b32_e32 v109, v0
	v_mov_b32_e32 v110, v0
	v_mov_b32_e32 v111, v0
	v_mov_b32_e32 v120, v0
	v_mov_b32_e32 v121, v0
	v_mov_b32_e32 v122, v0
	v_mov_b32_e32 v123, v0
	v_mov_b32_e32 v124, v0
	v_mov_b32_e32 v125, v0
	v_mov_b32_e32 v126, v0
	v_mov_b32_e32 v127, v0
	s_cmp_lg_u32 s99, 0
	s_cbranch_scc0 .LBB0_158
	ds_read_b128 v[144:147], v151
	ds_read_b128 v[154:157], v151 offset:1024
	ds_read_b128 v[158:161], v151 offset:2048
	ds_read_b128 v[162:165], v151 offset:3072
	ds_read_b128 v[166:169], v152
	ds_read_b128 v[170:173], v152 offset:1024
	ds_read_b128 v[174:177], v152 offset:2048
	ds_read_b128 v[178:181], v152 offset:3072
	s_add_u32 s24, s22, 0xfff80080
	s_addc_u32 s25, s23, -1
	s_cmp_eq_u32 s49, 28
	s_cselect_b32 s27, s5, s25
	s_cselect_b32 s26, s15, s24
	s_cselect_b32 s25, s13, s48
	s_cselect_b32 s24, s46, s47
	v_lshl_add_u64 v[214:215], s[22:23], 0, v[136:137]
	s_add_i32 m0, s21, 0xc000
	ds_read_b128 v[182:185], v153
	ds_read_b128 v[186:189], v153 offset:1024
	ds_read_b128 v[190:193], v153 offset:2048
	ds_read_b128 v[194:197], v153 offset:3072
	ds_read_b128 v[198:201], v153 offset:4096
	ds_read_b128 v[202:205], v153 offset:5120
	ds_read_b128 v[206:209], v153 offset:6144
	ds_read_b128 v[210:213], v153 offset:7168
	global_load_lds_dwordx4 v[214:215], off
	v_lshl_add_u64 v[214:215], s[22:23], 0, v[138:139]
	s_add_i32 m0, s21, 0xe000
	s_nop 0
	global_load_lds_dwordx4 v[214:215], off
	s_waitcnt vmcnt(24)
	s_waitcnt lgkmcnt(0)
	s_barrier
; #define PG8_STAGE(bufoff, gbase, voff) do { _Pragma("unroll") for (int _i = 0; _i < 2; ++_i) \
;         __builtin_amdgcn_global_load_lds((const unsigned*)((const char*)(gbase) + (voff)[_i]), (PG8_LAS unsigned*)(lds + (bufoff) + ldsw + _i * 8192), 16, 0, 0); } while (0)
; #define PG8_LDA(dst, b, h) do { _Pragma("unroll") for (int m = 0; m < 4; ++m) _Pragma("unroll") for (int k = 0; k < 2; ++k) dst[m][k] = *(const PG8_LAS bf16x8*)(lds + PG8_SA(b, h) + aoff + m * 2048 + k * 1024); } while (0)
; #define PG8_MMA(ai, bj, At, Bt) do { __builtin_amdgcn_s_setprio(1); _Pragma("unroll") for (int m = 0; m < 4; ++m) _Pragma("unroll") for (int n = 0; n < 2; ++n) _Pragma("unroll") for (int k = 0; k < 2; ++k) \
;         acc[ai][bj][m][n] = __builtin_amdgcn_mfma_f32_16x16x32_bf16(Bt[n][k], At[m][k], acc[ai][bj][m][n], 0, 0, 0); __builtin_amdgcn_s_setprio(0); } while (0)
; #define PG8_WAIT_V(n) asm volatile("s_waitcnt vmcnt(" #n ")" ::: "memory")
; #define PG8_WAIT_L(n) asm volatile("s_waitcnt lgkmcnt(" #n ")" ::: "memory")
; #define PG8_BAR __builtin_amdgcn_s_barrier()
; #define PG8_SCHED __builtin_amdgcn_sched_barrier(0)
; template <class Epi, class Sched, bool ALIGN_EPI = false, bool SP2 = false>
; __device__ __forceinline__ void gemm_phase(PG8_LAS unsigned char* lds, const Gemm g, const Sched& S, const Epi& E, const int wave_in) {
;     ...
;             PG8_WAIT_V(8); PG8_WAIT_L(0); PG8_BAR; PG8_MMA(0, 0, At, B0); PG8_MMA(0, 1, At, B1); PG8_BAR; PG8_SCHED;
;             PG8_LDA(At, 0, 1); PG8_STAGE(PG8_SB(0, 0), b2, voffB); PG8_STAGE(PG8_SB(0, 1), b2 + hstepB, voffB); PG8_STAGE(PG8_SA(0, 0), a2, voffA);
;             PG8_WAIT_V(8); PG8_WAIT_L(0); PG8_BAR; PG8_MMA(1, 0, At, B0); PG8_MMA(1, 1, At, B1); PG8_BAR; PG8_SCHED;
	s_setprio 1
	s_waitcnt lgkmcnt(0)
	v_mfma_f32_16x16x32_bf16 v[124:127], v[144:147], v[182:185], v[124:127]
	v_mfma_f32_16x16x32_bf16 v[120:123], v[158:161], v[182:185], v[120:123]
	v_mfma_f32_16x16x32_bf16 v[108:111], v[144:147], v[190:193], v[108:111]
	v_mfma_f32_16x16x32_bf16 v[104:107], v[158:161], v[190:193], v[104:107]
	v_mfma_f32_16x16x32_bf16 v[92:95], v[144:147], v[198:201], v[92:95]
	v_mfma_f32_16x16x32_bf16 v[88:91], v[158:161], v[198:201], v[88:91]
	v_mfma_f32_16x16x32_bf16 v[76:79], v[144:147], v[206:209], v[76:79]
	v_mfma_f32_16x16x32_bf16 v[72:75], v[158:161], v[206:209], v[72:75]
	v_mfma_f32_16x16x32_bf16 v[124:127], v[154:157], v[186:189], v[124:127]
	v_mfma_f32_16x16x32_bf16 v[120:123], v[162:165], v[186:189], v[120:123]
	v_mfma_f32_16x16x32_bf16 v[108:111], v[154:157], v[194:197], v[108:111]
	v_mfma_f32_16x16x32_bf16 v[104:107], v[162:165], v[194:197], v[104:107]
	v_mfma_f32_16x16x32_bf16 v[92:95], v[154:157], v[202:205], v[92:95]
	v_mfma_f32_16x16x32_bf16 v[88:91], v[162:165], v[202:205], v[88:91]
	v_mfma_f32_16x16x32_bf16 v[76:79], v[154:157], v[210:213], v[76:79]
	v_mfma_f32_16x16x32_bf16 v[72:75], v[162:165], v[210:213], v[72:75]
	s_setprio 0
	s_setprio 1
	v_mfma_f32_16x16x32_bf16 v[116:119], v[166:169], v[182:185], v[116:119]
	v_mfma_f32_16x16x32_bf16 v[112:115], v[174:177], v[182:185], v[112:115]
	v_mfma_f32_16x16x32_bf16 v[100:103], v[166:169], v[190:193], v[100:103]
	v_mfma_f32_16x16x32_bf16 v[96:99], v[174:177], v[190:193], v[96:99]
	v_mfma_f32_16x16x32_bf16 v[84:87], v[166:169], v[198:201], v[84:87]
	v_mfma_f32_16x16x32_bf16 v[80:83], v[174:177], v[198:201], v[80:83]
	v_mfma_f32_16x16x32_bf16 v[68:71], v[166:169], v[206:209], v[68:71]
	v_mfma_f32_16x16x32_bf16 v[64:67], v[174:177], v[206:209], v[64:67]
	v_mfma_f32_16x16x32_bf16 v[116:119], v[170:173], v[186:189], v[116:119]
	v_mfma_f32_16x16x32_bf16 v[112:115], v[178:181], v[186:189], v[112:115]
	v_mfma_f32_16x16x32_bf16 v[100:103], v[170:173], v[194:197], v[100:103]
	v_mfma_f32_16x16x32_bf16 v[96:99], v[178:181], v[194:197], v[96:99]
	v_mfma_f32_16x16x32_bf16 v[84:87], v[170:173], v[202:205], v[84:87]
	v_mfma_f32_16x16x32_bf16 v[80:83], v[178:181], v[202:205], v[80:83]
	v_mfma_f32_16x16x32_bf16 v[68:71], v[170:173], v[210:213], v[68:71]
	v_mfma_f32_16x16x32_bf16 v[64:67], v[178:181], v[210:213], v[64:67]
	s_setprio 0
	s_barrier
	s_add_i32 s50, s43, s34
	v_lshl_add_u64 v[214:215], s[24:25], 0, v[130:131]
	s_mov_b32 m0, s50
	ds_read_b128 v[182:185], v153 offset:16384
	ds_read_b128 v[186:189], v153 offset:17408
	ds_read_b128 v[190:193], v153 offset:18432
	ds_read_b128 v[194:197], v153 offset:19456
	ds_read_b128 v[198:201], v153 offset:20480
	ds_read_b128 v[202:205], v153 offset:21504
	ds_read_b128 v[206:209], v153 offset:22528
	ds_read_b128 v[210:213], v153 offset:23552
	global_load_lds_dwordx4 v[214:215], off
	s_add_i32 m0, s50, 0x2000
	s_add_u32 s50, s24, 0x80000
	v_lshl_add_u64 v[216:217], s[24:25], 0, v[134:135]
	s_addc_u32 s51, s25, 0
	s_add_i32 s52, s44, s34
	global_load_lds_dwordx4 v[216:217], off
	v_lshl_add_u64 v[218:219], s[50:51], 0, v[130:131]
	s_mov_b32 m0, s52
	v_lshl_add_u64 v[220:221], s[26:27], 0, v[132:133]
	global_load_lds_dwordx4 v[218:219], off
	v_lshl_add_u64 v[218:219], s[50:51], 0, v[134:135]
	s_add_i32 m0, s52, 0x2000
	s_nop 0
	global_load_lds_dwordx4 v[218:219], off
	v_lshl_add_u64 v[218:219], s[26:27], 0, v[128:129]
	s_mov_b32 m0, s21
	s_nop 0
	global_load_lds_dwordx4 v[218:219], off
	s_mov_b32 m0, s35
	s_nop 0
	global_load_lds_dwordx4 v[220:221], off
	s_waitcnt vmcnt(24)
	s_waitcnt lgkmcnt(0)
	s_barrier
	s_setprio 1
	s_waitcnt lgkmcnt(0)
	v_mfma_f32_16x16x32_bf16 v[60:63], v[144:147], v[182:185], v[60:63]
	v_mfma_f32_16x16x32_bf16 v[56:59], v[158:161], v[182:185], v[56:59]
	v_mfma_f32_16x16x32_bf16 v[44:47], v[144:147], v[190:193], v[44:47]
	v_mfma_f32_16x16x32_bf16 v[40:43], v[158:161], v[190:193], v[40:43]
	v_mfma_f32_16x16x32_bf16 v[28:31], v[144:147], v[198:201], v[28:31]
	v_mfma_f32_16x16x32_bf16 v[24:27], v[158:161], v[198:201], v[24:27]
	v_mfma_f32_16x16x32_bf16 v[12:15], v[144:147], v[206:209], v[12:15]
	v_mfma_f32_16x16x32_bf16 v[8:11], v[158:161], v[206:209], v[8:11]
	v_mfma_f32_16x16x32_bf16 v[60:63], v[154:157], v[186:189], v[60:63]
	v_mfma_f32_16x16x32_bf16 v[56:59], v[162:165], v[186:189], v[56:59]
	v_mfma_f32_16x16x32_bf16 v[44:47], v[154:157], v[194:197], v[44:47]
	v_mfma_f32_16x16x32_bf16 v[40:43], v[162:165], v[194:197], v[40:43]
	v_mfma_f32_16x16x32_bf16 v[28:31], v[154:157], v[202:205], v[28:31]
	v_mfma_f32_16x16x32_bf16 v[24:27], v[162:165], v[202:205], v[24:27]
	v_mfma_f32_16x16x32_bf16 v[12:15], v[154:157], v[210:213], v[12:15]
	v_mfma_f32_16x16x32_bf16 v[8:11], v[162:165], v[210:213], v[8:11]
	s_setprio 0
	s_setprio 1
	v_mfma_f32_16x16x32_bf16 v[52:55], v[166:169], v[182:185], v[52:55]
	v_mfma_f32_16x16x32_bf16 v[48:51], v[174:177], v[182:185], v[48:51]
	v_mfma_f32_16x16x32_bf16 v[36:39], v[166:169], v[190:193], v[36:39]
	v_mfma_f32_16x16x32_bf16 v[32:35], v[174:177], v[190:193], v[32:35]
	v_mfma_f32_16x16x32_bf16 v[20:23], v[166:169], v[198:201], v[20:23]
	v_mfma_f32_16x16x32_bf16 v[16:19], v[174:177], v[198:201], v[16:19]
	v_mfma_f32_16x16x32_bf16 v[4:7], v[166:169], v[206:209], v[4:7]
	v_mfma_f32_16x16x32_bf16 v[0:3], v[174:177], v[206:209], v[0:3]
	v_mfma_f32_16x16x32_bf16 v[52:55], v[170:173], v[186:189], v[52:55]
	v_mfma_f32_16x16x32_bf16 v[48:51], v[178:181], v[186:189], v[48:51]
	v_mfma_f32_16x16x32_bf16 v[36:39], v[170:173], v[194:197], v[36:39]
	v_mfma_f32_16x16x32_bf16 v[32:35], v[178:181], v[194:197], v[32:35]
	v_mfma_f32_16x16x32_bf16 v[20:23], v[170:173], v[202:205], v[20:23]
	v_mfma_f32_16x16x32_bf16 v[16:19], v[178:181], v[202:205], v[16:19]
	v_mfma_f32_16x16x32_bf16 v[4:7], v[170:173], v[210:213], v[4:7]
	v_mfma_f32_16x16x32_bf16 v[0:3], v[178:181], v[210:213], v[0:3]
	s_setprio 0
	s_barrier
; #define PG8_STAGE(bufoff, gbase, voff) do { _Pragma("unroll") for (int _i = 0; _i < 2; ++_i) \
;         __builtin_amdgcn_global_load_lds((const unsigned*)((const char*)(gbase) + (voff)[_i]), (PG8_LAS unsigned*)(lds + (bufoff) + ldsw + _i * 8192), 16, 0, 0); } while (0)
; #define PG8_LDA(dst, b, h) do { _Pragma("unroll") for (int m = 0; m < 4; ++m) _Pragma("unroll") for (int k = 0; k < 2; ++k) dst[m][k] = *(const PG8_LAS bf16x8*)(lds + PG8_SA(b, h) + aoff + m * 2048 + k * 1024); } while (0)
; #define PG8_LDB(dst, b, h) do { _Pragma("unroll") for (int n = 0; n < 2; ++n) _Pragma("unroll") for (int k = 0; k < 2; ++k) dst[n][k] = *(const PG8_LAS bf16x8*)(lds + PG8_SB(b, h) + boff + n * 2048 + k * 1024); } while (0)
; #define PG8_MMA(ai, bj, At, Bt) do { __builtin_amdgcn_s_setprio(1); _Pragma("unroll") for (int m = 0; m < 4; ++m) _Pragma("unroll") for (int n = 0; n < 2; ++n) _Pragma("unroll") for (int k = 0; k < 2; ++k) \
;         acc[ai][bj][m][n] = __builtin_amdgcn_mfma_f32_16x16x32_bf16(Bt[n][k], At[m][k], acc[ai][bj][m][n], 0, 0, 0); __builtin_amdgcn_s_setprio(0); } while (0)
; #define PG8_WAIT_V(n) asm volatile("s_waitcnt vmcnt(" #n ")" ::: "memory")
; #define PG8_WAIT_L(n) asm volatile("s_waitcnt lgkmcnt(" #n ")" ::: "memory")
; #define PG8_BAR __builtin_amdgcn_s_barrier()
; #define PG8_SCHED __builtin_amdgcn_sched_barrier(0)
; template <class Epi, class Sched, bool ALIGN_EPI = false, bool SP2 = false>
; __device__ __forceinline__ void gemm_phase(PG8_LAS unsigned char* lds, const Gemm g, const Sched& S, const Epi& E, const int wave_in) {
;     ...
;             PG8_LDB(B0, 1, 0); PG8_LDB(B1, 1, 1); PG8_SCHED; PG8_LDA(At, 1, 0); PG8_STAGE(PG8_SA(0, 1), a2 + hstepA, voffA);
;             PG8_WAIT_V(8); PG8_WAIT_L(0); PG8_BAR; PG8_MMA(0, 0, At, B0); PG8_MMA(0, 1, At, B1); PG8_BAR; PG8_SCHED;
;             PG8_LDA(At, 1, 1); PG8_STAGE(PG8_SB(1, 0), b3, voffB); PG8_STAGE(PG8_SB(1, 1), b3 + hstepB, voffB); PG8_STAGE(PG8_SA(1, 0), a3, voffA);
;             PG8_WAIT_V(8); PG8_WAIT_L(0); PG8_BAR; PG8_MMA(1, 0, At, B0); PG8_MMA(1, 1, At, B1); PG8_BAR; PG8_SCHED;
	s_add_i32 s50, 0, 0x18000
	s_add_i32 s51, 0, 0x1c000
	v_add_u32_e32 v162, s50, v149
	v_add_u32_e32 v178, s51, v149
	ds_read_b128 v[144:147], v162
	ds_read_b128 v[154:157], v162 offset:1024
	ds_read_b128 v[158:161], v162 offset:2048
	ds_read_b128 v[162:165], v162 offset:3072
	ds_read_b128 v[166:169], v178
	ds_read_b128 v[170:173], v178 offset:1024
	ds_read_b128 v[174:177], v178 offset:2048
	ds_read_b128 v[178:181], v178 offset:3072
	s_add_u32 s26, s26, 0x80000
	s_addc_u32 s27, s27, 0
	s_mov_b32 m0, s36
	v_lshl_add_u64 v[222:223], s[26:27], 0, v[128:129]
	ds_read_b128 v[182:185], v153 offset:32768
	ds_read_b128 v[186:189], v153 offset:33792
	ds_read_b128 v[190:193], v153 offset:34816
	ds_read_b128 v[194:197], v153 offset:35840
	ds_read_b128 v[198:201], v153 offset:36864
	ds_read_b128 v[202:205], v153 offset:37888
	ds_read_b128 v[206:209], v153 offset:38912
	ds_read_b128 v[210:213], v153 offset:39936
	global_load_lds_dwordx4 v[222:223], off
	v_lshl_add_u64 v[222:223], s[26:27], 0, v[132:133]
	s_mov_b32 m0, s37
	s_nop 0
	global_load_lds_dwordx4 v[222:223], off
	s_waitcnt vmcnt(8)
	s_waitcnt lgkmcnt(0)
	s_barrier
	s_setprio 1
	s_waitcnt lgkmcnt(0)
	v_mfma_f32_16x16x32_bf16 v[124:127], v[144:147], v[182:185], v[124:127]
	v_mfma_f32_16x16x32_bf16 v[120:123], v[158:161], v[182:185], v[120:123]
	v_mfma_f32_16x16x32_bf16 v[108:111], v[144:147], v[190:193], v[108:111]
	v_mfma_f32_16x16x32_bf16 v[104:107], v[158:161], v[190:193], v[104:107]
	v_mfma_f32_16x16x32_bf16 v[92:95], v[144:147], v[198:201], v[92:95]
	v_mfma_f32_16x16x32_bf16 v[88:91], v[158:161], v[198:201], v[88:91]
	v_mfma_f32_16x16x32_bf16 v[76:79], v[144:147], v[206:209], v[76:79]
	v_mfma_f32_16x16x32_bf16 v[72:75], v[158:161], v[206:209], v[72:75]
	v_mfma_f32_16x16x32_bf16 v[124:127], v[154:157], v[186:189], v[124:127]
	v_mfma_f32_16x16x32_bf16 v[120:123], v[162:165], v[186:189], v[120:123]
	v_mfma_f32_16x16x32_bf16 v[108:111], v[154:157], v[194:197], v[108:111]
	v_mfma_f32_16x16x32_bf16 v[104:107], v[162:165], v[194:197], v[104:107]
	v_mfma_f32_16x16x32_bf16 v[92:95], v[154:157], v[202:205], v[92:95]
	v_mfma_f32_16x16x32_bf16 v[88:91], v[162:165], v[202:205], v[88:91]
	v_mfma_f32_16x16x32_bf16 v[76:79], v[154:157], v[210:213], v[76:79]
	v_mfma_f32_16x16x32_bf16 v[72:75], v[162:165], v[210:213], v[72:75]
	s_setprio 0
	s_setprio 1
	v_mfma_f32_16x16x32_bf16 v[116:119], v[166:169], v[182:185], v[116:119]
	v_mfma_f32_16x16x32_bf16 v[112:115], v[174:177], v[182:185], v[112:115]
	v_mfma_f32_16x16x32_bf16 v[100:103], v[166:169], v[190:193], v[100:103]
	v_mfma_f32_16x16x32_bf16 v[96:99], v[174:177], v[190:193], v[96:99]
	v_mfma_f32_16x16x32_bf16 v[84:87], v[166:169], v[198:201], v[84:87]
	v_mfma_f32_16x16x32_bf16 v[80:83], v[174:177], v[198:201], v[80:83]
	v_mfma_f32_16x16x32_bf16 v[68:71], v[166:169], v[206:209], v[68:71]
	v_mfma_f32_16x16x32_bf16 v[64:67], v[174:177], v[206:209], v[64:67]
	v_mfma_f32_16x16x32_bf16 v[116:119], v[170:173], v[186:189], v[116:119]
	v_mfma_f32_16x16x32_bf16 v[112:115], v[178:181], v[186:189], v[112:115]
	v_mfma_f32_16x16x32_bf16 v[100:103], v[170:173], v[194:197], v[100:103]
	v_mfma_f32_16x16x32_bf16 v[96:99], v[178:181], v[194:197], v[96:99]
	v_mfma_f32_16x16x32_bf16 v[84:87], v[170:173], v[202:205], v[84:87]
	v_mfma_f32_16x16x32_bf16 v[80:83], v[178:181], v[202:205], v[80:83]
	v_mfma_f32_16x16x32_bf16 v[68:71], v[170:173], v[210:213], v[68:71]
	v_mfma_f32_16x16x32_bf16 v[64:67], v[178:181], v[210:213], v[64:67]
	s_setprio 0
	s_barrier
	s_add_i32 s26, s50, s34
	v_lshl_add_u64 v[214:215], v[214:215], 0, s[8:9]
	s_mov_b32 m0, s26
	ds_read_b128 v[182:185], v153 offset:49152
	ds_read_b128 v[186:189], v153 offset:50176
	ds_read_b128 v[190:193], v153 offset:51200
	ds_read_b128 v[194:197], v153 offset:52224
	ds_read_b128 v[198:201], v153 offset:53248
	ds_read_b128 v[202:205], v153 offset:54272
	ds_read_b128 v[206:209], v153 offset:55296
	ds_read_b128 v[210:213], v153 offset:56320
	global_load_lds_dwordx4 v[214:215], off
	s_add_i32 m0, s26, 0x2000
	s_add_u32 s24, s24, 0x80080
	v_lshl_add_u64 v[214:215], v[216:217], 0, s[8:9]
	s_addc_u32 s25, s25, 0
	s_add_i32 s26, s51, s34
	global_load_lds_dwordx4 v[214:215], off
	v_lshl_add_u64 v[214:215], s[24:25], 0, v[130:131]
	s_mov_b32 m0, s26
	s_nop 0
	global_load_lds_dwordx4 v[214:215], off
	v_lshl_add_u64 v[214:215], s[24:25], 0, v[134:135]
	s_add_i32 m0, s26, 0x2000
	s_nop 0
	global_load_lds_dwordx4 v[214:215], off
	v_lshl_add_u64 v[214:215], v[218:219], 0, s[8:9]
	s_mov_b32 m0, s39
	s_nop 0
	global_load_lds_dwordx4 v[214:215], off
	v_lshl_add_u64 v[214:215], v[220:221], 0, s[8:9]
	s_mov_b32 m0, s40
	s_nop 0
	global_load_lds_dwordx4 v[214:215], off
	s_waitcnt vmcnt(8)
	s_waitcnt lgkmcnt(0)
	s_barrier
; #define PG8_STAGE(bufoff, gbase, voff) do { _Pragma("unroll") for (int _i = 0; _i < 2; ++_i) \
;         __builtin_amdgcn_global_load_lds((const unsigned*)((const char*)(gbase) + (voff)[_i]), (PG8_LAS unsigned*)(lds + (bufoff) + ldsw + _i * 8192), 16, 0, 0); } while (0)
; #define PG8_LDA(dst, b, h) do { _Pragma("unroll") for (int m = 0; m < 4; ++m) _Pragma("unroll") for (int k = 0; k < 2; ++k) dst[m][k] = *(const PG8_LAS bf16x8*)(lds + PG8_SA(b, h) + aoff + m * 2048 + k * 1024); } while (0)
; #define PG8_LDB(dst, b, h) do { _Pragma("unroll") for (int n = 0; n < 2; ++n) _Pragma("unroll") for (int k = 0; k < 2; ++k) dst[n][k] = *(const PG8_LAS bf16x8*)(lds + PG8_SB(b, h) + boff + n * 2048 + k * 1024); } while (0)
; #define PG8_MMA(ai, bj, At, Bt) do { __builtin_amdgcn_s_setprio(1); _Pragma("unroll") for (int m = 0; m < 4; ++m) _Pragma("unroll") for (int n = 0; n < 2; ++n) _Pragma("unroll") for (int k = 0; k < 2; ++k) \
;         acc[ai][bj][m][n] = __builtin_amdgcn_mfma_f32_16x16x32_bf16(Bt[n][k], At[m][k], acc[ai][bj][m][n], 0, 0, 0); __builtin_amdgcn_s_setprio(0); } while (0)
; #define PG8_WAIT_V(n) asm volatile("s_waitcnt vmcnt(" #n ")" ::: "memory")
; #define PG8_WAIT_L(n) asm volatile("s_waitcnt lgkmcnt(" #n ")" ::: "memory")
; #define PG8_BAR __builtin_amdgcn_s_barrier()
; #define PG8_SCHED __builtin_amdgcn_sched_barrier(0)
; template <class Epi, class Sched, bool ALIGN_EPI = false, bool SP2 = false>
; __device__ __forceinline__ void gemm_phase(PG8_LAS unsigned char* lds, const Gemm g, const Sched& S, const Epi& E, const int wave_in) {
;     ...
;         for (int t = 0; t < nt; t += 2) {
;             const bool last = (t == nt - 2);
;             const char* a1 = cA + (size_t)(t + 1) * kstep;
;             const char* a2 = last ? nA : cA + (size_t)(t + 2) * kstep; const char* b2 = last ? nB : cB + (size_t)(t + 2) * kstep;
;             const char* a3 = a2 + kstep; const char* b3 = b2 + kstep;
;             if (last && has_next) S.a_ready(nxt);
;             if constexpr (SP2) {
;             PG8_LDB(B0, 0, 0); PG8_LDB(B1, 0, 1); PG8_SCHED; PG8_LDA(At, 0, 0); PG8_STAGE(PG8_SA(1, 1), a1 + hstepA, voffA);
;             PG8_WAIT_V(8); PG8_WAIT_L(0); PG8_BAR; PG8_MMA(0, 0, At, B0); PG8_MMA(0, 1, At, B1); PG8_BAR; PG8_SCHED;
;     ...
;             PG8_WAIT_V(8); PG8_WAIT_L(0); PG8_BAR; PG8_MMA(1, 0, At, B0); PG8_MMA(1, 1, At, B1); PG8_BAR; PG8_SCHED;
	s_setprio 1
	s_waitcnt lgkmcnt(0)
	v_mfma_f32_16x16x32_bf16 v[60:63], v[144:147], v[182:185], v[60:63]
	v_mfma_f32_16x16x32_bf16 v[56:59], v[158:161], v[182:185], v[56:59]
	v_mfma_f32_16x16x32_bf16 v[44:47], v[144:147], v[190:193], v[44:47]
	v_mfma_f32_16x16x32_bf16 v[40:43], v[158:161], v[190:193], v[40:43]
	v_mfma_f32_16x16x32_bf16 v[28:31], v[144:147], v[198:201], v[28:31]
	v_mfma_f32_16x16x32_bf16 v[24:27], v[158:161], v[198:201], v[24:27]
	v_mfma_f32_16x16x32_bf16 v[12:15], v[144:147], v[206:209], v[12:15]
	v_mfma_f32_16x16x32_bf16 v[8:11], v[158:161], v[206:209], v[8:11]
	v_mfma_f32_16x16x32_bf16 v[60:63], v[154:157], v[186:189], v[60:63]
	v_mfma_f32_16x16x32_bf16 v[56:59], v[162:165], v[186:189], v[56:59]
	v_mfma_f32_16x16x32_bf16 v[44:47], v[154:157], v[194:197], v[44:47]
	v_mfma_f32_16x16x32_bf16 v[40:43], v[162:165], v[194:197], v[40:43]
	v_mfma_f32_16x16x32_bf16 v[28:31], v[154:157], v[202:205], v[28:31]
	v_mfma_f32_16x16x32_bf16 v[24:27], v[162:165], v[202:205], v[24:27]
	v_mfma_f32_16x16x32_bf16 v[12:15], v[154:157], v[210:213], v[12:15]
	v_mfma_f32_16x16x32_bf16 v[8:11], v[162:165], v[210:213], v[8:11]
	s_setprio 0
	s_setprio 1
	v_mfma_f32_16x16x32_bf16 v[52:55], v[166:169], v[182:185], v[52:55]
	v_mfma_f32_16x16x32_bf16 v[48:51], v[174:177], v[182:185], v[48:51]
	v_mfma_f32_16x16x32_bf16 v[36:39], v[166:169], v[190:193], v[36:39]
	v_mfma_f32_16x16x32_bf16 v[32:35], v[174:177], v[190:193], v[32:35]
	v_mfma_f32_16x16x32_bf16 v[20:23], v[166:169], v[198:201], v[20:23]
	v_mfma_f32_16x16x32_bf16 v[16:19], v[174:177], v[198:201], v[16:19]
	v_mfma_f32_16x16x32_bf16 v[4:7], v[166:169], v[206:209], v[4:7]
	v_mfma_f32_16x16x32_bf16 v[0:3], v[174:177], v[206:209], v[0:3]
	v_mfma_f32_16x16x32_bf16 v[52:55], v[170:173], v[186:189], v[52:55]
	v_mfma_f32_16x16x32_bf16 v[48:51], v[178:181], v[186:189], v[48:51]
	v_mfma_f32_16x16x32_bf16 v[36:39], v[170:173], v[194:197], v[36:39]
	v_mfma_f32_16x16x32_bf16 v[32:35], v[178:181], v[194:197], v[32:35]
	v_mfma_f32_16x16x32_bf16 v[20:23], v[170:173], v[202:205], v[20:23]
	v_mfma_f32_16x16x32_bf16 v[16:19], v[178:181], v[202:205], v[16:19]
	v_mfma_f32_16x16x32_bf16 v[4:7], v[170:173], v[210:213], v[4:7]
	v_mfma_f32_16x16x32_bf16 v[0:3], v[178:181], v[210:213], v[0:3]
	s_setprio 0
	s_barrier
	s_add_i32 s49, s49, 2
	s_add_u32 s22, s22, 0x100
	s_addc_u32 s23, s23, 0
	s_add_u32 s47, s47, 0x100
	s_addc_u32 s48, s48, 0
	s_cmp_gt_u32 s49, 29
	s_cbranch_scc0 .LBB0_158
.LBB0_158:
	ds_read_b128 v[144:147], v151
	ds_read_b128 v[154:157], v151 offset:1024
	ds_read_b128 v[158:161], v151 offset:2048
	ds_read_b128 v[162:165], v151 offset:3072
	ds_read_b128 v[166:169], v152
	ds_read_b128 v[170:173], v152 offset:1024
	ds_read_b128 v[174:177], v152 offset:2048
	ds_read_b128 v[178:181], v152 offset:3072
	s_add_u32 s24, s22, 0xfff80080
	s_addc_u32 s25, s23, -1
	s_cmp_eq_u32 s49, 28
	s_cselect_b32 s27, s5, s25
	s_cselect_b32 s26, s15, s24
	s_cselect_b32 s25, s13, s48
	s_cselect_b32 s24, s46, s47
	v_lshl_add_u64 v[214:215], s[22:23], 0, v[136:137]
	s_add_i32 m0, s21, 0xc000
	ds_read_b128 v[182:185], v153
	ds_read_b128 v[186:189], v153 offset:1024
	ds_read_b128 v[190:193], v153 offset:2048
	ds_read_b128 v[194:197], v153 offset:3072
	ds_read_b128 v[198:201], v153 offset:4096
	ds_read_b128 v[202:205], v153 offset:5120
	ds_read_b128 v[206:209], v153 offset:6144
	ds_read_b128 v[210:213], v153 offset:7168
	global_load_lds_dwordx4 v[214:215], off
	v_lshl_add_u64 v[214:215], s[22:23], 0, v[138:139]
	s_add_i32 m0, s21, 0xe000
	s_nop 0
	global_load_lds_dwordx4 v[214:215], off
	s_waitcnt vmcnt(8)
	s_waitcnt lgkmcnt(0)
	s_barrier
	s_setprio 1
	s_waitcnt lgkmcnt(0)
	v_mfma_f32_16x16x32_bf16 v[124:127], v[144:147], v[182:185], v[124:127]
	v_mfma_f32_16x16x32_bf16 v[120:123], v[158:161], v[182:185], v[120:123]
	v_mfma_f32_16x16x32_bf16 v[108:111], v[144:147], v[190:193], v[108:111]
	v_mfma_f32_16x16x32_bf16 v[104:107], v[158:161], v[190:193], v[104:107]
	v_mfma_f32_16x16x32_bf16 v[92:95], v[144:147], v[198:201], v[92:95]
	v_mfma_f32_16x16x32_bf16 v[88:91], v[158:161], v[198:201], v[88:91]
	v_mfma_f32_16x16x32_bf16 v[76:79], v[144:147], v[206:209], v[76:79]
	v_mfma_f32_16x16x32_bf16 v[72:75], v[158:161], v[206:209], v[72:75]
	v_mfma_f32_16x16x32_bf16 v[124:127], v[154:157], v[186:189], v[124:127]
	v_mfma_f32_16x16x32_bf16 v[120:123], v[162:165], v[186:189], v[120:123]
	v_mfma_f32_16x16x32_bf16 v[108:111], v[154:157], v[194:197], v[108:111]
	v_mfma_f32_16x16x32_bf16 v[104:107], v[162:165], v[194:197], v[104:107]
	v_mfma_f32_16x16x32_bf16 v[92:95], v[154:157], v[202:205], v[92:95]
	v_mfma_f32_16x16x32_bf16 v[88:91], v[162:165], v[202:205], v[88:91]
	v_mfma_f32_16x16x32_bf16 v[76:79], v[154:157], v[210:213], v[76:79]
	v_mfma_f32_16x16x32_bf16 v[72:75], v[162:165], v[210:213], v[72:75]
	s_setprio 0
	s_setprio 1
	v_mfma_f32_16x16x32_bf16 v[116:119], v[166:169], v[182:185], v[116:119]
	v_mfma_f32_16x16x32_bf16 v[112:115], v[174:177], v[182:185], v[112:115]
	v_mfma_f32_16x16x32_bf16 v[100:103], v[166:169], v[190:193], v[100:103]
	v_mfma_f32_16x16x32_bf16 v[96:99], v[174:177], v[190:193], v[96:99]
	v_mfma_f32_16x16x32_bf16 v[84:87], v[166:169], v[198:201], v[84:87]
	v_mfma_f32_16x16x32_bf16 v[80:83], v[174:177], v[198:201], v[80:83]
	v_mfma_f32_16x16x32_bf16 v[68:71], v[166:169], v[206:209], v[68:71]
	v_mfma_f32_16x16x32_bf16 v[64:67], v[174:177], v[206:209], v[64:67]
	v_mfma_f32_16x16x32_bf16 v[116:119], v[170:173], v[186:189], v[116:119]
	v_mfma_f32_16x16x32_bf16 v[112:115], v[178:181], v[186:189], v[112:115]
	v_mfma_f32_16x16x32_bf16 v[100:103], v[170:173], v[194:197], v[100:103]
	v_mfma_f32_16x16x32_bf16 v[96:99], v[178:181], v[194:197], v[96:99]
	v_mfma_f32_16x16x32_bf16 v[84:87], v[170:173], v[202:205], v[84:87]
	v_mfma_f32_16x16x32_bf16 v[80:83], v[178:181], v[202:205], v[80:83]
	v_mfma_f32_16x16x32_bf16 v[68:71], v[170:173], v[210:213], v[68:71]
	v_mfma_f32_16x16x32_bf16 v[64:67], v[178:181], v[210:213], v[64:67]
	s_setprio 0
	s_barrier
; #define PG8_STAGE(bufoff, gbase, voff) do { _Pragma("unroll") for (int _i = 0; _i < 2; ++_i) \
;         __builtin_amdgcn_global_load_lds((const unsigned*)((const char*)(gbase) + (voff)[_i]), (PG8_LAS unsigned*)(lds + (bufoff) + ldsw + _i * 8192), 16, 0, 0); } while (0)
; #define PG8_LDA(dst, b, h) do { _Pragma("unroll") for (int m = 0; m < 4; ++m) _Pragma("unroll") for (int k = 0; k < 2; ++k) dst[m][k] = *(const PG8_LAS bf16x8*)(lds + PG8_SA(b, h) + aoff + m * 2048 + k * 1024); } while (0)
; #define PG8_LDB(dst, b, h) do { _Pragma("unroll") for (int n = 0; n < 2; ++n) _Pragma("unroll") for (int k = 0; k < 2; ++k) dst[n][k] = *(const PG8_LAS bf16x8*)(lds + PG8_SB(b, h) + boff + n * 2048 + k * 1024); } while (0)
; #define PG8_MMA(ai, bj, At, Bt) do { __builtin_amdgcn_s_setprio(1); _Pragma("unroll") for (int m = 0; m < 4; ++m) _Pragma("unroll") for (int n = 0; n < 2; ++n) _Pragma("unroll") for (int k = 0; k < 2; ++k) \
;         acc[ai][bj][m][n] = __builtin_amdgcn_mfma_f32_16x16x32_bf16(Bt[n][k], At[m][k], acc[ai][bj][m][n], 0, 0, 0); __builtin_amdgcn_s_setprio(0); } while (0)
; #define PG8_WAIT_V(n) asm volatile("s_waitcnt vmcnt(" #n ")" ::: "memory")
; #define PG8_WAIT_L(n) asm volatile("s_waitcnt lgkmcnt(" #n ")" ::: "memory")
; #define PG8_BAR __builtin_amdgcn_s_barrier()
; #define PG8_SCHED __builtin_amdgcn_sched_barrier(0)
; template <class Epi, class Sched, bool ALIGN_EPI = false, bool SP2 = false>
; __device__ __forceinline__ void gemm_phase(PG8_LAS unsigned char* lds, const Gemm g, const Sched& S, const Epi& E, const int wave_in) {
;     ...
;             PG8_WAIT_V(8); PG8_WAIT_L(0); PG8_BAR; PG8_MMA(0, 0, At, B0); PG8_MMA(0, 1, At, B1); PG8_BAR; PG8_SCHED;
;             PG8_LDA(At, 0, 1); PG8_STAGE(PG8_SB(0, 0), b2, voffB); PG8_STAGE(PG8_SB(0, 1), b2 + hstepB, voffB); PG8_STAGE(PG8_SA(0, 0), a2, voffA);
;             PG8_WAIT_V(8); PG8_WAIT_L(0); PG8_BAR; PG8_MMA(1, 0, At, B0); PG8_MMA(1, 1, At, B1); PG8_BAR; PG8_SCHED;
;             PG8_LDB(B0, 1, 0); PG8_LDB(B1, 1, 1); PG8_SCHED; PG8_LDA(At, 1, 0); PG8_STAGE(PG8_SA(0, 1), a2 + hstepA, voffA);
;             PG8_WAIT_V(8); PG8_WAIT_L(0); PG8_BAR; PG8_MMA(0, 0, At, B0); PG8_MMA(0, 1, At, B1); PG8_BAR; PG8_SCHED;
	s_add_i32 s50, s43, s34
	v_lshl_add_u64 v[214:215], s[24:25], 0, v[130:131]
	s_mov_b32 m0, s50
	ds_read_b128 v[182:185], v153 offset:16384
	ds_read_b128 v[186:189], v153 offset:17408
	ds_read_b128 v[190:193], v153 offset:18432
	ds_read_b128 v[194:197], v153 offset:19456
	ds_read_b128 v[198:201], v153 offset:20480
	ds_read_b128 v[202:205], v153 offset:21504
	ds_read_b128 v[206:209], v153 offset:22528
	ds_read_b128 v[210:213], v153 offset:23552
	global_load_lds_dwordx4 v[214:215], off
	s_add_i32 m0, s50, 0x2000
	s_add_u32 s50, s24, 0x80000
	v_lshl_add_u64 v[216:217], s[24:25], 0, v[134:135]
	s_addc_u32 s51, s25, 0
	s_add_i32 s52, s44, s34
	global_load_lds_dwordx4 v[216:217], off
	v_lshl_add_u64 v[218:219], s[50:51], 0, v[130:131]
	s_mov_b32 m0, s52
	v_lshl_add_u64 v[220:221], s[26:27], 0, v[132:133]
	global_load_lds_dwordx4 v[218:219], off
	v_lshl_add_u64 v[218:219], s[50:51], 0, v[134:135]
	s_add_i32 m0, s52, 0x2000
	s_nop 0
	global_load_lds_dwordx4 v[218:219], off
	v_lshl_add_u64 v[218:219], s[26:27], 0, v[128:129]
	s_mov_b32 m0, s21
	s_nop 0
	global_load_lds_dwordx4 v[218:219], off
	s_mov_b32 m0, s35
	s_nop 0
	global_load_lds_dwordx4 v[220:221], off
	s_waitcnt vmcnt(8)
	s_waitcnt lgkmcnt(0)
	s_barrier
	s_setprio 1
	s_waitcnt lgkmcnt(0)
	v_mfma_f32_16x16x32_bf16 v[60:63], v[144:147], v[182:185], v[60:63]
	v_mfma_f32_16x16x32_bf16 v[56:59], v[158:161], v[182:185], v[56:59]
	v_mfma_f32_16x16x32_bf16 v[44:47], v[144:147], v[190:193], v[44:47]
	v_mfma_f32_16x16x32_bf16 v[40:43], v[158:161], v[190:193], v[40:43]
	v_mfma_f32_16x16x32_bf16 v[28:31], v[144:147], v[198:201], v[28:31]
	v_mfma_f32_16x16x32_bf16 v[24:27], v[158:161], v[198:201], v[24:27]
	v_mfma_f32_16x16x32_bf16 v[12:15], v[144:147], v[206:209], v[12:15]
	v_mfma_f32_16x16x32_bf16 v[8:11], v[158:161], v[206:209], v[8:11]
	v_mfma_f32_16x16x32_bf16 v[60:63], v[154:157], v[186:189], v[60:63]
	v_mfma_f32_16x16x32_bf16 v[56:59], v[162:165], v[186:189], v[56:59]
	v_mfma_f32_16x16x32_bf16 v[44:47], v[154:157], v[194:197], v[44:47]
	v_mfma_f32_16x16x32_bf16 v[40:43], v[162:165], v[194:197], v[40:43]
	v_mfma_f32_16x16x32_bf16 v[28:31], v[154:157], v[202:205], v[28:31]
	v_mfma_f32_16x16x32_bf16 v[24:27], v[162:165], v[202:205], v[24:27]
	v_mfma_f32_16x16x32_bf16 v[12:15], v[154:157], v[210:213], v[12:15]
	v_mfma_f32_16x16x32_bf16 v[8:11], v[162:165], v[210:213], v[8:11]
	s_setprio 0
	s_setprio 1
	v_mfma_f32_16x16x32_bf16 v[52:55], v[166:169], v[182:185], v[52:55]
	v_mfma_f32_16x16x32_bf16 v[48:51], v[174:177], v[182:185], v[48:51]
	v_mfma_f32_16x16x32_bf16 v[36:39], v[166:169], v[190:193], v[36:39]
	v_mfma_f32_16x16x32_bf16 v[32:35], v[174:177], v[190:193], v[32:35]
	v_mfma_f32_16x16x32_bf16 v[20:23], v[166:169], v[198:201], v[20:23]
	v_mfma_f32_16x16x32_bf16 v[16:19], v[174:177], v[198:201], v[16:19]
	v_mfma_f32_16x16x32_bf16 v[4:7], v[166:169], v[206:209], v[4:7]
	v_mfma_f32_16x16x32_bf16 v[0:3], v[174:177], v[206:209], v[0:3]
	v_mfma_f32_16x16x32_bf16 v[52:55], v[170:173], v[186:189], v[52:55]
	v_mfma_f32_16x16x32_bf16 v[48:51], v[178:181], v[186:189], v[48:51]
	v_mfma_f32_16x16x32_bf16 v[36:39], v[170:173], v[194:197], v[36:39]
	v_mfma_f32_16x16x32_bf16 v[32:35], v[178:181], v[194:197], v[32:35]
	v_mfma_f32_16x16x32_bf16 v[20:23], v[170:173], v[202:205], v[20:23]
	v_mfma_f32_16x16x32_bf16 v[16:19], v[178:181], v[202:205], v[16:19]
	v_mfma_f32_16x16x32_bf16 v[4:7], v[170:173], v[210:213], v[4:7]
	v_mfma_f32_16x16x32_bf16 v[0:3], v[178:181], v[210:213], v[0:3]
	s_setprio 0
	s_barrier
	s_add_i32 s50, 0, 0x18000
	s_add_i32 s51, 0, 0x1c000
	v_add_u32_e32 v162, s50, v149
	v_add_u32_e32 v178, s51, v149
	ds_read_b128 v[144:147], v162
	ds_read_b128 v[154:157], v162 offset:1024
	ds_read_b128 v[158:161], v162 offset:2048
	ds_read_b128 v[162:165], v162 offset:3072
	ds_read_b128 v[166:169], v178
	ds_read_b128 v[170:173], v178 offset:1024
	ds_read_b128 v[174:177], v178 offset:2048
	ds_read_b128 v[178:181], v178 offset:3072
	s_add_u32 s26, s26, 0x80000
	s_addc_u32 s27, s27, 0
	s_mov_b32 m0, s36
	v_lshl_add_u64 v[222:223], s[26:27], 0, v[128:129]
	ds_read_b128 v[182:185], v153 offset:32768
	ds_read_b128 v[186:189], v153 offset:33792
	ds_read_b128 v[190:193], v153 offset:34816
	ds_read_b128 v[194:197], v153 offset:35840
	ds_read_b128 v[198:201], v153 offset:36864
	ds_read_b128 v[202:205], v153 offset:37888
	ds_read_b128 v[206:209], v153 offset:38912
	ds_read_b128 v[210:213], v153 offset:39936
	global_load_lds_dwordx4 v[222:223], off
	v_lshl_add_u64 v[222:223], s[26:27], 0, v[132:133]
	s_mov_b32 m0, s37
	s_nop 0
	global_load_lds_dwordx4 v[222:223], off
	s_waitcnt vmcnt(8)
	s_waitcnt lgkmcnt(0)
	s_barrier
; #define PG8_STAGE(bufoff, gbase, voff) do { _Pragma("unroll") for (int _i = 0; _i < 2; ++_i) \
;         __builtin_amdgcn_global_load_lds((const unsigned*)((const char*)(gbase) + (voff)[_i]), (PG8_LAS unsigned*)(lds + (bufoff) + ldsw + _i * 8192), 16, 0, 0); } while (0)
; #define PG8_LDA(dst, b, h) do { _Pragma("unroll") for (int m = 0; m < 4; ++m) _Pragma("unroll") for (int k = 0; k < 2; ++k) dst[m][k] = *(const PG8_LAS bf16x8*)(lds + PG8_SA(b, h) + aoff + m * 2048 + k * 1024); } while (0)
; #define PG8_MMA(ai, bj, At, Bt) do { __builtin_amdgcn_s_setprio(1); _Pragma("unroll") for (int m = 0; m < 4; ++m) _Pragma("unroll") for (int n = 0; n < 2; ++n) _Pragma("unroll") for (int k = 0; k < 2; ++k) \
;         acc[ai][bj][m][n] = __builtin_amdgcn_mfma_f32_16x16x32_bf16(Bt[n][k], At[m][k], acc[ai][bj][m][n], 0, 0, 0); __builtin_amdgcn_s_setprio(0); } while (0)
; #define PG8_WAIT_V(n) asm volatile("s_waitcnt vmcnt(" #n ")" ::: "memory")
; #define PG8_WAIT_L(n) asm volatile("s_waitcnt lgkmcnt(" #n ")" ::: "memory")
; #define PG8_BAR __builtin_amdgcn_s_barrier()
; #define PG8_SCHED __builtin_amdgcn_sched_barrier(0)
; template <class Epi, class Sched, bool ALIGN_EPI = false, bool SP2 = false>
; __device__ __forceinline__ void gemm_phase(PG8_LAS unsigned char* lds, const Gemm g, const Sched& S, const Epi& E, const int wave_in) {
;     ...
;             PG8_WAIT_V(8); PG8_WAIT_L(0); PG8_BAR; PG8_MMA(0, 0, At, B0); PG8_MMA(0, 1, At, B1); PG8_BAR; PG8_SCHED;
;             PG8_LDA(At, 1, 1); PG8_STAGE(PG8_SB(1, 0), b3, voffB); PG8_STAGE(PG8_SB(1, 1), b3 + hstepB, voffB); PG8_STAGE(PG8_SA(1, 0), a3, voffA);
;             PG8_WAIT_V(8); PG8_WAIT_L(0); PG8_BAR; PG8_MMA(1, 0, At, B0); PG8_MMA(1, 1, At, B1); PG8_BAR; PG8_SCHED;
;     ...
;         if constexpr (ALIGN_EPI) { if (wr == 0) PG8_BAR; }
;         if constexpr (!Epi::AFTER_DRAIN) { E(acc, cur, wr, wc, fr, fq); S.done(cur); }
;         if (!has_next) break;
	s_setprio 1
	s_waitcnt lgkmcnt(0)
	v_mfma_f32_16x16x32_bf16 v[124:127], v[144:147], v[182:185], v[124:127]
	v_mfma_f32_16x16x32_bf16 v[120:123], v[158:161], v[182:185], v[120:123]
	v_mfma_f32_16x16x32_bf16 v[108:111], v[144:147], v[190:193], v[108:111]
	v_mfma_f32_16x16x32_bf16 v[104:107], v[158:161], v[190:193], v[104:107]
	v_mfma_f32_16x16x32_bf16 v[92:95], v[144:147], v[198:201], v[92:95]
	v_mfma_f32_16x16x32_bf16 v[88:91], v[158:161], v[198:201], v[88:91]
	v_mfma_f32_16x16x32_bf16 v[76:79], v[144:147], v[206:209], v[76:79]
	v_mfma_f32_16x16x32_bf16 v[72:75], v[158:161], v[206:209], v[72:75]
	v_mfma_f32_16x16x32_bf16 v[124:127], v[154:157], v[186:189], v[124:127]
	v_mfma_f32_16x16x32_bf16 v[120:123], v[162:165], v[186:189], v[120:123]
	v_mfma_f32_16x16x32_bf16 v[108:111], v[154:157], v[194:197], v[108:111]
	v_mfma_f32_16x16x32_bf16 v[104:107], v[162:165], v[194:197], v[104:107]
	v_mfma_f32_16x16x32_bf16 v[92:95], v[154:157], v[202:205], v[92:95]
	v_mfma_f32_16x16x32_bf16 v[88:91], v[162:165], v[202:205], v[88:91]
	v_mfma_f32_16x16x32_bf16 v[76:79], v[154:157], v[210:213], v[76:79]
	v_mfma_f32_16x16x32_bf16 v[72:75], v[162:165], v[210:213], v[72:75]
	s_setprio 0
	s_setprio 1
	v_mfma_f32_16x16x32_bf16 v[116:119], v[166:169], v[182:185], v[116:119]
	v_mfma_f32_16x16x32_bf16 v[112:115], v[174:177], v[182:185], v[112:115]
	v_mfma_f32_16x16x32_bf16 v[100:103], v[166:169], v[190:193], v[100:103]
	v_mfma_f32_16x16x32_bf16 v[96:99], v[174:177], v[190:193], v[96:99]
	v_mfma_f32_16x16x32_bf16 v[84:87], v[166:169], v[198:201], v[84:87]
	v_mfma_f32_16x16x32_bf16 v[80:83], v[174:177], v[198:201], v[80:83]
	v_mfma_f32_16x16x32_bf16 v[68:71], v[166:169], v[206:209], v[68:71]
	v_mfma_f32_16x16x32_bf16 v[64:67], v[174:177], v[206:209], v[64:67]
	v_mfma_f32_16x16x32_bf16 v[116:119], v[170:173], v[186:189], v[116:119]
	v_mfma_f32_16x16x32_bf16 v[112:115], v[178:181], v[186:189], v[112:115]
	v_mfma_f32_16x16x32_bf16 v[100:103], v[170:173], v[194:197], v[100:103]
	v_mfma_f32_16x16x32_bf16 v[96:99], v[178:181], v[194:197], v[96:99]
	v_mfma_f32_16x16x32_bf16 v[84:87], v[170:173], v[202:205], v[84:87]
	v_mfma_f32_16x16x32_bf16 v[80:83], v[178:181], v[202:205], v[80:83]
	v_mfma_f32_16x16x32_bf16 v[68:71], v[170:173], v[210:213], v[68:71]
	v_mfma_f32_16x16x32_bf16 v[64:67], v[178:181], v[210:213], v[64:67]
	s_setprio 0
	s_barrier
	s_add_i32 s26, s50, s34
	v_lshl_add_u64 v[214:215], v[214:215], 0, s[8:9]
	s_mov_b32 m0, s26
	ds_read_b128 v[182:185], v153 offset:49152
	ds_read_b128 v[186:189], v153 offset:50176
	ds_read_b128 v[190:193], v153 offset:51200
	ds_read_b128 v[194:197], v153 offset:52224
	ds_read_b128 v[198:201], v153 offset:53248
	ds_read_b128 v[202:205], v153 offset:54272
	ds_read_b128 v[206:209], v153 offset:55296
	ds_read_b128 v[210:213], v153 offset:56320
	global_load_lds_dwordx4 v[214:215], off
	s_add_i32 m0, s26, 0x2000
	s_add_u32 s24, s24, 0x80080
	v_lshl_add_u64 v[214:215], v[216:217], 0, s[8:9]
	s_addc_u32 s25, s25, 0
	s_add_i32 s26, s51, s34
	global_load_lds_dwordx4 v[214:215], off
	v_lshl_add_u64 v[214:215], s[24:25], 0, v[130:131]
	s_mov_b32 m0, s26
	s_nop 0
	global_load_lds_dwordx4 v[214:215], off
	v_lshl_add_u64 v[214:215], s[24:25], 0, v[134:135]
	s_add_i32 m0, s26, 0x2000
	s_nop 0
	global_load_lds_dwordx4 v[214:215], off
	v_lshl_add_u64 v[214:215], v[218:219], 0, s[8:9]
	s_mov_b32 m0, s39
	s_nop 0
	global_load_lds_dwordx4 v[214:215], off
	v_lshl_add_u64 v[214:215], v[220:221], 0, s[8:9]
	s_mov_b32 m0, s40
	s_nop 0
	global_load_lds_dwordx4 v[214:215], off
	s_waitcnt vmcnt(8)
	s_waitcnt lgkmcnt(0)
	s_barrier
	s_setprio 1
	s_waitcnt lgkmcnt(0)
	v_mfma_f32_16x16x32_bf16 v[60:63], v[144:147], v[182:185], v[60:63]
	v_mfma_f32_16x16x32_bf16 v[56:59], v[158:161], v[182:185], v[56:59]
	v_mfma_f32_16x16x32_bf16 v[44:47], v[144:147], v[190:193], v[44:47]
	v_mfma_f32_16x16x32_bf16 v[40:43], v[158:161], v[190:193], v[40:43]
	v_mfma_f32_16x16x32_bf16 v[28:31], v[144:147], v[198:201], v[28:31]
	v_mfma_f32_16x16x32_bf16 v[24:27], v[158:161], v[198:201], v[24:27]
	v_mfma_f32_16x16x32_bf16 v[12:15], v[144:147], v[206:209], v[12:15]
	v_mfma_f32_16x16x32_bf16 v[8:11], v[158:161], v[206:209], v[8:11]
	v_mfma_f32_16x16x32_bf16 v[60:63], v[154:157], v[186:189], v[60:63]
	v_mfma_f32_16x16x32_bf16 v[56:59], v[162:165], v[186:189], v[56:59]
	v_mfma_f32_16x16x32_bf16 v[44:47], v[154:157], v[194:197], v[44:47]
	v_mfma_f32_16x16x32_bf16 v[40:43], v[162:165], v[194:197], v[40:43]
	v_mfma_f32_16x16x32_bf16 v[28:31], v[154:157], v[202:205], v[28:31]
	v_mfma_f32_16x16x32_bf16 v[24:27], v[162:165], v[202:205], v[24:27]
	v_mfma_f32_16x16x32_bf16 v[12:15], v[154:157], v[210:213], v[12:15]
	v_mfma_f32_16x16x32_bf16 v[8:11], v[162:165], v[210:213], v[8:11]
	s_setprio 0
	s_setprio 1
	v_mfma_f32_16x16x32_bf16 v[52:55], v[166:169], v[182:185], v[52:55]
	v_mfma_f32_16x16x32_bf16 v[48:51], v[174:177], v[182:185], v[48:51]
	v_mfma_f32_16x16x32_bf16 v[36:39], v[166:169], v[190:193], v[36:39]
	v_mfma_f32_16x16x32_bf16 v[32:35], v[174:177], v[190:193], v[32:35]
	v_mfma_f32_16x16x32_bf16 v[20:23], v[166:169], v[198:201], v[20:23]
	v_mfma_f32_16x16x32_bf16 v[16:19], v[174:177], v[198:201], v[16:19]
	v_mfma_f32_16x16x32_bf16 v[4:7], v[166:169], v[206:209], v[4:7]
	v_mfma_f32_16x16x32_bf16 v[0:3], v[174:177], v[206:209], v[0:3]
	v_mfma_f32_16x16x32_bf16 v[52:55], v[170:173], v[186:189], v[52:55]
	v_mfma_f32_16x16x32_bf16 v[48:51], v[178:181], v[186:189], v[48:51]
	v_mfma_f32_16x16x32_bf16 v[36:39], v[170:173], v[194:197], v[36:39]
	v_mfma_f32_16x16x32_bf16 v[32:35], v[178:181], v[194:197], v[32:35]
	v_mfma_f32_16x16x32_bf16 v[20:23], v[170:173], v[202:205], v[20:23]
	v_mfma_f32_16x16x32_bf16 v[16:19], v[178:181], v[202:205], v[16:19]
	v_mfma_f32_16x16x32_bf16 v[4:7], v[170:173], v[210:213], v[4:7]
	v_mfma_f32_16x16x32_bf16 v[0:3], v[178:181], v[210:213], v[0:3]
	s_setprio 0
	s_barrier
	s_add_i32 s49, s49, 2
	s_add_u32 s22, s22, 0x100
	s_addc_u32 s23, s23, 0
	s_add_u32 s47, s47, 0x100
	s_addc_u32 s48, s48, 0
	s_cmp_gt_u32 s49, 29
	s_cbranch_scc0 .LBB0_158
	s_mov_b32 s99, 1
	s_and_b64 vcc, exec, s[10:11]
	s_cbranch_vccz .LBB0_161
	s_barrier

; __device__ __forceinline__ int lane_id_asm() { int l; asm volatile("v_mbcnt_lo_u32_b32 %0, -1, 0\n\tv_mbcnt_hi_u32_b32 %0, -1, %0" : "=v"(l)); return l; }
;     __host__ __device__ bool next(int i, Unit& u) const { const bool ok = StaticOrder::next(i, u); u.pm = 0; u.pn = 0; return ok; }
; template <class Epi, class Sched, bool ALIGN_EPI = false, bool SP2 = false>
; __device__ __forceinline__ void gemm_phase(PG8_LAS unsigned char* lds, const Gemm g, const Sched& S, const Epi& E, const int wave_in) {
;     const int lane = lane_id_asm(), wid = __builtin_amdgcn_readfirstlane(wave_in), tid = wid * 64 + lane, wr = wid >> 2, wc = wid & 3, fr = lane & 15, fq = lane >> 4;
;     const int K = g.K, nt = K / BK;
;     unsigned voffA[2], voffB[2];
; #pragma unroll
;     for (int i = 0; i < 2; ++i) { int R, C; stage_rc(tid * 16 + i * 8192, R, C); const int Rb = Epi::PERM ? ((R & ~31) + perm32(R & 31)) : R;
;         voffA[i] = (unsigned)(R * g.lda + C) * 2u; voffB[i] = (unsigned)(Rb * K + C) * 2u; }
;     const size_t kstep = (size_t)(BK * 2);
;     const size_t hstepA = (size_t)HALF * g.lda * 2, hstepB = (size_t)HALF * K * 2;
;     const size_t tstepA = 2 * hstepA, tstepB = 2 * hstepB;
;     const unsigned ldsw = (unsigned)wid * 1024u;
;     const int aoff = lds_byte(wr * 64 + fr, fq * 8), boff = lds_byte(wc * 32 + fr, fq * 8);
;     ...
;     Unit cur, nxt; int ui = 0;
;     if (!S.next(0, cur)) return;
;     f32x4 acc[2][2][4][2];
; #pragma unroll
;     for (int a = 0; a < 2; ++a)
; #pragma unroll
;         for (int b = 0; b < 2; ++b)
; #pragma unroll
;             for (int m = 0; m < 4; ++m)
; #pragma unroll
;                 for (int n = 0; n < 2; ++n) acc[a][b][m][n] = (f32x4){0.f, 0.f, 0.f, 0.f};
;     bf16x8 At[4][2], B0[2][2], B1[2][2];
;     const char* cA = (const char*)g.A + (size_t)cur.pm * tstepA; const char* cB = (const char*)g.Bt + (size_t)cur.pn * tstepB;
;     S.a_ready(cur);
;     if constexpr (SP2) {
;         PG8_STAGE(PG8_SB(0, 0), cB, voffB); PG8_STAGE(PG8_SB(0, 1), cB + hstepB, voffB); PG8_STAGE(PG8_SA(0, 0), cA, voffA); PG8_STAGE(PG8_SA(0, 1), cA + hstepA, voffA);
;         if (wr == 1) PG8_BAR;
;         PG8_WAIT_V(2); PG8_BAR;
;         PG8_STAGE(PG8_SB(1, 0), cB + kstep, voffB); PG8_STAGE(PG8_SA(1, 0), cA + kstep, voffA); PG8_STAGE(PG8_SB(1, 1), cB + hstepB + kstep, voffB);
;         PG8_WAIT_V(6); PG8_BAR;
.LBB0_341:
	s_load_dwordx2 s[0:1], s[94:95], 0xd0
	s_cmp_gt_i32 s52, 4
	s_waitcnt lgkmcnt(0)
	v_writelane_b32 v255, s0, 8
	s_nop 1
	v_writelane_b32 v255, s1, 9
	s_cselect_b64 s[0:1], -1, 0
	s_cmp_lt_i32 s53, 5
	s_cselect_b64 s[2:3], -1, 0
	s_or_b64 s[0:1], s[0:1], s[2:3]
	s_and_b64 vcc, exec, s[0:1]
	s_cbranch_vccnz .LBB0_410
	s_mov_b32 s99, 0
	s_cmpk_gt_i32 s73, 0x47f
	v_mbcnt_lo_u32_b32 v12, -1, 0
	v_mbcnt_hi_u32_b32 v12, -1, v12
	s_cbranch_scc1 .LBB0_360
	s_add_u32 s28, s70, 0xa704000
	s_addc_u32 s29, s71, 0
	s_add_u32 s30, s70, 0x5600000
	s_addc_u32 s31, s71, 0
	s_lshl_b32 s34, s33, 10
	v_lshl_add_u32 v0, v12, 4, s34
	v_add_u32_e32 v1, 0x2000, v0
	v_ashrrev_i32_e32 v2, 31, v1
	v_lshrrev_b32_e32 v2, 22, v2
	v_add_u32_e32 v2, v1, v2
	v_ashrrev_i32_e32 v8, 10, v2
	v_mul_i32_i24_e32 v2, 0x400, v8
	v_sub_u32_e32 v1, v1, v2
	v_lshrrev_b32_e32 v2, 4, v1
	v_bitop3_b32 v1, v2, v1, 32 bitop3:0x6c
	v_ashrrev_i32_e32 v2, 31, v1
	v_lshrrev_b32_e32 v2, 26, v2
	v_add_u32_e32 v2, v1, v2
	v_ashrrev_i32_e32 v9, 6, v2
	v_lshlrev_b32_e32 v3, 3, v8
	v_and_b32_e32 v2, 0xffc0, v2
	v_and_b32_e32 v3, -16, v3
	v_sub_u32_e32 v1, v1, v2
	v_add_u32_e32 v3, v9, v3
	v_lshrrev_b16_e32 v2, 7, v1
	v_and_b32_e32 v4, 3, v9
	s_mov_b32 s0, 0xfffe0
	v_lshrrev_b32_e32 v5, 2, v3
	v_lshlrev_b32_e32 v6, 1, v3
	v_and_b32_e32 v2, 1, v2
	v_and_or_b32 v4, v3, s0, v4
	v_and_b32_e32 v5, 4, v5
	v_and_b32_e32 v6, 24, v6
	v_add_u16_e32 v1, v1, v2
	v_mov_b32_e32 v2, 1
	v_or3_b32 v4, v4, v5, v6
	v_lshlrev_b32_e32 v5, 5, v8
	v_ashrrev_i16_sdwa v1, v2, sext(v1) dst_sel:DWORD dst_unused:UNUSED_PAD src0_sel:DWORD src1_sel:BYTE_0
	v_and_b32_e32 v10, 32, v5
	v_bfe_i32 v11, v1, 0, 16
	s_movk_i32 s3, 0x2800
	v_add_u32_e32 v1, v10, v11
	v_mul_lo_u32 v3, v3, s3
	v_lshlrev_b32_e32 v5, 1, v1
	v_add_lshl_u32 v146, v1, v3, 1
	v_ashrrev_i32_e32 v1, 31, v0
	v_lshrrev_b32_e32 v1, 22, v1
	v_add_u32_e32 v1, v0, v1
	v_ashrrev_i32_e32 v13, 10, v1
	v_mul_i32_i24_e32 v1, 0x400, v13
	v_sub_u32_e32 v0, v0, v1
	v_lshrrev_b32_e32 v1, 4, v0
	v_bitop3_b32 v0, v1, v0, 32 bitop3:0x6c
	v_ashrrev_i32_e32 v1, 31, v0
	v_lshrrev_b32_e32 v1, 26, v1
	v_add_u32_e32 v1, v0, v1
	v_lshlrev_b32_e32 v3, 3, v13
	v_ashrrev_i32_e32 v14, 6, v1
	v_and_b32_e32 v3, -16, v3
	v_lshl_add_u32 v144, v4, 12, v5
	v_add_u32_e32 v3, v14, v3
	v_and_b32_e32 v4, 3, v14
	s_ashr_i32 s35, s73, 31
	v_and_or_b32 v4, v3, s0, v4
	s_lshr_b32 s0, s35, 29
	s_add_i32 s0, s73, s0
	s_ashr_i32 s1, s0, 3
	s_and_b32 s0, s0, -8
	s_ashr_i32 s4, s33, 2
	s_sub_i32 s0, s73, s0
	s_cmp_lt_i32 s0, 0
	s_movk_i32 s36, 0x91
	s_cselect_b32 s2, s36, 0x90
	s_mul_i32 s0, s2, s0
	s_add_i32 s0, s0, s1
	s_ashr_i32 s1, s0, 31
	s_lshr_b32 s1, s1, 27
	s_add_i32 s1, s0, s1
	s_ashr_i32 s2, s1, 5
	s_andn2_b32 s1, s1, 31
	s_sub_i32 s0, s0, s1
	s_bfe_i32 s1, s0, 0x80000
	s_bfe_u32 s1, s1, 0x2000d
	s_add_i32 s1, s0, s1
	s_lshl_b32 s5, s2, 2
	s_bfe_i32 s2, s1, 0x80000
	s_and_b32 s1, s1, 0xfc
	v_lshrrev_b32_e32 v5, 2, v3
	v_lshlrev_b32_e32 v6, 1, v3
	v_and_b32_e32 v1, 0xc0, v1
	s_sext_i32_i16 s2, s2
	s_sub_i32 s0, s0, s1
	v_and_b32_e32 v5, 4, v5
	v_and_b32_e32 v6, 24, v6
	v_sub_u32_e32 v0, v0, v1
	s_lshr_b32 s2, s2, 2
	s_sext_i32_i8 s0, s0
	v_or3_b32 v4, v4, v5, v6
	v_lshlrev_b32_e32 v5, 5, v13
	v_ashrrev_i16_sdwa v0, v2, sext(v0) dst_sel:DWORD dst_unused:UNUSED_PAD src0_sel:DWORD src1_sel:BYTE_0
	s_add_i32 s20, s5, s0
	s_bfe_i64 s[0:1], s[2:3], 0x100000
	v_and_b32_e32 v15, 32, v5
	v_bfe_i32 v16, v0, 0, 16
	s_lshl_b64 s[0:1], s[0:1], 20
	v_add_u32_e32 v0, v15, v16
	s_add_u32 s24, s30, s0
	v_lshlrev_b32_e32 v1, 1, v0
	s_addc_u32 s25, s31, s1
	s_add_i32 s37, s34, 0
	v_lshl_add_u32 v148, v4, 12, v1
	s_add_i32 m0, s37, 0x10000
	s_mul_i32 s6, s20, 0x500000
	global_load_lds_dwordx4 v148, s[24:25]
	s_add_i32 m0, s37, 0x12000
	s_add_u32 s0, s24, 0x80000
	global_load_lds_dwordx4 v144, s[24:25]
	s_addc_u32 s1, s25, 0
	s_add_i32 m0, s37, 0x14000
	s_mul_hi_i32 s5, s20, 0x500000
	global_load_lds_dwordx4 v148, s[0:1]
	s_add_i32 m0, s37, 0x16000
	s_add_u32 s22, s28, s6
	v_mul_lo_u32 v1, v3, s3
	s_addc_u32 s23, s29, s5
	s_add_i32 s38, s37, 0x2000
	v_add_lshl_u32 v150, v0, v1, 1
	global_load_lds_dwordx4 v144, s[0:1]
	s_mov_b32 m0, s37
	s_add_u32 s0, s22, 0x280000
	global_load_lds_dwordx4 v150, s[22:23]
	s_mov_b32 m0, s38
	s_addc_u32 s1, s23, 0
	s_add_i32 s39, s37, 0x4000
	global_load_lds_dwordx4 v146, s[22:23]
	s_mov_b32 m0, s39
	s_add_i32 s40, s37, 0x6000
	global_load_lds_dwordx4 v150, s[0:1]
	s_mov_b32 m0, s40
	v_mov_b32_e32 v149, 0
	global_load_lds_dwordx4 v146, s[0:1]
	s_load_dwordx2 s[0:1], s[94:95], 0x0
	s_load_dwordx2 s[6:7], s[94:95], 0x10
	v_mov_b32_e32 v145, v149
	v_mov_b32_e32 v151, v149
	v_mov_b32_e32 v147, v149
	s_cmp_eq_u32 s4, 1
	s_mov_b32 s41, 0
	v_lshl_add_u64 v[6:7], s[24:25], 0, v[148:149]
	v_lshl_add_u64 v[2:3], s[24:25], 0, v[144:145]
	v_lshl_add_u64 v[0:1], s[22:23], 0, v[150:151]
	s_cselect_b64 s[8:9], -1, 0
	s_cmp_lg_u32 s4, 1
	v_lshl_add_u64 v[4:5], s[22:23], 0, v[146:147]
	s_cbranch_scc1 .LBB0_345
	s_barrier

;     __host__ __device__ bool next(int i, Unit& u) const { const bool ok = StaticOrder::next(i, u); u.pm = 0; u.pn = 0; return ok; }
; #define PG8_STAGE(bufoff, gbase, voff) do { _Pragma("unroll") for (int _i = 0; _i < 2; ++_i) \
;         __builtin_amdgcn_global_load_lds((const unsigned*)((const char*)(gbase) + (voff)[_i]), (PG8_LAS unsigned*)(lds + (bufoff) + ldsw + _i * 8192), 16, 0, 0); } while (0)
; #define PG8_LDA(dst, b, h) do { _Pragma("unroll") for (int m = 0; m < 4; ++m) _Pragma("unroll") for (int k = 0; k < 2; ++k) dst[m][k] = *(const PG8_LAS bf16x8*)(lds + PG8_SA(b, h) + aoff + m * 2048 + k * 1024); } while (0)
; #define PG8_LDB(dst, b, h) do { _Pragma("unroll") for (int n = 0; n < 2; ++n) _Pragma("unroll") for (int k = 0; k < 2; ++k) dst[n][k] = *(const PG8_LAS bf16x8*)(lds + PG8_SB(b, h) + boff + n * 2048 + k * 1024); } while (0)
; #define PG8_MMA(ai, bj, At, Bt) do { __builtin_amdgcn_s_setprio(1); _Pragma("unroll") for (int m = 0; m < 4; ++m) _Pragma("unroll") for (int n = 0; n < 2; ++n) _Pragma("unroll") for (int k = 0; k < 2; ++k) \
;         acc[ai][bj][m][n] = __builtin_amdgcn_mfma_f32_16x16x32_bf16(Bt[n][k], At[m][k], acc[ai][bj][m][n], 0, 0, 0); __builtin_amdgcn_s_setprio(0); } while (0)
; template <class Epi, class Sched, bool ALIGN_EPI = false, bool SP2 = false>
; __device__ __forceinline__ void gemm_phase(PG8_LAS unsigned char* lds, const Gemm g, const Sched& S, const Epi& E, const int wave_in) {
;     ...
;     for (;;) {
;         const bool has_next = S.next(ui + 1, nxt);
;         const char* nA = has_next ? (const char*)g.A + (size_t)nxt.pm * tstepA : cA; const char* nB = has_next ? (const char*)g.Bt + (size_t)nxt.pn * tstepB : cB;
;         for (int t = 0; t < nt; t += 2) {
;             const bool last = (t == nt - 2);
;             const char* a1 = cA + (size_t)(t + 1) * kstep;
;             const char* a2 = last ? nA : cA + (size_t)(t + 2) * kstep; const char* b2 = last ? nB : cB + (size_t)(t + 2) * kstep;
;             const char* a3 = a2 + kstep; const char* b3 = b2 + kstep;
;             if (last && has_next) S.a_ready(nxt);
;             if constexpr (SP2) {
;             PG8_LDB(B0, 0, 0); PG8_LDB(B1, 0, 1); PG8_SCHED; PG8_LDA(At, 0, 0); PG8_STAGE(PG8_SA(1, 1), a1 + hstepA, voffA);
;             PG8_WAIT_V(8); PG8_WAIT_L(0); PG8_BAR; PG8_MMA(0, 0, At, B0); PG8_MMA(0, 1, At, B1); PG8_BAR; PG8_SCHED;
.LBB0_352:
	s_ashr_i32 s15, s14, 31
	s_lshl_b64 s[18:19], s[14:15], 20
	s_add_u32 s18, s30, s18
	s_addc_u32 s19, s31, s19
	s_and_b64 s[4:5], s[4:5], exec
	s_cselect_b32 s15, s19, s25
	s_cselect_b32 s21, s18, s24
	s_add_u32 s51, s24, 0x100
	v_mov_b32_e32 v0, 0
	s_addc_u32 s52, s25, 0
	s_mov_b32 s53, -2
	v_mov_b32_e32 v1, v0
	v_mov_b32_e32 v2, v0
	v_mov_b32_e32 v3, v0
	v_mov_b32_e32 v4, v0
	v_mov_b32_e32 v5, v0
	v_mov_b32_e32 v6, v0
	v_mov_b32_e32 v7, v0
	v_mov_b32_e32 v8, v0
	v_mov_b32_e32 v9, v0
	v_mov_b32_e32 v10, v0
	v_mov_b32_e32 v11, v0
	v_mov_b32_e32 v16, v0
	v_mov_b32_e32 v17, v0
	v_mov_b32_e32 v18, v0
	v_mov_b32_e32 v19, v0
	v_mov_b32_e32 v24, v0
	v_mov_b32_e32 v25, v0
	v_mov_b32_e32 v26, v0
	v_mov_b32_e32 v27, v0
	v_mov_b32_e32 v32, v0
	v_mov_b32_e32 v33, v0
	v_mov_b32_e32 v34, v0
	v_mov_b32_e32 v35, v0
	v_mov_b32_e32 v40, v0
	v_mov_b32_e32 v41, v0
	v_mov_b32_e32 v42, v0
	v_mov_b32_e32 v43, v0
	v_mov_b32_e32 v48, v0
	v_mov_b32_e32 v49, v0
	v_mov_b32_e32 v50, v0
	v_mov_b32_e32 v51, v0
	v_mov_b32_e32 v12, v0
	v_mov_b32_e32 v13, v0
	v_mov_b32_e32 v14, v0
	v_mov_b32_e32 v15, v0
	v_mov_b32_e32 v20, v0
	v_mov_b32_e32 v21, v0
	v_mov_b32_e32 v22, v0
	v_mov_b32_e32 v23, v0
	v_mov_b32_e32 v28, v0
	v_mov_b32_e32 v29, v0
	v_mov_b32_e32 v30, v0
	v_mov_b32_e32 v31, v0
	v_mov_b32_e32 v36, v0
	v_mov_b32_e32 v37, v0
	v_mov_b32_e32 v38, v0
	v_mov_b32_e32 v39, v0
	v_mov_b32_e32 v44, v0
	v_mov_b32_e32 v45, v0
	v_mov_b32_e32 v46, v0
	v_mov_b32_e32 v47, v0
	v_mov_b32_e32 v52, v0
	v_mov_b32_e32 v53, v0
	v_mov_b32_e32 v54, v0
	v_mov_b32_e32 v55, v0
	v_mov_b32_e32 v56, v0
	v_mov_b32_e32 v57, v0
	v_mov_b32_e32 v58, v0
	v_mov_b32_e32 v59, v0
	v_mov_b32_e32 v60, v0
	v_mov_b32_e32 v61, v0
	v_mov_b32_e32 v62, v0
	v_mov_b32_e32 v63, v0
	v_mov_b32_e32 v64, v0
	v_mov_b32_e32 v65, v0
	v_mov_b32_e32 v66, v0
	v_mov_b32_e32 v67, v0
	v_mov_b32_e32 v68, v0
	v_mov_b32_e32 v69, v0
	v_mov_b32_e32 v70, v0
	v_mov_b32_e32 v71, v0
	v_mov_b32_e32 v72, v0
	v_mov_b32_e32 v73, v0
	v_mov_b32_e32 v74, v0
	v_mov_b32_e32 v75, v0
	v_mov_b32_e32 v80, v0
	v_mov_b32_e32 v81, v0
	v_mov_b32_e32 v82, v0
	v_mov_b32_e32 v83, v0
	v_mov_b32_e32 v96, v0
	v_mov_b32_e32 v97, v0
	v_mov_b32_e32 v98, v0
	v_mov_b32_e32 v99, v0
	v_mov_b32_e32 v100, v0
	v_mov_b32_e32 v101, v0
	v_mov_b32_e32 v102, v0
	v_mov_b32_e32 v103, v0
	v_mov_b32_e32 v104, v0
	v_mov_b32_e32 v105, v0
	v_mov_b32_e32 v106, v0
	v_mov_b32_e32 v107, v0
	v_mov_b32_e32 v108, v0
	v_mov_b32_e32 v109, v0
	v_mov_b32_e32 v110, v0
	v_mov_b32_e32 v111, v0
	v_mov_b32_e32 v76, v0
	v_mov_b32_e32 v77, v0
	v_mov_b32_e32 v78, v0
	v_mov_b32_e32 v79, v0
	v_mov_b32_e32 v84, v0
	v_mov_b32_e32 v85, v0
	v_mov_b32_e32 v86, v0
	v_mov_b32_e32 v87, v0
	v_mov_b32_e32 v88, v0
	v_mov_b32_e32 v89, v0
	v_mov_b32_e32 v90, v0
	v_mov_b32_e32 v91, v0
	v_mov_b32_e32 v92, v0
	v_mov_b32_e32 v93, v0
	v_mov_b32_e32 v94, v0
	v_mov_b32_e32 v95, v0
	v_mov_b32_e32 v112, v0
	v_mov_b32_e32 v113, v0
	v_mov_b32_e32 v114, v0
	v_mov_b32_e32 v115, v0
	v_mov_b32_e32 v116, v0
	v_mov_b32_e32 v117, v0
	v_mov_b32_e32 v118, v0
	v_mov_b32_e32 v119, v0
	v_mov_b32_e32 v120, v0
	v_mov_b32_e32 v121, v0
	v_mov_b32_e32 v122, v0
	v_mov_b32_e32 v123, v0
	v_mov_b32_e32 v124, v0
	v_mov_b32_e32 v125, v0
	v_mov_b32_e32 v126, v0
	v_mov_b32_e32 v127, v0
	s_cmp_lg_u32 s99, 0
	s_cbranch_scc0 .LBB0_353
	ds_read_b128 v[128:131], v168
	ds_read_b128 v[132:135], v168 offset:1024
	ds_read_b128 v[136:139], v168 offset:2048
	ds_read_b128 v[140:143], v168 offset:3072
	ds_read_b128 v[162:165], v169
	ds_read_b128 v[172:175], v169 offset:1024
	ds_read_b128 v[176:179], v169 offset:2048
	ds_read_b128 v[180:183], v169 offset:3072
	s_add_u32 s4, s22, 0x100
	s_addc_u32 s5, s23, 0
	s_cmp_eq_u32 s53, 28
	s_cselect_b32 s27, s17, s5
	s_cselect_b32 s26, s16, s4
	s_cselect_b32 s25, s15, s52
	s_cselect_b32 s24, s21, s51
	v_lshl_add_u64 v[216:217], s[22:23], 0, v[154:155]
	s_add_i32 m0, s37, 0xc000
	ds_read_b128 v[184:187], v170
	ds_read_b128 v[188:191], v170 offset:1024
	ds_read_b128 v[192:195], v170 offset:2048
	ds_read_b128 v[196:199], v170 offset:3072
	ds_read_b128 v[200:203], v170 offset:4096
	ds_read_b128 v[204:207], v170 offset:5120
	ds_read_b128 v[208:211], v170 offset:6144
	ds_read_b128 v[212:215], v170 offset:7168
	global_load_lds_dwordx4 v[216:217], off
	v_lshl_add_u64 v[216:217], s[22:23], 0, v[156:157]
	s_add_i32 m0, s37, 0xe000
	s_nop 0
	global_load_lds_dwordx4 v[216:217], off
	s_waitcnt vmcnt(24)
	s_waitcnt lgkmcnt(0)
	s_barrier
	s_setprio 1
	s_waitcnt lgkmcnt(0)
	v_mfma_f32_16x16x32_bf16 v[124:127], v[128:131], v[184:187], v[124:127]
	v_mfma_f32_16x16x32_bf16 v[120:123], v[136:139], v[184:187], v[120:123]
	v_mfma_f32_16x16x32_bf16 v[116:119], v[128:131], v[192:195], v[116:119]
	v_mfma_f32_16x16x32_bf16 v[112:115], v[136:139], v[192:195], v[112:115]
	v_mfma_f32_16x16x32_bf16 v[92:95], v[128:131], v[200:203], v[92:95]
	v_mfma_f32_16x16x32_bf16 v[88:91], v[136:139], v[200:203], v[88:91]
	v_mfma_f32_16x16x32_bf16 v[84:87], v[128:131], v[208:211], v[84:87]
	v_mfma_f32_16x16x32_bf16 v[76:79], v[136:139], v[208:211], v[76:79]
	v_mfma_f32_16x16x32_bf16 v[124:127], v[132:135], v[188:191], v[124:127]
	v_mfma_f32_16x16x32_bf16 v[120:123], v[140:143], v[188:191], v[120:123]
	v_mfma_f32_16x16x32_bf16 v[116:119], v[132:135], v[196:199], v[116:119]
	v_mfma_f32_16x16x32_bf16 v[112:115], v[140:143], v[196:199], v[112:115]
	v_mfma_f32_16x16x32_bf16 v[92:95], v[132:135], v[204:207], v[92:95]
	v_mfma_f32_16x16x32_bf16 v[88:91], v[140:143], v[204:207], v[88:91]
	v_mfma_f32_16x16x32_bf16 v[84:87], v[132:135], v[212:215], v[84:87]
	v_mfma_f32_16x16x32_bf16 v[76:79], v[140:143], v[212:215], v[76:79]
	s_setprio 0
	s_setprio 1
	v_mfma_f32_16x16x32_bf16 v[108:111], v[162:165], v[184:187], v[108:111]
	v_mfma_f32_16x16x32_bf16 v[104:107], v[176:179], v[184:187], v[104:107]
	v_mfma_f32_16x16x32_bf16 v[100:103], v[162:165], v[192:195], v[100:103]
	v_mfma_f32_16x16x32_bf16 v[96:99], v[176:179], v[192:195], v[96:99]
	v_mfma_f32_16x16x32_bf16 v[80:83], v[162:165], v[200:203], v[80:83]
	v_mfma_f32_16x16x32_bf16 v[72:75], v[176:179], v[200:203], v[72:75]
	v_mfma_f32_16x16x32_bf16 v[68:71], v[162:165], v[208:211], v[68:71]
	v_mfma_f32_16x16x32_bf16 v[64:67], v[176:179], v[208:211], v[64:67]
	v_mfma_f32_16x16x32_bf16 v[108:111], v[172:175], v[188:191], v[108:111]
	v_mfma_f32_16x16x32_bf16 v[104:107], v[180:183], v[188:191], v[104:107]
	v_mfma_f32_16x16x32_bf16 v[100:103], v[172:175], v[196:199], v[100:103]
	v_mfma_f32_16x16x32_bf16 v[96:99], v[180:183], v[196:199], v[96:99]
	v_mfma_f32_16x16x32_bf16 v[80:83], v[172:175], v[204:207], v[80:83]
	v_mfma_f32_16x16x32_bf16 v[72:75], v[180:183], v[204:207], v[72:75]
	v_mfma_f32_16x16x32_bf16 v[68:71], v[172:175], v[212:215], v[68:71]
	v_mfma_f32_16x16x32_bf16 v[64:67], v[180:183], v[212:215], v[64:67]
	s_setprio 0
	s_barrier
; #define PG8_STAGE(bufoff, gbase, voff) do { _Pragma("unroll") for (int _i = 0; _i < 2; ++_i) \
;         __builtin_amdgcn_global_load_lds((const unsigned*)((const char*)(gbase) + (voff)[_i]), (PG8_LAS unsigned*)(lds + (bufoff) + ldsw + _i * 8192), 16, 0, 0); } while (0)
; #define PG8_LDA(dst, b, h) do { _Pragma("unroll") for (int m = 0; m < 4; ++m) _Pragma("unroll") for (int k = 0; k < 2; ++k) dst[m][k] = *(const PG8_LAS bf16x8*)(lds + PG8_SA(b, h) + aoff + m * 2048 + k * 1024); } while (0)
; #define PG8_LDB(dst, b, h) do { _Pragma("unroll") for (int n = 0; n < 2; ++n) _Pragma("unroll") for (int k = 0; k < 2; ++k) dst[n][k] = *(const PG8_LAS bf16x8*)(lds + PG8_SB(b, h) + boff + n * 2048 + k * 1024); } while (0)
; #define PG8_MMA(ai, bj, At, Bt) do { __builtin_amdgcn_s_setprio(1); _Pragma("unroll") for (int m = 0; m < 4; ++m) _Pragma("unroll") for (int n = 0; n < 2; ++n) _Pragma("unroll") for (int k = 0; k < 2; ++k) \
;         acc[ai][bj][m][n] = __builtin_amdgcn_mfma_f32_16x16x32_bf16(Bt[n][k], At[m][k], acc[ai][bj][m][n], 0, 0, 0); __builtin_amdgcn_s_setprio(0); } while (0)
; #define PG8_WAIT_V(n) asm volatile("s_waitcnt vmcnt(" #n ")" ::: "memory")
; #define PG8_WAIT_L(n) asm volatile("s_waitcnt lgkmcnt(" #n ")" ::: "memory")
; #define PG8_BAR __builtin_amdgcn_s_barrier()
; #define PG8_SCHED __builtin_amdgcn_sched_barrier(0)
; template <class Epi, class Sched, bool ALIGN_EPI = false, bool SP2 = false>
; __device__ __forceinline__ void gemm_phase(PG8_LAS unsigned char* lds, const Gemm g, const Sched& S, const Epi& E, const int wave_in) {
;     ...
;             PG8_LDA(At, 0, 1); PG8_STAGE(PG8_SB(0, 0), b2, voffB); PG8_STAGE(PG8_SB(0, 1), b2 + hstepB, voffB); PG8_STAGE(PG8_SA(0, 0), a2, voffA);
;             PG8_WAIT_V(8); PG8_WAIT_L(0); PG8_BAR; PG8_MMA(1, 0, At, B0); PG8_MMA(1, 1, At, B1); PG8_BAR; PG8_SCHED;
;             PG8_LDB(B0, 1, 0); PG8_LDB(B1, 1, 1); PG8_SCHED; PG8_LDA(At, 1, 0); PG8_STAGE(PG8_SA(0, 1), a2 + hstepA, voffA);
;             PG8_WAIT_V(8); PG8_WAIT_L(0); PG8_BAR; PG8_MMA(0, 0, At, B0); PG8_MMA(0, 1, At, B1); PG8_BAR; PG8_SCHED;
	s_add_i32 s22, s47, s34
	v_lshl_add_u64 v[216:217], s[24:25], 0, v[148:149]
	s_mov_b32 m0, s22
	ds_read_b128 v[184:187], v170 offset:16384
	ds_read_b128 v[188:191], v170 offset:17408
	ds_read_b128 v[192:195], v170 offset:18432
	ds_read_b128 v[196:199], v170 offset:19456
	ds_read_b128 v[200:203], v170 offset:20480
	ds_read_b128 v[204:207], v170 offset:21504
	ds_read_b128 v[208:211], v170 offset:22528
	ds_read_b128 v[212:215], v170 offset:23552
	global_load_lds_dwordx4 v[216:217], off
	s_add_i32 m0, s22, 0x2000
	s_add_u32 s22, s24, 0x80000
	v_lshl_add_u64 v[218:219], s[24:25], 0, v[144:145]
	s_addc_u32 s23, s25, 0
	s_add_i32 s54, s48, s34
	global_load_lds_dwordx4 v[218:219], off
	v_lshl_add_u64 v[220:221], s[22:23], 0, v[148:149]
	s_mov_b32 m0, s54
	v_lshl_add_u64 v[222:223], s[26:27], 0, v[146:147]
	global_load_lds_dwordx4 v[220:221], off
	v_lshl_add_u64 v[220:221], s[22:23], 0, v[144:145]
	s_add_i32 m0, s54, 0x2000
	s_nop 0
	global_load_lds_dwordx4 v[220:221], off
	v_lshl_add_u64 v[220:221], s[26:27], 0, v[150:151]
	s_mov_b32 m0, s37
	s_nop 0
	global_load_lds_dwordx4 v[220:221], off
	s_mov_b32 m0, s38
	s_nop 0
	global_load_lds_dwordx4 v[222:223], off
	s_waitcnt vmcnt(24)
	s_waitcnt lgkmcnt(0)
	s_barrier
	s_setprio 1
	s_waitcnt lgkmcnt(0)
	v_mfma_f32_16x16x32_bf16 v[60:63], v[128:131], v[184:187], v[60:63]
	v_mfma_f32_16x16x32_bf16 v[56:59], v[136:139], v[184:187], v[56:59]
	v_mfma_f32_16x16x32_bf16 v[52:55], v[128:131], v[192:195], v[52:55]
	v_mfma_f32_16x16x32_bf16 v[44:47], v[136:139], v[192:195], v[44:47]
	v_mfma_f32_16x16x32_bf16 v[36:39], v[128:131], v[200:203], v[36:39]
	v_mfma_f32_16x16x32_bf16 v[28:31], v[136:139], v[200:203], v[28:31]
	v_mfma_f32_16x16x32_bf16 v[20:23], v[128:131], v[208:211], v[20:23]
	v_mfma_f32_16x16x32_bf16 v[12:15], v[136:139], v[208:211], v[12:15]
	v_mfma_f32_16x16x32_bf16 v[60:63], v[132:135], v[188:191], v[60:63]
	v_mfma_f32_16x16x32_bf16 v[56:59], v[140:143], v[188:191], v[56:59]
	v_mfma_f32_16x16x32_bf16 v[52:55], v[132:135], v[196:199], v[52:55]
	v_mfma_f32_16x16x32_bf16 v[44:47], v[140:143], v[196:199], v[44:47]
	v_mfma_f32_16x16x32_bf16 v[36:39], v[132:135], v[204:207], v[36:39]
	v_mfma_f32_16x16x32_bf16 v[28:31], v[140:143], v[204:207], v[28:31]
	v_mfma_f32_16x16x32_bf16 v[20:23], v[132:135], v[212:215], v[20:23]
	v_mfma_f32_16x16x32_bf16 v[12:15], v[140:143], v[212:215], v[12:15]
	s_setprio 0
	s_setprio 1
	v_mfma_f32_16x16x32_bf16 v[48:51], v[162:165], v[184:187], v[48:51]
	v_mfma_f32_16x16x32_bf16 v[40:43], v[176:179], v[184:187], v[40:43]
	v_mfma_f32_16x16x32_bf16 v[32:35], v[162:165], v[192:195], v[32:35]
	v_mfma_f32_16x16x32_bf16 v[24:27], v[176:179], v[192:195], v[24:27]
	v_mfma_f32_16x16x32_bf16 v[16:19], v[162:165], v[200:203], v[16:19]
	v_mfma_f32_16x16x32_bf16 v[8:11], v[176:179], v[200:203], v[8:11]
	v_mfma_f32_16x16x32_bf16 v[4:7], v[162:165], v[208:211], v[4:7]
	v_mfma_f32_16x16x32_bf16 v[0:3], v[176:179], v[208:211], v[0:3]
	v_mfma_f32_16x16x32_bf16 v[48:51], v[172:175], v[188:191], v[48:51]
	v_mfma_f32_16x16x32_bf16 v[40:43], v[180:183], v[188:191], v[40:43]
	v_mfma_f32_16x16x32_bf16 v[32:35], v[172:175], v[196:199], v[32:35]
	v_mfma_f32_16x16x32_bf16 v[24:27], v[180:183], v[196:199], v[24:27]
	v_mfma_f32_16x16x32_bf16 v[16:19], v[172:175], v[204:207], v[16:19]
	v_mfma_f32_16x16x32_bf16 v[8:11], v[180:183], v[204:207], v[8:11]
	v_mfma_f32_16x16x32_bf16 v[4:7], v[172:175], v[212:215], v[4:7]
	v_mfma_f32_16x16x32_bf16 v[0:3], v[180:183], v[212:215], v[0:3]
	s_setprio 0
	s_barrier
	s_add_i32 s54, 0, 0x18000
	s_add_i32 s55, 0, 0x1c000
	v_add_u32_e32 v140, s54, v166
	v_add_u32_e32 v171, s55, v166
	ds_read_b128 v[128:131], v140
	ds_read_b128 v[132:135], v140 offset:1024
	ds_read_b128 v[136:139], v140 offset:2048
	ds_read_b128 v[140:143], v140 offset:3072
	ds_read_b128 v[162:165], v171
	ds_read_b128 v[172:175], v171 offset:1024
	ds_read_b128 v[176:179], v171 offset:2048
	ds_read_b128 v[180:183], v171 offset:3072
	s_add_u32 s22, s26, 0x280000
	s_addc_u32 s23, s27, 0
	s_mov_b32 m0, s39
	v_lshl_add_u64 v[224:225], s[22:23], 0, v[150:151]
	ds_read_b128 v[184:187], v170 offset:32768
	ds_read_b128 v[188:191], v170 offset:33792
	ds_read_b128 v[192:195], v170 offset:34816
	ds_read_b128 v[196:199], v170 offset:35840
	ds_read_b128 v[200:203], v170 offset:36864
	ds_read_b128 v[204:207], v170 offset:37888
	ds_read_b128 v[208:211], v170 offset:38912
	ds_read_b128 v[212:215], v170 offset:39936
	global_load_lds_dwordx4 v[224:225], off
	v_lshl_add_u64 v[224:225], s[22:23], 0, v[146:147]
	s_mov_b32 m0, s40
	s_nop 0
	global_load_lds_dwordx4 v[224:225], off
	s_waitcnt vmcnt(8)
	s_waitcnt lgkmcnt(0)
	s_barrier
; #define PG8_STAGE(bufoff, gbase, voff) do { _Pragma("unroll") for (int _i = 0; _i < 2; ++_i) \
;         __builtin_amdgcn_global_load_lds((const unsigned*)((const char*)(gbase) + (voff)[_i]), (PG8_LAS unsigned*)(lds + (bufoff) + ldsw + _i * 8192), 16, 0, 0); } while (0)
; #define PG8_LDA(dst, b, h) do { _Pragma("unroll") for (int m = 0; m < 4; ++m) _Pragma("unroll") for (int k = 0; k < 2; ++k) dst[m][k] = *(const PG8_LAS bf16x8*)(lds + PG8_SA(b, h) + aoff + m * 2048 + k * 1024); } while (0)
; #define PG8_MMA(ai, bj, At, Bt) do { __builtin_amdgcn_s_setprio(1); _Pragma("unroll") for (int m = 0; m < 4; ++m) _Pragma("unroll") for (int n = 0; n < 2; ++n) _Pragma("unroll") for (int k = 0; k < 2; ++k) \
;         acc[ai][bj][m][n] = __builtin_amdgcn_mfma_f32_16x16x32_bf16(Bt[n][k], At[m][k], acc[ai][bj][m][n], 0, 0, 0); __builtin_amdgcn_s_setprio(0); } while (0)
; #define PG8_WAIT_V(n) asm volatile("s_waitcnt vmcnt(" #n ")" ::: "memory")
; #define PG8_WAIT_L(n) asm volatile("s_waitcnt lgkmcnt(" #n ")" ::: "memory")
; #define PG8_BAR __builtin_amdgcn_s_barrier()
; #define PG8_SCHED __builtin_amdgcn_sched_barrier(0)
; template <class Epi, class Sched, bool ALIGN_EPI = false, bool SP2 = false>
; __device__ __forceinline__ void gemm_phase(PG8_LAS unsigned char* lds, const Gemm g, const Sched& S, const Epi& E, const int wave_in) {
;     ...
;             PG8_WAIT_V(8); PG8_WAIT_L(0); PG8_BAR; PG8_MMA(0, 0, At, B0); PG8_MMA(0, 1, At, B1); PG8_BAR; PG8_SCHED;
;             PG8_LDA(At, 1, 1); PG8_STAGE(PG8_SB(1, 0), b3, voffB); PG8_STAGE(PG8_SB(1, 1), b3 + hstepB, voffB); PG8_STAGE(PG8_SA(1, 0), a3, voffA);
;             PG8_WAIT_V(8); PG8_WAIT_L(0); PG8_BAR; PG8_MMA(1, 0, At, B0); PG8_MMA(1, 1, At, B1); PG8_BAR; PG8_SCHED;
	s_setprio 1
	s_waitcnt lgkmcnt(0)
	v_mfma_f32_16x16x32_bf16 v[124:127], v[128:131], v[184:187], v[124:127]
	v_mfma_f32_16x16x32_bf16 v[120:123], v[136:139], v[184:187], v[120:123]
	v_mfma_f32_16x16x32_bf16 v[116:119], v[128:131], v[192:195], v[116:119]
	v_mfma_f32_16x16x32_bf16 v[112:115], v[136:139], v[192:195], v[112:115]
	v_mfma_f32_16x16x32_bf16 v[92:95], v[128:131], v[200:203], v[92:95]
	v_mfma_f32_16x16x32_bf16 v[88:91], v[136:139], v[200:203], v[88:91]
	v_mfma_f32_16x16x32_bf16 v[84:87], v[128:131], v[208:211], v[84:87]
	v_mfma_f32_16x16x32_bf16 v[76:79], v[136:139], v[208:211], v[76:79]
	v_mfma_f32_16x16x32_bf16 v[124:127], v[132:135], v[188:191], v[124:127]
	v_mfma_f32_16x16x32_bf16 v[120:123], v[140:143], v[188:191], v[120:123]
	v_mfma_f32_16x16x32_bf16 v[116:119], v[132:135], v[196:199], v[116:119]
	v_mfma_f32_16x16x32_bf16 v[112:115], v[140:143], v[196:199], v[112:115]
	v_mfma_f32_16x16x32_bf16 v[92:95], v[132:135], v[204:207], v[92:95]
	v_mfma_f32_16x16x32_bf16 v[88:91], v[140:143], v[204:207], v[88:91]
	v_mfma_f32_16x16x32_bf16 v[84:87], v[132:135], v[212:215], v[84:87]
	v_mfma_f32_16x16x32_bf16 v[76:79], v[140:143], v[212:215], v[76:79]
	s_setprio 0
	s_setprio 1
	v_mfma_f32_16x16x32_bf16 v[108:111], v[162:165], v[184:187], v[108:111]
	v_mfma_f32_16x16x32_bf16 v[104:107], v[176:179], v[184:187], v[104:107]
	v_mfma_f32_16x16x32_bf16 v[100:103], v[162:165], v[192:195], v[100:103]
	v_mfma_f32_16x16x32_bf16 v[96:99], v[176:179], v[192:195], v[96:99]
	v_mfma_f32_16x16x32_bf16 v[80:83], v[162:165], v[200:203], v[80:83]
	v_mfma_f32_16x16x32_bf16 v[72:75], v[176:179], v[200:203], v[72:75]
	v_mfma_f32_16x16x32_bf16 v[68:71], v[162:165], v[208:211], v[68:71]
	v_mfma_f32_16x16x32_bf16 v[64:67], v[176:179], v[208:211], v[64:67]
	v_mfma_f32_16x16x32_bf16 v[108:111], v[172:175], v[188:191], v[108:111]
	v_mfma_f32_16x16x32_bf16 v[104:107], v[180:183], v[188:191], v[104:107]
	v_mfma_f32_16x16x32_bf16 v[100:103], v[172:175], v[196:199], v[100:103]
	v_mfma_f32_16x16x32_bf16 v[96:99], v[180:183], v[196:199], v[96:99]
	v_mfma_f32_16x16x32_bf16 v[80:83], v[172:175], v[204:207], v[80:83]
	v_mfma_f32_16x16x32_bf16 v[72:75], v[180:183], v[204:207], v[72:75]
	v_mfma_f32_16x16x32_bf16 v[68:71], v[172:175], v[212:215], v[68:71]
	v_mfma_f32_16x16x32_bf16 v[64:67], v[180:183], v[212:215], v[64:67]
	s_setprio 0
	s_barrier
	s_add_i32 s22, s54, s34
	v_lshl_add_u64 v[216:217], v[216:217], 0, s[10:11]
	s_mov_b32 m0, s22
	ds_read_b128 v[184:187], v170 offset:49152
	ds_read_b128 v[188:191], v170 offset:50176
	ds_read_b128 v[192:195], v170 offset:51200
	ds_read_b128 v[196:199], v170 offset:52224
	ds_read_b128 v[200:203], v170 offset:53248
	ds_read_b128 v[204:207], v170 offset:54272
	ds_read_b128 v[208:211], v170 offset:55296
	ds_read_b128 v[212:215], v170 offset:56320
	global_load_lds_dwordx4 v[216:217], off
	s_add_i32 m0, s22, 0x2000
	s_add_u32 s22, s24, 0x80080
	v_lshl_add_u64 v[216:217], v[218:219], 0, s[10:11]
	s_addc_u32 s23, s25, 0
	s_add_i32 s24, s55, s34
	global_load_lds_dwordx4 v[216:217], off
	v_lshl_add_u64 v[216:217], s[22:23], 0, v[148:149]
	s_mov_b32 m0, s24
	s_nop 0
	global_load_lds_dwordx4 v[216:217], off
	v_lshl_add_u64 v[216:217], s[22:23], 0, v[144:145]
	s_add_i32 m0, s24, 0x2000
	s_nop 0
	global_load_lds_dwordx4 v[216:217], off
	v_lshl_add_u64 v[216:217], v[220:221], 0, s[10:11]
	s_mov_b32 m0, s44
	s_nop 0
	global_load_lds_dwordx4 v[216:217], off
	v_lshl_add_u64 v[216:217], v[222:223], 0, s[10:11]
	s_mov_b32 m0, s45
	s_nop 0
	global_load_lds_dwordx4 v[216:217], off
	s_waitcnt vmcnt(8)
	s_waitcnt lgkmcnt(0)
	s_barrier
	s_setprio 1
	s_waitcnt lgkmcnt(0)
	v_mfma_f32_16x16x32_bf16 v[60:63], v[128:131], v[184:187], v[60:63]
	v_mfma_f32_16x16x32_bf16 v[56:59], v[136:139], v[184:187], v[56:59]
	v_mfma_f32_16x16x32_bf16 v[52:55], v[128:131], v[192:195], v[52:55]
	v_mfma_f32_16x16x32_bf16 v[44:47], v[136:139], v[192:195], v[44:47]
	v_mfma_f32_16x16x32_bf16 v[36:39], v[128:131], v[200:203], v[36:39]
	v_mfma_f32_16x16x32_bf16 v[28:31], v[136:139], v[200:203], v[28:31]
	v_mfma_f32_16x16x32_bf16 v[20:23], v[128:131], v[208:211], v[20:23]
	v_mfma_f32_16x16x32_bf16 v[12:15], v[136:139], v[208:211], v[12:15]
	v_mfma_f32_16x16x32_bf16 v[60:63], v[132:135], v[188:191], v[60:63]
	v_mfma_f32_16x16x32_bf16 v[56:59], v[140:143], v[188:191], v[56:59]
	v_mfma_f32_16x16x32_bf16 v[52:55], v[132:135], v[196:199], v[52:55]
	v_mfma_f32_16x16x32_bf16 v[44:47], v[140:143], v[196:199], v[44:47]
	v_mfma_f32_16x16x32_bf16 v[36:39], v[132:135], v[204:207], v[36:39]
	v_mfma_f32_16x16x32_bf16 v[28:31], v[140:143], v[204:207], v[28:31]
	v_mfma_f32_16x16x32_bf16 v[20:23], v[132:135], v[212:215], v[20:23]
	v_mfma_f32_16x16x32_bf16 v[12:15], v[140:143], v[212:215], v[12:15]
	s_setprio 0
	s_setprio 1
	v_mfma_f32_16x16x32_bf16 v[48:51], v[162:165], v[184:187], v[48:51]
	v_mfma_f32_16x16x32_bf16 v[40:43], v[176:179], v[184:187], v[40:43]
	v_mfma_f32_16x16x32_bf16 v[32:35], v[162:165], v[192:195], v[32:35]
	v_mfma_f32_16x16x32_bf16 v[24:27], v[176:179], v[192:195], v[24:27]
	v_mfma_f32_16x16x32_bf16 v[16:19], v[162:165], v[200:203], v[16:19]
	v_mfma_f32_16x16x32_bf16 v[8:11], v[176:179], v[200:203], v[8:11]
	v_mfma_f32_16x16x32_bf16 v[4:7], v[162:165], v[208:211], v[4:7]
	v_mfma_f32_16x16x32_bf16 v[0:3], v[176:179], v[208:211], v[0:3]
	v_mfma_f32_16x16x32_bf16 v[48:51], v[172:175], v[188:191], v[48:51]
	v_mfma_f32_16x16x32_bf16 v[40:43], v[180:183], v[188:191], v[40:43]
	v_mfma_f32_16x16x32_bf16 v[32:35], v[172:175], v[196:199], v[32:35]
	v_mfma_f32_16x16x32_bf16 v[24:27], v[180:183], v[196:199], v[24:27]
	v_mfma_f32_16x16x32_bf16 v[16:19], v[172:175], v[204:207], v[16:19]
	v_mfma_f32_16x16x32_bf16 v[8:11], v[180:183], v[204:207], v[8:11]
	v_mfma_f32_16x16x32_bf16 v[4:7], v[172:175], v[212:215], v[4:7]
	v_mfma_f32_16x16x32_bf16 v[0:3], v[180:183], v[212:215], v[0:3]
	s_setprio 0
	s_barrier
	s_add_i32 s53, s53, 2
	s_add_u32 s51, s51, 0x100
	s_addc_u32 s52, s52, 0
	s_cmp_gt_u32 s53, 29
	s_mov_b64 s[22:23], s[4:5]
	s_cbranch_scc0 .LBB0_353
; #define PG8_STAGE(bufoff, gbase, voff) do { _Pragma("unroll") for (int _i = 0; _i < 2; ++_i) \
;         __builtin_amdgcn_global_load_lds((const unsigned*)((const char*)(gbase) + (voff)[_i]), (PG8_LAS unsigned*)(lds + (bufoff) + ldsw + _i * 8192), 16, 0, 0); } while (0)
; #define PG8_LDA(dst, b, h) do { _Pragma("unroll") for (int m = 0; m < 4; ++m) _Pragma("unroll") for (int k = 0; k < 2; ++k) dst[m][k] = *(const PG8_LAS bf16x8*)(lds + PG8_SA(b, h) + aoff + m * 2048 + k * 1024); } while (0)
; #define PG8_LDB(dst, b, h) do { _Pragma("unroll") for (int n = 0; n < 2; ++n) _Pragma("unroll") for (int k = 0; k < 2; ++k) dst[n][k] = *(const PG8_LAS bf16x8*)(lds + PG8_SB(b, h) + boff + n * 2048 + k * 1024); } while (0)
; #define PG8_MMA(ai, bj, At, Bt) do { __builtin_amdgcn_s_setprio(1); _Pragma("unroll") for (int m = 0; m < 4; ++m) _Pragma("unroll") for (int n = 0; n < 2; ++n) _Pragma("unroll") for (int k = 0; k < 2; ++k) \
;         acc[ai][bj][m][n] = __builtin_amdgcn_mfma_f32_16x16x32_bf16(Bt[n][k], At[m][k], acc[ai][bj][m][n], 0, 0, 0); __builtin_amdgcn_s_setprio(0); } while (0)
; #define PG8_WAIT_V(n) asm volatile("s_waitcnt vmcnt(" #n ")" ::: "memory")
; #define PG8_BAR __builtin_amdgcn_s_barrier()
; template <class Epi, class Sched, bool ALIGN_EPI = false, bool SP2 = false>
; __device__ __forceinline__ void gemm_phase(PG8_LAS unsigned char* lds, const Gemm g, const Sched& S, const Epi& E, const int wave_in) {
;     ...
;         for (int t = 0; t < nt; t += 2) {
;             const bool last = (t == nt - 2);
;             const char* a1 = cA + (size_t)(t + 1) * kstep;
;             const char* a2 = last ? nA : cA + (size_t)(t + 2) * kstep; const char* b2 = last ? nB : cB + (size_t)(t + 2) * kstep;
;             const char* a3 = a2 + kstep; const char* b3 = b2 + kstep;
;             if (last && has_next) S.a_ready(nxt);
;             if constexpr (SP2) {
;             PG8_LDB(B0, 0, 0); PG8_LDB(B1, 0, 1); PG8_SCHED; PG8_LDA(At, 0, 0); PG8_STAGE(PG8_SA(1, 1), a1 + hstepA, voffA);
;             PG8_WAIT_V(8); PG8_WAIT_L(0); PG8_BAR; PG8_MMA(0, 0, At, B0); PG8_MMA(0, 1, At, B1); PG8_BAR; PG8_SCHED;
;             PG8_LDA(At, 0, 1); PG8_STAGE(PG8_SB(0, 0), b2, voffB); PG8_STAGE(PG8_SB(0, 1), b2 + hstepB, voffB); PG8_STAGE(PG8_SA(0, 0), a2, voffA);
;             PG8_WAIT_V(8); PG8_WAIT_L(0); PG8_BAR; PG8_MMA(1, 0, At, B0); PG8_MMA(1, 1, At, B1); PG8_BAR; PG8_SCHED;
.LBB0_353:
	ds_read_b128 v[128:131], v168
	ds_read_b128 v[132:135], v168 offset:1024
	ds_read_b128 v[136:139], v168 offset:2048
	ds_read_b128 v[140:143], v168 offset:3072
	ds_read_b128 v[162:165], v169
	ds_read_b128 v[172:175], v169 offset:1024
	ds_read_b128 v[176:179], v169 offset:2048
	ds_read_b128 v[180:183], v169 offset:3072
	s_add_u32 s4, s22, 0x100
	s_addc_u32 s5, s23, 0
	s_cmp_eq_u32 s53, 28
	s_cselect_b32 s27, s17, s5
	s_cselect_b32 s26, s16, s4
	s_cselect_b32 s25, s15, s52
	s_cselect_b32 s24, s21, s51
	v_lshl_add_u64 v[216:217], s[22:23], 0, v[154:155]
	s_add_i32 m0, s37, 0xc000
	ds_read_b128 v[184:187], v170
	ds_read_b128 v[188:191], v170 offset:1024
	ds_read_b128 v[192:195], v170 offset:2048
	ds_read_b128 v[196:199], v170 offset:3072
	ds_read_b128 v[200:203], v170 offset:4096
	ds_read_b128 v[204:207], v170 offset:5120
	ds_read_b128 v[208:211], v170 offset:6144
	ds_read_b128 v[212:215], v170 offset:7168
	global_load_lds_dwordx4 v[216:217], off
	v_lshl_add_u64 v[216:217], s[22:23], 0, v[156:157]
	s_add_i32 m0, s37, 0xe000
	s_nop 0
	global_load_lds_dwordx4 v[216:217], off
	s_waitcnt vmcnt(8)
	s_waitcnt lgkmcnt(0)
	s_barrier
	s_setprio 1
	s_waitcnt lgkmcnt(0)
	v_mfma_f32_16x16x32_bf16 v[124:127], v[128:131], v[184:187], v[124:127]
	v_mfma_f32_16x16x32_bf16 v[120:123], v[136:139], v[184:187], v[120:123]
	v_mfma_f32_16x16x32_bf16 v[116:119], v[128:131], v[192:195], v[116:119]
	v_mfma_f32_16x16x32_bf16 v[112:115], v[136:139], v[192:195], v[112:115]
	v_mfma_f32_16x16x32_bf16 v[92:95], v[128:131], v[200:203], v[92:95]
	v_mfma_f32_16x16x32_bf16 v[88:91], v[136:139], v[200:203], v[88:91]
	v_mfma_f32_16x16x32_bf16 v[84:87], v[128:131], v[208:211], v[84:87]
	v_mfma_f32_16x16x32_bf16 v[76:79], v[136:139], v[208:211], v[76:79]
	v_mfma_f32_16x16x32_bf16 v[124:127], v[132:135], v[188:191], v[124:127]
	v_mfma_f32_16x16x32_bf16 v[120:123], v[140:143], v[188:191], v[120:123]
	v_mfma_f32_16x16x32_bf16 v[116:119], v[132:135], v[196:199], v[116:119]
	v_mfma_f32_16x16x32_bf16 v[112:115], v[140:143], v[196:199], v[112:115]
	v_mfma_f32_16x16x32_bf16 v[92:95], v[132:135], v[204:207], v[92:95]
	v_mfma_f32_16x16x32_bf16 v[88:91], v[140:143], v[204:207], v[88:91]
	v_mfma_f32_16x16x32_bf16 v[84:87], v[132:135], v[212:215], v[84:87]
	v_mfma_f32_16x16x32_bf16 v[76:79], v[140:143], v[212:215], v[76:79]
	s_setprio 0
	s_setprio 1
	v_mfma_f32_16x16x32_bf16 v[108:111], v[162:165], v[184:187], v[108:111]
	v_mfma_f32_16x16x32_bf16 v[104:107], v[176:179], v[184:187], v[104:107]
	v_mfma_f32_16x16x32_bf16 v[100:103], v[162:165], v[192:195], v[100:103]
	v_mfma_f32_16x16x32_bf16 v[96:99], v[176:179], v[192:195], v[96:99]
	v_mfma_f32_16x16x32_bf16 v[80:83], v[162:165], v[200:203], v[80:83]
	v_mfma_f32_16x16x32_bf16 v[72:75], v[176:179], v[200:203], v[72:75]
	v_mfma_f32_16x16x32_bf16 v[68:71], v[162:165], v[208:211], v[68:71]
	v_mfma_f32_16x16x32_bf16 v[64:67], v[176:179], v[208:211], v[64:67]
	v_mfma_f32_16x16x32_bf16 v[108:111], v[172:175], v[188:191], v[108:111]
	v_mfma_f32_16x16x32_bf16 v[104:107], v[180:183], v[188:191], v[104:107]
	v_mfma_f32_16x16x32_bf16 v[100:103], v[172:175], v[196:199], v[100:103]
	v_mfma_f32_16x16x32_bf16 v[96:99], v[180:183], v[196:199], v[96:99]
	v_mfma_f32_16x16x32_bf16 v[80:83], v[172:175], v[204:207], v[80:83]
	v_mfma_f32_16x16x32_bf16 v[72:75], v[180:183], v[204:207], v[72:75]
	v_mfma_f32_16x16x32_bf16 v[68:71], v[172:175], v[212:215], v[68:71]
	v_mfma_f32_16x16x32_bf16 v[64:67], v[180:183], v[212:215], v[64:67]
	s_setprio 0
	s_barrier
	s_add_i32 s22, s47, s34
	v_lshl_add_u64 v[216:217], s[24:25], 0, v[148:149]
	s_mov_b32 m0, s22
	ds_read_b128 v[184:187], v170 offset:16384
	ds_read_b128 v[188:191], v170 offset:17408
	ds_read_b128 v[192:195], v170 offset:18432
	ds_read_b128 v[196:199], v170 offset:19456
	ds_read_b128 v[200:203], v170 offset:20480
	ds_read_b128 v[204:207], v170 offset:21504
	ds_read_b128 v[208:211], v170 offset:22528
	ds_read_b128 v[212:215], v170 offset:23552
	global_load_lds_dwordx4 v[216:217], off
	s_add_i32 m0, s22, 0x2000
	s_add_u32 s22, s24, 0x80000
	v_lshl_add_u64 v[218:219], s[24:25], 0, v[144:145]
	s_addc_u32 s23, s25, 0
	s_add_i32 s54, s48, s34
	global_load_lds_dwordx4 v[218:219], off
	v_lshl_add_u64 v[220:221], s[22:23], 0, v[148:149]
	s_mov_b32 m0, s54
	v_lshl_add_u64 v[222:223], s[26:27], 0, v[146:147]
	global_load_lds_dwordx4 v[220:221], off
	v_lshl_add_u64 v[220:221], s[22:23], 0, v[144:145]
	s_add_i32 m0, s54, 0x2000
	s_nop 0
	global_load_lds_dwordx4 v[220:221], off
	v_lshl_add_u64 v[220:221], s[26:27], 0, v[150:151]
	s_mov_b32 m0, s37
	s_nop 0
	global_load_lds_dwordx4 v[220:221], off
	s_mov_b32 m0, s38
	s_nop 0
	global_load_lds_dwordx4 v[222:223], off
	s_waitcnt vmcnt(8)
	s_waitcnt lgkmcnt(0)
	s_barrier
; #define PG8_STAGE(bufoff, gbase, voff) do { _Pragma("unroll") for (int _i = 0; _i < 2; ++_i) \
;         __builtin_amdgcn_global_load_lds((const unsigned*)((const char*)(gbase) + (voff)[_i]), (PG8_LAS unsigned*)(lds + (bufoff) + ldsw + _i * 8192), 16, 0, 0); } while (0)
; #define PG8_LDA(dst, b, h) do { _Pragma("unroll") for (int m = 0; m < 4; ++m) _Pragma("unroll") for (int k = 0; k < 2; ++k) dst[m][k] = *(const PG8_LAS bf16x8*)(lds + PG8_SA(b, h) + aoff + m * 2048 + k * 1024); } while (0)
; #define PG8_LDB(dst, b, h) do { _Pragma("unroll") for (int n = 0; n < 2; ++n) _Pragma("unroll") for (int k = 0; k < 2; ++k) dst[n][k] = *(const PG8_LAS bf16x8*)(lds + PG8_SB(b, h) + boff + n * 2048 + k * 1024); } while (0)
; #define PG8_MMA(ai, bj, At, Bt) do { __builtin_amdgcn_s_setprio(1); _Pragma("unroll") for (int m = 0; m < 4; ++m) _Pragma("unroll") for (int n = 0; n < 2; ++n) _Pragma("unroll") for (int k = 0; k < 2; ++k) \
;         acc[ai][bj][m][n] = __builtin_amdgcn_mfma_f32_16x16x32_bf16(Bt[n][k], At[m][k], acc[ai][bj][m][n], 0, 0, 0); __builtin_amdgcn_s_setprio(0); } while (0)
; template <class Epi, class Sched, bool ALIGN_EPI = false, bool SP2 = false>
; __device__ __forceinline__ void gemm_phase(PG8_LAS unsigned char* lds, const Gemm g, const Sched& S, const Epi& E, const int wave_in) {
;     ...
;             if constexpr (SP2) {
;             PG8_LDB(B0, 0, 0); PG8_LDB(B1, 0, 1); PG8_SCHED; PG8_LDA(At, 0, 0); PG8_STAGE(PG8_SA(1, 1), a1 + hstepA, voffA);
;             PG8_WAIT_V(8); PG8_WAIT_L(0); PG8_BAR; PG8_MMA(0, 0, At, B0); PG8_MMA(0, 1, At, B1); PG8_BAR; PG8_SCHED;
;             PG8_LDA(At, 0, 1); PG8_STAGE(PG8_SB(0, 0), b2, voffB); PG8_STAGE(PG8_SB(0, 1), b2 + hstepB, voffB); PG8_STAGE(PG8_SA(0, 0), a2, voffA);
;             PG8_WAIT_V(8); PG8_WAIT_L(0); PG8_BAR; PG8_MMA(1, 0, At, B0); PG8_MMA(1, 1, At, B1); PG8_BAR; PG8_SCHED;
;             PG8_LDB(B0, 1, 0); PG8_LDB(B1, 1, 1); PG8_SCHED; PG8_LDA(At, 1, 0); PG8_STAGE(PG8_SA(0, 1), a2 + hstepA, voffA);
;             PG8_WAIT_V(8); PG8_WAIT_L(0); PG8_BAR; PG8_MMA(0, 0, At, B0); PG8_MMA(0, 1, At, B1); PG8_BAR; PG8_SCHED;
;             PG8_LDA(At, 1, 1); PG8_STAGE(PG8_SB(1, 0), b3, voffB); PG8_STAGE(PG8_SB(1, 1), b3 + hstepB, voffB); PG8_STAGE(PG8_SA(1, 0), a3, voffA);
;             PG8_WAIT_V(8); PG8_WAIT_L(0); PG8_BAR; PG8_MMA(1, 0, At, B0); PG8_MMA(1, 1, At, B1); PG8_BAR; PG8_SCHED;
	s_setprio 1
	s_waitcnt lgkmcnt(0)
	v_mfma_f32_16x16x32_bf16 v[60:63], v[128:131], v[184:187], v[60:63]
	v_mfma_f32_16x16x32_bf16 v[56:59], v[136:139], v[184:187], v[56:59]
	v_mfma_f32_16x16x32_bf16 v[52:55], v[128:131], v[192:195], v[52:55]
	v_mfma_f32_16x16x32_bf16 v[44:47], v[136:139], v[192:195], v[44:47]
	v_mfma_f32_16x16x32_bf16 v[36:39], v[128:131], v[200:203], v[36:39]
	v_mfma_f32_16x16x32_bf16 v[28:31], v[136:139], v[200:203], v[28:31]
	v_mfma_f32_16x16x32_bf16 v[20:23], v[128:131], v[208:211], v[20:23]
	v_mfma_f32_16x16x32_bf16 v[12:15], v[136:139], v[208:211], v[12:15]
	v_mfma_f32_16x16x32_bf16 v[60:63], v[132:135], v[188:191], v[60:63]
	v_mfma_f32_16x16x32_bf16 v[56:59], v[140:143], v[188:191], v[56:59]
	v_mfma_f32_16x16x32_bf16 v[52:55], v[132:135], v[196:199], v[52:55]
	v_mfma_f32_16x16x32_bf16 v[44:47], v[140:143], v[196:199], v[44:47]
	v_mfma_f32_16x16x32_bf16 v[36:39], v[132:135], v[204:207], v[36:39]
	v_mfma_f32_16x16x32_bf16 v[28:31], v[140:143], v[204:207], v[28:31]
	v_mfma_f32_16x16x32_bf16 v[20:23], v[132:135], v[212:215], v[20:23]
	v_mfma_f32_16x16x32_bf16 v[12:15], v[140:143], v[212:215], v[12:15]
	s_setprio 0
	s_setprio 1
	v_mfma_f32_16x16x32_bf16 v[48:51], v[162:165], v[184:187], v[48:51]
	v_mfma_f32_16x16x32_bf16 v[40:43], v[176:179], v[184:187], v[40:43]
	v_mfma_f32_16x16x32_bf16 v[32:35], v[162:165], v[192:195], v[32:35]
	v_mfma_f32_16x16x32_bf16 v[24:27], v[176:179], v[192:195], v[24:27]
	v_mfma_f32_16x16x32_bf16 v[16:19], v[162:165], v[200:203], v[16:19]
	v_mfma_f32_16x16x32_bf16 v[8:11], v[176:179], v[200:203], v[8:11]
	v_mfma_f32_16x16x32_bf16 v[4:7], v[162:165], v[208:211], v[4:7]
	v_mfma_f32_16x16x32_bf16 v[0:3], v[176:179], v[208:211], v[0:3]
	v_mfma_f32_16x16x32_bf16 v[48:51], v[172:175], v[188:191], v[48:51]
	v_mfma_f32_16x16x32_bf16 v[40:43], v[180:183], v[188:191], v[40:43]
	v_mfma_f32_16x16x32_bf16 v[32:35], v[172:175], v[196:199], v[32:35]
	v_mfma_f32_16x16x32_bf16 v[24:27], v[180:183], v[196:199], v[24:27]
	v_mfma_f32_16x16x32_bf16 v[16:19], v[172:175], v[204:207], v[16:19]
	v_mfma_f32_16x16x32_bf16 v[8:11], v[180:183], v[204:207], v[8:11]
	v_mfma_f32_16x16x32_bf16 v[4:7], v[172:175], v[212:215], v[4:7]
	v_mfma_f32_16x16x32_bf16 v[0:3], v[180:183], v[212:215], v[0:3]
	s_setprio 0
	s_barrier
	s_add_i32 s54, 0, 0x18000
	s_add_i32 s55, 0, 0x1c000
	v_add_u32_e32 v140, s54, v166
	v_add_u32_e32 v171, s55, v166
	ds_read_b128 v[128:131], v140
	ds_read_b128 v[132:135], v140 offset:1024
	ds_read_b128 v[136:139], v140 offset:2048
	ds_read_b128 v[140:143], v140 offset:3072
	ds_read_b128 v[162:165], v171
	ds_read_b128 v[172:175], v171 offset:1024
	ds_read_b128 v[176:179], v171 offset:2048
	ds_read_b128 v[180:183], v171 offset:3072
	s_add_u32 s22, s26, 0x280000
	s_addc_u32 s23, s27, 0
	s_mov_b32 m0, s39
	v_lshl_add_u64 v[224:225], s[22:23], 0, v[150:151]
	ds_read_b128 v[184:187], v170 offset:32768
	ds_read_b128 v[188:191], v170 offset:33792
	ds_read_b128 v[192:195], v170 offset:34816
	ds_read_b128 v[196:199], v170 offset:35840
	ds_read_b128 v[200:203], v170 offset:36864
	ds_read_b128 v[204:207], v170 offset:37888
	ds_read_b128 v[208:211], v170 offset:38912
	ds_read_b128 v[212:215], v170 offset:39936
	global_load_lds_dwordx4 v[224:225], off
	v_lshl_add_u64 v[224:225], s[22:23], 0, v[146:147]
	s_mov_b32 m0, s40
	s_nop 0
	global_load_lds_dwordx4 v[224:225], off
	s_waitcnt vmcnt(8)
	s_waitcnt lgkmcnt(0)
	s_barrier
	s_setprio 1
	s_waitcnt lgkmcnt(0)
	v_mfma_f32_16x16x32_bf16 v[124:127], v[128:131], v[184:187], v[124:127]
	v_mfma_f32_16x16x32_bf16 v[120:123], v[136:139], v[184:187], v[120:123]
	v_mfma_f32_16x16x32_bf16 v[116:119], v[128:131], v[192:195], v[116:119]
	v_mfma_f32_16x16x32_bf16 v[112:115], v[136:139], v[192:195], v[112:115]
	v_mfma_f32_16x16x32_bf16 v[92:95], v[128:131], v[200:203], v[92:95]
	v_mfma_f32_16x16x32_bf16 v[88:91], v[136:139], v[200:203], v[88:91]
	v_mfma_f32_16x16x32_bf16 v[84:87], v[128:131], v[208:211], v[84:87]
	v_mfma_f32_16x16x32_bf16 v[76:79], v[136:139], v[208:211], v[76:79]
	v_mfma_f32_16x16x32_bf16 v[124:127], v[132:135], v[188:191], v[124:127]
	v_mfma_f32_16x16x32_bf16 v[120:123], v[140:143], v[188:191], v[120:123]
	v_mfma_f32_16x16x32_bf16 v[116:119], v[132:135], v[196:199], v[116:119]
	v_mfma_f32_16x16x32_bf16 v[112:115], v[140:143], v[196:199], v[112:115]
	v_mfma_f32_16x16x32_bf16 v[92:95], v[132:135], v[204:207], v[92:95]
	v_mfma_f32_16x16x32_bf16 v[88:91], v[140:143], v[204:207], v[88:91]
	v_mfma_f32_16x16x32_bf16 v[84:87], v[132:135], v[212:215], v[84:87]
	v_mfma_f32_16x16x32_bf16 v[76:79], v[140:143], v[212:215], v[76:79]
	s_setprio 0
	s_setprio 1
	v_mfma_f32_16x16x32_bf16 v[108:111], v[162:165], v[184:187], v[108:111]
	v_mfma_f32_16x16x32_bf16 v[104:107], v[176:179], v[184:187], v[104:107]
	v_mfma_f32_16x16x32_bf16 v[100:103], v[162:165], v[192:195], v[100:103]
	v_mfma_f32_16x16x32_bf16 v[96:99], v[176:179], v[192:195], v[96:99]
	v_mfma_f32_16x16x32_bf16 v[80:83], v[162:165], v[200:203], v[80:83]
	v_mfma_f32_16x16x32_bf16 v[72:75], v[176:179], v[200:203], v[72:75]
	v_mfma_f32_16x16x32_bf16 v[68:71], v[162:165], v[208:211], v[68:71]
	v_mfma_f32_16x16x32_bf16 v[64:67], v[176:179], v[208:211], v[64:67]
	v_mfma_f32_16x16x32_bf16 v[108:111], v[172:175], v[188:191], v[108:111]
	v_mfma_f32_16x16x32_bf16 v[104:107], v[180:183], v[188:191], v[104:107]
	v_mfma_f32_16x16x32_bf16 v[100:103], v[172:175], v[196:199], v[100:103]
	v_mfma_f32_16x16x32_bf16 v[96:99], v[180:183], v[196:199], v[96:99]
	v_mfma_f32_16x16x32_bf16 v[80:83], v[172:175], v[204:207], v[80:83]
	v_mfma_f32_16x16x32_bf16 v[72:75], v[180:183], v[204:207], v[72:75]
	v_mfma_f32_16x16x32_bf16 v[68:71], v[172:175], v[212:215], v[68:71]
	v_mfma_f32_16x16x32_bf16 v[64:67], v[180:183], v[212:215], v[64:67]
	s_setprio 0
	s_barrier
; #define PG8_STAGE(bufoff, gbase, voff) do { _Pragma("unroll") for (int _i = 0; _i < 2; ++_i) \
;         __builtin_amdgcn_global_load_lds((const unsigned*)((const char*)(gbase) + (voff)[_i]), (PG8_LAS unsigned*)(lds + (bufoff) + ldsw + _i * 8192), 16, 0, 0); } while (0)
; #define PG8_LDA(dst, b, h) do { _Pragma("unroll") for (int m = 0; m < 4; ++m) _Pragma("unroll") for (int k = 0; k < 2; ++k) dst[m][k] = *(const PG8_LAS bf16x8*)(lds + PG8_SA(b, h) + aoff + m * 2048 + k * 1024); } while (0)
; #define PG8_MMA(ai, bj, At, Bt) do { __builtin_amdgcn_s_setprio(1); _Pragma("unroll") for (int m = 0; m < 4; ++m) _Pragma("unroll") for (int n = 0; n < 2; ++n) _Pragma("unroll") for (int k = 0; k < 2; ++k) \
;         acc[ai][bj][m][n] = __builtin_amdgcn_mfma_f32_16x16x32_bf16(Bt[n][k], At[m][k], acc[ai][bj][m][n], 0, 0, 0); __builtin_amdgcn_s_setprio(0); } while (0)
; #define PG8_WAIT_V(n) asm volatile("s_waitcnt vmcnt(" #n ")" ::: "memory")
; #define PG8_WAIT_L(n) asm volatile("s_waitcnt lgkmcnt(" #n ")" ::: "memory")
; #define PG8_BAR __builtin_amdgcn_s_barrier()
; #define PG8_SCHED __builtin_amdgcn_sched_barrier(0)
; template <class Epi, class Sched, bool ALIGN_EPI = false, bool SP2 = false>
; __device__ __forceinline__ void gemm_phase(PG8_LAS unsigned char* lds, const Gemm g, const Sched& S, const Epi& E, const int wave_in) {
;     ...
;             PG8_LDA(At, 1, 1); PG8_STAGE(PG8_SB(1, 0), b3, voffB); PG8_STAGE(PG8_SB(1, 1), b3 + hstepB, voffB); PG8_STAGE(PG8_SA(1, 0), a3, voffA);
;             PG8_WAIT_V(8); PG8_WAIT_L(0); PG8_BAR; PG8_MMA(1, 0, At, B0); PG8_MMA(1, 1, At, B1); PG8_BAR; PG8_SCHED;
;     ...
;         if (!has_next) break;
; #pragma unroll
;         for (int a = 0; a < 2; ++a)
; #pragma unroll
;             for (int b = 0; b < 2; ++b)
; #pragma unroll
;                 for (int m = 0; m < 4; ++m)
; #pragma unroll
;                     for (int n = 0; n < 2; ++n) acc[a][b][m][n] = (f32x4){0.f, 0.f, 0.f, 0.f};
;         cur = nxt; cA = nA; cB = nB; ++ui;
	s_add_i32 s22, s54, s34
	v_lshl_add_u64 v[216:217], v[216:217], 0, s[10:11]
	s_mov_b32 m0, s22
	ds_read_b128 v[184:187], v170 offset:49152
	ds_read_b128 v[188:191], v170 offset:50176
	ds_read_b128 v[192:195], v170 offset:51200
	ds_read_b128 v[196:199], v170 offset:52224
	ds_read_b128 v[200:203], v170 offset:53248
	ds_read_b128 v[204:207], v170 offset:54272
	ds_read_b128 v[208:211], v170 offset:55296
	ds_read_b128 v[212:215], v170 offset:56320
	global_load_lds_dwordx4 v[216:217], off
	s_add_i32 m0, s22, 0x2000
	s_add_u32 s22, s24, 0x80080
	v_lshl_add_u64 v[216:217], v[218:219], 0, s[10:11]
	s_addc_u32 s23, s25, 0
	s_add_i32 s24, s55, s34
	global_load_lds_dwordx4 v[216:217], off
	v_lshl_add_u64 v[216:217], s[22:23], 0, v[148:149]
	s_mov_b32 m0, s24
	s_nop 0
	global_load_lds_dwordx4 v[216:217], off
	v_lshl_add_u64 v[216:217], s[22:23], 0, v[144:145]
	s_add_i32 m0, s24, 0x2000
	s_nop 0
	global_load_lds_dwordx4 v[216:217], off
	v_lshl_add_u64 v[216:217], v[220:221], 0, s[10:11]
	s_mov_b32 m0, s44
	s_nop 0
	global_load_lds_dwordx4 v[216:217], off
	v_lshl_add_u64 v[216:217], v[222:223], 0, s[10:11]
	s_mov_b32 m0, s45
	s_nop 0
	global_load_lds_dwordx4 v[216:217], off
	s_waitcnt vmcnt(8)
	s_waitcnt lgkmcnt(0)
	s_barrier
	s_setprio 1
	s_waitcnt lgkmcnt(0)
	v_mfma_f32_16x16x32_bf16 v[60:63], v[128:131], v[184:187], v[60:63]
	v_mfma_f32_16x16x32_bf16 v[56:59], v[136:139], v[184:187], v[56:59]
	v_mfma_f32_16x16x32_bf16 v[52:55], v[128:131], v[192:195], v[52:55]
	v_mfma_f32_16x16x32_bf16 v[44:47], v[136:139], v[192:195], v[44:47]
	v_mfma_f32_16x16x32_bf16 v[36:39], v[128:131], v[200:203], v[36:39]
	v_mfma_f32_16x16x32_bf16 v[28:31], v[136:139], v[200:203], v[28:31]
	v_mfma_f32_16x16x32_bf16 v[20:23], v[128:131], v[208:211], v[20:23]
	v_mfma_f32_16x16x32_bf16 v[12:15], v[136:139], v[208:211], v[12:15]
	v_mfma_f32_16x16x32_bf16 v[60:63], v[132:135], v[188:191], v[60:63]
	v_mfma_f32_16x16x32_bf16 v[56:59], v[140:143], v[188:191], v[56:59]
	v_mfma_f32_16x16x32_bf16 v[52:55], v[132:135], v[196:199], v[52:55]
	v_mfma_f32_16x16x32_bf16 v[44:47], v[140:143], v[196:199], v[44:47]
	v_mfma_f32_16x16x32_bf16 v[36:39], v[132:135], v[204:207], v[36:39]
	v_mfma_f32_16x16x32_bf16 v[28:31], v[140:143], v[204:207], v[28:31]
	v_mfma_f32_16x16x32_bf16 v[20:23], v[132:135], v[212:215], v[20:23]
	v_mfma_f32_16x16x32_bf16 v[12:15], v[140:143], v[212:215], v[12:15]
	s_setprio 0
	s_setprio 1
	v_mfma_f32_16x16x32_bf16 v[48:51], v[162:165], v[184:187], v[48:51]
	v_mfma_f32_16x16x32_bf16 v[40:43], v[176:179], v[184:187], v[40:43]
	v_mfma_f32_16x16x32_bf16 v[32:35], v[162:165], v[192:195], v[32:35]
	v_mfma_f32_16x16x32_bf16 v[24:27], v[176:179], v[192:195], v[24:27]
	v_mfma_f32_16x16x32_bf16 v[16:19], v[162:165], v[200:203], v[16:19]
	v_mfma_f32_16x16x32_bf16 v[8:11], v[176:179], v[200:203], v[8:11]
	v_mfma_f32_16x16x32_bf16 v[4:7], v[162:165], v[208:211], v[4:7]
	v_mfma_f32_16x16x32_bf16 v[0:3], v[176:179], v[208:211], v[0:3]
	v_mfma_f32_16x16x32_bf16 v[48:51], v[172:175], v[188:191], v[48:51]
	v_mfma_f32_16x16x32_bf16 v[40:43], v[180:183], v[188:191], v[40:43]
	v_mfma_f32_16x16x32_bf16 v[32:35], v[172:175], v[196:199], v[32:35]
	v_mfma_f32_16x16x32_bf16 v[24:27], v[180:183], v[196:199], v[24:27]
	v_mfma_f32_16x16x32_bf16 v[16:19], v[172:175], v[204:207], v[16:19]
	v_mfma_f32_16x16x32_bf16 v[8:11], v[180:183], v[204:207], v[8:11]
	v_mfma_f32_16x16x32_bf16 v[4:7], v[172:175], v[212:215], v[4:7]
	v_mfma_f32_16x16x32_bf16 v[0:3], v[180:183], v[212:215], v[0:3]
	s_setprio 0
	s_barrier
	s_add_i32 s53, s53, 2
	s_add_u32 s51, s51, 0x100
	s_addc_u32 s52, s52, 0
	s_cmp_gt_u32 s53, 29
	s_mov_b64 s[22:23], s[4:5]
	s_cbranch_scc0 .LBB0_353
	s_mov_b32 s99, 1
	s_load_dwordx2 s[52:53], s[94:95], 0xe0
	s_and_b64 vcc, exec, s[12:13]
	s_cbranch_vccz .LBB0_356
	s_barrier

;     __host__ __device__ bool next(int i, Unit& u) const { const bool ok = StaticOrder::next(i, u); u.pm = 0; u.pn = 0; return ok; }
;     __host__ __device__ bool next(int i, Unit& u) const {
;         const long L = (long)i * G + c; if (L >= nwg) return false;
;         int wgid = (int)L; { const int q = nwg / NXCD, r = nwg % NXCD, xcd = wgid % NXCD, off = wgid / NXCD; wgid = (xcd < r ? xcd * (q + 1) : r * (q + 1) + (xcd - r) * q) + off; }
;         const int nig = WGM * nN, gid = wgid / nig, fm = gid * WGM, gsz = (nM - fm) < WGM ? (nM - fm) : WGM;
;         u.pm = fm + ((wgid % nig) % gsz); u.pn = (wgid % nig) / gsz; return true;
;     }
; template <int L> __device__ __forceinline__ void layer_body(Frame& F, const Args& args, unsigned char* const wsg, const int lo, const int hi, const XcdBarrier& bar) {
;     ...
;         if (IN(base + 5)) {
;             const int Mr = M_ALL - row_lo2;
;             pg8::Gemm g{(const pg8::bf16_t*)(wsg + WS_H) + (size_t)row_lo2 * DM, (const pg8::bf16_t*)(wsg + WS_WT_UP), Mr, UP_N, DM, DM};
;             pg8::StaticOrder S; S.init(Mr, UP_N, F.G, (int)blockIdx.x);
;             pg8::EpiConvGate E{(pg8::bf16_t*)(wsg + WS_P) + (size_t)row_lo2 * DFF, (pg8::bf16_t*)(wsg + WS_WT_IN), args.in[I_FFNCW] + (size_t)L * 3 * UP_N, pm02};
;             pg8::gemm_phase<pg8::EpiConvGate, pg8::StaticOrder, true, true>(F.lds, g, S, E, F.wave);
.LBB0_466:
	s_cmp_gt_i32 s52, 6
	s_cselect_b64 s[0:1], -1, 0
	s_cmp_lt_i32 s53, 7
	s_cselect_b64 s[2:3], -1, 0
	s_or_b64 s[0:1], s[0:1], s[2:3]
	s_and_b64 vcc, exec, s[0:1]
	s_cbranch_vccnz .LBB0_551
	s_mov_b32 s99, 0
	s_cmpk_lt_i32 s73, 0x1830
	s_cselect_b64 s[2:3], -1, 0
	s_cmpk_gt_i32 s73, 0x182f
	v_mbcnt_lo_u32_b32 v10, -1, 0
	v_mbcnt_hi_u32_b32 v10, -1, v10
	s_cbranch_scc1 .LBB0_470
	s_ashr_i32 s0, s73, 31
	s_lshr_b32 s0, s0, 29
	s_add_i32 s0, s73, s0
	s_ashr_i32 s1, s0, 3
	s_and_b32 s0, s0, -8
	s_sub_i32 s0, s73, s0
	s_cmp_lt_i32 s0, 0
	s_movk_i32 s4, 0x307
	s_cselect_b32 s4, s4, 0x306
	s_mul_i32 s0, s4, s0
	s_add_i32 s0, s0, s1
	s_mul_hi_i32 s1, s0, 0x2fa0be83
	s_lshr_b32 s4, s1, 31
	s_ashr_i32 s1, s1, 5
	s_add_i32 s1, s1, s4
	s_lshl_b32 s4, s1, 2
	s_mulk_i32 s1, 0xac
	s_sub_i32 s0, s0, s1
	s_sext_i32_i16 s1, s0
	s_bfe_u32 s1, s1, 0x2001d
	s_add_i32 s1, s0, s1
	s_sext_i32_i16 s5, s1
	s_and_b32 s1, s1, 0xfffc
	s_sub_i32 s0, s0, s1
	s_sext_i32_i16 s0, s0
	s_add_i32 s12, s4, s0
	s_ashr_i32 s0, s5, 2
	s_andn2_b64 vcc, exec, s[2:3]
	s_cbranch_vccz .LBB0_471

;     __host__ __device__ bool next(int i, Unit& u) const { const bool ok = StaticOrder::next(i, u); u.pm = 0; u.pn = 0; return ok; }
; #define PG8_STAGE(bufoff, gbase, voff) do { _Pragma("unroll") for (int _i = 0; _i < 2; ++_i) \
;         __builtin_amdgcn_global_load_lds((const unsigned*)((const char*)(gbase) + (voff)[_i]), (PG8_LAS unsigned*)(lds + (bufoff) + ldsw + _i * 8192), 16, 0, 0); } while (0)
; #define PG8_LDA(dst, b, h) do { _Pragma("unroll") for (int m = 0; m < 4; ++m) _Pragma("unroll") for (int k = 0; k < 2; ++k) dst[m][k] = *(const PG8_LAS bf16x8*)(lds + PG8_SA(b, h) + aoff + m * 2048 + k * 1024); } while (0)
; #define PG8_LDB(dst, b, h) do { _Pragma("unroll") for (int n = 0; n < 2; ++n) _Pragma("unroll") for (int k = 0; k < 2; ++k) dst[n][k] = *(const PG8_LAS bf16x8*)(lds + PG8_SB(b, h) + boff + n * 2048 + k * 1024); } while (0)
; #define PG8_SCHED __builtin_amdgcn_sched_barrier(0)
; template <class Epi, class Sched, bool ALIGN_EPI = false, bool SP2 = false>
; __device__ __forceinline__ void gemm_phase(PG8_LAS unsigned char* lds, const Gemm g, const Sched& S, const Epi& E, const int wave_in) {
;     ...
;     for (;;) {
;         const bool has_next = S.next(ui + 1, nxt);
;         const char* nA = has_next ? (const char*)g.A + (size_t)nxt.pm * tstepA : cA; const char* nB = has_next ? (const char*)g.Bt + (size_t)nxt.pn * tstepB : cB;
;         for (int t = 0; t < nt; t += 2) {
;             const bool last = (t == nt - 2);
;             const char* a1 = cA + (size_t)(t + 1) * kstep;
;             const char* a2 = last ? nA : cA + (size_t)(t + 2) * kstep; const char* b2 = last ? nB : cB + (size_t)(t + 2) * kstep;
;             const char* a3 = a2 + kstep; const char* b3 = b2 + kstep;
;             if (last && has_next) S.a_ready(nxt);
;             if constexpr (SP2) {
;             PG8_LDB(B0, 0, 0); PG8_LDB(B1, 0, 1); PG8_SCHED; PG8_LDA(At, 0, 0); PG8_STAGE(PG8_SA(1, 1), a1 + hstepA, voffA);
;     ...
; #pragma unroll
;         for (int a = 0; a < 2; ++a)
; #pragma unroll
;             for (int b = 0; b < 2; ++b)
; #pragma unroll
;                 for (int m = 0; m < 4; ++m)
; #pragma unroll
;                     for (int n = 0; n < 2; ++n) acc[a][b][m][n] = (f32x4){0.f, 0.f, 0.f, 0.f};
;         cur = nxt; cA = nA; cB = nB; ++ui;
.LBB0_478:
	s_ashr_i32 s41, s40, 31
	s_lshl_b64 s[42:43], s[40:41], 20
	s_add_u32 s42, s52, s42
	s_addc_u32 s43, s53, s43
	s_and_b64 s[44:45], s[10:11], exec
	s_cselect_b32 s1, s43, s47
	s_cselect_b32 s13, s42, s46
	s_ashr_i32 s39, s38, 31
	s_lshl_b64 s[44:45], s[38:39], 20
	s_add_u32 s44, s54, s44
	s_addc_u32 s45, s55, s45
	s_and_b64 s[50:51], s[10:11], exec
	s_cselect_b32 s39, s45, s49
	s_cselect_b32 s41, s44, s48
	s_add_u32 s46, s46, 0x80080
	s_addc_u32 s47, s47, 0
	s_add_u32 s72, s48, 0x100
	v_mov_b32_e32 v0, 0
	s_addc_u32 s73, s49, 0
	s_mov_b32 s74, -2
	v_mov_b32_e32 v1, v0
	v_mov_b32_e32 v2, v0
	v_mov_b32_e32 v3, v0
	v_mov_b32_e32 v4, v0
	v_mov_b32_e32 v5, v0
	v_mov_b32_e32 v6, v0
	v_mov_b32_e32 v7, v0
	v_mov_b32_e32 v16, v0
	v_mov_b32_e32 v17, v0
	v_mov_b32_e32 v18, v0
	v_mov_b32_e32 v19, v0
	v_mov_b32_e32 v24, v0
	v_mov_b32_e32 v25, v0
	v_mov_b32_e32 v26, v0
	v_mov_b32_e32 v27, v0
	v_mov_b32_e32 v32, v0
	v_mov_b32_e32 v33, v0
	v_mov_b32_e32 v34, v0
	v_mov_b32_e32 v35, v0
	v_mov_b32_e32 v40, v0
	v_mov_b32_e32 v41, v0
	v_mov_b32_e32 v42, v0
	v_mov_b32_e32 v43, v0
	v_mov_b32_e32 v72, v0
	v_mov_b32_e32 v73, v0
	v_mov_b32_e32 v74, v0
	v_mov_b32_e32 v75, v0
	v_mov_b32_e32 v104, v0
	v_mov_b32_e32 v105, v0
	v_mov_b32_e32 v106, v0
	v_mov_b32_e32 v107, v0
	v_mov_b32_e32 v8, v0
	v_mov_b32_e32 v9, v0
	v_mov_b32_e32 v10, v0
	v_mov_b32_e32 v11, v0
	v_mov_b32_e32 v12, v0
	v_mov_b32_e32 v13, v0
	v_mov_b32_e32 v14, v0
	v_mov_b32_e32 v15, v0
	v_mov_b32_e32 v20, v0
	v_mov_b32_e32 v21, v0
	v_mov_b32_e32 v22, v0
	v_mov_b32_e32 v23, v0
	v_mov_b32_e32 v28, v0
	v_mov_b32_e32 v29, v0
	v_mov_b32_e32 v30, v0
	v_mov_b32_e32 v31, v0
	v_mov_b32_e32 v36, v0
	v_mov_b32_e32 v37, v0
	v_mov_b32_e32 v38, v0
	v_mov_b32_e32 v39, v0
	v_mov_b32_e32 v68, v0
	v_mov_b32_e32 v69, v0
	v_mov_b32_e32 v70, v0
	v_mov_b32_e32 v71, v0
	v_mov_b32_e32 v76, v0
	v_mov_b32_e32 v77, v0
	v_mov_b32_e32 v78, v0
	v_mov_b32_e32 v79, v0
	v_mov_b32_e32 v108, v0
	v_mov_b32_e32 v109, v0
	v_mov_b32_e32 v110, v0
	v_mov_b32_e32 v111, v0
	v_mov_b32_e32 v112, v0
	v_mov_b32_e32 v113, v0
	v_mov_b32_e32 v114, v0
	v_mov_b32_e32 v115, v0
	v_mov_b32_e32 v116, v0
	v_mov_b32_e32 v117, v0
	v_mov_b32_e32 v118, v0
	v_mov_b32_e32 v119, v0
	v_mov_b32_e32 v128, v0
	v_mov_b32_e32 v129, v0
	v_mov_b32_e32 v130, v0
	v_mov_b32_e32 v131, v0
	v_mov_b32_e32 v136, v0
	v_mov_b32_e32 v137, v0
	v_mov_b32_e32 v138, v0
	v_mov_b32_e32 v139, v0
	v_mov_b32_e32 v144, v0
	v_mov_b32_e32 v145, v0
	v_mov_b32_e32 v146, v0
	v_mov_b32_e32 v147, v0
	v_mov_b32_e32 v152, v0
	v_mov_b32_e32 v153, v0
	v_mov_b32_e32 v154, v0
	v_mov_b32_e32 v155, v0
	v_mov_b32_e32 v160, v0
	v_mov_b32_e32 v161, v0
	v_mov_b32_e32 v162, v0
	v_mov_b32_e32 v163, v0
	v_mov_b32_e32 v168, v0
	v_mov_b32_e32 v169, v0
	v_mov_b32_e32 v170, v0
	v_mov_b32_e32 v171, v0
	v_mov_b32_e32 v120, v0
	v_mov_b32_e32 v121, v0
	v_mov_b32_e32 v122, v0
	v_mov_b32_e32 v123, v0
	v_mov_b32_e32 v124, v0
	v_mov_b32_e32 v125, v0
	v_mov_b32_e32 v126, v0
	v_mov_b32_e32 v127, v0
	v_mov_b32_e32 v132, v0
	v_mov_b32_e32 v133, v0
	v_mov_b32_e32 v134, v0
	v_mov_b32_e32 v135, v0
	v_mov_b32_e32 v140, v0
	v_mov_b32_e32 v141, v0
	v_mov_b32_e32 v142, v0
	v_mov_b32_e32 v143, v0
	v_mov_b32_e32 v148, v0
	v_mov_b32_e32 v149, v0
	v_mov_b32_e32 v150, v0
	v_mov_b32_e32 v151, v0
	v_mov_b32_e32 v156, v0
	v_mov_b32_e32 v157, v0
	v_mov_b32_e32 v158, v0
	v_mov_b32_e32 v159, v0
	v_mov_b32_e32 v164, v0
	v_mov_b32_e32 v165, v0
	v_mov_b32_e32 v166, v0
	v_mov_b32_e32 v167, v0
	v_mov_b32_e32 v172, v0
	v_mov_b32_e32 v173, v0
	v_mov_b32_e32 v174, v0
	v_mov_b32_e32 v175, v0
	s_cmp_lg_u32 s99, 0
	s_cbranch_scc0 .LBB0_479
	ds_read_b128 v[44:47], v189
	ds_read_b128 v[48:51], v189 offset:1024
	ds_read_b128 v[52:55], v189 offset:2048
	ds_read_b128 v[56:59], v189 offset:3072
	ds_read_b128 v[60:63], v197
	ds_read_b128 v[64:67], v197 offset:1024
	ds_read_b128 v[80:83], v197 offset:2048
	ds_read_b128 v[84:87], v197 offset:3072
	s_add_u32 s48, s46, 0xfff80080
	s_addc_u32 s49, s47, -1
	s_cmp_eq_u32 s74, 28
	s_cselect_b32 s51, s1, s49
	s_cselect_b32 s50, s13, s48
	s_cselect_b32 s49, s39, s73
	s_cselect_b32 s48, s41, s72
	v_lshl_add_u64 v[224:225], s[46:47], 0, v[206:207]
	s_add_i32 m0, s57, 0xc000
	ds_read_b128 v[88:91], v199
	ds_read_b128 v[92:95], v199 offset:1024
	ds_read_b128 v[96:99], v199 offset:2048
	ds_read_b128 v[100:103], v199 offset:3072
	ds_read_b128 v[176:179], v199 offset:4096
	ds_read_b128 v[212:215], v199 offset:5120
	ds_read_b128 v[216:219], v199 offset:6144
	ds_read_b128 v[220:223], v199 offset:7168
	global_load_lds_dwordx4 v[224:225], off
	v_lshl_add_u64 v[224:225], s[46:47], 0, v[208:209]
	s_add_i32 m0, s57, 0xe000
	s_nop 0
	global_load_lds_dwordx4 v[224:225], off
	s_waitcnt vmcnt(24)
	s_waitcnt lgkmcnt(0)
	s_barrier
; #define PG8_STAGE(bufoff, gbase, voff) do { _Pragma("unroll") for (int _i = 0; _i < 2; ++_i) \
;         __builtin_amdgcn_global_load_lds((const unsigned*)((const char*)(gbase) + (voff)[_i]), (PG8_LAS unsigned*)(lds + (bufoff) + ldsw + _i * 8192), 16, 0, 0); } while (0)
; #define PG8_LDA(dst, b, h) do { _Pragma("unroll") for (int m = 0; m < 4; ++m) _Pragma("unroll") for (int k = 0; k < 2; ++k) dst[m][k] = *(const PG8_LAS bf16x8*)(lds + PG8_SA(b, h) + aoff + m * 2048 + k * 1024); } while (0)
; #define PG8_LDB(dst, b, h) do { _Pragma("unroll") for (int n = 0; n < 2; ++n) _Pragma("unroll") for (int k = 0; k < 2; ++k) dst[n][k] = *(const PG8_LAS bf16x8*)(lds + PG8_SB(b, h) + boff + n * 2048 + k * 1024); } while (0)
; #define PG8_MMA(ai, bj, At, Bt) do { __builtin_amdgcn_s_setprio(1); _Pragma("unroll") for (int m = 0; m < 4; ++m) _Pragma("unroll") for (int n = 0; n < 2; ++n) _Pragma("unroll") for (int k = 0; k < 2; ++k) \
;         acc[ai][bj][m][n] = __builtin_amdgcn_mfma_f32_16x16x32_bf16(Bt[n][k], At[m][k], acc[ai][bj][m][n], 0, 0, 0); __builtin_amdgcn_s_setprio(0); } while (0)
; #define PG8_WAIT_V(n) asm volatile("s_waitcnt vmcnt(" #n ")" ::: "memory")
; #define PG8_WAIT_L(n) asm volatile("s_waitcnt lgkmcnt(" #n ")" ::: "memory")
; #define PG8_BAR __builtin_amdgcn_s_barrier()
; #define PG8_SCHED __builtin_amdgcn_sched_barrier(0)
; template <class Epi, class Sched, bool ALIGN_EPI = false, bool SP2 = false>
; __device__ __forceinline__ void gemm_phase(PG8_LAS unsigned char* lds, const Gemm g, const Sched& S, const Epi& E, const int wave_in) {
;     ...
;             PG8_LDB(B0, 0, 0); PG8_LDB(B1, 0, 1); PG8_SCHED; PG8_LDA(At, 0, 0); PG8_STAGE(PG8_SA(1, 1), a1 + hstepA, voffA);
;             PG8_WAIT_V(8); PG8_WAIT_L(0); PG8_BAR; PG8_MMA(0, 0, At, B0); PG8_MMA(0, 1, At, B1); PG8_BAR; PG8_SCHED;
;             PG8_LDA(At, 0, 1); PG8_STAGE(PG8_SB(0, 0), b2, voffB); PG8_STAGE(PG8_SB(0, 1), b2 + hstepB, voffB); PG8_STAGE(PG8_SA(0, 0), a2, voffA);
;             PG8_WAIT_V(8); PG8_WAIT_L(0); PG8_BAR; PG8_MMA(1, 0, At, B0); PG8_MMA(1, 1, At, B1); PG8_BAR; PG8_SCHED;
	s_setprio 1
	s_waitcnt lgkmcnt(0)
	v_mfma_f32_16x16x32_bf16 v[172:175], v[44:47], v[88:91], v[172:175]
	v_mfma_f32_16x16x32_bf16 v[164:167], v[52:55], v[88:91], v[164:167]
	v_mfma_f32_16x16x32_bf16 v[156:159], v[44:47], v[96:99], v[156:159]
	v_mfma_f32_16x16x32_bf16 v[148:151], v[52:55], v[96:99], v[148:151]
	v_mfma_f32_16x16x32_bf16 v[140:143], v[44:47], v[176:179], v[140:143]
	v_mfma_f32_16x16x32_bf16 v[132:135], v[52:55], v[176:179], v[132:135]
	v_mfma_f32_16x16x32_bf16 v[124:127], v[44:47], v[216:219], v[124:127]
	v_mfma_f32_16x16x32_bf16 v[120:123], v[52:55], v[216:219], v[120:123]
	v_mfma_f32_16x16x32_bf16 v[172:175], v[48:51], v[92:95], v[172:175]
	v_mfma_f32_16x16x32_bf16 v[164:167], v[56:59], v[92:95], v[164:167]
	v_mfma_f32_16x16x32_bf16 v[156:159], v[48:51], v[100:103], v[156:159]
	v_mfma_f32_16x16x32_bf16 v[148:151], v[56:59], v[100:103], v[148:151]
	v_mfma_f32_16x16x32_bf16 v[140:143], v[48:51], v[212:215], v[140:143]
	v_mfma_f32_16x16x32_bf16 v[132:135], v[56:59], v[212:215], v[132:135]
	v_mfma_f32_16x16x32_bf16 v[124:127], v[48:51], v[220:223], v[124:127]
	v_mfma_f32_16x16x32_bf16 v[120:123], v[56:59], v[220:223], v[120:123]
	s_setprio 0
	s_setprio 1
	v_mfma_f32_16x16x32_bf16 v[168:171], v[60:63], v[88:91], v[168:171]
	v_mfma_f32_16x16x32_bf16 v[88:91], v[80:83], v[88:91], v[160:163]
	v_mfma_f32_16x16x32_bf16 v[168:171], v[64:67], v[92:95], v[168:171]
	v_mfma_f32_16x16x32_bf16 v[88:91], v[84:87], v[92:95], v[88:91]
	v_mfma_f32_16x16x32_bf16 v[92:95], v[60:63], v[96:99], v[152:155]
	v_mfma_f32_16x16x32_bf16 v[96:99], v[80:83], v[96:99], v[144:147]
	v_mfma_f32_16x16x32_bf16 v[128:131], v[80:83], v[176:179], v[128:131]
	v_mfma_f32_16x16x32_bf16 v[116:119], v[60:63], v[216:219], v[116:119]
	v_mfma_f32_16x16x32_bf16 v[112:115], v[80:83], v[216:219], v[112:115]
	v_mfma_f32_16x16x32_bf16 v[92:95], v[64:67], v[100:103], v[92:95]
	v_mfma_f32_16x16x32_bf16 v[96:99], v[84:87], v[100:103], v[96:99]
	v_mfma_f32_16x16x32_bf16 v[100:103], v[60:63], v[176:179], v[136:139]
	v_mfma_f32_16x16x32_bf16 v[128:131], v[84:87], v[212:215], v[128:131]
	v_mfma_f32_16x16x32_bf16 v[116:119], v[64:67], v[220:223], v[116:119]
	v_mfma_f32_16x16x32_bf16 v[112:115], v[84:87], v[220:223], v[112:115]
	v_mfma_f32_16x16x32_bf16 v[100:103], v[64:67], v[212:215], v[100:103]
	s_setprio 0
	s_barrier
	s_add_i32 s75, s68, s56
	v_lshl_add_u64 v[232:233], s[48:49], 0, v[182:183]
	s_mov_b32 m0, s75
	ds_read_b128 v[136:139], v199 offset:16384
	ds_read_b128 v[144:147], v199 offset:17408
	ds_read_b128 v[152:155], v199 offset:18432
	ds_read_b128 v[160:163], v199 offset:19456
	ds_read_b128 v[176:179], v199 offset:20480
	ds_read_b128 v[212:215], v199 offset:21504
	ds_read_b128 v[216:219], v199 offset:22528
	ds_read_b128 v[220:223], v199 offset:23552
	global_load_lds_dwordx4 v[232:233], off
	s_add_i32 m0, s75, 0x2000
	s_add_u32 s76, s48, 0x80000
	v_lshl_add_u64 v[234:235], s[48:49], 0, v[186:187]
	s_addc_u32 s77, s49, 0
	s_add_i32 s75, s69, s56
	global_load_lds_dwordx4 v[234:235], off
	v_lshl_add_u64 v[224:225], s[76:77], 0, v[182:183]
	s_mov_b32 m0, s75
	v_lshl_add_u64 v[236:237], s[50:51], 0, v[180:181]
	global_load_lds_dwordx4 v[224:225], off
	v_lshl_add_u64 v[224:225], s[76:77], 0, v[186:187]
	s_add_i32 m0, s75, 0x2000
	v_lshl_add_u64 v[238:239], s[50:51], 0, v[184:185]
	global_load_lds_dwordx4 v[224:225], off
	s_mov_b32 m0, s57
	s_nop 0
	global_load_lds_dwordx4 v[236:237], off
	s_mov_b32 m0, s58
	s_nop 0
	global_load_lds_dwordx4 v[238:239], off
	s_waitcnt vmcnt(24)
	s_waitcnt lgkmcnt(0)
	s_barrier
	s_setprio 1
	s_waitcnt lgkmcnt(0)
	v_mfma_f32_16x16x32_bf16 v[108:111], v[44:47], v[136:139], v[108:111]
	v_mfma_f32_16x16x32_bf16 v[76:79], v[52:55], v[136:139], v[76:79]
	v_mfma_f32_16x16x32_bf16 v[68:71], v[44:47], v[152:155], v[68:71]
	v_mfma_f32_16x16x32_bf16 v[36:39], v[52:55], v[152:155], v[36:39]
	v_mfma_f32_16x16x32_bf16 v[28:31], v[44:47], v[176:179], v[28:31]
	v_mfma_f32_16x16x32_bf16 v[20:23], v[52:55], v[176:179], v[20:23]
	v_mfma_f32_16x16x32_bf16 v[12:15], v[44:47], v[216:219], v[12:15]
	v_mfma_f32_16x16x32_bf16 v[8:11], v[52:55], v[216:219], v[8:11]
	v_mfma_f32_16x16x32_bf16 v[108:111], v[48:51], v[144:147], v[108:111]
	v_mfma_f32_16x16x32_bf16 v[76:79], v[56:59], v[144:147], v[76:79]
	v_mfma_f32_16x16x32_bf16 v[68:71], v[48:51], v[160:163], v[68:71]
	v_mfma_f32_16x16x32_bf16 v[36:39], v[56:59], v[160:163], v[36:39]
	v_mfma_f32_16x16x32_bf16 v[28:31], v[48:51], v[212:215], v[28:31]
	v_mfma_f32_16x16x32_bf16 v[20:23], v[56:59], v[212:215], v[20:23]
	v_mfma_f32_16x16x32_bf16 v[12:15], v[48:51], v[220:223], v[12:15]
	v_mfma_f32_16x16x32_bf16 v[8:11], v[56:59], v[220:223], v[8:11]
	s_setprio 0
	s_setprio 1
	v_mfma_f32_16x16x32_bf16 v[40:43], v[60:63], v[152:155], v[40:43]
	v_mfma_f32_16x16x32_bf16 v[32:35], v[80:83], v[152:155], v[32:35]
	v_mfma_f32_16x16x32_bf16 v[24:27], v[60:63], v[176:179], v[24:27]
	v_mfma_f32_16x16x32_bf16 v[16:19], v[80:83], v[176:179], v[16:19]
	v_mfma_f32_16x16x32_bf16 v[4:7], v[60:63], v[216:219], v[4:7]
	v_mfma_f32_16x16x32_bf16 v[0:3], v[80:83], v[216:219], v[0:3]
	v_mfma_f32_16x16x32_bf16 v[44:47], v[60:63], v[136:139], v[104:107]
	v_mfma_f32_16x16x32_bf16 v[48:51], v[80:83], v[136:139], v[72:75]
	v_mfma_f32_16x16x32_bf16 v[40:43], v[64:67], v[160:163], v[40:43]
	v_mfma_f32_16x16x32_bf16 v[32:35], v[84:87], v[160:163], v[32:35]
	v_mfma_f32_16x16x32_bf16 v[24:27], v[64:67], v[212:215], v[24:27]
	v_mfma_f32_16x16x32_bf16 v[16:19], v[84:87], v[212:215], v[16:19]
	v_mfma_f32_16x16x32_bf16 v[4:7], v[64:67], v[220:223], v[4:7]
	v_mfma_f32_16x16x32_bf16 v[0:3], v[84:87], v[220:223], v[0:3]
	v_mfma_f32_16x16x32_bf16 v[44:47], v[64:67], v[144:147], v[44:47]
	v_mfma_f32_16x16x32_bf16 v[48:51], v[84:87], v[144:147], v[48:51]
	s_setprio 0
	s_barrier
; #define PG8_STAGE(bufoff, gbase, voff) do { _Pragma("unroll") for (int _i = 0; _i < 2; ++_i) \
;         __builtin_amdgcn_global_load_lds((const unsigned*)((const char*)(gbase) + (voff)[_i]), (PG8_LAS unsigned*)(lds + (bufoff) + ldsw + _i * 8192), 16, 0, 0); } while (0)
; #define PG8_LDA(dst, b, h) do { _Pragma("unroll") for (int m = 0; m < 4; ++m) _Pragma("unroll") for (int k = 0; k < 2; ++k) dst[m][k] = *(const PG8_LAS bf16x8*)(lds + PG8_SA(b, h) + aoff + m * 2048 + k * 1024); } while (0)
; #define PG8_LDB(dst, b, h) do { _Pragma("unroll") for (int n = 0; n < 2; ++n) _Pragma("unroll") for (int k = 0; k < 2; ++k) dst[n][k] = *(const PG8_LAS bf16x8*)(lds + PG8_SB(b, h) + boff + n * 2048 + k * 1024); } while (0)
; #define PG8_MMA(ai, bj, At, Bt) do { __builtin_amdgcn_s_setprio(1); _Pragma("unroll") for (int m = 0; m < 4; ++m) _Pragma("unroll") for (int n = 0; n < 2; ++n) _Pragma("unroll") for (int k = 0; k < 2; ++k) \
;         acc[ai][bj][m][n] = __builtin_amdgcn_mfma_f32_16x16x32_bf16(Bt[n][k], At[m][k], acc[ai][bj][m][n], 0, 0, 0); __builtin_amdgcn_s_setprio(0); } while (0)
; #define PG8_WAIT_V(n) asm volatile("s_waitcnt vmcnt(" #n ")" ::: "memory")
; #define PG8_WAIT_L(n) asm volatile("s_waitcnt lgkmcnt(" #n ")" ::: "memory")
; #define PG8_BAR __builtin_amdgcn_s_barrier()
; #define PG8_SCHED __builtin_amdgcn_sched_barrier(0)
; template <class Epi, class Sched, bool ALIGN_EPI = false, bool SP2 = false>
; __device__ __forceinline__ void gemm_phase(PG8_LAS unsigned char* lds, const Gemm g, const Sched& S, const Epi& E, const int wave_in) {
;     ...
;             PG8_LDB(B0, 1, 0); PG8_LDB(B1, 1, 1); PG8_SCHED; PG8_LDA(At, 1, 0); PG8_STAGE(PG8_SA(0, 1), a2 + hstepA, voffA);
;             PG8_WAIT_V(8); PG8_WAIT_L(0); PG8_BAR; PG8_MMA(0, 0, At, B0); PG8_MMA(0, 1, At, B1); PG8_BAR; PG8_SCHED;
;             PG8_LDA(At, 1, 1); PG8_STAGE(PG8_SB(1, 0), b3, voffB); PG8_STAGE(PG8_SB(1, 1), b3 + hstepB, voffB); PG8_STAGE(PG8_SA(1, 0), a3, voffA);
;             PG8_WAIT_V(8); PG8_WAIT_L(0); PG8_BAR; PG8_MMA(1, 0, At, B0); PG8_MMA(1, 1, At, B1); PG8_BAR; PG8_SCHED;
	s_add_i32 s75, 0, 0x18000
	s_add_i32 s76, 0, 0x1c000
	v_add_u32_e32 v64, s75, v195
	v_add_u32_e32 v72, s76, v195
	ds_read_b128 v[52:55], v64
	ds_read_b128 v[56:59], v64 offset:1024
	ds_read_b128 v[60:63], v64 offset:2048
	ds_read_b128 v[64:67], v64 offset:3072
	ds_read_b128 v[80:83], v72
	ds_read_b128 v[84:87], v72 offset:1024
	ds_read_b128 v[176:179], v72 offset:2048
	ds_read_b128 v[212:215], v72 offset:3072
	s_add_u32 s50, s50, 0x80000
	s_addc_u32 s51, s51, 0
	s_mov_b32 m0, s59
	v_lshl_add_u64 v[152:153], s[50:51], 0, v[180:181]
	ds_read_b128 v[72:75], v199 offset:32768
	ds_read_b128 v[104:107], v199 offset:33792
	ds_read_b128 v[136:139], v199 offset:34816
	ds_read_b128 v[144:147], v199 offset:35840
	ds_read_b128 v[216:219], v199 offset:36864
	ds_read_b128 v[220:223], v199 offset:37888
	ds_read_b128 v[224:227], v199 offset:38912
	ds_read_b128 v[228:231], v199 offset:39936
	global_load_lds_dwordx4 v[152:153], off
	v_lshl_add_u64 v[152:153], s[50:51], 0, v[184:185]
	s_mov_b32 m0, s60
	s_nop 0
	global_load_lds_dwordx4 v[152:153], off
	s_waitcnt vmcnt(8)
	s_waitcnt lgkmcnt(0)
	s_barrier
	s_setprio 1
	s_waitcnt lgkmcnt(0)
	v_mfma_f32_16x16x32_bf16 v[152:155], v[52:55], v[72:75], v[172:175]
	v_mfma_f32_16x16x32_bf16 v[172:175], v[56:59], v[104:107], v[152:155]
	v_mfma_f32_16x16x32_bf16 v[152:155], v[60:63], v[72:75], v[164:167]
	v_mfma_f32_16x16x32_bf16 v[164:167], v[64:67], v[104:107], v[152:155]
	v_mfma_f32_16x16x32_bf16 v[152:155], v[52:55], v[136:139], v[156:159]
	v_mfma_f32_16x16x32_bf16 v[148:151], v[60:63], v[136:139], v[148:151]
	v_mfma_f32_16x16x32_bf16 v[140:143], v[52:55], v[216:219], v[140:143]
	v_mfma_f32_16x16x32_bf16 v[132:135], v[60:63], v[216:219], v[132:135]
	v_mfma_f32_16x16x32_bf16 v[124:127], v[52:55], v[224:227], v[124:127]
	v_mfma_f32_16x16x32_bf16 v[120:123], v[60:63], v[224:227], v[120:123]
	v_mfma_f32_16x16x32_bf16 v[156:159], v[56:59], v[144:147], v[152:155]
	v_mfma_f32_16x16x32_bf16 v[148:151], v[64:67], v[144:147], v[148:151]
	v_mfma_f32_16x16x32_bf16 v[140:143], v[56:59], v[220:223], v[140:143]
	v_mfma_f32_16x16x32_bf16 v[132:135], v[64:67], v[220:223], v[132:135]
	v_mfma_f32_16x16x32_bf16 v[124:127], v[56:59], v[228:231], v[124:127]
	v_mfma_f32_16x16x32_bf16 v[120:123], v[64:67], v[228:231], v[120:123]
	s_setprio 0
	s_setprio 1
	v_mfma_f32_16x16x32_bf16 v[152:155], v[80:83], v[72:75], v[168:171]
	v_mfma_f32_16x16x32_bf16 v[72:75], v[176:179], v[72:75], v[88:91]
	v_mfma_f32_16x16x32_bf16 v[160:163], v[212:215], v[104:107], v[72:75]
	v_mfma_f32_16x16x32_bf16 v[72:75], v[80:83], v[136:139], v[92:95]
	v_mfma_f32_16x16x32_bf16 v[168:171], v[84:87], v[104:107], v[152:155]
	v_mfma_f32_16x16x32_bf16 v[152:155], v[84:87], v[144:147], v[72:75]
	v_mfma_f32_16x16x32_bf16 v[72:75], v[176:179], v[136:139], v[96:99]
	v_mfma_f32_16x16x32_bf16 v[144:147], v[212:215], v[144:147], v[72:75]
	v_mfma_f32_16x16x32_bf16 v[72:75], v[80:83], v[216:219], v[100:103]
	v_mfma_f32_16x16x32_bf16 v[136:139], v[84:87], v[220:223], v[72:75]
	v_mfma_f32_16x16x32_bf16 v[72:75], v[176:179], v[216:219], v[128:131]
	v_mfma_f32_16x16x32_bf16 v[128:131], v[212:215], v[220:223], v[72:75]
	v_mfma_f32_16x16x32_bf16 v[72:75], v[80:83], v[224:227], v[116:119]
	v_mfma_f32_16x16x32_bf16 v[116:119], v[84:87], v[228:231], v[72:75]
	v_mfma_f32_16x16x32_bf16 v[72:75], v[176:179], v[224:227], v[112:115]
	v_mfma_f32_16x16x32_bf16 v[112:115], v[212:215], v[228:231], v[72:75]
	s_setprio 0
	s_barrier
	s_add_i32 s50, s75, s56
	v_lshl_add_u64 v[104:105], v[232:233], 0, s[22:23]
	s_mov_b32 m0, s50
	s_nop 1
	ds_read_b128 v[72:75], v199 offset:49152
	ds_read_b128 v[88:91], v199 offset:50176
	ds_read_b128 v[92:95], v199 offset:51200
	ds_read_b128 v[96:99], v199 offset:52224
	ds_read_b128 v[100:103], v199 offset:53248
	ds_read_b128 v[216:219], v199 offset:54272
	ds_read_b128 v[220:223], v199 offset:55296
	ds_read_b128 v[224:227], v199 offset:56320
	global_load_lds_dwordx4 v[104:105], off
	s_add_i32 m0, s50, 0x2000
	s_add_u32 s48, s48, 0x80080
	v_lshl_add_u64 v[104:105], v[234:235], 0, s[22:23]
	s_addc_u32 s49, s49, 0
	s_add_i32 s50, s76, s56
	global_load_lds_dwordx4 v[104:105], off
	v_lshl_add_u64 v[104:105], s[48:49], 0, v[182:183]
	s_mov_b32 m0, s50
	s_nop 0
	global_load_lds_dwordx4 v[104:105], off
	v_lshl_add_u64 v[104:105], s[48:49], 0, v[186:187]
	s_add_i32 m0, s50, 0x2000
	s_nop 0
	global_load_lds_dwordx4 v[104:105], off
	v_lshl_add_u64 v[104:105], v[236:237], 0, s[22:23]
	s_mov_b32 m0, s63
	s_nop 0
	global_load_lds_dwordx4 v[104:105], off
	v_lshl_add_u64 v[104:105], v[238:239], 0, s[22:23]
	s_mov_b32 m0, s64
	s_nop 0
	global_load_lds_dwordx4 v[104:105], off
	s_waitcnt vmcnt(8)
	s_waitcnt lgkmcnt(0)
	s_barrier
	s_setprio 1
	s_waitcnt lgkmcnt(0)
	v_mfma_f32_16x16x32_bf16 v[104:107], v[52:55], v[72:75], v[108:111]
	v_mfma_f32_16x16x32_bf16 v[76:79], v[60:63], v[72:75], v[76:79]
	v_mfma_f32_16x16x32_bf16 v[68:71], v[52:55], v[92:95], v[68:71]
	v_mfma_f32_16x16x32_bf16 v[36:39], v[60:63], v[92:95], v[36:39]
	v_mfma_f32_16x16x32_bf16 v[28:31], v[52:55], v[100:103], v[28:31]
	v_mfma_f32_16x16x32_bf16 v[20:23], v[60:63], v[100:103], v[20:23]
	v_mfma_f32_16x16x32_bf16 v[12:15], v[52:55], v[220:223], v[12:15]
	v_mfma_f32_16x16x32_bf16 v[8:11], v[60:63], v[220:223], v[8:11]
	v_mfma_f32_16x16x32_bf16 v[108:111], v[56:59], v[88:91], v[104:107]
	v_mfma_f32_16x16x32_bf16 v[76:79], v[64:67], v[88:91], v[76:79]
	v_mfma_f32_16x16x32_bf16 v[68:71], v[56:59], v[96:99], v[68:71]
	v_mfma_f32_16x16x32_bf16 v[36:39], v[64:67], v[96:99], v[36:39]
	v_mfma_f32_16x16x32_bf16 v[28:31], v[56:59], v[216:219], v[28:31]
	v_mfma_f32_16x16x32_bf16 v[20:23], v[64:67], v[216:219], v[20:23]
	v_mfma_f32_16x16x32_bf16 v[12:15], v[56:59], v[224:227], v[12:15]
	v_mfma_f32_16x16x32_bf16 v[8:11], v[64:67], v[224:227], v[8:11]
	s_setprio 0
	s_setprio 1
	v_mfma_f32_16x16x32_bf16 v[44:47], v[80:83], v[72:75], v[44:47]
	v_mfma_f32_16x16x32_bf16 v[104:107], v[84:87], v[88:91], v[44:47]
	v_mfma_f32_16x16x32_bf16 v[44:47], v[176:179], v[72:75], v[48:51]
	v_mfma_f32_16x16x32_bf16 v[40:43], v[80:83], v[92:95], v[40:43]
	v_mfma_f32_16x16x32_bf16 v[32:35], v[176:179], v[92:95], v[32:35]
	v_mfma_f32_16x16x32_bf16 v[24:27], v[80:83], v[100:103], v[24:27]
	v_mfma_f32_16x16x32_bf16 v[16:19], v[176:179], v[100:103], v[16:19]
	v_mfma_f32_16x16x32_bf16 v[4:7], v[80:83], v[220:223], v[4:7]
	v_mfma_f32_16x16x32_bf16 v[0:3], v[176:179], v[220:223], v[0:3]
	v_mfma_f32_16x16x32_bf16 v[72:75], v[212:215], v[88:91], v[44:47]
	v_mfma_f32_16x16x32_bf16 v[40:43], v[84:87], v[96:99], v[40:43]
	v_mfma_f32_16x16x32_bf16 v[32:35], v[212:215], v[96:99], v[32:35]
	v_mfma_f32_16x16x32_bf16 v[24:27], v[84:87], v[216:219], v[24:27]
	v_mfma_f32_16x16x32_bf16 v[16:19], v[212:215], v[216:219], v[16:19]
	v_mfma_f32_16x16x32_bf16 v[4:7], v[84:87], v[224:227], v[4:7]
	v_mfma_f32_16x16x32_bf16 v[0:3], v[212:215], v[224:227], v[0:3]
	s_setprio 0
	s_barrier
	s_add_i32 s74, s74, 2
	s_add_u32 s46, s46, 0x100
	s_addc_u32 s47, s47, 0
	s_add_u32 s72, s72, 0x100
	s_addc_u32 s73, s73, 0
	s_cmp_gt_u32 s74, 29
	s_cbranch_scc0 .LBB0_479
; #define PG8_STAGE(bufoff, gbase, voff) do { _Pragma("unroll") for (int _i = 0; _i < 2; ++_i) \
;         __builtin_amdgcn_global_load_lds((const unsigned*)((const char*)(gbase) + (voff)[_i]), (PG8_LAS unsigned*)(lds + (bufoff) + ldsw + _i * 8192), 16, 0, 0); } while (0)
; #define PG8_LDA(dst, b, h) do { _Pragma("unroll") for (int m = 0; m < 4; ++m) _Pragma("unroll") for (int k = 0; k < 2; ++k) dst[m][k] = *(const PG8_LAS bf16x8*)(lds + PG8_SA(b, h) + aoff + m * 2048 + k * 1024); } while (0)
; #define PG8_LDB(dst, b, h) do { _Pragma("unroll") for (int n = 0; n < 2; ++n) _Pragma("unroll") for (int k = 0; k < 2; ++k) dst[n][k] = *(const PG8_LAS bf16x8*)(lds + PG8_SB(b, h) + boff + n * 2048 + k * 1024); } while (0)
; #define PG8_MMA(ai, bj, At, Bt) do { __builtin_amdgcn_s_setprio(1); _Pragma("unroll") for (int m = 0; m < 4; ++m) _Pragma("unroll") for (int n = 0; n < 2; ++n) _Pragma("unroll") for (int k = 0; k < 2; ++k) \
;         acc[ai][bj][m][n] = __builtin_amdgcn_mfma_f32_16x16x32_bf16(Bt[n][k], At[m][k], acc[ai][bj][m][n], 0, 0, 0); __builtin_amdgcn_s_setprio(0); } while (0)
; #define PG8_WAIT_V(n) asm volatile("s_waitcnt vmcnt(" #n ")" ::: "memory")
; #define PG8_WAIT_L(n) asm volatile("s_waitcnt lgkmcnt(" #n ")" ::: "memory")
; #define PG8_BAR __builtin_amdgcn_s_barrier()
; #define PG8_SCHED __builtin_amdgcn_sched_barrier(0)
; template <class Epi, class Sched, bool ALIGN_EPI = false, bool SP2 = false>
; __device__ __forceinline__ void gemm_phase(PG8_LAS unsigned char* lds, const Gemm g, const Sched& S, const Epi& E, const int wave_in) {
;     ...
;             PG8_LDB(B0, 0, 0); PG8_LDB(B1, 0, 1); PG8_SCHED; PG8_LDA(At, 0, 0); PG8_STAGE(PG8_SA(1, 1), a1 + hstepA, voffA);
;             PG8_WAIT_V(8); PG8_WAIT_L(0); PG8_BAR; PG8_MMA(0, 0, At, B0); PG8_MMA(0, 1, At, B1); PG8_BAR; PG8_SCHED;
;             PG8_LDA(At, 0, 1); PG8_STAGE(PG8_SB(0, 0), b2, voffB); PG8_STAGE(PG8_SB(0, 1), b2 + hstepB, voffB); PG8_STAGE(PG8_SA(0, 0), a2, voffA);
;             PG8_WAIT_V(8); PG8_WAIT_L(0); PG8_BAR; PG8_MMA(1, 0, At, B0); PG8_MMA(1, 1, At, B1); PG8_BAR; PG8_SCHED;
.LBB0_479:
	ds_read_b128 v[44:47], v189
	ds_read_b128 v[48:51], v189 offset:1024
	ds_read_b128 v[52:55], v189 offset:2048
	ds_read_b128 v[56:59], v189 offset:3072
	ds_read_b128 v[60:63], v197
	ds_read_b128 v[64:67], v197 offset:1024
	ds_read_b128 v[80:83], v197 offset:2048
	ds_read_b128 v[84:87], v197 offset:3072
	s_add_u32 s48, s46, 0xfff80080
	s_addc_u32 s49, s47, -1
	s_cmp_eq_u32 s74, 28
	s_cselect_b32 s51, s1, s49
	s_cselect_b32 s50, s13, s48
	s_cselect_b32 s49, s39, s73
	s_cselect_b32 s48, s41, s72
	v_lshl_add_u64 v[224:225], s[46:47], 0, v[206:207]
	s_add_i32 m0, s57, 0xc000
	ds_read_b128 v[88:91], v199
	ds_read_b128 v[92:95], v199 offset:1024
	ds_read_b128 v[96:99], v199 offset:2048
	ds_read_b128 v[100:103], v199 offset:3072
	ds_read_b128 v[176:179], v199 offset:4096
	ds_read_b128 v[212:215], v199 offset:5120
	ds_read_b128 v[216:219], v199 offset:6144
	ds_read_b128 v[220:223], v199 offset:7168
	global_load_lds_dwordx4 v[224:225], off
	v_lshl_add_u64 v[224:225], s[46:47], 0, v[208:209]
	s_add_i32 m0, s57, 0xe000
	s_nop 0
	global_load_lds_dwordx4 v[224:225], off
	s_waitcnt vmcnt(8)
	s_waitcnt lgkmcnt(0)
	s_barrier
	s_setprio 1
	s_waitcnt lgkmcnt(0)
	v_mfma_f32_16x16x32_bf16 v[172:175], v[44:47], v[88:91], v[172:175]
	v_mfma_f32_16x16x32_bf16 v[164:167], v[52:55], v[88:91], v[164:167]
	v_mfma_f32_16x16x32_bf16 v[156:159], v[44:47], v[96:99], v[156:159]
	v_mfma_f32_16x16x32_bf16 v[148:151], v[52:55], v[96:99], v[148:151]
	v_mfma_f32_16x16x32_bf16 v[140:143], v[44:47], v[176:179], v[140:143]
	v_mfma_f32_16x16x32_bf16 v[132:135], v[52:55], v[176:179], v[132:135]
	v_mfma_f32_16x16x32_bf16 v[124:127], v[44:47], v[216:219], v[124:127]
	v_mfma_f32_16x16x32_bf16 v[120:123], v[52:55], v[216:219], v[120:123]
	v_mfma_f32_16x16x32_bf16 v[172:175], v[48:51], v[92:95], v[172:175]
	v_mfma_f32_16x16x32_bf16 v[164:167], v[56:59], v[92:95], v[164:167]
	v_mfma_f32_16x16x32_bf16 v[156:159], v[48:51], v[100:103], v[156:159]
	v_mfma_f32_16x16x32_bf16 v[148:151], v[56:59], v[100:103], v[148:151]
	v_mfma_f32_16x16x32_bf16 v[140:143], v[48:51], v[212:215], v[140:143]
	v_mfma_f32_16x16x32_bf16 v[132:135], v[56:59], v[212:215], v[132:135]
	v_mfma_f32_16x16x32_bf16 v[124:127], v[48:51], v[220:223], v[124:127]
	v_mfma_f32_16x16x32_bf16 v[120:123], v[56:59], v[220:223], v[120:123]
	s_setprio 0
	s_setprio 1
	v_mfma_f32_16x16x32_bf16 v[168:171], v[60:63], v[88:91], v[168:171]
	v_mfma_f32_16x16x32_bf16 v[88:91], v[80:83], v[88:91], v[160:163]
	v_mfma_f32_16x16x32_bf16 v[168:171], v[64:67], v[92:95], v[168:171]
	v_mfma_f32_16x16x32_bf16 v[88:91], v[84:87], v[92:95], v[88:91]
	v_mfma_f32_16x16x32_bf16 v[92:95], v[60:63], v[96:99], v[152:155]
	v_mfma_f32_16x16x32_bf16 v[96:99], v[80:83], v[96:99], v[144:147]
	v_mfma_f32_16x16x32_bf16 v[128:131], v[80:83], v[176:179], v[128:131]
	v_mfma_f32_16x16x32_bf16 v[116:119], v[60:63], v[216:219], v[116:119]
	v_mfma_f32_16x16x32_bf16 v[112:115], v[80:83], v[216:219], v[112:115]
	v_mfma_f32_16x16x32_bf16 v[92:95], v[64:67], v[100:103], v[92:95]
	v_mfma_f32_16x16x32_bf16 v[96:99], v[84:87], v[100:103], v[96:99]
	v_mfma_f32_16x16x32_bf16 v[100:103], v[60:63], v[176:179], v[136:139]
	v_mfma_f32_16x16x32_bf16 v[128:131], v[84:87], v[212:215], v[128:131]
	v_mfma_f32_16x16x32_bf16 v[116:119], v[64:67], v[220:223], v[116:119]
	v_mfma_f32_16x16x32_bf16 v[112:115], v[84:87], v[220:223], v[112:115]
	v_mfma_f32_16x16x32_bf16 v[100:103], v[64:67], v[212:215], v[100:103]
	s_setprio 0
	s_barrier
	s_add_i32 s75, s68, s56
	v_lshl_add_u64 v[232:233], s[48:49], 0, v[182:183]
	s_mov_b32 m0, s75
	ds_read_b128 v[136:139], v199 offset:16384
	ds_read_b128 v[144:147], v199 offset:17408
	ds_read_b128 v[152:155], v199 offset:18432
	ds_read_b128 v[160:163], v199 offset:19456
	ds_read_b128 v[176:179], v199 offset:20480
	ds_read_b128 v[212:215], v199 offset:21504
	ds_read_b128 v[216:219], v199 offset:22528
	ds_read_b128 v[220:223], v199 offset:23552
	global_load_lds_dwordx4 v[232:233], off
	s_add_i32 m0, s75, 0x2000
	s_add_u32 s76, s48, 0x80000
	v_lshl_add_u64 v[234:235], s[48:49], 0, v[186:187]
	s_addc_u32 s77, s49, 0
	s_add_i32 s75, s69, s56
	global_load_lds_dwordx4 v[234:235], off
	v_lshl_add_u64 v[224:225], s[76:77], 0, v[182:183]
	s_mov_b32 m0, s75
	v_lshl_add_u64 v[236:237], s[50:51], 0, v[180:181]
	global_load_lds_dwordx4 v[224:225], off
	v_lshl_add_u64 v[224:225], s[76:77], 0, v[186:187]
	s_add_i32 m0, s75, 0x2000
	v_lshl_add_u64 v[238:239], s[50:51], 0, v[184:185]
	global_load_lds_dwordx4 v[224:225], off
	s_mov_b32 m0, s57
	s_nop 0
	global_load_lds_dwordx4 v[236:237], off
	s_mov_b32 m0, s58
	s_nop 0
	global_load_lds_dwordx4 v[238:239], off
	s_waitcnt vmcnt(8)
	s_waitcnt lgkmcnt(0)
	s_barrier
; #define PG8_STAGE(bufoff, gbase, voff) do { _Pragma("unroll") for (int _i = 0; _i < 2; ++_i) \
;         __builtin_amdgcn_global_load_lds((const unsigned*)((const char*)(gbase) + (voff)[_i]), (PG8_LAS unsigned*)(lds + (bufoff) + ldsw + _i * 8192), 16, 0, 0); } while (0)
; #define PG8_LDA(dst, b, h) do { _Pragma("unroll") for (int m = 0; m < 4; ++m) _Pragma("unroll") for (int k = 0; k < 2; ++k) dst[m][k] = *(const PG8_LAS bf16x8*)(lds + PG8_SA(b, h) + aoff + m * 2048 + k * 1024); } while (0)
; #define PG8_LDB(dst, b, h) do { _Pragma("unroll") for (int n = 0; n < 2; ++n) _Pragma("unroll") for (int k = 0; k < 2; ++k) dst[n][k] = *(const PG8_LAS bf16x8*)(lds + PG8_SB(b, h) + boff + n * 2048 + k * 1024); } while (0)
; #define PG8_MMA(ai, bj, At, Bt) do { __builtin_amdgcn_s_setprio(1); _Pragma("unroll") for (int m = 0; m < 4; ++m) _Pragma("unroll") for (int n = 0; n < 2; ++n) _Pragma("unroll") for (int k = 0; k < 2; ++k) \
;         acc[ai][bj][m][n] = __builtin_amdgcn_mfma_f32_16x16x32_bf16(Bt[n][k], At[m][k], acc[ai][bj][m][n], 0, 0, 0); __builtin_amdgcn_s_setprio(0); } while (0)
; #define PG8_WAIT_V(n) asm volatile("s_waitcnt vmcnt(" #n ")" ::: "memory")
; #define PG8_WAIT_L(n) asm volatile("s_waitcnt lgkmcnt(" #n ")" ::: "memory")
; #define PG8_BAR __builtin_amdgcn_s_barrier()
; #define PG8_SCHED __builtin_amdgcn_sched_barrier(0)
; template <class Epi, class Sched, bool ALIGN_EPI = false, bool SP2 = false>
; __device__ __forceinline__ void gemm_phase(PG8_LAS unsigned char* lds, const Gemm g, const Sched& S, const Epi& E, const int wave_in) {
;     ...
;             PG8_WAIT_V(8); PG8_WAIT_L(0); PG8_BAR; PG8_MMA(1, 0, At, B0); PG8_MMA(1, 1, At, B1); PG8_BAR; PG8_SCHED;
;             PG8_LDB(B0, 1, 0); PG8_LDB(B1, 1, 1); PG8_SCHED; PG8_LDA(At, 1, 0); PG8_STAGE(PG8_SA(0, 1), a2 + hstepA, voffA);
;             PG8_WAIT_V(8); PG8_WAIT_L(0); PG8_BAR; PG8_MMA(0, 0, At, B0); PG8_MMA(0, 1, At, B1); PG8_BAR; PG8_SCHED;
	s_setprio 1
	s_waitcnt lgkmcnt(0)
	v_mfma_f32_16x16x32_bf16 v[108:111], v[44:47], v[136:139], v[108:111]
	v_mfma_f32_16x16x32_bf16 v[76:79], v[52:55], v[136:139], v[76:79]
	v_mfma_f32_16x16x32_bf16 v[68:71], v[44:47], v[152:155], v[68:71]
	v_mfma_f32_16x16x32_bf16 v[36:39], v[52:55], v[152:155], v[36:39]
	v_mfma_f32_16x16x32_bf16 v[28:31], v[44:47], v[176:179], v[28:31]
	v_mfma_f32_16x16x32_bf16 v[20:23], v[52:55], v[176:179], v[20:23]
	v_mfma_f32_16x16x32_bf16 v[12:15], v[44:47], v[216:219], v[12:15]
	v_mfma_f32_16x16x32_bf16 v[8:11], v[52:55], v[216:219], v[8:11]
	v_mfma_f32_16x16x32_bf16 v[108:111], v[48:51], v[144:147], v[108:111]
	v_mfma_f32_16x16x32_bf16 v[76:79], v[56:59], v[144:147], v[76:79]
	v_mfma_f32_16x16x32_bf16 v[68:71], v[48:51], v[160:163], v[68:71]
	v_mfma_f32_16x16x32_bf16 v[36:39], v[56:59], v[160:163], v[36:39]
	v_mfma_f32_16x16x32_bf16 v[28:31], v[48:51], v[212:215], v[28:31]
	v_mfma_f32_16x16x32_bf16 v[20:23], v[56:59], v[212:215], v[20:23]
	v_mfma_f32_16x16x32_bf16 v[12:15], v[48:51], v[220:223], v[12:15]
	v_mfma_f32_16x16x32_bf16 v[8:11], v[56:59], v[220:223], v[8:11]
	s_setprio 0
	s_setprio 1
	v_mfma_f32_16x16x32_bf16 v[40:43], v[60:63], v[152:155], v[40:43]
	v_mfma_f32_16x16x32_bf16 v[32:35], v[80:83], v[152:155], v[32:35]
	v_mfma_f32_16x16x32_bf16 v[24:27], v[60:63], v[176:179], v[24:27]
	v_mfma_f32_16x16x32_bf16 v[16:19], v[80:83], v[176:179], v[16:19]
	v_mfma_f32_16x16x32_bf16 v[4:7], v[60:63], v[216:219], v[4:7]
	v_mfma_f32_16x16x32_bf16 v[0:3], v[80:83], v[216:219], v[0:3]
	v_mfma_f32_16x16x32_bf16 v[44:47], v[60:63], v[136:139], v[104:107]
	v_mfma_f32_16x16x32_bf16 v[48:51], v[80:83], v[136:139], v[72:75]
	v_mfma_f32_16x16x32_bf16 v[40:43], v[64:67], v[160:163], v[40:43]
	v_mfma_f32_16x16x32_bf16 v[32:35], v[84:87], v[160:163], v[32:35]
	v_mfma_f32_16x16x32_bf16 v[24:27], v[64:67], v[212:215], v[24:27]
	v_mfma_f32_16x16x32_bf16 v[16:19], v[84:87], v[212:215], v[16:19]
	v_mfma_f32_16x16x32_bf16 v[4:7], v[64:67], v[220:223], v[4:7]
	v_mfma_f32_16x16x32_bf16 v[0:3], v[84:87], v[220:223], v[0:3]
	v_mfma_f32_16x16x32_bf16 v[44:47], v[64:67], v[144:147], v[44:47]
	v_mfma_f32_16x16x32_bf16 v[48:51], v[84:87], v[144:147], v[48:51]
	s_setprio 0
	s_barrier
	s_add_i32 s75, 0, 0x18000
	s_add_i32 s76, 0, 0x1c000
	v_add_u32_e32 v64, s75, v195
	v_add_u32_e32 v72, s76, v195
	ds_read_b128 v[52:55], v64
	ds_read_b128 v[56:59], v64 offset:1024
	ds_read_b128 v[60:63], v64 offset:2048
	ds_read_b128 v[64:67], v64 offset:3072
	ds_read_b128 v[80:83], v72
	ds_read_b128 v[84:87], v72 offset:1024
	ds_read_b128 v[176:179], v72 offset:2048
	ds_read_b128 v[212:215], v72 offset:3072
	s_add_u32 s50, s50, 0x80000
	s_addc_u32 s51, s51, 0
	s_mov_b32 m0, s59
	v_lshl_add_u64 v[152:153], s[50:51], 0, v[180:181]
	ds_read_b128 v[72:75], v199 offset:32768
	ds_read_b128 v[104:107], v199 offset:33792
	ds_read_b128 v[136:139], v199 offset:34816
	ds_read_b128 v[144:147], v199 offset:35840
	ds_read_b128 v[216:219], v199 offset:36864
	ds_read_b128 v[220:223], v199 offset:37888
	ds_read_b128 v[224:227], v199 offset:38912
	ds_read_b128 v[228:231], v199 offset:39936
	global_load_lds_dwordx4 v[152:153], off
	v_lshl_add_u64 v[152:153], s[50:51], 0, v[184:185]
	s_mov_b32 m0, s60
	s_nop 0
	global_load_lds_dwordx4 v[152:153], off
	s_waitcnt vmcnt(8)
	s_waitcnt lgkmcnt(0)
	s_barrier
	s_setprio 1
	s_waitcnt lgkmcnt(0)
	v_mfma_f32_16x16x32_bf16 v[152:155], v[52:55], v[72:75], v[172:175]
	v_mfma_f32_16x16x32_bf16 v[172:175], v[56:59], v[104:107], v[152:155]
	v_mfma_f32_16x16x32_bf16 v[152:155], v[60:63], v[72:75], v[164:167]
	v_mfma_f32_16x16x32_bf16 v[164:167], v[64:67], v[104:107], v[152:155]
	v_mfma_f32_16x16x32_bf16 v[152:155], v[52:55], v[136:139], v[156:159]
	v_mfma_f32_16x16x32_bf16 v[148:151], v[60:63], v[136:139], v[148:151]
	v_mfma_f32_16x16x32_bf16 v[140:143], v[52:55], v[216:219], v[140:143]
	v_mfma_f32_16x16x32_bf16 v[132:135], v[60:63], v[216:219], v[132:135]
	v_mfma_f32_16x16x32_bf16 v[124:127], v[52:55], v[224:227], v[124:127]
	v_mfma_f32_16x16x32_bf16 v[120:123], v[60:63], v[224:227], v[120:123]
	v_mfma_f32_16x16x32_bf16 v[156:159], v[56:59], v[144:147], v[152:155]
	v_mfma_f32_16x16x32_bf16 v[148:151], v[64:67], v[144:147], v[148:151]
	v_mfma_f32_16x16x32_bf16 v[140:143], v[56:59], v[220:223], v[140:143]
	v_mfma_f32_16x16x32_bf16 v[132:135], v[64:67], v[220:223], v[132:135]
	v_mfma_f32_16x16x32_bf16 v[124:127], v[56:59], v[228:231], v[124:127]
	v_mfma_f32_16x16x32_bf16 v[120:123], v[64:67], v[228:231], v[120:123]
	s_setprio 0
	s_setprio 1
	v_mfma_f32_16x16x32_bf16 v[152:155], v[80:83], v[72:75], v[168:171]
	v_mfma_f32_16x16x32_bf16 v[72:75], v[176:179], v[72:75], v[88:91]
	v_mfma_f32_16x16x32_bf16 v[160:163], v[212:215], v[104:107], v[72:75]
	v_mfma_f32_16x16x32_bf16 v[72:75], v[80:83], v[136:139], v[92:95]
	v_mfma_f32_16x16x32_bf16 v[168:171], v[84:87], v[104:107], v[152:155]
	v_mfma_f32_16x16x32_bf16 v[152:155], v[84:87], v[144:147], v[72:75]
	v_mfma_f32_16x16x32_bf16 v[72:75], v[176:179], v[136:139], v[96:99]
	v_mfma_f32_16x16x32_bf16 v[144:147], v[212:215], v[144:147], v[72:75]
	v_mfma_f32_16x16x32_bf16 v[72:75], v[80:83], v[216:219], v[100:103]
	v_mfma_f32_16x16x32_bf16 v[136:139], v[84:87], v[220:223], v[72:75]
	v_mfma_f32_16x16x32_bf16 v[72:75], v[176:179], v[216:219], v[128:131]
	v_mfma_f32_16x16x32_bf16 v[128:131], v[212:215], v[220:223], v[72:75]
	v_mfma_f32_16x16x32_bf16 v[72:75], v[80:83], v[224:227], v[116:119]
	v_mfma_f32_16x16x32_bf16 v[116:119], v[84:87], v[228:231], v[72:75]
	v_mfma_f32_16x16x32_bf16 v[72:75], v[176:179], v[224:227], v[112:115]
	v_mfma_f32_16x16x32_bf16 v[112:115], v[212:215], v[228:231], v[72:75]
	s_setprio 0
	s_barrier
; #define PG8_STAGE(bufoff, gbase, voff) do { _Pragma("unroll") for (int _i = 0; _i < 2; ++_i) \
;         __builtin_amdgcn_global_load_lds((const unsigned*)((const char*)(gbase) + (voff)[_i]), (PG8_LAS unsigned*)(lds + (bufoff) + ldsw + _i * 8192), 16, 0, 0); } while (0)
; #define PG8_LDA(dst, b, h) do { _Pragma("unroll") for (int m = 0; m < 4; ++m) _Pragma("unroll") for (int k = 0; k < 2; ++k) dst[m][k] = *(const PG8_LAS bf16x8*)(lds + PG8_SA(b, h) + aoff + m * 2048 + k * 1024); } while (0)
; #define PG8_MMA(ai, bj, At, Bt) do { __builtin_amdgcn_s_setprio(1); _Pragma("unroll") for (int m = 0; m < 4; ++m) _Pragma("unroll") for (int n = 0; n < 2; ++n) _Pragma("unroll") for (int k = 0; k < 2; ++k) \
;         acc[ai][bj][m][n] = __builtin_amdgcn_mfma_f32_16x16x32_bf16(Bt[n][k], At[m][k], acc[ai][bj][m][n], 0, 0, 0); __builtin_amdgcn_s_setprio(0); } while (0)
; #define PG8_WAIT_V(n) asm volatile("s_waitcnt vmcnt(" #n ")" ::: "memory")
; #define PG8_WAIT_L(n) asm volatile("s_waitcnt lgkmcnt(" #n ")" ::: "memory")
; #define PG8_BAR __builtin_amdgcn_s_barrier()
; #define PG8_SCHED __builtin_amdgcn_sched_barrier(0)
; template <class Epi, class Sched, bool ALIGN_EPI = false, bool SP2 = false>
; __device__ __forceinline__ void gemm_phase(PG8_LAS unsigned char* lds, const Gemm g, const Sched& S, const Epi& E, const int wave_in) {
;     ...
;             PG8_LDA(At, 1, 1); PG8_STAGE(PG8_SB(1, 0), b3, voffB); PG8_STAGE(PG8_SB(1, 1), b3 + hstepB, voffB); PG8_STAGE(PG8_SA(1, 0), a3, voffA);
;             PG8_WAIT_V(8); PG8_WAIT_L(0); PG8_BAR; PG8_MMA(1, 0, At, B0); PG8_MMA(1, 1, At, B1); PG8_BAR; PG8_SCHED;
;     ...
;         if (!has_next) break;
	s_add_i32 s50, s75, s56
	v_lshl_add_u64 v[104:105], v[232:233], 0, s[22:23]
	s_mov_b32 m0, s50
	s_nop 1
	ds_read_b128 v[72:75], v199 offset:49152
	ds_read_b128 v[88:91], v199 offset:50176
	ds_read_b128 v[92:95], v199 offset:51200
	ds_read_b128 v[96:99], v199 offset:52224
	ds_read_b128 v[100:103], v199 offset:53248
	ds_read_b128 v[216:219], v199 offset:54272
	ds_read_b128 v[220:223], v199 offset:55296
	ds_read_b128 v[224:227], v199 offset:56320
	global_load_lds_dwordx4 v[104:105], off
	s_add_i32 m0, s50, 0x2000
	s_add_u32 s48, s48, 0x80080
	v_lshl_add_u64 v[104:105], v[234:235], 0, s[22:23]
	s_addc_u32 s49, s49, 0
	s_add_i32 s50, s76, s56
	global_load_lds_dwordx4 v[104:105], off
	v_lshl_add_u64 v[104:105], s[48:49], 0, v[182:183]
	s_mov_b32 m0, s50
	s_nop 0
	global_load_lds_dwordx4 v[104:105], off
	v_lshl_add_u64 v[104:105], s[48:49], 0, v[186:187]
	s_add_i32 m0, s50, 0x2000
	s_nop 0
	global_load_lds_dwordx4 v[104:105], off
	v_lshl_add_u64 v[104:105], v[236:237], 0, s[22:23]
	s_mov_b32 m0, s63
	s_nop 0
	global_load_lds_dwordx4 v[104:105], off
	v_lshl_add_u64 v[104:105], v[238:239], 0, s[22:23]
	s_mov_b32 m0, s64
	s_nop 0
	global_load_lds_dwordx4 v[104:105], off
	s_waitcnt vmcnt(8)
	s_waitcnt lgkmcnt(0)
	s_barrier
	s_setprio 1
	s_waitcnt lgkmcnt(0)
	v_mfma_f32_16x16x32_bf16 v[104:107], v[52:55], v[72:75], v[108:111]
	v_mfma_f32_16x16x32_bf16 v[76:79], v[60:63], v[72:75], v[76:79]
	v_mfma_f32_16x16x32_bf16 v[68:71], v[52:55], v[92:95], v[68:71]
	v_mfma_f32_16x16x32_bf16 v[36:39], v[60:63], v[92:95], v[36:39]
	v_mfma_f32_16x16x32_bf16 v[28:31], v[52:55], v[100:103], v[28:31]
	v_mfma_f32_16x16x32_bf16 v[20:23], v[60:63], v[100:103], v[20:23]
	v_mfma_f32_16x16x32_bf16 v[12:15], v[52:55], v[220:223], v[12:15]
	v_mfma_f32_16x16x32_bf16 v[8:11], v[60:63], v[220:223], v[8:11]
	v_mfma_f32_16x16x32_bf16 v[108:111], v[56:59], v[88:91], v[104:107]
	v_mfma_f32_16x16x32_bf16 v[76:79], v[64:67], v[88:91], v[76:79]
	v_mfma_f32_16x16x32_bf16 v[68:71], v[56:59], v[96:99], v[68:71]
	v_mfma_f32_16x16x32_bf16 v[36:39], v[64:67], v[96:99], v[36:39]
	v_mfma_f32_16x16x32_bf16 v[28:31], v[56:59], v[216:219], v[28:31]
	v_mfma_f32_16x16x32_bf16 v[20:23], v[64:67], v[216:219], v[20:23]
	v_mfma_f32_16x16x32_bf16 v[12:15], v[56:59], v[224:227], v[12:15]
	v_mfma_f32_16x16x32_bf16 v[8:11], v[64:67], v[224:227], v[8:11]
	s_setprio 0
	s_setprio 1
	v_mfma_f32_16x16x32_bf16 v[44:47], v[80:83], v[72:75], v[44:47]
	v_mfma_f32_16x16x32_bf16 v[104:107], v[84:87], v[88:91], v[44:47]
	v_mfma_f32_16x16x32_bf16 v[44:47], v[176:179], v[72:75], v[48:51]
	v_mfma_f32_16x16x32_bf16 v[40:43], v[80:83], v[92:95], v[40:43]
	v_mfma_f32_16x16x32_bf16 v[32:35], v[176:179], v[92:95], v[32:35]
	v_mfma_f32_16x16x32_bf16 v[24:27], v[80:83], v[100:103], v[24:27]
	v_mfma_f32_16x16x32_bf16 v[16:19], v[176:179], v[100:103], v[16:19]
	v_mfma_f32_16x16x32_bf16 v[4:7], v[80:83], v[220:223], v[4:7]
	v_mfma_f32_16x16x32_bf16 v[0:3], v[176:179], v[220:223], v[0:3]
	v_mfma_f32_16x16x32_bf16 v[72:75], v[212:215], v[88:91], v[44:47]
	v_mfma_f32_16x16x32_bf16 v[40:43], v[84:87], v[96:99], v[40:43]
	v_mfma_f32_16x16x32_bf16 v[32:35], v[212:215], v[96:99], v[32:35]
	v_mfma_f32_16x16x32_bf16 v[24:27], v[84:87], v[216:219], v[24:27]
	v_mfma_f32_16x16x32_bf16 v[16:19], v[212:215], v[216:219], v[16:19]
	v_mfma_f32_16x16x32_bf16 v[4:7], v[84:87], v[224:227], v[4:7]
	v_mfma_f32_16x16x32_bf16 v[0:3], v[212:215], v[224:227], v[0:3]
	s_setprio 0
	s_barrier
	s_add_i32 s74, s74, 2
	s_add_u32 s46, s46, 0x100
	s_addc_u32 s47, s47, 0
	s_add_u32 s72, s72, 0x100
	s_addc_u32 s73, s73, 0
	s_cmp_gt_u32 s74, 29
	s_cbranch_scc0 .LBB0_479
	s_mov_b32 s99, 1
	s_and_b64 vcc, exec, s[24:25]
	s_cbranch_vccz .LBB0_482
	s_barrier

; template <class Epi, class Sched, bool ALIGN_EPI = false, bool SP2 = false>
; __device__ __forceinline__ void gemm_phase(PG8_LAS unsigned char* lds, const Gemm g, const Sched& S, const Epi& E, const int wave_in) {
;     const int lane = lane_id_asm(), wid = __builtin_amdgcn_readfirstlane(wave_in), tid = wid * 64 + lane, wr = wid >> 2, wc = wid & 3, fr = lane & 15, fq = lane >> 4;
;     const int K = g.K, nt = K / BK;
;     unsigned voffA[2], voffB[2];
; #pragma unroll
;     for (int i = 0; i < 2; ++i) { int R, C; stage_rc(tid * 16 + i * 8192, R, C); const int Rb = Epi::PERM ? ((R & ~31) + perm32(R & 31)) : R;
;         voffA[i] = (unsigned)(R * g.lda + C) * 2u; voffB[i] = (unsigned)(Rb * K + C) * 2u; }
;     const size_t kstep = (size_t)(BK * 2);
;     const size_t hstepA = (size_t)HALF * g.lda * 2, hstepB = (size_t)HALF * K * 2;
;     const size_t tstepA = 2 * hstepA, tstepB = 2 * hstepB;
;     const unsigned ldsw = (unsigned)wid * 1024u;
;     const int aoff = lds_byte(wr * 64 + fr, fq * 8), boff = lds_byte(wc * 32 + fr, fq * 8);
;     ...
;     Unit cur, nxt; int ui = 0;
;     if (!S.next(0, cur)) return;
;     f32x4 acc[2][2][4][2];
; #pragma unroll
;     for (int a = 0; a < 2; ++a)
; #pragma unroll
;         for (int b = 0; b < 2; ++b)
; #pragma unroll
;             for (int m = 0; m < 4; ++m)
; #pragma unroll
;                 for (int n = 0; n < 2; ++n) acc[a][b][m][n] = (f32x4){0.f, 0.f, 0.f, 0.f};
;     bf16x8 At[4][2], B0[2][2], B1[2][2];
;     const char* cA = (const char*)g.A + (size_t)cur.pm * tstepA; const char* cB = (const char*)g.Bt + (size_t)cur.pn * tstepB;
;     S.a_ready(cur);
;     if constexpr (SP2) {
; template <int L> __device__ __forceinline__ void layer_body(Frame& F, const Args& args, unsigned char* const wsg, const int lo, const int hi, const XcdBarrier& bar) {
;     ...
;         if (IN(base + 7)) {
;             const int Mr = M_ALL - row_lo2;
;             pg8::Gemm g{(const pg8::bf16_t*)(wsg + WS_P) + (size_t)row_lo2 * DFF, (const pg8::bf16_t*)(wsg + WS_WT_DN), Mr, DM, DFF, DFF};
;             pg8::StaticOrder S; S.init(Mr, DM, F.G, (int)blockIdx.x);
;             typedef pg8::EpiResidT<true, !last> EpiD;
;             EpiD E{nullptr, nullptr, X16mid, X16A, args.out, (const float*)(wsg + WS_MOD) + (size_t)L * 17 * NMODC + 5 * DM, pm02, 0};
;             pg8::gemm_phase<EpiD, pg8::StaticOrder, true, true>(F.lds, g, S, E, F.wave);
.LBB0_621:
	s_cmp_gt_i32 s52, 8
	s_cselect_b64 s[0:1], -1, 0
	s_cmp_lt_i32 s53, 9
	s_cselect_b64 s[2:3], -1, 0
	s_or_b64 s[0:1], s[0:1], s[2:3]
	s_and_b64 vcc, exec, s[0:1]
	s_cbranch_vccnz .LBB0_692
	s_mov_b32 s99, 0
	s_cmpk_gt_i32 s73, 0x47f
	v_mbcnt_lo_u32_b32 v14, -1, 0
	v_mbcnt_hi_u32_b32 v14, -1, v14
	s_cbranch_scc1 .LBB0_642
	s_add_u32 s26, s70, 0xa700000
	s_addc_u32 s27, s71, 0
	s_add_u32 s28, s70, 0x9100000
	s_addc_u32 s29, s71, 0
	s_lshl_b32 s30, s33, 10
	v_lshl_add_u32 v0, v14, 4, s30
	v_add_u32_e32 v1, 0x2000, v0
	v_ashrrev_i32_e32 v2, 31, v1
	v_lshrrev_b32_e32 v2, 22, v2
	v_add_u32_e32 v2, v1, v2
	v_ashrrev_i32_e32 v8, 10, v2
	v_mul_i32_i24_e32 v2, 0x400, v8
	v_sub_u32_e32 v1, v1, v2
	v_lshrrev_b32_e32 v2, 4, v1
	v_bitop3_b32 v1, v2, v1, 32 bitop3:0x6c
	v_ashrrev_i32_e32 v2, 31, v1
	v_lshrrev_b32_e32 v2, 26, v2
	v_add_u32_e32 v2, v1, v2
	v_ashrrev_i32_e32 v9, 6, v2
	v_lshlrev_b32_e32 v3, 3, v8
	v_and_b32_e32 v2, 0xffc0, v2
	v_and_b32_e32 v3, -16, v3
	v_sub_u32_e32 v1, v1, v2
	v_add_u32_e32 v3, v9, v3
	v_lshrrev_b16_e32 v2, 7, v1
	v_and_b32_e32 v4, 3, v9
	s_mov_b32 s0, 0x1ffffe0
	v_lshrrev_b32_e32 v5, 2, v3
	v_lshlrev_b32_e32 v6, 1, v3
	v_and_b32_e32 v2, 1, v2
	v_and_or_b32 v4, v3, s0, v4
	v_and_b32_e32 v5, 4, v5
	v_and_b32_e32 v6, 24, v6
	v_add_u16_e32 v1, v1, v2
	v_mov_b32_e32 v2, 1
	v_or3_b32 v4, v4, v5, v6
	v_lshlrev_b32_e32 v5, 5, v8
	v_ashrrev_i16_sdwa v1, v2, sext(v1) dst_sel:DWORD dst_unused:UNUSED_PAD src0_sel:DWORD src1_sel:BYTE_0
	s_movk_i32 s2, 0x1580
	v_and_b32_e32 v10, 32, v5
	v_bfe_i32 v11, v1, 0, 16
	v_mul_lo_u32 v4, v4, s2
	v_add_u32_e32 v1, v10, v11
	v_mul_lo_u32 v3, v3, s2
	v_add_lshl_u32 v152, v4, v1, 1
	v_add_lshl_u32 v154, v1, v3, 1
	v_ashrrev_i32_e32 v1, 31, v0
	v_lshrrev_b32_e32 v1, 22, v1
	v_add_u32_e32 v1, v0, v1
	v_ashrrev_i32_e32 v12, 10, v1
	v_mul_i32_i24_e32 v1, 0x400, v12
	v_sub_u32_e32 v0, v0, v1
	v_lshrrev_b32_e32 v1, 4, v0
	v_bitop3_b32 v0, v1, v0, 32 bitop3:0x6c
	v_ashrrev_i32_e32 v1, 31, v0
	v_lshrrev_b32_e32 v1, 26, v1
	v_add_u32_e32 v1, v0, v1
	v_lshlrev_b32_e32 v3, 3, v12
	v_ashrrev_i32_e32 v13, 6, v1
	v_and_b32_e32 v3, -16, v3
	v_add_u32_e32 v3, v13, v3
	v_and_b32_e32 v4, 3, v13
	s_ashr_i32 s31, s73, 31
	v_and_or_b32 v4, v3, s0, v4
	s_lshr_b32 s0, s31, 29
	s_add_i32 s0, s73, s0
	s_ashr_i32 s1, s0, 3
	s_and_b32 s0, s0, -8
	s_ashr_i32 s3, s33, 2
	s_sub_i32 s0, s73, s0
	s_cmp_lt_i32 s0, 0
	s_movk_i32 s34, 0x91
	s_cselect_b32 s4, s34, 0x90
	s_mul_i32 s0, s4, s0
	s_add_i32 s0, s0, s1
	s_ashr_i32 s1, s0, 31
	s_lshr_b32 s1, s1, 27
	s_add_i32 s1, s0, s1
	s_ashr_i32 s4, s1, 5
	s_andn2_b32 s1, s1, 31
	s_sub_i32 s0, s0, s1
	s_bfe_i32 s1, s0, 0x80000
	s_bfe_u32 s1, s1, 0x2000d
	s_add_i32 s1, s0, s1
	s_lshl_b32 s5, s4, 2
	s_bfe_i32 s4, s1, 0x80000
	s_and_b32 s1, s1, 0xfc
	s_sub_i32 s0, s0, s1
	v_lshrrev_b32_e32 v5, 2, v3
	v_lshlrev_b32_e32 v6, 1, v3
	v_and_b32_e32 v1, 0xc0, v1
	s_sext_i32_i16 s6, s4
	s_sext_i32_i8 s0, s0
	v_and_b32_e32 v5, 4, v5
	v_and_b32_e32 v6, 24, v6
	v_sub_u32_e32 v0, v0, v1
	s_add_i32 s16, s5, s0
	s_ashr_i32 s0, s6, 2
	v_or3_b32 v4, v4, v5, v6
	v_lshlrev_b32_e32 v5, 5, v12
	v_ashrrev_i16_sdwa v0, v2, sext(v0) dst_sel:DWORD dst_unused:UNUSED_PAD src0_sel:DWORD src1_sel:BYTE_0
	s_lshr_b32 s4, s6, 2
	s_mul_hi_i32 s1, s0, 0x2b0000
	s_mul_i32 s0, s0, 0x2b0000
	v_and_b32_e32 v15, 32, v5
	v_bfe_i32 v16, v0, 0, 16
	s_add_u32 s20, s28, s0
	v_mul_lo_u32 v4, v4, s2
	v_add_u32_e32 v0, v15, v16
	s_addc_u32 s21, s29, s1
	s_add_i32 s35, s30, 0
	v_add_lshl_u32 v156, v4, v0, 1
	s_add_i32 m0, s35, 0x10000
	s_mul_i32 s7, s16, 0x2b0000
	global_load_lds_dwordx4 v156, s[20:21]
	s_add_i32 m0, s35, 0x12000
	s_add_u32 s0, s20, 0x158000
	global_load_lds_dwordx4 v152, s[20:21]
	s_addc_u32 s1, s21, 0
	s_add_i32 m0, s35, 0x14000
	s_mul_hi_i32 s5, s16, 0x2b0000
	global_load_lds_dwordx4 v156, s[0:1]
	s_add_i32 m0, s35, 0x16000
	s_add_u32 s18, s26, s7
	v_mul_lo_u32 v1, v3, s2
	s_addc_u32 s19, s27, s5
	s_add_i32 s36, s35, 0x2000
	v_add_lshl_u32 v158, v0, v1, 1
	global_load_lds_dwordx4 v152, s[0:1]
	s_mov_b32 m0, s35
	s_add_u32 s0, s18, 0x158000
	global_load_lds_dwordx4 v158, s[18:19]
	s_mov_b32 m0, s36
	s_addc_u32 s1, s19, 0
	s_add_i32 s37, s35, 0x4000
	global_load_lds_dwordx4 v154, s[18:19]
	s_mov_b32 m0, s37
	s_add_i32 s38, s35, 0x6000
	global_load_lds_dwordx4 v158, s[0:1]
	s_mov_b32 m0, s38
	v_mov_b32_e32 v157, 0
	global_load_lds_dwordx4 v154, s[0:1]
	v_mov_b32_e32 v153, v157
	v_mov_b32_e32 v159, v157
	v_mov_b32_e32 v155, v157
	s_cmp_eq_u32 s3, 1
	s_mov_b32 s39, 0
	v_lshl_add_u64 v[6:7], s[20:21], 0, v[156:157]
	v_lshl_add_u64 v[4:5], s[20:21], 0, v[152:153]
	v_lshl_add_u64 v[0:1], s[18:19], 0, v[158:159]
	s_cselect_b64 s[0:1], -1, 0
	s_cmp_lg_u32 s3, 1
	v_lshl_add_u64 v[2:3], s[18:19], 0, v[154:155]
	s_cbranch_scc1 .LBB0_625
	s_barrier

;     __host__ __device__ bool next(int i, Unit& u) const { const bool ok = StaticOrder::next(i, u); u.pm = 0; u.pn = 0; return ok; }
; #define PG8_STAGE(bufoff, gbase, voff) do { _Pragma("unroll") for (int _i = 0; _i < 2; ++_i) \
;         __builtin_amdgcn_global_load_lds((const unsigned*)((const char*)(gbase) + (voff)[_i]), (PG8_LAS unsigned*)(lds + (bufoff) + ldsw + _i * 8192), 16, 0, 0); } while (0)
; #define PG8_LDA(dst, b, h) do { _Pragma("unroll") for (int m = 0; m < 4; ++m) _Pragma("unroll") for (int k = 0; k < 2; ++k) dst[m][k] = *(const PG8_LAS bf16x8*)(lds + PG8_SA(b, h) + aoff + m * 2048 + k * 1024); } while (0)
; template <class Epi, class Sched, bool ALIGN_EPI = false, bool SP2 = false>
; __device__ __forceinline__ void gemm_phase(PG8_LAS unsigned char* lds, const Gemm g, const Sched& S, const Epi& E, const int wave_in) {
;     ...
;     for (;;) {
;         const bool has_next = S.next(ui + 1, nxt);
;         const char* nA = has_next ? (const char*)g.A + (size_t)nxt.pm * tstepA : cA; const char* nB = has_next ? (const char*)g.Bt + (size_t)nxt.pn * tstepB : cB;
;         for (int t = 0; t < nt; t += 2) {
;             const bool last = (t == nt - 2);
;             const char* a1 = cA + (size_t)(t + 1) * kstep;
;             const char* a2 = last ? nA : cA + (size_t)(t + 2) * kstep; const char* b2 = last ? nB : cB + (size_t)(t + 2) * kstep;
;             const char* a3 = a2 + kstep; const char* b3 = b2 + kstep;
;             if (last && has_next) S.a_ready(nxt);
;             if constexpr (SP2) {
;             PG8_LDB(B0, 0, 0); PG8_LDB(B1, 0, 1); PG8_SCHED; PG8_LDA(At, 0, 0); PG8_STAGE(PG8_SA(1, 1), a1 + hstepA, voffA);
;             PG8_WAIT_V(8); PG8_WAIT_L(0); PG8_BAR; PG8_MMA(0, 0, At, B0); PG8_MMA(0, 1, At, B1); PG8_BAR; PG8_SCHED;
;             PG8_LDA(At, 0, 1); PG8_STAGE(PG8_SB(0, 0), b2, voffB); PG8_STAGE(PG8_SB(0, 1), b2 + hstepB, voffB); PG8_STAGE(PG8_SA(0, 0), a2, voffA);
;             PG8_WAIT_V(8); PG8_WAIT_L(0); PG8_BAR; PG8_MMA(1, 0, At, B0); PG8_MMA(1, 1, At, B1); PG8_BAR; PG8_SCHED;
;     ...
; #pragma unroll
;         for (int a = 0; a < 2; ++a)
; #pragma unroll
;             for (int b = 0; b < 2; ++b)
; #pragma unroll
;                 for (int m = 0; m < 4; ++m)
; #pragma unroll
;                     for (int n = 0; n < 2; ++n) acc[a][b][m][n] = (f32x4){0.f, 0.f, 0.f, 0.f};
;         cur = nxt; cA = nA; cB = nB; ++ui;
.LBB0_634:
	s_add_u32 s17, s20, 0x100
	v_mov_b32_e32 v0, 0
	s_addc_u32 s52, s21, 0
	s_mov_b32 s53, -2
	v_mov_b32_e32 v1, v0
	v_mov_b32_e32 v2, v0
	v_mov_b32_e32 v3, v0
	v_mov_b32_e32 v4, v0
	v_mov_b32_e32 v5, v0
	v_mov_b32_e32 v6, v0
	v_mov_b32_e32 v7, v0
	v_mov_b32_e32 v12, v0
	v_mov_b32_e32 v13, v0
	v_mov_b32_e32 v14, v0
	v_mov_b32_e32 v15, v0
	v_mov_b32_e32 v20, v0
	v_mov_b32_e32 v21, v0
	v_mov_b32_e32 v22, v0
	v_mov_b32_e32 v23, v0
	v_mov_b32_e32 v28, v0
	v_mov_b32_e32 v29, v0
	v_mov_b32_e32 v30, v0
	v_mov_b32_e32 v31, v0
	v_mov_b32_e32 v36, v0
	v_mov_b32_e32 v37, v0
	v_mov_b32_e32 v38, v0
	v_mov_b32_e32 v39, v0
	v_mov_b32_e32 v44, v0
	v_mov_b32_e32 v45, v0
	v_mov_b32_e32 v46, v0
	v_mov_b32_e32 v47, v0
	v_mov_b32_e32 v52, v0
	v_mov_b32_e32 v53, v0
	v_mov_b32_e32 v54, v0
	v_mov_b32_e32 v55, v0
	v_mov_b32_e32 v8, v0
	v_mov_b32_e32 v9, v0
	v_mov_b32_e32 v10, v0
	v_mov_b32_e32 v11, v0
	v_mov_b32_e32 v16, v0
	v_mov_b32_e32 v17, v0
	v_mov_b32_e32 v18, v0
	v_mov_b32_e32 v19, v0
	v_mov_b32_e32 v24, v0
	v_mov_b32_e32 v25, v0
	v_mov_b32_e32 v26, v0
	v_mov_b32_e32 v27, v0
	v_mov_b32_e32 v32, v0
	v_mov_b32_e32 v33, v0
	v_mov_b32_e32 v34, v0
	v_mov_b32_e32 v35, v0
	v_mov_b32_e32 v40, v0
	v_mov_b32_e32 v41, v0
	v_mov_b32_e32 v42, v0
	v_mov_b32_e32 v43, v0
	v_mov_b32_e32 v48, v0
	v_mov_b32_e32 v49, v0
	v_mov_b32_e32 v50, v0
	v_mov_b32_e32 v51, v0
	v_mov_b32_e32 v56, v0
	v_mov_b32_e32 v57, v0
	v_mov_b32_e32 v58, v0
	v_mov_b32_e32 v59, v0
	v_mov_b32_e32 v60, v0
	v_mov_b32_e32 v61, v0
	v_mov_b32_e32 v62, v0
	v_mov_b32_e32 v63, v0
	v_mov_b32_e32 v80, v0
	v_mov_b32_e32 v81, v0
	v_mov_b32_e32 v82, v0
	v_mov_b32_e32 v83, v0
	v_mov_b32_e32 v84, v0
	v_mov_b32_e32 v85, v0
	v_mov_b32_e32 v86, v0
	v_mov_b32_e32 v87, v0
	v_mov_b32_e32 v88, v0
	v_mov_b32_e32 v89, v0
	v_mov_b32_e32 v90, v0
	v_mov_b32_e32 v91, v0
	v_mov_b32_e32 v92, v0
	v_mov_b32_e32 v93, v0
	v_mov_b32_e32 v94, v0
	v_mov_b32_e32 v95, v0
	v_mov_b32_e32 v104, v0
	v_mov_b32_e32 v105, v0
	v_mov_b32_e32 v106, v0
	v_mov_b32_e32 v107, v0
	v_mov_b32_e32 v108, v0
	v_mov_b32_e32 v109, v0
	v_mov_b32_e32 v110, v0
	v_mov_b32_e32 v111, v0
	v_mov_b32_e32 v124, v0
	v_mov_b32_e32 v125, v0
	v_mov_b32_e32 v126, v0
	v_mov_b32_e32 v127, v0
	v_mov_b32_e32 v132, v0
	v_mov_b32_e32 v133, v0
	v_mov_b32_e32 v134, v0
	v_mov_b32_e32 v135, v0
	v_mov_b32_e32 v96, v0
	v_mov_b32_e32 v97, v0
	v_mov_b32_e32 v98, v0
	v_mov_b32_e32 v99, v0
	v_mov_b32_e32 v100, v0
	v_mov_b32_e32 v101, v0
	v_mov_b32_e32 v102, v0
	v_mov_b32_e32 v103, v0
	v_mov_b32_e32 v112, v0
	v_mov_b32_e32 v113, v0
	v_mov_b32_e32 v114, v0
	v_mov_b32_e32 v115, v0
	v_mov_b32_e32 v116, v0
	v_mov_b32_e32 v117, v0
	v_mov_b32_e32 v118, v0
	v_mov_b32_e32 v119, v0
	v_mov_b32_e32 v120, v0
	v_mov_b32_e32 v121, v0
	v_mov_b32_e32 v122, v0
	v_mov_b32_e32 v123, v0
	v_mov_b32_e32 v128, v0
	v_mov_b32_e32 v129, v0
	v_mov_b32_e32 v130, v0
	v_mov_b32_e32 v131, v0
	v_mov_b32_e32 v136, v0
	v_mov_b32_e32 v137, v0
	v_mov_b32_e32 v138, v0
	v_mov_b32_e32 v139, v0
	v_mov_b32_e32 v140, v0
	v_mov_b32_e32 v141, v0
	v_mov_b32_e32 v142, v0
	v_mov_b32_e32 v143, v0
	s_cmp_lg_u32 s99, 0
	s_cbranch_scc0 .LBB0_635
	ds_read_b128 v[64:67], v230
	ds_read_b128 v[68:71], v230 offset:1024
	ds_read_b128 v[72:75], v230 offset:2048
	ds_read_b128 v[76:79], v230 offset:3072
	ds_read_b128 v[144:147], v231
	ds_read_b128 v[148:151], v231 offset:1024
	ds_read_b128 v[170:173], v231 offset:2048
	ds_read_b128 v[174:177], v231 offset:3072
	s_add_u32 s20, s18, 0x100
	s_addc_u32 s21, s19, 0
	s_cmpk_eq_i32 s53, 0x52
	s_cselect_b32 s25, s5, s21
	s_cselect_b32 s24, s4, s20
	s_cselect_b32 s23, s15, s52
	s_cselect_b32 s22, s14, s17
	v_lshl_add_u64 v[210:211], s[18:19], 0, v[162:163]
	s_add_i32 m0, s35, 0xc000
	ds_read_b128 v[178:181], v232
	ds_read_b128 v[182:185], v232 offset:1024
	ds_read_b128 v[186:189], v232 offset:2048
	ds_read_b128 v[190:193], v232 offset:3072
	ds_read_b128 v[194:197], v232 offset:4096
	ds_read_b128 v[198:201], v232 offset:5120
	ds_read_b128 v[202:205], v232 offset:6144
	ds_read_b128 v[206:209], v232 offset:7168
	global_load_lds_dwordx4 v[210:211], off
	v_lshl_add_u64 v[210:211], s[18:19], 0, v[164:165]
	s_add_i32 m0, s35, 0xe000
	s_nop 0
	global_load_lds_dwordx4 v[210:211], off
	s_waitcnt vmcnt(24)
	s_waitcnt lgkmcnt(0)
	s_barrier
	s_setprio 1
	s_waitcnt lgkmcnt(0)
	v_mfma_f32_16x16x32_bf16 v[140:143], v[64:67], v[178:181], v[140:143]
	v_mfma_f32_16x16x32_bf16 v[136:139], v[72:75], v[178:181], v[136:139]
	v_mfma_f32_16x16x32_bf16 v[128:131], v[64:67], v[186:189], v[128:131]
	v_mfma_f32_16x16x32_bf16 v[120:123], v[72:75], v[186:189], v[120:123]
	v_mfma_f32_16x16x32_bf16 v[116:119], v[64:67], v[194:197], v[116:119]
	v_mfma_f32_16x16x32_bf16 v[112:115], v[72:75], v[194:197], v[112:115]
	v_mfma_f32_16x16x32_bf16 v[100:103], v[64:67], v[202:205], v[100:103]
	v_mfma_f32_16x16x32_bf16 v[96:99], v[72:75], v[202:205], v[96:99]
	v_mfma_f32_16x16x32_bf16 v[140:143], v[68:71], v[182:185], v[140:143]
	v_mfma_f32_16x16x32_bf16 v[136:139], v[76:79], v[182:185], v[136:139]
	v_mfma_f32_16x16x32_bf16 v[128:131], v[68:71], v[190:193], v[128:131]
	v_mfma_f32_16x16x32_bf16 v[120:123], v[76:79], v[190:193], v[120:123]
	v_mfma_f32_16x16x32_bf16 v[116:119], v[68:71], v[198:201], v[116:119]
	v_mfma_f32_16x16x32_bf16 v[112:115], v[76:79], v[198:201], v[112:115]
	v_mfma_f32_16x16x32_bf16 v[100:103], v[68:71], v[206:209], v[100:103]
	v_mfma_f32_16x16x32_bf16 v[96:99], v[76:79], v[206:209], v[96:99]
	s_setprio 0
	s_setprio 1
	v_mfma_f32_16x16x32_bf16 v[132:135], v[144:147], v[178:181], v[132:135]
	v_mfma_f32_16x16x32_bf16 v[124:127], v[170:173], v[178:181], v[124:127]
	v_mfma_f32_16x16x32_bf16 v[108:111], v[144:147], v[186:189], v[108:111]
	v_mfma_f32_16x16x32_bf16 v[104:107], v[170:173], v[186:189], v[104:107]
	v_mfma_f32_16x16x32_bf16 v[92:95], v[144:147], v[194:197], v[92:95]
	v_mfma_f32_16x16x32_bf16 v[88:91], v[170:173], v[194:197], v[88:91]
	v_mfma_f32_16x16x32_bf16 v[84:87], v[144:147], v[202:205], v[84:87]
	v_mfma_f32_16x16x32_bf16 v[80:83], v[170:173], v[202:205], v[80:83]
	v_mfma_f32_16x16x32_bf16 v[132:135], v[148:151], v[182:185], v[132:135]
	v_mfma_f32_16x16x32_bf16 v[124:127], v[174:177], v[182:185], v[124:127]
	v_mfma_f32_16x16x32_bf16 v[108:111], v[148:151], v[190:193], v[108:111]
	v_mfma_f32_16x16x32_bf16 v[104:107], v[174:177], v[190:193], v[104:107]
	v_mfma_f32_16x16x32_bf16 v[92:95], v[148:151], v[198:201], v[92:95]
	v_mfma_f32_16x16x32_bf16 v[88:91], v[174:177], v[198:201], v[88:91]
	v_mfma_f32_16x16x32_bf16 v[84:87], v[148:151], v[206:209], v[84:87]
	v_mfma_f32_16x16x32_bf16 v[80:83], v[174:177], v[206:209], v[80:83]
	s_setprio 0
	s_barrier
; #define PG8_STAGE(bufoff, gbase, voff) do { _Pragma("unroll") for (int _i = 0; _i < 2; ++_i) \
;         __builtin_amdgcn_global_load_lds((const unsigned*)((const char*)(gbase) + (voff)[_i]), (PG8_LAS unsigned*)(lds + (bufoff) + ldsw + _i * 8192), 16, 0, 0); } while (0)
; #define PG8_LDA(dst, b, h) do { _Pragma("unroll") for (int m = 0; m < 4; ++m) _Pragma("unroll") for (int k = 0; k < 2; ++k) dst[m][k] = *(const PG8_LAS bf16x8*)(lds + PG8_SA(b, h) + aoff + m * 2048 + k * 1024); } while (0)
; #define PG8_LDB(dst, b, h) do { _Pragma("unroll") for (int n = 0; n < 2; ++n) _Pragma("unroll") for (int k = 0; k < 2; ++k) dst[n][k] = *(const PG8_LAS bf16x8*)(lds + PG8_SB(b, h) + boff + n * 2048 + k * 1024); } while (0)
; #define PG8_MMA(ai, bj, At, Bt) do { __builtin_amdgcn_s_setprio(1); _Pragma("unroll") for (int m = 0; m < 4; ++m) _Pragma("unroll") for (int n = 0; n < 2; ++n) _Pragma("unroll") for (int k = 0; k < 2; ++k) \
;         acc[ai][bj][m][n] = __builtin_amdgcn_mfma_f32_16x16x32_bf16(Bt[n][k], At[m][k], acc[ai][bj][m][n], 0, 0, 0); __builtin_amdgcn_s_setprio(0); } while (0)
; #define PG8_WAIT_V(n) asm volatile("s_waitcnt vmcnt(" #n ")" ::: "memory")
; #define PG8_WAIT_L(n) asm volatile("s_waitcnt lgkmcnt(" #n ")" ::: "memory")
; #define PG8_BAR __builtin_amdgcn_s_barrier()
; #define PG8_SCHED __builtin_amdgcn_sched_barrier(0)
; template <class Epi, class Sched, bool ALIGN_EPI = false, bool SP2 = false>
; __device__ __forceinline__ void gemm_phase(PG8_LAS unsigned char* lds, const Gemm g, const Sched& S, const Epi& E, const int wave_in) {
;     ...
;             PG8_LDA(At, 0, 1); PG8_STAGE(PG8_SB(0, 0), b2, voffB); PG8_STAGE(PG8_SB(0, 1), b2 + hstepB, voffB); PG8_STAGE(PG8_SA(0, 0), a2, voffA);
;             PG8_WAIT_V(8); PG8_WAIT_L(0); PG8_BAR; PG8_MMA(1, 0, At, B0); PG8_MMA(1, 1, At, B1); PG8_BAR; PG8_SCHED;
;             PG8_LDB(B0, 1, 0); PG8_LDB(B1, 1, 1); PG8_SCHED; PG8_LDA(At, 1, 0); PG8_STAGE(PG8_SA(0, 1), a2 + hstepA, voffA);
;             PG8_WAIT_V(8); PG8_WAIT_L(0); PG8_BAR; PG8_MMA(0, 0, At, B0); PG8_MMA(0, 1, At, B1); PG8_BAR; PG8_SCHED;
	s_add_i32 s18, s45, s30
	v_lshl_add_u64 v[210:211], s[22:23], 0, v[156:157]
	s_mov_b32 m0, s18
	ds_read_b128 v[178:181], v232 offset:16384
	ds_read_b128 v[182:185], v232 offset:17408
	ds_read_b128 v[186:189], v232 offset:18432
	ds_read_b128 v[190:193], v232 offset:19456
	ds_read_b128 v[194:197], v232 offset:20480
	ds_read_b128 v[198:201], v232 offset:21504
	ds_read_b128 v[202:205], v232 offset:22528
	ds_read_b128 v[206:209], v232 offset:23552
	global_load_lds_dwordx4 v[210:211], off
	s_add_i32 m0, s18, 0x2000
	s_add_u32 s18, s22, 0x158000
	v_lshl_add_u64 v[212:213], s[22:23], 0, v[152:153]
	s_addc_u32 s19, s23, 0
	s_add_i32 s54, s46, s30
	global_load_lds_dwordx4 v[212:213], off
	v_lshl_add_u64 v[214:215], s[18:19], 0, v[156:157]
	s_mov_b32 m0, s54
	v_lshl_add_u64 v[216:217], s[24:25], 0, v[154:155]
	global_load_lds_dwordx4 v[214:215], off
	v_lshl_add_u64 v[214:215], s[18:19], 0, v[152:153]
	s_add_i32 m0, s54, 0x2000
	s_nop 0
	global_load_lds_dwordx4 v[214:215], off
	v_lshl_add_u64 v[214:215], s[24:25], 0, v[158:159]
	s_mov_b32 m0, s35
	s_nop 0
	global_load_lds_dwordx4 v[214:215], off
	s_mov_b32 m0, s36
	s_nop 0
	global_load_lds_dwordx4 v[216:217], off
	s_waitcnt vmcnt(24)
	s_waitcnt lgkmcnt(0)
	s_barrier
	s_setprio 1
	s_waitcnt lgkmcnt(0)
	v_mfma_f32_16x16x32_bf16 v[60:63], v[64:67], v[178:181], v[60:63]
	v_mfma_f32_16x16x32_bf16 v[56:59], v[72:75], v[178:181], v[56:59]
	v_mfma_f32_16x16x32_bf16 v[48:51], v[64:67], v[186:189], v[48:51]
	v_mfma_f32_16x16x32_bf16 v[40:43], v[72:75], v[186:189], v[40:43]
	v_mfma_f32_16x16x32_bf16 v[32:35], v[64:67], v[194:197], v[32:35]
	v_mfma_f32_16x16x32_bf16 v[24:27], v[72:75], v[194:197], v[24:27]
	v_mfma_f32_16x16x32_bf16 v[16:19], v[64:67], v[202:205], v[16:19]
	v_mfma_f32_16x16x32_bf16 v[8:11], v[72:75], v[202:205], v[8:11]
	v_mfma_f32_16x16x32_bf16 v[60:63], v[68:71], v[182:185], v[60:63]
	v_mfma_f32_16x16x32_bf16 v[56:59], v[76:79], v[182:185], v[56:59]
	v_mfma_f32_16x16x32_bf16 v[48:51], v[68:71], v[190:193], v[48:51]
	v_mfma_f32_16x16x32_bf16 v[40:43], v[76:79], v[190:193], v[40:43]
	v_mfma_f32_16x16x32_bf16 v[32:35], v[68:71], v[198:201], v[32:35]
	v_mfma_f32_16x16x32_bf16 v[24:27], v[76:79], v[198:201], v[24:27]
	v_mfma_f32_16x16x32_bf16 v[16:19], v[68:71], v[206:209], v[16:19]
	v_mfma_f32_16x16x32_bf16 v[8:11], v[76:79], v[206:209], v[8:11]
	s_setprio 0
	s_setprio 1
	v_mfma_f32_16x16x32_bf16 v[52:55], v[144:147], v[178:181], v[52:55]
	v_mfma_f32_16x16x32_bf16 v[44:47], v[170:173], v[178:181], v[44:47]
	v_mfma_f32_16x16x32_bf16 v[36:39], v[144:147], v[186:189], v[36:39]
	v_mfma_f32_16x16x32_bf16 v[28:31], v[170:173], v[186:189], v[28:31]
	v_mfma_f32_16x16x32_bf16 v[20:23], v[144:147], v[194:197], v[20:23]
	v_mfma_f32_16x16x32_bf16 v[12:15], v[170:173], v[194:197], v[12:15]
	v_mfma_f32_16x16x32_bf16 v[4:7], v[144:147], v[202:205], v[4:7]
	v_mfma_f32_16x16x32_bf16 v[0:3], v[170:173], v[202:205], v[0:3]
	v_mfma_f32_16x16x32_bf16 v[52:55], v[148:151], v[182:185], v[52:55]
	v_mfma_f32_16x16x32_bf16 v[44:47], v[174:177], v[182:185], v[44:47]
	v_mfma_f32_16x16x32_bf16 v[36:39], v[148:151], v[190:193], v[36:39]
	v_mfma_f32_16x16x32_bf16 v[28:31], v[174:177], v[190:193], v[28:31]
	v_mfma_f32_16x16x32_bf16 v[20:23], v[148:151], v[198:201], v[20:23]
	v_mfma_f32_16x16x32_bf16 v[12:15], v[174:177], v[198:201], v[12:15]
	v_mfma_f32_16x16x32_bf16 v[4:7], v[148:151], v[206:209], v[4:7]
	v_mfma_f32_16x16x32_bf16 v[0:3], v[174:177], v[206:209], v[0:3]
	s_setprio 0
	s_barrier
	s_add_i32 s54, 0, 0x18000
	s_add_i32 s55, 0, 0x1c000
	v_add_u32_e32 v76, s54, v228
	v_add_u32_e32 v174, s55, v228
	ds_read_b128 v[64:67], v76
	ds_read_b128 v[68:71], v76 offset:1024
	ds_read_b128 v[72:75], v76 offset:2048
	ds_read_b128 v[76:79], v76 offset:3072
	ds_read_b128 v[144:147], v174
	ds_read_b128 v[148:151], v174 offset:1024
	ds_read_b128 v[170:173], v174 offset:2048
	ds_read_b128 v[174:177], v174 offset:3072
	s_add_u32 s18, s24, 0x158000
	s_addc_u32 s19, s25, 0
	s_mov_b32 m0, s37
	v_lshl_add_u64 v[218:219], s[18:19], 0, v[158:159]
	ds_read_b128 v[178:181], v232 offset:32768
	ds_read_b128 v[182:185], v232 offset:33792
	ds_read_b128 v[186:189], v232 offset:34816
	ds_read_b128 v[190:193], v232 offset:35840
	ds_read_b128 v[194:197], v232 offset:36864
	ds_read_b128 v[198:201], v232 offset:37888
	ds_read_b128 v[202:205], v232 offset:38912
	ds_read_b128 v[206:209], v232 offset:39936
	global_load_lds_dwordx4 v[218:219], off
	v_lshl_add_u64 v[218:219], s[18:19], 0, v[154:155]
	s_mov_b32 m0, s38
	s_nop 0
	global_load_lds_dwordx4 v[218:219], off
	s_waitcnt vmcnt(8)
	s_waitcnt lgkmcnt(0)
	s_barrier
; #define PG8_STAGE(bufoff, gbase, voff) do { _Pragma("unroll") for (int _i = 0; _i < 2; ++_i) \
;         __builtin_amdgcn_global_load_lds((const unsigned*)((const char*)(gbase) + (voff)[_i]), (PG8_LAS unsigned*)(lds + (bufoff) + ldsw + _i * 8192), 16, 0, 0); } while (0)
; #define PG8_LDA(dst, b, h) do { _Pragma("unroll") for (int m = 0; m < 4; ++m) _Pragma("unroll") for (int k = 0; k < 2; ++k) dst[m][k] = *(const PG8_LAS bf16x8*)(lds + PG8_SA(b, h) + aoff + m * 2048 + k * 1024); } while (0)
; #define PG8_MMA(ai, bj, At, Bt) do { __builtin_amdgcn_s_setprio(1); _Pragma("unroll") for (int m = 0; m < 4; ++m) _Pragma("unroll") for (int n = 0; n < 2; ++n) _Pragma("unroll") for (int k = 0; k < 2; ++k) \
;         acc[ai][bj][m][n] = __builtin_amdgcn_mfma_f32_16x16x32_bf16(Bt[n][k], At[m][k], acc[ai][bj][m][n], 0, 0, 0); __builtin_amdgcn_s_setprio(0); } while (0)
; #define PG8_WAIT_V(n) asm volatile("s_waitcnt vmcnt(" #n ")" ::: "memory")
; #define PG8_WAIT_L(n) asm volatile("s_waitcnt lgkmcnt(" #n ")" ::: "memory")
; #define PG8_BAR __builtin_amdgcn_s_barrier()
; #define PG8_SCHED __builtin_amdgcn_sched_barrier(0)
; template <class Epi, class Sched, bool ALIGN_EPI = false, bool SP2 = false>
; __device__ __forceinline__ void gemm_phase(PG8_LAS unsigned char* lds, const Gemm g, const Sched& S, const Epi& E, const int wave_in) {
;     ...
;             PG8_WAIT_V(8); PG8_WAIT_L(0); PG8_BAR; PG8_MMA(0, 0, At, B0); PG8_MMA(0, 1, At, B1); PG8_BAR; PG8_SCHED;
;             PG8_LDA(At, 1, 1); PG8_STAGE(PG8_SB(1, 0), b3, voffB); PG8_STAGE(PG8_SB(1, 1), b3 + hstepB, voffB); PG8_STAGE(PG8_SA(1, 0), a3, voffA);
;             PG8_WAIT_V(8); PG8_WAIT_L(0); PG8_BAR; PG8_MMA(1, 0, At, B0); PG8_MMA(1, 1, At, B1); PG8_BAR; PG8_SCHED;
	s_setprio 1
	s_waitcnt lgkmcnt(0)
	v_mfma_f32_16x16x32_bf16 v[140:143], v[64:67], v[178:181], v[140:143]
	v_mfma_f32_16x16x32_bf16 v[136:139], v[72:75], v[178:181], v[136:139]
	v_mfma_f32_16x16x32_bf16 v[128:131], v[64:67], v[186:189], v[128:131]
	v_mfma_f32_16x16x32_bf16 v[120:123], v[72:75], v[186:189], v[120:123]
	v_mfma_f32_16x16x32_bf16 v[116:119], v[64:67], v[194:197], v[116:119]
	v_mfma_f32_16x16x32_bf16 v[112:115], v[72:75], v[194:197], v[112:115]
	v_mfma_f32_16x16x32_bf16 v[100:103], v[64:67], v[202:205], v[100:103]
	v_mfma_f32_16x16x32_bf16 v[96:99], v[72:75], v[202:205], v[96:99]
	v_mfma_f32_16x16x32_bf16 v[140:143], v[68:71], v[182:185], v[140:143]
	v_mfma_f32_16x16x32_bf16 v[136:139], v[76:79], v[182:185], v[136:139]
	v_mfma_f32_16x16x32_bf16 v[128:131], v[68:71], v[190:193], v[128:131]
	v_mfma_f32_16x16x32_bf16 v[120:123], v[76:79], v[190:193], v[120:123]
	v_mfma_f32_16x16x32_bf16 v[116:119], v[68:71], v[198:201], v[116:119]
	v_mfma_f32_16x16x32_bf16 v[112:115], v[76:79], v[198:201], v[112:115]
	v_mfma_f32_16x16x32_bf16 v[100:103], v[68:71], v[206:209], v[100:103]
	v_mfma_f32_16x16x32_bf16 v[96:99], v[76:79], v[206:209], v[96:99]
	s_setprio 0
	s_setprio 1
	v_mfma_f32_16x16x32_bf16 v[132:135], v[144:147], v[178:181], v[132:135]
	v_mfma_f32_16x16x32_bf16 v[124:127], v[170:173], v[178:181], v[124:127]
	v_mfma_f32_16x16x32_bf16 v[108:111], v[144:147], v[186:189], v[108:111]
	v_mfma_f32_16x16x32_bf16 v[104:107], v[170:173], v[186:189], v[104:107]
	v_mfma_f32_16x16x32_bf16 v[92:95], v[144:147], v[194:197], v[92:95]
	v_mfma_f32_16x16x32_bf16 v[88:91], v[170:173], v[194:197], v[88:91]
	v_mfma_f32_16x16x32_bf16 v[84:87], v[144:147], v[202:205], v[84:87]
	v_mfma_f32_16x16x32_bf16 v[80:83], v[170:173], v[202:205], v[80:83]
	v_mfma_f32_16x16x32_bf16 v[132:135], v[148:151], v[182:185], v[132:135]
	v_mfma_f32_16x16x32_bf16 v[124:127], v[174:177], v[182:185], v[124:127]
	v_mfma_f32_16x16x32_bf16 v[108:111], v[148:151], v[190:193], v[108:111]
	v_mfma_f32_16x16x32_bf16 v[104:107], v[174:177], v[190:193], v[104:107]
	v_mfma_f32_16x16x32_bf16 v[92:95], v[148:151], v[198:201], v[92:95]
	v_mfma_f32_16x16x32_bf16 v[88:91], v[174:177], v[198:201], v[88:91]
	v_mfma_f32_16x16x32_bf16 v[84:87], v[148:151], v[206:209], v[84:87]
	v_mfma_f32_16x16x32_bf16 v[80:83], v[174:177], v[206:209], v[80:83]
	s_setprio 0
	s_barrier
	s_add_i32 s18, s54, s30
	v_lshl_add_u64 v[210:211], v[210:211], 0, s[6:7]
	s_mov_b32 m0, s18
	ds_read_b128 v[178:181], v232 offset:49152
	ds_read_b128 v[182:185], v232 offset:50176
	ds_read_b128 v[186:189], v232 offset:51200
	ds_read_b128 v[190:193], v232 offset:52224
	ds_read_b128 v[194:197], v232 offset:53248
	ds_read_b128 v[198:201], v232 offset:54272
	ds_read_b128 v[202:205], v232 offset:55296
	ds_read_b128 v[206:209], v232 offset:56320
	global_load_lds_dwordx4 v[210:211], off
	s_add_i32 m0, s18, 0x2000
	s_add_u32 s18, s22, 0x158080
	v_lshl_add_u64 v[210:211], v[212:213], 0, s[6:7]
	s_addc_u32 s19, s23, 0
	s_add_i32 s22, s55, s30
	global_load_lds_dwordx4 v[210:211], off
	v_lshl_add_u64 v[210:211], s[18:19], 0, v[156:157]
	s_mov_b32 m0, s22
	s_nop 0
	global_load_lds_dwordx4 v[210:211], off
	v_lshl_add_u64 v[210:211], s[18:19], 0, v[152:153]
	s_add_i32 m0, s22, 0x2000
	s_nop 0
	global_load_lds_dwordx4 v[210:211], off
	v_lshl_add_u64 v[210:211], v[214:215], 0, s[6:7]
	s_mov_b32 m0, s42
	s_nop 0
	global_load_lds_dwordx4 v[210:211], off
	v_lshl_add_u64 v[210:211], v[216:217], 0, s[6:7]
	s_mov_b32 m0, s43
	s_nop 0
	global_load_lds_dwordx4 v[210:211], off
	s_waitcnt vmcnt(8)
	s_waitcnt lgkmcnt(0)
	s_barrier
	s_setprio 1
	s_waitcnt lgkmcnt(0)
	v_mfma_f32_16x16x32_bf16 v[60:63], v[64:67], v[178:181], v[60:63]
	v_mfma_f32_16x16x32_bf16 v[56:59], v[72:75], v[178:181], v[56:59]
	v_mfma_f32_16x16x32_bf16 v[48:51], v[64:67], v[186:189], v[48:51]
	v_mfma_f32_16x16x32_bf16 v[40:43], v[72:75], v[186:189], v[40:43]
	v_mfma_f32_16x16x32_bf16 v[32:35], v[64:67], v[194:197], v[32:35]
	v_mfma_f32_16x16x32_bf16 v[24:27], v[72:75], v[194:197], v[24:27]
	v_mfma_f32_16x16x32_bf16 v[16:19], v[64:67], v[202:205], v[16:19]
	v_mfma_f32_16x16x32_bf16 v[8:11], v[72:75], v[202:205], v[8:11]
	v_mfma_f32_16x16x32_bf16 v[60:63], v[68:71], v[182:185], v[60:63]
	v_mfma_f32_16x16x32_bf16 v[56:59], v[76:79], v[182:185], v[56:59]
	v_mfma_f32_16x16x32_bf16 v[48:51], v[68:71], v[190:193], v[48:51]
	v_mfma_f32_16x16x32_bf16 v[40:43], v[76:79], v[190:193], v[40:43]
	v_mfma_f32_16x16x32_bf16 v[32:35], v[68:71], v[198:201], v[32:35]
	v_mfma_f32_16x16x32_bf16 v[24:27], v[76:79], v[198:201], v[24:27]
	v_mfma_f32_16x16x32_bf16 v[16:19], v[68:71], v[206:209], v[16:19]
	v_mfma_f32_16x16x32_bf16 v[8:11], v[76:79], v[206:209], v[8:11]
	s_setprio 0
	s_setprio 1
	v_mfma_f32_16x16x32_bf16 v[52:55], v[144:147], v[178:181], v[52:55]
	v_mfma_f32_16x16x32_bf16 v[44:47], v[170:173], v[178:181], v[44:47]
	v_mfma_f32_16x16x32_bf16 v[36:39], v[144:147], v[186:189], v[36:39]
	v_mfma_f32_16x16x32_bf16 v[28:31], v[170:173], v[186:189], v[28:31]
	v_mfma_f32_16x16x32_bf16 v[20:23], v[144:147], v[194:197], v[20:23]
	v_mfma_f32_16x16x32_bf16 v[12:15], v[170:173], v[194:197], v[12:15]
	v_mfma_f32_16x16x32_bf16 v[4:7], v[144:147], v[202:205], v[4:7]
	v_mfma_f32_16x16x32_bf16 v[0:3], v[170:173], v[202:205], v[0:3]
	v_mfma_f32_16x16x32_bf16 v[52:55], v[148:151], v[182:185], v[52:55]
	v_mfma_f32_16x16x32_bf16 v[44:47], v[174:177], v[182:185], v[44:47]
	v_mfma_f32_16x16x32_bf16 v[36:39], v[148:151], v[190:193], v[36:39]
	v_mfma_f32_16x16x32_bf16 v[28:31], v[174:177], v[190:193], v[28:31]
	v_mfma_f32_16x16x32_bf16 v[20:23], v[148:151], v[198:201], v[20:23]
	v_mfma_f32_16x16x32_bf16 v[12:15], v[174:177], v[198:201], v[12:15]
	v_mfma_f32_16x16x32_bf16 v[4:7], v[148:151], v[206:209], v[4:7]
	v_mfma_f32_16x16x32_bf16 v[0:3], v[174:177], v[206:209], v[0:3]
	s_setprio 0
	s_barrier
	s_add_i32 s53, s53, 2
	s_add_u32 s17, s17, 0x100
	s_addc_u32 s52, s52, 0
	s_cmpk_gt_u32 s53, 0x53
	s_mov_b64 s[18:19], s[20:21]
	s_cbranch_scc0 .LBB0_635
; #define PG8_STAGE(bufoff, gbase, voff) do { _Pragma("unroll") for (int _i = 0; _i < 2; ++_i) \
;         __builtin_amdgcn_global_load_lds((const unsigned*)((const char*)(gbase) + (voff)[_i]), (PG8_LAS unsigned*)(lds + (bufoff) + ldsw + _i * 8192), 16, 0, 0); } while (0)
; #define PG8_LDA(dst, b, h) do { _Pragma("unroll") for (int m = 0; m < 4; ++m) _Pragma("unroll") for (int k = 0; k < 2; ++k) dst[m][k] = *(const PG8_LAS bf16x8*)(lds + PG8_SA(b, h) + aoff + m * 2048 + k * 1024); } while (0)
; #define PG8_LDB(dst, b, h) do { _Pragma("unroll") for (int n = 0; n < 2; ++n) _Pragma("unroll") for (int k = 0; k < 2; ++k) dst[n][k] = *(const PG8_LAS bf16x8*)(lds + PG8_SB(b, h) + boff + n * 2048 + k * 1024); } while (0)
; #define PG8_MMA(ai, bj, At, Bt) do { __builtin_amdgcn_s_setprio(1); _Pragma("unroll") for (int m = 0; m < 4; ++m) _Pragma("unroll") for (int n = 0; n < 2; ++n) _Pragma("unroll") for (int k = 0; k < 2; ++k) \
;         acc[ai][bj][m][n] = __builtin_amdgcn_mfma_f32_16x16x32_bf16(Bt[n][k], At[m][k], acc[ai][bj][m][n], 0, 0, 0); __builtin_amdgcn_s_setprio(0); } while (0)
; #define PG8_WAIT_V(n) asm volatile("s_waitcnt vmcnt(" #n ")" ::: "memory")
; #define PG8_WAIT_L(n) asm volatile("s_waitcnt lgkmcnt(" #n ")" ::: "memory")
; #define PG8_BAR __builtin_amdgcn_s_barrier()
; #define PG8_SCHED __builtin_amdgcn_sched_barrier(0)
; template <class Epi, class Sched, bool ALIGN_EPI = false, bool SP2 = false>
; __device__ __forceinline__ void gemm_phase(PG8_LAS unsigned char* lds, const Gemm g, const Sched& S, const Epi& E, const int wave_in) {
;     ...
;             PG8_LDB(B0, 0, 0); PG8_LDB(B1, 0, 1); PG8_SCHED; PG8_LDA(At, 0, 0); PG8_STAGE(PG8_SA(1, 1), a1 + hstepA, voffA);
;             PG8_WAIT_V(8); PG8_WAIT_L(0); PG8_BAR; PG8_MMA(0, 0, At, B0); PG8_MMA(0, 1, At, B1); PG8_BAR; PG8_SCHED;
;             PG8_LDA(At, 0, 1); PG8_STAGE(PG8_SB(0, 0), b2, voffB); PG8_STAGE(PG8_SB(0, 1), b2 + hstepB, voffB); PG8_STAGE(PG8_SA(0, 0), a2, voffA);
;             PG8_WAIT_V(8); PG8_WAIT_L(0); PG8_BAR; PG8_MMA(1, 0, At, B0); PG8_MMA(1, 1, At, B1); PG8_BAR; PG8_SCHED;
.LBB0_635:
	ds_read_b128 v[64:67], v230
	ds_read_b128 v[68:71], v230 offset:1024
	ds_read_b128 v[72:75], v230 offset:2048
	ds_read_b128 v[76:79], v230 offset:3072
	ds_read_b128 v[144:147], v231
	ds_read_b128 v[148:151], v231 offset:1024
	ds_read_b128 v[170:173], v231 offset:2048
	ds_read_b128 v[174:177], v231 offset:3072
	s_add_u32 s20, s18, 0x100
	s_addc_u32 s21, s19, 0
	s_cmpk_eq_i32 s53, 0x52
	s_cselect_b32 s25, s5, s21
	s_cselect_b32 s24, s4, s20
	s_cselect_b32 s23, s15, s52
	s_cselect_b32 s22, s14, s17
	v_lshl_add_u64 v[210:211], s[18:19], 0, v[162:163]
	s_add_i32 m0, s35, 0xc000
	ds_read_b128 v[178:181], v232
	ds_read_b128 v[182:185], v232 offset:1024
	ds_read_b128 v[186:189], v232 offset:2048
	ds_read_b128 v[190:193], v232 offset:3072
	ds_read_b128 v[194:197], v232 offset:4096
	ds_read_b128 v[198:201], v232 offset:5120
	ds_read_b128 v[202:205], v232 offset:6144
	ds_read_b128 v[206:209], v232 offset:7168
	global_load_lds_dwordx4 v[210:211], off
	v_lshl_add_u64 v[210:211], s[18:19], 0, v[164:165]
	s_add_i32 m0, s35, 0xe000
	s_nop 0
	global_load_lds_dwordx4 v[210:211], off
	s_waitcnt vmcnt(8)
	s_waitcnt lgkmcnt(0)
	s_barrier
	s_setprio 1
	s_waitcnt lgkmcnt(0)
	v_mfma_f32_16x16x32_bf16 v[140:143], v[64:67], v[178:181], v[140:143]
	v_mfma_f32_16x16x32_bf16 v[136:139], v[72:75], v[178:181], v[136:139]
	v_mfma_f32_16x16x32_bf16 v[128:131], v[64:67], v[186:189], v[128:131]
	v_mfma_f32_16x16x32_bf16 v[120:123], v[72:75], v[186:189], v[120:123]
	v_mfma_f32_16x16x32_bf16 v[116:119], v[64:67], v[194:197], v[116:119]
	v_mfma_f32_16x16x32_bf16 v[112:115], v[72:75], v[194:197], v[112:115]
	v_mfma_f32_16x16x32_bf16 v[100:103], v[64:67], v[202:205], v[100:103]
	v_mfma_f32_16x16x32_bf16 v[96:99], v[72:75], v[202:205], v[96:99]
	v_mfma_f32_16x16x32_bf16 v[140:143], v[68:71], v[182:185], v[140:143]
	v_mfma_f32_16x16x32_bf16 v[136:139], v[76:79], v[182:185], v[136:139]
	v_mfma_f32_16x16x32_bf16 v[128:131], v[68:71], v[190:193], v[128:131]
	v_mfma_f32_16x16x32_bf16 v[120:123], v[76:79], v[190:193], v[120:123]
	v_mfma_f32_16x16x32_bf16 v[116:119], v[68:71], v[198:201], v[116:119]
	v_mfma_f32_16x16x32_bf16 v[112:115], v[76:79], v[198:201], v[112:115]
	v_mfma_f32_16x16x32_bf16 v[100:103], v[68:71], v[206:209], v[100:103]
	v_mfma_f32_16x16x32_bf16 v[96:99], v[76:79], v[206:209], v[96:99]
	s_setprio 0
	s_setprio 1
	v_mfma_f32_16x16x32_bf16 v[132:135], v[144:147], v[178:181], v[132:135]
	v_mfma_f32_16x16x32_bf16 v[124:127], v[170:173], v[178:181], v[124:127]
	v_mfma_f32_16x16x32_bf16 v[108:111], v[144:147], v[186:189], v[108:111]
	v_mfma_f32_16x16x32_bf16 v[104:107], v[170:173], v[186:189], v[104:107]
	v_mfma_f32_16x16x32_bf16 v[92:95], v[144:147], v[194:197], v[92:95]
	v_mfma_f32_16x16x32_bf16 v[88:91], v[170:173], v[194:197], v[88:91]
	v_mfma_f32_16x16x32_bf16 v[84:87], v[144:147], v[202:205], v[84:87]
	v_mfma_f32_16x16x32_bf16 v[80:83], v[170:173], v[202:205], v[80:83]
	v_mfma_f32_16x16x32_bf16 v[132:135], v[148:151], v[182:185], v[132:135]
	v_mfma_f32_16x16x32_bf16 v[124:127], v[174:177], v[182:185], v[124:127]
	v_mfma_f32_16x16x32_bf16 v[108:111], v[148:151], v[190:193], v[108:111]
	v_mfma_f32_16x16x32_bf16 v[104:107], v[174:177], v[190:193], v[104:107]
	v_mfma_f32_16x16x32_bf16 v[92:95], v[148:151], v[198:201], v[92:95]
	v_mfma_f32_16x16x32_bf16 v[88:91], v[174:177], v[198:201], v[88:91]
	v_mfma_f32_16x16x32_bf16 v[84:87], v[148:151], v[206:209], v[84:87]
	v_mfma_f32_16x16x32_bf16 v[80:83], v[174:177], v[206:209], v[80:83]
	s_setprio 0
	s_barrier
	s_add_i32 s18, s45, s30
	v_lshl_add_u64 v[210:211], s[22:23], 0, v[156:157]
	s_mov_b32 m0, s18
	ds_read_b128 v[178:181], v232 offset:16384
	ds_read_b128 v[182:185], v232 offset:17408
	ds_read_b128 v[186:189], v232 offset:18432
	ds_read_b128 v[190:193], v232 offset:19456
	ds_read_b128 v[194:197], v232 offset:20480
	ds_read_b128 v[198:201], v232 offset:21504
	ds_read_b128 v[202:205], v232 offset:22528
	ds_read_b128 v[206:209], v232 offset:23552
	global_load_lds_dwordx4 v[210:211], off
	s_add_i32 m0, s18, 0x2000
	s_add_u32 s18, s22, 0x158000
	v_lshl_add_u64 v[212:213], s[22:23], 0, v[152:153]
	s_addc_u32 s19, s23, 0
	s_add_i32 s54, s46, s30
	global_load_lds_dwordx4 v[212:213], off
	v_lshl_add_u64 v[214:215], s[18:19], 0, v[156:157]
	s_mov_b32 m0, s54
	v_lshl_add_u64 v[216:217], s[24:25], 0, v[154:155]
	global_load_lds_dwordx4 v[214:215], off
	v_lshl_add_u64 v[214:215], s[18:19], 0, v[152:153]
	s_add_i32 m0, s54, 0x2000
	s_nop 0
	global_load_lds_dwordx4 v[214:215], off
	v_lshl_add_u64 v[214:215], s[24:25], 0, v[158:159]
	s_mov_b32 m0, s35
	s_nop 0
	global_load_lds_dwordx4 v[214:215], off
	s_mov_b32 m0, s36
	s_nop 0
	global_load_lds_dwordx4 v[216:217], off
	s_waitcnt vmcnt(8)
	s_waitcnt lgkmcnt(0)
	s_barrier
; #define PG8_STAGE(bufoff, gbase, voff) do { _Pragma("unroll") for (int _i = 0; _i < 2; ++_i) \
;         __builtin_amdgcn_global_load_lds((const unsigned*)((const char*)(gbase) + (voff)[_i]), (PG8_LAS unsigned*)(lds + (bufoff) + ldsw + _i * 8192), 16, 0, 0); } while (0)
; #define PG8_LDA(dst, b, h) do { _Pragma("unroll") for (int m = 0; m < 4; ++m) _Pragma("unroll") for (int k = 0; k < 2; ++k) dst[m][k] = *(const PG8_LAS bf16x8*)(lds + PG8_SA(b, h) + aoff + m * 2048 + k * 1024); } while (0)
; #define PG8_LDB(dst, b, h) do { _Pragma("unroll") for (int n = 0; n < 2; ++n) _Pragma("unroll") for (int k = 0; k < 2; ++k) dst[n][k] = *(const PG8_LAS bf16x8*)(lds + PG8_SB(b, h) + boff + n * 2048 + k * 1024); } while (0)
; #define PG8_MMA(ai, bj, At, Bt) do { __builtin_amdgcn_s_setprio(1); _Pragma("unroll") for (int m = 0; m < 4; ++m) _Pragma("unroll") for (int n = 0; n < 2; ++n) _Pragma("unroll") for (int k = 0; k < 2; ++k) \
;         acc[ai][bj][m][n] = __builtin_amdgcn_mfma_f32_16x16x32_bf16(Bt[n][k], At[m][k], acc[ai][bj][m][n], 0, 0, 0); __builtin_amdgcn_s_setprio(0); } while (0)
; #define PG8_WAIT_V(n) asm volatile("s_waitcnt vmcnt(" #n ")" ::: "memory")
; #define PG8_WAIT_L(n) asm volatile("s_waitcnt lgkmcnt(" #n ")" ::: "memory")
; #define PG8_BAR __builtin_amdgcn_s_barrier()
; #define PG8_SCHED __builtin_amdgcn_sched_barrier(0)
; template <class Epi, class Sched, bool ALIGN_EPI = false, bool SP2 = false>
; __device__ __forceinline__ void gemm_phase(PG8_LAS unsigned char* lds, const Gemm g, const Sched& S, const Epi& E, const int wave_in) {
;     ...
;             PG8_WAIT_V(8); PG8_WAIT_L(0); PG8_BAR; PG8_MMA(1, 0, At, B0); PG8_MMA(1, 1, At, B1); PG8_BAR; PG8_SCHED;
;             PG8_LDB(B0, 1, 0); PG8_LDB(B1, 1, 1); PG8_SCHED; PG8_LDA(At, 1, 0); PG8_STAGE(PG8_SA(0, 1), a2 + hstepA, voffA);
;             PG8_WAIT_V(8); PG8_WAIT_L(0); PG8_BAR; PG8_MMA(0, 0, At, B0); PG8_MMA(0, 1, At, B1); PG8_BAR; PG8_SCHED;
	s_setprio 1
	s_waitcnt lgkmcnt(0)
	v_mfma_f32_16x16x32_bf16 v[60:63], v[64:67], v[178:181], v[60:63]
	v_mfma_f32_16x16x32_bf16 v[56:59], v[72:75], v[178:181], v[56:59]
	v_mfma_f32_16x16x32_bf16 v[48:51], v[64:67], v[186:189], v[48:51]
	v_mfma_f32_16x16x32_bf16 v[40:43], v[72:75], v[186:189], v[40:43]
	v_mfma_f32_16x16x32_bf16 v[32:35], v[64:67], v[194:197], v[32:35]
	v_mfma_f32_16x16x32_bf16 v[24:27], v[72:75], v[194:197], v[24:27]
	v_mfma_f32_16x16x32_bf16 v[16:19], v[64:67], v[202:205], v[16:19]
	v_mfma_f32_16x16x32_bf16 v[8:11], v[72:75], v[202:205], v[8:11]
	v_mfma_f32_16x16x32_bf16 v[60:63], v[68:71], v[182:185], v[60:63]
	v_mfma_f32_16x16x32_bf16 v[56:59], v[76:79], v[182:185], v[56:59]
	v_mfma_f32_16x16x32_bf16 v[48:51], v[68:71], v[190:193], v[48:51]
	v_mfma_f32_16x16x32_bf16 v[40:43], v[76:79], v[190:193], v[40:43]
	v_mfma_f32_16x16x32_bf16 v[32:35], v[68:71], v[198:201], v[32:35]
	v_mfma_f32_16x16x32_bf16 v[24:27], v[76:79], v[198:201], v[24:27]
	v_mfma_f32_16x16x32_bf16 v[16:19], v[68:71], v[206:209], v[16:19]
	v_mfma_f32_16x16x32_bf16 v[8:11], v[76:79], v[206:209], v[8:11]
	s_setprio 0
	s_setprio 1
	v_mfma_f32_16x16x32_bf16 v[52:55], v[144:147], v[178:181], v[52:55]
	v_mfma_f32_16x16x32_bf16 v[44:47], v[170:173], v[178:181], v[44:47]
	v_mfma_f32_16x16x32_bf16 v[36:39], v[144:147], v[186:189], v[36:39]
	v_mfma_f32_16x16x32_bf16 v[28:31], v[170:173], v[186:189], v[28:31]
	v_mfma_f32_16x16x32_bf16 v[20:23], v[144:147], v[194:197], v[20:23]
	v_mfma_f32_16x16x32_bf16 v[12:15], v[170:173], v[194:197], v[12:15]
	v_mfma_f32_16x16x32_bf16 v[4:7], v[144:147], v[202:205], v[4:7]
	v_mfma_f32_16x16x32_bf16 v[0:3], v[170:173], v[202:205], v[0:3]
	v_mfma_f32_16x16x32_bf16 v[52:55], v[148:151], v[182:185], v[52:55]
	v_mfma_f32_16x16x32_bf16 v[44:47], v[174:177], v[182:185], v[44:47]
	v_mfma_f32_16x16x32_bf16 v[36:39], v[148:151], v[190:193], v[36:39]
	v_mfma_f32_16x16x32_bf16 v[28:31], v[174:177], v[190:193], v[28:31]
	v_mfma_f32_16x16x32_bf16 v[20:23], v[148:151], v[198:201], v[20:23]
	v_mfma_f32_16x16x32_bf16 v[12:15], v[174:177], v[198:201], v[12:15]
	v_mfma_f32_16x16x32_bf16 v[4:7], v[148:151], v[206:209], v[4:7]
	v_mfma_f32_16x16x32_bf16 v[0:3], v[174:177], v[206:209], v[0:3]
	s_setprio 0
	s_barrier
	s_add_i32 s54, 0, 0x18000
	s_add_i32 s55, 0, 0x1c000
	v_add_u32_e32 v76, s54, v228
	v_add_u32_e32 v174, s55, v228
	ds_read_b128 v[64:67], v76
	ds_read_b128 v[68:71], v76 offset:1024
	ds_read_b128 v[72:75], v76 offset:2048
	ds_read_b128 v[76:79], v76 offset:3072
	ds_read_b128 v[144:147], v174
	ds_read_b128 v[148:151], v174 offset:1024
	ds_read_b128 v[170:173], v174 offset:2048
	ds_read_b128 v[174:177], v174 offset:3072
	s_add_u32 s18, s24, 0x158000
	s_addc_u32 s19, s25, 0
	s_mov_b32 m0, s37
	v_lshl_add_u64 v[218:219], s[18:19], 0, v[158:159]
	ds_read_b128 v[178:181], v232 offset:32768
	ds_read_b128 v[182:185], v232 offset:33792
	ds_read_b128 v[186:189], v232 offset:34816
	ds_read_b128 v[190:193], v232 offset:35840
	ds_read_b128 v[194:197], v232 offset:36864
	ds_read_b128 v[198:201], v232 offset:37888
	ds_read_b128 v[202:205], v232 offset:38912
	ds_read_b128 v[206:209], v232 offset:39936
	global_load_lds_dwordx4 v[218:219], off
	v_lshl_add_u64 v[218:219], s[18:19], 0, v[154:155]
	s_mov_b32 m0, s38
	s_nop 0
	global_load_lds_dwordx4 v[218:219], off
	s_waitcnt vmcnt(8)
	s_waitcnt lgkmcnt(0)
	s_barrier
	s_setprio 1
	s_waitcnt lgkmcnt(0)
	v_mfma_f32_16x16x32_bf16 v[140:143], v[64:67], v[178:181], v[140:143]
	v_mfma_f32_16x16x32_bf16 v[136:139], v[72:75], v[178:181], v[136:139]
	v_mfma_f32_16x16x32_bf16 v[128:131], v[64:67], v[186:189], v[128:131]
	v_mfma_f32_16x16x32_bf16 v[120:123], v[72:75], v[186:189], v[120:123]
	v_mfma_f32_16x16x32_bf16 v[116:119], v[64:67], v[194:197], v[116:119]
	v_mfma_f32_16x16x32_bf16 v[112:115], v[72:75], v[194:197], v[112:115]
	v_mfma_f32_16x16x32_bf16 v[100:103], v[64:67], v[202:205], v[100:103]
	v_mfma_f32_16x16x32_bf16 v[96:99], v[72:75], v[202:205], v[96:99]
	v_mfma_f32_16x16x32_bf16 v[140:143], v[68:71], v[182:185], v[140:143]
	v_mfma_f32_16x16x32_bf16 v[136:139], v[76:79], v[182:185], v[136:139]
	v_mfma_f32_16x16x32_bf16 v[128:131], v[68:71], v[190:193], v[128:131]
	v_mfma_f32_16x16x32_bf16 v[120:123], v[76:79], v[190:193], v[120:123]
	v_mfma_f32_16x16x32_bf16 v[116:119], v[68:71], v[198:201], v[116:119]
	v_mfma_f32_16x16x32_bf16 v[112:115], v[76:79], v[198:201], v[112:115]
	v_mfma_f32_16x16x32_bf16 v[100:103], v[68:71], v[206:209], v[100:103]
	v_mfma_f32_16x16x32_bf16 v[96:99], v[76:79], v[206:209], v[96:99]
	s_setprio 0
	s_setprio 1
	v_mfma_f32_16x16x32_bf16 v[132:135], v[144:147], v[178:181], v[132:135]
	v_mfma_f32_16x16x32_bf16 v[124:127], v[170:173], v[178:181], v[124:127]
	v_mfma_f32_16x16x32_bf16 v[108:111], v[144:147], v[186:189], v[108:111]
	v_mfma_f32_16x16x32_bf16 v[104:107], v[170:173], v[186:189], v[104:107]
	v_mfma_f32_16x16x32_bf16 v[92:95], v[144:147], v[194:197], v[92:95]
	v_mfma_f32_16x16x32_bf16 v[88:91], v[170:173], v[194:197], v[88:91]
	v_mfma_f32_16x16x32_bf16 v[84:87], v[144:147], v[202:205], v[84:87]
	v_mfma_f32_16x16x32_bf16 v[80:83], v[170:173], v[202:205], v[80:83]
	v_mfma_f32_16x16x32_bf16 v[132:135], v[148:151], v[182:185], v[132:135]
	v_mfma_f32_16x16x32_bf16 v[124:127], v[174:177], v[182:185], v[124:127]
	v_mfma_f32_16x16x32_bf16 v[108:111], v[148:151], v[190:193], v[108:111]
	v_mfma_f32_16x16x32_bf16 v[104:107], v[174:177], v[190:193], v[104:107]
	v_mfma_f32_16x16x32_bf16 v[92:95], v[148:151], v[198:201], v[92:95]
	v_mfma_f32_16x16x32_bf16 v[88:91], v[174:177], v[198:201], v[88:91]
	v_mfma_f32_16x16x32_bf16 v[84:87], v[148:151], v[206:209], v[84:87]
	v_mfma_f32_16x16x32_bf16 v[80:83], v[174:177], v[206:209], v[80:83]
	s_setprio 0
	s_barrier
; #define PG8_STAGE(bufoff, gbase, voff) do { _Pragma("unroll") for (int _i = 0; _i < 2; ++_i) \
;         __builtin_amdgcn_global_load_lds((const unsigned*)((const char*)(gbase) + (voff)[_i]), (PG8_LAS unsigned*)(lds + (bufoff) + ldsw + _i * 8192), 16, 0, 0); } while (0)
; #define PG8_LDA(dst, b, h) do { _Pragma("unroll") for (int m = 0; m < 4; ++m) _Pragma("unroll") for (int k = 0; k < 2; ++k) dst[m][k] = *(const PG8_LAS bf16x8*)(lds + PG8_SA(b, h) + aoff + m * 2048 + k * 1024); } while (0)
; #define PG8_MMA(ai, bj, At, Bt) do { __builtin_amdgcn_s_setprio(1); _Pragma("unroll") for (int m = 0; m < 4; ++m) _Pragma("unroll") for (int n = 0; n < 2; ++n) _Pragma("unroll") for (int k = 0; k < 2; ++k) \
;         acc[ai][bj][m][n] = __builtin_amdgcn_mfma_f32_16x16x32_bf16(Bt[n][k], At[m][k], acc[ai][bj][m][n], 0, 0, 0); __builtin_amdgcn_s_setprio(0); } while (0)
; #define PG8_WAIT_V(n) asm volatile("s_waitcnt vmcnt(" #n ")" ::: "memory")
; #define PG8_WAIT_L(n) asm volatile("s_waitcnt lgkmcnt(" #n ")" ::: "memory")
; #define PG8_BAR __builtin_amdgcn_s_barrier()
; #define PG8_SCHED __builtin_amdgcn_sched_barrier(0)
; template <class Epi, class Sched, bool ALIGN_EPI = false, bool SP2 = false>
; __device__ __forceinline__ void gemm_phase(PG8_LAS unsigned char* lds, const Gemm g, const Sched& S, const Epi& E, const int wave_in) {
;     ...
;             PG8_LDA(At, 1, 1); PG8_STAGE(PG8_SB(1, 0), b3, voffB); PG8_STAGE(PG8_SB(1, 1), b3 + hstepB, voffB); PG8_STAGE(PG8_SA(1, 0), a3, voffA);
;             PG8_WAIT_V(8); PG8_WAIT_L(0); PG8_BAR; PG8_MMA(1, 0, At, B0); PG8_MMA(1, 1, At, B1); PG8_BAR; PG8_SCHED;
;     ...
;         if (!has_next) break;
	s_add_i32 s18, s54, s30
	v_lshl_add_u64 v[210:211], v[210:211], 0, s[6:7]
	s_mov_b32 m0, s18
	ds_read_b128 v[178:181], v232 offset:49152
	ds_read_b128 v[182:185], v232 offset:50176
	ds_read_b128 v[186:189], v232 offset:51200
	ds_read_b128 v[190:193], v232 offset:52224
	ds_read_b128 v[194:197], v232 offset:53248
	ds_read_b128 v[198:201], v232 offset:54272
	ds_read_b128 v[202:205], v232 offset:55296
	ds_read_b128 v[206:209], v232 offset:56320
	global_load_lds_dwordx4 v[210:211], off
	s_add_i32 m0, s18, 0x2000
	s_add_u32 s18, s22, 0x158080
	v_lshl_add_u64 v[210:211], v[212:213], 0, s[6:7]
	s_addc_u32 s19, s23, 0
	s_add_i32 s22, s55, s30
	global_load_lds_dwordx4 v[210:211], off
	v_lshl_add_u64 v[210:211], s[18:19], 0, v[156:157]
	s_mov_b32 m0, s22
	s_nop 0
	global_load_lds_dwordx4 v[210:211], off
	v_lshl_add_u64 v[210:211], s[18:19], 0, v[152:153]
	s_add_i32 m0, s22, 0x2000
	s_nop 0
	global_load_lds_dwordx4 v[210:211], off
	v_lshl_add_u64 v[210:211], v[214:215], 0, s[6:7]
	s_mov_b32 m0, s42
	s_nop 0
	global_load_lds_dwordx4 v[210:211], off
	v_lshl_add_u64 v[210:211], v[216:217], 0, s[6:7]
	s_mov_b32 m0, s43
	s_nop 0
	global_load_lds_dwordx4 v[210:211], off
	s_waitcnt vmcnt(8)
	s_waitcnt lgkmcnt(0)
	s_barrier
	s_setprio 1
	s_waitcnt lgkmcnt(0)
	v_mfma_f32_16x16x32_bf16 v[60:63], v[64:67], v[178:181], v[60:63]
	v_mfma_f32_16x16x32_bf16 v[56:59], v[72:75], v[178:181], v[56:59]
	v_mfma_f32_16x16x32_bf16 v[48:51], v[64:67], v[186:189], v[48:51]
	v_mfma_f32_16x16x32_bf16 v[40:43], v[72:75], v[186:189], v[40:43]
	v_mfma_f32_16x16x32_bf16 v[32:35], v[64:67], v[194:197], v[32:35]
	v_mfma_f32_16x16x32_bf16 v[24:27], v[72:75], v[194:197], v[24:27]
	v_mfma_f32_16x16x32_bf16 v[16:19], v[64:67], v[202:205], v[16:19]
	v_mfma_f32_16x16x32_bf16 v[8:11], v[72:75], v[202:205], v[8:11]
	v_mfma_f32_16x16x32_bf16 v[60:63], v[68:71], v[182:185], v[60:63]
	v_mfma_f32_16x16x32_bf16 v[56:59], v[76:79], v[182:185], v[56:59]
	v_mfma_f32_16x16x32_bf16 v[48:51], v[68:71], v[190:193], v[48:51]
	v_mfma_f32_16x16x32_bf16 v[40:43], v[76:79], v[190:193], v[40:43]
	v_mfma_f32_16x16x32_bf16 v[32:35], v[68:71], v[198:201], v[32:35]
	v_mfma_f32_16x16x32_bf16 v[24:27], v[76:79], v[198:201], v[24:27]
	v_mfma_f32_16x16x32_bf16 v[16:19], v[68:71], v[206:209], v[16:19]
	v_mfma_f32_16x16x32_bf16 v[8:11], v[76:79], v[206:209], v[8:11]
	s_setprio 0
	s_setprio 1
	v_mfma_f32_16x16x32_bf16 v[52:55], v[144:147], v[178:181], v[52:55]
	v_mfma_f32_16x16x32_bf16 v[44:47], v[170:173], v[178:181], v[44:47]
	v_mfma_f32_16x16x32_bf16 v[36:39], v[144:147], v[186:189], v[36:39]
	v_mfma_f32_16x16x32_bf16 v[28:31], v[170:173], v[186:189], v[28:31]
	v_mfma_f32_16x16x32_bf16 v[20:23], v[144:147], v[194:197], v[20:23]
	v_mfma_f32_16x16x32_bf16 v[12:15], v[170:173], v[194:197], v[12:15]
	v_mfma_f32_16x16x32_bf16 v[4:7], v[144:147], v[202:205], v[4:7]
	v_mfma_f32_16x16x32_bf16 v[0:3], v[170:173], v[202:205], v[0:3]
	v_mfma_f32_16x16x32_bf16 v[52:55], v[148:151], v[182:185], v[52:55]
	v_mfma_f32_16x16x32_bf16 v[44:47], v[174:177], v[182:185], v[44:47]
	v_mfma_f32_16x16x32_bf16 v[36:39], v[148:151], v[190:193], v[36:39]
	v_mfma_f32_16x16x32_bf16 v[28:31], v[174:177], v[190:193], v[28:31]
	v_mfma_f32_16x16x32_bf16 v[20:23], v[148:151], v[198:201], v[20:23]
	v_mfma_f32_16x16x32_bf16 v[12:15], v[174:177], v[198:201], v[12:15]
	v_mfma_f32_16x16x32_bf16 v[4:7], v[148:151], v[206:209], v[4:7]
	v_mfma_f32_16x16x32_bf16 v[0:3], v[174:177], v[206:209], v[0:3]
	s_setprio 0
	s_barrier
	s_add_i32 s53, s53, 2
	s_add_u32 s17, s17, 0x100
	s_addc_u32 s52, s52, 0
	s_cmpk_gt_u32 s53, 0x53
	s_mov_b64 s[18:19], s[20:21]
	s_cbranch_scc0 .LBB0_635
	s_mov_b32 s99, 1
	s_and_b64 vcc, exec, s[8:9]
	s_cbranch_vccz .LBB0_638
	s_barrier

;     __host__ __device__ bool next(int i, Unit& u) const { const bool ok = StaticOrder::next(i, u); u.pm = 0; u.pn = 0; return ok; }
;     __host__ __device__ bool next(int i, Unit& u) const {
;         const long L = (long)i * G + c; if (L >= nwg) return false;
;         int wgid = (int)L; { const int q = nwg / NXCD, r = nwg % NXCD, xcd = wgid % NXCD, off = wgid / NXCD; wgid = (xcd < r ? xcd * (q + 1) : r * (q + 1) + (xcd - r) * q) + off; }
;         const int nig = WGM * nN, gid = wgid / nig, fm = gid * WGM, gsz = (nM - fm) < WGM ? (nM - fm) : WGM;
;         u.pm = fm + ((wgid % nig) % gsz); u.pn = (wgid % nig) / gsz; return true;
;     }
; template <int L> __device__ __forceinline__ void layer_body(Frame& F, const Args& args, unsigned char* const wsg, const int lo, const int hi, const XcdBarrier& bar) {
;     ...
;         if (IN(base + 1)) {
;             pg8::Gemm g{(const pg8::bf16_t*)(wsg + WS_H), (const pg8::bf16_t*)(wsg + WS_WT_IN), M_ALL, NinP, DM, DM};
;             pg8::StaticOrder S; S.init(M_ALL, NinP, F.G, (int)blockIdx.x);
;             pg8::EpiStore E{(pg8::bf16_t*)(wsg + WS_P), NinP, (m == 0) ? 0 : 0, (m == 0) ? 8 : 0, (m == 2) ? 0 : 32, (m == 0) ? 40 : (m == 1) ? 48 : 0};
;             pg8::gemm_phase<pg8::EpiStore, pg8::StaticOrder, true, true>(F.lds, g, S, E, F.wave);
.LBB0_766:
	s_cmp_gt_i32 s52, 10
	s_cselect_b64 s[0:1], -1, 0
	s_cmp_lt_i32 s53, 11
	s_cselect_b64 s[2:3], -1, 0
	s_or_b64 s[0:1], s[0:1], s[2:3]
	s_and_b64 vcc, exec, s[0:1]
	s_cbranch_vccnz .LBB0_867
	s_mov_b32 s99, 0
	s_cmpk_lt_i32 s73, 0x1b90
	s_cselect_b64 s[0:1], -1, 0
	s_cmpk_gt_i32 s73, 0x1b8f
	v_mbcnt_lo_u32_b32 v8, -1, 0
	v_mbcnt_hi_u32_b32 v8, -1, v8
	s_cbranch_scc1 .LBB0_770
	s_ashr_i32 s2, s73, 31
	s_lshr_b32 s2, s2, 29
	s_add_i32 s2, s73, s2
	s_ashr_i32 s3, s2, 3
	s_and_b32 s2, s2, -8
	s_sub_i32 s2, s73, s2
	s_cmp_lt_i32 s2, 0
	s_movk_i32 s4, 0x373
	s_cselect_b32 s4, s4, 0x372
	s_mul_i32 s2, s4, s2
	s_add_i32 s2, s2, s3
	s_mul_hi_i32 s3, s2, 0x5397829d
	s_lshr_b32 s4, s3, 31
	s_ashr_i32 s3, s3, 6
	s_add_i32 s3, s3, s4
	s_lshl_b32 s4, s3, 2
	s_mulk_i32 s3, 0xc4
	s_sub_i32 s2, s2, s3
	s_sext_i32_i16 s3, s2
	s_bfe_u32 s3, s3, 0x2001d
	s_add_i32 s3, s2, s3
	s_sext_i32_i16 s5, s3
	s_and_b32 s3, s3, 0xfffc
	s_sub_i32 s2, s2, s3
	s_sext_i32_i16 s2, s2
	s_add_i32 s20, s4, s2
	s_ashr_i32 s4, s5, 2
	s_andn2_b64 vcc, exec, s[0:1]
	s_cbranch_vccz .LBB0_771

; template <class Epi, class Sched, bool ALIGN_EPI = false, bool SP2 = false>
; __device__ __forceinline__ void gemm_phase(PG8_LAS unsigned char* lds, const Gemm g, const Sched& S, const Epi& E, const int wave_in) {
;     const int lane = lane_id_asm(), wid = __builtin_amdgcn_readfirstlane(wave_in), tid = wid * 64 + lane, wr = wid >> 2, wc = wid & 3, fr = lane & 15, fq = lane >> 4;
;     const int K = g.K, nt = K / BK;
;     unsigned voffA[2], voffB[2];
; #pragma unroll
;     for (int i = 0; i < 2; ++i) { int R, C; stage_rc(tid * 16 + i * 8192, R, C); const int Rb = Epi::PERM ? ((R & ~31) + perm32(R & 31)) : R;
;         voffA[i] = (unsigned)(R * g.lda + C) * 2u; voffB[i] = (unsigned)(Rb * K + C) * 2u; }
;     const size_t kstep = (size_t)(BK * 2);
;     const size_t hstepA = (size_t)HALF * g.lda * 2, hstepB = (size_t)HALF * K * 2;
;     const size_t tstepA = 2 * hstepA, tstepB = 2 * hstepB;
;     const unsigned ldsw = (unsigned)wid * 1024u;
;     const int aoff = lds_byte(wr * 64 + fr, fq * 8), boff = lds_byte(wc * 32 + fr, fq * 8);
;     ...
;     Unit cur, nxt; int ui = 0;
;     if (!S.next(0, cur)) return;
;     f32x4 acc[2][2][4][2];
; #pragma unroll
;     for (int a = 0; a < 2; ++a)
; #pragma unroll
;         for (int b = 0; b < 2; ++b)
; #pragma unroll
;             for (int m = 0; m < 4; ++m)
; #pragma unroll
;                 for (int n = 0; n < 2; ++n) acc[a][b][m][n] = (f32x4){0.f, 0.f, 0.f, 0.f};
; template <int L> __device__ __forceinline__ void layer_body(Frame& F, const Args& args, unsigned char* const wsg, const int lo, const int hi, const XcdBarrier& bar) {
;     ...
;         if (IN(base + 3)) {
;             const pg8::bf16_t* A = (m == 2) ? (const pg8::bf16_t*)(wsg + WS_O) : (const pg8::bf16_t*)(wsg + WS_P) + 4 * DM;
;             const int lda = (m == 0) ? HG_N : (m == 1) ? GDN_NP : DM, Kout = (m == 1) ? 2 * DM : DM;
;             const int Mr = M_ALL - row_lo2;
;             pg8::Gemm g{A + (size_t)row_lo2 * lda, (const pg8::bf16_t*)(wsg + WS_WT_OUT), Mr, DM, Kout, lda};
;             pg8::StaticOrder S; S.init(Mr, DM, F.G, (int)blockIdx.x);
;             typedef pg8::EpiResidT<(L != 0), true> EpiO;
;             EpiO E{(const float*)args.in[I_X], (const float*)args.in[I_CTX], X16A, X16mid, nullptr, (const float*)modL + 2 * DM, pm02, 0};
;             pg8::gemm_phase<EpiO, pg8::StaticOrder, true, true>(F.lds, g, S, E, F.wave);
.LBB0_1081:
	s_cmp_gt_i32 s52, 12
	s_cselect_b64 s[0:1], -1, 0
	s_cmp_lt_i32 s53, 13
	s_cselect_b64 s[2:3], -1, 0
	s_or_b64 s[0:1], s[0:1], s[2:3]
	s_and_b64 vcc, exec, s[0:1]
	s_cbranch_vccnz .LBB0_1150
	s_mov_b32 s99, 0
	s_cmpk_gt_i32 s73, 0x47f
	v_mbcnt_lo_u32_b32 v11, -1, 0
	v_mbcnt_hi_u32_b32 v11, -1, v11
	s_cbranch_scc1 .LBB0_1100
	s_waitcnt lgkmcnt(0)
	s_add_u32 s28, s70, 0xa704000
	s_addc_u32 s29, s71, 0
	s_add_u32 s30, s70, 0x5600000
	s_addc_u32 s31, s71, 0
	s_lshl_b32 s34, s33, 10
	v_lshl_add_u32 v0, v11, 4, s34
	v_add_u32_e32 v1, 0x2000, v0
	v_ashrrev_i32_e32 v2, 31, v1
	v_lshrrev_b32_e32 v2, 22, v2
	v_add_u32_e32 v2, v1, v2
	v_ashrrev_i32_e32 v8, 10, v2
	v_mul_i32_i24_e32 v2, 0x400, v8
	v_sub_u32_e32 v1, v1, v2
	v_lshrrev_b32_e32 v2, 4, v1
	v_bitop3_b32 v1, v2, v1, 32 bitop3:0x6c
	v_ashrrev_i32_e32 v2, 31, v1
	v_lshrrev_b32_e32 v2, 26, v2
	v_add_u32_e32 v2, v1, v2
	v_ashrrev_i32_e32 v9, 6, v2
	v_lshlrev_b32_e32 v3, 3, v8
	v_and_b32_e32 v2, 0xffc0, v2
	v_and_b32_e32 v3, -16, v3
	v_sub_u32_e32 v1, v1, v2
	v_add_u32_e32 v3, v9, v3
	v_lshrrev_b16_e32 v2, 7, v1
	v_and_b32_e32 v4, 3, v9
	s_mov_b32 s0, 0x7ffe0
	v_lshrrev_b32_e32 v5, 2, v3
	v_lshlrev_b32_e32 v6, 1, v3
	v_and_b32_e32 v2, 1, v2
	v_and_or_b32 v4, v3, s0, v4
	v_and_b32_e32 v5, 4, v5
	v_and_b32_e32 v6, 24, v6
	v_add_u16_e32 v1, v1, v2
	v_mov_b32_e32 v2, 1
	v_or3_b32 v4, v4, v5, v6
	v_lshlrev_b32_e32 v5, 5, v8
	v_ashrrev_i16_sdwa v1, v2, sext(v1) dst_sel:DWORD dst_unused:UNUSED_PAD src0_sel:DWORD src1_sel:BYTE_0
	v_and_b32_e32 v10, 32, v5
	v_bfe_i32 v12, v1, 0, 16
	s_movk_i32 s4, 0x3100
	v_add_u32_e32 v1, v10, v12
	v_mul_lo_u32 v3, v3, s4
	v_lshlrev_b32_e32 v5, 1, v1
	v_add_lshl_u32 v146, v1, v3, 1
	v_ashrrev_i32_e32 v1, 31, v0
	v_lshrrev_b32_e32 v1, 22, v1
	v_add_u32_e32 v1, v0, v1
	v_ashrrev_i32_e32 v13, 10, v1
	v_mul_i32_i24_e32 v1, 0x400, v13
	v_sub_u32_e32 v0, v0, v1
	v_lshrrev_b32_e32 v1, 4, v0
	v_bitop3_b32 v0, v1, v0, 32 bitop3:0x6c
	v_ashrrev_i32_e32 v1, 31, v0
	v_lshrrev_b32_e32 v1, 26, v1
	v_add_u32_e32 v1, v0, v1
	v_lshlrev_b32_e32 v3, 3, v13
	v_ashrrev_i32_e32 v14, 6, v1
	v_and_b32_e32 v3, -16, v3
	v_lshl_add_u32 v144, v4, 13, v5
	v_add_u32_e32 v3, v14, v3
	v_and_b32_e32 v4, 3, v14
	s_ashr_i32 s35, s73, 31
	v_and_or_b32 v4, v3, s0, v4
	s_lshr_b32 s0, s35, 29
	s_add_i32 s0, s73, s0
	s_ashr_i32 s1, s0, 3
	s_and_b32 s0, s0, -8
	s_ashr_i32 s3, s33, 2
	s_sub_i32 s0, s73, s0
	s_cmp_lt_i32 s0, 0
	s_movk_i32 s36, 0x91
	s_cselect_b32 s2, s36, 0x90
	s_mul_i32 s0, s2, s0
	s_add_i32 s0, s0, s1
	s_ashr_i32 s1, s0, 31
	s_lshr_b32 s1, s1, 27
	s_add_i32 s1, s0, s1
	s_ashr_i32 s2, s1, 5
	s_andn2_b32 s1, s1, 31
	s_sub_i32 s0, s0, s1
	s_bfe_i32 s1, s0, 0x80000
	s_bfe_u32 s1, s1, 0x2000d
	s_add_i32 s1, s0, s1
	s_lshl_b32 s5, s2, 2
	s_bfe_i32 s2, s1, 0x80000
	s_and_b32 s1, s1, 0xfc
	v_lshrrev_b32_e32 v5, 2, v3
	v_lshlrev_b32_e32 v6, 1, v3
	v_and_b32_e32 v1, 0xc0, v1
	s_sext_i32_i16 s2, s2
	s_sub_i32 s0, s0, s1
	v_and_b32_e32 v5, 4, v5
	v_and_b32_e32 v6, 24, v6
	v_sub_u32_e32 v0, v0, v1
	s_lshr_b32 s2, s2, 2
	s_sext_i32_i8 s0, s0
	v_or3_b32 v4, v4, v5, v6
	v_lshlrev_b32_e32 v5, 5, v13
	v_ashrrev_i16_sdwa v0, v2, sext(v0) dst_sel:DWORD dst_unused:UNUSED_PAD src0_sel:DWORD src1_sel:BYTE_0
	s_add_i32 s20, s5, s0
	s_bfe_i64 s[0:1], s[2:3], 0x100000
	v_and_b32_e32 v15, 32, v5
	v_bfe_i32 v16, v0, 0, 16
	s_lshl_b64 s[0:1], s[0:1], 21
	v_add_u32_e32 v0, v15, v16
	s_add_u32 s24, s30, s0
	v_lshlrev_b32_e32 v1, 1, v0
	s_addc_u32 s25, s31, s1
	s_add_i32 s37, s34, 0
	v_lshl_add_u32 v148, v4, 13, v1
	s_add_i32 m0, s37, 0x10000
	s_mul_i32 s6, s20, 0x620000
	global_load_lds_dwordx4 v148, s[24:25]
	s_add_i32 m0, s37, 0x12000
	s_add_u32 s0, s24, 0x100000
	global_load_lds_dwordx4 v144, s[24:25]
	s_addc_u32 s1, s25, 0
	s_add_i32 m0, s37, 0x14000
	s_mul_hi_i32 s5, s20, 0x620000
	global_load_lds_dwordx4 v148, s[0:1]
	s_add_i32 m0, s37, 0x16000
	s_add_u32 s22, s28, s6
	v_mul_lo_u32 v1, v3, s4
	s_addc_u32 s23, s29, s5
	s_add_i32 s38, s37, 0x2000
	v_add_lshl_u32 v150, v0, v1, 1
	global_load_lds_dwordx4 v144, s[0:1]
	s_mov_b32 m0, s37
	s_add_u32 s0, s22, 0x310000
	global_load_lds_dwordx4 v150, s[22:23]
	s_mov_b32 m0, s38
	s_addc_u32 s1, s23, 0
	s_add_i32 s39, s37, 0x4000
	global_load_lds_dwordx4 v146, s[22:23]
	s_mov_b32 m0, s39
	s_add_i32 s40, s37, 0x6000
	global_load_lds_dwordx4 v150, s[0:1]
	s_mov_b32 m0, s40
	v_mov_b32_e32 v149, 0
	global_load_lds_dwordx4 v146, s[0:1]
	v_mov_b32_e32 v145, v149
	v_mov_b32_e32 v151, v149
	v_mov_b32_e32 v147, v149
	s_cmp_eq_u32 s3, 1
	s_mov_b32 s41, 0
	v_lshl_add_u64 v[6:7], s[24:25], 0, v[148:149]
	v_lshl_add_u64 v[4:5], s[24:25], 0, v[144:145]
	v_lshl_add_u64 v[0:1], s[22:23], 0, v[150:151]
	s_cselect_b64 s[0:1], -1, 0
	s_cmp_lg_u32 s3, 1
	v_lshl_add_u64 v[2:3], s[22:23], 0, v[146:147]
	s_cbranch_scc1 .LBB0_1085
	s_barrier

;     __host__ __device__ bool next(int i, Unit& u) const { const bool ok = StaticOrder::next(i, u); u.pm = 0; u.pn = 0; return ok; }
; #define PG8_STAGE(bufoff, gbase, voff) do { _Pragma("unroll") for (int _i = 0; _i < 2; ++_i) \
;         __builtin_amdgcn_global_load_lds((const unsigned*)((const char*)(gbase) + (voff)[_i]), (PG8_LAS unsigned*)(lds + (bufoff) + ldsw + _i * 8192), 16, 0, 0); } while (0)
; #define PG8_LDA(dst, b, h) do { _Pragma("unroll") for (int m = 0; m < 4; ++m) _Pragma("unroll") for (int k = 0; k < 2; ++k) dst[m][k] = *(const PG8_LAS bf16x8*)(lds + PG8_SA(b, h) + aoff + m * 2048 + k * 1024); } while (0)
; template <class Epi, class Sched, bool ALIGN_EPI = false, bool SP2 = false>
; __device__ __forceinline__ void gemm_phase(PG8_LAS unsigned char* lds, const Gemm g, const Sched& S, const Epi& E, const int wave_in) {
;     ...
;     for (;;) {
;         const bool has_next = S.next(ui + 1, nxt);
;         const char* nA = has_next ? (const char*)g.A + (size_t)nxt.pm * tstepA : cA; const char* nB = has_next ? (const char*)g.Bt + (size_t)nxt.pn * tstepB : cB;
;         for (int t = 0; t < nt; t += 2) {
;             const bool last = (t == nt - 2);
;             const char* a1 = cA + (size_t)(t + 1) * kstep;
;             const char* a2 = last ? nA : cA + (size_t)(t + 2) * kstep; const char* b2 = last ? nB : cB + (size_t)(t + 2) * kstep;
;             const char* a3 = a2 + kstep; const char* b3 = b2 + kstep;
;             if (last && has_next) S.a_ready(nxt);
;             if constexpr (SP2) {
;             PG8_LDB(B0, 0, 0); PG8_LDB(B1, 0, 1); PG8_SCHED; PG8_LDA(At, 0, 0); PG8_STAGE(PG8_SA(1, 1), a1 + hstepA, voffA);
;             PG8_WAIT_V(8); PG8_WAIT_L(0); PG8_BAR; PG8_MMA(0, 0, At, B0); PG8_MMA(0, 1, At, B1); PG8_BAR; PG8_SCHED;
;             PG8_LDA(At, 0, 1); PG8_STAGE(PG8_SB(0, 0), b2, voffB); PG8_STAGE(PG8_SB(0, 1), b2 + hstepB, voffB); PG8_STAGE(PG8_SA(0, 0), a2, voffA);
;             PG8_WAIT_V(8); PG8_WAIT_L(0); PG8_BAR; PG8_MMA(1, 0, At, B0); PG8_MMA(1, 1, At, B1); PG8_BAR; PG8_SCHED;
;     ...
; #pragma unroll
;         for (int a = 0; a < 2; ++a)
; #pragma unroll
;             for (int b = 0; b < 2; ++b)
; #pragma unroll
;                 for (int m = 0; m < 4; ++m)
; #pragma unroll
;                     for (int n = 0; n < 2; ++n) acc[a][b][m][n] = (f32x4){0.f, 0.f, 0.f, 0.f};
;         cur = nxt; cA = nA; cB = nB; ++ui;
.LBB0_1092:
	s_ashr_i32 s15, s14, 31
	s_lshl_b64 s[18:19], s[14:15], 21
	s_add_u32 s18, s30, s18
	s_addc_u32 s19, s31, s19
	s_and_b64 s[4:5], s[4:5], exec
	s_cselect_b32 s15, s19, s25
	s_cselect_b32 s21, s18, s24
	s_add_u32 s53, s24, 0x100
	v_mov_b32_e32 v0, 0
	s_addc_u32 s54, s25, 0
	s_mov_b32 s55, -2
	v_mov_b32_e32 v1, v0
	v_mov_b32_e32 v2, v0
	v_mov_b32_e32 v3, v0
	v_mov_b32_e32 v4, v0
	v_mov_b32_e32 v5, v0
	v_mov_b32_e32 v6, v0
	v_mov_b32_e32 v7, v0
	v_mov_b32_e32 v12, v0
	v_mov_b32_e32 v13, v0
	v_mov_b32_e32 v14, v0
	v_mov_b32_e32 v15, v0
	v_mov_b32_e32 v20, v0
	v_mov_b32_e32 v21, v0
	v_mov_b32_e32 v22, v0
	v_mov_b32_e32 v23, v0
	v_mov_b32_e32 v28, v0
	v_mov_b32_e32 v29, v0
	v_mov_b32_e32 v30, v0
	v_mov_b32_e32 v31, v0
	v_mov_b32_e32 v36, v0
	v_mov_b32_e32 v37, v0
	v_mov_b32_e32 v38, v0
	v_mov_b32_e32 v39, v0
	v_mov_b32_e32 v44, v0
	v_mov_b32_e32 v45, v0
	v_mov_b32_e32 v46, v0
	v_mov_b32_e32 v47, v0
	v_mov_b32_e32 v52, v0
	v_mov_b32_e32 v53, v0
	v_mov_b32_e32 v54, v0
	v_mov_b32_e32 v55, v0
	v_mov_b32_e32 v8, v0
	v_mov_b32_e32 v9, v0
	v_mov_b32_e32 v10, v0
	v_mov_b32_e32 v11, v0
	v_mov_b32_e32 v16, v0
	v_mov_b32_e32 v17, v0
	v_mov_b32_e32 v18, v0
	v_mov_b32_e32 v19, v0
	v_mov_b32_e32 v24, v0
	v_mov_b32_e32 v25, v0
	v_mov_b32_e32 v26, v0
	v_mov_b32_e32 v27, v0
	v_mov_b32_e32 v32, v0
	v_mov_b32_e32 v33, v0
	v_mov_b32_e32 v34, v0
	v_mov_b32_e32 v35, v0
	v_mov_b32_e32 v40, v0
	v_mov_b32_e32 v41, v0
	v_mov_b32_e32 v42, v0
	v_mov_b32_e32 v43, v0
	v_mov_b32_e32 v48, v0
	v_mov_b32_e32 v49, v0
	v_mov_b32_e32 v50, v0
	v_mov_b32_e32 v51, v0
	v_mov_b32_e32 v56, v0
	v_mov_b32_e32 v57, v0
	v_mov_b32_e32 v58, v0
	v_mov_b32_e32 v59, v0
	v_mov_b32_e32 v60, v0
	v_mov_b32_e32 v61, v0
	v_mov_b32_e32 v62, v0
	v_mov_b32_e32 v63, v0
	v_mov_b32_e32 v64, v0
	v_mov_b32_e32 v65, v0
	v_mov_b32_e32 v66, v0
	v_mov_b32_e32 v67, v0
	v_mov_b32_e32 v68, v0
	v_mov_b32_e32 v69, v0
	v_mov_b32_e32 v70, v0
	v_mov_b32_e32 v71, v0
	v_mov_b32_e32 v80, v0
	v_mov_b32_e32 v81, v0
	v_mov_b32_e32 v82, v0
	v_mov_b32_e32 v83, v0
	v_mov_b32_e32 v84, v0
	v_mov_b32_e32 v85, v0
	v_mov_b32_e32 v86, v0
	v_mov_b32_e32 v87, v0
	v_mov_b32_e32 v88, v0
	v_mov_b32_e32 v89, v0
	v_mov_b32_e32 v90, v0
	v_mov_b32_e32 v91, v0
	v_mov_b32_e32 v92, v0
	v_mov_b32_e32 v93, v0
	v_mov_b32_e32 v94, v0
	v_mov_b32_e32 v95, v0
	v_mov_b32_e32 v108, v0
	v_mov_b32_e32 v109, v0
	v_mov_b32_e32 v110, v0
	v_mov_b32_e32 v111, v0
	v_mov_b32_e32 v116, v0
	v_mov_b32_e32 v117, v0
	v_mov_b32_e32 v118, v0
	v_mov_b32_e32 v119, v0
	v_mov_b32_e32 v72, v0
	v_mov_b32_e32 v73, v0
	v_mov_b32_e32 v74, v0
	v_mov_b32_e32 v75, v0
	v_mov_b32_e32 v76, v0
	v_mov_b32_e32 v77, v0
	v_mov_b32_e32 v78, v0
	v_mov_b32_e32 v79, v0
	v_mov_b32_e32 v96, v0
	v_mov_b32_e32 v97, v0
	v_mov_b32_e32 v98, v0
	v_mov_b32_e32 v99, v0
	v_mov_b32_e32 v100, v0
	v_mov_b32_e32 v101, v0
	v_mov_b32_e32 v102, v0
	v_mov_b32_e32 v103, v0
	v_mov_b32_e32 v104, v0
	v_mov_b32_e32 v105, v0
	v_mov_b32_e32 v106, v0
	v_mov_b32_e32 v107, v0
	v_mov_b32_e32 v112, v0
	v_mov_b32_e32 v113, v0
	v_mov_b32_e32 v114, v0
	v_mov_b32_e32 v115, v0
	v_mov_b32_e32 v120, v0
	v_mov_b32_e32 v121, v0
	v_mov_b32_e32 v122, v0
	v_mov_b32_e32 v123, v0
	v_mov_b32_e32 v124, v0
	v_mov_b32_e32 v125, v0
	v_mov_b32_e32 v126, v0
	v_mov_b32_e32 v127, v0
	s_cmp_lg_u32 s99, 0
	s_cbranch_scc0 .LBB0_1093
	ds_read_b128 v[128:131], v214
	ds_read_b128 v[132:135], v214 offset:1024
	ds_read_b128 v[136:139], v214 offset:2048
	ds_read_b128 v[140:143], v214 offset:3072
	ds_read_b128 v[162:165], v215
	ds_read_b128 v[166:169], v215 offset:1024
	ds_read_b128 v[170:173], v215 offset:2048
	ds_read_b128 v[174:177], v215 offset:3072
	s_add_u32 s4, s22, 0x100
	s_addc_u32 s5, s23, 0
	s_cmp_eq_u32 s55, 60
	s_cselect_b32 s27, s17, s5
	s_cselect_b32 s26, s16, s4
	s_cselect_b32 s25, s15, s54
	s_cselect_b32 s24, s21, s53
	v_lshl_add_u64 v[210:211], s[22:23], 0, v[154:155]
	s_add_i32 m0, s37, 0xc000
	ds_read_b128 v[178:181], v216
	ds_read_b128 v[182:185], v216 offset:1024
	ds_read_b128 v[186:189], v216 offset:2048
	ds_read_b128 v[190:193], v216 offset:3072
	ds_read_b128 v[194:197], v216 offset:4096
	ds_read_b128 v[198:201], v216 offset:5120
	ds_read_b128 v[202:205], v216 offset:6144
	ds_read_b128 v[206:209], v216 offset:7168
	global_load_lds_dwordx4 v[210:211], off
	v_lshl_add_u64 v[210:211], s[22:23], 0, v[156:157]
	s_add_i32 m0, s37, 0xe000
	s_nop 0
	global_load_lds_dwordx4 v[210:211], off
	s_waitcnt vmcnt(24)
	s_waitcnt lgkmcnt(0)
	s_barrier
	s_setprio 1
	s_waitcnt lgkmcnt(0)
	v_mfma_f32_16x16x32_bf16 v[124:127], v[128:131], v[178:181], v[124:127]
	v_mfma_f32_16x16x32_bf16 v[120:123], v[136:139], v[178:181], v[120:123]
	v_mfma_f32_16x16x32_bf16 v[112:115], v[128:131], v[186:189], v[112:115]
	v_mfma_f32_16x16x32_bf16 v[104:107], v[136:139], v[186:189], v[104:107]
	v_mfma_f32_16x16x32_bf16 v[100:103], v[128:131], v[194:197], v[100:103]
	v_mfma_f32_16x16x32_bf16 v[96:99], v[136:139], v[194:197], v[96:99]
	v_mfma_f32_16x16x32_bf16 v[76:79], v[128:131], v[202:205], v[76:79]
	v_mfma_f32_16x16x32_bf16 v[72:75], v[136:139], v[202:205], v[72:75]
	v_mfma_f32_16x16x32_bf16 v[124:127], v[132:135], v[182:185], v[124:127]
	v_mfma_f32_16x16x32_bf16 v[120:123], v[140:143], v[182:185], v[120:123]
	v_mfma_f32_16x16x32_bf16 v[112:115], v[132:135], v[190:193], v[112:115]
	v_mfma_f32_16x16x32_bf16 v[104:107], v[140:143], v[190:193], v[104:107]
	v_mfma_f32_16x16x32_bf16 v[100:103], v[132:135], v[198:201], v[100:103]
	v_mfma_f32_16x16x32_bf16 v[96:99], v[140:143], v[198:201], v[96:99]
	v_mfma_f32_16x16x32_bf16 v[76:79], v[132:135], v[206:209], v[76:79]
	v_mfma_f32_16x16x32_bf16 v[72:75], v[140:143], v[206:209], v[72:75]
	s_setprio 0
	s_setprio 1
	v_mfma_f32_16x16x32_bf16 v[116:119], v[162:165], v[178:181], v[116:119]
	v_mfma_f32_16x16x32_bf16 v[108:111], v[170:173], v[178:181], v[108:111]
	v_mfma_f32_16x16x32_bf16 v[92:95], v[162:165], v[186:189], v[92:95]
	v_mfma_f32_16x16x32_bf16 v[88:91], v[170:173], v[186:189], v[88:91]
	v_mfma_f32_16x16x32_bf16 v[84:87], v[162:165], v[194:197], v[84:87]
	v_mfma_f32_16x16x32_bf16 v[80:83], v[170:173], v[194:197], v[80:83]
	v_mfma_f32_16x16x32_bf16 v[68:71], v[162:165], v[202:205], v[68:71]
	v_mfma_f32_16x16x32_bf16 v[64:67], v[170:173], v[202:205], v[64:67]
	v_mfma_f32_16x16x32_bf16 v[116:119], v[166:169], v[182:185], v[116:119]
	v_mfma_f32_16x16x32_bf16 v[108:111], v[174:177], v[182:185], v[108:111]
	v_mfma_f32_16x16x32_bf16 v[92:95], v[166:169], v[190:193], v[92:95]
	v_mfma_f32_16x16x32_bf16 v[88:91], v[174:177], v[190:193], v[88:91]
	v_mfma_f32_16x16x32_bf16 v[84:87], v[166:169], v[198:201], v[84:87]
	v_mfma_f32_16x16x32_bf16 v[80:83], v[174:177], v[198:201], v[80:83]
	v_mfma_f32_16x16x32_bf16 v[68:71], v[166:169], v[206:209], v[68:71]
	v_mfma_f32_16x16x32_bf16 v[64:67], v[174:177], v[206:209], v[64:67]
	s_setprio 0
	s_barrier
; #define PG8_STAGE(bufoff, gbase, voff) do { _Pragma("unroll") for (int _i = 0; _i < 2; ++_i) \
;         __builtin_amdgcn_global_load_lds((const unsigned*)((const char*)(gbase) + (voff)[_i]), (PG8_LAS unsigned*)(lds + (bufoff) + ldsw + _i * 8192), 16, 0, 0); } while (0)
; #define PG8_LDA(dst, b, h) do { _Pragma("unroll") for (int m = 0; m < 4; ++m) _Pragma("unroll") for (int k = 0; k < 2; ++k) dst[m][k] = *(const PG8_LAS bf16x8*)(lds + PG8_SA(b, h) + aoff + m * 2048 + k * 1024); } while (0)
; #define PG8_LDB(dst, b, h) do { _Pragma("unroll") for (int n = 0; n < 2; ++n) _Pragma("unroll") for (int k = 0; k < 2; ++k) dst[n][k] = *(const PG8_LAS bf16x8*)(lds + PG8_SB(b, h) + boff + n * 2048 + k * 1024); } while (0)
; #define PG8_MMA(ai, bj, At, Bt) do { __builtin_amdgcn_s_setprio(1); _Pragma("unroll") for (int m = 0; m < 4; ++m) _Pragma("unroll") for (int n = 0; n < 2; ++n) _Pragma("unroll") for (int k = 0; k < 2; ++k) \
;         acc[ai][bj][m][n] = __builtin_amdgcn_mfma_f32_16x16x32_bf16(Bt[n][k], At[m][k], acc[ai][bj][m][n], 0, 0, 0); __builtin_amdgcn_s_setprio(0); } while (0)
; #define PG8_WAIT_V(n) asm volatile("s_waitcnt vmcnt(" #n ")" ::: "memory")
; #define PG8_WAIT_L(n) asm volatile("s_waitcnt lgkmcnt(" #n ")" ::: "memory")
; #define PG8_BAR __builtin_amdgcn_s_barrier()
; #define PG8_SCHED __builtin_amdgcn_sched_barrier(0)
; template <class Epi, class Sched, bool ALIGN_EPI = false, bool SP2 = false>
; __device__ __forceinline__ void gemm_phase(PG8_LAS unsigned char* lds, const Gemm g, const Sched& S, const Epi& E, const int wave_in) {
;     ...
;             PG8_LDA(At, 0, 1); PG8_STAGE(PG8_SB(0, 0), b2, voffB); PG8_STAGE(PG8_SB(0, 1), b2 + hstepB, voffB); PG8_STAGE(PG8_SA(0, 0), a2, voffA);
;             PG8_WAIT_V(8); PG8_WAIT_L(0); PG8_BAR; PG8_MMA(1, 0, At, B0); PG8_MMA(1, 1, At, B1); PG8_BAR; PG8_SCHED;
;             PG8_LDB(B0, 1, 0); PG8_LDB(B1, 1, 1); PG8_SCHED; PG8_LDA(At, 1, 0); PG8_STAGE(PG8_SA(0, 1), a2 + hstepA, voffA);
;             PG8_WAIT_V(8); PG8_WAIT_L(0); PG8_BAR; PG8_MMA(0, 0, At, B0); PG8_MMA(0, 1, At, B1); PG8_BAR; PG8_SCHED;
	s_add_i32 s22, s47, s34
	v_lshl_add_u64 v[210:211], s[24:25], 0, v[148:149]
	s_mov_b32 m0, s22
	ds_read_b128 v[178:181], v216 offset:16384
	ds_read_b128 v[182:185], v216 offset:17408
	ds_read_b128 v[186:189], v216 offset:18432
	ds_read_b128 v[190:193], v216 offset:19456
	ds_read_b128 v[194:197], v216 offset:20480
	ds_read_b128 v[198:201], v216 offset:21504
	ds_read_b128 v[202:205], v216 offset:22528
	ds_read_b128 v[206:209], v216 offset:23552
	global_load_lds_dwordx4 v[210:211], off
	s_add_i32 m0, s22, 0x2000
	s_add_u32 s22, s24, 0x100000
	v_lshl_add_u64 v[218:219], s[24:25], 0, v[144:145]
	s_addc_u32 s23, s25, 0
	s_add_i32 s56, s48, s34
	global_load_lds_dwordx4 v[218:219], off
	v_lshl_add_u64 v[220:221], s[22:23], 0, v[148:149]
	s_mov_b32 m0, s56
	v_lshl_add_u64 v[222:223], s[26:27], 0, v[146:147]
	global_load_lds_dwordx4 v[220:221], off
	v_lshl_add_u64 v[220:221], s[22:23], 0, v[144:145]
	s_add_i32 m0, s56, 0x2000
	s_nop 0
	global_load_lds_dwordx4 v[220:221], off
	v_lshl_add_u64 v[220:221], s[26:27], 0, v[150:151]
	s_mov_b32 m0, s37
	s_nop 0
	global_load_lds_dwordx4 v[220:221], off
	s_mov_b32 m0, s38
	s_nop 0
	global_load_lds_dwordx4 v[222:223], off
	s_waitcnt vmcnt(24)
	s_waitcnt lgkmcnt(0)
	s_barrier
	s_setprio 1
	s_waitcnt lgkmcnt(0)
	v_mfma_f32_16x16x32_bf16 v[60:63], v[128:131], v[178:181], v[60:63]
	v_mfma_f32_16x16x32_bf16 v[56:59], v[136:139], v[178:181], v[56:59]
	v_mfma_f32_16x16x32_bf16 v[48:51], v[128:131], v[186:189], v[48:51]
	v_mfma_f32_16x16x32_bf16 v[40:43], v[136:139], v[186:189], v[40:43]
	v_mfma_f32_16x16x32_bf16 v[32:35], v[128:131], v[194:197], v[32:35]
	v_mfma_f32_16x16x32_bf16 v[24:27], v[136:139], v[194:197], v[24:27]
	v_mfma_f32_16x16x32_bf16 v[16:19], v[128:131], v[202:205], v[16:19]
	v_mfma_f32_16x16x32_bf16 v[8:11], v[136:139], v[202:205], v[8:11]
	v_mfma_f32_16x16x32_bf16 v[60:63], v[132:135], v[182:185], v[60:63]
	v_mfma_f32_16x16x32_bf16 v[56:59], v[140:143], v[182:185], v[56:59]
	v_mfma_f32_16x16x32_bf16 v[48:51], v[132:135], v[190:193], v[48:51]
	v_mfma_f32_16x16x32_bf16 v[40:43], v[140:143], v[190:193], v[40:43]
	v_mfma_f32_16x16x32_bf16 v[32:35], v[132:135], v[198:201], v[32:35]
	v_mfma_f32_16x16x32_bf16 v[24:27], v[140:143], v[198:201], v[24:27]
	v_mfma_f32_16x16x32_bf16 v[16:19], v[132:135], v[206:209], v[16:19]
	v_mfma_f32_16x16x32_bf16 v[8:11], v[140:143], v[206:209], v[8:11]
	s_setprio 0
	s_setprio 1
	v_mfma_f32_16x16x32_bf16 v[52:55], v[162:165], v[178:181], v[52:55]
	v_mfma_f32_16x16x32_bf16 v[44:47], v[170:173], v[178:181], v[44:47]
	v_mfma_f32_16x16x32_bf16 v[36:39], v[162:165], v[186:189], v[36:39]
	v_mfma_f32_16x16x32_bf16 v[28:31], v[170:173], v[186:189], v[28:31]
	v_mfma_f32_16x16x32_bf16 v[20:23], v[162:165], v[194:197], v[20:23]
	v_mfma_f32_16x16x32_bf16 v[12:15], v[170:173], v[194:197], v[12:15]
	v_mfma_f32_16x16x32_bf16 v[4:7], v[162:165], v[202:205], v[4:7]
	v_mfma_f32_16x16x32_bf16 v[0:3], v[170:173], v[202:205], v[0:3]
	v_mfma_f32_16x16x32_bf16 v[52:55], v[166:169], v[182:185], v[52:55]
	v_mfma_f32_16x16x32_bf16 v[44:47], v[174:177], v[182:185], v[44:47]
	v_mfma_f32_16x16x32_bf16 v[36:39], v[166:169], v[190:193], v[36:39]
	v_mfma_f32_16x16x32_bf16 v[28:31], v[174:177], v[190:193], v[28:31]
	v_mfma_f32_16x16x32_bf16 v[20:23], v[166:169], v[198:201], v[20:23]
	v_mfma_f32_16x16x32_bf16 v[12:15], v[174:177], v[198:201], v[12:15]
	v_mfma_f32_16x16x32_bf16 v[4:7], v[166:169], v[206:209], v[4:7]
	v_mfma_f32_16x16x32_bf16 v[0:3], v[174:177], v[206:209], v[0:3]
	s_setprio 0
	s_barrier
	s_add_i32 s56, 0, 0x18000
	s_add_i32 s57, 0, 0x1c000
	v_add_u32_e32 v140, s56, v212
	v_add_u32_e32 v174, s57, v212
	ds_read_b128 v[128:131], v140
	ds_read_b128 v[132:135], v140 offset:1024
	ds_read_b128 v[136:139], v140 offset:2048
	ds_read_b128 v[140:143], v140 offset:3072
	ds_read_b128 v[162:165], v174
	ds_read_b128 v[166:169], v174 offset:1024
	ds_read_b128 v[170:173], v174 offset:2048
	ds_read_b128 v[174:177], v174 offset:3072
	s_add_u32 s22, s26, 0x310000
	s_addc_u32 s23, s27, 0
	s_mov_b32 m0, s39
	v_lshl_add_u64 v[224:225], s[22:23], 0, v[150:151]
	ds_read_b128 v[178:181], v216 offset:32768
	ds_read_b128 v[182:185], v216 offset:33792
	ds_read_b128 v[186:189], v216 offset:34816
	ds_read_b128 v[190:193], v216 offset:35840
	ds_read_b128 v[194:197], v216 offset:36864
	ds_read_b128 v[198:201], v216 offset:37888
	ds_read_b128 v[202:205], v216 offset:38912
	ds_read_b128 v[206:209], v216 offset:39936
	global_load_lds_dwordx4 v[224:225], off
	v_lshl_add_u64 v[224:225], s[22:23], 0, v[146:147]
	s_mov_b32 m0, s40
	s_nop 0
	global_load_lds_dwordx4 v[224:225], off
	s_waitcnt vmcnt(8)
	s_waitcnt lgkmcnt(0)
	s_barrier
; #define PG8_STAGE(bufoff, gbase, voff) do { _Pragma("unroll") for (int _i = 0; _i < 2; ++_i) \
;         __builtin_amdgcn_global_load_lds((const unsigned*)((const char*)(gbase) + (voff)[_i]), (PG8_LAS unsigned*)(lds + (bufoff) + ldsw + _i * 8192), 16, 0, 0); } while (0)
; #define PG8_LDA(dst, b, h) do { _Pragma("unroll") for (int m = 0; m < 4; ++m) _Pragma("unroll") for (int k = 0; k < 2; ++k) dst[m][k] = *(const PG8_LAS bf16x8*)(lds + PG8_SA(b, h) + aoff + m * 2048 + k * 1024); } while (0)
; #define PG8_MMA(ai, bj, At, Bt) do { __builtin_amdgcn_s_setprio(1); _Pragma("unroll") for (int m = 0; m < 4; ++m) _Pragma("unroll") for (int n = 0; n < 2; ++n) _Pragma("unroll") for (int k = 0; k < 2; ++k) \
;         acc[ai][bj][m][n] = __builtin_amdgcn_mfma_f32_16x16x32_bf16(Bt[n][k], At[m][k], acc[ai][bj][m][n], 0, 0, 0); __builtin_amdgcn_s_setprio(0); } while (0)
; #define PG8_WAIT_V(n) asm volatile("s_waitcnt vmcnt(" #n ")" ::: "memory")
; #define PG8_WAIT_L(n) asm volatile("s_waitcnt lgkmcnt(" #n ")" ::: "memory")
; #define PG8_BAR __builtin_amdgcn_s_barrier()
; #define PG8_SCHED __builtin_amdgcn_sched_barrier(0)
; template <class Epi, class Sched, bool ALIGN_EPI = false, bool SP2 = false>
; __device__ __forceinline__ void gemm_phase(PG8_LAS unsigned char* lds, const Gemm g, const Sched& S, const Epi& E, const int wave_in) {
;     ...
;             PG8_WAIT_V(8); PG8_WAIT_L(0); PG8_BAR; PG8_MMA(0, 0, At, B0); PG8_MMA(0, 1, At, B1); PG8_BAR; PG8_SCHED;
;             PG8_LDA(At, 1, 1); PG8_STAGE(PG8_SB(1, 0), b3, voffB); PG8_STAGE(PG8_SB(1, 1), b3 + hstepB, voffB); PG8_STAGE(PG8_SA(1, 0), a3, voffA);
;             PG8_WAIT_V(8); PG8_WAIT_L(0); PG8_BAR; PG8_MMA(1, 0, At, B0); PG8_MMA(1, 1, At, B1); PG8_BAR; PG8_SCHED;
	s_setprio 1
	s_waitcnt lgkmcnt(0)
	v_mfma_f32_16x16x32_bf16 v[124:127], v[128:131], v[178:181], v[124:127]
	v_mfma_f32_16x16x32_bf16 v[120:123], v[136:139], v[178:181], v[120:123]
	v_mfma_f32_16x16x32_bf16 v[112:115], v[128:131], v[186:189], v[112:115]
	v_mfma_f32_16x16x32_bf16 v[104:107], v[136:139], v[186:189], v[104:107]
	v_mfma_f32_16x16x32_bf16 v[100:103], v[128:131], v[194:197], v[100:103]
	v_mfma_f32_16x16x32_bf16 v[96:99], v[136:139], v[194:197], v[96:99]
	v_mfma_f32_16x16x32_bf16 v[76:79], v[128:131], v[202:205], v[76:79]
	v_mfma_f32_16x16x32_bf16 v[72:75], v[136:139], v[202:205], v[72:75]
	v_mfma_f32_16x16x32_bf16 v[124:127], v[132:135], v[182:185], v[124:127]
	v_mfma_f32_16x16x32_bf16 v[120:123], v[140:143], v[182:185], v[120:123]
	v_mfma_f32_16x16x32_bf16 v[112:115], v[132:135], v[190:193], v[112:115]
	v_mfma_f32_16x16x32_bf16 v[104:107], v[140:143], v[190:193], v[104:107]
	v_mfma_f32_16x16x32_bf16 v[100:103], v[132:135], v[198:201], v[100:103]
	v_mfma_f32_16x16x32_bf16 v[96:99], v[140:143], v[198:201], v[96:99]
	v_mfma_f32_16x16x32_bf16 v[76:79], v[132:135], v[206:209], v[76:79]
	v_mfma_f32_16x16x32_bf16 v[72:75], v[140:143], v[206:209], v[72:75]
	s_setprio 0
	s_setprio 1
	v_mfma_f32_16x16x32_bf16 v[116:119], v[162:165], v[178:181], v[116:119]
	v_mfma_f32_16x16x32_bf16 v[108:111], v[170:173], v[178:181], v[108:111]
	v_mfma_f32_16x16x32_bf16 v[92:95], v[162:165], v[186:189], v[92:95]
	v_mfma_f32_16x16x32_bf16 v[88:91], v[170:173], v[186:189], v[88:91]
	v_mfma_f32_16x16x32_bf16 v[84:87], v[162:165], v[194:197], v[84:87]
	v_mfma_f32_16x16x32_bf16 v[80:83], v[170:173], v[194:197], v[80:83]
	v_mfma_f32_16x16x32_bf16 v[68:71], v[162:165], v[202:205], v[68:71]
	v_mfma_f32_16x16x32_bf16 v[64:67], v[170:173], v[202:205], v[64:67]
	v_mfma_f32_16x16x32_bf16 v[116:119], v[166:169], v[182:185], v[116:119]
	v_mfma_f32_16x16x32_bf16 v[108:111], v[174:177], v[182:185], v[108:111]
	v_mfma_f32_16x16x32_bf16 v[92:95], v[166:169], v[190:193], v[92:95]
	v_mfma_f32_16x16x32_bf16 v[88:91], v[174:177], v[190:193], v[88:91]
	v_mfma_f32_16x16x32_bf16 v[84:87], v[166:169], v[198:201], v[84:87]
	v_mfma_f32_16x16x32_bf16 v[80:83], v[174:177], v[198:201], v[80:83]
	v_mfma_f32_16x16x32_bf16 v[68:71], v[166:169], v[206:209], v[68:71]
	v_mfma_f32_16x16x32_bf16 v[64:67], v[174:177], v[206:209], v[64:67]
	s_setprio 0
	s_barrier
	s_add_i32 s22, s56, s34
	v_lshl_add_u64 v[210:211], v[210:211], 0, s[6:7]
	s_mov_b32 m0, s22
	ds_read_b128 v[178:181], v216 offset:49152
	ds_read_b128 v[182:185], v216 offset:50176
	ds_read_b128 v[186:189], v216 offset:51200
	ds_read_b128 v[190:193], v216 offset:52224
	ds_read_b128 v[194:197], v216 offset:53248
	ds_read_b128 v[198:201], v216 offset:54272
	ds_read_b128 v[202:205], v216 offset:55296
	ds_read_b128 v[206:209], v216 offset:56320
	global_load_lds_dwordx4 v[210:211], off
	s_add_i32 m0, s22, 0x2000
	s_add_u32 s22, s24, 0x100080
	v_lshl_add_u64 v[210:211], v[218:219], 0, s[6:7]
	s_addc_u32 s23, s25, 0
	s_add_i32 s24, s57, s34
	global_load_lds_dwordx4 v[210:211], off
	v_lshl_add_u64 v[210:211], s[22:23], 0, v[148:149]
	s_mov_b32 m0, s24
	s_nop 0
	global_load_lds_dwordx4 v[210:211], off
	v_lshl_add_u64 v[210:211], s[22:23], 0, v[144:145]
	s_add_i32 m0, s24, 0x2000
	s_nop 0
	global_load_lds_dwordx4 v[210:211], off
	v_lshl_add_u64 v[210:211], v[220:221], 0, s[6:7]
	s_mov_b32 m0, s44
	s_nop 0
	global_load_lds_dwordx4 v[210:211], off
	v_lshl_add_u64 v[210:211], v[222:223], 0, s[6:7]
	s_mov_b32 m0, s45
	s_nop 0
	global_load_lds_dwordx4 v[210:211], off
	s_waitcnt vmcnt(8)
	s_waitcnt lgkmcnt(0)
	s_barrier
	s_setprio 1
	s_waitcnt lgkmcnt(0)
	v_mfma_f32_16x16x32_bf16 v[60:63], v[128:131], v[178:181], v[60:63]
	v_mfma_f32_16x16x32_bf16 v[56:59], v[136:139], v[178:181], v[56:59]
	v_mfma_f32_16x16x32_bf16 v[48:51], v[128:131], v[186:189], v[48:51]
	v_mfma_f32_16x16x32_bf16 v[40:43], v[136:139], v[186:189], v[40:43]
	v_mfma_f32_16x16x32_bf16 v[32:35], v[128:131], v[194:197], v[32:35]
	v_mfma_f32_16x16x32_bf16 v[24:27], v[136:139], v[194:197], v[24:27]
	v_mfma_f32_16x16x32_bf16 v[16:19], v[128:131], v[202:205], v[16:19]
	v_mfma_f32_16x16x32_bf16 v[8:11], v[136:139], v[202:205], v[8:11]
	v_mfma_f32_16x16x32_bf16 v[60:63], v[132:135], v[182:185], v[60:63]
	v_mfma_f32_16x16x32_bf16 v[56:59], v[140:143], v[182:185], v[56:59]
	v_mfma_f32_16x16x32_bf16 v[48:51], v[132:135], v[190:193], v[48:51]
	v_mfma_f32_16x16x32_bf16 v[40:43], v[140:143], v[190:193], v[40:43]
	v_mfma_f32_16x16x32_bf16 v[32:35], v[132:135], v[198:201], v[32:35]
	v_mfma_f32_16x16x32_bf16 v[24:27], v[140:143], v[198:201], v[24:27]
	v_mfma_f32_16x16x32_bf16 v[16:19], v[132:135], v[206:209], v[16:19]
	v_mfma_f32_16x16x32_bf16 v[8:11], v[140:143], v[206:209], v[8:11]
	s_setprio 0
	s_setprio 1
	v_mfma_f32_16x16x32_bf16 v[52:55], v[162:165], v[178:181], v[52:55]
	v_mfma_f32_16x16x32_bf16 v[44:47], v[170:173], v[178:181], v[44:47]
	v_mfma_f32_16x16x32_bf16 v[36:39], v[162:165], v[186:189], v[36:39]
	v_mfma_f32_16x16x32_bf16 v[28:31], v[170:173], v[186:189], v[28:31]
	v_mfma_f32_16x16x32_bf16 v[20:23], v[162:165], v[194:197], v[20:23]
	v_mfma_f32_16x16x32_bf16 v[12:15], v[170:173], v[194:197], v[12:15]
	v_mfma_f32_16x16x32_bf16 v[4:7], v[162:165], v[202:205], v[4:7]
	v_mfma_f32_16x16x32_bf16 v[0:3], v[170:173], v[202:205], v[0:3]
	v_mfma_f32_16x16x32_bf16 v[52:55], v[166:169], v[182:185], v[52:55]
	v_mfma_f32_16x16x32_bf16 v[44:47], v[174:177], v[182:185], v[44:47]
	v_mfma_f32_16x16x32_bf16 v[36:39], v[166:169], v[190:193], v[36:39]
	v_mfma_f32_16x16x32_bf16 v[28:31], v[174:177], v[190:193], v[28:31]
	v_mfma_f32_16x16x32_bf16 v[20:23], v[166:169], v[198:201], v[20:23]
	v_mfma_f32_16x16x32_bf16 v[12:15], v[174:177], v[198:201], v[12:15]
	v_mfma_f32_16x16x32_bf16 v[4:7], v[166:169], v[206:209], v[4:7]
	v_mfma_f32_16x16x32_bf16 v[0:3], v[174:177], v[206:209], v[0:3]
	s_setprio 0
	s_barrier
	s_add_i32 s55, s55, 2
	s_add_u32 s53, s53, 0x100
	s_addc_u32 s54, s54, 0
	s_cmp_gt_u32 s55, 61
	s_mov_b64 s[22:23], s[4:5]
	s_cbranch_scc0 .LBB0_1093
; #define PG8_STAGE(bufoff, gbase, voff) do { _Pragma("unroll") for (int _i = 0; _i < 2; ++_i) \
;         __builtin_amdgcn_global_load_lds((const unsigned*)((const char*)(gbase) + (voff)[_i]), (PG8_LAS unsigned*)(lds + (bufoff) + ldsw + _i * 8192), 16, 0, 0); } while (0)
; #define PG8_LDA(dst, b, h) do { _Pragma("unroll") for (int m = 0; m < 4; ++m) _Pragma("unroll") for (int k = 0; k < 2; ++k) dst[m][k] = *(const PG8_LAS bf16x8*)(lds + PG8_SA(b, h) + aoff + m * 2048 + k * 1024); } while (0)
; #define PG8_LDB(dst, b, h) do { _Pragma("unroll") for (int n = 0; n < 2; ++n) _Pragma("unroll") for (int k = 0; k < 2; ++k) dst[n][k] = *(const PG8_LAS bf16x8*)(lds + PG8_SB(b, h) + boff + n * 2048 + k * 1024); } while (0)
; #define PG8_MMA(ai, bj, At, Bt) do { __builtin_amdgcn_s_setprio(1); _Pragma("unroll") for (int m = 0; m < 4; ++m) _Pragma("unroll") for (int n = 0; n < 2; ++n) _Pragma("unroll") for (int k = 0; k < 2; ++k) \
;         acc[ai][bj][m][n] = __builtin_amdgcn_mfma_f32_16x16x32_bf16(Bt[n][k], At[m][k], acc[ai][bj][m][n], 0, 0, 0); __builtin_amdgcn_s_setprio(0); } while (0)
; #define PG8_WAIT_V(n) asm volatile("s_waitcnt vmcnt(" #n ")" ::: "memory")
; #define PG8_WAIT_L(n) asm volatile("s_waitcnt lgkmcnt(" #n ")" ::: "memory")
; #define PG8_BAR __builtin_amdgcn_s_barrier()
; #define PG8_SCHED __builtin_amdgcn_sched_barrier(0)
; template <class Epi, class Sched, bool ALIGN_EPI = false, bool SP2 = false>
; __device__ __forceinline__ void gemm_phase(PG8_LAS unsigned char* lds, const Gemm g, const Sched& S, const Epi& E, const int wave_in) {
;     ...
;             PG8_LDB(B0, 0, 0); PG8_LDB(B1, 0, 1); PG8_SCHED; PG8_LDA(At, 0, 0); PG8_STAGE(PG8_SA(1, 1), a1 + hstepA, voffA);
;             PG8_WAIT_V(8); PG8_WAIT_L(0); PG8_BAR; PG8_MMA(0, 0, At, B0); PG8_MMA(0, 1, At, B1); PG8_BAR; PG8_SCHED;
;             PG8_LDA(At, 0, 1); PG8_STAGE(PG8_SB(0, 0), b2, voffB); PG8_STAGE(PG8_SB(0, 1), b2 + hstepB, voffB); PG8_STAGE(PG8_SA(0, 0), a2, voffA);
;             PG8_WAIT_V(8); PG8_WAIT_L(0); PG8_BAR; PG8_MMA(1, 0, At, B0); PG8_MMA(1, 1, At, B1); PG8_BAR; PG8_SCHED;
.LBB0_1093:
	ds_read_b128 v[128:131], v214
	ds_read_b128 v[132:135], v214 offset:1024
	ds_read_b128 v[136:139], v214 offset:2048
	ds_read_b128 v[140:143], v214 offset:3072
	ds_read_b128 v[162:165], v215
	ds_read_b128 v[166:169], v215 offset:1024
	ds_read_b128 v[170:173], v215 offset:2048
	ds_read_b128 v[174:177], v215 offset:3072
	s_add_u32 s4, s22, 0x100
	s_addc_u32 s5, s23, 0
	s_cmp_eq_u32 s55, 60
	s_cselect_b32 s27, s17, s5
	s_cselect_b32 s26, s16, s4
	s_cselect_b32 s25, s15, s54
	s_cselect_b32 s24, s21, s53
	v_lshl_add_u64 v[210:211], s[22:23], 0, v[154:155]
	s_add_i32 m0, s37, 0xc000
	ds_read_b128 v[178:181], v216
	ds_read_b128 v[182:185], v216 offset:1024
	ds_read_b128 v[186:189], v216 offset:2048
	ds_read_b128 v[190:193], v216 offset:3072
	ds_read_b128 v[194:197], v216 offset:4096
	ds_read_b128 v[198:201], v216 offset:5120
	ds_read_b128 v[202:205], v216 offset:6144
	ds_read_b128 v[206:209], v216 offset:7168
	global_load_lds_dwordx4 v[210:211], off
	v_lshl_add_u64 v[210:211], s[22:23], 0, v[156:157]
	s_add_i32 m0, s37, 0xe000
	s_nop 0
	global_load_lds_dwordx4 v[210:211], off
	s_waitcnt vmcnt(8)
	s_waitcnt lgkmcnt(0)
	s_barrier
	s_setprio 1
	s_waitcnt lgkmcnt(0)
	v_mfma_f32_16x16x32_bf16 v[124:127], v[128:131], v[178:181], v[124:127]
	v_mfma_f32_16x16x32_bf16 v[120:123], v[136:139], v[178:181], v[120:123]
	v_mfma_f32_16x16x32_bf16 v[112:115], v[128:131], v[186:189], v[112:115]
	v_mfma_f32_16x16x32_bf16 v[104:107], v[136:139], v[186:189], v[104:107]
	v_mfma_f32_16x16x32_bf16 v[100:103], v[128:131], v[194:197], v[100:103]
	v_mfma_f32_16x16x32_bf16 v[96:99], v[136:139], v[194:197], v[96:99]
	v_mfma_f32_16x16x32_bf16 v[76:79], v[128:131], v[202:205], v[76:79]
	v_mfma_f32_16x16x32_bf16 v[72:75], v[136:139], v[202:205], v[72:75]
	v_mfma_f32_16x16x32_bf16 v[124:127], v[132:135], v[182:185], v[124:127]
	v_mfma_f32_16x16x32_bf16 v[120:123], v[140:143], v[182:185], v[120:123]
	v_mfma_f32_16x16x32_bf16 v[112:115], v[132:135], v[190:193], v[112:115]
	v_mfma_f32_16x16x32_bf16 v[104:107], v[140:143], v[190:193], v[104:107]
	v_mfma_f32_16x16x32_bf16 v[100:103], v[132:135], v[198:201], v[100:103]
	v_mfma_f32_16x16x32_bf16 v[96:99], v[140:143], v[198:201], v[96:99]
	v_mfma_f32_16x16x32_bf16 v[76:79], v[132:135], v[206:209], v[76:79]
	v_mfma_f32_16x16x32_bf16 v[72:75], v[140:143], v[206:209], v[72:75]
	s_setprio 0
	s_setprio 1
	v_mfma_f32_16x16x32_bf16 v[116:119], v[162:165], v[178:181], v[116:119]
	v_mfma_f32_16x16x32_bf16 v[108:111], v[170:173], v[178:181], v[108:111]
	v_mfma_f32_16x16x32_bf16 v[92:95], v[162:165], v[186:189], v[92:95]
	v_mfma_f32_16x16x32_bf16 v[88:91], v[170:173], v[186:189], v[88:91]
	v_mfma_f32_16x16x32_bf16 v[84:87], v[162:165], v[194:197], v[84:87]
	v_mfma_f32_16x16x32_bf16 v[80:83], v[170:173], v[194:197], v[80:83]
	v_mfma_f32_16x16x32_bf16 v[68:71], v[162:165], v[202:205], v[68:71]
	v_mfma_f32_16x16x32_bf16 v[64:67], v[170:173], v[202:205], v[64:67]
	v_mfma_f32_16x16x32_bf16 v[116:119], v[166:169], v[182:185], v[116:119]
	v_mfma_f32_16x16x32_bf16 v[108:111], v[174:177], v[182:185], v[108:111]
	v_mfma_f32_16x16x32_bf16 v[92:95], v[166:169], v[190:193], v[92:95]
	v_mfma_f32_16x16x32_bf16 v[88:91], v[174:177], v[190:193], v[88:91]
	v_mfma_f32_16x16x32_bf16 v[84:87], v[166:169], v[198:201], v[84:87]
	v_mfma_f32_16x16x32_bf16 v[80:83], v[174:177], v[198:201], v[80:83]
	v_mfma_f32_16x16x32_bf16 v[68:71], v[166:169], v[206:209], v[68:71]
	v_mfma_f32_16x16x32_bf16 v[64:67], v[174:177], v[206:209], v[64:67]
	s_setprio 0
	s_barrier
	s_add_i32 s22, s47, s34
	v_lshl_add_u64 v[210:211], s[24:25], 0, v[148:149]
	s_mov_b32 m0, s22
	ds_read_b128 v[178:181], v216 offset:16384
	ds_read_b128 v[182:185], v216 offset:17408
	ds_read_b128 v[186:189], v216 offset:18432
	ds_read_b128 v[190:193], v216 offset:19456
	ds_read_b128 v[194:197], v216 offset:20480
	ds_read_b128 v[198:201], v216 offset:21504
	ds_read_b128 v[202:205], v216 offset:22528
	ds_read_b128 v[206:209], v216 offset:23552
	global_load_lds_dwordx4 v[210:211], off
	s_add_i32 m0, s22, 0x2000
	s_add_u32 s22, s24, 0x100000
	v_lshl_add_u64 v[218:219], s[24:25], 0, v[144:145]
	s_addc_u32 s23, s25, 0
	s_add_i32 s56, s48, s34
	global_load_lds_dwordx4 v[218:219], off
	v_lshl_add_u64 v[220:221], s[22:23], 0, v[148:149]
	s_mov_b32 m0, s56
	v_lshl_add_u64 v[222:223], s[26:27], 0, v[146:147]
	global_load_lds_dwordx4 v[220:221], off
	v_lshl_add_u64 v[220:221], s[22:23], 0, v[144:145]
	s_add_i32 m0, s56, 0x2000
	s_nop 0
	global_load_lds_dwordx4 v[220:221], off
	v_lshl_add_u64 v[220:221], s[26:27], 0, v[150:151]
	s_mov_b32 m0, s37
	s_nop 0
	global_load_lds_dwordx4 v[220:221], off
	s_mov_b32 m0, s38
	s_nop 0
	global_load_lds_dwordx4 v[222:223], off
	s_waitcnt vmcnt(8)
	s_waitcnt lgkmcnt(0)
	s_barrier
; #define PG8_STAGE(bufoff, gbase, voff) do { _Pragma("unroll") for (int _i = 0; _i < 2; ++_i) \
;         __builtin_amdgcn_global_load_lds((const unsigned*)((const char*)(gbase) + (voff)[_i]), (PG8_LAS unsigned*)(lds + (bufoff) + ldsw + _i * 8192), 16, 0, 0); } while (0)
; #define PG8_LDA(dst, b, h) do { _Pragma("unroll") for (int m = 0; m < 4; ++m) _Pragma("unroll") for (int k = 0; k < 2; ++k) dst[m][k] = *(const PG8_LAS bf16x8*)(lds + PG8_SA(b, h) + aoff + m * 2048 + k * 1024); } while (0)
; #define PG8_LDB(dst, b, h) do { _Pragma("unroll") for (int n = 0; n < 2; ++n) _Pragma("unroll") for (int k = 0; k < 2; ++k) dst[n][k] = *(const PG8_LAS bf16x8*)(lds + PG8_SB(b, h) + boff + n * 2048 + k * 1024); } while (0)
; #define PG8_MMA(ai, bj, At, Bt) do { __builtin_amdgcn_s_setprio(1); _Pragma("unroll") for (int m = 0; m < 4; ++m) _Pragma("unroll") for (int n = 0; n < 2; ++n) _Pragma("unroll") for (int k = 0; k < 2; ++k) \
;         acc[ai][bj][m][n] = __builtin_amdgcn_mfma_f32_16x16x32_bf16(Bt[n][k], At[m][k], acc[ai][bj][m][n], 0, 0, 0); __builtin_amdgcn_s_setprio(0); } while (0)
; #define PG8_WAIT_V(n) asm volatile("s_waitcnt vmcnt(" #n ")" ::: "memory")
; #define PG8_WAIT_L(n) asm volatile("s_waitcnt lgkmcnt(" #n ")" ::: "memory")
; #define PG8_BAR __builtin_amdgcn_s_barrier()
; #define PG8_SCHED __builtin_amdgcn_sched_barrier(0)
; template <class Epi, class Sched, bool ALIGN_EPI = false, bool SP2 = false>
; __device__ __forceinline__ void gemm_phase(PG8_LAS unsigned char* lds, const Gemm g, const Sched& S, const Epi& E, const int wave_in) {
;     ...
;             PG8_WAIT_V(8); PG8_WAIT_L(0); PG8_BAR; PG8_MMA(1, 0, At, B0); PG8_MMA(1, 1, At, B1); PG8_BAR; PG8_SCHED;
;             PG8_LDB(B0, 1, 0); PG8_LDB(B1, 1, 1); PG8_SCHED; PG8_LDA(At, 1, 0); PG8_STAGE(PG8_SA(0, 1), a2 + hstepA, voffA);
;             PG8_WAIT_V(8); PG8_WAIT_L(0); PG8_BAR; PG8_MMA(0, 0, At, B0); PG8_MMA(0, 1, At, B1); PG8_BAR; PG8_SCHED;
	s_setprio 1
	s_waitcnt lgkmcnt(0)
	v_mfma_f32_16x16x32_bf16 v[60:63], v[128:131], v[178:181], v[60:63]
	v_mfma_f32_16x16x32_bf16 v[56:59], v[136:139], v[178:181], v[56:59]
	v_mfma_f32_16x16x32_bf16 v[48:51], v[128:131], v[186:189], v[48:51]
	v_mfma_f32_16x16x32_bf16 v[40:43], v[136:139], v[186:189], v[40:43]
	v_mfma_f32_16x16x32_bf16 v[32:35], v[128:131], v[194:197], v[32:35]
	v_mfma_f32_16x16x32_bf16 v[24:27], v[136:139], v[194:197], v[24:27]
	v_mfma_f32_16x16x32_bf16 v[16:19], v[128:131], v[202:205], v[16:19]
	v_mfma_f32_16x16x32_bf16 v[8:11], v[136:139], v[202:205], v[8:11]
	v_mfma_f32_16x16x32_bf16 v[60:63], v[132:135], v[182:185], v[60:63]
	v_mfma_f32_16x16x32_bf16 v[56:59], v[140:143], v[182:185], v[56:59]
	v_mfma_f32_16x16x32_bf16 v[48:51], v[132:135], v[190:193], v[48:51]
	v_mfma_f32_16x16x32_bf16 v[40:43], v[140:143], v[190:193], v[40:43]
	v_mfma_f32_16x16x32_bf16 v[32:35], v[132:135], v[198:201], v[32:35]
	v_mfma_f32_16x16x32_bf16 v[24:27], v[140:143], v[198:201], v[24:27]
	v_mfma_f32_16x16x32_bf16 v[16:19], v[132:135], v[206:209], v[16:19]
	v_mfma_f32_16x16x32_bf16 v[8:11], v[140:143], v[206:209], v[8:11]
	s_setprio 0
	s_setprio 1
	v_mfma_f32_16x16x32_bf16 v[52:55], v[162:165], v[178:181], v[52:55]
	v_mfma_f32_16x16x32_bf16 v[44:47], v[170:173], v[178:181], v[44:47]
	v_mfma_f32_16x16x32_bf16 v[36:39], v[162:165], v[186:189], v[36:39]
	v_mfma_f32_16x16x32_bf16 v[28:31], v[170:173], v[186:189], v[28:31]
	v_mfma_f32_16x16x32_bf16 v[20:23], v[162:165], v[194:197], v[20:23]
	v_mfma_f32_16x16x32_bf16 v[12:15], v[170:173], v[194:197], v[12:15]
	v_mfma_f32_16x16x32_bf16 v[4:7], v[162:165], v[202:205], v[4:7]
	v_mfma_f32_16x16x32_bf16 v[0:3], v[170:173], v[202:205], v[0:3]
	v_mfma_f32_16x16x32_bf16 v[52:55], v[166:169], v[182:185], v[52:55]
	v_mfma_f32_16x16x32_bf16 v[44:47], v[174:177], v[182:185], v[44:47]
	v_mfma_f32_16x16x32_bf16 v[36:39], v[166:169], v[190:193], v[36:39]
	v_mfma_f32_16x16x32_bf16 v[28:31], v[174:177], v[190:193], v[28:31]
	v_mfma_f32_16x16x32_bf16 v[20:23], v[166:169], v[198:201], v[20:23]
	v_mfma_f32_16x16x32_bf16 v[12:15], v[174:177], v[198:201], v[12:15]
	v_mfma_f32_16x16x32_bf16 v[4:7], v[166:169], v[206:209], v[4:7]
	v_mfma_f32_16x16x32_bf16 v[0:3], v[174:177], v[206:209], v[0:3]
	s_setprio 0
	s_barrier
	s_add_i32 s56, 0, 0x18000
	s_add_i32 s57, 0, 0x1c000
	v_add_u32_e32 v140, s56, v212
	v_add_u32_e32 v174, s57, v212
	ds_read_b128 v[128:131], v140
	ds_read_b128 v[132:135], v140 offset:1024
	ds_read_b128 v[136:139], v140 offset:2048
	ds_read_b128 v[140:143], v140 offset:3072
	ds_read_b128 v[162:165], v174
	ds_read_b128 v[166:169], v174 offset:1024
	ds_read_b128 v[170:173], v174 offset:2048
	ds_read_b128 v[174:177], v174 offset:3072
	s_add_u32 s22, s26, 0x310000
	s_addc_u32 s23, s27, 0
	s_mov_b32 m0, s39
	v_lshl_add_u64 v[224:225], s[22:23], 0, v[150:151]
	ds_read_b128 v[178:181], v216 offset:32768
	ds_read_b128 v[182:185], v216 offset:33792
	ds_read_b128 v[186:189], v216 offset:34816
	ds_read_b128 v[190:193], v216 offset:35840
	ds_read_b128 v[194:197], v216 offset:36864
	ds_read_b128 v[198:201], v216 offset:37888
	ds_read_b128 v[202:205], v216 offset:38912
	ds_read_b128 v[206:209], v216 offset:39936
	global_load_lds_dwordx4 v[224:225], off
	v_lshl_add_u64 v[224:225], s[22:23], 0, v[146:147]
	s_mov_b32 m0, s40
	s_nop 0
	global_load_lds_dwordx4 v[224:225], off
	s_waitcnt vmcnt(8)
	s_waitcnt lgkmcnt(0)
	s_barrier
	s_setprio 1
	s_waitcnt lgkmcnt(0)
	v_mfma_f32_16x16x32_bf16 v[124:127], v[128:131], v[178:181], v[124:127]
	v_mfma_f32_16x16x32_bf16 v[120:123], v[136:139], v[178:181], v[120:123]
	v_mfma_f32_16x16x32_bf16 v[112:115], v[128:131], v[186:189], v[112:115]
	v_mfma_f32_16x16x32_bf16 v[104:107], v[136:139], v[186:189], v[104:107]
	v_mfma_f32_16x16x32_bf16 v[100:103], v[128:131], v[194:197], v[100:103]
	v_mfma_f32_16x16x32_bf16 v[96:99], v[136:139], v[194:197], v[96:99]
	v_mfma_f32_16x16x32_bf16 v[76:79], v[128:131], v[202:205], v[76:79]
	v_mfma_f32_16x16x32_bf16 v[72:75], v[136:139], v[202:205], v[72:75]
	v_mfma_f32_16x16x32_bf16 v[124:127], v[132:135], v[182:185], v[124:127]
	v_mfma_f32_16x16x32_bf16 v[120:123], v[140:143], v[182:185], v[120:123]
	v_mfma_f32_16x16x32_bf16 v[112:115], v[132:135], v[190:193], v[112:115]
	v_mfma_f32_16x16x32_bf16 v[104:107], v[140:143], v[190:193], v[104:107]
	v_mfma_f32_16x16x32_bf16 v[100:103], v[132:135], v[198:201], v[100:103]
	v_mfma_f32_16x16x32_bf16 v[96:99], v[140:143], v[198:201], v[96:99]
	v_mfma_f32_16x16x32_bf16 v[76:79], v[132:135], v[206:209], v[76:79]
	v_mfma_f32_16x16x32_bf16 v[72:75], v[140:143], v[206:209], v[72:75]
	s_setprio 0
	s_setprio 1
	v_mfma_f32_16x16x32_bf16 v[116:119], v[162:165], v[178:181], v[116:119]
	v_mfma_f32_16x16x32_bf16 v[108:111], v[170:173], v[178:181], v[108:111]
	v_mfma_f32_16x16x32_bf16 v[92:95], v[162:165], v[186:189], v[92:95]
	v_mfma_f32_16x16x32_bf16 v[88:91], v[170:173], v[186:189], v[88:91]
	v_mfma_f32_16x16x32_bf16 v[84:87], v[162:165], v[194:197], v[84:87]
	v_mfma_f32_16x16x32_bf16 v[80:83], v[170:173], v[194:197], v[80:83]
	v_mfma_f32_16x16x32_bf16 v[68:71], v[162:165], v[202:205], v[68:71]
	v_mfma_f32_16x16x32_bf16 v[64:67], v[170:173], v[202:205], v[64:67]
	v_mfma_f32_16x16x32_bf16 v[116:119], v[166:169], v[182:185], v[116:119]
	v_mfma_f32_16x16x32_bf16 v[108:111], v[174:177], v[182:185], v[108:111]
	v_mfma_f32_16x16x32_bf16 v[92:95], v[166:169], v[190:193], v[92:95]
	v_mfma_f32_16x16x32_bf16 v[88:91], v[174:177], v[190:193], v[88:91]
	v_mfma_f32_16x16x32_bf16 v[84:87], v[166:169], v[198:201], v[84:87]
	v_mfma_f32_16x16x32_bf16 v[80:83], v[174:177], v[198:201], v[80:83]
	v_mfma_f32_16x16x32_bf16 v[68:71], v[166:169], v[206:209], v[68:71]
	v_mfma_f32_16x16x32_bf16 v[64:67], v[174:177], v[206:209], v[64:67]
	s_setprio 0
	s_barrier
; #define PG8_STAGE(bufoff, gbase, voff) do { _Pragma("unroll") for (int _i = 0; _i < 2; ++_i) \
;         __builtin_amdgcn_global_load_lds((const unsigned*)((const char*)(gbase) + (voff)[_i]), (PG8_LAS unsigned*)(lds + (bufoff) + ldsw + _i * 8192), 16, 0, 0); } while (0)
; #define PG8_LDA(dst, b, h) do { _Pragma("unroll") for (int m = 0; m < 4; ++m) _Pragma("unroll") for (int k = 0; k < 2; ++k) dst[m][k] = *(const PG8_LAS bf16x8*)(lds + PG8_SA(b, h) + aoff + m * 2048 + k * 1024); } while (0)
; #define PG8_MMA(ai, bj, At, Bt) do { __builtin_amdgcn_s_setprio(1); _Pragma("unroll") for (int m = 0; m < 4; ++m) _Pragma("unroll") for (int n = 0; n < 2; ++n) _Pragma("unroll") for (int k = 0; k < 2; ++k) \
;         acc[ai][bj][m][n] = __builtin_amdgcn_mfma_f32_16x16x32_bf16(Bt[n][k], At[m][k], acc[ai][bj][m][n], 0, 0, 0); __builtin_amdgcn_s_setprio(0); } while (0)
; #define PG8_WAIT_V(n) asm volatile("s_waitcnt vmcnt(" #n ")" ::: "memory")
; #define PG8_WAIT_L(n) asm volatile("s_waitcnt lgkmcnt(" #n ")" ::: "memory")
; #define PG8_BAR __builtin_amdgcn_s_barrier()
; #define PG8_SCHED __builtin_amdgcn_sched_barrier(0)
; template <class Epi, class Sched, bool ALIGN_EPI = false, bool SP2 = false>
; __device__ __forceinline__ void gemm_phase(PG8_LAS unsigned char* lds, const Gemm g, const Sched& S, const Epi& E, const int wave_in) {
;     ...
;             PG8_LDA(At, 1, 1); PG8_STAGE(PG8_SB(1, 0), b3, voffB); PG8_STAGE(PG8_SB(1, 1), b3 + hstepB, voffB); PG8_STAGE(PG8_SA(1, 0), a3, voffA);
;             PG8_WAIT_V(8); PG8_WAIT_L(0); PG8_BAR; PG8_MMA(1, 0, At, B0); PG8_MMA(1, 1, At, B1); PG8_BAR; PG8_SCHED;
;     ...
;         if (!has_next) break;
	s_add_i32 s22, s56, s34
	v_lshl_add_u64 v[210:211], v[210:211], 0, s[6:7]
	s_mov_b32 m0, s22
	ds_read_b128 v[178:181], v216 offset:49152
	ds_read_b128 v[182:185], v216 offset:50176
	ds_read_b128 v[186:189], v216 offset:51200
	ds_read_b128 v[190:193], v216 offset:52224
	ds_read_b128 v[194:197], v216 offset:53248
	ds_read_b128 v[198:201], v216 offset:54272
	ds_read_b128 v[202:205], v216 offset:55296
	ds_read_b128 v[206:209], v216 offset:56320
	global_load_lds_dwordx4 v[210:211], off
	s_add_i32 m0, s22, 0x2000
	s_add_u32 s22, s24, 0x100080
	v_lshl_add_u64 v[210:211], v[218:219], 0, s[6:7]
	s_addc_u32 s23, s25, 0
	s_add_i32 s24, s57, s34
	global_load_lds_dwordx4 v[210:211], off
	v_lshl_add_u64 v[210:211], s[22:23], 0, v[148:149]
	s_mov_b32 m0, s24
	s_nop 0
	global_load_lds_dwordx4 v[210:211], off
	v_lshl_add_u64 v[210:211], s[22:23], 0, v[144:145]
	s_add_i32 m0, s24, 0x2000
	s_nop 0
	global_load_lds_dwordx4 v[210:211], off
	v_lshl_add_u64 v[210:211], v[220:221], 0, s[6:7]
	s_mov_b32 m0, s44
	s_nop 0
	global_load_lds_dwordx4 v[210:211], off
	v_lshl_add_u64 v[210:211], v[222:223], 0, s[6:7]
	s_mov_b32 m0, s45
	s_nop 0
	global_load_lds_dwordx4 v[210:211], off
	s_waitcnt vmcnt(8)
	s_waitcnt lgkmcnt(0)
	s_barrier
	s_setprio 1
	s_waitcnt lgkmcnt(0)
	v_mfma_f32_16x16x32_bf16 v[60:63], v[128:131], v[178:181], v[60:63]
	v_mfma_f32_16x16x32_bf16 v[56:59], v[136:139], v[178:181], v[56:59]
	v_mfma_f32_16x16x32_bf16 v[48:51], v[128:131], v[186:189], v[48:51]
	v_mfma_f32_16x16x32_bf16 v[40:43], v[136:139], v[186:189], v[40:43]
	v_mfma_f32_16x16x32_bf16 v[32:35], v[128:131], v[194:197], v[32:35]
	v_mfma_f32_16x16x32_bf16 v[24:27], v[136:139], v[194:197], v[24:27]
	v_mfma_f32_16x16x32_bf16 v[16:19], v[128:131], v[202:205], v[16:19]
	v_mfma_f32_16x16x32_bf16 v[8:11], v[136:139], v[202:205], v[8:11]
	v_mfma_f32_16x16x32_bf16 v[60:63], v[132:135], v[182:185], v[60:63]
	v_mfma_f32_16x16x32_bf16 v[56:59], v[140:143], v[182:185], v[56:59]
	v_mfma_f32_16x16x32_bf16 v[48:51], v[132:135], v[190:193], v[48:51]
	v_mfma_f32_16x16x32_bf16 v[40:43], v[140:143], v[190:193], v[40:43]
	v_mfma_f32_16x16x32_bf16 v[32:35], v[132:135], v[198:201], v[32:35]
	v_mfma_f32_16x16x32_bf16 v[24:27], v[140:143], v[198:201], v[24:27]
	v_mfma_f32_16x16x32_bf16 v[16:19], v[132:135], v[206:209], v[16:19]
	v_mfma_f32_16x16x32_bf16 v[8:11], v[140:143], v[206:209], v[8:11]
	s_setprio 0
	s_setprio 1
	v_mfma_f32_16x16x32_bf16 v[52:55], v[162:165], v[178:181], v[52:55]
	v_mfma_f32_16x16x32_bf16 v[44:47], v[170:173], v[178:181], v[44:47]
	v_mfma_f32_16x16x32_bf16 v[36:39], v[162:165], v[186:189], v[36:39]
	v_mfma_f32_16x16x32_bf16 v[28:31], v[170:173], v[186:189], v[28:31]
	v_mfma_f32_16x16x32_bf16 v[20:23], v[162:165], v[194:197], v[20:23]
	v_mfma_f32_16x16x32_bf16 v[12:15], v[170:173], v[194:197], v[12:15]
	v_mfma_f32_16x16x32_bf16 v[4:7], v[162:165], v[202:205], v[4:7]
	v_mfma_f32_16x16x32_bf16 v[0:3], v[170:173], v[202:205], v[0:3]
	v_mfma_f32_16x16x32_bf16 v[52:55], v[166:169], v[182:185], v[52:55]
	v_mfma_f32_16x16x32_bf16 v[44:47], v[174:177], v[182:185], v[44:47]
	v_mfma_f32_16x16x32_bf16 v[36:39], v[166:169], v[190:193], v[36:39]
	v_mfma_f32_16x16x32_bf16 v[28:31], v[174:177], v[190:193], v[28:31]
	v_mfma_f32_16x16x32_bf16 v[20:23], v[166:169], v[198:201], v[20:23]
	v_mfma_f32_16x16x32_bf16 v[12:15], v[174:177], v[198:201], v[12:15]
	v_mfma_f32_16x16x32_bf16 v[4:7], v[166:169], v[206:209], v[4:7]
	v_mfma_f32_16x16x32_bf16 v[0:3], v[174:177], v[206:209], v[0:3]
	s_setprio 0
	s_barrier
	s_add_i32 s55, s55, 2
	s_add_u32 s53, s53, 0x100
	s_addc_u32 s54, s54, 0
	s_cmp_gt_u32 s55, 61
	s_mov_b64 s[22:23], s[4:5]
	s_cbranch_scc0 .LBB0_1093
	s_mov_b32 s99, 1
	s_and_b64 vcc, exec, s[8:9]
	s_cbranch_vccz .LBB0_1096
	s_barrier

;     __host__ __device__ bool next(int i, Unit& u) const { const bool ok = StaticOrder::next(i, u); u.pm = 0; u.pn = 0; return ok; }
;     __host__ __device__ bool next(int i, Unit& u) const {
;         const long L = (long)i * G + c; if (L >= nwg) return false;
;         int wgid = (int)L; { const int q = nwg / NXCD, r = nwg % NXCD, xcd = wgid % NXCD, off = wgid / NXCD; wgid = (xcd < r ? xcd * (q + 1) : r * (q + 1) + (xcd - r) * q) + off; }
;         const int nig = WGM * nN, gid = wgid / nig, fm = gid * WGM, gsz = (nM - fm) < WGM ? (nM - fm) : WGM;
;         u.pm = fm + ((wgid % nig) % gsz); u.pn = (wgid % nig) / gsz; return true;
;     }
; template <int L> __device__ __forceinline__ void layer_body(Frame& F, const Args& args, unsigned char* const wsg, const int lo, const int hi, const XcdBarrier& bar) {
;     ...
;         if (IN(base + 5)) {
;             const int Mr = M_ALL - row_lo2;
;             pg8::Gemm g{(const pg8::bf16_t*)(wsg + WS_H) + (size_t)row_lo2 * DM, (const pg8::bf16_t*)(wsg + WS_WT_UP), Mr, UP_N, DM, DM};
;             pg8::StaticOrder S; S.init(Mr, UP_N, F.G, (int)blockIdx.x);
;             pg8::EpiConvGate E{(pg8::bf16_t*)(wsg + WS_P) + (size_t)row_lo2 * DFF, (pg8::bf16_t*)(wsg + WS_WT_IN), args.in[I_FFNCW] + (size_t)L * 3 * UP_N, pm02};
;             pg8::gemm_phase<pg8::EpiConvGate, pg8::StaticOrder, true, true>(F.lds, g, S, E, F.wave);
.LBB0_1206:
	s_cmp_gt_i32 s52, 14
	s_cselect_b64 s[0:1], -1, 0
	s_cmp_lt_i32 s53, 15
	s_cselect_b64 s[2:3], -1, 0
	s_or_b64 s[0:1], s[0:1], s[2:3]
	s_and_b64 vcc, exec, s[0:1]
	s_cbranch_vccnz .LBB0_1291
	s_mov_b32 s99, 0
	s_cmpk_lt_i32 s73, 0x1830
	s_cselect_b64 s[2:3], -1, 0
	s_cmpk_gt_i32 s73, 0x182f
	v_mbcnt_lo_u32_b32 v10, -1, 0
	v_mbcnt_hi_u32_b32 v10, -1, v10
	s_cbranch_scc1 .LBB0_1210
	s_ashr_i32 s0, s73, 31
	s_lshr_b32 s0, s0, 29
	s_add_i32 s0, s73, s0
	s_ashr_i32 s1, s0, 3
	s_and_b32 s0, s0, -8
	s_sub_i32 s0, s73, s0
	s_cmp_lt_i32 s0, 0
	s_movk_i32 s4, 0x307
	s_cselect_b32 s4, s4, 0x306
	s_mul_i32 s0, s4, s0
	s_add_i32 s0, s0, s1
	s_mul_hi_i32 s1, s0, 0x2fa0be83
	s_lshr_b32 s4, s1, 31
	s_ashr_i32 s1, s1, 5
	s_add_i32 s1, s1, s4
	s_lshl_b32 s4, s1, 2
	s_mulk_i32 s1, 0xac
	s_sub_i32 s0, s0, s1
	s_sext_i32_i16 s1, s0
	s_bfe_u32 s1, s1, 0x2001d
	s_add_i32 s1, s0, s1
	s_sext_i32_i16 s5, s1
	s_and_b32 s1, s1, 0xfffc
	s_sub_i32 s0, s0, s1
	s_sext_i32_i16 s0, s0
	s_add_i32 s12, s4, s0
	s_ashr_i32 s0, s5, 2
	s_andn2_b64 vcc, exec, s[2:3]
	s_cbranch_vccz .LBB0_1211

; template <class Epi, class Sched, bool ALIGN_EPI = false, bool SP2 = false>
; __device__ __forceinline__ void gemm_phase(PG8_LAS unsigned char* lds, const Gemm g, const Sched& S, const Epi& E, const int wave_in) {
;     const int lane = lane_id_asm(), wid = __builtin_amdgcn_readfirstlane(wave_in), tid = wid * 64 + lane, wr = wid >> 2, wc = wid & 3, fr = lane & 15, fq = lane >> 4;
;     const int K = g.K, nt = K / BK;
;     unsigned voffA[2], voffB[2];
; #pragma unroll
;     for (int i = 0; i < 2; ++i) { int R, C; stage_rc(tid * 16 + i * 8192, R, C); const int Rb = Epi::PERM ? ((R & ~31) + perm32(R & 31)) : R;
;         voffA[i] = (unsigned)(R * g.lda + C) * 2u; voffB[i] = (unsigned)(Rb * K + C) * 2u; }
;     const size_t kstep = (size_t)(BK * 2);
;     const size_t hstepA = (size_t)HALF * g.lda * 2, hstepB = (size_t)HALF * K * 2;
;     const size_t tstepA = 2 * hstepA, tstepB = 2 * hstepB;
;     const unsigned ldsw = (unsigned)wid * 1024u;
;     const int aoff = lds_byte(wr * 64 + fr, fq * 8), boff = lds_byte(wc * 32 + fr, fq * 8);
;     ...
;     Unit cur, nxt; int ui = 0;
;     if (!S.next(0, cur)) return;
;     f32x4 acc[2][2][4][2];
; #pragma unroll
;     for (int a = 0; a < 2; ++a)
; #pragma unroll
;         for (int b = 0; b < 2; ++b)
; #pragma unroll
;             for (int m = 0; m < 4; ++m)
; #pragma unroll
;                 for (int n = 0; n < 2; ++n) acc[a][b][m][n] = (f32x4){0.f, 0.f, 0.f, 0.f};
;     bf16x8 At[4][2], B0[2][2], B1[2][2];
;     const char* cA = (const char*)g.A + (size_t)cur.pm * tstepA; const char* cB = (const char*)g.Bt + (size_t)cur.pn * tstepB;
;     S.a_ready(cur);
;     if constexpr (SP2) {
; template <int L> __device__ __forceinline__ void layer_body(Frame& F, const Args& args, unsigned char* const wsg, const int lo, const int hi, const XcdBarrier& bar) {
;     ...
;         if (IN(base + 7)) {
;             const int Mr = M_ALL - row_lo2;
;             pg8::Gemm g{(const pg8::bf16_t*)(wsg + WS_P) + (size_t)row_lo2 * DFF, (const pg8::bf16_t*)(wsg + WS_WT_DN), Mr, DM, DFF, DFF};
;             pg8::StaticOrder S; S.init(Mr, DM, F.G, (int)blockIdx.x);
;             typedef pg8::EpiResidT<true, !last> EpiD;
;             EpiD E{nullptr, nullptr, X16mid, X16A, args.out, (const float*)(wsg + WS_MOD) + (size_t)L * 17 * NMODC + 5 * DM, pm02, 0};
;             pg8::gemm_phase<EpiD, pg8::StaticOrder, true, true>(F.lds, g, S, E, F.wave);
.LBB0_1361:
	s_cmp_gt_i32 s52, 16
	s_cselect_b64 s[0:1], -1, 0
	s_cmp_lt_i32 s53, 17
	s_cselect_b64 s[2:3], -1, 0
	s_or_b64 s[0:1], s[0:1], s[2:3]
	s_and_b64 vcc, exec, s[0:1]
	s_cbranch_vccnz .LBB0_1432
	s_mov_b32 s99, 0
	s_cmpk_gt_i32 s73, 0x47f
	v_mbcnt_lo_u32_b32 v10, -1, 0
	v_mbcnt_hi_u32_b32 v10, -1, v10
	s_cbranch_scc1 .LBB0_1382
	s_waitcnt lgkmcnt(0)
	s_add_u32 s26, s70, 0xa700000
	s_addc_u32 s27, s71, 0
	s_add_u32 s28, s70, 0x9100000
	s_addc_u32 s29, s71, 0
	s_lshl_b32 s30, s33, 10
	v_lshl_add_u32 v0, v10, 4, s30
	v_add_u32_e32 v1, 0x2000, v0
	v_ashrrev_i32_e32 v2, 31, v1
	v_lshrrev_b32_e32 v2, 22, v2
	v_add_u32_e32 v2, v1, v2
	v_ashrrev_i32_e32 v8, 10, v2
	v_mul_i32_i24_e32 v2, 0x400, v8
	v_sub_u32_e32 v1, v1, v2
	v_lshrrev_b32_e32 v2, 4, v1
	v_bitop3_b32 v1, v2, v1, 32 bitop3:0x6c
	v_ashrrev_i32_e32 v2, 31, v1
	v_lshrrev_b32_e32 v2, 26, v2
	v_add_u32_e32 v2, v1, v2
	v_ashrrev_i32_e32 v9, 6, v2
	v_lshlrev_b32_e32 v3, 3, v8
	v_and_b32_e32 v2, 0xffc0, v2
	v_and_b32_e32 v3, -16, v3
	v_sub_u32_e32 v1, v1, v2
	v_add_u32_e32 v3, v9, v3
	v_lshrrev_b16_e32 v2, 7, v1
	v_and_b32_e32 v4, 3, v9
	s_mov_b32 s0, 0x1ffffe0
	v_lshrrev_b32_e32 v5, 2, v3
	v_lshlrev_b32_e32 v6, 1, v3
	v_and_b32_e32 v2, 1, v2
	v_and_or_b32 v4, v3, s0, v4
	v_and_b32_e32 v5, 4, v5
	v_and_b32_e32 v6, 24, v6
	v_add_u16_e32 v1, v1, v2
	v_mov_b32_e32 v2, 1
	v_or3_b32 v4, v4, v5, v6
	v_lshlrev_b32_e32 v5, 5, v8
	v_ashrrev_i16_sdwa v1, v2, sext(v1) dst_sel:DWORD dst_unused:UNUSED_PAD src0_sel:DWORD src1_sel:BYTE_0
	s_movk_i32 s2, 0x1580
	v_and_b32_e32 v11, 32, v5
	v_bfe_i32 v12, v1, 0, 16
	v_mul_lo_u32 v4, v4, s2
	v_add_u32_e32 v1, v11, v12
	v_mul_lo_u32 v3, v3, s2
	v_add_lshl_u32 v144, v4, v1, 1
	v_add_lshl_u32 v146, v1, v3, 1
	v_ashrrev_i32_e32 v1, 31, v0
	v_lshrrev_b32_e32 v1, 22, v1
	v_add_u32_e32 v1, v0, v1
	v_ashrrev_i32_e32 v13, 10, v1
	v_mul_i32_i24_e32 v1, 0x400, v13
	v_sub_u32_e32 v0, v0, v1
	v_lshrrev_b32_e32 v1, 4, v0
	v_bitop3_b32 v0, v1, v0, 32 bitop3:0x6c
	v_ashrrev_i32_e32 v1, 31, v0
	v_lshrrev_b32_e32 v1, 26, v1
	v_add_u32_e32 v1, v0, v1
	v_lshlrev_b32_e32 v3, 3, v13
	v_ashrrev_i32_e32 v14, 6, v1
	v_and_b32_e32 v3, -16, v3
	v_add_u32_e32 v3, v14, v3
	v_and_b32_e32 v4, 3, v14
	s_ashr_i32 s31, s73, 31
	v_and_or_b32 v4, v3, s0, v4
	s_lshr_b32 s0, s31, 29
	s_add_i32 s0, s73, s0
	s_ashr_i32 s1, s0, 3
	s_and_b32 s0, s0, -8
	s_ashr_i32 s3, s33, 2
	s_sub_i32 s0, s73, s0
	s_cmp_lt_i32 s0, 0
	s_movk_i32 s34, 0x91
	s_cselect_b32 s4, s34, 0x90
	s_mul_i32 s0, s4, s0
	s_add_i32 s0, s0, s1
	s_ashr_i32 s1, s0, 31
	s_lshr_b32 s1, s1, 27
	s_add_i32 s1, s0, s1
	s_ashr_i32 s4, s1, 5
	s_andn2_b32 s1, s1, 31
	s_sub_i32 s0, s0, s1
	s_bfe_i32 s1, s0, 0x80000
	s_bfe_u32 s1, s1, 0x2000d
	s_add_i32 s1, s0, s1
	s_lshl_b32 s5, s4, 2
	s_bfe_i32 s4, s1, 0x80000
	s_and_b32 s1, s1, 0xfc
	s_sub_i32 s0, s0, s1
	v_lshrrev_b32_e32 v5, 2, v3
	v_lshlrev_b32_e32 v6, 1, v3
	v_and_b32_e32 v1, 0xc0, v1
	s_sext_i32_i16 s6, s4
	s_sext_i32_i8 s0, s0
	v_and_b32_e32 v5, 4, v5
	v_and_b32_e32 v6, 24, v6
	v_sub_u32_e32 v0, v0, v1
	s_add_i32 s16, s5, s0
	s_ashr_i32 s0, s6, 2
	v_or3_b32 v4, v4, v5, v6
	v_lshlrev_b32_e32 v5, 5, v13
	v_ashrrev_i16_sdwa v0, v2, sext(v0) dst_sel:DWORD dst_unused:UNUSED_PAD src0_sel:DWORD src1_sel:BYTE_0
	s_lshr_b32 s4, s6, 2
	s_mul_hi_i32 s1, s0, 0x2b0000
	s_mul_i32 s0, s0, 0x2b0000
	v_and_b32_e32 v15, 32, v5
	v_bfe_i32 v16, v0, 0, 16
	s_add_u32 s20, s28, s0
	v_mul_lo_u32 v4, v4, s2
	v_add_u32_e32 v0, v15, v16
	s_addc_u32 s21, s29, s1
	s_add_i32 s35, s30, 0
	v_add_lshl_u32 v148, v4, v0, 1
	s_add_i32 m0, s35, 0x10000
	s_mul_i32 s7, s16, 0x2b0000
	global_load_lds_dwordx4 v148, s[20:21]
	s_add_i32 m0, s35, 0x12000
	s_add_u32 s0, s20, 0x158000
	global_load_lds_dwordx4 v144, s[20:21]
	s_addc_u32 s1, s21, 0
	s_add_i32 m0, s35, 0x14000
	s_mul_hi_i32 s5, s16, 0x2b0000
	global_load_lds_dwordx4 v148, s[0:1]
	s_add_i32 m0, s35, 0x16000
	s_add_u32 s18, s26, s7
	v_mul_lo_u32 v1, v3, s2
	s_addc_u32 s19, s27, s5
	s_add_i32 s36, s35, 0x2000
	v_add_lshl_u32 v150, v0, v1, 1
	global_load_lds_dwordx4 v144, s[0:1]
	s_mov_b32 m0, s35
	s_add_u32 s0, s18, 0x158000
	global_load_lds_dwordx4 v150, s[18:19]
	s_mov_b32 m0, s36
	s_addc_u32 s1, s19, 0
	s_add_i32 s37, s35, 0x4000
	global_load_lds_dwordx4 v146, s[18:19]
	s_mov_b32 m0, s37
	s_add_i32 s38, s35, 0x6000
	global_load_lds_dwordx4 v150, s[0:1]
	s_mov_b32 m0, s38
	v_mov_b32_e32 v149, 0
	global_load_lds_dwordx4 v146, s[0:1]
	v_mov_b32_e32 v145, v149
	v_mov_b32_e32 v151, v149
	v_mov_b32_e32 v147, v149
	s_cmp_eq_u32 s3, 1
	s_mov_b32 s39, 0
	v_lshl_add_u64 v[6:7], s[20:21], 0, v[148:149]
	v_lshl_add_u64 v[4:5], s[20:21], 0, v[144:145]
	v_lshl_add_u64 v[0:1], s[18:19], 0, v[150:151]
	s_cselect_b64 s[0:1], -1, 0
	s_cmp_lg_u32 s3, 1
	v_lshl_add_u64 v[2:3], s[18:19], 0, v[146:147]
	s_cbranch_scc1 .LBB0_1365
	s_barrier

; #define PG8_STAGE(bufoff, gbase, voff) do { _Pragma("unroll") for (int _i = 0; _i < 2; ++_i) \
;         __builtin_amdgcn_global_load_lds((const unsigned*)((const char*)(gbase) + (voff)[_i]), (PG8_LAS unsigned*)(lds + (bufoff) + ldsw + _i * 8192), 16, 0, 0); } while (0)
; #define PG8_LDA(dst, b, h) do { _Pragma("unroll") for (int m = 0; m < 4; ++m) _Pragma("unroll") for (int k = 0; k < 2; ++k) dst[m][k] = *(const PG8_LAS bf16x8*)(lds + PG8_SA(b, h) + aoff + m * 2048 + k * 1024); } while (0)
; #define PG8_LDB(dst, b, h) do { _Pragma("unroll") for (int n = 0; n < 2; ++n) _Pragma("unroll") for (int k = 0; k < 2; ++k) dst[n][k] = *(const PG8_LAS bf16x8*)(lds + PG8_SB(b, h) + boff + n * 2048 + k * 1024); } while (0)
; #define PG8_MMA(ai, bj, At, Bt) do { __builtin_amdgcn_s_setprio(1); _Pragma("unroll") for (int m = 0; m < 4; ++m) _Pragma("unroll") for (int n = 0; n < 2; ++n) _Pragma("unroll") for (int k = 0; k < 2; ++k) \
;         acc[ai][bj][m][n] = __builtin_amdgcn_mfma_f32_16x16x32_bf16(Bt[n][k], At[m][k], acc[ai][bj][m][n], 0, 0, 0); __builtin_amdgcn_s_setprio(0); } while (0)
; #define PG8_WAIT_V(n) asm volatile("s_waitcnt vmcnt(" #n ")" ::: "memory")
; #define PG8_WAIT_L(n) asm volatile("s_waitcnt lgkmcnt(" #n ")" ::: "memory")
; #define PG8_BAR __builtin_amdgcn_s_barrier()
; #define PG8_SCHED __builtin_amdgcn_sched_barrier(0)
; template <class Epi, class Sched, bool ALIGN_EPI = false, bool SP2 = false>
; __device__ __forceinline__ void gemm_phase(PG8_LAS unsigned char* lds, const Gemm g, const Sched& S, const Epi& E, const int wave_in) {
;     ...
;             PG8_LDB(B0, 0, 0); PG8_LDB(B1, 0, 1); PG8_SCHED; PG8_LDA(At, 0, 0); PG8_STAGE(PG8_SA(1, 1), a1 + hstepA, voffA);
;             PG8_WAIT_V(8); PG8_WAIT_L(0); PG8_BAR; PG8_MMA(0, 0, At, B0); PG8_MMA(0, 1, At, B1); PG8_BAR; PG8_SCHED;
;     ...
; #pragma unroll
;         for (int a = 0; a < 2; ++a)
; #pragma unroll
;             for (int b = 0; b < 2; ++b)
; #pragma unroll
;                 for (int m = 0; m < 4; ++m)
; #pragma unroll
;                     for (int n = 0; n < 2; ++n) acc[a][b][m][n] = (f32x4){0.f, 0.f, 0.f, 0.f};
.LBB0_1374:
	s_add_u32 s17, s20, 0x100
	v_mov_b32_e32 v0, 0
	s_addc_u32 s53, s21, 0
	s_mov_b32 s54, -2
	v_mov_b32_e32 v1, v0
	v_mov_b32_e32 v2, v0
	v_mov_b32_e32 v3, v0
	v_mov_b32_e32 v4, v0
	v_mov_b32_e32 v5, v0
	v_mov_b32_e32 v6, v0
	v_mov_b32_e32 v7, v0
	v_mov_b32_e32 v12, v0
	v_mov_b32_e32 v13, v0
	v_mov_b32_e32 v14, v0
	v_mov_b32_e32 v15, v0
	v_mov_b32_e32 v20, v0
	v_mov_b32_e32 v21, v0
	v_mov_b32_e32 v22, v0
	v_mov_b32_e32 v23, v0
	v_mov_b32_e32 v28, v0
	v_mov_b32_e32 v29, v0
	v_mov_b32_e32 v30, v0
	v_mov_b32_e32 v31, v0
	v_mov_b32_e32 v36, v0
	v_mov_b32_e32 v37, v0
	v_mov_b32_e32 v38, v0
	v_mov_b32_e32 v39, v0
	v_mov_b32_e32 v44, v0
	v_mov_b32_e32 v45, v0
	v_mov_b32_e32 v46, v0
	v_mov_b32_e32 v47, v0
	v_mov_b32_e32 v52, v0
	v_mov_b32_e32 v53, v0
	v_mov_b32_e32 v54, v0
	v_mov_b32_e32 v55, v0
	v_mov_b32_e32 v8, v0
	v_mov_b32_e32 v9, v0
	v_mov_b32_e32 v10, v0
	v_mov_b32_e32 v11, v0
	v_mov_b32_e32 v16, v0
	v_mov_b32_e32 v17, v0
	v_mov_b32_e32 v18, v0
	v_mov_b32_e32 v19, v0
	v_mov_b32_e32 v24, v0
	v_mov_b32_e32 v25, v0
	v_mov_b32_e32 v26, v0
	v_mov_b32_e32 v27, v0
	v_mov_b32_e32 v32, v0
	v_mov_b32_e32 v33, v0
	v_mov_b32_e32 v34, v0
	v_mov_b32_e32 v35, v0
	v_mov_b32_e32 v40, v0
	v_mov_b32_e32 v41, v0
	v_mov_b32_e32 v42, v0
	v_mov_b32_e32 v43, v0
	v_mov_b32_e32 v48, v0
	v_mov_b32_e32 v49, v0
	v_mov_b32_e32 v50, v0
	v_mov_b32_e32 v51, v0
	v_mov_b32_e32 v56, v0
	v_mov_b32_e32 v57, v0
	v_mov_b32_e32 v58, v0
	v_mov_b32_e32 v59, v0
	v_mov_b32_e32 v60, v0
	v_mov_b32_e32 v61, v0
	v_mov_b32_e32 v62, v0
	v_mov_b32_e32 v63, v0
	v_mov_b32_e32 v64, v0
	v_mov_b32_e32 v65, v0
	v_mov_b32_e32 v66, v0
	v_mov_b32_e32 v67, v0
	v_mov_b32_e32 v68, v0
	v_mov_b32_e32 v69, v0
	v_mov_b32_e32 v70, v0
	v_mov_b32_e32 v71, v0
	v_mov_b32_e32 v80, v0
	v_mov_b32_e32 v81, v0
	v_mov_b32_e32 v82, v0
	v_mov_b32_e32 v83, v0
	v_mov_b32_e32 v84, v0
	v_mov_b32_e32 v85, v0
	v_mov_b32_e32 v86, v0
	v_mov_b32_e32 v87, v0
	v_mov_b32_e32 v88, v0
	v_mov_b32_e32 v89, v0
	v_mov_b32_e32 v90, v0
	v_mov_b32_e32 v91, v0
	v_mov_b32_e32 v92, v0
	v_mov_b32_e32 v93, v0
	v_mov_b32_e32 v94, v0
	v_mov_b32_e32 v95, v0
	v_mov_b32_e32 v108, v0
	v_mov_b32_e32 v109, v0
	v_mov_b32_e32 v110, v0
	v_mov_b32_e32 v111, v0
	v_mov_b32_e32 v116, v0
	v_mov_b32_e32 v117, v0
	v_mov_b32_e32 v118, v0
	v_mov_b32_e32 v119, v0
	v_mov_b32_e32 v72, v0
	v_mov_b32_e32 v73, v0
	v_mov_b32_e32 v74, v0
	v_mov_b32_e32 v75, v0
	v_mov_b32_e32 v76, v0
	v_mov_b32_e32 v77, v0
	v_mov_b32_e32 v78, v0
	v_mov_b32_e32 v79, v0
	v_mov_b32_e32 v96, v0
	v_mov_b32_e32 v97, v0
	v_mov_b32_e32 v98, v0
	v_mov_b32_e32 v99, v0
	v_mov_b32_e32 v100, v0
	v_mov_b32_e32 v101, v0
	v_mov_b32_e32 v102, v0
	v_mov_b32_e32 v103, v0
	v_mov_b32_e32 v104, v0
	v_mov_b32_e32 v105, v0
	v_mov_b32_e32 v106, v0
	v_mov_b32_e32 v107, v0
	v_mov_b32_e32 v112, v0
	v_mov_b32_e32 v113, v0
	v_mov_b32_e32 v114, v0
	v_mov_b32_e32 v115, v0
	v_mov_b32_e32 v120, v0
	v_mov_b32_e32 v121, v0
	v_mov_b32_e32 v122, v0
	v_mov_b32_e32 v123, v0
	v_mov_b32_e32 v124, v0
	v_mov_b32_e32 v125, v0
	v_mov_b32_e32 v126, v0
	v_mov_b32_e32 v127, v0
	s_cmp_lg_u32 s99, 0
	s_cbranch_scc0 .LBB0_1375
	ds_read_b128 v[128:131], v214
	ds_read_b128 v[132:135], v214 offset:1024
	ds_read_b128 v[136:139], v214 offset:2048
	ds_read_b128 v[140:143], v214 offset:3072
	ds_read_b128 v[162:165], v215
	ds_read_b128 v[166:169], v215 offset:1024
	ds_read_b128 v[170:173], v215 offset:2048
	ds_read_b128 v[174:177], v215 offset:3072
	s_add_u32 s20, s18, 0x100
	s_addc_u32 s21, s19, 0
	s_cmpk_eq_i32 s54, 0x52
	s_cselect_b32 s25, s5, s21
	s_cselect_b32 s24, s4, s20
	s_cselect_b32 s23, s15, s53
	s_cselect_b32 s22, s14, s17
	v_lshl_add_u64 v[210:211], s[18:19], 0, v[154:155]
	s_add_i32 m0, s35, 0xc000
	ds_read_b128 v[178:181], v216
	ds_read_b128 v[182:185], v216 offset:1024
	ds_read_b128 v[186:189], v216 offset:2048
	ds_read_b128 v[190:193], v216 offset:3072
	ds_read_b128 v[194:197], v216 offset:4096
	ds_read_b128 v[198:201], v216 offset:5120
	ds_read_b128 v[202:205], v216 offset:6144
	ds_read_b128 v[206:209], v216 offset:7168
	global_load_lds_dwordx4 v[210:211], off
	v_lshl_add_u64 v[210:211], s[18:19], 0, v[156:157]
	s_add_i32 m0, s35, 0xe000
	s_nop 0
	global_load_lds_dwordx4 v[210:211], off
	s_waitcnt vmcnt(24)
	s_waitcnt lgkmcnt(0)
	s_barrier
	s_setprio 1
	s_waitcnt lgkmcnt(0)
	v_mfma_f32_16x16x32_bf16 v[124:127], v[128:131], v[178:181], v[124:127]
	v_mfma_f32_16x16x32_bf16 v[120:123], v[136:139], v[178:181], v[120:123]
	v_mfma_f32_16x16x32_bf16 v[112:115], v[128:131], v[186:189], v[112:115]
	v_mfma_f32_16x16x32_bf16 v[104:107], v[136:139], v[186:189], v[104:107]
	v_mfma_f32_16x16x32_bf16 v[100:103], v[128:131], v[194:197], v[100:103]
	v_mfma_f32_16x16x32_bf16 v[96:99], v[136:139], v[194:197], v[96:99]
	v_mfma_f32_16x16x32_bf16 v[76:79], v[128:131], v[202:205], v[76:79]
	v_mfma_f32_16x16x32_bf16 v[72:75], v[136:139], v[202:205], v[72:75]
	v_mfma_f32_16x16x32_bf16 v[124:127], v[132:135], v[182:185], v[124:127]
	v_mfma_f32_16x16x32_bf16 v[120:123], v[140:143], v[182:185], v[120:123]
	v_mfma_f32_16x16x32_bf16 v[112:115], v[132:135], v[190:193], v[112:115]
	v_mfma_f32_16x16x32_bf16 v[104:107], v[140:143], v[190:193], v[104:107]
	v_mfma_f32_16x16x32_bf16 v[100:103], v[132:135], v[198:201], v[100:103]
	v_mfma_f32_16x16x32_bf16 v[96:99], v[140:143], v[198:201], v[96:99]
	v_mfma_f32_16x16x32_bf16 v[76:79], v[132:135], v[206:209], v[76:79]
	v_mfma_f32_16x16x32_bf16 v[72:75], v[140:143], v[206:209], v[72:75]
	s_setprio 0
	s_setprio 1
	v_mfma_f32_16x16x32_bf16 v[116:119], v[162:165], v[178:181], v[116:119]
	v_mfma_f32_16x16x32_bf16 v[108:111], v[170:173], v[178:181], v[108:111]
	v_mfma_f32_16x16x32_bf16 v[92:95], v[162:165], v[186:189], v[92:95]
	v_mfma_f32_16x16x32_bf16 v[88:91], v[170:173], v[186:189], v[88:91]
	v_mfma_f32_16x16x32_bf16 v[84:87], v[162:165], v[194:197], v[84:87]
	v_mfma_f32_16x16x32_bf16 v[80:83], v[170:173], v[194:197], v[80:83]
	v_mfma_f32_16x16x32_bf16 v[68:71], v[162:165], v[202:205], v[68:71]
	v_mfma_f32_16x16x32_bf16 v[64:67], v[170:173], v[202:205], v[64:67]
	v_mfma_f32_16x16x32_bf16 v[116:119], v[166:169], v[182:185], v[116:119]
	v_mfma_f32_16x16x32_bf16 v[108:111], v[174:177], v[182:185], v[108:111]
	v_mfma_f32_16x16x32_bf16 v[92:95], v[166:169], v[190:193], v[92:95]
	v_mfma_f32_16x16x32_bf16 v[88:91], v[174:177], v[190:193], v[88:91]
	v_mfma_f32_16x16x32_bf16 v[84:87], v[166:169], v[198:201], v[84:87]
	v_mfma_f32_16x16x32_bf16 v[80:83], v[174:177], v[198:201], v[80:83]
	v_mfma_f32_16x16x32_bf16 v[68:71], v[166:169], v[206:209], v[68:71]
	v_mfma_f32_16x16x32_bf16 v[64:67], v[174:177], v[206:209], v[64:67]
	s_setprio 0
	s_barrier
; #define PG8_STAGE(bufoff, gbase, voff) do { _Pragma("unroll") for (int _i = 0; _i < 2; ++_i) \
;         __builtin_amdgcn_global_load_lds((const unsigned*)((const char*)(gbase) + (voff)[_i]), (PG8_LAS unsigned*)(lds + (bufoff) + ldsw + _i * 8192), 16, 0, 0); } while (0)
; #define PG8_LDA(dst, b, h) do { _Pragma("unroll") for (int m = 0; m < 4; ++m) _Pragma("unroll") for (int k = 0; k < 2; ++k) dst[m][k] = *(const PG8_LAS bf16x8*)(lds + PG8_SA(b, h) + aoff + m * 2048 + k * 1024); } while (0)
; #define PG8_LDB(dst, b, h) do { _Pragma("unroll") for (int n = 0; n < 2; ++n) _Pragma("unroll") for (int k = 0; k < 2; ++k) dst[n][k] = *(const PG8_LAS bf16x8*)(lds + PG8_SB(b, h) + boff + n * 2048 + k * 1024); } while (0)
; #define PG8_MMA(ai, bj, At, Bt) do { __builtin_amdgcn_s_setprio(1); _Pragma("unroll") for (int m = 0; m < 4; ++m) _Pragma("unroll") for (int n = 0; n < 2; ++n) _Pragma("unroll") for (int k = 0; k < 2; ++k) \
;         acc[ai][bj][m][n] = __builtin_amdgcn_mfma_f32_16x16x32_bf16(Bt[n][k], At[m][k], acc[ai][bj][m][n], 0, 0, 0); __builtin_amdgcn_s_setprio(0); } while (0)
; #define PG8_WAIT_V(n) asm volatile("s_waitcnt vmcnt(" #n ")" ::: "memory")
; #define PG8_WAIT_L(n) asm volatile("s_waitcnt lgkmcnt(" #n ")" ::: "memory")
; #define PG8_BAR __builtin_amdgcn_s_barrier()
; #define PG8_SCHED __builtin_amdgcn_sched_barrier(0)
; template <class Epi, class Sched, bool ALIGN_EPI = false, bool SP2 = false>
; __device__ __forceinline__ void gemm_phase(PG8_LAS unsigned char* lds, const Gemm g, const Sched& S, const Epi& E, const int wave_in) {
;     ...
;             PG8_LDA(At, 0, 1); PG8_STAGE(PG8_SB(0, 0), b2, voffB); PG8_STAGE(PG8_SB(0, 1), b2 + hstepB, voffB); PG8_STAGE(PG8_SA(0, 0), a2, voffA);
;             PG8_WAIT_V(8); PG8_WAIT_L(0); PG8_BAR; PG8_MMA(1, 0, At, B0); PG8_MMA(1, 1, At, B1); PG8_BAR; PG8_SCHED;
;             PG8_LDB(B0, 1, 0); PG8_LDB(B1, 1, 1); PG8_SCHED; PG8_LDA(At, 1, 0); PG8_STAGE(PG8_SA(0, 1), a2 + hstepA, voffA);
;             PG8_WAIT_V(8); PG8_WAIT_L(0); PG8_BAR; PG8_MMA(0, 0, At, B0); PG8_MMA(0, 1, At, B1); PG8_BAR; PG8_SCHED;
	s_add_i32 s18, s45, s30
	v_lshl_add_u64 v[210:211], s[22:23], 0, v[148:149]
	s_mov_b32 m0, s18
	ds_read_b128 v[178:181], v216 offset:16384
	ds_read_b128 v[182:185], v216 offset:17408
	ds_read_b128 v[186:189], v216 offset:18432
	ds_read_b128 v[190:193], v216 offset:19456
	ds_read_b128 v[194:197], v216 offset:20480
	ds_read_b128 v[198:201], v216 offset:21504
	ds_read_b128 v[202:205], v216 offset:22528
	ds_read_b128 v[206:209], v216 offset:23552
	global_load_lds_dwordx4 v[210:211], off
	s_add_i32 m0, s18, 0x2000
	s_add_u32 s18, s22, 0x158000
	v_lshl_add_u64 v[218:219], s[22:23], 0, v[144:145]
	s_addc_u32 s19, s23, 0
	s_add_i32 s55, s46, s30
	global_load_lds_dwordx4 v[218:219], off
	v_lshl_add_u64 v[220:221], s[18:19], 0, v[148:149]
	s_mov_b32 m0, s55
	v_lshl_add_u64 v[222:223], s[24:25], 0, v[146:147]
	global_load_lds_dwordx4 v[220:221], off
	v_lshl_add_u64 v[220:221], s[18:19], 0, v[144:145]
	s_add_i32 m0, s55, 0x2000
	s_nop 0
	global_load_lds_dwordx4 v[220:221], off
	v_lshl_add_u64 v[220:221], s[24:25], 0, v[150:151]
	s_mov_b32 m0, s35
	s_nop 0
	global_load_lds_dwordx4 v[220:221], off
	s_mov_b32 m0, s36
	s_nop 0
	global_load_lds_dwordx4 v[222:223], off
	s_waitcnt vmcnt(24)
	s_waitcnt lgkmcnt(0)
	s_barrier
	s_setprio 1
	s_waitcnt lgkmcnt(0)
	v_mfma_f32_16x16x32_bf16 v[60:63], v[128:131], v[178:181], v[60:63]
	v_mfma_f32_16x16x32_bf16 v[56:59], v[136:139], v[178:181], v[56:59]
	v_mfma_f32_16x16x32_bf16 v[48:51], v[128:131], v[186:189], v[48:51]
	v_mfma_f32_16x16x32_bf16 v[40:43], v[136:139], v[186:189], v[40:43]
	v_mfma_f32_16x16x32_bf16 v[32:35], v[128:131], v[194:197], v[32:35]
	v_mfma_f32_16x16x32_bf16 v[24:27], v[136:139], v[194:197], v[24:27]
	v_mfma_f32_16x16x32_bf16 v[16:19], v[128:131], v[202:205], v[16:19]
	v_mfma_f32_16x16x32_bf16 v[8:11], v[136:139], v[202:205], v[8:11]
	v_mfma_f32_16x16x32_bf16 v[60:63], v[132:135], v[182:185], v[60:63]
	v_mfma_f32_16x16x32_bf16 v[56:59], v[140:143], v[182:185], v[56:59]
	v_mfma_f32_16x16x32_bf16 v[48:51], v[132:135], v[190:193], v[48:51]
	v_mfma_f32_16x16x32_bf16 v[40:43], v[140:143], v[190:193], v[40:43]
	v_mfma_f32_16x16x32_bf16 v[32:35], v[132:135], v[198:201], v[32:35]
	v_mfma_f32_16x16x32_bf16 v[24:27], v[140:143], v[198:201], v[24:27]
	v_mfma_f32_16x16x32_bf16 v[16:19], v[132:135], v[206:209], v[16:19]
	v_mfma_f32_16x16x32_bf16 v[8:11], v[140:143], v[206:209], v[8:11]
	s_setprio 0
	s_setprio 1
	v_mfma_f32_16x16x32_bf16 v[52:55], v[162:165], v[178:181], v[52:55]
	v_mfma_f32_16x16x32_bf16 v[44:47], v[170:173], v[178:181], v[44:47]
	v_mfma_f32_16x16x32_bf16 v[36:39], v[162:165], v[186:189], v[36:39]
	v_mfma_f32_16x16x32_bf16 v[28:31], v[170:173], v[186:189], v[28:31]
	v_mfma_f32_16x16x32_bf16 v[20:23], v[162:165], v[194:197], v[20:23]
	v_mfma_f32_16x16x32_bf16 v[12:15], v[170:173], v[194:197], v[12:15]
	v_mfma_f32_16x16x32_bf16 v[4:7], v[162:165], v[202:205], v[4:7]
	v_mfma_f32_16x16x32_bf16 v[0:3], v[170:173], v[202:205], v[0:3]
	v_mfma_f32_16x16x32_bf16 v[52:55], v[166:169], v[182:185], v[52:55]
	v_mfma_f32_16x16x32_bf16 v[44:47], v[174:177], v[182:185], v[44:47]
	v_mfma_f32_16x16x32_bf16 v[36:39], v[166:169], v[190:193], v[36:39]
	v_mfma_f32_16x16x32_bf16 v[28:31], v[174:177], v[190:193], v[28:31]
	v_mfma_f32_16x16x32_bf16 v[20:23], v[166:169], v[198:201], v[20:23]
	v_mfma_f32_16x16x32_bf16 v[12:15], v[174:177], v[198:201], v[12:15]
	v_mfma_f32_16x16x32_bf16 v[4:7], v[166:169], v[206:209], v[4:7]
	v_mfma_f32_16x16x32_bf16 v[0:3], v[174:177], v[206:209], v[0:3]
	s_setprio 0
	s_barrier
	s_add_i32 s55, 0, 0x18000
	s_add_i32 s56, 0, 0x1c000
	v_add_u32_e32 v140, s55, v212
	v_add_u32_e32 v174, s56, v212
	ds_read_b128 v[128:131], v140
	ds_read_b128 v[132:135], v140 offset:1024
	ds_read_b128 v[136:139], v140 offset:2048
	ds_read_b128 v[140:143], v140 offset:3072
	ds_read_b128 v[162:165], v174
	ds_read_b128 v[166:169], v174 offset:1024
	ds_read_b128 v[170:173], v174 offset:2048
	ds_read_b128 v[174:177], v174 offset:3072
	s_add_u32 s18, s24, 0x158000
	s_addc_u32 s19, s25, 0
	s_mov_b32 m0, s37
	v_lshl_add_u64 v[224:225], s[18:19], 0, v[150:151]
	ds_read_b128 v[178:181], v216 offset:32768
	ds_read_b128 v[182:185], v216 offset:33792
	ds_read_b128 v[186:189], v216 offset:34816
	ds_read_b128 v[190:193], v216 offset:35840
	ds_read_b128 v[194:197], v216 offset:36864
	ds_read_b128 v[198:201], v216 offset:37888
	ds_read_b128 v[202:205], v216 offset:38912
	ds_read_b128 v[206:209], v216 offset:39936
	global_load_lds_dwordx4 v[224:225], off
	v_lshl_add_u64 v[224:225], s[18:19], 0, v[146:147]
	s_mov_b32 m0, s38
	s_nop 0
	global_load_lds_dwordx4 v[224:225], off
	s_waitcnt vmcnt(8)
	s_waitcnt lgkmcnt(0)
	s_barrier
; #define PG8_STAGE(bufoff, gbase, voff) do { _Pragma("unroll") for (int _i = 0; _i < 2; ++_i) \
;         __builtin_amdgcn_global_load_lds((const unsigned*)((const char*)(gbase) + (voff)[_i]), (PG8_LAS unsigned*)(lds + (bufoff) + ldsw + _i * 8192), 16, 0, 0); } while (0)
; #define PG8_LDA(dst, b, h) do { _Pragma("unroll") for (int m = 0; m < 4; ++m) _Pragma("unroll") for (int k = 0; k < 2; ++k) dst[m][k] = *(const PG8_LAS bf16x8*)(lds + PG8_SA(b, h) + aoff + m * 2048 + k * 1024); } while (0)
; #define PG8_MMA(ai, bj, At, Bt) do { __builtin_amdgcn_s_setprio(1); _Pragma("unroll") for (int m = 0; m < 4; ++m) _Pragma("unroll") for (int n = 0; n < 2; ++n) _Pragma("unroll") for (int k = 0; k < 2; ++k) \
;         acc[ai][bj][m][n] = __builtin_amdgcn_mfma_f32_16x16x32_bf16(Bt[n][k], At[m][k], acc[ai][bj][m][n], 0, 0, 0); __builtin_amdgcn_s_setprio(0); } while (0)
; #define PG8_WAIT_V(n) asm volatile("s_waitcnt vmcnt(" #n ")" ::: "memory")
; #define PG8_WAIT_L(n) asm volatile("s_waitcnt lgkmcnt(" #n ")" ::: "memory")
; #define PG8_BAR __builtin_amdgcn_s_barrier()
; #define PG8_SCHED __builtin_amdgcn_sched_barrier(0)
; template <class Epi, class Sched, bool ALIGN_EPI = false, bool SP2 = false>
; __device__ __forceinline__ void gemm_phase(PG8_LAS unsigned char* lds, const Gemm g, const Sched& S, const Epi& E, const int wave_in) {
;     ...
;         for (int t = 0; t < nt; t += 2) {
;     ...
;             PG8_WAIT_V(8); PG8_WAIT_L(0); PG8_BAR; PG8_MMA(0, 0, At, B0); PG8_MMA(0, 1, At, B1); PG8_BAR; PG8_SCHED;
;             PG8_LDA(At, 1, 1); PG8_STAGE(PG8_SB(1, 0), b3, voffB); PG8_STAGE(PG8_SB(1, 1), b3 + hstepB, voffB); PG8_STAGE(PG8_SA(1, 0), a3, voffA);
;             PG8_WAIT_V(8); PG8_WAIT_L(0); PG8_BAR; PG8_MMA(1, 0, At, B0); PG8_MMA(1, 1, At, B1); PG8_BAR; PG8_SCHED;
	s_setprio 1
	s_waitcnt lgkmcnt(0)
	v_mfma_f32_16x16x32_bf16 v[124:127], v[128:131], v[178:181], v[124:127]
	v_mfma_f32_16x16x32_bf16 v[120:123], v[136:139], v[178:181], v[120:123]
	v_mfma_f32_16x16x32_bf16 v[112:115], v[128:131], v[186:189], v[112:115]
	v_mfma_f32_16x16x32_bf16 v[104:107], v[136:139], v[186:189], v[104:107]
	v_mfma_f32_16x16x32_bf16 v[100:103], v[128:131], v[194:197], v[100:103]
	v_mfma_f32_16x16x32_bf16 v[96:99], v[136:139], v[194:197], v[96:99]
	v_mfma_f32_16x16x32_bf16 v[76:79], v[128:131], v[202:205], v[76:79]
	v_mfma_f32_16x16x32_bf16 v[72:75], v[136:139], v[202:205], v[72:75]
	v_mfma_f32_16x16x32_bf16 v[124:127], v[132:135], v[182:185], v[124:127]
	v_mfma_f32_16x16x32_bf16 v[120:123], v[140:143], v[182:185], v[120:123]
	v_mfma_f32_16x16x32_bf16 v[112:115], v[132:135], v[190:193], v[112:115]
	v_mfma_f32_16x16x32_bf16 v[104:107], v[140:143], v[190:193], v[104:107]
	v_mfma_f32_16x16x32_bf16 v[100:103], v[132:135], v[198:201], v[100:103]
	v_mfma_f32_16x16x32_bf16 v[96:99], v[140:143], v[198:201], v[96:99]
	v_mfma_f32_16x16x32_bf16 v[76:79], v[132:135], v[206:209], v[76:79]
	v_mfma_f32_16x16x32_bf16 v[72:75], v[140:143], v[206:209], v[72:75]
	s_setprio 0
	s_setprio 1
	v_mfma_f32_16x16x32_bf16 v[116:119], v[162:165], v[178:181], v[116:119]
	v_mfma_f32_16x16x32_bf16 v[108:111], v[170:173], v[178:181], v[108:111]
	v_mfma_f32_16x16x32_bf16 v[92:95], v[162:165], v[186:189], v[92:95]
	v_mfma_f32_16x16x32_bf16 v[88:91], v[170:173], v[186:189], v[88:91]
	v_mfma_f32_16x16x32_bf16 v[84:87], v[162:165], v[194:197], v[84:87]
	v_mfma_f32_16x16x32_bf16 v[80:83], v[170:173], v[194:197], v[80:83]
	v_mfma_f32_16x16x32_bf16 v[68:71], v[162:165], v[202:205], v[68:71]
	v_mfma_f32_16x16x32_bf16 v[64:67], v[170:173], v[202:205], v[64:67]
	v_mfma_f32_16x16x32_bf16 v[116:119], v[166:169], v[182:185], v[116:119]
	v_mfma_f32_16x16x32_bf16 v[108:111], v[174:177], v[182:185], v[108:111]
	v_mfma_f32_16x16x32_bf16 v[92:95], v[166:169], v[190:193], v[92:95]
	v_mfma_f32_16x16x32_bf16 v[88:91], v[174:177], v[190:193], v[88:91]
	v_mfma_f32_16x16x32_bf16 v[84:87], v[166:169], v[198:201], v[84:87]
	v_mfma_f32_16x16x32_bf16 v[80:83], v[174:177], v[198:201], v[80:83]
	v_mfma_f32_16x16x32_bf16 v[68:71], v[166:169], v[206:209], v[68:71]
	v_mfma_f32_16x16x32_bf16 v[64:67], v[174:177], v[206:209], v[64:67]
	s_setprio 0
	s_barrier
	s_add_i32 s18, s55, s30
	v_lshl_add_u64 v[210:211], v[210:211], 0, s[6:7]
	s_mov_b32 m0, s18
	ds_read_b128 v[178:181], v216 offset:49152
	ds_read_b128 v[182:185], v216 offset:50176
	ds_read_b128 v[186:189], v216 offset:51200
	ds_read_b128 v[190:193], v216 offset:52224
	ds_read_b128 v[194:197], v216 offset:53248
	ds_read_b128 v[198:201], v216 offset:54272
	ds_read_b128 v[202:205], v216 offset:55296
	ds_read_b128 v[206:209], v216 offset:56320
	global_load_lds_dwordx4 v[210:211], off
	s_add_i32 m0, s18, 0x2000
	s_add_u32 s18, s22, 0x158080
	v_lshl_add_u64 v[210:211], v[218:219], 0, s[6:7]
	s_addc_u32 s19, s23, 0
	s_add_i32 s22, s56, s30
	global_load_lds_dwordx4 v[210:211], off
	v_lshl_add_u64 v[210:211], s[18:19], 0, v[148:149]
	s_mov_b32 m0, s22
	s_nop 0
	global_load_lds_dwordx4 v[210:211], off
	v_lshl_add_u64 v[210:211], s[18:19], 0, v[144:145]
	s_add_i32 m0, s22, 0x2000
	s_nop 0
	global_load_lds_dwordx4 v[210:211], off
	v_lshl_add_u64 v[210:211], v[220:221], 0, s[6:7]
	s_mov_b32 m0, s42
	s_nop 0
	global_load_lds_dwordx4 v[210:211], off
	v_lshl_add_u64 v[210:211], v[222:223], 0, s[6:7]
	s_mov_b32 m0, s43
	s_nop 0
	global_load_lds_dwordx4 v[210:211], off
	s_waitcnt vmcnt(8)
	s_waitcnt lgkmcnt(0)
	s_barrier
	s_setprio 1
	s_waitcnt lgkmcnt(0)
	v_mfma_f32_16x16x32_bf16 v[60:63], v[128:131], v[178:181], v[60:63]
	v_mfma_f32_16x16x32_bf16 v[56:59], v[136:139], v[178:181], v[56:59]
	v_mfma_f32_16x16x32_bf16 v[48:51], v[128:131], v[186:189], v[48:51]
	v_mfma_f32_16x16x32_bf16 v[40:43], v[136:139], v[186:189], v[40:43]
	v_mfma_f32_16x16x32_bf16 v[32:35], v[128:131], v[194:197], v[32:35]
	v_mfma_f32_16x16x32_bf16 v[24:27], v[136:139], v[194:197], v[24:27]
	v_mfma_f32_16x16x32_bf16 v[16:19], v[128:131], v[202:205], v[16:19]
	v_mfma_f32_16x16x32_bf16 v[8:11], v[136:139], v[202:205], v[8:11]
	v_mfma_f32_16x16x32_bf16 v[60:63], v[132:135], v[182:185], v[60:63]
	v_mfma_f32_16x16x32_bf16 v[56:59], v[140:143], v[182:185], v[56:59]
	v_mfma_f32_16x16x32_bf16 v[48:51], v[132:135], v[190:193], v[48:51]
	v_mfma_f32_16x16x32_bf16 v[40:43], v[140:143], v[190:193], v[40:43]
	v_mfma_f32_16x16x32_bf16 v[32:35], v[132:135], v[198:201], v[32:35]
	v_mfma_f32_16x16x32_bf16 v[24:27], v[140:143], v[198:201], v[24:27]
	v_mfma_f32_16x16x32_bf16 v[16:19], v[132:135], v[206:209], v[16:19]
	v_mfma_f32_16x16x32_bf16 v[8:11], v[140:143], v[206:209], v[8:11]
	s_setprio 0
	s_setprio 1
	v_mfma_f32_16x16x32_bf16 v[52:55], v[162:165], v[178:181], v[52:55]
	v_mfma_f32_16x16x32_bf16 v[44:47], v[170:173], v[178:181], v[44:47]
	v_mfma_f32_16x16x32_bf16 v[36:39], v[162:165], v[186:189], v[36:39]
	v_mfma_f32_16x16x32_bf16 v[28:31], v[170:173], v[186:189], v[28:31]
	v_mfma_f32_16x16x32_bf16 v[20:23], v[162:165], v[194:197], v[20:23]
	v_mfma_f32_16x16x32_bf16 v[12:15], v[170:173], v[194:197], v[12:15]
	v_mfma_f32_16x16x32_bf16 v[4:7], v[162:165], v[202:205], v[4:7]
	v_mfma_f32_16x16x32_bf16 v[0:3], v[170:173], v[202:205], v[0:3]
	v_mfma_f32_16x16x32_bf16 v[52:55], v[166:169], v[182:185], v[52:55]
	v_mfma_f32_16x16x32_bf16 v[44:47], v[174:177], v[182:185], v[44:47]
	v_mfma_f32_16x16x32_bf16 v[36:39], v[166:169], v[190:193], v[36:39]
	v_mfma_f32_16x16x32_bf16 v[28:31], v[174:177], v[190:193], v[28:31]
	v_mfma_f32_16x16x32_bf16 v[20:23], v[166:169], v[198:201], v[20:23]
	v_mfma_f32_16x16x32_bf16 v[12:15], v[174:177], v[198:201], v[12:15]
	v_mfma_f32_16x16x32_bf16 v[4:7], v[166:169], v[206:209], v[4:7]
	v_mfma_f32_16x16x32_bf16 v[0:3], v[174:177], v[206:209], v[0:3]
	s_setprio 0
	s_barrier
	s_add_i32 s54, s54, 2
	s_add_u32 s17, s17, 0x100
	s_addc_u32 s53, s53, 0
	s_cmpk_gt_u32 s54, 0x53
	s_mov_b64 s[18:19], s[20:21]
	s_cbranch_scc0 .LBB0_1375
; #define PG8_STAGE(bufoff, gbase, voff) do { _Pragma("unroll") for (int _i = 0; _i < 2; ++_i) \
;         __builtin_amdgcn_global_load_lds((const unsigned*)((const char*)(gbase) + (voff)[_i]), (PG8_LAS unsigned*)(lds + (bufoff) + ldsw + _i * 8192), 16, 0, 0); } while (0)
; #define PG8_LDA(dst, b, h) do { _Pragma("unroll") for (int m = 0; m < 4; ++m) _Pragma("unroll") for (int k = 0; k < 2; ++k) dst[m][k] = *(const PG8_LAS bf16x8*)(lds + PG8_SA(b, h) + aoff + m * 2048 + k * 1024); } while (0)
; #define PG8_LDB(dst, b, h) do { _Pragma("unroll") for (int n = 0; n < 2; ++n) _Pragma("unroll") for (int k = 0; k < 2; ++k) dst[n][k] = *(const PG8_LAS bf16x8*)(lds + PG8_SB(b, h) + boff + n * 2048 + k * 1024); } while (0)
; #define PG8_MMA(ai, bj, At, Bt) do { __builtin_amdgcn_s_setprio(1); _Pragma("unroll") for (int m = 0; m < 4; ++m) _Pragma("unroll") for (int n = 0; n < 2; ++n) _Pragma("unroll") for (int k = 0; k < 2; ++k) \
;         acc[ai][bj][m][n] = __builtin_amdgcn_mfma_f32_16x16x32_bf16(Bt[n][k], At[m][k], acc[ai][bj][m][n], 0, 0, 0); __builtin_amdgcn_s_setprio(0); } while (0)
; #define PG8_WAIT_V(n) asm volatile("s_waitcnt vmcnt(" #n ")" ::: "memory")
; #define PG8_BAR __builtin_amdgcn_s_barrier()
; template <class Epi, class Sched, bool ALIGN_EPI = false, bool SP2 = false>
; __device__ __forceinline__ void gemm_phase(PG8_LAS unsigned char* lds, const Gemm g, const Sched& S, const Epi& E, const int wave_in) {
;     ...
;         for (int t = 0; t < nt; t += 2) {
;             const bool last = (t == nt - 2);
;             const char* a1 = cA + (size_t)(t + 1) * kstep;
;             const char* a2 = last ? nA : cA + (size_t)(t + 2) * kstep; const char* b2 = last ? nB : cB + (size_t)(t + 2) * kstep;
;             const char* a3 = a2 + kstep; const char* b3 = b2 + kstep;
;             if (last && has_next) S.a_ready(nxt);
;             if constexpr (SP2) {
;             PG8_LDB(B0, 0, 0); PG8_LDB(B1, 0, 1); PG8_SCHED; PG8_LDA(At, 0, 0); PG8_STAGE(PG8_SA(1, 1), a1 + hstepA, voffA);
;             PG8_WAIT_V(8); PG8_WAIT_L(0); PG8_BAR; PG8_MMA(0, 0, At, B0); PG8_MMA(0, 1, At, B1); PG8_BAR; PG8_SCHED;
;             PG8_LDA(At, 0, 1); PG8_STAGE(PG8_SB(0, 0), b2, voffB); PG8_STAGE(PG8_SB(0, 1), b2 + hstepB, voffB); PG8_STAGE(PG8_SA(0, 0), a2, voffA);
;             PG8_WAIT_V(8); PG8_WAIT_L(0); PG8_BAR; PG8_MMA(1, 0, At, B0); PG8_MMA(1, 1, At, B1); PG8_BAR; PG8_SCHED;
.LBB0_1375:
	ds_read_b128 v[128:131], v214
	ds_read_b128 v[132:135], v214 offset:1024
	ds_read_b128 v[136:139], v214 offset:2048
	ds_read_b128 v[140:143], v214 offset:3072
	ds_read_b128 v[162:165], v215
	ds_read_b128 v[166:169], v215 offset:1024
	ds_read_b128 v[170:173], v215 offset:2048
	ds_read_b128 v[174:177], v215 offset:3072
	s_add_u32 s20, s18, 0x100
	s_addc_u32 s21, s19, 0
	s_cmpk_eq_i32 s54, 0x52
	s_cselect_b32 s25, s5, s21
	s_cselect_b32 s24, s4, s20
	s_cselect_b32 s23, s15, s53
	s_cselect_b32 s22, s14, s17
	v_lshl_add_u64 v[210:211], s[18:19], 0, v[154:155]
	s_add_i32 m0, s35, 0xc000
	ds_read_b128 v[178:181], v216
	ds_read_b128 v[182:185], v216 offset:1024
	ds_read_b128 v[186:189], v216 offset:2048
	ds_read_b128 v[190:193], v216 offset:3072
	ds_read_b128 v[194:197], v216 offset:4096
	ds_read_b128 v[198:201], v216 offset:5120
	ds_read_b128 v[202:205], v216 offset:6144
	ds_read_b128 v[206:209], v216 offset:7168
	global_load_lds_dwordx4 v[210:211], off
	v_lshl_add_u64 v[210:211], s[18:19], 0, v[156:157]
	s_add_i32 m0, s35, 0xe000
	s_nop 0
	global_load_lds_dwordx4 v[210:211], off
	s_waitcnt vmcnt(8)
	s_waitcnt lgkmcnt(0)
	s_barrier
	s_setprio 1
	s_waitcnt lgkmcnt(0)
	v_mfma_f32_16x16x32_bf16 v[124:127], v[128:131], v[178:181], v[124:127]
	v_mfma_f32_16x16x32_bf16 v[120:123], v[136:139], v[178:181], v[120:123]
	v_mfma_f32_16x16x32_bf16 v[112:115], v[128:131], v[186:189], v[112:115]
	v_mfma_f32_16x16x32_bf16 v[104:107], v[136:139], v[186:189], v[104:107]
	v_mfma_f32_16x16x32_bf16 v[100:103], v[128:131], v[194:197], v[100:103]
	v_mfma_f32_16x16x32_bf16 v[96:99], v[136:139], v[194:197], v[96:99]
	v_mfma_f32_16x16x32_bf16 v[76:79], v[128:131], v[202:205], v[76:79]
	v_mfma_f32_16x16x32_bf16 v[72:75], v[136:139], v[202:205], v[72:75]
	v_mfma_f32_16x16x32_bf16 v[124:127], v[132:135], v[182:185], v[124:127]
	v_mfma_f32_16x16x32_bf16 v[120:123], v[140:143], v[182:185], v[120:123]
	v_mfma_f32_16x16x32_bf16 v[112:115], v[132:135], v[190:193], v[112:115]
	v_mfma_f32_16x16x32_bf16 v[104:107], v[140:143], v[190:193], v[104:107]
	v_mfma_f32_16x16x32_bf16 v[100:103], v[132:135], v[198:201], v[100:103]
	v_mfma_f32_16x16x32_bf16 v[96:99], v[140:143], v[198:201], v[96:99]
	v_mfma_f32_16x16x32_bf16 v[76:79], v[132:135], v[206:209], v[76:79]
	v_mfma_f32_16x16x32_bf16 v[72:75], v[140:143], v[206:209], v[72:75]
	s_setprio 0
	s_setprio 1
	v_mfma_f32_16x16x32_bf16 v[116:119], v[162:165], v[178:181], v[116:119]
	v_mfma_f32_16x16x32_bf16 v[108:111], v[170:173], v[178:181], v[108:111]
	v_mfma_f32_16x16x32_bf16 v[92:95], v[162:165], v[186:189], v[92:95]
	v_mfma_f32_16x16x32_bf16 v[88:91], v[170:173], v[186:189], v[88:91]
	v_mfma_f32_16x16x32_bf16 v[84:87], v[162:165], v[194:197], v[84:87]
	v_mfma_f32_16x16x32_bf16 v[80:83], v[170:173], v[194:197], v[80:83]
	v_mfma_f32_16x16x32_bf16 v[68:71], v[162:165], v[202:205], v[68:71]
	v_mfma_f32_16x16x32_bf16 v[64:67], v[170:173], v[202:205], v[64:67]
	v_mfma_f32_16x16x32_bf16 v[116:119], v[166:169], v[182:185], v[116:119]
	v_mfma_f32_16x16x32_bf16 v[108:111], v[174:177], v[182:185], v[108:111]
	v_mfma_f32_16x16x32_bf16 v[92:95], v[166:169], v[190:193], v[92:95]
	v_mfma_f32_16x16x32_bf16 v[88:91], v[174:177], v[190:193], v[88:91]
	v_mfma_f32_16x16x32_bf16 v[84:87], v[166:169], v[198:201], v[84:87]
	v_mfma_f32_16x16x32_bf16 v[80:83], v[174:177], v[198:201], v[80:83]
	v_mfma_f32_16x16x32_bf16 v[68:71], v[166:169], v[206:209], v[68:71]
	v_mfma_f32_16x16x32_bf16 v[64:67], v[174:177], v[206:209], v[64:67]
	s_setprio 0
	s_barrier
	s_add_i32 s18, s45, s30
	v_lshl_add_u64 v[210:211], s[22:23], 0, v[148:149]
	s_mov_b32 m0, s18
	ds_read_b128 v[178:181], v216 offset:16384
	ds_read_b128 v[182:185], v216 offset:17408
	ds_read_b128 v[186:189], v216 offset:18432
	ds_read_b128 v[190:193], v216 offset:19456
	ds_read_b128 v[194:197], v216 offset:20480
	ds_read_b128 v[198:201], v216 offset:21504
	ds_read_b128 v[202:205], v216 offset:22528
	ds_read_b128 v[206:209], v216 offset:23552
	global_load_lds_dwordx4 v[210:211], off
	s_add_i32 m0, s18, 0x2000
	s_add_u32 s18, s22, 0x158000
	v_lshl_add_u64 v[218:219], s[22:23], 0, v[144:145]
	s_addc_u32 s19, s23, 0
	s_add_i32 s55, s46, s30
	global_load_lds_dwordx4 v[218:219], off
	v_lshl_add_u64 v[220:221], s[18:19], 0, v[148:149]
	s_mov_b32 m0, s55
	v_lshl_add_u64 v[222:223], s[24:25], 0, v[146:147]
	global_load_lds_dwordx4 v[220:221], off
	v_lshl_add_u64 v[220:221], s[18:19], 0, v[144:145]
	s_add_i32 m0, s55, 0x2000
	s_nop 0
	global_load_lds_dwordx4 v[220:221], off
	v_lshl_add_u64 v[220:221], s[24:25], 0, v[150:151]
	s_mov_b32 m0, s35
	s_nop 0
	global_load_lds_dwordx4 v[220:221], off
	s_mov_b32 m0, s36
	s_nop 0
	global_load_lds_dwordx4 v[222:223], off
	s_waitcnt vmcnt(8)
	s_waitcnt lgkmcnt(0)
	s_barrier
; #define PG8_STAGE(bufoff, gbase, voff) do { _Pragma("unroll") for (int _i = 0; _i < 2; ++_i) \
;         __builtin_amdgcn_global_load_lds((const unsigned*)((const char*)(gbase) + (voff)[_i]), (PG8_LAS unsigned*)(lds + (bufoff) + ldsw + _i * 8192), 16, 0, 0); } while (0)
; #define PG8_LDA(dst, b, h) do { _Pragma("unroll") for (int m = 0; m < 4; ++m) _Pragma("unroll") for (int k = 0; k < 2; ++k) dst[m][k] = *(const PG8_LAS bf16x8*)(lds + PG8_SA(b, h) + aoff + m * 2048 + k * 1024); } while (0)
; #define PG8_LDB(dst, b, h) do { _Pragma("unroll") for (int n = 0; n < 2; ++n) _Pragma("unroll") for (int k = 0; k < 2; ++k) dst[n][k] = *(const PG8_LAS bf16x8*)(lds + PG8_SB(b, h) + boff + n * 2048 + k * 1024); } while (0)
; #define PG8_MMA(ai, bj, At, Bt) do { __builtin_amdgcn_s_setprio(1); _Pragma("unroll") for (int m = 0; m < 4; ++m) _Pragma("unroll") for (int n = 0; n < 2; ++n) _Pragma("unroll") for (int k = 0; k < 2; ++k) \
;         acc[ai][bj][m][n] = __builtin_amdgcn_mfma_f32_16x16x32_bf16(Bt[n][k], At[m][k], acc[ai][bj][m][n], 0, 0, 0); __builtin_amdgcn_s_setprio(0); } while (0)
; #define PG8_WAIT_V(n) asm volatile("s_waitcnt vmcnt(" #n ")" ::: "memory")
; #define PG8_WAIT_L(n) asm volatile("s_waitcnt lgkmcnt(" #n ")" ::: "memory")
; #define PG8_BAR __builtin_amdgcn_s_barrier()
; #define PG8_SCHED __builtin_amdgcn_sched_barrier(0)
; template <class Epi, class Sched, bool ALIGN_EPI = false, bool SP2 = false>
; __device__ __forceinline__ void gemm_phase(PG8_LAS unsigned char* lds, const Gemm g, const Sched& S, const Epi& E, const int wave_in) {
;     ...
;             PG8_WAIT_V(8); PG8_WAIT_L(0); PG8_BAR; PG8_MMA(1, 0, At, B0); PG8_MMA(1, 1, At, B1); PG8_BAR; PG8_SCHED;
;             PG8_LDB(B0, 1, 0); PG8_LDB(B1, 1, 1); PG8_SCHED; PG8_LDA(At, 1, 0); PG8_STAGE(PG8_SA(0, 1), a2 + hstepA, voffA);
;             PG8_WAIT_V(8); PG8_WAIT_L(0); PG8_BAR; PG8_MMA(0, 0, At, B0); PG8_MMA(0, 1, At, B1); PG8_BAR; PG8_SCHED;
;             PG8_LDA(At, 1, 1); PG8_STAGE(PG8_SB(1, 0), b3, voffB); PG8_STAGE(PG8_SB(1, 1), b3 + hstepB, voffB); PG8_STAGE(PG8_SA(1, 0), a3, voffA);
	s_setprio 1
	s_waitcnt lgkmcnt(0)
	v_mfma_f32_16x16x32_bf16 v[60:63], v[128:131], v[178:181], v[60:63]
	v_mfma_f32_16x16x32_bf16 v[56:59], v[136:139], v[178:181], v[56:59]
	v_mfma_f32_16x16x32_bf16 v[48:51], v[128:131], v[186:189], v[48:51]
	v_mfma_f32_16x16x32_bf16 v[40:43], v[136:139], v[186:189], v[40:43]
	v_mfma_f32_16x16x32_bf16 v[32:35], v[128:131], v[194:197], v[32:35]
	v_mfma_f32_16x16x32_bf16 v[24:27], v[136:139], v[194:197], v[24:27]
	v_mfma_f32_16x16x32_bf16 v[16:19], v[128:131], v[202:205], v[16:19]
	v_mfma_f32_16x16x32_bf16 v[8:11], v[136:139], v[202:205], v[8:11]
	v_mfma_f32_16x16x32_bf16 v[60:63], v[132:135], v[182:185], v[60:63]
	v_mfma_f32_16x16x32_bf16 v[56:59], v[140:143], v[182:185], v[56:59]
	v_mfma_f32_16x16x32_bf16 v[48:51], v[132:135], v[190:193], v[48:51]
	v_mfma_f32_16x16x32_bf16 v[40:43], v[140:143], v[190:193], v[40:43]
	v_mfma_f32_16x16x32_bf16 v[32:35], v[132:135], v[198:201], v[32:35]
	v_mfma_f32_16x16x32_bf16 v[24:27], v[140:143], v[198:201], v[24:27]
	v_mfma_f32_16x16x32_bf16 v[16:19], v[132:135], v[206:209], v[16:19]
	v_mfma_f32_16x16x32_bf16 v[8:11], v[140:143], v[206:209], v[8:11]
	s_setprio 0
	s_setprio 1
	v_mfma_f32_16x16x32_bf16 v[52:55], v[162:165], v[178:181], v[52:55]
	v_mfma_f32_16x16x32_bf16 v[44:47], v[170:173], v[178:181], v[44:47]
	v_mfma_f32_16x16x32_bf16 v[36:39], v[162:165], v[186:189], v[36:39]
	v_mfma_f32_16x16x32_bf16 v[28:31], v[170:173], v[186:189], v[28:31]
	v_mfma_f32_16x16x32_bf16 v[20:23], v[162:165], v[194:197], v[20:23]
	v_mfma_f32_16x16x32_bf16 v[12:15], v[170:173], v[194:197], v[12:15]
	v_mfma_f32_16x16x32_bf16 v[4:7], v[162:165], v[202:205], v[4:7]
	v_mfma_f32_16x16x32_bf16 v[0:3], v[170:173], v[202:205], v[0:3]
	v_mfma_f32_16x16x32_bf16 v[52:55], v[166:169], v[182:185], v[52:55]
	v_mfma_f32_16x16x32_bf16 v[44:47], v[174:177], v[182:185], v[44:47]
	v_mfma_f32_16x16x32_bf16 v[36:39], v[166:169], v[190:193], v[36:39]
	v_mfma_f32_16x16x32_bf16 v[28:31], v[174:177], v[190:193], v[28:31]
	v_mfma_f32_16x16x32_bf16 v[20:23], v[166:169], v[198:201], v[20:23]
	v_mfma_f32_16x16x32_bf16 v[12:15], v[174:177], v[198:201], v[12:15]
	v_mfma_f32_16x16x32_bf16 v[4:7], v[166:169], v[206:209], v[4:7]
	v_mfma_f32_16x16x32_bf16 v[0:3], v[174:177], v[206:209], v[0:3]
	s_setprio 0
	s_barrier
	s_add_i32 s55, 0, 0x18000
	s_add_i32 s56, 0, 0x1c000
	v_add_u32_e32 v140, s55, v212
	v_add_u32_e32 v174, s56, v212
	ds_read_b128 v[128:131], v140
	ds_read_b128 v[132:135], v140 offset:1024
	ds_read_b128 v[136:139], v140 offset:2048
	ds_read_b128 v[140:143], v140 offset:3072
	ds_read_b128 v[162:165], v174
	ds_read_b128 v[166:169], v174 offset:1024
	ds_read_b128 v[170:173], v174 offset:2048
	ds_read_b128 v[174:177], v174 offset:3072
	s_add_u32 s18, s24, 0x158000
	s_addc_u32 s19, s25, 0
	s_mov_b32 m0, s37
	v_lshl_add_u64 v[224:225], s[18:19], 0, v[150:151]
	ds_read_b128 v[178:181], v216 offset:32768
	ds_read_b128 v[182:185], v216 offset:33792
	ds_read_b128 v[186:189], v216 offset:34816
	ds_read_b128 v[190:193], v216 offset:35840
	ds_read_b128 v[194:197], v216 offset:36864
	ds_read_b128 v[198:201], v216 offset:37888
	ds_read_b128 v[202:205], v216 offset:38912
	ds_read_b128 v[206:209], v216 offset:39936
	global_load_lds_dwordx4 v[224:225], off
	v_lshl_add_u64 v[224:225], s[18:19], 0, v[146:147]
	s_mov_b32 m0, s38
	s_nop 0
	global_load_lds_dwordx4 v[224:225], off
	s_waitcnt vmcnt(8)
	s_waitcnt lgkmcnt(0)
	s_barrier
	s_setprio 1
	s_waitcnt lgkmcnt(0)
	v_mfma_f32_16x16x32_bf16 v[124:127], v[128:131], v[178:181], v[124:127]
	v_mfma_f32_16x16x32_bf16 v[120:123], v[136:139], v[178:181], v[120:123]
	v_mfma_f32_16x16x32_bf16 v[112:115], v[128:131], v[186:189], v[112:115]
	v_mfma_f32_16x16x32_bf16 v[104:107], v[136:139], v[186:189], v[104:107]
	v_mfma_f32_16x16x32_bf16 v[100:103], v[128:131], v[194:197], v[100:103]
	v_mfma_f32_16x16x32_bf16 v[96:99], v[136:139], v[194:197], v[96:99]
	v_mfma_f32_16x16x32_bf16 v[76:79], v[128:131], v[202:205], v[76:79]
	v_mfma_f32_16x16x32_bf16 v[72:75], v[136:139], v[202:205], v[72:75]
	v_mfma_f32_16x16x32_bf16 v[124:127], v[132:135], v[182:185], v[124:127]
	v_mfma_f32_16x16x32_bf16 v[120:123], v[140:143], v[182:185], v[120:123]
	v_mfma_f32_16x16x32_bf16 v[112:115], v[132:135], v[190:193], v[112:115]
	v_mfma_f32_16x16x32_bf16 v[104:107], v[140:143], v[190:193], v[104:107]
	v_mfma_f32_16x16x32_bf16 v[100:103], v[132:135], v[198:201], v[100:103]
	v_mfma_f32_16x16x32_bf16 v[96:99], v[140:143], v[198:201], v[96:99]
	v_mfma_f32_16x16x32_bf16 v[76:79], v[132:135], v[206:209], v[76:79]
	v_mfma_f32_16x16x32_bf16 v[72:75], v[140:143], v[206:209], v[72:75]
	s_setprio 0
	s_setprio 1
	v_mfma_f32_16x16x32_bf16 v[116:119], v[162:165], v[178:181], v[116:119]
	v_mfma_f32_16x16x32_bf16 v[108:111], v[170:173], v[178:181], v[108:111]
	v_mfma_f32_16x16x32_bf16 v[92:95], v[162:165], v[186:189], v[92:95]
	v_mfma_f32_16x16x32_bf16 v[88:91], v[170:173], v[186:189], v[88:91]
	v_mfma_f32_16x16x32_bf16 v[84:87], v[162:165], v[194:197], v[84:87]
	v_mfma_f32_16x16x32_bf16 v[80:83], v[170:173], v[194:197], v[80:83]
	v_mfma_f32_16x16x32_bf16 v[68:71], v[162:165], v[202:205], v[68:71]
	v_mfma_f32_16x16x32_bf16 v[64:67], v[170:173], v[202:205], v[64:67]
	v_mfma_f32_16x16x32_bf16 v[116:119], v[166:169], v[182:185], v[116:119]
	v_mfma_f32_16x16x32_bf16 v[108:111], v[174:177], v[182:185], v[108:111]
	v_mfma_f32_16x16x32_bf16 v[92:95], v[166:169], v[190:193], v[92:95]
	v_mfma_f32_16x16x32_bf16 v[88:91], v[174:177], v[190:193], v[88:91]
	v_mfma_f32_16x16x32_bf16 v[84:87], v[166:169], v[198:201], v[84:87]
	v_mfma_f32_16x16x32_bf16 v[80:83], v[174:177], v[198:201], v[80:83]
	v_mfma_f32_16x16x32_bf16 v[68:71], v[166:169], v[206:209], v[68:71]
	v_mfma_f32_16x16x32_bf16 v[64:67], v[174:177], v[206:209], v[64:67]
	s_setprio 0
	s_barrier
; #define PG8_STAGE(bufoff, gbase, voff) do { _Pragma("unroll") for (int _i = 0; _i < 2; ++_i) \
;         __builtin_amdgcn_global_load_lds((const unsigned*)((const char*)(gbase) + (voff)[_i]), (PG8_LAS unsigned*)(lds + (bufoff) + ldsw + _i * 8192), 16, 0, 0); } while (0)
; #define PG8_LDA(dst, b, h) do { _Pragma("unroll") for (int m = 0; m < 4; ++m) _Pragma("unroll") for (int k = 0; k < 2; ++k) dst[m][k] = *(const PG8_LAS bf16x8*)(lds + PG8_SA(b, h) + aoff + m * 2048 + k * 1024); } while (0)
; #define PG8_MMA(ai, bj, At, Bt) do { __builtin_amdgcn_s_setprio(1); _Pragma("unroll") for (int m = 0; m < 4; ++m) _Pragma("unroll") for (int n = 0; n < 2; ++n) _Pragma("unroll") for (int k = 0; k < 2; ++k) \
;         acc[ai][bj][m][n] = __builtin_amdgcn_mfma_f32_16x16x32_bf16(Bt[n][k], At[m][k], acc[ai][bj][m][n], 0, 0, 0); __builtin_amdgcn_s_setprio(0); } while (0)
; #define PG8_WAIT_V(n) asm volatile("s_waitcnt vmcnt(" #n ")" ::: "memory")
; #define PG8_WAIT_L(n) asm volatile("s_waitcnt lgkmcnt(" #n ")" ::: "memory")
; #define PG8_BAR __builtin_amdgcn_s_barrier()
; #define PG8_SCHED __builtin_amdgcn_sched_barrier(0)
; template <class Epi, class Sched, bool ALIGN_EPI = false, bool SP2 = false>
; __device__ __forceinline__ void gemm_phase(PG8_LAS unsigned char* lds, const Gemm g, const Sched& S, const Epi& E, const int wave_in) {
;     ...
;             PG8_LDA(At, 1, 1); PG8_STAGE(PG8_SB(1, 0), b3, voffB); PG8_STAGE(PG8_SB(1, 1), b3 + hstepB, voffB); PG8_STAGE(PG8_SA(1, 0), a3, voffA);
;             PG8_WAIT_V(8); PG8_WAIT_L(0); PG8_BAR; PG8_MMA(1, 0, At, B0); PG8_MMA(1, 1, At, B1); PG8_BAR; PG8_SCHED;
;     ...
;         if constexpr (ALIGN_EPI) { if (wr == 0) PG8_BAR; }
	s_add_i32 s18, s55, s30
	v_lshl_add_u64 v[210:211], v[210:211], 0, s[6:7]
	s_mov_b32 m0, s18
	ds_read_b128 v[178:181], v216 offset:49152
	ds_read_b128 v[182:185], v216 offset:50176
	ds_read_b128 v[186:189], v216 offset:51200
	ds_read_b128 v[190:193], v216 offset:52224
	ds_read_b128 v[194:197], v216 offset:53248
	ds_read_b128 v[198:201], v216 offset:54272
	ds_read_b128 v[202:205], v216 offset:55296
	ds_read_b128 v[206:209], v216 offset:56320
	global_load_lds_dwordx4 v[210:211], off
	s_add_i32 m0, s18, 0x2000
	s_add_u32 s18, s22, 0x158080
	v_lshl_add_u64 v[210:211], v[218:219], 0, s[6:7]
	s_addc_u32 s19, s23, 0
	s_add_i32 s22, s56, s30
	global_load_lds_dwordx4 v[210:211], off
	v_lshl_add_u64 v[210:211], s[18:19], 0, v[148:149]
	s_mov_b32 m0, s22
	s_nop 0
	global_load_lds_dwordx4 v[210:211], off
	v_lshl_add_u64 v[210:211], s[18:19], 0, v[144:145]
	s_add_i32 m0, s22, 0x2000
	s_nop 0
	global_load_lds_dwordx4 v[210:211], off
	v_lshl_add_u64 v[210:211], v[220:221], 0, s[6:7]
	s_mov_b32 m0, s42
	s_nop 0
	global_load_lds_dwordx4 v[210:211], off
	v_lshl_add_u64 v[210:211], v[222:223], 0, s[6:7]
	s_mov_b32 m0, s43
	s_nop 0
	global_load_lds_dwordx4 v[210:211], off
	s_waitcnt vmcnt(8)
	s_waitcnt lgkmcnt(0)
	s_barrier
	s_setprio 1
	s_waitcnt lgkmcnt(0)
	v_mfma_f32_16x16x32_bf16 v[60:63], v[128:131], v[178:181], v[60:63]
	v_mfma_f32_16x16x32_bf16 v[56:59], v[136:139], v[178:181], v[56:59]
	v_mfma_f32_16x16x32_bf16 v[48:51], v[128:131], v[186:189], v[48:51]
	v_mfma_f32_16x16x32_bf16 v[40:43], v[136:139], v[186:189], v[40:43]
	v_mfma_f32_16x16x32_bf16 v[32:35], v[128:131], v[194:197], v[32:35]
	v_mfma_f32_16x16x32_bf16 v[24:27], v[136:139], v[194:197], v[24:27]
	v_mfma_f32_16x16x32_bf16 v[16:19], v[128:131], v[202:205], v[16:19]
	v_mfma_f32_16x16x32_bf16 v[8:11], v[136:139], v[202:205], v[8:11]
	v_mfma_f32_16x16x32_bf16 v[60:63], v[132:135], v[182:185], v[60:63]
	v_mfma_f32_16x16x32_bf16 v[56:59], v[140:143], v[182:185], v[56:59]
	v_mfma_f32_16x16x32_bf16 v[48:51], v[132:135], v[190:193], v[48:51]
	v_mfma_f32_16x16x32_bf16 v[40:43], v[140:143], v[190:193], v[40:43]
	v_mfma_f32_16x16x32_bf16 v[32:35], v[132:135], v[198:201], v[32:35]
	v_mfma_f32_16x16x32_bf16 v[24:27], v[140:143], v[198:201], v[24:27]
	v_mfma_f32_16x16x32_bf16 v[16:19], v[132:135], v[206:209], v[16:19]
	v_mfma_f32_16x16x32_bf16 v[8:11], v[140:143], v[206:209], v[8:11]
	s_setprio 0
	s_setprio 1
	v_mfma_f32_16x16x32_bf16 v[52:55], v[162:165], v[178:181], v[52:55]
	v_mfma_f32_16x16x32_bf16 v[44:47], v[170:173], v[178:181], v[44:47]
	v_mfma_f32_16x16x32_bf16 v[36:39], v[162:165], v[186:189], v[36:39]
	v_mfma_f32_16x16x32_bf16 v[28:31], v[170:173], v[186:189], v[28:31]
	v_mfma_f32_16x16x32_bf16 v[20:23], v[162:165], v[194:197], v[20:23]
	v_mfma_f32_16x16x32_bf16 v[12:15], v[170:173], v[194:197], v[12:15]
	v_mfma_f32_16x16x32_bf16 v[4:7], v[162:165], v[202:205], v[4:7]
	v_mfma_f32_16x16x32_bf16 v[0:3], v[170:173], v[202:205], v[0:3]
	v_mfma_f32_16x16x32_bf16 v[52:55], v[166:169], v[182:185], v[52:55]
	v_mfma_f32_16x16x32_bf16 v[44:47], v[174:177], v[182:185], v[44:47]
	v_mfma_f32_16x16x32_bf16 v[36:39], v[166:169], v[190:193], v[36:39]
	v_mfma_f32_16x16x32_bf16 v[28:31], v[174:177], v[190:193], v[28:31]
	v_mfma_f32_16x16x32_bf16 v[20:23], v[166:169], v[198:201], v[20:23]
	v_mfma_f32_16x16x32_bf16 v[12:15], v[174:177], v[198:201], v[12:15]
	v_mfma_f32_16x16x32_bf16 v[4:7], v[166:169], v[206:209], v[4:7]
	v_mfma_f32_16x16x32_bf16 v[0:3], v[174:177], v[206:209], v[0:3]
	s_setprio 0
	s_barrier
	s_add_i32 s54, s54, 2
	s_add_u32 s17, s17, 0x100
	s_addc_u32 s53, s53, 0
	s_cmpk_gt_u32 s54, 0x53
	s_mov_b64 s[18:19], s[20:21]
	s_cbranch_scc0 .LBB0_1375
	s_mov_b32 s99, 1
	s_and_b64 vcc, exec, s[8:9]
	s_cbranch_vccz .LBB0_1378
	s_barrier

;     __host__ __device__ bool next(int i, Unit& u) const {
;         const long L = (long)i * G + c; if (L >= nwg) return false;
;         int wgid = (int)L; { const int q = nwg / NXCD, r = nwg % NXCD, xcd = wgid % NXCD, off = wgid / NXCD; wgid = (xcd < r ? xcd * (q + 1) : r * (q + 1) + (xcd - r) * q) + off; }
;         const int nig = WGM * nN, gid = wgid / nig, fm = gid * WGM, gsz = (nM - fm) < WGM ? (nM - fm) : WGM;
;         u.pm = fm + ((wgid % nig) % gsz); u.pn = (wgid % nig) / gsz; return true;
; template <class Epi, class Sched, bool ALIGN_EPI = false, bool SP2 = false>
; __device__ __forceinline__ void gemm_phase(PG8_LAS unsigned char* lds, const Gemm g, const Sched& S, const Epi& E, const int wave_in) {
;     const int lane = lane_id_asm(), wid = __builtin_amdgcn_readfirstlane(wave_in), tid = wid * 64 + lane, wr = wid >> 2, wc = wid & 3, fr = lane & 15, fq = lane >> 4;
;     const int K = g.K, nt = K / BK;
;     unsigned voffA[2], voffB[2];
; #pragma unroll
;     for (int i = 0; i < 2; ++i) { int R, C; stage_rc(tid * 16 + i * 8192, R, C); const int Rb = Epi::PERM ? ((R & ~31) + perm32(R & 31)) : R;
;         voffA[i] = (unsigned)(R * g.lda + C) * 2u; voffB[i] = (unsigned)(Rb * K + C) * 2u; }
;     const size_t kstep = (size_t)(BK * 2);
;     const size_t hstepA = (size_t)HALF * g.lda * 2, hstepB = (size_t)HALF * K * 2;
;     const size_t tstepA = 2 * hstepA, tstepB = 2 * hstepB;
;     const unsigned ldsw = (unsigned)wid * 1024u;
;     const int aoff = lds_byte(wr * 64 + fr, fq * 8), boff = lds_byte(wc * 32 + fr, fq * 8);
;     ...
;     Unit cur, nxt; int ui = 0;
;     if (!S.next(0, cur)) return;
;     f32x4 acc[2][2][4][2];
; #pragma unroll
;     for (int a = 0; a < 2; ++a)
; #pragma unroll
;         for (int b = 0; b < 2; ++b)
; #pragma unroll
;             for (int m = 0; m < 4; ++m)
; #pragma unroll
;                 for (int n = 0; n < 2; ++n) acc[a][b][m][n] = (f32x4){0.f, 0.f, 0.f, 0.f};
;     bf16x8 At[4][2], B0[2][2], B1[2][2];
;     const char* cA = (const char*)g.A + (size_t)cur.pm * tstepA; const char* cB = (const char*)g.Bt + (size_t)cur.pn * tstepB;
;     S.a_ready(cur);
;     if constexpr (SP2) {
;         PG8_STAGE(PG8_SB(0, 0), cB, voffB); PG8_STAGE(PG8_SB(0, 1), cB + hstepB, voffB); PG8_STAGE(PG8_SA(0, 0), cA, voffA); PG8_STAGE(PG8_SA(0, 1), cA + hstepA, voffA);
;         if (wr == 1) PG8_BAR;
;         PG8_WAIT_V(2); PG8_BAR;
.LBB0_1503:
	s_cmp_gt_i32 s52, 18
	s_cselect_b64 s[0:1], -1, 0
	s_cmp_lt_i32 s53, 19
	s_cselect_b64 s[2:3], -1, 0
	s_or_b64 s[0:1], s[0:1], s[2:3]
	s_and_b64 vcc, exec, s[0:1]
	s_cbranch_vccnz .LBB0_1570
	s_mov_b32 s99, 0
	s_cmpk_gt_i32 s73, 0xd7f
	v_mbcnt_lo_u32_b32 v10, -1, 0
	v_mbcnt_hi_u32_b32 v10, -1, v10
	s_cbranch_scc1 .LBB0_1520
	s_waitcnt lgkmcnt(0)
	s_add_u32 s26, s70, 0x53900000
	s_addc_u32 s27, s71, 0
	s_add_u32 s28, s70, 0x2500000
	s_addc_u32 s29, s71, 0
	s_lshl_b32 s30, s33, 10
	v_lshl_add_u32 v0, v10, 4, s30
	v_add_u32_e32 v1, 0x2000, v0
	v_ashrrev_i32_e32 v2, 31, v1
	v_lshrrev_b32_e32 v2, 22, v2
	v_add_u32_e32 v2, v1, v2
	v_ashrrev_i32_e32 v8, 10, v2
	v_mul_i32_i24_e32 v2, 0x400, v8
	v_sub_u32_e32 v1, v1, v2
	v_lshrrev_b32_e32 v2, 4, v1
	v_bitop3_b32 v1, v2, v1, 32 bitop3:0x6c
	v_ashrrev_i32_e32 v2, 31, v1
	v_lshrrev_b32_e32 v2, 26, v2
	v_add_u32_e32 v2, v1, v2
	v_ashrrev_i32_e32 v9, 6, v2
	v_lshlrev_b32_e32 v3, 3, v8
	v_and_b32_e32 v2, 0xffc0, v2
	v_and_b32_e32 v3, -16, v3
	v_sub_u32_e32 v1, v1, v2
	v_add_u32_e32 v3, v9, v3
	v_lshrrev_b16_e32 v2, 7, v1
	v_and_b32_e32 v4, 3, v9
	s_mov_b32 s0, 0xfffe0
	v_lshrrev_b32_e32 v5, 2, v3
	v_lshlrev_b32_e32 v6, 1, v3
	v_and_b32_e32 v2, 1, v2
	v_and_or_b32 v4, v3, s0, v4
	v_and_b32_e32 v5, 4, v5
	v_and_b32_e32 v6, 24, v6
	v_add_u16_e32 v1, v1, v2
	v_mov_b32_e32 v2, 1
	v_or3_b32 v4, v4, v5, v6
	v_lshlrev_b32_e32 v5, 5, v8
	v_ashrrev_i16_sdwa v1, v2, sext(v1) dst_sel:DWORD dst_unused:UNUSED_PAD src0_sel:DWORD src1_sel:BYTE_0
	v_and_b32_e32 v5, 32, v5
	v_bfe_i32 v11, v1, 0, 16
	v_add_lshl_u32 v1, v5, v11, 1
	v_lshl_add_u32 v128, v4, 12, v1
	v_lshl_add_u32 v130, v3, 12, v1
	v_ashrrev_i32_e32 v1, 31, v0
	v_lshrrev_b32_e32 v1, 22, v1
	v_add_u32_e32 v1, v0, v1
	v_ashrrev_i32_e32 v12, 10, v1
	v_mul_i32_i24_e32 v1, 0x400, v12
	v_sub_u32_e32 v0, v0, v1
	v_lshrrev_b32_e32 v1, 4, v0
	v_bitop3_b32 v0, v1, v0, 32 bitop3:0x6c
	v_ashrrev_i32_e32 v1, 31, v0
	v_lshrrev_b32_e32 v1, 26, v1
	v_add_u32_e32 v1, v0, v1
	v_lshlrev_b32_e32 v3, 3, v12
	v_ashrrev_i32_e32 v13, 6, v1
	v_and_b32_e32 v3, -16, v3
	v_add_u32_e32 v3, v13, v3
	v_and_b32_e32 v4, 3, v13
	s_ashr_i32 s31, s73, 31
	v_and_or_b32 v4, v3, s0, v4
	s_lshr_b32 s0, s31, 29
	s_add_i32 s0, s73, s0
	s_ashr_i32 s1, s0, 3
	s_and_b32 s0, s0, -8
	s_ashr_i32 s3, s33, 2
	s_sub_i32 s0, s73, s0
	s_cmp_lt_i32 s0, 0
	s_movk_i32 s34, 0x1b1
	s_cselect_b32 s2, s34, 0x1b0
	s_mul_i32 s0, s2, s0
	s_add_i32 s0, s0, s1
	s_mul_hi_i32 s1, s0, 0x2aaaaaab
	s_lshr_b32 s2, s1, 31
	s_ashr_i32 s1, s1, 4
	s_add_i32 s1, s1, s2
	s_lshl_b32 s4, s1, 2
	s_mulk_i32 s1, 0x60
	s_sub_i32 s0, s0, s1
	s_bfe_i32 s1, s0, 0x80000
	s_bfe_u32 s1, s1, 0x2000d
	s_add_i32 s1, s0, s1
	s_bfe_i32 s2, s1, 0x80000
	s_and_b32 s1, s1, 0xfc
	s_sub_i32 s0, s0, s1
	s_sext_i32_i16 s2, s2
	s_sext_i32_i8 s0, s0
	v_lshrrev_b32_e32 v5, 2, v3
	v_lshlrev_b32_e32 v6, 1, v3
	v_and_b32_e32 v1, 0xc0, v1
	s_lshr_b32 s2, s2, 2
	s_add_i32 s18, s4, s0
	v_and_b32_e32 v5, 4, v5
	v_and_b32_e32 v6, 24, v6
	v_sub_u32_e32 v0, v0, v1
	s_ashr_i32 s19, s18, 31
	s_bfe_i64 s[4:5], s[2:3], 0x100000
	v_or3_b32 v4, v4, v5, v6
	v_lshlrev_b32_e32 v5, 5, v12
	v_ashrrev_i16_sdwa v0, v2, sext(v0) dst_sel:DWORD dst_unused:UNUSED_PAD src0_sel:DWORD src1_sel:BYTE_0
	s_lshl_b64 s[0:1], s[18:19], 20
	s_lshl_b64 s[4:5], s[4:5], 20
	v_and_b32_e32 v5, 32, v5
	v_bfe_i32 v14, v0, 0, 16
	s_add_u32 s22, s28, s4
	v_add_lshl_u32 v0, v5, v14, 1
	s_addc_u32 s23, s29, s5
	s_add_i32 s19, s30, 0
	v_lshl_add_u32 v132, v4, 12, v0
	s_add_i32 m0, s19, 0x10000
	v_lshl_add_u32 v134, v3, 12, v0
	global_load_lds_dwordx4 v132, s[22:23]
	s_add_i32 m0, s19, 0x12000
	s_add_u32 s4, s22, 0x80000
	global_load_lds_dwordx4 v128, s[22:23]
	s_addc_u32 s5, s23, 0
	s_add_i32 m0, s19, 0x14000
	v_mov_b32_e32 v133, 0
	global_load_lds_dwordx4 v132, s[4:5]
	s_add_i32 m0, s19, 0x16000
	s_add_u32 s20, s26, s0
	s_addc_u32 s21, s27, s1
	s_add_i32 s35, s19, 0x2000
	global_load_lds_dwordx4 v128, s[4:5]
	s_mov_b32 m0, s19
	s_add_u32 s0, s20, 0x80000
	global_load_lds_dwordx4 v134, s[20:21]
	s_mov_b32 m0, s35
	s_addc_u32 s1, s21, 0
	s_add_i32 s36, s19, 0x4000
	global_load_lds_dwordx4 v130, s[20:21]
	s_mov_b32 m0, s36
	s_add_i32 s37, s19, 0x6000
	global_load_lds_dwordx4 v134, s[0:1]
	s_mov_b32 m0, s37
	v_mov_b32_e32 v129, v133
	global_load_lds_dwordx4 v130, s[0:1]
	v_mov_b32_e32 v135, v133
	v_mov_b32_e32 v131, v133
	s_cmp_eq_u32 s3, 1
	s_mov_b32 s38, 0
	v_lshl_add_u64 v[6:7], s[22:23], 0, v[132:133]
	v_lshl_add_u64 v[4:5], s[22:23], 0, v[128:129]
	v_lshl_add_u64 v[0:1], s[20:21], 0, v[134:135]
	s_cselect_b64 s[0:1], -1, 0
	s_cmp_lg_u32 s3, 1
	v_lshl_add_u64 v[2:3], s[20:21], 0, v[130:131]
	s_cbranch_scc1 .LBB0_1507
	s_barrier

; #define PG8_STAGE(bufoff, gbase, voff) do { _Pragma("unroll") for (int _i = 0; _i < 2; ++_i) \
;         __builtin_amdgcn_global_load_lds((const unsigned*)((const char*)(gbase) + (voff)[_i]), (PG8_LAS unsigned*)(lds + (bufoff) + ldsw + _i * 8192), 16, 0, 0); } while (0)
; #define PG8_LDA(dst, b, h) do { _Pragma("unroll") for (int m = 0; m < 4; ++m) _Pragma("unroll") for (int k = 0; k < 2; ++k) dst[m][k] = *(const PG8_LAS bf16x8*)(lds + PG8_SA(b, h) + aoff + m * 2048 + k * 1024); } while (0)
; #define PG8_LDB(dst, b, h) do { _Pragma("unroll") for (int n = 0; n < 2; ++n) _Pragma("unroll") for (int k = 0; k < 2; ++k) dst[n][k] = *(const PG8_LAS bf16x8*)(lds + PG8_SB(b, h) + boff + n * 2048 + k * 1024); } while (0)
; template <class Epi, class Sched, bool ALIGN_EPI = false, bool SP2 = false>
; __device__ __forceinline__ void gemm_phase(PG8_LAS unsigned char* lds, const Gemm g, const Sched& S, const Epi& E, const int wave_in) {
;     ...
;         const char* nA = has_next ? (const char*)g.A + (size_t)nxt.pm * tstepA : cA; const char* nB = has_next ? (const char*)g.Bt + (size_t)nxt.pn * tstepB : cB;
;         for (int t = 0; t < nt; t += 2) {
;             const bool last = (t == nt - 2);
;             const char* a1 = cA + (size_t)(t + 1) * kstep;
;             const char* a2 = last ? nA : cA + (size_t)(t + 2) * kstep; const char* b2 = last ? nB : cB + (size_t)(t + 2) * kstep;
;             const char* a3 = a2 + kstep; const char* b3 = b2 + kstep;
;             if (last && has_next) S.a_ready(nxt);
;             if constexpr (SP2) {
;             PG8_LDB(B0, 0, 0); PG8_LDB(B1, 0, 1); PG8_SCHED; PG8_LDA(At, 0, 0); PG8_STAGE(PG8_SA(1, 1), a1 + hstepA, voffA);
;             PG8_WAIT_V(8); PG8_WAIT_L(0); PG8_BAR; PG8_MMA(0, 0, At, B0); PG8_MMA(0, 1, At, B1); PG8_BAR; PG8_SCHED;
;             PG8_LDA(At, 0, 1); PG8_STAGE(PG8_SB(0, 0), b2, voffB); PG8_STAGE(PG8_SB(0, 1), b2 + hstepB, voffB); PG8_STAGE(PG8_SA(0, 0), a2, voffA);
;             PG8_WAIT_V(8); PG8_WAIT_L(0); PG8_BAR; PG8_MMA(1, 0, At, B0); PG8_MMA(1, 1, At, B1); PG8_BAR; PG8_SCHED;
;     ...
; #pragma unroll
;         for (int a = 0; a < 2; ++a)
; #pragma unroll
;             for (int b = 0; b < 2; ++b)
; #pragma unroll
;                 for (int m = 0; m < 4; ++m)
; #pragma unroll
;                     for (int n = 0; n < 2; ++n) acc[a][b][m][n] = (f32x4){0.f, 0.f, 0.f, 0.f};
;         cur = nxt; cA = nA; cB = nB; ++ui;
.LBB0_1512:
	s_ashr_i32 s13, s12, 31
	s_lshl_b64 s[14:15], s[12:13], 20
	s_add_u32 s14, s26, s14
	s_addc_u32 s15, s27, s15
	s_and_b64 s[16:17], s[2:3], exec
	s_cselect_b32 s13, s15, s21
	s_cselect_b32 s46, s14, s20
	s_ashr_i32 s11, s10, 31
	s_lshl_b64 s[16:17], s[10:11], 20
	s_add_u32 s16, s28, s16
	s_addc_u32 s17, s29, s17
	s_and_b64 s[24:25], s[2:3], exec
	s_cselect_b32 s11, s17, s23
	s_cselect_b32 s47, s16, s22
	s_add_u32 s20, s20, 0x80080
	s_addc_u32 s21, s21, 0
	s_add_u32 s48, s22, 0x100
	v_mov_b32_e32 v0, 0
	s_addc_u32 s49, s23, 0
	s_mov_b32 s50, -2
	v_mov_b32_e32 v1, v0
	v_mov_b32_e32 v2, v0
	v_mov_b32_e32 v3, v0
	v_mov_b32_e32 v4, v0
	v_mov_b32_e32 v5, v0
	v_mov_b32_e32 v6, v0
	v_mov_b32_e32 v7, v0
	v_mov_b32_e32 v8, v0
	v_mov_b32_e32 v9, v0
	v_mov_b32_e32 v10, v0
	v_mov_b32_e32 v11, v0
	v_mov_b32_e32 v16, v0
	v_mov_b32_e32 v17, v0
	v_mov_b32_e32 v18, v0
	v_mov_b32_e32 v19, v0
	v_mov_b32_e32 v24, v0
	v_mov_b32_e32 v25, v0
	v_mov_b32_e32 v26, v0
	v_mov_b32_e32 v27, v0
	v_mov_b32_e32 v32, v0
	v_mov_b32_e32 v33, v0
	v_mov_b32_e32 v34, v0
	v_mov_b32_e32 v35, v0
	v_mov_b32_e32 v40, v0
	v_mov_b32_e32 v41, v0
	v_mov_b32_e32 v42, v0
	v_mov_b32_e32 v43, v0
	v_mov_b32_e32 v48, v0
	v_mov_b32_e32 v49, v0
	v_mov_b32_e32 v50, v0
	v_mov_b32_e32 v51, v0
	v_mov_b32_e32 v12, v0
	v_mov_b32_e32 v13, v0
	v_mov_b32_e32 v14, v0
	v_mov_b32_e32 v15, v0
	v_mov_b32_e32 v20, v0
	v_mov_b32_e32 v21, v0
	v_mov_b32_e32 v22, v0
	v_mov_b32_e32 v23, v0
	v_mov_b32_e32 v28, v0
	v_mov_b32_e32 v29, v0
	v_mov_b32_e32 v30, v0
	v_mov_b32_e32 v31, v0
	v_mov_b32_e32 v36, v0
	v_mov_b32_e32 v37, v0
	v_mov_b32_e32 v38, v0
	v_mov_b32_e32 v39, v0
	v_mov_b32_e32 v44, v0
	v_mov_b32_e32 v45, v0
	v_mov_b32_e32 v46, v0
	v_mov_b32_e32 v47, v0
	v_mov_b32_e32 v52, v0
	v_mov_b32_e32 v53, v0
	v_mov_b32_e32 v54, v0
	v_mov_b32_e32 v55, v0
	v_mov_b32_e32 v56, v0
	v_mov_b32_e32 v57, v0
	v_mov_b32_e32 v58, v0
	v_mov_b32_e32 v59, v0
	v_mov_b32_e32 v60, v0
	v_mov_b32_e32 v61, v0
	v_mov_b32_e32 v62, v0
	v_mov_b32_e32 v63, v0
	v_mov_b32_e32 v64, v0
	v_mov_b32_e32 v65, v0
	v_mov_b32_e32 v66, v0
	v_mov_b32_e32 v67, v0
	v_mov_b32_e32 v68, v0
	v_mov_b32_e32 v69, v0
	v_mov_b32_e32 v70, v0
	v_mov_b32_e32 v71, v0
	v_mov_b32_e32 v72, v0
	v_mov_b32_e32 v73, v0
	v_mov_b32_e32 v74, v0
	v_mov_b32_e32 v75, v0
	v_mov_b32_e32 v80, v0
	v_mov_b32_e32 v81, v0
	v_mov_b32_e32 v82, v0
	v_mov_b32_e32 v83, v0
	v_mov_b32_e32 v88, v0
	v_mov_b32_e32 v89, v0
	v_mov_b32_e32 v90, v0
	v_mov_b32_e32 v91, v0
	v_mov_b32_e32 v96, v0
	v_mov_b32_e32 v97, v0
	v_mov_b32_e32 v98, v0
	v_mov_b32_e32 v99, v0
	v_mov_b32_e32 v104, v0
	v_mov_b32_e32 v105, v0
	v_mov_b32_e32 v106, v0
	v_mov_b32_e32 v107, v0
	v_mov_b32_e32 v112, v0
	v_mov_b32_e32 v113, v0
	v_mov_b32_e32 v114, v0
	v_mov_b32_e32 v115, v0
	v_mov_b32_e32 v76, v0
	v_mov_b32_e32 v77, v0
	v_mov_b32_e32 v78, v0
	v_mov_b32_e32 v79, v0
	v_mov_b32_e32 v84, v0
	v_mov_b32_e32 v85, v0
	v_mov_b32_e32 v86, v0
	v_mov_b32_e32 v87, v0
	v_mov_b32_e32 v92, v0
	v_mov_b32_e32 v93, v0
	v_mov_b32_e32 v94, v0
	v_mov_b32_e32 v95, v0
	v_mov_b32_e32 v100, v0
	v_mov_b32_e32 v101, v0
	v_mov_b32_e32 v102, v0
	v_mov_b32_e32 v103, v0
	v_mov_b32_e32 v108, v0
	v_mov_b32_e32 v109, v0
	v_mov_b32_e32 v110, v0
	v_mov_b32_e32 v111, v0
	v_mov_b32_e32 v116, v0
	v_mov_b32_e32 v117, v0
	v_mov_b32_e32 v118, v0
	v_mov_b32_e32 v119, v0
	v_mov_b32_e32 v120, v0
	v_mov_b32_e32 v121, v0
	v_mov_b32_e32 v122, v0
	v_mov_b32_e32 v123, v0
	v_mov_b32_e32 v124, v0
	v_mov_b32_e32 v125, v0
	v_mov_b32_e32 v126, v0
	v_mov_b32_e32 v127, v0
	s_cmp_lg_u32 s99, 0
	s_cbranch_scc0 .LBB0_1513
	ds_read_b128 v[144:147], v151
	ds_read_b128 v[154:157], v151 offset:1024
	ds_read_b128 v[158:161], v151 offset:2048
	ds_read_b128 v[162:165], v151 offset:3072
	ds_read_b128 v[166:169], v152
	ds_read_b128 v[170:173], v152 offset:1024
	ds_read_b128 v[174:177], v152 offset:2048
	ds_read_b128 v[178:181], v152 offset:3072
	s_add_u32 s22, s20, 0xfff80080
	s_addc_u32 s23, s21, -1
	s_cmp_eq_u32 s50, 28
	s_cselect_b32 s25, s13, s23
	s_cselect_b32 s24, s46, s22
	s_cselect_b32 s23, s11, s49
	s_cselect_b32 s22, s47, s48
	v_lshl_add_u64 v[214:215], s[20:21], 0, v[136:137]
	s_add_i32 m0, s19, 0xc000
	ds_read_b128 v[182:185], v153
	ds_read_b128 v[186:189], v153 offset:1024
	ds_read_b128 v[190:193], v153 offset:2048
	ds_read_b128 v[194:197], v153 offset:3072
	ds_read_b128 v[198:201], v153 offset:4096
	ds_read_b128 v[202:205], v153 offset:5120
	ds_read_b128 v[206:209], v153 offset:6144
	ds_read_b128 v[210:213], v153 offset:7168
	global_load_lds_dwordx4 v[214:215], off
	v_lshl_add_u64 v[214:215], s[20:21], 0, v[138:139]
	s_add_i32 m0, s19, 0xe000
	s_nop 0
	global_load_lds_dwordx4 v[214:215], off
	s_waitcnt vmcnt(24)
	s_waitcnt lgkmcnt(0)
	s_barrier
; #define PG8_STAGE(bufoff, gbase, voff) do { _Pragma("unroll") for (int _i = 0; _i < 2; ++_i) \
;         __builtin_amdgcn_global_load_lds((const unsigned*)((const char*)(gbase) + (voff)[_i]), (PG8_LAS unsigned*)(lds + (bufoff) + ldsw + _i * 8192), 16, 0, 0); } while (0)
; #define PG8_LDA(dst, b, h) do { _Pragma("unroll") for (int m = 0; m < 4; ++m) _Pragma("unroll") for (int k = 0; k < 2; ++k) dst[m][k] = *(const PG8_LAS bf16x8*)(lds + PG8_SA(b, h) + aoff + m * 2048 + k * 1024); } while (0)
; #define PG8_LDB(dst, b, h) do { _Pragma("unroll") for (int n = 0; n < 2; ++n) _Pragma("unroll") for (int k = 0; k < 2; ++k) dst[n][k] = *(const PG8_LAS bf16x8*)(lds + PG8_SB(b, h) + boff + n * 2048 + k * 1024); } while (0)
; #define PG8_MMA(ai, bj, At, Bt) do { __builtin_amdgcn_s_setprio(1); _Pragma("unroll") for (int m = 0; m < 4; ++m) _Pragma("unroll") for (int n = 0; n < 2; ++n) _Pragma("unroll") for (int k = 0; k < 2; ++k) \
;         acc[ai][bj][m][n] = __builtin_amdgcn_mfma_f32_16x16x32_bf16(Bt[n][k], At[m][k], acc[ai][bj][m][n], 0, 0, 0); __builtin_amdgcn_s_setprio(0); } while (0)
; #define PG8_WAIT_V(n) asm volatile("s_waitcnt vmcnt(" #n ")" ::: "memory")
; #define PG8_WAIT_L(n) asm volatile("s_waitcnt lgkmcnt(" #n ")" ::: "memory")
; #define PG8_BAR __builtin_amdgcn_s_barrier()
; #define PG8_SCHED __builtin_amdgcn_sched_barrier(0)
; template <class Epi, class Sched, bool ALIGN_EPI = false, bool SP2 = false>
; __device__ __forceinline__ void gemm_phase(PG8_LAS unsigned char* lds, const Gemm g, const Sched& S, const Epi& E, const int wave_in) {
;     ...
;             PG8_WAIT_V(8); PG8_WAIT_L(0); PG8_BAR; PG8_MMA(0, 0, At, B0); PG8_MMA(0, 1, At, B1); PG8_BAR; PG8_SCHED;
;             PG8_LDA(At, 0, 1); PG8_STAGE(PG8_SB(0, 0), b2, voffB); PG8_STAGE(PG8_SB(0, 1), b2 + hstepB, voffB); PG8_STAGE(PG8_SA(0, 0), a2, voffA);
;             PG8_WAIT_V(8); PG8_WAIT_L(0); PG8_BAR; PG8_MMA(1, 0, At, B0); PG8_MMA(1, 1, At, B1); PG8_BAR; PG8_SCHED;
;             PG8_LDB(B0, 1, 0); PG8_LDB(B1, 1, 1); PG8_SCHED; PG8_LDA(At, 1, 0); PG8_STAGE(PG8_SA(0, 1), a2 + hstepA, voffA);
;             PG8_WAIT_V(8); PG8_WAIT_L(0); PG8_BAR; PG8_MMA(0, 0, At, B0); PG8_MMA(0, 1, At, B1); PG8_BAR; PG8_SCHED;
	s_setprio 1
	s_waitcnt lgkmcnt(0)
	v_mfma_f32_16x16x32_bf16 v[124:127], v[144:147], v[182:185], v[124:127]
	v_mfma_f32_16x16x32_bf16 v[120:123], v[158:161], v[182:185], v[120:123]
	v_mfma_f32_16x16x32_bf16 v[116:119], v[144:147], v[190:193], v[116:119]
	v_mfma_f32_16x16x32_bf16 v[108:111], v[158:161], v[190:193], v[108:111]
	v_mfma_f32_16x16x32_bf16 v[100:103], v[144:147], v[198:201], v[100:103]
	v_mfma_f32_16x16x32_bf16 v[92:95], v[158:161], v[198:201], v[92:95]
	v_mfma_f32_16x16x32_bf16 v[84:87], v[144:147], v[206:209], v[84:87]
	v_mfma_f32_16x16x32_bf16 v[76:79], v[158:161], v[206:209], v[76:79]
	v_mfma_f32_16x16x32_bf16 v[124:127], v[154:157], v[186:189], v[124:127]
	v_mfma_f32_16x16x32_bf16 v[120:123], v[162:165], v[186:189], v[120:123]
	v_mfma_f32_16x16x32_bf16 v[116:119], v[154:157], v[194:197], v[116:119]
	v_mfma_f32_16x16x32_bf16 v[108:111], v[162:165], v[194:197], v[108:111]
	v_mfma_f32_16x16x32_bf16 v[100:103], v[154:157], v[202:205], v[100:103]
	v_mfma_f32_16x16x32_bf16 v[92:95], v[162:165], v[202:205], v[92:95]
	v_mfma_f32_16x16x32_bf16 v[84:87], v[154:157], v[210:213], v[84:87]
	v_mfma_f32_16x16x32_bf16 v[76:79], v[162:165], v[210:213], v[76:79]
	s_setprio 0
	s_setprio 1
	v_mfma_f32_16x16x32_bf16 v[112:115], v[166:169], v[182:185], v[112:115]
	v_mfma_f32_16x16x32_bf16 v[104:107], v[174:177], v[182:185], v[104:107]
	v_mfma_f32_16x16x32_bf16 v[96:99], v[166:169], v[190:193], v[96:99]
	v_mfma_f32_16x16x32_bf16 v[88:91], v[174:177], v[190:193], v[88:91]
	v_mfma_f32_16x16x32_bf16 v[80:83], v[166:169], v[198:201], v[80:83]
	v_mfma_f32_16x16x32_bf16 v[72:75], v[174:177], v[198:201], v[72:75]
	v_mfma_f32_16x16x32_bf16 v[68:71], v[166:169], v[206:209], v[68:71]
	v_mfma_f32_16x16x32_bf16 v[64:67], v[174:177], v[206:209], v[64:67]
	v_mfma_f32_16x16x32_bf16 v[112:115], v[170:173], v[186:189], v[112:115]
	v_mfma_f32_16x16x32_bf16 v[104:107], v[178:181], v[186:189], v[104:107]
	v_mfma_f32_16x16x32_bf16 v[96:99], v[170:173], v[194:197], v[96:99]
	v_mfma_f32_16x16x32_bf16 v[88:91], v[178:181], v[194:197], v[88:91]
	v_mfma_f32_16x16x32_bf16 v[80:83], v[170:173], v[202:205], v[80:83]
	v_mfma_f32_16x16x32_bf16 v[72:75], v[178:181], v[202:205], v[72:75]
	v_mfma_f32_16x16x32_bf16 v[68:71], v[170:173], v[210:213], v[68:71]
	v_mfma_f32_16x16x32_bf16 v[64:67], v[178:181], v[210:213], v[64:67]
	s_setprio 0
	s_barrier
	s_add_i32 s51, s42, s30
	v_lshl_add_u64 v[214:215], s[22:23], 0, v[132:133]
	s_mov_b32 m0, s51
	ds_read_b128 v[182:185], v153 offset:16384
	ds_read_b128 v[186:189], v153 offset:17408
	ds_read_b128 v[190:193], v153 offset:18432
	ds_read_b128 v[194:197], v153 offset:19456
	ds_read_b128 v[198:201], v153 offset:20480
	ds_read_b128 v[202:205], v153 offset:21504
	ds_read_b128 v[206:209], v153 offset:22528
	ds_read_b128 v[210:213], v153 offset:23552
	global_load_lds_dwordx4 v[214:215], off
	s_add_i32 m0, s51, 0x2000
	s_add_u32 s52, s22, 0x80000
	v_lshl_add_u64 v[216:217], s[22:23], 0, v[128:129]
	s_addc_u32 s53, s23, 0
	s_add_i32 s51, s43, s30
	global_load_lds_dwordx4 v[216:217], off
	v_lshl_add_u64 v[218:219], s[52:53], 0, v[132:133]
	s_mov_b32 m0, s51
	v_lshl_add_u64 v[220:221], s[24:25], 0, v[130:131]
	global_load_lds_dwordx4 v[218:219], off
	v_lshl_add_u64 v[218:219], s[52:53], 0, v[128:129]
	s_add_i32 m0, s51, 0x2000
	s_nop 0
	global_load_lds_dwordx4 v[218:219], off
	v_lshl_add_u64 v[218:219], s[24:25], 0, v[134:135]
	s_mov_b32 m0, s19
	s_nop 0
	global_load_lds_dwordx4 v[218:219], off
	s_mov_b32 m0, s35
	s_nop 0
	global_load_lds_dwordx4 v[220:221], off
	s_waitcnt vmcnt(24)
	s_waitcnt lgkmcnt(0)
	s_barrier
	s_setprio 1
	s_waitcnt lgkmcnt(0)
	v_mfma_f32_16x16x32_bf16 v[60:63], v[144:147], v[182:185], v[60:63]
	v_mfma_f32_16x16x32_bf16 v[56:59], v[158:161], v[182:185], v[56:59]
	v_mfma_f32_16x16x32_bf16 v[52:55], v[144:147], v[190:193], v[52:55]
	v_mfma_f32_16x16x32_bf16 v[44:47], v[158:161], v[190:193], v[44:47]
	v_mfma_f32_16x16x32_bf16 v[36:39], v[144:147], v[198:201], v[36:39]
	v_mfma_f32_16x16x32_bf16 v[28:31], v[158:161], v[198:201], v[28:31]
	v_mfma_f32_16x16x32_bf16 v[20:23], v[144:147], v[206:209], v[20:23]
	v_mfma_f32_16x16x32_bf16 v[12:15], v[158:161], v[206:209], v[12:15]
	v_mfma_f32_16x16x32_bf16 v[60:63], v[154:157], v[186:189], v[60:63]
	v_mfma_f32_16x16x32_bf16 v[56:59], v[162:165], v[186:189], v[56:59]
	v_mfma_f32_16x16x32_bf16 v[52:55], v[154:157], v[194:197], v[52:55]
	v_mfma_f32_16x16x32_bf16 v[44:47], v[162:165], v[194:197], v[44:47]
	v_mfma_f32_16x16x32_bf16 v[36:39], v[154:157], v[202:205], v[36:39]
	v_mfma_f32_16x16x32_bf16 v[28:31], v[162:165], v[202:205], v[28:31]
	v_mfma_f32_16x16x32_bf16 v[20:23], v[154:157], v[210:213], v[20:23]
	v_mfma_f32_16x16x32_bf16 v[12:15], v[162:165], v[210:213], v[12:15]
	s_setprio 0
	s_setprio 1
	v_mfma_f32_16x16x32_bf16 v[48:51], v[166:169], v[182:185], v[48:51]
	v_mfma_f32_16x16x32_bf16 v[40:43], v[174:177], v[182:185], v[40:43]
	v_mfma_f32_16x16x32_bf16 v[32:35], v[166:169], v[190:193], v[32:35]
	v_mfma_f32_16x16x32_bf16 v[24:27], v[174:177], v[190:193], v[24:27]
	v_mfma_f32_16x16x32_bf16 v[16:19], v[166:169], v[198:201], v[16:19]
	v_mfma_f32_16x16x32_bf16 v[8:11], v[174:177], v[198:201], v[8:11]
	v_mfma_f32_16x16x32_bf16 v[4:7], v[166:169], v[206:209], v[4:7]
	v_mfma_f32_16x16x32_bf16 v[0:3], v[174:177], v[206:209], v[0:3]
	v_mfma_f32_16x16x32_bf16 v[48:51], v[170:173], v[186:189], v[48:51]
	v_mfma_f32_16x16x32_bf16 v[40:43], v[178:181], v[186:189], v[40:43]
	v_mfma_f32_16x16x32_bf16 v[32:35], v[170:173], v[194:197], v[32:35]
	v_mfma_f32_16x16x32_bf16 v[24:27], v[178:181], v[194:197], v[24:27]
	v_mfma_f32_16x16x32_bf16 v[16:19], v[170:173], v[202:205], v[16:19]
	v_mfma_f32_16x16x32_bf16 v[8:11], v[178:181], v[202:205], v[8:11]
	v_mfma_f32_16x16x32_bf16 v[4:7], v[170:173], v[210:213], v[4:7]
	v_mfma_f32_16x16x32_bf16 v[0:3], v[178:181], v[210:213], v[0:3]
	s_setprio 0
	s_barrier
; #define PG8_STAGE(bufoff, gbase, voff) do { _Pragma("unroll") for (int _i = 0; _i < 2; ++_i) \
;         __builtin_amdgcn_global_load_lds((const unsigned*)((const char*)(gbase) + (voff)[_i]), (PG8_LAS unsigned*)(lds + (bufoff) + ldsw + _i * 8192), 16, 0, 0); } while (0)
; #define PG8_LDA(dst, b, h) do { _Pragma("unroll") for (int m = 0; m < 4; ++m) _Pragma("unroll") for (int k = 0; k < 2; ++k) dst[m][k] = *(const PG8_LAS bf16x8*)(lds + PG8_SA(b, h) + aoff + m * 2048 + k * 1024); } while (0)
; #define PG8_LDB(dst, b, h) do { _Pragma("unroll") for (int n = 0; n < 2; ++n) _Pragma("unroll") for (int k = 0; k < 2; ++k) dst[n][k] = *(const PG8_LAS bf16x8*)(lds + PG8_SB(b, h) + boff + n * 2048 + k * 1024); } while (0)
; #define PG8_MMA(ai, bj, At, Bt) do { __builtin_amdgcn_s_setprio(1); _Pragma("unroll") for (int m = 0; m < 4; ++m) _Pragma("unroll") for (int n = 0; n < 2; ++n) _Pragma("unroll") for (int k = 0; k < 2; ++k) \
;         acc[ai][bj][m][n] = __builtin_amdgcn_mfma_f32_16x16x32_bf16(Bt[n][k], At[m][k], acc[ai][bj][m][n], 0, 0, 0); __builtin_amdgcn_s_setprio(0); } while (0)
; #define PG8_WAIT_V(n) asm volatile("s_waitcnt vmcnt(" #n ")" ::: "memory")
; #define PG8_WAIT_L(n) asm volatile("s_waitcnt lgkmcnt(" #n ")" ::: "memory")
; #define PG8_BAR __builtin_amdgcn_s_barrier()
; #define PG8_SCHED __builtin_amdgcn_sched_barrier(0)
; template <class Epi, class Sched, bool ALIGN_EPI = false, bool SP2 = false>
; __device__ __forceinline__ void gemm_phase(PG8_LAS unsigned char* lds, const Gemm g, const Sched& S, const Epi& E, const int wave_in) {
;     ...
;             PG8_WAIT_V(8); PG8_WAIT_L(0); PG8_BAR; PG8_MMA(1, 0, At, B0); PG8_MMA(1, 1, At, B1); PG8_BAR; PG8_SCHED;
;             PG8_LDB(B0, 1, 0); PG8_LDB(B1, 1, 1); PG8_SCHED; PG8_LDA(At, 1, 0); PG8_STAGE(PG8_SA(0, 1), a2 + hstepA, voffA);
;             PG8_WAIT_V(8); PG8_WAIT_L(0); PG8_BAR; PG8_MMA(0, 0, At, B0); PG8_MMA(0, 1, At, B1); PG8_BAR; PG8_SCHED;
;             PG8_LDA(At, 1, 1); PG8_STAGE(PG8_SB(1, 0), b3, voffB); PG8_STAGE(PG8_SB(1, 1), b3 + hstepB, voffB); PG8_STAGE(PG8_SA(1, 0), a3, voffA);
;             PG8_WAIT_V(8); PG8_WAIT_L(0); PG8_BAR; PG8_MMA(1, 0, At, B0); PG8_MMA(1, 1, At, B1); PG8_BAR; PG8_SCHED;
	s_add_i32 s51, 0, 0x18000
	s_add_i32 s52, 0, 0x1c000
	v_add_u32_e32 v162, s51, v149
	v_add_u32_e32 v178, s52, v149
	ds_read_b128 v[144:147], v162
	ds_read_b128 v[154:157], v162 offset:1024
	ds_read_b128 v[158:161], v162 offset:2048
	ds_read_b128 v[162:165], v162 offset:3072
	ds_read_b128 v[166:169], v178
	ds_read_b128 v[170:173], v178 offset:1024
	ds_read_b128 v[174:177], v178 offset:2048
	ds_read_b128 v[178:181], v178 offset:3072
	s_add_u32 s24, s24, 0x80000
	s_addc_u32 s25, s25, 0
	s_mov_b32 m0, s36
	v_lshl_add_u64 v[222:223], s[24:25], 0, v[134:135]
	ds_read_b128 v[182:185], v153 offset:32768
	ds_read_b128 v[186:189], v153 offset:33792
	ds_read_b128 v[190:193], v153 offset:34816
	ds_read_b128 v[194:197], v153 offset:35840
	ds_read_b128 v[198:201], v153 offset:36864
	ds_read_b128 v[202:205], v153 offset:37888
	ds_read_b128 v[206:209], v153 offset:38912
	ds_read_b128 v[210:213], v153 offset:39936
	global_load_lds_dwordx4 v[222:223], off
	v_lshl_add_u64 v[222:223], s[24:25], 0, v[130:131]
	s_mov_b32 m0, s37
	s_nop 0
	global_load_lds_dwordx4 v[222:223], off
	s_waitcnt vmcnt(8)
	s_waitcnt lgkmcnt(0)
	s_barrier
	s_setprio 1
	s_waitcnt lgkmcnt(0)
	v_mfma_f32_16x16x32_bf16 v[124:127], v[144:147], v[182:185], v[124:127]
	v_mfma_f32_16x16x32_bf16 v[120:123], v[158:161], v[182:185], v[120:123]
	v_mfma_f32_16x16x32_bf16 v[116:119], v[144:147], v[190:193], v[116:119]
	v_mfma_f32_16x16x32_bf16 v[108:111], v[158:161], v[190:193], v[108:111]
	v_mfma_f32_16x16x32_bf16 v[100:103], v[144:147], v[198:201], v[100:103]
	v_mfma_f32_16x16x32_bf16 v[92:95], v[158:161], v[198:201], v[92:95]
	v_mfma_f32_16x16x32_bf16 v[84:87], v[144:147], v[206:209], v[84:87]
	v_mfma_f32_16x16x32_bf16 v[76:79], v[158:161], v[206:209], v[76:79]
	v_mfma_f32_16x16x32_bf16 v[124:127], v[154:157], v[186:189], v[124:127]
	v_mfma_f32_16x16x32_bf16 v[120:123], v[162:165], v[186:189], v[120:123]
	v_mfma_f32_16x16x32_bf16 v[116:119], v[154:157], v[194:197], v[116:119]
	v_mfma_f32_16x16x32_bf16 v[108:111], v[162:165], v[194:197], v[108:111]
	v_mfma_f32_16x16x32_bf16 v[100:103], v[154:157], v[202:205], v[100:103]
	v_mfma_f32_16x16x32_bf16 v[92:95], v[162:165], v[202:205], v[92:95]
	v_mfma_f32_16x16x32_bf16 v[84:87], v[154:157], v[210:213], v[84:87]
	v_mfma_f32_16x16x32_bf16 v[76:79], v[162:165], v[210:213], v[76:79]
	s_setprio 0
	s_setprio 1
	v_mfma_f32_16x16x32_bf16 v[112:115], v[166:169], v[182:185], v[112:115]
	v_mfma_f32_16x16x32_bf16 v[104:107], v[174:177], v[182:185], v[104:107]
	v_mfma_f32_16x16x32_bf16 v[96:99], v[166:169], v[190:193], v[96:99]
	v_mfma_f32_16x16x32_bf16 v[88:91], v[174:177], v[190:193], v[88:91]
	v_mfma_f32_16x16x32_bf16 v[80:83], v[166:169], v[198:201], v[80:83]
	v_mfma_f32_16x16x32_bf16 v[72:75], v[174:177], v[198:201], v[72:75]
	v_mfma_f32_16x16x32_bf16 v[68:71], v[166:169], v[206:209], v[68:71]
	v_mfma_f32_16x16x32_bf16 v[64:67], v[174:177], v[206:209], v[64:67]
	v_mfma_f32_16x16x32_bf16 v[112:115], v[170:173], v[186:189], v[112:115]
	v_mfma_f32_16x16x32_bf16 v[104:107], v[178:181], v[186:189], v[104:107]
	v_mfma_f32_16x16x32_bf16 v[96:99], v[170:173], v[194:197], v[96:99]
	v_mfma_f32_16x16x32_bf16 v[88:91], v[178:181], v[194:197], v[88:91]
	v_mfma_f32_16x16x32_bf16 v[80:83], v[170:173], v[202:205], v[80:83]
	v_mfma_f32_16x16x32_bf16 v[72:75], v[178:181], v[202:205], v[72:75]
	v_mfma_f32_16x16x32_bf16 v[68:71], v[170:173], v[210:213], v[68:71]
	v_mfma_f32_16x16x32_bf16 v[64:67], v[178:181], v[210:213], v[64:67]
	s_setprio 0
	s_barrier
	s_add_i32 s24, s51, s30
	v_lshl_add_u64 v[214:215], v[214:215], 0, s[6:7]
	s_mov_b32 m0, s24
	ds_read_b128 v[182:185], v153 offset:49152
	ds_read_b128 v[186:189], v153 offset:50176
	ds_read_b128 v[190:193], v153 offset:51200
	ds_read_b128 v[194:197], v153 offset:52224
	ds_read_b128 v[198:201], v153 offset:53248
	ds_read_b128 v[202:205], v153 offset:54272
	ds_read_b128 v[206:209], v153 offset:55296
	ds_read_b128 v[210:213], v153 offset:56320
	global_load_lds_dwordx4 v[214:215], off
	s_add_i32 m0, s24, 0x2000
	s_add_u32 s22, s22, 0x80080
	v_lshl_add_u64 v[214:215], v[216:217], 0, s[6:7]
	s_addc_u32 s23, s23, 0
	s_add_i32 s24, s52, s30
	global_load_lds_dwordx4 v[214:215], off
	v_lshl_add_u64 v[214:215], s[22:23], 0, v[132:133]
	s_mov_b32 m0, s24
	s_nop 0
	global_load_lds_dwordx4 v[214:215], off
	v_lshl_add_u64 v[214:215], s[22:23], 0, v[128:129]
	s_add_i32 m0, s24, 0x2000
	s_nop 0
	global_load_lds_dwordx4 v[214:215], off
	v_lshl_add_u64 v[214:215], v[218:219], 0, s[6:7]
	s_mov_b32 m0, s39
	s_nop 0
	global_load_lds_dwordx4 v[214:215], off
	v_lshl_add_u64 v[214:215], v[220:221], 0, s[6:7]
	s_mov_b32 m0, s40
	s_nop 0
	global_load_lds_dwordx4 v[214:215], off
	s_waitcnt vmcnt(8)
	s_waitcnt lgkmcnt(0)
	s_barrier
; #define PG8_STAGE(bufoff, gbase, voff) do { _Pragma("unroll") for (int _i = 0; _i < 2; ++_i) \
;         __builtin_amdgcn_global_load_lds((const unsigned*)((const char*)(gbase) + (voff)[_i]), (PG8_LAS unsigned*)(lds + (bufoff) + ldsw + _i * 8192), 16, 0, 0); } while (0)
; #define PG8_LDA(dst, b, h) do { _Pragma("unroll") for (int m = 0; m < 4; ++m) _Pragma("unroll") for (int k = 0; k < 2; ++k) dst[m][k] = *(const PG8_LAS bf16x8*)(lds + PG8_SA(b, h) + aoff + m * 2048 + k * 1024); } while (0)
; #define PG8_LDB(dst, b, h) do { _Pragma("unroll") for (int n = 0; n < 2; ++n) _Pragma("unroll") for (int k = 0; k < 2; ++k) dst[n][k] = *(const PG8_LAS bf16x8*)(lds + PG8_SB(b, h) + boff + n * 2048 + k * 1024); } while (0)
; #define PG8_MMA(ai, bj, At, Bt) do { __builtin_amdgcn_s_setprio(1); _Pragma("unroll") for (int m = 0; m < 4; ++m) _Pragma("unroll") for (int n = 0; n < 2; ++n) _Pragma("unroll") for (int k = 0; k < 2; ++k) \
;         acc[ai][bj][m][n] = __builtin_amdgcn_mfma_f32_16x16x32_bf16(Bt[n][k], At[m][k], acc[ai][bj][m][n], 0, 0, 0); __builtin_amdgcn_s_setprio(0); } while (0)
; template <class Epi, class Sched, bool ALIGN_EPI = false, bool SP2 = false>
; __device__ __forceinline__ void gemm_phase(PG8_LAS unsigned char* lds, const Gemm g, const Sched& S, const Epi& E, const int wave_in) {
;     ...
;         for (int t = 0; t < nt; t += 2) {
;             const bool last = (t == nt - 2);
;             const char* a1 = cA + (size_t)(t + 1) * kstep;
;             const char* a2 = last ? nA : cA + (size_t)(t + 2) * kstep; const char* b2 = last ? nB : cB + (size_t)(t + 2) * kstep;
;             const char* a3 = a2 + kstep; const char* b3 = b2 + kstep;
;             if (last && has_next) S.a_ready(nxt);
;             if constexpr (SP2) {
;             PG8_LDB(B0, 0, 0); PG8_LDB(B1, 0, 1); PG8_SCHED; PG8_LDA(At, 0, 0); PG8_STAGE(PG8_SA(1, 1), a1 + hstepA, voffA);
;             PG8_WAIT_V(8); PG8_WAIT_L(0); PG8_BAR; PG8_MMA(0, 0, At, B0); PG8_MMA(0, 1, At, B1); PG8_BAR; PG8_SCHED;
;             PG8_LDA(At, 0, 1); PG8_STAGE(PG8_SB(0, 0), b2, voffB); PG8_STAGE(PG8_SB(0, 1), b2 + hstepB, voffB); PG8_STAGE(PG8_SA(0, 0), a2, voffA);
;             PG8_WAIT_V(8); PG8_WAIT_L(0); PG8_BAR; PG8_MMA(1, 0, At, B0); PG8_MMA(1, 1, At, B1); PG8_BAR; PG8_SCHED;
;     ...
;             PG8_WAIT_V(8); PG8_WAIT_L(0); PG8_BAR; PG8_MMA(1, 0, At, B0); PG8_MMA(1, 1, At, B1); PG8_BAR; PG8_SCHED;
	s_setprio 1
	s_waitcnt lgkmcnt(0)
	v_mfma_f32_16x16x32_bf16 v[60:63], v[144:147], v[182:185], v[60:63]
	v_mfma_f32_16x16x32_bf16 v[56:59], v[158:161], v[182:185], v[56:59]
	v_mfma_f32_16x16x32_bf16 v[52:55], v[144:147], v[190:193], v[52:55]
	v_mfma_f32_16x16x32_bf16 v[44:47], v[158:161], v[190:193], v[44:47]
	v_mfma_f32_16x16x32_bf16 v[36:39], v[144:147], v[198:201], v[36:39]
	v_mfma_f32_16x16x32_bf16 v[28:31], v[158:161], v[198:201], v[28:31]
	v_mfma_f32_16x16x32_bf16 v[20:23], v[144:147], v[206:209], v[20:23]
	v_mfma_f32_16x16x32_bf16 v[12:15], v[158:161], v[206:209], v[12:15]
	v_mfma_f32_16x16x32_bf16 v[60:63], v[154:157], v[186:189], v[60:63]
	v_mfma_f32_16x16x32_bf16 v[56:59], v[162:165], v[186:189], v[56:59]
	v_mfma_f32_16x16x32_bf16 v[52:55], v[154:157], v[194:197], v[52:55]
	v_mfma_f32_16x16x32_bf16 v[44:47], v[162:165], v[194:197], v[44:47]
	v_mfma_f32_16x16x32_bf16 v[36:39], v[154:157], v[202:205], v[36:39]
	v_mfma_f32_16x16x32_bf16 v[28:31], v[162:165], v[202:205], v[28:31]
	v_mfma_f32_16x16x32_bf16 v[20:23], v[154:157], v[210:213], v[20:23]
	v_mfma_f32_16x16x32_bf16 v[12:15], v[162:165], v[210:213], v[12:15]
	s_setprio 0
	s_setprio 1
	v_mfma_f32_16x16x32_bf16 v[48:51], v[166:169], v[182:185], v[48:51]
	v_mfma_f32_16x16x32_bf16 v[40:43], v[174:177], v[182:185], v[40:43]
	v_mfma_f32_16x16x32_bf16 v[32:35], v[166:169], v[190:193], v[32:35]
	v_mfma_f32_16x16x32_bf16 v[24:27], v[174:177], v[190:193], v[24:27]
	v_mfma_f32_16x16x32_bf16 v[16:19], v[166:169], v[198:201], v[16:19]
	v_mfma_f32_16x16x32_bf16 v[8:11], v[174:177], v[198:201], v[8:11]
	v_mfma_f32_16x16x32_bf16 v[4:7], v[166:169], v[206:209], v[4:7]
	v_mfma_f32_16x16x32_bf16 v[0:3], v[174:177], v[206:209], v[0:3]
	v_mfma_f32_16x16x32_bf16 v[48:51], v[170:173], v[186:189], v[48:51]
	v_mfma_f32_16x16x32_bf16 v[40:43], v[178:181], v[186:189], v[40:43]
	v_mfma_f32_16x16x32_bf16 v[32:35], v[170:173], v[194:197], v[32:35]
	v_mfma_f32_16x16x32_bf16 v[24:27], v[178:181], v[194:197], v[24:27]
	v_mfma_f32_16x16x32_bf16 v[16:19], v[170:173], v[202:205], v[16:19]
	v_mfma_f32_16x16x32_bf16 v[8:11], v[178:181], v[202:205], v[8:11]
	v_mfma_f32_16x16x32_bf16 v[4:7], v[170:173], v[210:213], v[4:7]
	v_mfma_f32_16x16x32_bf16 v[0:3], v[178:181], v[210:213], v[0:3]
	s_setprio 0
	s_barrier
	s_add_i32 s50, s50, 2
	s_add_u32 s20, s20, 0x100
	s_addc_u32 s21, s21, 0
	s_add_u32 s48, s48, 0x100
	s_addc_u32 s49, s49, 0
	s_cmp_gt_u32 s50, 29
	s_cbranch_scc0 .LBB0_1513
.LBB0_1513:
	ds_read_b128 v[144:147], v151
	ds_read_b128 v[154:157], v151 offset:1024
	ds_read_b128 v[158:161], v151 offset:2048
	ds_read_b128 v[162:165], v151 offset:3072
	ds_read_b128 v[166:169], v152
	ds_read_b128 v[170:173], v152 offset:1024
	ds_read_b128 v[174:177], v152 offset:2048
	ds_read_b128 v[178:181], v152 offset:3072
	s_add_u32 s22, s20, 0xfff80080
	s_addc_u32 s23, s21, -1
	s_cmp_eq_u32 s50, 28
	s_cselect_b32 s25, s13, s23
	s_cselect_b32 s24, s46, s22
	s_cselect_b32 s23, s11, s49
	s_cselect_b32 s22, s47, s48
	v_lshl_add_u64 v[214:215], s[20:21], 0, v[136:137]
	s_add_i32 m0, s19, 0xc000
	ds_read_b128 v[182:185], v153
	ds_read_b128 v[186:189], v153 offset:1024
	ds_read_b128 v[190:193], v153 offset:2048
	ds_read_b128 v[194:197], v153 offset:3072
	ds_read_b128 v[198:201], v153 offset:4096
	ds_read_b128 v[202:205], v153 offset:5120
	ds_read_b128 v[206:209], v153 offset:6144
	ds_read_b128 v[210:213], v153 offset:7168
	global_load_lds_dwordx4 v[214:215], off
	v_lshl_add_u64 v[214:215], s[20:21], 0, v[138:139]
	s_add_i32 m0, s19, 0xe000
	s_nop 0
	global_load_lds_dwordx4 v[214:215], off
	s_waitcnt vmcnt(8)
	s_waitcnt lgkmcnt(0)
	s_barrier
	s_setprio 1
	s_waitcnt lgkmcnt(0)
	v_mfma_f32_16x16x32_bf16 v[124:127], v[144:147], v[182:185], v[124:127]
	v_mfma_f32_16x16x32_bf16 v[120:123], v[158:161], v[182:185], v[120:123]
	v_mfma_f32_16x16x32_bf16 v[116:119], v[144:147], v[190:193], v[116:119]
	v_mfma_f32_16x16x32_bf16 v[108:111], v[158:161], v[190:193], v[108:111]
	v_mfma_f32_16x16x32_bf16 v[100:103], v[144:147], v[198:201], v[100:103]
	v_mfma_f32_16x16x32_bf16 v[92:95], v[158:161], v[198:201], v[92:95]
	v_mfma_f32_16x16x32_bf16 v[84:87], v[144:147], v[206:209], v[84:87]
	v_mfma_f32_16x16x32_bf16 v[76:79], v[158:161], v[206:209], v[76:79]
	v_mfma_f32_16x16x32_bf16 v[124:127], v[154:157], v[186:189], v[124:127]
	v_mfma_f32_16x16x32_bf16 v[120:123], v[162:165], v[186:189], v[120:123]
	v_mfma_f32_16x16x32_bf16 v[116:119], v[154:157], v[194:197], v[116:119]
	v_mfma_f32_16x16x32_bf16 v[108:111], v[162:165], v[194:197], v[108:111]
	v_mfma_f32_16x16x32_bf16 v[100:103], v[154:157], v[202:205], v[100:103]
	v_mfma_f32_16x16x32_bf16 v[92:95], v[162:165], v[202:205], v[92:95]
	v_mfma_f32_16x16x32_bf16 v[84:87], v[154:157], v[210:213], v[84:87]
	v_mfma_f32_16x16x32_bf16 v[76:79], v[162:165], v[210:213], v[76:79]
	s_setprio 0
	s_setprio 1
	v_mfma_f32_16x16x32_bf16 v[112:115], v[166:169], v[182:185], v[112:115]
	v_mfma_f32_16x16x32_bf16 v[104:107], v[174:177], v[182:185], v[104:107]
	v_mfma_f32_16x16x32_bf16 v[96:99], v[166:169], v[190:193], v[96:99]
	v_mfma_f32_16x16x32_bf16 v[88:91], v[174:177], v[190:193], v[88:91]
	v_mfma_f32_16x16x32_bf16 v[80:83], v[166:169], v[198:201], v[80:83]
	v_mfma_f32_16x16x32_bf16 v[72:75], v[174:177], v[198:201], v[72:75]
	v_mfma_f32_16x16x32_bf16 v[68:71], v[166:169], v[206:209], v[68:71]
	v_mfma_f32_16x16x32_bf16 v[64:67], v[174:177], v[206:209], v[64:67]
	v_mfma_f32_16x16x32_bf16 v[112:115], v[170:173], v[186:189], v[112:115]
	v_mfma_f32_16x16x32_bf16 v[104:107], v[178:181], v[186:189], v[104:107]
	v_mfma_f32_16x16x32_bf16 v[96:99], v[170:173], v[194:197], v[96:99]
	v_mfma_f32_16x16x32_bf16 v[88:91], v[178:181], v[194:197], v[88:91]
	v_mfma_f32_16x16x32_bf16 v[80:83], v[170:173], v[202:205], v[80:83]
	v_mfma_f32_16x16x32_bf16 v[72:75], v[178:181], v[202:205], v[72:75]
	v_mfma_f32_16x16x32_bf16 v[68:71], v[170:173], v[210:213], v[68:71]
	v_mfma_f32_16x16x32_bf16 v[64:67], v[178:181], v[210:213], v[64:67]
	s_setprio 0
	s_barrier
; #define PG8_STAGE(bufoff, gbase, voff) do { _Pragma("unroll") for (int _i = 0; _i < 2; ++_i) \
;         __builtin_amdgcn_global_load_lds((const unsigned*)((const char*)(gbase) + (voff)[_i]), (PG8_LAS unsigned*)(lds + (bufoff) + ldsw + _i * 8192), 16, 0, 0); } while (0)
; #define PG8_LDA(dst, b, h) do { _Pragma("unroll") for (int m = 0; m < 4; ++m) _Pragma("unroll") for (int k = 0; k < 2; ++k) dst[m][k] = *(const PG8_LAS bf16x8*)(lds + PG8_SA(b, h) + aoff + m * 2048 + k * 1024); } while (0)
; #define PG8_LDB(dst, b, h) do { _Pragma("unroll") for (int n = 0; n < 2; ++n) _Pragma("unroll") for (int k = 0; k < 2; ++k) dst[n][k] = *(const PG8_LAS bf16x8*)(lds + PG8_SB(b, h) + boff + n * 2048 + k * 1024); } while (0)
; #define PG8_MMA(ai, bj, At, Bt) do { __builtin_amdgcn_s_setprio(1); _Pragma("unroll") for (int m = 0; m < 4; ++m) _Pragma("unroll") for (int n = 0; n < 2; ++n) _Pragma("unroll") for (int k = 0; k < 2; ++k) \
;         acc[ai][bj][m][n] = __builtin_amdgcn_mfma_f32_16x16x32_bf16(Bt[n][k], At[m][k], acc[ai][bj][m][n], 0, 0, 0); __builtin_amdgcn_s_setprio(0); } while (0)
; #define PG8_WAIT_V(n) asm volatile("s_waitcnt vmcnt(" #n ")" ::: "memory")
; #define PG8_WAIT_L(n) asm volatile("s_waitcnt lgkmcnt(" #n ")" ::: "memory")
; #define PG8_BAR __builtin_amdgcn_s_barrier()
; #define PG8_SCHED __builtin_amdgcn_sched_barrier(0)
; template <class Epi, class Sched, bool ALIGN_EPI = false, bool SP2 = false>
; __device__ __forceinline__ void gemm_phase(PG8_LAS unsigned char* lds, const Gemm g, const Sched& S, const Epi& E, const int wave_in) {
;     ...
;             PG8_LDA(At, 0, 1); PG8_STAGE(PG8_SB(0, 0), b2, voffB); PG8_STAGE(PG8_SB(0, 1), b2 + hstepB, voffB); PG8_STAGE(PG8_SA(0, 0), a2, voffA);
;             PG8_WAIT_V(8); PG8_WAIT_L(0); PG8_BAR; PG8_MMA(1, 0, At, B0); PG8_MMA(1, 1, At, B1); PG8_BAR; PG8_SCHED;
;             PG8_LDB(B0, 1, 0); PG8_LDB(B1, 1, 1); PG8_SCHED; PG8_LDA(At, 1, 0); PG8_STAGE(PG8_SA(0, 1), a2 + hstepA, voffA);
;             PG8_WAIT_V(8); PG8_WAIT_L(0); PG8_BAR; PG8_MMA(0, 0, At, B0); PG8_MMA(0, 1, At, B1); PG8_BAR; PG8_SCHED;
;             PG8_LDA(At, 1, 1); PG8_STAGE(PG8_SB(1, 0), b3, voffB); PG8_STAGE(PG8_SB(1, 1), b3 + hstepB, voffB); PG8_STAGE(PG8_SA(1, 0), a3, voffA);
	s_add_i32 s51, s42, s30
	v_lshl_add_u64 v[214:215], s[22:23], 0, v[132:133]
	s_mov_b32 m0, s51
	ds_read_b128 v[182:185], v153 offset:16384
	ds_read_b128 v[186:189], v153 offset:17408
	ds_read_b128 v[190:193], v153 offset:18432
	ds_read_b128 v[194:197], v153 offset:19456
	ds_read_b128 v[198:201], v153 offset:20480
	ds_read_b128 v[202:205], v153 offset:21504
	ds_read_b128 v[206:209], v153 offset:22528
	ds_read_b128 v[210:213], v153 offset:23552
	global_load_lds_dwordx4 v[214:215], off
	s_add_i32 m0, s51, 0x2000
	s_add_u32 s52, s22, 0x80000
	v_lshl_add_u64 v[216:217], s[22:23], 0, v[128:129]
	s_addc_u32 s53, s23, 0
	s_add_i32 s51, s43, s30
	global_load_lds_dwordx4 v[216:217], off
	v_lshl_add_u64 v[218:219], s[52:53], 0, v[132:133]
	s_mov_b32 m0, s51
	v_lshl_add_u64 v[220:221], s[24:25], 0, v[130:131]
	global_load_lds_dwordx4 v[218:219], off
	v_lshl_add_u64 v[218:219], s[52:53], 0, v[128:129]
	s_add_i32 m0, s51, 0x2000
	s_nop 0
	global_load_lds_dwordx4 v[218:219], off
	v_lshl_add_u64 v[218:219], s[24:25], 0, v[134:135]
	s_mov_b32 m0, s19
	s_nop 0
	global_load_lds_dwordx4 v[218:219], off
	s_mov_b32 m0, s35
	s_nop 0
	global_load_lds_dwordx4 v[220:221], off
	s_waitcnt vmcnt(8)
	s_waitcnt lgkmcnt(0)
	s_barrier
	s_setprio 1
	s_waitcnt lgkmcnt(0)
	v_mfma_f32_16x16x32_bf16 v[60:63], v[144:147], v[182:185], v[60:63]
	v_mfma_f32_16x16x32_bf16 v[56:59], v[158:161], v[182:185], v[56:59]
	v_mfma_f32_16x16x32_bf16 v[52:55], v[144:147], v[190:193], v[52:55]
	v_mfma_f32_16x16x32_bf16 v[44:47], v[158:161], v[190:193], v[44:47]
	v_mfma_f32_16x16x32_bf16 v[36:39], v[144:147], v[198:201], v[36:39]
	v_mfma_f32_16x16x32_bf16 v[28:31], v[158:161], v[198:201], v[28:31]
	v_mfma_f32_16x16x32_bf16 v[20:23], v[144:147], v[206:209], v[20:23]
	v_mfma_f32_16x16x32_bf16 v[12:15], v[158:161], v[206:209], v[12:15]
	v_mfma_f32_16x16x32_bf16 v[60:63], v[154:157], v[186:189], v[60:63]
	v_mfma_f32_16x16x32_bf16 v[56:59], v[162:165], v[186:189], v[56:59]
	v_mfma_f32_16x16x32_bf16 v[52:55], v[154:157], v[194:197], v[52:55]
	v_mfma_f32_16x16x32_bf16 v[44:47], v[162:165], v[194:197], v[44:47]
	v_mfma_f32_16x16x32_bf16 v[36:39], v[154:157], v[202:205], v[36:39]
	v_mfma_f32_16x16x32_bf16 v[28:31], v[162:165], v[202:205], v[28:31]
	v_mfma_f32_16x16x32_bf16 v[20:23], v[154:157], v[210:213], v[20:23]
	v_mfma_f32_16x16x32_bf16 v[12:15], v[162:165], v[210:213], v[12:15]
	s_setprio 0
	s_setprio 1
	v_mfma_f32_16x16x32_bf16 v[48:51], v[166:169], v[182:185], v[48:51]
	v_mfma_f32_16x16x32_bf16 v[40:43], v[174:177], v[182:185], v[40:43]
	v_mfma_f32_16x16x32_bf16 v[32:35], v[166:169], v[190:193], v[32:35]
	v_mfma_f32_16x16x32_bf16 v[24:27], v[174:177], v[190:193], v[24:27]
	v_mfma_f32_16x16x32_bf16 v[16:19], v[166:169], v[198:201], v[16:19]
	v_mfma_f32_16x16x32_bf16 v[8:11], v[174:177], v[198:201], v[8:11]
	v_mfma_f32_16x16x32_bf16 v[4:7], v[166:169], v[206:209], v[4:7]
	v_mfma_f32_16x16x32_bf16 v[0:3], v[174:177], v[206:209], v[0:3]
	v_mfma_f32_16x16x32_bf16 v[48:51], v[170:173], v[186:189], v[48:51]
	v_mfma_f32_16x16x32_bf16 v[40:43], v[178:181], v[186:189], v[40:43]
	v_mfma_f32_16x16x32_bf16 v[32:35], v[170:173], v[194:197], v[32:35]
	v_mfma_f32_16x16x32_bf16 v[24:27], v[178:181], v[194:197], v[24:27]
	v_mfma_f32_16x16x32_bf16 v[16:19], v[170:173], v[202:205], v[16:19]
	v_mfma_f32_16x16x32_bf16 v[8:11], v[178:181], v[202:205], v[8:11]
	v_mfma_f32_16x16x32_bf16 v[4:7], v[170:173], v[210:213], v[4:7]
	v_mfma_f32_16x16x32_bf16 v[0:3], v[178:181], v[210:213], v[0:3]
	s_setprio 0
	s_barrier
	s_add_i32 s51, 0, 0x18000
	s_add_i32 s52, 0, 0x1c000
	v_add_u32_e32 v162, s51, v149
	v_add_u32_e32 v178, s52, v149
	ds_read_b128 v[144:147], v162
	ds_read_b128 v[154:157], v162 offset:1024
	ds_read_b128 v[158:161], v162 offset:2048
	ds_read_b128 v[162:165], v162 offset:3072
	ds_read_b128 v[166:169], v178
	ds_read_b128 v[170:173], v178 offset:1024
	ds_read_b128 v[174:177], v178 offset:2048
	ds_read_b128 v[178:181], v178 offset:3072
	s_add_u32 s24, s24, 0x80000
	s_addc_u32 s25, s25, 0
	s_mov_b32 m0, s36
	v_lshl_add_u64 v[222:223], s[24:25], 0, v[134:135]
	ds_read_b128 v[182:185], v153 offset:32768
	ds_read_b128 v[186:189], v153 offset:33792
	ds_read_b128 v[190:193], v153 offset:34816
	ds_read_b128 v[194:197], v153 offset:35840
	ds_read_b128 v[198:201], v153 offset:36864
	ds_read_b128 v[202:205], v153 offset:37888
	ds_read_b128 v[206:209], v153 offset:38912
	ds_read_b128 v[210:213], v153 offset:39936
	global_load_lds_dwordx4 v[222:223], off
	v_lshl_add_u64 v[222:223], s[24:25], 0, v[130:131]
	s_mov_b32 m0, s37
	s_nop 0
	global_load_lds_dwordx4 v[222:223], off
	s_waitcnt vmcnt(8)
	s_waitcnt lgkmcnt(0)
	s_barrier
; #define PG8_STAGE(bufoff, gbase, voff) do { _Pragma("unroll") for (int _i = 0; _i < 2; ++_i) \
;         __builtin_amdgcn_global_load_lds((const unsigned*)((const char*)(gbase) + (voff)[_i]), (PG8_LAS unsigned*)(lds + (bufoff) + ldsw + _i * 8192), 16, 0, 0); } while (0)
; #define PG8_LDA(dst, b, h) do { _Pragma("unroll") for (int m = 0; m < 4; ++m) _Pragma("unroll") for (int k = 0; k < 2; ++k) dst[m][k] = *(const PG8_LAS bf16x8*)(lds + PG8_SA(b, h) + aoff + m * 2048 + k * 1024); } while (0)
; #define PG8_MMA(ai, bj, At, Bt) do { __builtin_amdgcn_s_setprio(1); _Pragma("unroll") for (int m = 0; m < 4; ++m) _Pragma("unroll") for (int n = 0; n < 2; ++n) _Pragma("unroll") for (int k = 0; k < 2; ++k) \
;         acc[ai][bj][m][n] = __builtin_amdgcn_mfma_f32_16x16x32_bf16(Bt[n][k], At[m][k], acc[ai][bj][m][n], 0, 0, 0); __builtin_amdgcn_s_setprio(0); } while (0)
; #define PG8_WAIT_V(n) asm volatile("s_waitcnt vmcnt(" #n ")" ::: "memory")
; #define PG8_WAIT_L(n) asm volatile("s_waitcnt lgkmcnt(" #n ")" ::: "memory")
; #define PG8_BAR __builtin_amdgcn_s_barrier()
; #define PG8_SCHED __builtin_amdgcn_sched_barrier(0)
; template <class Epi, class Sched, bool ALIGN_EPI = false, bool SP2 = false>
; __device__ __forceinline__ void gemm_phase(PG8_LAS unsigned char* lds, const Gemm g, const Sched& S, const Epi& E, const int wave_in) {
;     ...
;             PG8_WAIT_V(8); PG8_WAIT_L(0); PG8_BAR; PG8_MMA(0, 0, At, B0); PG8_MMA(0, 1, At, B1); PG8_BAR; PG8_SCHED;
;             PG8_LDA(At, 1, 1); PG8_STAGE(PG8_SB(1, 0), b3, voffB); PG8_STAGE(PG8_SB(1, 1), b3 + hstepB, voffB); PG8_STAGE(PG8_SA(1, 0), a3, voffA);
;             PG8_WAIT_V(8); PG8_WAIT_L(0); PG8_BAR; PG8_MMA(1, 0, At, B0); PG8_MMA(1, 1, At, B1); PG8_BAR; PG8_SCHED;
;     ...
;         if constexpr (ALIGN_EPI) { if (wr == 0) PG8_BAR; }
	s_setprio 1
	s_waitcnt lgkmcnt(0)
	v_mfma_f32_16x16x32_bf16 v[124:127], v[144:147], v[182:185], v[124:127]
	v_mfma_f32_16x16x32_bf16 v[120:123], v[158:161], v[182:185], v[120:123]
	v_mfma_f32_16x16x32_bf16 v[116:119], v[144:147], v[190:193], v[116:119]
	v_mfma_f32_16x16x32_bf16 v[108:111], v[158:161], v[190:193], v[108:111]
	v_mfma_f32_16x16x32_bf16 v[100:103], v[144:147], v[198:201], v[100:103]
	v_mfma_f32_16x16x32_bf16 v[92:95], v[158:161], v[198:201], v[92:95]
	v_mfma_f32_16x16x32_bf16 v[84:87], v[144:147], v[206:209], v[84:87]
	v_mfma_f32_16x16x32_bf16 v[76:79], v[158:161], v[206:209], v[76:79]
	v_mfma_f32_16x16x32_bf16 v[124:127], v[154:157], v[186:189], v[124:127]
	v_mfma_f32_16x16x32_bf16 v[120:123], v[162:165], v[186:189], v[120:123]
	v_mfma_f32_16x16x32_bf16 v[116:119], v[154:157], v[194:197], v[116:119]
	v_mfma_f32_16x16x32_bf16 v[108:111], v[162:165], v[194:197], v[108:111]
	v_mfma_f32_16x16x32_bf16 v[100:103], v[154:157], v[202:205], v[100:103]
	v_mfma_f32_16x16x32_bf16 v[92:95], v[162:165], v[202:205], v[92:95]
	v_mfma_f32_16x16x32_bf16 v[84:87], v[154:157], v[210:213], v[84:87]
	v_mfma_f32_16x16x32_bf16 v[76:79], v[162:165], v[210:213], v[76:79]
	s_setprio 0
	s_setprio 1
	v_mfma_f32_16x16x32_bf16 v[112:115], v[166:169], v[182:185], v[112:115]
	v_mfma_f32_16x16x32_bf16 v[104:107], v[174:177], v[182:185], v[104:107]
	v_mfma_f32_16x16x32_bf16 v[96:99], v[166:169], v[190:193], v[96:99]
	v_mfma_f32_16x16x32_bf16 v[88:91], v[174:177], v[190:193], v[88:91]
	v_mfma_f32_16x16x32_bf16 v[80:83], v[166:169], v[198:201], v[80:83]
	v_mfma_f32_16x16x32_bf16 v[72:75], v[174:177], v[198:201], v[72:75]
	v_mfma_f32_16x16x32_bf16 v[68:71], v[166:169], v[206:209], v[68:71]
	v_mfma_f32_16x16x32_bf16 v[64:67], v[174:177], v[206:209], v[64:67]
	v_mfma_f32_16x16x32_bf16 v[112:115], v[170:173], v[186:189], v[112:115]
	v_mfma_f32_16x16x32_bf16 v[104:107], v[178:181], v[186:189], v[104:107]
	v_mfma_f32_16x16x32_bf16 v[96:99], v[170:173], v[194:197], v[96:99]
	v_mfma_f32_16x16x32_bf16 v[88:91], v[178:181], v[194:197], v[88:91]
	v_mfma_f32_16x16x32_bf16 v[80:83], v[170:173], v[202:205], v[80:83]
	v_mfma_f32_16x16x32_bf16 v[72:75], v[178:181], v[202:205], v[72:75]
	v_mfma_f32_16x16x32_bf16 v[68:71], v[170:173], v[210:213], v[68:71]
	v_mfma_f32_16x16x32_bf16 v[64:67], v[178:181], v[210:213], v[64:67]
	s_setprio 0
	s_barrier
	s_add_i32 s24, s51, s30
	v_lshl_add_u64 v[214:215], v[214:215], 0, s[6:7]
	s_mov_b32 m0, s24
	ds_read_b128 v[182:185], v153 offset:49152
	ds_read_b128 v[186:189], v153 offset:50176
	ds_read_b128 v[190:193], v153 offset:51200
	ds_read_b128 v[194:197], v153 offset:52224
	ds_read_b128 v[198:201], v153 offset:53248
	ds_read_b128 v[202:205], v153 offset:54272
	ds_read_b128 v[206:209], v153 offset:55296
	ds_read_b128 v[210:213], v153 offset:56320
	global_load_lds_dwordx4 v[214:215], off
	s_add_i32 m0, s24, 0x2000
	s_add_u32 s22, s22, 0x80080
	v_lshl_add_u64 v[214:215], v[216:217], 0, s[6:7]
	s_addc_u32 s23, s23, 0
	s_add_i32 s24, s52, s30
	global_load_lds_dwordx4 v[214:215], off
	v_lshl_add_u64 v[214:215], s[22:23], 0, v[132:133]
	s_mov_b32 m0, s24
	s_nop 0
	global_load_lds_dwordx4 v[214:215], off
	v_lshl_add_u64 v[214:215], s[22:23], 0, v[128:129]
	s_add_i32 m0, s24, 0x2000
	s_nop 0
	global_load_lds_dwordx4 v[214:215], off
	v_lshl_add_u64 v[214:215], v[218:219], 0, s[6:7]
	s_mov_b32 m0, s39
	s_nop 0
	global_load_lds_dwordx4 v[214:215], off
	v_lshl_add_u64 v[214:215], v[220:221], 0, s[6:7]
	s_mov_b32 m0, s40
	s_nop 0
	global_load_lds_dwordx4 v[214:215], off
	s_waitcnt vmcnt(8)
	s_waitcnt lgkmcnt(0)
	s_barrier
	s_setprio 1
	s_waitcnt lgkmcnt(0)
	v_mfma_f32_16x16x32_bf16 v[60:63], v[144:147], v[182:185], v[60:63]
	v_mfma_f32_16x16x32_bf16 v[56:59], v[158:161], v[182:185], v[56:59]
	v_mfma_f32_16x16x32_bf16 v[52:55], v[144:147], v[190:193], v[52:55]
	v_mfma_f32_16x16x32_bf16 v[44:47], v[158:161], v[190:193], v[44:47]
	v_mfma_f32_16x16x32_bf16 v[36:39], v[144:147], v[198:201], v[36:39]
	v_mfma_f32_16x16x32_bf16 v[28:31], v[158:161], v[198:201], v[28:31]
	v_mfma_f32_16x16x32_bf16 v[20:23], v[144:147], v[206:209], v[20:23]
	v_mfma_f32_16x16x32_bf16 v[12:15], v[158:161], v[206:209], v[12:15]
	v_mfma_f32_16x16x32_bf16 v[60:63], v[154:157], v[186:189], v[60:63]
	v_mfma_f32_16x16x32_bf16 v[56:59], v[162:165], v[186:189], v[56:59]
	v_mfma_f32_16x16x32_bf16 v[52:55], v[154:157], v[194:197], v[52:55]
	v_mfma_f32_16x16x32_bf16 v[44:47], v[162:165], v[194:197], v[44:47]
	v_mfma_f32_16x16x32_bf16 v[36:39], v[154:157], v[202:205], v[36:39]
	v_mfma_f32_16x16x32_bf16 v[28:31], v[162:165], v[202:205], v[28:31]
	v_mfma_f32_16x16x32_bf16 v[20:23], v[154:157], v[210:213], v[20:23]
	v_mfma_f32_16x16x32_bf16 v[12:15], v[162:165], v[210:213], v[12:15]
	s_setprio 0
	s_setprio 1
	v_mfma_f32_16x16x32_bf16 v[48:51], v[166:169], v[182:185], v[48:51]
	v_mfma_f32_16x16x32_bf16 v[40:43], v[174:177], v[182:185], v[40:43]
	v_mfma_f32_16x16x32_bf16 v[32:35], v[166:169], v[190:193], v[32:35]
	v_mfma_f32_16x16x32_bf16 v[24:27], v[174:177], v[190:193], v[24:27]
	v_mfma_f32_16x16x32_bf16 v[16:19], v[166:169], v[198:201], v[16:19]
	v_mfma_f32_16x16x32_bf16 v[8:11], v[174:177], v[198:201], v[8:11]
	v_mfma_f32_16x16x32_bf16 v[4:7], v[166:169], v[206:209], v[4:7]
	v_mfma_f32_16x16x32_bf16 v[0:3], v[174:177], v[206:209], v[0:3]
	v_mfma_f32_16x16x32_bf16 v[48:51], v[170:173], v[186:189], v[48:51]
	v_mfma_f32_16x16x32_bf16 v[40:43], v[178:181], v[186:189], v[40:43]
	v_mfma_f32_16x16x32_bf16 v[32:35], v[170:173], v[194:197], v[32:35]
	v_mfma_f32_16x16x32_bf16 v[24:27], v[178:181], v[194:197], v[24:27]
	v_mfma_f32_16x16x32_bf16 v[16:19], v[170:173], v[202:205], v[16:19]
	v_mfma_f32_16x16x32_bf16 v[8:11], v[178:181], v[202:205], v[8:11]
	v_mfma_f32_16x16x32_bf16 v[4:7], v[170:173], v[210:213], v[4:7]
	v_mfma_f32_16x16x32_bf16 v[0:3], v[178:181], v[210:213], v[0:3]
	s_setprio 0
	s_barrier
	s_add_i32 s50, s50, 2
	s_add_u32 s20, s20, 0x100
	s_addc_u32 s21, s21, 0
	s_add_u32 s48, s48, 0x100
	s_addc_u32 s49, s49, 0
	s_cmp_gt_u32 s50, 29
	s_cbranch_scc0 .LBB0_1513
	s_mov_b32 s99, 1
	s_and_b64 vcc, exec, s[8:9]
	s_cbranch_vccz .LBB0_1516
	s_barrier

;     __host__ __device__ bool next(int i, Unit& u) const {
;         const long L = (long)i * G + c; if (L >= nwg) return false;
;         int wgid = (int)L; { const int q = nwg / NXCD, r = nwg % NXCD, xcd = wgid % NXCD, off = wgid / NXCD; wgid = (xcd < r ? xcd * (q + 1) : r * (q + 1) + (xcd - r) * q) + off; }
;         const int nig = WGM * nN, gid = wgid / nig, fm = gid * WGM, gsz = (nM - fm) < WGM ? (nM - fm) : WGM;
;         u.pm = fm + ((wgid % nig) % gsz); u.pn = (wgid % nig) / gsz; return true;
; template <class Epi, class Sched, bool ALIGN_EPI = false, bool SP2 = false>
; __device__ __forceinline__ void gemm_phase(PG8_LAS unsigned char* lds, const Gemm g, const Sched& S, const Epi& E, const int wave_in) {
;     const int lane = lane_id_asm(), wid = __builtin_amdgcn_readfirstlane(wave_in), tid = wid * 64 + lane, wr = wid >> 2, wc = wid & 3, fr = lane & 15, fq = lane >> 4;
;     const int K = g.K, nt = K / BK;
;     unsigned voffA[2], voffB[2];
; #pragma unroll
;     for (int i = 0; i < 2; ++i) { int R, C; stage_rc(tid * 16 + i * 8192, R, C); const int Rb = Epi::PERM ? ((R & ~31) + perm32(R & 31)) : R;
;         voffA[i] = (unsigned)(R * g.lda + C) * 2u; voffB[i] = (unsigned)(Rb * K + C) * 2u; }
;     const size_t kstep = (size_t)(BK * 2);
;     const size_t hstepA = (size_t)HALF * g.lda * 2, hstepB = (size_t)HALF * K * 2;
;     const size_t tstepA = 2 * hstepA, tstepB = 2 * hstepB;
;     const unsigned ldsw = (unsigned)wid * 1024u;
;     const int aoff = lds_byte(wr * 64 + fr, fq * 8), boff = lds_byte(wc * 32 + fr, fq * 8);
;     ...
;     Unit cur, nxt; int ui = 0;
;     if (!S.next(0, cur)) return;
;     f32x4 acc[2][2][4][2];
; #pragma unroll
;     for (int a = 0; a < 2; ++a)
; #pragma unroll
;         for (int b = 0; b < 2; ++b)
; #pragma unroll
;             for (int m = 0; m < 4; ++m)
; #pragma unroll
;                 for (int n = 0; n < 2; ++n) acc[a][b][m][n] = (f32x4){0.f, 0.f, 0.f, 0.f};
;     bf16x8 At[4][2], B0[2][2], B1[2][2];
;     const char* cA = (const char*)g.A + (size_t)cur.pm * tstepA; const char* cB = (const char*)g.Bt + (size_t)cur.pn * tstepB;
;     S.a_ready(cur);
;     if constexpr (SP2) {
;         PG8_STAGE(PG8_SB(0, 0), cB, voffB); PG8_STAGE(PG8_SB(0, 1), cB + hstepB, voffB); PG8_STAGE(PG8_SA(0, 0), cA, voffA); PG8_STAGE(PG8_SA(0, 1), cA + hstepA, voffA);
;         if (wr == 1) PG8_BAR;
;         PG8_WAIT_V(2); PG8_BAR;
.LBB0_1815:
	s_cmp_gt_i32 s52, 20
	s_cselect_b64 s[0:1], -1, 0
	s_cmp_lt_i32 s53, 21
	s_cselect_b64 s[2:3], -1, 0
	s_or_b64 s[0:1], s[0:1], s[2:3]
	s_and_b64 vcc, exec, s[0:1]
	s_cbranch_vccnz .LBB0_1882
	s_mov_b32 s99, 0
	s_cmpk_gt_i32 s73, 0x47f
	v_mbcnt_lo_u32_b32 v10, -1, 0
	v_mbcnt_hi_u32_b32 v10, -1, v10
	s_cbranch_scc1 .LBB0_1832
	s_waitcnt lgkmcnt(0)
	s_add_u32 s34, s70, 0x41900000
	s_addc_u32 s35, s71, 0
	s_add_u32 s36, s70, 0x5600000
	s_addc_u32 s37, s71, 0
	s_lshl_b32 s38, s33, 10
	v_lshl_add_u32 v0, v10, 4, s38
	v_add_u32_e32 v1, 0x2000, v0
	v_ashrrev_i32_e32 v2, 31, v1
	v_lshrrev_b32_e32 v2, 22, v2
	v_add_u32_e32 v2, v1, v2
	v_ashrrev_i32_e32 v8, 10, v2
	v_mul_i32_i24_e32 v2, 0x400, v8
	v_sub_u32_e32 v1, v1, v2
	v_lshrrev_b32_e32 v2, 4, v1
	v_bitop3_b32 v1, v2, v1, 32 bitop3:0x6c
	v_ashrrev_i32_e32 v2, 31, v1
	v_lshrrev_b32_e32 v2, 26, v2
	v_add_u32_e32 v2, v1, v2
	v_ashrrev_i32_e32 v9, 6, v2
	v_lshlrev_b32_e32 v3, 3, v8
	v_and_b32_e32 v2, 0xffc0, v2
	v_and_b32_e32 v3, -16, v3
	v_sub_u32_e32 v1, v1, v2
	v_add_u32_e32 v3, v9, v3
	v_lshrrev_b16_e32 v2, 7, v1
	v_and_b32_e32 v4, 3, v9
	s_mov_b32 s0, 0xfffe0
	v_lshrrev_b32_e32 v5, 2, v3
	v_lshlrev_b32_e32 v6, 1, v3
	v_and_b32_e32 v2, 1, v2
	v_and_or_b32 v4, v3, s0, v4
	v_and_b32_e32 v5, 4, v5
	v_and_b32_e32 v6, 24, v6
	v_add_u16_e32 v1, v1, v2
	v_mov_b32_e32 v2, 1
	v_or3_b32 v4, v4, v5, v6
	v_lshlrev_b32_e32 v5, 5, v8
	v_ashrrev_i16_sdwa v1, v2, sext(v1) dst_sel:DWORD dst_unused:UNUSED_PAD src0_sel:DWORD src1_sel:BYTE_0
	v_and_b32_e32 v5, 32, v5
	v_bfe_i32 v11, v1, 0, 16
	v_add_lshl_u32 v1, v5, v11, 1
	v_lshl_add_u32 v144, v4, 12, v1
	v_lshl_add_u32 v146, v3, 12, v1
	v_ashrrev_i32_e32 v1, 31, v0
	v_lshrrev_b32_e32 v1, 22, v1
	v_add_u32_e32 v1, v0, v1
	v_ashrrev_i32_e32 v12, 10, v1
	v_mul_i32_i24_e32 v1, 0x400, v12
	v_sub_u32_e32 v0, v0, v1
	v_lshrrev_b32_e32 v1, 4, v0
	v_bitop3_b32 v0, v1, v0, 32 bitop3:0x6c
	v_ashrrev_i32_e32 v1, 31, v0
	v_lshrrev_b32_e32 v1, 26, v1
	v_add_u32_e32 v1, v0, v1
	v_lshlrev_b32_e32 v3, 3, v12
	v_ashrrev_i32_e32 v13, 6, v1
	v_and_b32_e32 v3, -16, v3
	v_add_u32_e32 v3, v13, v3
	v_and_b32_e32 v4, 3, v13
	s_ashr_i32 s39, s73, 31
	v_and_or_b32 v4, v3, s0, v4
	s_lshr_b32 s0, s39, 29
	s_add_i32 s0, s73, s0
	s_ashr_i32 s1, s0, 3
	s_and_b32 s0, s0, -8
	s_ashr_i32 s3, s33, 2
	s_sub_i32 s0, s73, s0
	s_cmp_lt_i32 s0, 0
	s_movk_i32 s40, 0x91
	s_cselect_b32 s2, s40, 0x90
	s_mul_i32 s0, s2, s0
	s_add_i32 s0, s0, s1
	s_ashr_i32 s1, s0, 31
	s_lshr_b32 s1, s1, 27
	s_add_i32 s1, s0, s1
	s_ashr_i32 s2, s1, 5
	s_andn2_b32 s1, s1, 31
	s_sub_i32 s0, s0, s1
	s_bfe_i32 s1, s0, 0x80000
	s_bfe_u32 s1, s1, 0x2000d
	s_add_i32 s1, s0, s1
	s_lshl_b32 s4, s2, 2
	s_bfe_i32 s2, s1, 0x80000
	s_and_b32 s1, s1, 0xfc
	s_sub_i32 s0, s0, s1
	s_sext_i32_i16 s2, s2
	s_sext_i32_i8 s0, s0
	v_lshrrev_b32_e32 v5, 2, v3
	v_lshlrev_b32_e32 v6, 1, v3
	v_and_b32_e32 v1, 0xc0, v1
	s_lshr_b32 s2, s2, 2
	s_add_i32 s24, s4, s0
	v_and_b32_e32 v5, 4, v5
	v_and_b32_e32 v6, 24, v6
	v_sub_u32_e32 v0, v0, v1
	s_ashr_i32 s25, s24, 31
	s_bfe_i64 s[4:5], s[2:3], 0x100000
	v_or3_b32 v4, v4, v5, v6
	v_lshlrev_b32_e32 v5, 5, v12
	v_ashrrev_i16_sdwa v0, v2, sext(v0) dst_sel:DWORD dst_unused:UNUSED_PAD src0_sel:DWORD src1_sel:BYTE_0
	s_lshl_b64 s[0:1], s[24:25], 20
	s_lshl_b64 s[4:5], s[4:5], 20
	v_and_b32_e32 v5, 32, v5
	v_bfe_i32 v14, v0, 0, 16
	s_add_u32 s28, s36, s4
	v_add_lshl_u32 v0, v5, v14, 1
	s_addc_u32 s29, s37, s5
	s_add_i32 s41, s38, 0
	v_lshl_add_u32 v148, v4, 12, v0
	s_add_i32 m0, s41, 0x10000
	v_lshl_add_u32 v150, v3, 12, v0
	global_load_lds_dwordx4 v148, s[28:29]
	s_add_i32 m0, s41, 0x12000
	s_add_u32 s4, s28, 0x80000
	global_load_lds_dwordx4 v144, s[28:29]
	s_addc_u32 s5, s29, 0
	s_add_i32 m0, s41, 0x14000
	v_mov_b32_e32 v149, 0
	global_load_lds_dwordx4 v148, s[4:5]
	s_add_i32 m0, s41, 0x16000
	s_add_u32 s26, s34, s0
	s_addc_u32 s27, s35, s1
	s_add_i32 s42, s41, 0x2000
	global_load_lds_dwordx4 v144, s[4:5]
	s_mov_b32 m0, s41
	s_add_u32 s0, s26, 0x80000
	global_load_lds_dwordx4 v150, s[26:27]
	s_mov_b32 m0, s42
	s_addc_u32 s1, s27, 0
	s_add_i32 s43, s41, 0x4000
	global_load_lds_dwordx4 v146, s[26:27]
	s_mov_b32 m0, s43
	s_add_i32 s44, s41, 0x6000
	global_load_lds_dwordx4 v150, s[0:1]
	s_mov_b32 m0, s44
	v_mov_b32_e32 v145, v149
	global_load_lds_dwordx4 v146, s[0:1]
	v_mov_b32_e32 v151, v149
	v_mov_b32_e32 v147, v149
	s_cmp_eq_u32 s3, 1
	s_mov_b32 s45, 0
	v_lshl_add_u64 v[6:7], s[28:29], 0, v[148:149]
	v_lshl_add_u64 v[2:3], s[28:29], 0, v[144:145]
	s_mov_b64 s[0:1], 0x80000
	v_lshl_add_u64 v[0:1], s[26:27], 0, v[150:151]
	s_cselect_b64 s[4:5], -1, 0
	s_cmp_lg_u32 s3, 1
	v_lshl_add_u64 v[4:5], s[26:27], 0, v[146:147]
	s_cbranch_scc1 .LBB0_1819
	s_barrier

; #define PG8_STAGE(bufoff, gbase, voff) do { _Pragma("unroll") for (int _i = 0; _i < 2; ++_i) \
;         __builtin_amdgcn_global_load_lds((const unsigned*)((const char*)(gbase) + (voff)[_i]), (PG8_LAS unsigned*)(lds + (bufoff) + ldsw + _i * 8192), 16, 0, 0); } while (0)
; #define PG8_LDA(dst, b, h) do { _Pragma("unroll") for (int m = 0; m < 4; ++m) _Pragma("unroll") for (int k = 0; k < 2; ++k) dst[m][k] = *(const PG8_LAS bf16x8*)(lds + PG8_SA(b, h) + aoff + m * 2048 + k * 1024); } while (0)
; #define PG8_LDB(dst, b, h) do { _Pragma("unroll") for (int n = 0; n < 2; ++n) _Pragma("unroll") for (int k = 0; k < 2; ++k) dst[n][k] = *(const PG8_LAS bf16x8*)(lds + PG8_SB(b, h) + boff + n * 2048 + k * 1024); } while (0)
; template <class Epi, class Sched, bool ALIGN_EPI = false, bool SP2 = false>
; __device__ __forceinline__ void gemm_phase(PG8_LAS unsigned char* lds, const Gemm g, const Sched& S, const Epi& E, const int wave_in) {
;     ...
;         const char* nA = has_next ? (const char*)g.A + (size_t)nxt.pm * tstepA : cA; const char* nB = has_next ? (const char*)g.Bt + (size_t)nxt.pn * tstepB : cB;
;         for (int t = 0; t < nt; t += 2) {
;             const bool last = (t == nt - 2);
;             const char* a1 = cA + (size_t)(t + 1) * kstep;
;             const char* a2 = last ? nA : cA + (size_t)(t + 2) * kstep; const char* b2 = last ? nB : cB + (size_t)(t + 2) * kstep;
;             const char* a3 = a2 + kstep; const char* b3 = b2 + kstep;
;             if (last && has_next) S.a_ready(nxt);
;             if constexpr (SP2) {
;             PG8_LDB(B0, 0, 0); PG8_LDB(B1, 0, 1); PG8_SCHED; PG8_LDA(At, 0, 0); PG8_STAGE(PG8_SA(1, 1), a1 + hstepA, voffA);
;             PG8_WAIT_V(8); PG8_WAIT_L(0); PG8_BAR; PG8_MMA(0, 0, At, B0); PG8_MMA(0, 1, At, B1); PG8_BAR; PG8_SCHED;
;             PG8_LDA(At, 0, 1); PG8_STAGE(PG8_SB(0, 0), b2, voffB); PG8_STAGE(PG8_SB(0, 1), b2 + hstepB, voffB); PG8_STAGE(PG8_SA(0, 0), a2, voffA);
;             PG8_WAIT_V(8); PG8_WAIT_L(0); PG8_BAR; PG8_MMA(1, 0, At, B0); PG8_MMA(1, 1, At, B1); PG8_BAR; PG8_SCHED;
;     ...
; #pragma unroll
;         for (int a = 0; a < 2; ++a)
; #pragma unroll
;             for (int b = 0; b < 2; ++b)
; #pragma unroll
;                 for (int m = 0; m < 4; ++m)
; #pragma unroll
;                     for (int n = 0; n < 2; ++n) acc[a][b][m][n] = (f32x4){0.f, 0.f, 0.f, 0.f};
;         cur = nxt; cA = nA; cB = nB; ++ui;
.LBB0_1824:
	s_ashr_i32 s19, s18, 31
	s_lshl_b64 s[20:21], s[18:19], 20
	s_add_u32 s20, s34, s20
	s_addc_u32 s21, s35, s21
	s_and_b64 s[22:23], s[2:3], exec
	s_cselect_b32 s19, s21, s27
	s_cselect_b32 s25, s20, s26
	s_ashr_i32 s17, s16, 31
	s_lshl_b64 s[22:23], s[16:17], 20
	s_add_u32 s22, s36, s22
	s_addc_u32 s23, s37, s23
	s_and_b64 s[30:31], s[2:3], exec
	s_cselect_b32 s17, s23, s29
	s_cselect_b32 s58, s22, s28
	s_add_u32 s26, s26, 0x80080
	s_addc_u32 s27, s27, 0
	s_add_u32 s59, s28, 0x100
	v_mov_b32_e32 v0, 0
	s_addc_u32 s60, s29, 0
	s_mov_b32 s61, -2
	v_mov_b32_e32 v1, v0
	v_mov_b32_e32 v2, v0
	v_mov_b32_e32 v3, v0
	v_mov_b32_e32 v4, v0
	v_mov_b32_e32 v5, v0
	v_mov_b32_e32 v6, v0
	v_mov_b32_e32 v7, v0
	v_mov_b32_e32 v12, v0
	v_mov_b32_e32 v13, v0
	v_mov_b32_e32 v14, v0
	v_mov_b32_e32 v15, v0
	v_mov_b32_e32 v20, v0
	v_mov_b32_e32 v21, v0
	v_mov_b32_e32 v22, v0
	v_mov_b32_e32 v23, v0
	v_mov_b32_e32 v28, v0
	v_mov_b32_e32 v29, v0
	v_mov_b32_e32 v30, v0
	v_mov_b32_e32 v31, v0
	v_mov_b32_e32 v36, v0
	v_mov_b32_e32 v37, v0
	v_mov_b32_e32 v38, v0
	v_mov_b32_e32 v39, v0
	v_mov_b32_e32 v44, v0
	v_mov_b32_e32 v45, v0
	v_mov_b32_e32 v46, v0
	v_mov_b32_e32 v47, v0
	v_mov_b32_e32 v52, v0
	v_mov_b32_e32 v53, v0
	v_mov_b32_e32 v54, v0
	v_mov_b32_e32 v55, v0
	v_mov_b32_e32 v8, v0
	v_mov_b32_e32 v9, v0
	v_mov_b32_e32 v10, v0
	v_mov_b32_e32 v11, v0
	v_mov_b32_e32 v16, v0
	v_mov_b32_e32 v17, v0
	v_mov_b32_e32 v18, v0
	v_mov_b32_e32 v19, v0
	v_mov_b32_e32 v24, v0
	v_mov_b32_e32 v25, v0
	v_mov_b32_e32 v26, v0
	v_mov_b32_e32 v27, v0
	v_mov_b32_e32 v32, v0
	v_mov_b32_e32 v33, v0
	v_mov_b32_e32 v34, v0
	v_mov_b32_e32 v35, v0
	v_mov_b32_e32 v40, v0
	v_mov_b32_e32 v41, v0
	v_mov_b32_e32 v42, v0
	v_mov_b32_e32 v43, v0
	v_mov_b32_e32 v48, v0
	v_mov_b32_e32 v49, v0
	v_mov_b32_e32 v50, v0
	v_mov_b32_e32 v51, v0
	v_mov_b32_e32 v56, v0
	v_mov_b32_e32 v57, v0
	v_mov_b32_e32 v58, v0
	v_mov_b32_e32 v59, v0
	v_mov_b32_e32 v60, v0
	v_mov_b32_e32 v61, v0
	v_mov_b32_e32 v62, v0
	v_mov_b32_e32 v63, v0
	v_mov_b32_e32 v64, v0
	v_mov_b32_e32 v65, v0
	v_mov_b32_e32 v66, v0
	v_mov_b32_e32 v67, v0
	v_mov_b32_e32 v68, v0
	v_mov_b32_e32 v69, v0
	v_mov_b32_e32 v70, v0
	v_mov_b32_e32 v71, v0
	v_mov_b32_e32 v80, v0
	v_mov_b32_e32 v81, v0
	v_mov_b32_e32 v82, v0
	v_mov_b32_e32 v83, v0
	v_mov_b32_e32 v84, v0
	v_mov_b32_e32 v85, v0
	v_mov_b32_e32 v86, v0
	v_mov_b32_e32 v87, v0
	v_mov_b32_e32 v88, v0
	v_mov_b32_e32 v89, v0
	v_mov_b32_e32 v90, v0
	v_mov_b32_e32 v91, v0
	v_mov_b32_e32 v92, v0
	v_mov_b32_e32 v93, v0
	v_mov_b32_e32 v94, v0
	v_mov_b32_e32 v95, v0
	v_mov_b32_e32 v108, v0
	v_mov_b32_e32 v109, v0
	v_mov_b32_e32 v110, v0
	v_mov_b32_e32 v111, v0
	s_waitcnt vmcnt(0)
	v_mov_b32_e32 v116, v0
	v_mov_b32_e32 v117, v0
	v_mov_b32_e32 v118, v0
	v_mov_b32_e32 v119, v0
	v_mov_b32_e32 v72, v0
	v_mov_b32_e32 v73, v0
	v_mov_b32_e32 v74, v0
	v_mov_b32_e32 v75, v0
	v_mov_b32_e32 v76, v0
	v_mov_b32_e32 v77, v0
	v_mov_b32_e32 v78, v0
	v_mov_b32_e32 v79, v0
	v_mov_b32_e32 v96, v0
	v_mov_b32_e32 v97, v0
	v_mov_b32_e32 v98, v0
	v_mov_b32_e32 v99, v0
	v_mov_b32_e32 v100, v0
	v_mov_b32_e32 v101, v0
	v_mov_b32_e32 v102, v0
	v_mov_b32_e32 v103, v0
	v_mov_b32_e32 v104, v0
	v_mov_b32_e32 v105, v0
	v_mov_b32_e32 v106, v0
	v_mov_b32_e32 v107, v0
	v_mov_b32_e32 v112, v0
	v_mov_b32_e32 v113, v0
	v_mov_b32_e32 v114, v0
	v_mov_b32_e32 v115, v0
	v_mov_b32_e32 v120, v0
	v_mov_b32_e32 v121, v0
	v_mov_b32_e32 v122, v0
	v_mov_b32_e32 v123, v0
	v_mov_b32_e32 v124, v0
	v_mov_b32_e32 v125, v0
	v_mov_b32_e32 v126, v0
	v_mov_b32_e32 v127, v0
	s_cmp_lg_u32 s99, 0
	s_cbranch_scc0 .LBB0_1825
	ds_read_b128 v[128:131], v214
	ds_read_b128 v[132:135], v214 offset:1024
	ds_read_b128 v[136:139], v214 offset:2048
	ds_read_b128 v[140:143], v214 offset:3072
	ds_read_b128 v[162:165], v215
	ds_read_b128 v[166:169], v215 offset:1024
	ds_read_b128 v[170:173], v215 offset:2048
	ds_read_b128 v[174:177], v215 offset:3072
	s_add_u32 s28, s26, 0xfff80080
	s_addc_u32 s29, s27, -1
	s_cmp_eq_u32 s61, 28
	s_cselect_b32 s31, s19, s29
	s_cselect_b32 s30, s25, s28
	s_cselect_b32 s29, s17, s60
	s_cselect_b32 s28, s58, s59
	v_lshl_add_u64 v[210:211], s[26:27], 0, v[154:155]
	s_add_i32 m0, s41, 0xc000
	ds_read_b128 v[178:181], v216
	ds_read_b128 v[182:185], v216 offset:1024
	ds_read_b128 v[186:189], v216 offset:2048
	ds_read_b128 v[190:193], v216 offset:3072
	ds_read_b128 v[194:197], v216 offset:4096
	ds_read_b128 v[198:201], v216 offset:5120
	ds_read_b128 v[202:205], v216 offset:6144
	ds_read_b128 v[206:209], v216 offset:7168
	global_load_lds_dwordx4 v[210:211], off
	v_lshl_add_u64 v[210:211], s[26:27], 0, v[156:157]
	s_add_i32 m0, s41, 0xe000
	s_nop 0
	global_load_lds_dwordx4 v[210:211], off
	s_waitcnt vmcnt(24)
	s_waitcnt lgkmcnt(0)
	s_barrier
; #define PG8_STAGE(bufoff, gbase, voff) do { _Pragma("unroll") for (int _i = 0; _i < 2; ++_i) \
;         __builtin_amdgcn_global_load_lds((const unsigned*)((const char*)(gbase) + (voff)[_i]), (PG8_LAS unsigned*)(lds + (bufoff) + ldsw + _i * 8192), 16, 0, 0); } while (0)
; #define PG8_LDA(dst, b, h) do { _Pragma("unroll") for (int m = 0; m < 4; ++m) _Pragma("unroll") for (int k = 0; k < 2; ++k) dst[m][k] = *(const PG8_LAS bf16x8*)(lds + PG8_SA(b, h) + aoff + m * 2048 + k * 1024); } while (0)
; #define PG8_LDB(dst, b, h) do { _Pragma("unroll") for (int n = 0; n < 2; ++n) _Pragma("unroll") for (int k = 0; k < 2; ++k) dst[n][k] = *(const PG8_LAS bf16x8*)(lds + PG8_SB(b, h) + boff + n * 2048 + k * 1024); } while (0)
; #define PG8_MMA(ai, bj, At, Bt) do { __builtin_amdgcn_s_setprio(1); _Pragma("unroll") for (int m = 0; m < 4; ++m) _Pragma("unroll") for (int n = 0; n < 2; ++n) _Pragma("unroll") for (int k = 0; k < 2; ++k) \
;         acc[ai][bj][m][n] = __builtin_amdgcn_mfma_f32_16x16x32_bf16(Bt[n][k], At[m][k], acc[ai][bj][m][n], 0, 0, 0); __builtin_amdgcn_s_setprio(0); } while (0)
; #define PG8_WAIT_V(n) asm volatile("s_waitcnt vmcnt(" #n ")" ::: "memory")
; #define PG8_WAIT_L(n) asm volatile("s_waitcnt lgkmcnt(" #n ")" ::: "memory")
; #define PG8_BAR __builtin_amdgcn_s_barrier()
; #define PG8_SCHED __builtin_amdgcn_sched_barrier(0)
; template <class Epi, class Sched, bool ALIGN_EPI = false, bool SP2 = false>
; __device__ __forceinline__ void gemm_phase(PG8_LAS unsigned char* lds, const Gemm g, const Sched& S, const Epi& E, const int wave_in) {
;     ...
;             PG8_WAIT_V(8); PG8_WAIT_L(0); PG8_BAR; PG8_MMA(0, 0, At, B0); PG8_MMA(0, 1, At, B1); PG8_BAR; PG8_SCHED;
;             PG8_LDA(At, 0, 1); PG8_STAGE(PG8_SB(0, 0), b2, voffB); PG8_STAGE(PG8_SB(0, 1), b2 + hstepB, voffB); PG8_STAGE(PG8_SA(0, 0), a2, voffA);
;             PG8_WAIT_V(8); PG8_WAIT_L(0); PG8_BAR; PG8_MMA(1, 0, At, B0); PG8_MMA(1, 1, At, B1); PG8_BAR; PG8_SCHED;
;             PG8_LDB(B0, 1, 0); PG8_LDB(B1, 1, 1); PG8_SCHED; PG8_LDA(At, 1, 0); PG8_STAGE(PG8_SA(0, 1), a2 + hstepA, voffA);
;             PG8_WAIT_V(8); PG8_WAIT_L(0); PG8_BAR; PG8_MMA(0, 0, At, B0); PG8_MMA(0, 1, At, B1); PG8_BAR; PG8_SCHED;
	s_setprio 1
	s_waitcnt lgkmcnt(0)
	v_mfma_f32_16x16x32_bf16 v[124:127], v[128:131], v[178:181], v[124:127]
	v_mfma_f32_16x16x32_bf16 v[120:123], v[136:139], v[178:181], v[120:123]
	v_mfma_f32_16x16x32_bf16 v[112:115], v[128:131], v[186:189], v[112:115]
	v_mfma_f32_16x16x32_bf16 v[104:107], v[136:139], v[186:189], v[104:107]
	v_mfma_f32_16x16x32_bf16 v[100:103], v[128:131], v[194:197], v[100:103]
	v_mfma_f32_16x16x32_bf16 v[96:99], v[136:139], v[194:197], v[96:99]
	v_mfma_f32_16x16x32_bf16 v[76:79], v[128:131], v[202:205], v[76:79]
	v_mfma_f32_16x16x32_bf16 v[72:75], v[136:139], v[202:205], v[72:75]
	v_mfma_f32_16x16x32_bf16 v[124:127], v[132:135], v[182:185], v[124:127]
	v_mfma_f32_16x16x32_bf16 v[120:123], v[140:143], v[182:185], v[120:123]
	v_mfma_f32_16x16x32_bf16 v[112:115], v[132:135], v[190:193], v[112:115]
	v_mfma_f32_16x16x32_bf16 v[104:107], v[140:143], v[190:193], v[104:107]
	v_mfma_f32_16x16x32_bf16 v[100:103], v[132:135], v[198:201], v[100:103]
	v_mfma_f32_16x16x32_bf16 v[96:99], v[140:143], v[198:201], v[96:99]
	v_mfma_f32_16x16x32_bf16 v[76:79], v[132:135], v[206:209], v[76:79]
	v_mfma_f32_16x16x32_bf16 v[72:75], v[140:143], v[206:209], v[72:75]
	s_setprio 0
	s_setprio 1
	v_mfma_f32_16x16x32_bf16 v[116:119], v[162:165], v[178:181], v[116:119]
	v_mfma_f32_16x16x32_bf16 v[108:111], v[170:173], v[178:181], v[108:111]
	v_mfma_f32_16x16x32_bf16 v[92:95], v[162:165], v[186:189], v[92:95]
	v_mfma_f32_16x16x32_bf16 v[88:91], v[170:173], v[186:189], v[88:91]
	v_mfma_f32_16x16x32_bf16 v[84:87], v[162:165], v[194:197], v[84:87]
	v_mfma_f32_16x16x32_bf16 v[80:83], v[170:173], v[194:197], v[80:83]
	v_mfma_f32_16x16x32_bf16 v[68:71], v[162:165], v[202:205], v[68:71]
	v_mfma_f32_16x16x32_bf16 v[64:67], v[170:173], v[202:205], v[64:67]
	v_mfma_f32_16x16x32_bf16 v[116:119], v[166:169], v[182:185], v[116:119]
	v_mfma_f32_16x16x32_bf16 v[108:111], v[174:177], v[182:185], v[108:111]
	v_mfma_f32_16x16x32_bf16 v[92:95], v[166:169], v[190:193], v[92:95]
	v_mfma_f32_16x16x32_bf16 v[88:91], v[174:177], v[190:193], v[88:91]
	v_mfma_f32_16x16x32_bf16 v[84:87], v[166:169], v[198:201], v[84:87]
	v_mfma_f32_16x16x32_bf16 v[80:83], v[174:177], v[198:201], v[80:83]
	v_mfma_f32_16x16x32_bf16 v[68:71], v[166:169], v[206:209], v[68:71]
	v_mfma_f32_16x16x32_bf16 v[64:67], v[174:177], v[206:209], v[64:67]
	s_setprio 0
	s_barrier
	s_add_i32 s62, s51, s38
	v_lshl_add_u64 v[210:211], s[28:29], 0, v[148:149]
	s_mov_b32 m0, s62
	ds_read_b128 v[178:181], v216 offset:16384
	ds_read_b128 v[182:185], v216 offset:17408
	ds_read_b128 v[186:189], v216 offset:18432
	ds_read_b128 v[190:193], v216 offset:19456
	ds_read_b128 v[194:197], v216 offset:20480
	ds_read_b128 v[198:201], v216 offset:21504
	ds_read_b128 v[202:205], v216 offset:22528
	ds_read_b128 v[206:209], v216 offset:23552
	global_load_lds_dwordx4 v[210:211], off
	s_add_i32 m0, s62, 0x2000
	s_add_u32 s62, s28, 0x80000
	v_lshl_add_u64 v[218:219], s[28:29], 0, v[144:145]
	s_addc_u32 s63, s29, 0
	s_add_i32 s64, s52, s38
	global_load_lds_dwordx4 v[218:219], off
	v_lshl_add_u64 v[220:221], s[62:63], 0, v[148:149]
	s_mov_b32 m0, s64
	v_lshl_add_u64 v[222:223], s[30:31], 0, v[146:147]
	global_load_lds_dwordx4 v[220:221], off
	v_lshl_add_u64 v[220:221], s[62:63], 0, v[144:145]
	s_add_i32 m0, s64, 0x2000
	s_nop 0
	global_load_lds_dwordx4 v[220:221], off
	v_lshl_add_u64 v[220:221], s[30:31], 0, v[150:151]
	s_mov_b32 m0, s41
	s_nop 0
	global_load_lds_dwordx4 v[220:221], off
	s_mov_b32 m0, s42
	s_nop 0
	global_load_lds_dwordx4 v[222:223], off
	s_waitcnt vmcnt(24)
	s_waitcnt lgkmcnt(0)
	s_barrier
	s_setprio 1
	s_waitcnt lgkmcnt(0)
	v_mfma_f32_16x16x32_bf16 v[60:63], v[128:131], v[178:181], v[60:63]
	v_mfma_f32_16x16x32_bf16 v[56:59], v[136:139], v[178:181], v[56:59]
	v_mfma_f32_16x16x32_bf16 v[48:51], v[128:131], v[186:189], v[48:51]
	v_mfma_f32_16x16x32_bf16 v[40:43], v[136:139], v[186:189], v[40:43]
	v_mfma_f32_16x16x32_bf16 v[32:35], v[128:131], v[194:197], v[32:35]
	v_mfma_f32_16x16x32_bf16 v[24:27], v[136:139], v[194:197], v[24:27]
	v_mfma_f32_16x16x32_bf16 v[16:19], v[128:131], v[202:205], v[16:19]
	v_mfma_f32_16x16x32_bf16 v[8:11], v[136:139], v[202:205], v[8:11]
	v_mfma_f32_16x16x32_bf16 v[60:63], v[132:135], v[182:185], v[60:63]
	v_mfma_f32_16x16x32_bf16 v[56:59], v[140:143], v[182:185], v[56:59]
	v_mfma_f32_16x16x32_bf16 v[48:51], v[132:135], v[190:193], v[48:51]
	v_mfma_f32_16x16x32_bf16 v[40:43], v[140:143], v[190:193], v[40:43]
	v_mfma_f32_16x16x32_bf16 v[32:35], v[132:135], v[198:201], v[32:35]
	v_mfma_f32_16x16x32_bf16 v[24:27], v[140:143], v[198:201], v[24:27]
	v_mfma_f32_16x16x32_bf16 v[16:19], v[132:135], v[206:209], v[16:19]
	v_mfma_f32_16x16x32_bf16 v[8:11], v[140:143], v[206:209], v[8:11]
	s_setprio 0
	s_setprio 1
	v_mfma_f32_16x16x32_bf16 v[52:55], v[162:165], v[178:181], v[52:55]
	v_mfma_f32_16x16x32_bf16 v[44:47], v[170:173], v[178:181], v[44:47]
	v_mfma_f32_16x16x32_bf16 v[36:39], v[162:165], v[186:189], v[36:39]
	v_mfma_f32_16x16x32_bf16 v[28:31], v[170:173], v[186:189], v[28:31]
	v_mfma_f32_16x16x32_bf16 v[20:23], v[162:165], v[194:197], v[20:23]
	v_mfma_f32_16x16x32_bf16 v[12:15], v[170:173], v[194:197], v[12:15]
	v_mfma_f32_16x16x32_bf16 v[4:7], v[162:165], v[202:205], v[4:7]
	v_mfma_f32_16x16x32_bf16 v[0:3], v[170:173], v[202:205], v[0:3]
	v_mfma_f32_16x16x32_bf16 v[52:55], v[166:169], v[182:185], v[52:55]
	v_mfma_f32_16x16x32_bf16 v[44:47], v[174:177], v[182:185], v[44:47]
	v_mfma_f32_16x16x32_bf16 v[36:39], v[166:169], v[190:193], v[36:39]
	v_mfma_f32_16x16x32_bf16 v[28:31], v[174:177], v[190:193], v[28:31]
	v_mfma_f32_16x16x32_bf16 v[20:23], v[166:169], v[198:201], v[20:23]
	v_mfma_f32_16x16x32_bf16 v[12:15], v[174:177], v[198:201], v[12:15]
	v_mfma_f32_16x16x32_bf16 v[4:7], v[166:169], v[206:209], v[4:7]
	v_mfma_f32_16x16x32_bf16 v[0:3], v[174:177], v[206:209], v[0:3]
	s_setprio 0
	s_barrier
; #define PG8_STAGE(bufoff, gbase, voff) do { _Pragma("unroll") for (int _i = 0; _i < 2; ++_i) \
;         __builtin_amdgcn_global_load_lds((const unsigned*)((const char*)(gbase) + (voff)[_i]), (PG8_LAS unsigned*)(lds + (bufoff) + ldsw + _i * 8192), 16, 0, 0); } while (0)
; #define PG8_LDA(dst, b, h) do { _Pragma("unroll") for (int m = 0; m < 4; ++m) _Pragma("unroll") for (int k = 0; k < 2; ++k) dst[m][k] = *(const PG8_LAS bf16x8*)(lds + PG8_SA(b, h) + aoff + m * 2048 + k * 1024); } while (0)
; #define PG8_LDB(dst, b, h) do { _Pragma("unroll") for (int n = 0; n < 2; ++n) _Pragma("unroll") for (int k = 0; k < 2; ++k) dst[n][k] = *(const PG8_LAS bf16x8*)(lds + PG8_SB(b, h) + boff + n * 2048 + k * 1024); } while (0)
; #define PG8_MMA(ai, bj, At, Bt) do { __builtin_amdgcn_s_setprio(1); _Pragma("unroll") for (int m = 0; m < 4; ++m) _Pragma("unroll") for (int n = 0; n < 2; ++n) _Pragma("unroll") for (int k = 0; k < 2; ++k) \
;         acc[ai][bj][m][n] = __builtin_amdgcn_mfma_f32_16x16x32_bf16(Bt[n][k], At[m][k], acc[ai][bj][m][n], 0, 0, 0); __builtin_amdgcn_s_setprio(0); } while (0)
; #define PG8_WAIT_V(n) asm volatile("s_waitcnt vmcnt(" #n ")" ::: "memory")
; #define PG8_WAIT_L(n) asm volatile("s_waitcnt lgkmcnt(" #n ")" ::: "memory")
; #define PG8_BAR __builtin_amdgcn_s_barrier()
; #define PG8_SCHED __builtin_amdgcn_sched_barrier(0)
; template <class Epi, class Sched, bool ALIGN_EPI = false, bool SP2 = false>
; __device__ __forceinline__ void gemm_phase(PG8_LAS unsigned char* lds, const Gemm g, const Sched& S, const Epi& E, const int wave_in) {
;     ...
;             PG8_WAIT_V(8); PG8_WAIT_L(0); PG8_BAR; PG8_MMA(1, 0, At, B0); PG8_MMA(1, 1, At, B1); PG8_BAR; PG8_SCHED;
;             PG8_LDB(B0, 1, 0); PG8_LDB(B1, 1, 1); PG8_SCHED; PG8_LDA(At, 1, 0); PG8_STAGE(PG8_SA(0, 1), a2 + hstepA, voffA);
;             PG8_WAIT_V(8); PG8_WAIT_L(0); PG8_BAR; PG8_MMA(0, 0, At, B0); PG8_MMA(0, 1, At, B1); PG8_BAR; PG8_SCHED;
;             PG8_LDA(At, 1, 1); PG8_STAGE(PG8_SB(1, 0), b3, voffB); PG8_STAGE(PG8_SB(1, 1), b3 + hstepB, voffB); PG8_STAGE(PG8_SA(1, 0), a3, voffA);
;             PG8_WAIT_V(8); PG8_WAIT_L(0); PG8_BAR; PG8_MMA(1, 0, At, B0); PG8_MMA(1, 1, At, B1); PG8_BAR; PG8_SCHED;
	s_add_i32 s62, 0, 0x18000
	s_add_i32 s63, 0, 0x1c000
	v_add_u32_e32 v140, s62, v212
	v_add_u32_e32 v174, s63, v212
	ds_read_b128 v[128:131], v140
	ds_read_b128 v[132:135], v140 offset:1024
	ds_read_b128 v[136:139], v140 offset:2048
	ds_read_b128 v[140:143], v140 offset:3072
	ds_read_b128 v[162:165], v174
	ds_read_b128 v[166:169], v174 offset:1024
	ds_read_b128 v[170:173], v174 offset:2048
	ds_read_b128 v[174:177], v174 offset:3072
	s_add_u32 s30, s30, 0x80000
	s_addc_u32 s31, s31, 0
	s_mov_b32 m0, s43
	v_lshl_add_u64 v[224:225], s[30:31], 0, v[150:151]
	ds_read_b128 v[178:181], v216 offset:32768
	ds_read_b128 v[182:185], v216 offset:33792
	ds_read_b128 v[186:189], v216 offset:34816
	ds_read_b128 v[190:193], v216 offset:35840
	ds_read_b128 v[194:197], v216 offset:36864
	ds_read_b128 v[198:201], v216 offset:37888
	ds_read_b128 v[202:205], v216 offset:38912
	ds_read_b128 v[206:209], v216 offset:39936
	global_load_lds_dwordx4 v[224:225], off
	v_lshl_add_u64 v[224:225], s[30:31], 0, v[146:147]
	s_mov_b32 m0, s44
	s_nop 0
	global_load_lds_dwordx4 v[224:225], off
	s_waitcnt vmcnt(8)
	s_waitcnt lgkmcnt(0)
	s_barrier
	s_setprio 1
	s_waitcnt lgkmcnt(0)
	v_mfma_f32_16x16x32_bf16 v[124:127], v[128:131], v[178:181], v[124:127]
	v_mfma_f32_16x16x32_bf16 v[120:123], v[136:139], v[178:181], v[120:123]
	v_mfma_f32_16x16x32_bf16 v[112:115], v[128:131], v[186:189], v[112:115]
	v_mfma_f32_16x16x32_bf16 v[104:107], v[136:139], v[186:189], v[104:107]
	v_mfma_f32_16x16x32_bf16 v[100:103], v[128:131], v[194:197], v[100:103]
	v_mfma_f32_16x16x32_bf16 v[96:99], v[136:139], v[194:197], v[96:99]
	v_mfma_f32_16x16x32_bf16 v[76:79], v[128:131], v[202:205], v[76:79]
	v_mfma_f32_16x16x32_bf16 v[72:75], v[136:139], v[202:205], v[72:75]
	v_mfma_f32_16x16x32_bf16 v[124:127], v[132:135], v[182:185], v[124:127]
	v_mfma_f32_16x16x32_bf16 v[120:123], v[140:143], v[182:185], v[120:123]
	v_mfma_f32_16x16x32_bf16 v[112:115], v[132:135], v[190:193], v[112:115]
	v_mfma_f32_16x16x32_bf16 v[104:107], v[140:143], v[190:193], v[104:107]
	v_mfma_f32_16x16x32_bf16 v[100:103], v[132:135], v[198:201], v[100:103]
	v_mfma_f32_16x16x32_bf16 v[96:99], v[140:143], v[198:201], v[96:99]
	v_mfma_f32_16x16x32_bf16 v[76:79], v[132:135], v[206:209], v[76:79]
	v_mfma_f32_16x16x32_bf16 v[72:75], v[140:143], v[206:209], v[72:75]
	s_setprio 0
	s_setprio 1
	v_mfma_f32_16x16x32_bf16 v[116:119], v[162:165], v[178:181], v[116:119]
	v_mfma_f32_16x16x32_bf16 v[108:111], v[170:173], v[178:181], v[108:111]
	v_mfma_f32_16x16x32_bf16 v[92:95], v[162:165], v[186:189], v[92:95]
	v_mfma_f32_16x16x32_bf16 v[88:91], v[170:173], v[186:189], v[88:91]
	v_mfma_f32_16x16x32_bf16 v[84:87], v[162:165], v[194:197], v[84:87]
	v_mfma_f32_16x16x32_bf16 v[80:83], v[170:173], v[194:197], v[80:83]
	v_mfma_f32_16x16x32_bf16 v[68:71], v[162:165], v[202:205], v[68:71]
	v_mfma_f32_16x16x32_bf16 v[64:67], v[170:173], v[202:205], v[64:67]
	v_mfma_f32_16x16x32_bf16 v[116:119], v[166:169], v[182:185], v[116:119]
	v_mfma_f32_16x16x32_bf16 v[108:111], v[174:177], v[182:185], v[108:111]
	v_mfma_f32_16x16x32_bf16 v[92:95], v[166:169], v[190:193], v[92:95]
	v_mfma_f32_16x16x32_bf16 v[88:91], v[174:177], v[190:193], v[88:91]
	v_mfma_f32_16x16x32_bf16 v[84:87], v[166:169], v[198:201], v[84:87]
	v_mfma_f32_16x16x32_bf16 v[80:83], v[174:177], v[198:201], v[80:83]
	v_mfma_f32_16x16x32_bf16 v[68:71], v[166:169], v[206:209], v[68:71]
	v_mfma_f32_16x16x32_bf16 v[64:67], v[174:177], v[206:209], v[64:67]
	s_setprio 0
	s_barrier
	s_add_i32 s30, s62, s38
	v_lshl_add_u64 v[210:211], v[210:211], 0, s[6:7]
	s_mov_b32 m0, s30
	ds_read_b128 v[178:181], v216 offset:49152
	ds_read_b128 v[182:185], v216 offset:50176
	ds_read_b128 v[186:189], v216 offset:51200
	ds_read_b128 v[190:193], v216 offset:52224
	ds_read_b128 v[194:197], v216 offset:53248
	ds_read_b128 v[198:201], v216 offset:54272
	ds_read_b128 v[202:205], v216 offset:55296
	ds_read_b128 v[206:209], v216 offset:56320
	global_load_lds_dwordx4 v[210:211], off
	s_add_i32 m0, s30, 0x2000
	s_add_u32 s28, s28, 0x80080
	v_lshl_add_u64 v[210:211], v[218:219], 0, s[6:7]
	s_addc_u32 s29, s29, 0
	s_add_i32 s30, s63, s38
	global_load_lds_dwordx4 v[210:211], off
	v_lshl_add_u64 v[210:211], s[28:29], 0, v[148:149]
	s_mov_b32 m0, s30
	s_nop 0
	global_load_lds_dwordx4 v[210:211], off
	v_lshl_add_u64 v[210:211], s[28:29], 0, v[144:145]
	s_add_i32 m0, s30, 0x2000
	s_nop 0
	global_load_lds_dwordx4 v[210:211], off
	v_lshl_add_u64 v[210:211], v[220:221], 0, s[6:7]
	s_mov_b32 m0, s48
	s_nop 0
	global_load_lds_dwordx4 v[210:211], off
	v_lshl_add_u64 v[210:211], v[222:223], 0, s[6:7]
	s_mov_b32 m0, s49
	s_nop 0
	global_load_lds_dwordx4 v[210:211], off
	s_waitcnt vmcnt(8)
	s_waitcnt lgkmcnt(0)
	s_barrier
; #define PG8_STAGE(bufoff, gbase, voff) do { _Pragma("unroll") for (int _i = 0; _i < 2; ++_i) \
;         __builtin_amdgcn_global_load_lds((const unsigned*)((const char*)(gbase) + (voff)[_i]), (PG8_LAS unsigned*)(lds + (bufoff) + ldsw + _i * 8192), 16, 0, 0); } while (0)
; #define PG8_LDA(dst, b, h) do { _Pragma("unroll") for (int m = 0; m < 4; ++m) _Pragma("unroll") for (int k = 0; k < 2; ++k) dst[m][k] = *(const PG8_LAS bf16x8*)(lds + PG8_SA(b, h) + aoff + m * 2048 + k * 1024); } while (0)
; #define PG8_LDB(dst, b, h) do { _Pragma("unroll") for (int n = 0; n < 2; ++n) _Pragma("unroll") for (int k = 0; k < 2; ++k) dst[n][k] = *(const PG8_LAS bf16x8*)(lds + PG8_SB(b, h) + boff + n * 2048 + k * 1024); } while (0)
; #define PG8_MMA(ai, bj, At, Bt) do { __builtin_amdgcn_s_setprio(1); _Pragma("unroll") for (int m = 0; m < 4; ++m) _Pragma("unroll") for (int n = 0; n < 2; ++n) _Pragma("unroll") for (int k = 0; k < 2; ++k) \
;         acc[ai][bj][m][n] = __builtin_amdgcn_mfma_f32_16x16x32_bf16(Bt[n][k], At[m][k], acc[ai][bj][m][n], 0, 0, 0); __builtin_amdgcn_s_setprio(0); } while (0)
; template <class Epi, class Sched, bool ALIGN_EPI = false, bool SP2 = false>
; __device__ __forceinline__ void gemm_phase(PG8_LAS unsigned char* lds, const Gemm g, const Sched& S, const Epi& E, const int wave_in) {
;     ...
;         for (int t = 0; t < nt; t += 2) {
;             const bool last = (t == nt - 2);
;             const char* a1 = cA + (size_t)(t + 1) * kstep;
;             const char* a2 = last ? nA : cA + (size_t)(t + 2) * kstep; const char* b2 = last ? nB : cB + (size_t)(t + 2) * kstep;
;             const char* a3 = a2 + kstep; const char* b3 = b2 + kstep;
;             if (last && has_next) S.a_ready(nxt);
;             if constexpr (SP2) {
;             PG8_LDB(B0, 0, 0); PG8_LDB(B1, 0, 1); PG8_SCHED; PG8_LDA(At, 0, 0); PG8_STAGE(PG8_SA(1, 1), a1 + hstepA, voffA);
;             PG8_WAIT_V(8); PG8_WAIT_L(0); PG8_BAR; PG8_MMA(0, 0, At, B0); PG8_MMA(0, 1, At, B1); PG8_BAR; PG8_SCHED;
;             PG8_LDA(At, 0, 1); PG8_STAGE(PG8_SB(0, 0), b2, voffB); PG8_STAGE(PG8_SB(0, 1), b2 + hstepB, voffB); PG8_STAGE(PG8_SA(0, 0), a2, voffA);
;             PG8_WAIT_V(8); PG8_WAIT_L(0); PG8_BAR; PG8_MMA(1, 0, At, B0); PG8_MMA(1, 1, At, B1); PG8_BAR; PG8_SCHED;
;     ...
;             PG8_WAIT_V(8); PG8_WAIT_L(0); PG8_BAR; PG8_MMA(1, 0, At, B0); PG8_MMA(1, 1, At, B1); PG8_BAR; PG8_SCHED;
	s_setprio 1
	s_waitcnt lgkmcnt(0)
	v_mfma_f32_16x16x32_bf16 v[60:63], v[128:131], v[178:181], v[60:63]
	v_mfma_f32_16x16x32_bf16 v[56:59], v[136:139], v[178:181], v[56:59]
	v_mfma_f32_16x16x32_bf16 v[48:51], v[128:131], v[186:189], v[48:51]
	v_mfma_f32_16x16x32_bf16 v[40:43], v[136:139], v[186:189], v[40:43]
	v_mfma_f32_16x16x32_bf16 v[32:35], v[128:131], v[194:197], v[32:35]
	v_mfma_f32_16x16x32_bf16 v[24:27], v[136:139], v[194:197], v[24:27]
	v_mfma_f32_16x16x32_bf16 v[16:19], v[128:131], v[202:205], v[16:19]
	v_mfma_f32_16x16x32_bf16 v[8:11], v[136:139], v[202:205], v[8:11]
	v_mfma_f32_16x16x32_bf16 v[60:63], v[132:135], v[182:185], v[60:63]
	v_mfma_f32_16x16x32_bf16 v[56:59], v[140:143], v[182:185], v[56:59]
	v_mfma_f32_16x16x32_bf16 v[48:51], v[132:135], v[190:193], v[48:51]
	v_mfma_f32_16x16x32_bf16 v[40:43], v[140:143], v[190:193], v[40:43]
	v_mfma_f32_16x16x32_bf16 v[32:35], v[132:135], v[198:201], v[32:35]
	v_mfma_f32_16x16x32_bf16 v[24:27], v[140:143], v[198:201], v[24:27]
	v_mfma_f32_16x16x32_bf16 v[16:19], v[132:135], v[206:209], v[16:19]
	v_mfma_f32_16x16x32_bf16 v[8:11], v[140:143], v[206:209], v[8:11]
	s_setprio 0
	s_setprio 1
	v_mfma_f32_16x16x32_bf16 v[52:55], v[162:165], v[178:181], v[52:55]
	v_mfma_f32_16x16x32_bf16 v[44:47], v[170:173], v[178:181], v[44:47]
	v_mfma_f32_16x16x32_bf16 v[36:39], v[162:165], v[186:189], v[36:39]
	v_mfma_f32_16x16x32_bf16 v[28:31], v[170:173], v[186:189], v[28:31]
	v_mfma_f32_16x16x32_bf16 v[20:23], v[162:165], v[194:197], v[20:23]
	v_mfma_f32_16x16x32_bf16 v[12:15], v[170:173], v[194:197], v[12:15]
	v_mfma_f32_16x16x32_bf16 v[4:7], v[162:165], v[202:205], v[4:7]
	v_mfma_f32_16x16x32_bf16 v[0:3], v[170:173], v[202:205], v[0:3]
	v_mfma_f32_16x16x32_bf16 v[52:55], v[166:169], v[182:185], v[52:55]
	v_mfma_f32_16x16x32_bf16 v[44:47], v[174:177], v[182:185], v[44:47]
	v_mfma_f32_16x16x32_bf16 v[36:39], v[166:169], v[190:193], v[36:39]
	v_mfma_f32_16x16x32_bf16 v[28:31], v[174:177], v[190:193], v[28:31]
	v_mfma_f32_16x16x32_bf16 v[20:23], v[166:169], v[198:201], v[20:23]
	v_mfma_f32_16x16x32_bf16 v[12:15], v[174:177], v[198:201], v[12:15]
	v_mfma_f32_16x16x32_bf16 v[4:7], v[166:169], v[206:209], v[4:7]
	v_mfma_f32_16x16x32_bf16 v[0:3], v[174:177], v[206:209], v[0:3]
	s_setprio 0
	s_barrier
	s_add_i32 s61, s61, 2
	s_add_u32 s26, s26, 0x100
	s_addc_u32 s27, s27, 0
	s_add_u32 s59, s59, 0x100
	s_addc_u32 s60, s60, 0
	s_cmp_gt_u32 s61, 29
	s_cbranch_scc0 .LBB0_1825
.LBB0_1825:
	ds_read_b128 v[128:131], v214
	ds_read_b128 v[132:135], v214 offset:1024
	ds_read_b128 v[136:139], v214 offset:2048
	ds_read_b128 v[140:143], v214 offset:3072
	ds_read_b128 v[162:165], v215
	ds_read_b128 v[166:169], v215 offset:1024
	ds_read_b128 v[170:173], v215 offset:2048
	ds_read_b128 v[174:177], v215 offset:3072
	s_add_u32 s28, s26, 0xfff80080
	s_addc_u32 s29, s27, -1
	s_cmp_eq_u32 s61, 28
	s_cselect_b32 s31, s19, s29
	s_cselect_b32 s30, s25, s28
	s_cselect_b32 s29, s17, s60
	s_cselect_b32 s28, s58, s59
	v_lshl_add_u64 v[210:211], s[26:27], 0, v[154:155]
	s_add_i32 m0, s41, 0xc000
	ds_read_b128 v[178:181], v216
	ds_read_b128 v[182:185], v216 offset:1024
	ds_read_b128 v[186:189], v216 offset:2048
	ds_read_b128 v[190:193], v216 offset:3072
	ds_read_b128 v[194:197], v216 offset:4096
	ds_read_b128 v[198:201], v216 offset:5120
	ds_read_b128 v[202:205], v216 offset:6144
	ds_read_b128 v[206:209], v216 offset:7168
	global_load_lds_dwordx4 v[210:211], off
	v_lshl_add_u64 v[210:211], s[26:27], 0, v[156:157]
	s_add_i32 m0, s41, 0xe000
	s_nop 0
	global_load_lds_dwordx4 v[210:211], off
	s_waitcnt vmcnt(8)
	s_waitcnt lgkmcnt(0)
	s_barrier
	s_setprio 1
	s_waitcnt lgkmcnt(0)
	v_mfma_f32_16x16x32_bf16 v[124:127], v[128:131], v[178:181], v[124:127]
	v_mfma_f32_16x16x32_bf16 v[120:123], v[136:139], v[178:181], v[120:123]
	v_mfma_f32_16x16x32_bf16 v[112:115], v[128:131], v[186:189], v[112:115]
	v_mfma_f32_16x16x32_bf16 v[104:107], v[136:139], v[186:189], v[104:107]
	v_mfma_f32_16x16x32_bf16 v[100:103], v[128:131], v[194:197], v[100:103]
	v_mfma_f32_16x16x32_bf16 v[96:99], v[136:139], v[194:197], v[96:99]
	v_mfma_f32_16x16x32_bf16 v[76:79], v[128:131], v[202:205], v[76:79]
	v_mfma_f32_16x16x32_bf16 v[72:75], v[136:139], v[202:205], v[72:75]
	v_mfma_f32_16x16x32_bf16 v[124:127], v[132:135], v[182:185], v[124:127]
	v_mfma_f32_16x16x32_bf16 v[120:123], v[140:143], v[182:185], v[120:123]
	v_mfma_f32_16x16x32_bf16 v[112:115], v[132:135], v[190:193], v[112:115]
	v_mfma_f32_16x16x32_bf16 v[104:107], v[140:143], v[190:193], v[104:107]
	v_mfma_f32_16x16x32_bf16 v[100:103], v[132:135], v[198:201], v[100:103]
	v_mfma_f32_16x16x32_bf16 v[96:99], v[140:143], v[198:201], v[96:99]
	v_mfma_f32_16x16x32_bf16 v[76:79], v[132:135], v[206:209], v[76:79]
	v_mfma_f32_16x16x32_bf16 v[72:75], v[140:143], v[206:209], v[72:75]
	s_setprio 0
	s_setprio 1
	v_mfma_f32_16x16x32_bf16 v[116:119], v[162:165], v[178:181], v[116:119]
	v_mfma_f32_16x16x32_bf16 v[108:111], v[170:173], v[178:181], v[108:111]
	v_mfma_f32_16x16x32_bf16 v[92:95], v[162:165], v[186:189], v[92:95]
	v_mfma_f32_16x16x32_bf16 v[88:91], v[170:173], v[186:189], v[88:91]
	v_mfma_f32_16x16x32_bf16 v[84:87], v[162:165], v[194:197], v[84:87]
	v_mfma_f32_16x16x32_bf16 v[80:83], v[170:173], v[194:197], v[80:83]
	v_mfma_f32_16x16x32_bf16 v[68:71], v[162:165], v[202:205], v[68:71]
	v_mfma_f32_16x16x32_bf16 v[64:67], v[170:173], v[202:205], v[64:67]
	v_mfma_f32_16x16x32_bf16 v[116:119], v[166:169], v[182:185], v[116:119]
	v_mfma_f32_16x16x32_bf16 v[108:111], v[174:177], v[182:185], v[108:111]
	v_mfma_f32_16x16x32_bf16 v[92:95], v[166:169], v[190:193], v[92:95]
	v_mfma_f32_16x16x32_bf16 v[88:91], v[174:177], v[190:193], v[88:91]
	v_mfma_f32_16x16x32_bf16 v[84:87], v[166:169], v[198:201], v[84:87]
	v_mfma_f32_16x16x32_bf16 v[80:83], v[174:177], v[198:201], v[80:83]
	v_mfma_f32_16x16x32_bf16 v[68:71], v[166:169], v[206:209], v[68:71]
	v_mfma_f32_16x16x32_bf16 v[64:67], v[174:177], v[206:209], v[64:67]
	s_setprio 0
	s_barrier
; #define PG8_STAGE(bufoff, gbase, voff) do { _Pragma("unroll") for (int _i = 0; _i < 2; ++_i) \
;         __builtin_amdgcn_global_load_lds((const unsigned*)((const char*)(gbase) + (voff)[_i]), (PG8_LAS unsigned*)(lds + (bufoff) + ldsw + _i * 8192), 16, 0, 0); } while (0)
; #define PG8_LDA(dst, b, h) do { _Pragma("unroll") for (int m = 0; m < 4; ++m) _Pragma("unroll") for (int k = 0; k < 2; ++k) dst[m][k] = *(const PG8_LAS bf16x8*)(lds + PG8_SA(b, h) + aoff + m * 2048 + k * 1024); } while (0)
; #define PG8_LDB(dst, b, h) do { _Pragma("unroll") for (int n = 0; n < 2; ++n) _Pragma("unroll") for (int k = 0; k < 2; ++k) dst[n][k] = *(const PG8_LAS bf16x8*)(lds + PG8_SB(b, h) + boff + n * 2048 + k * 1024); } while (0)
; #define PG8_MMA(ai, bj, At, Bt) do { __builtin_amdgcn_s_setprio(1); _Pragma("unroll") for (int m = 0; m < 4; ++m) _Pragma("unroll") for (int n = 0; n < 2; ++n) _Pragma("unroll") for (int k = 0; k < 2; ++k) \
;         acc[ai][bj][m][n] = __builtin_amdgcn_mfma_f32_16x16x32_bf16(Bt[n][k], At[m][k], acc[ai][bj][m][n], 0, 0, 0); __builtin_amdgcn_s_setprio(0); } while (0)
; #define PG8_WAIT_V(n) asm volatile("s_waitcnt vmcnt(" #n ")" ::: "memory")
; #define PG8_WAIT_L(n) asm volatile("s_waitcnt lgkmcnt(" #n ")" ::: "memory")
; #define PG8_BAR __builtin_amdgcn_s_barrier()
; #define PG8_SCHED __builtin_amdgcn_sched_barrier(0)
; template <class Epi, class Sched, bool ALIGN_EPI = false, bool SP2 = false>
; __device__ __forceinline__ void gemm_phase(PG8_LAS unsigned char* lds, const Gemm g, const Sched& S, const Epi& E, const int wave_in) {
;     ...
;             PG8_LDA(At, 0, 1); PG8_STAGE(PG8_SB(0, 0), b2, voffB); PG8_STAGE(PG8_SB(0, 1), b2 + hstepB, voffB); PG8_STAGE(PG8_SA(0, 0), a2, voffA);
;             PG8_WAIT_V(8); PG8_WAIT_L(0); PG8_BAR; PG8_MMA(1, 0, At, B0); PG8_MMA(1, 1, At, B1); PG8_BAR; PG8_SCHED;
;             PG8_LDB(B0, 1, 0); PG8_LDB(B1, 1, 1); PG8_SCHED; PG8_LDA(At, 1, 0); PG8_STAGE(PG8_SA(0, 1), a2 + hstepA, voffA);
;             PG8_WAIT_V(8); PG8_WAIT_L(0); PG8_BAR; PG8_MMA(0, 0, At, B0); PG8_MMA(0, 1, At, B1); PG8_BAR; PG8_SCHED;
;             PG8_LDA(At, 1, 1); PG8_STAGE(PG8_SB(1, 0), b3, voffB); PG8_STAGE(PG8_SB(1, 1), b3 + hstepB, voffB); PG8_STAGE(PG8_SA(1, 0), a3, voffA);
	s_add_i32 s62, s51, s38
	v_lshl_add_u64 v[210:211], s[28:29], 0, v[148:149]
	s_mov_b32 m0, s62
	ds_read_b128 v[178:181], v216 offset:16384
	ds_read_b128 v[182:185], v216 offset:17408
	ds_read_b128 v[186:189], v216 offset:18432
	ds_read_b128 v[190:193], v216 offset:19456
	ds_read_b128 v[194:197], v216 offset:20480
	ds_read_b128 v[198:201], v216 offset:21504
	ds_read_b128 v[202:205], v216 offset:22528
	ds_read_b128 v[206:209], v216 offset:23552
	global_load_lds_dwordx4 v[210:211], off
	s_add_i32 m0, s62, 0x2000
	s_add_u32 s62, s28, 0x80000
	v_lshl_add_u64 v[218:219], s[28:29], 0, v[144:145]
	s_addc_u32 s63, s29, 0
	s_add_i32 s64, s52, s38
	global_load_lds_dwordx4 v[218:219], off
	v_lshl_add_u64 v[220:221], s[62:63], 0, v[148:149]
	s_mov_b32 m0, s64
	v_lshl_add_u64 v[222:223], s[30:31], 0, v[146:147]
	global_load_lds_dwordx4 v[220:221], off
	v_lshl_add_u64 v[220:221], s[62:63], 0, v[144:145]
	s_add_i32 m0, s64, 0x2000
	s_nop 0
	global_load_lds_dwordx4 v[220:221], off
	v_lshl_add_u64 v[220:221], s[30:31], 0, v[150:151]
	s_mov_b32 m0, s41
	s_nop 0
	global_load_lds_dwordx4 v[220:221], off
	s_mov_b32 m0, s42
	s_nop 0
	global_load_lds_dwordx4 v[222:223], off
	s_waitcnt vmcnt(8)
	s_waitcnt lgkmcnt(0)
	s_barrier
	s_setprio 1
	s_waitcnt lgkmcnt(0)
	v_mfma_f32_16x16x32_bf16 v[60:63], v[128:131], v[178:181], v[60:63]
	v_mfma_f32_16x16x32_bf16 v[56:59], v[136:139], v[178:181], v[56:59]
	v_mfma_f32_16x16x32_bf16 v[48:51], v[128:131], v[186:189], v[48:51]
	v_mfma_f32_16x16x32_bf16 v[40:43], v[136:139], v[186:189], v[40:43]
	v_mfma_f32_16x16x32_bf16 v[32:35], v[128:131], v[194:197], v[32:35]
	v_mfma_f32_16x16x32_bf16 v[24:27], v[136:139], v[194:197], v[24:27]
	v_mfma_f32_16x16x32_bf16 v[16:19], v[128:131], v[202:205], v[16:19]
	v_mfma_f32_16x16x32_bf16 v[8:11], v[136:139], v[202:205], v[8:11]
	v_mfma_f32_16x16x32_bf16 v[60:63], v[132:135], v[182:185], v[60:63]
	v_mfma_f32_16x16x32_bf16 v[56:59], v[140:143], v[182:185], v[56:59]
	v_mfma_f32_16x16x32_bf16 v[48:51], v[132:135], v[190:193], v[48:51]
	v_mfma_f32_16x16x32_bf16 v[40:43], v[140:143], v[190:193], v[40:43]
	v_mfma_f32_16x16x32_bf16 v[32:35], v[132:135], v[198:201], v[32:35]
	v_mfma_f32_16x16x32_bf16 v[24:27], v[140:143], v[198:201], v[24:27]
	v_mfma_f32_16x16x32_bf16 v[16:19], v[132:135], v[206:209], v[16:19]
	v_mfma_f32_16x16x32_bf16 v[8:11], v[140:143], v[206:209], v[8:11]
	s_setprio 0
	s_setprio 1
	v_mfma_f32_16x16x32_bf16 v[52:55], v[162:165], v[178:181], v[52:55]
	v_mfma_f32_16x16x32_bf16 v[44:47], v[170:173], v[178:181], v[44:47]
	v_mfma_f32_16x16x32_bf16 v[36:39], v[162:165], v[186:189], v[36:39]
	v_mfma_f32_16x16x32_bf16 v[28:31], v[170:173], v[186:189], v[28:31]
	v_mfma_f32_16x16x32_bf16 v[20:23], v[162:165], v[194:197], v[20:23]
	v_mfma_f32_16x16x32_bf16 v[12:15], v[170:173], v[194:197], v[12:15]
	v_mfma_f32_16x16x32_bf16 v[4:7], v[162:165], v[202:205], v[4:7]
	v_mfma_f32_16x16x32_bf16 v[0:3], v[170:173], v[202:205], v[0:3]
	v_mfma_f32_16x16x32_bf16 v[52:55], v[166:169], v[182:185], v[52:55]
	v_mfma_f32_16x16x32_bf16 v[44:47], v[174:177], v[182:185], v[44:47]
	v_mfma_f32_16x16x32_bf16 v[36:39], v[166:169], v[190:193], v[36:39]
	v_mfma_f32_16x16x32_bf16 v[28:31], v[174:177], v[190:193], v[28:31]
	v_mfma_f32_16x16x32_bf16 v[20:23], v[166:169], v[198:201], v[20:23]
	v_mfma_f32_16x16x32_bf16 v[12:15], v[174:177], v[198:201], v[12:15]
	v_mfma_f32_16x16x32_bf16 v[4:7], v[166:169], v[206:209], v[4:7]
	v_mfma_f32_16x16x32_bf16 v[0:3], v[174:177], v[206:209], v[0:3]
	s_setprio 0
	s_barrier
	s_add_i32 s62, 0, 0x18000
	s_add_i32 s63, 0, 0x1c000
	v_add_u32_e32 v140, s62, v212
	v_add_u32_e32 v174, s63, v212
	ds_read_b128 v[128:131], v140
	ds_read_b128 v[132:135], v140 offset:1024
	ds_read_b128 v[136:139], v140 offset:2048
	ds_read_b128 v[140:143], v140 offset:3072
	ds_read_b128 v[162:165], v174
	ds_read_b128 v[166:169], v174 offset:1024
	ds_read_b128 v[170:173], v174 offset:2048
	ds_read_b128 v[174:177], v174 offset:3072
	s_add_u32 s30, s30, 0x80000
	s_addc_u32 s31, s31, 0
	s_mov_b32 m0, s43
	v_lshl_add_u64 v[224:225], s[30:31], 0, v[150:151]
	ds_read_b128 v[178:181], v216 offset:32768
	ds_read_b128 v[182:185], v216 offset:33792
	ds_read_b128 v[186:189], v216 offset:34816
	ds_read_b128 v[190:193], v216 offset:35840
	ds_read_b128 v[194:197], v216 offset:36864
	ds_read_b128 v[198:201], v216 offset:37888
	ds_read_b128 v[202:205], v216 offset:38912
	ds_read_b128 v[206:209], v216 offset:39936
	global_load_lds_dwordx4 v[224:225], off
	v_lshl_add_u64 v[224:225], s[30:31], 0, v[146:147]
	s_mov_b32 m0, s44
	s_nop 0
	global_load_lds_dwordx4 v[224:225], off
	s_waitcnt vmcnt(8)
	s_waitcnt lgkmcnt(0)
	s_barrier
; #define PG8_STAGE(bufoff, gbase, voff) do { _Pragma("unroll") for (int _i = 0; _i < 2; ++_i) \
;         __builtin_amdgcn_global_load_lds((const unsigned*)((const char*)(gbase) + (voff)[_i]), (PG8_LAS unsigned*)(lds + (bufoff) + ldsw + _i * 8192), 16, 0, 0); } while (0)
; #define PG8_LDA(dst, b, h) do { _Pragma("unroll") for (int m = 0; m < 4; ++m) _Pragma("unroll") for (int k = 0; k < 2; ++k) dst[m][k] = *(const PG8_LAS bf16x8*)(lds + PG8_SA(b, h) + aoff + m * 2048 + k * 1024); } while (0)
; #define PG8_MMA(ai, bj, At, Bt) do { __builtin_amdgcn_s_setprio(1); _Pragma("unroll") for (int m = 0; m < 4; ++m) _Pragma("unroll") for (int n = 0; n < 2; ++n) _Pragma("unroll") for (int k = 0; k < 2; ++k) \
;         acc[ai][bj][m][n] = __builtin_amdgcn_mfma_f32_16x16x32_bf16(Bt[n][k], At[m][k], acc[ai][bj][m][n], 0, 0, 0); __builtin_amdgcn_s_setprio(0); } while (0)
; #define PG8_WAIT_V(n) asm volatile("s_waitcnt vmcnt(" #n ")" ::: "memory")
; #define PG8_WAIT_L(n) asm volatile("s_waitcnt lgkmcnt(" #n ")" ::: "memory")
; #define PG8_BAR __builtin_amdgcn_s_barrier()
; #define PG8_SCHED __builtin_amdgcn_sched_barrier(0)
; template <class Epi, class Sched, bool ALIGN_EPI = false, bool SP2 = false>
; __device__ __forceinline__ void gemm_phase(PG8_LAS unsigned char* lds, const Gemm g, const Sched& S, const Epi& E, const int wave_in) {
;     ...
;             PG8_WAIT_V(8); PG8_WAIT_L(0); PG8_BAR; PG8_MMA(0, 0, At, B0); PG8_MMA(0, 1, At, B1); PG8_BAR; PG8_SCHED;
;             PG8_LDA(At, 1, 1); PG8_STAGE(PG8_SB(1, 0), b3, voffB); PG8_STAGE(PG8_SB(1, 1), b3 + hstepB, voffB); PG8_STAGE(PG8_SA(1, 0), a3, voffA);
;             PG8_WAIT_V(8); PG8_WAIT_L(0); PG8_BAR; PG8_MMA(1, 0, At, B0); PG8_MMA(1, 1, At, B1); PG8_BAR; PG8_SCHED;
;     ...
;         if constexpr (ALIGN_EPI) { if (wr == 0) PG8_BAR; }
	s_setprio 1
	s_waitcnt lgkmcnt(0)
	v_mfma_f32_16x16x32_bf16 v[124:127], v[128:131], v[178:181], v[124:127]
	v_mfma_f32_16x16x32_bf16 v[120:123], v[136:139], v[178:181], v[120:123]
	v_mfma_f32_16x16x32_bf16 v[112:115], v[128:131], v[186:189], v[112:115]
	v_mfma_f32_16x16x32_bf16 v[104:107], v[136:139], v[186:189], v[104:107]
	v_mfma_f32_16x16x32_bf16 v[100:103], v[128:131], v[194:197], v[100:103]
	v_mfma_f32_16x16x32_bf16 v[96:99], v[136:139], v[194:197], v[96:99]
	v_mfma_f32_16x16x32_bf16 v[76:79], v[128:131], v[202:205], v[76:79]
	v_mfma_f32_16x16x32_bf16 v[72:75], v[136:139], v[202:205], v[72:75]
	v_mfma_f32_16x16x32_bf16 v[124:127], v[132:135], v[182:185], v[124:127]
	v_mfma_f32_16x16x32_bf16 v[120:123], v[140:143], v[182:185], v[120:123]
	v_mfma_f32_16x16x32_bf16 v[112:115], v[132:135], v[190:193], v[112:115]
	v_mfma_f32_16x16x32_bf16 v[104:107], v[140:143], v[190:193], v[104:107]
	v_mfma_f32_16x16x32_bf16 v[100:103], v[132:135], v[198:201], v[100:103]
	v_mfma_f32_16x16x32_bf16 v[96:99], v[140:143], v[198:201], v[96:99]
	v_mfma_f32_16x16x32_bf16 v[76:79], v[132:135], v[206:209], v[76:79]
	v_mfma_f32_16x16x32_bf16 v[72:75], v[140:143], v[206:209], v[72:75]
	s_setprio 0
	s_setprio 1
	v_mfma_f32_16x16x32_bf16 v[116:119], v[162:165], v[178:181], v[116:119]
	v_mfma_f32_16x16x32_bf16 v[108:111], v[170:173], v[178:181], v[108:111]
	v_mfma_f32_16x16x32_bf16 v[92:95], v[162:165], v[186:189], v[92:95]
	v_mfma_f32_16x16x32_bf16 v[88:91], v[170:173], v[186:189], v[88:91]
	v_mfma_f32_16x16x32_bf16 v[84:87], v[162:165], v[194:197], v[84:87]
	v_mfma_f32_16x16x32_bf16 v[80:83], v[170:173], v[194:197], v[80:83]
	v_mfma_f32_16x16x32_bf16 v[68:71], v[162:165], v[202:205], v[68:71]
	v_mfma_f32_16x16x32_bf16 v[64:67], v[170:173], v[202:205], v[64:67]
	v_mfma_f32_16x16x32_bf16 v[116:119], v[166:169], v[182:185], v[116:119]
	v_mfma_f32_16x16x32_bf16 v[108:111], v[174:177], v[182:185], v[108:111]
	v_mfma_f32_16x16x32_bf16 v[92:95], v[166:169], v[190:193], v[92:95]
	v_mfma_f32_16x16x32_bf16 v[88:91], v[174:177], v[190:193], v[88:91]
	v_mfma_f32_16x16x32_bf16 v[84:87], v[166:169], v[198:201], v[84:87]
	v_mfma_f32_16x16x32_bf16 v[80:83], v[174:177], v[198:201], v[80:83]
	v_mfma_f32_16x16x32_bf16 v[68:71], v[166:169], v[206:209], v[68:71]
	v_mfma_f32_16x16x32_bf16 v[64:67], v[174:177], v[206:209], v[64:67]
	s_setprio 0
	s_barrier
	s_add_i32 s30, s62, s38
	v_lshl_add_u64 v[210:211], v[210:211], 0, s[6:7]
	s_mov_b32 m0, s30
	ds_read_b128 v[178:181], v216 offset:49152
	ds_read_b128 v[182:185], v216 offset:50176
	ds_read_b128 v[186:189], v216 offset:51200
	ds_read_b128 v[190:193], v216 offset:52224
	ds_read_b128 v[194:197], v216 offset:53248
	ds_read_b128 v[198:201], v216 offset:54272
	ds_read_b128 v[202:205], v216 offset:55296
	ds_read_b128 v[206:209], v216 offset:56320
	global_load_lds_dwordx4 v[210:211], off
	s_add_i32 m0, s30, 0x2000
	s_add_u32 s28, s28, 0x80080
	v_lshl_add_u64 v[210:211], v[218:219], 0, s[6:7]
	s_addc_u32 s29, s29, 0
	s_add_i32 s30, s63, s38
	global_load_lds_dwordx4 v[210:211], off
	v_lshl_add_u64 v[210:211], s[28:29], 0, v[148:149]
	s_mov_b32 m0, s30
	s_nop 0
	global_load_lds_dwordx4 v[210:211], off
	v_lshl_add_u64 v[210:211], s[28:29], 0, v[144:145]
	s_add_i32 m0, s30, 0x2000
	s_nop 0
	global_load_lds_dwordx4 v[210:211], off
	v_lshl_add_u64 v[210:211], v[220:221], 0, s[6:7]
	s_mov_b32 m0, s48
	s_nop 0
	global_load_lds_dwordx4 v[210:211], off
	v_lshl_add_u64 v[210:211], v[222:223], 0, s[6:7]
	s_mov_b32 m0, s49
	s_nop 0
	global_load_lds_dwordx4 v[210:211], off
	s_waitcnt vmcnt(8)
	s_waitcnt lgkmcnt(0)
	s_barrier
	s_setprio 1
	s_waitcnt lgkmcnt(0)
	v_mfma_f32_16x16x32_bf16 v[60:63], v[128:131], v[178:181], v[60:63]
	v_mfma_f32_16x16x32_bf16 v[56:59], v[136:139], v[178:181], v[56:59]
	v_mfma_f32_16x16x32_bf16 v[48:51], v[128:131], v[186:189], v[48:51]
	v_mfma_f32_16x16x32_bf16 v[40:43], v[136:139], v[186:189], v[40:43]
	v_mfma_f32_16x16x32_bf16 v[32:35], v[128:131], v[194:197], v[32:35]
	v_mfma_f32_16x16x32_bf16 v[24:27], v[136:139], v[194:197], v[24:27]
	v_mfma_f32_16x16x32_bf16 v[16:19], v[128:131], v[202:205], v[16:19]
	v_mfma_f32_16x16x32_bf16 v[8:11], v[136:139], v[202:205], v[8:11]
	v_mfma_f32_16x16x32_bf16 v[60:63], v[132:135], v[182:185], v[60:63]
	v_mfma_f32_16x16x32_bf16 v[56:59], v[140:143], v[182:185], v[56:59]
	v_mfma_f32_16x16x32_bf16 v[48:51], v[132:135], v[190:193], v[48:51]
	v_mfma_f32_16x16x32_bf16 v[40:43], v[140:143], v[190:193], v[40:43]
	v_mfma_f32_16x16x32_bf16 v[32:35], v[132:135], v[198:201], v[32:35]
	v_mfma_f32_16x16x32_bf16 v[24:27], v[140:143], v[198:201], v[24:27]
	v_mfma_f32_16x16x32_bf16 v[16:19], v[132:135], v[206:209], v[16:19]
	v_mfma_f32_16x16x32_bf16 v[8:11], v[140:143], v[206:209], v[8:11]
	s_setprio 0
	s_setprio 1
	v_mfma_f32_16x16x32_bf16 v[52:55], v[162:165], v[178:181], v[52:55]
	v_mfma_f32_16x16x32_bf16 v[44:47], v[170:173], v[178:181], v[44:47]
	v_mfma_f32_16x16x32_bf16 v[36:39], v[162:165], v[186:189], v[36:39]
	v_mfma_f32_16x16x32_bf16 v[28:31], v[170:173], v[186:189], v[28:31]
	v_mfma_f32_16x16x32_bf16 v[20:23], v[162:165], v[194:197], v[20:23]
	v_mfma_f32_16x16x32_bf16 v[12:15], v[170:173], v[194:197], v[12:15]
	v_mfma_f32_16x16x32_bf16 v[4:7], v[162:165], v[202:205], v[4:7]
	v_mfma_f32_16x16x32_bf16 v[0:3], v[170:173], v[202:205], v[0:3]
	v_mfma_f32_16x16x32_bf16 v[52:55], v[166:169], v[182:185], v[52:55]
	v_mfma_f32_16x16x32_bf16 v[44:47], v[174:177], v[182:185], v[44:47]
	v_mfma_f32_16x16x32_bf16 v[36:39], v[166:169], v[190:193], v[36:39]
	v_mfma_f32_16x16x32_bf16 v[28:31], v[174:177], v[190:193], v[28:31]
	v_mfma_f32_16x16x32_bf16 v[20:23], v[166:169], v[198:201], v[20:23]
	v_mfma_f32_16x16x32_bf16 v[12:15], v[174:177], v[198:201], v[12:15]
	v_mfma_f32_16x16x32_bf16 v[4:7], v[166:169], v[206:209], v[4:7]
	v_mfma_f32_16x16x32_bf16 v[0:3], v[174:177], v[206:209], v[0:3]
	s_setprio 0
	s_barrier
	s_add_i32 s61, s61, 2
	s_add_u32 s26, s26, 0x100
	s_addc_u32 s27, s27, 0
	s_add_u32 s59, s59, 0x100
	s_addc_u32 s60, s60, 0
	s_cmp_gt_u32 s61, 29
	s_cbranch_scc0 .LBB0_1825
	s_mov_b32 s99, 1
	s_and_b64 vcc, exec, s[8:9]
	s_cbranch_vccz .LBB0_1828
	s_barrier

; __device__ __forceinline__ int lane_id_asm() { int l; asm volatile("v_mbcnt_lo_u32_b32 %0, -1, 0\n\tv_mbcnt_hi_u32_b32 %0, -1, %0" : "=v"(l)); return l; }
;     __host__ __device__ bool next(int i, Unit& u) const { const bool ok = StaticOrder::next(i, u); u.pm = 0; u.pn = 0; return ok; }
;     __host__ __device__ bool next(int i, Unit& u) const {
;         const long L = (long)i * G + c; if (L >= nwg) return false;
;         int wgid = (int)L; { const int q = nwg / NXCD, r = nwg % NXCD, xcd = wgid % NXCD, off = wgid / NXCD; wgid = (xcd < r ? xcd * (q + 1) : r * (q + 1) + (xcd - r) * q) + off; }
;         const int nig = WGM * nN, gid = wgid / nig, fm = gid * WGM, gsz = (nM - fm) < WGM ? (nM - fm) : WGM;
;         u.pm = fm + ((wgid % nig) % gsz); u.pn = (wgid % nig) / gsz; return true;
; template <class Epi, class Sched, bool ALIGN_EPI = false, bool SP2 = false>
; __device__ __forceinline__ void gemm_phase(PG8_LAS unsigned char* lds, const Gemm g, const Sched& S, const Epi& E, const int wave_in) {
;     const int lane = lane_id_asm(), wid = __builtin_amdgcn_readfirstlane(wave_in), tid = wid * 64 + lane, wr = wid >> 2, wc = wid & 3, fr = lane & 15, fq = lane >> 4;
;     const int K = g.K, nt = K / BK;
.LBB0_1938:
	s_cmp_gt_i32 s52, 22
	s_cselect_b64 s[0:1], -1, 0
	s_cmp_lt_i32 s53, 23
	s_cselect_b64 s[2:3], -1, 0
	s_or_b64 s[0:1], s[0:1], s[2:3]
	s_and_b64 vcc, exec, s[0:1]
	s_cbranch_vccnz .LBB0_2023
	s_mov_b32 s99, 0
	s_cmpk_lt_i32 s73, 0x1830
	s_cselect_b64 s[2:3], -1, 0
	s_cmpk_gt_i32 s73, 0x182f
	v_mbcnt_lo_u32_b32 v10, -1, 0
	v_mbcnt_hi_u32_b32 v10, -1, v10
	s_cbranch_scc1 .LBB0_1942
	s_ashr_i32 s0, s73, 31
	s_lshr_b32 s0, s0, 29
	s_add_i32 s0, s73, s0
	s_ashr_i32 s1, s0, 3
	s_and_b32 s0, s0, -8
	s_sub_i32 s0, s73, s0
	s_cmp_lt_i32 s0, 0
	s_movk_i32 s4, 0x307
	s_cselect_b32 s4, s4, 0x306
	s_mul_i32 s0, s4, s0
	s_add_i32 s0, s0, s1
	s_mul_hi_i32 s1, s0, 0x2fa0be83
	s_lshr_b32 s4, s1, 31
	s_ashr_i32 s1, s1, 5
	s_add_i32 s1, s1, s4
	s_lshl_b32 s4, s1, 2
	s_mulk_i32 s1, 0xac
	s_sub_i32 s0, s0, s1
	s_sext_i32_i16 s1, s0
	s_bfe_u32 s1, s1, 0x2001d
	s_add_i32 s1, s0, s1
	s_sext_i32_i16 s5, s1
	s_and_b32 s1, s1, 0xfffc
	s_sub_i32 s0, s0, s1
	s_sext_i32_i16 s0, s0
	s_add_i32 s12, s4, s0
	s_ashr_i32 s0, s5, 2
	s_andn2_b64 vcc, exec, s[2:3]
	s_cbranch_vccz .LBB0_1943

; #define PG8_STAGE(bufoff, gbase, voff) do { _Pragma("unroll") for (int _i = 0; _i < 2; ++_i) \
;         __builtin_amdgcn_global_load_lds((const unsigned*)((const char*)(gbase) + (voff)[_i]), (PG8_LAS unsigned*)(lds + (bufoff) + ldsw + _i * 8192), 16, 0, 0); } while (0)
; #define PG8_LDA(dst, b, h) do { _Pragma("unroll") for (int m = 0; m < 4; ++m) _Pragma("unroll") for (int k = 0; k < 2; ++k) dst[m][k] = *(const PG8_LAS bf16x8*)(lds + PG8_SA(b, h) + aoff + m * 2048 + k * 1024); } while (0)
; #define PG8_LDB(dst, b, h) do { _Pragma("unroll") for (int n = 0; n < 2; ++n) _Pragma("unroll") for (int k = 0; k < 2; ++k) dst[n][k] = *(const PG8_LAS bf16x8*)(lds + PG8_SB(b, h) + boff + n * 2048 + k * 1024); } while (0)
; #define PG8_WAIT_V(n) asm volatile("s_waitcnt vmcnt(" #n ")" ::: "memory")
; #define PG8_BAR __builtin_amdgcn_s_barrier()
;     __device__ __forceinline__ void operator()(const f32x4 (&acc)[2][2][4][2], const Unit& u, int wr, int wc, int fr, int fq) const {
;         const int cc0 = wc * 32 + 8 * fq;
;         const int jg0 = u.pn * 128 + cc0;
;         f32x4 wa2[2][3], wb2[2][3];
; #pragma unroll
;         for (int n = 0; n < 2; ++n)
; #pragma unroll
;             for (int t = 0; t < 3; ++t) { wa2[n][t] = *(const f32x4*)(cw + t * 11008 + jg0 + 4 * n); wb2[n][t] = *(const f32x4*)(cw + t * 11008 + 5504 + jg0 + 4 * n); }
;         asm volatile("" :: "v"(wa2[0][0]), "v"(wa2[0][1]), "v"(wa2[0][2]), "v"(wb2[0][0]), "v"(wb2[0][1]), "v"(wb2[0][2]), "v"(wa2[1][0]), "v"(wa2[1][1]), "v"(wa2[1][2]), "v"(wb2[1][0]), "v"(wb2[1][1]), "v"(wb2[1][2]));
; template <class Epi, class Sched, bool ALIGN_EPI = false, bool SP2 = false>
; __device__ __forceinline__ void gemm_phase(PG8_LAS unsigned char* lds, const Gemm g, const Sched& S, const Epi& E, const int wave_in) {
;     ...
;             PG8_LDB(B0, 0, 0); PG8_LDB(B1, 0, 1); PG8_SCHED; PG8_LDA(At, 0, 0); PG8_STAGE(PG8_SA(1, 1), a1 + hstepA, voffA);
;             PG8_WAIT_V(8); PG8_WAIT_L(0); PG8_BAR; PG8_MMA(0, 0, At, B0); PG8_MMA(0, 1, At, B1); PG8_BAR; PG8_SCHED;
;     ...
; #pragma unroll
;         for (int a = 0; a < 2; ++a)
; #pragma unroll
;             for (int b = 0; b < 2; ++b)
; #pragma unroll
;                 for (int m = 0; m < 4; ++m)
; #pragma unroll
;                     for (int n = 0; n < 2; ++n) acc[a][b][m][n] = (f32x4){0.f, 0.f, 0.f, 0.f};
;         cur = nxt; cA = nA; cB = nB; ++ui;
.LBB0_1950:
	s_ashr_i32 s41, s40, 31
	s_lshl_b64 s[42:43], s[40:41], 20
	s_add_u32 s42, s52, s42
	s_addc_u32 s43, s53, s43
	s_and_b64 s[44:45], s[10:11], exec
	s_cselect_b32 s1, s43, s47
	s_cselect_b32 s13, s42, s46
	s_ashr_i32 s39, s38, 31
	s_lshl_b64 s[44:45], s[38:39], 20
	s_add_u32 s44, s54, s44
	s_addc_u32 s45, s55, s45
	s_and_b64 s[50:51], s[10:11], exec
	s_cselect_b32 s39, s45, s49
	s_cselect_b32 s41, s44, s48
	s_add_u32 s46, s46, 0x80080
	s_addc_u32 s47, s47, 0
	s_add_u32 s72, s48, 0x100
	v_mov_b32_e32 v0, 0
	s_addc_u32 s73, s49, 0
	s_mov_b32 s74, -2
	v_mov_b32_e32 v1, v0
	v_mov_b32_e32 v2, v0
	v_mov_b32_e32 v3, v0
	v_mov_b32_e32 v4, v0
	v_mov_b32_e32 v5, v0
	v_mov_b32_e32 v6, v0
	v_mov_b32_e32 v7, v0
	v_mov_b32_e32 v16, v0
	v_mov_b32_e32 v17, v0
	v_mov_b32_e32 v18, v0
	v_mov_b32_e32 v19, v0
	v_mov_b32_e32 v24, v0
	v_mov_b32_e32 v25, v0
	v_mov_b32_e32 v26, v0
	v_mov_b32_e32 v27, v0
	v_mov_b32_e32 v32, v0
	v_mov_b32_e32 v33, v0
	v_mov_b32_e32 v34, v0
	v_mov_b32_e32 v35, v0
	v_mov_b32_e32 v40, v0
	v_mov_b32_e32 v41, v0
	v_mov_b32_e32 v42, v0
	v_mov_b32_e32 v43, v0
	v_mov_b32_e32 v72, v0
	v_mov_b32_e32 v73, v0
	v_mov_b32_e32 v74, v0
	v_mov_b32_e32 v75, v0
	v_mov_b32_e32 v104, v0
	v_mov_b32_e32 v105, v0
	v_mov_b32_e32 v106, v0
	v_mov_b32_e32 v107, v0
	v_mov_b32_e32 v8, v0
	v_mov_b32_e32 v9, v0
	v_mov_b32_e32 v10, v0
	v_mov_b32_e32 v11, v0
	v_mov_b32_e32 v12, v0
	v_mov_b32_e32 v13, v0
	v_mov_b32_e32 v14, v0
	v_mov_b32_e32 v15, v0
	v_mov_b32_e32 v20, v0
	v_mov_b32_e32 v21, v0
	v_mov_b32_e32 v22, v0
	v_mov_b32_e32 v23, v0
	v_mov_b32_e32 v28, v0
	v_mov_b32_e32 v29, v0
	v_mov_b32_e32 v30, v0
	v_mov_b32_e32 v31, v0
	v_mov_b32_e32 v36, v0
	v_mov_b32_e32 v37, v0
	v_mov_b32_e32 v38, v0
	v_mov_b32_e32 v39, v0
	v_mov_b32_e32 v68, v0
	v_mov_b32_e32 v69, v0
	v_mov_b32_e32 v70, v0
	v_mov_b32_e32 v71, v0
	v_mov_b32_e32 v76, v0
	v_mov_b32_e32 v77, v0
	v_mov_b32_e32 v78, v0
	v_mov_b32_e32 v79, v0
	v_mov_b32_e32 v108, v0
	v_mov_b32_e32 v109, v0
	v_mov_b32_e32 v110, v0
	v_mov_b32_e32 v111, v0
	v_mov_b32_e32 v112, v0
	v_mov_b32_e32 v113, v0
	s_waitcnt vmcnt(0)
	v_mov_b32_e32 v114, v0
	v_mov_b32_e32 v115, v0
	v_mov_b32_e32 v116, v0
	v_mov_b32_e32 v117, v0
	v_mov_b32_e32 v118, v0
	v_mov_b32_e32 v119, v0
	v_mov_b32_e32 v128, v0
	v_mov_b32_e32 v129, v0
	v_mov_b32_e32 v130, v0
	v_mov_b32_e32 v131, v0
	v_mov_b32_e32 v136, v0
	v_mov_b32_e32 v137, v0
	v_mov_b32_e32 v138, v0
	v_mov_b32_e32 v139, v0
	v_mov_b32_e32 v144, v0
	v_mov_b32_e32 v145, v0
	v_mov_b32_e32 v146, v0
	v_mov_b32_e32 v147, v0
	v_mov_b32_e32 v152, v0
	v_mov_b32_e32 v153, v0
	v_mov_b32_e32 v154, v0
	v_mov_b32_e32 v155, v0
	v_mov_b32_e32 v160, v0
	v_mov_b32_e32 v161, v0
	v_mov_b32_e32 v162, v0
	v_mov_b32_e32 v163, v0
	v_mov_b32_e32 v168, v0
	v_mov_b32_e32 v169, v0
	v_mov_b32_e32 v170, v0
	v_mov_b32_e32 v171, v0
	v_mov_b32_e32 v120, v0
	v_mov_b32_e32 v121, v0
	v_mov_b32_e32 v122, v0
	v_mov_b32_e32 v123, v0
	v_mov_b32_e32 v124, v0
	v_mov_b32_e32 v125, v0
	v_mov_b32_e32 v126, v0
	v_mov_b32_e32 v127, v0
	v_mov_b32_e32 v132, v0
	v_mov_b32_e32 v133, v0
	v_mov_b32_e32 v134, v0
	v_mov_b32_e32 v135, v0
	v_mov_b32_e32 v140, v0
	v_mov_b32_e32 v141, v0
	v_mov_b32_e32 v142, v0
	v_mov_b32_e32 v143, v0
	v_mov_b32_e32 v148, v0
	v_mov_b32_e32 v149, v0
	v_mov_b32_e32 v150, v0
	v_mov_b32_e32 v151, v0
	v_mov_b32_e32 v156, v0
	v_mov_b32_e32 v157, v0
	v_mov_b32_e32 v158, v0
	v_mov_b32_e32 v159, v0
	v_mov_b32_e32 v164, v0
	v_mov_b32_e32 v165, v0
	v_mov_b32_e32 v166, v0
	v_mov_b32_e32 v167, v0
	v_mov_b32_e32 v172, v0
	v_mov_b32_e32 v173, v0
	v_mov_b32_e32 v174, v0
	v_mov_b32_e32 v175, v0
	s_cmp_lg_u32 s99, 0
	s_cbranch_scc0 .LBB0_1951
	ds_read_b128 v[44:47], v189
	ds_read_b128 v[48:51], v189 offset:1024
	ds_read_b128 v[52:55], v189 offset:2048
	ds_read_b128 v[56:59], v189 offset:3072
	ds_read_b128 v[60:63], v197
	ds_read_b128 v[64:67], v197 offset:1024
	ds_read_b128 v[80:83], v197 offset:2048
	ds_read_b128 v[84:87], v197 offset:3072
	s_add_u32 s48, s46, 0xfff80080
	s_addc_u32 s49, s47, -1
	s_cmp_eq_u32 s74, 28
	s_cselect_b32 s51, s1, s49
	s_cselect_b32 s50, s13, s48
	s_cselect_b32 s49, s39, s73
	s_cselect_b32 s48, s41, s72
	v_lshl_add_u64 v[224:225], s[46:47], 0, v[206:207]
	s_add_i32 m0, s57, 0xc000
	ds_read_b128 v[88:91], v199
	ds_read_b128 v[92:95], v199 offset:1024
	ds_read_b128 v[96:99], v199 offset:2048
	ds_read_b128 v[100:103], v199 offset:3072
	ds_read_b128 v[176:179], v199 offset:4096
	ds_read_b128 v[212:215], v199 offset:5120
	ds_read_b128 v[216:219], v199 offset:6144
	ds_read_b128 v[220:223], v199 offset:7168
	global_load_lds_dwordx4 v[224:225], off
	v_lshl_add_u64 v[224:225], s[46:47], 0, v[208:209]
	s_add_i32 m0, s57, 0xe000
	s_nop 0
	global_load_lds_dwordx4 v[224:225], off
	s_waitcnt vmcnt(24)
	s_waitcnt lgkmcnt(0)
	s_barrier
; #define PG8_STAGE(bufoff, gbase, voff) do { _Pragma("unroll") for (int _i = 0; _i < 2; ++_i) \
;         __builtin_amdgcn_global_load_lds((const unsigned*)((const char*)(gbase) + (voff)[_i]), (PG8_LAS unsigned*)(lds + (bufoff) + ldsw + _i * 8192), 16, 0, 0); } while (0)
; #define PG8_LDA(dst, b, h) do { _Pragma("unroll") for (int m = 0; m < 4; ++m) _Pragma("unroll") for (int k = 0; k < 2; ++k) dst[m][k] = *(const PG8_LAS bf16x8*)(lds + PG8_SA(b, h) + aoff + m * 2048 + k * 1024); } while (0)
; #define PG8_MMA(ai, bj, At, Bt) do { __builtin_amdgcn_s_setprio(1); _Pragma("unroll") for (int m = 0; m < 4; ++m) _Pragma("unroll") for (int n = 0; n < 2; ++n) _Pragma("unroll") for (int k = 0; k < 2; ++k) \
;         acc[ai][bj][m][n] = __builtin_amdgcn_mfma_f32_16x16x32_bf16(Bt[n][k], At[m][k], acc[ai][bj][m][n], 0, 0, 0); __builtin_amdgcn_s_setprio(0); } while (0)
; #define PG8_WAIT_V(n) asm volatile("s_waitcnt vmcnt(" #n ")" ::: "memory")
; #define PG8_WAIT_L(n) asm volatile("s_waitcnt lgkmcnt(" #n ")" ::: "memory")
; #define PG8_BAR __builtin_amdgcn_s_barrier()
; #define PG8_SCHED __builtin_amdgcn_sched_barrier(0)
; template <class Epi, class Sched, bool ALIGN_EPI = false, bool SP2 = false>
; __device__ __forceinline__ void gemm_phase(PG8_LAS unsigned char* lds, const Gemm g, const Sched& S, const Epi& E, const int wave_in) {
;     ...
;             PG8_WAIT_V(8); PG8_WAIT_L(0); PG8_BAR; PG8_MMA(0, 0, At, B0); PG8_MMA(0, 1, At, B1); PG8_BAR; PG8_SCHED;
;             PG8_LDA(At, 0, 1); PG8_STAGE(PG8_SB(0, 0), b2, voffB); PG8_STAGE(PG8_SB(0, 1), b2 + hstepB, voffB); PG8_STAGE(PG8_SA(0, 0), a2, voffA);
;             PG8_WAIT_V(8); PG8_WAIT_L(0); PG8_BAR; PG8_MMA(1, 0, At, B0); PG8_MMA(1, 1, At, B1); PG8_BAR; PG8_SCHED;
	s_setprio 1
	s_waitcnt lgkmcnt(0)
	v_mfma_f32_16x16x32_bf16 v[172:175], v[44:47], v[88:91], v[172:175]
	v_mfma_f32_16x16x32_bf16 v[164:167], v[52:55], v[88:91], v[164:167]
	v_mfma_f32_16x16x32_bf16 v[156:159], v[44:47], v[96:99], v[156:159]
	v_mfma_f32_16x16x32_bf16 v[148:151], v[52:55], v[96:99], v[148:151]
	v_mfma_f32_16x16x32_bf16 v[140:143], v[44:47], v[176:179], v[140:143]
	v_mfma_f32_16x16x32_bf16 v[132:135], v[52:55], v[176:179], v[132:135]
	v_mfma_f32_16x16x32_bf16 v[124:127], v[44:47], v[216:219], v[124:127]
	v_mfma_f32_16x16x32_bf16 v[120:123], v[52:55], v[216:219], v[120:123]
	v_mfma_f32_16x16x32_bf16 v[172:175], v[48:51], v[92:95], v[172:175]
	v_mfma_f32_16x16x32_bf16 v[164:167], v[56:59], v[92:95], v[164:167]
	v_mfma_f32_16x16x32_bf16 v[156:159], v[48:51], v[100:103], v[156:159]
	v_mfma_f32_16x16x32_bf16 v[148:151], v[56:59], v[100:103], v[148:151]
	v_mfma_f32_16x16x32_bf16 v[140:143], v[48:51], v[212:215], v[140:143]
	v_mfma_f32_16x16x32_bf16 v[132:135], v[56:59], v[212:215], v[132:135]
	v_mfma_f32_16x16x32_bf16 v[124:127], v[48:51], v[220:223], v[124:127]
	v_mfma_f32_16x16x32_bf16 v[120:123], v[56:59], v[220:223], v[120:123]
	s_setprio 0
	s_setprio 1
	v_mfma_f32_16x16x32_bf16 v[168:171], v[60:63], v[88:91], v[168:171]
	v_mfma_f32_16x16x32_bf16 v[88:91], v[80:83], v[88:91], v[160:163]
	v_mfma_f32_16x16x32_bf16 v[168:171], v[64:67], v[92:95], v[168:171]
	v_mfma_f32_16x16x32_bf16 v[88:91], v[84:87], v[92:95], v[88:91]
	v_mfma_f32_16x16x32_bf16 v[92:95], v[60:63], v[96:99], v[152:155]
	v_mfma_f32_16x16x32_bf16 v[96:99], v[80:83], v[96:99], v[144:147]
	v_mfma_f32_16x16x32_bf16 v[128:131], v[80:83], v[176:179], v[128:131]
	v_mfma_f32_16x16x32_bf16 v[116:119], v[60:63], v[216:219], v[116:119]
	v_mfma_f32_16x16x32_bf16 v[112:115], v[80:83], v[216:219], v[112:115]
	v_mfma_f32_16x16x32_bf16 v[92:95], v[64:67], v[100:103], v[92:95]
	v_mfma_f32_16x16x32_bf16 v[96:99], v[84:87], v[100:103], v[96:99]
	v_mfma_f32_16x16x32_bf16 v[100:103], v[60:63], v[176:179], v[136:139]
	v_mfma_f32_16x16x32_bf16 v[128:131], v[84:87], v[212:215], v[128:131]
	v_mfma_f32_16x16x32_bf16 v[116:119], v[64:67], v[220:223], v[116:119]
	v_mfma_f32_16x16x32_bf16 v[112:115], v[84:87], v[220:223], v[112:115]
	v_mfma_f32_16x16x32_bf16 v[100:103], v[64:67], v[212:215], v[100:103]
	s_setprio 0
	s_barrier
	s_add_i32 s75, s68, s56
	v_lshl_add_u64 v[232:233], s[48:49], 0, v[182:183]
	s_mov_b32 m0, s75
	ds_read_b128 v[136:139], v199 offset:16384
	ds_read_b128 v[144:147], v199 offset:17408
	ds_read_b128 v[152:155], v199 offset:18432
	ds_read_b128 v[160:163], v199 offset:19456
	ds_read_b128 v[176:179], v199 offset:20480
	ds_read_b128 v[212:215], v199 offset:21504
	ds_read_b128 v[216:219], v199 offset:22528
	ds_read_b128 v[220:223], v199 offset:23552
	global_load_lds_dwordx4 v[232:233], off
	s_add_i32 m0, s75, 0x2000
	s_add_u32 s76, s48, 0x80000
	v_lshl_add_u64 v[234:235], s[48:49], 0, v[186:187]
	s_addc_u32 s77, s49, 0
	s_add_i32 s75, s69, s56
	global_load_lds_dwordx4 v[234:235], off
	v_lshl_add_u64 v[224:225], s[76:77], 0, v[182:183]
	s_mov_b32 m0, s75
	v_lshl_add_u64 v[236:237], s[50:51], 0, v[180:181]
	global_load_lds_dwordx4 v[224:225], off
	v_lshl_add_u64 v[224:225], s[76:77], 0, v[186:187]
	s_add_i32 m0, s75, 0x2000
	v_lshl_add_u64 v[238:239], s[50:51], 0, v[184:185]
	global_load_lds_dwordx4 v[224:225], off
	s_mov_b32 m0, s57
	s_nop 0
	global_load_lds_dwordx4 v[236:237], off
	s_mov_b32 m0, s58
	s_nop 0
	global_load_lds_dwordx4 v[238:239], off
	s_waitcnt vmcnt(24)
	s_waitcnt lgkmcnt(0)
	s_barrier
	s_setprio 1
	s_waitcnt lgkmcnt(0)
	v_mfma_f32_16x16x32_bf16 v[108:111], v[44:47], v[136:139], v[108:111]
	v_mfma_f32_16x16x32_bf16 v[76:79], v[52:55], v[136:139], v[76:79]
	v_mfma_f32_16x16x32_bf16 v[68:71], v[44:47], v[152:155], v[68:71]
	v_mfma_f32_16x16x32_bf16 v[36:39], v[52:55], v[152:155], v[36:39]
	v_mfma_f32_16x16x32_bf16 v[28:31], v[44:47], v[176:179], v[28:31]
	v_mfma_f32_16x16x32_bf16 v[20:23], v[52:55], v[176:179], v[20:23]
	v_mfma_f32_16x16x32_bf16 v[12:15], v[44:47], v[216:219], v[12:15]
	v_mfma_f32_16x16x32_bf16 v[8:11], v[52:55], v[216:219], v[8:11]
	v_mfma_f32_16x16x32_bf16 v[108:111], v[48:51], v[144:147], v[108:111]
	v_mfma_f32_16x16x32_bf16 v[76:79], v[56:59], v[144:147], v[76:79]
	v_mfma_f32_16x16x32_bf16 v[68:71], v[48:51], v[160:163], v[68:71]
	v_mfma_f32_16x16x32_bf16 v[36:39], v[56:59], v[160:163], v[36:39]
	v_mfma_f32_16x16x32_bf16 v[28:31], v[48:51], v[212:215], v[28:31]
	v_mfma_f32_16x16x32_bf16 v[20:23], v[56:59], v[212:215], v[20:23]
	v_mfma_f32_16x16x32_bf16 v[12:15], v[48:51], v[220:223], v[12:15]
	v_mfma_f32_16x16x32_bf16 v[8:11], v[56:59], v[220:223], v[8:11]
	s_setprio 0
	s_setprio 1
	v_mfma_f32_16x16x32_bf16 v[40:43], v[60:63], v[152:155], v[40:43]
	v_mfma_f32_16x16x32_bf16 v[32:35], v[80:83], v[152:155], v[32:35]
	v_mfma_f32_16x16x32_bf16 v[24:27], v[60:63], v[176:179], v[24:27]
	v_mfma_f32_16x16x32_bf16 v[16:19], v[80:83], v[176:179], v[16:19]
	v_mfma_f32_16x16x32_bf16 v[4:7], v[60:63], v[216:219], v[4:7]
	v_mfma_f32_16x16x32_bf16 v[0:3], v[80:83], v[216:219], v[0:3]
	v_mfma_f32_16x16x32_bf16 v[44:47], v[60:63], v[136:139], v[104:107]
	v_mfma_f32_16x16x32_bf16 v[48:51], v[80:83], v[136:139], v[72:75]
	v_mfma_f32_16x16x32_bf16 v[40:43], v[64:67], v[160:163], v[40:43]
	v_mfma_f32_16x16x32_bf16 v[32:35], v[84:87], v[160:163], v[32:35]
	v_mfma_f32_16x16x32_bf16 v[24:27], v[64:67], v[212:215], v[24:27]
	v_mfma_f32_16x16x32_bf16 v[16:19], v[84:87], v[212:215], v[16:19]
	v_mfma_f32_16x16x32_bf16 v[4:7], v[64:67], v[220:223], v[4:7]
	v_mfma_f32_16x16x32_bf16 v[0:3], v[84:87], v[220:223], v[0:3]
	v_mfma_f32_16x16x32_bf16 v[44:47], v[64:67], v[144:147], v[44:47]
	v_mfma_f32_16x16x32_bf16 v[48:51], v[84:87], v[144:147], v[48:51]
	s_setprio 0
	s_barrier
; #define PG8_STAGE(bufoff, gbase, voff) do { _Pragma("unroll") for (int _i = 0; _i < 2; ++_i) \
;         __builtin_amdgcn_global_load_lds((const unsigned*)((const char*)(gbase) + (voff)[_i]), (PG8_LAS unsigned*)(lds + (bufoff) + ldsw + _i * 8192), 16, 0, 0); } while (0)
; #define PG8_LDA(dst, b, h) do { _Pragma("unroll") for (int m = 0; m < 4; ++m) _Pragma("unroll") for (int k = 0; k < 2; ++k) dst[m][k] = *(const PG8_LAS bf16x8*)(lds + PG8_SA(b, h) + aoff + m * 2048 + k * 1024); } while (0)
; #define PG8_WAIT_V(n) asm volatile("s_waitcnt vmcnt(" #n ")" ::: "memory")
; #define PG8_WAIT_L(n) asm volatile("s_waitcnt lgkmcnt(" #n ")" ::: "memory")
; #define PG8_BAR __builtin_amdgcn_s_barrier()
; template <class Epi, class Sched, bool ALIGN_EPI = false, bool SP2 = false>
; __device__ __forceinline__ void gemm_phase(PG8_LAS unsigned char* lds, const Gemm g, const Sched& S, const Epi& E, const int wave_in) {
;     ...
;         for (int t = 0; t < nt; t += 2) {
;             const bool last = (t == nt - 2);
;             const char* a1 = cA + (size_t)(t + 1) * kstep;
;             const char* a2 = last ? nA : cA + (size_t)(t + 2) * kstep; const char* b2 = last ? nB : cB + (size_t)(t + 2) * kstep;
;             const char* a3 = a2 + kstep; const char* b3 = b2 + kstep;
;             if (last && has_next) S.a_ready(nxt);
;             if constexpr (SP2) {
;             PG8_LDB(B0, 0, 0); PG8_LDB(B1, 0, 1); PG8_SCHED; PG8_LDA(At, 0, 0); PG8_STAGE(PG8_SA(1, 1), a1 + hstepA, voffA);
;             PG8_WAIT_V(8); PG8_WAIT_L(0); PG8_BAR; PG8_MMA(0, 0, At, B0); PG8_MMA(0, 1, At, B1); PG8_BAR; PG8_SCHED;
;             PG8_LDA(At, 0, 1); PG8_STAGE(PG8_SB(0, 0), b2, voffB); PG8_STAGE(PG8_SB(0, 1), b2 + hstepB, voffB); PG8_STAGE(PG8_SA(0, 0), a2, voffA);
;             PG8_WAIT_V(8); PG8_WAIT_L(0); PG8_BAR; PG8_MMA(1, 0, At, B0); PG8_MMA(1, 1, At, B1); PG8_BAR; PG8_SCHED;
;             PG8_LDB(B0, 1, 0); PG8_LDB(B1, 1, 1); PG8_SCHED; PG8_LDA(At, 1, 0); PG8_STAGE(PG8_SA(0, 1), a2 + hstepA, voffA);
;             PG8_WAIT_V(8); PG8_WAIT_L(0); PG8_BAR; PG8_MMA(0, 0, At, B0); PG8_MMA(0, 1, At, B1); PG8_BAR; PG8_SCHED;
;             PG8_LDA(At, 1, 1); PG8_STAGE(PG8_SB(1, 0), b3, voffB); PG8_STAGE(PG8_SB(1, 1), b3 + hstepB, voffB); PG8_STAGE(PG8_SA(1, 0), a3, voffA);
;             PG8_WAIT_V(8); PG8_WAIT_L(0); PG8_BAR; PG8_MMA(1, 0, At, B0); PG8_MMA(1, 1, At, B1); PG8_BAR; PG8_SCHED;
	s_add_i32 s75, 0, 0x18000
	s_add_i32 s76, 0, 0x1c000
	v_add_u32_e32 v64, s75, v195
	v_add_u32_e32 v72, s76, v195
	ds_read_b128 v[52:55], v64
	ds_read_b128 v[56:59], v64 offset:1024
	ds_read_b128 v[60:63], v64 offset:2048
	ds_read_b128 v[64:67], v64 offset:3072
	ds_read_b128 v[80:83], v72
	ds_read_b128 v[84:87], v72 offset:1024
	ds_read_b128 v[176:179], v72 offset:2048
	ds_read_b128 v[212:215], v72 offset:3072
	s_add_u32 s50, s50, 0x80000
	s_addc_u32 s51, s51, 0
	s_mov_b32 m0, s59
	v_lshl_add_u64 v[152:153], s[50:51], 0, v[180:181]
	ds_read_b128 v[72:75], v199 offset:32768
	ds_read_b128 v[104:107], v199 offset:33792
	ds_read_b128 v[136:139], v199 offset:34816
	ds_read_b128 v[144:147], v199 offset:35840
	ds_read_b128 v[216:219], v199 offset:36864
	ds_read_b128 v[220:223], v199 offset:37888
	ds_read_b128 v[224:227], v199 offset:38912
	ds_read_b128 v[228:231], v199 offset:39936
	global_load_lds_dwordx4 v[152:153], off
	v_lshl_add_u64 v[152:153], s[50:51], 0, v[184:185]
	s_mov_b32 m0, s60
	s_nop 0
	global_load_lds_dwordx4 v[152:153], off
	s_waitcnt vmcnt(8)
	s_waitcnt lgkmcnt(0)
	s_barrier
	s_setprio 1
	s_waitcnt lgkmcnt(0)
	v_mfma_f32_16x16x32_bf16 v[152:155], v[52:55], v[72:75], v[172:175]
	v_mfma_f32_16x16x32_bf16 v[172:175], v[56:59], v[104:107], v[152:155]
	v_mfma_f32_16x16x32_bf16 v[152:155], v[60:63], v[72:75], v[164:167]
	v_mfma_f32_16x16x32_bf16 v[164:167], v[64:67], v[104:107], v[152:155]
	v_mfma_f32_16x16x32_bf16 v[152:155], v[52:55], v[136:139], v[156:159]
	v_mfma_f32_16x16x32_bf16 v[148:151], v[60:63], v[136:139], v[148:151]
	v_mfma_f32_16x16x32_bf16 v[140:143], v[52:55], v[216:219], v[140:143]
	v_mfma_f32_16x16x32_bf16 v[132:135], v[60:63], v[216:219], v[132:135]
	v_mfma_f32_16x16x32_bf16 v[124:127], v[52:55], v[224:227], v[124:127]
	v_mfma_f32_16x16x32_bf16 v[120:123], v[60:63], v[224:227], v[120:123]
	v_mfma_f32_16x16x32_bf16 v[156:159], v[56:59], v[144:147], v[152:155]
	v_mfma_f32_16x16x32_bf16 v[148:151], v[64:67], v[144:147], v[148:151]
	v_mfma_f32_16x16x32_bf16 v[140:143], v[56:59], v[220:223], v[140:143]
	v_mfma_f32_16x16x32_bf16 v[132:135], v[64:67], v[220:223], v[132:135]
	v_mfma_f32_16x16x32_bf16 v[124:127], v[56:59], v[228:231], v[124:127]
	v_mfma_f32_16x16x32_bf16 v[120:123], v[64:67], v[228:231], v[120:123]
	s_setprio 0
	s_setprio 1
	v_mfma_f32_16x16x32_bf16 v[152:155], v[80:83], v[72:75], v[168:171]
	v_mfma_f32_16x16x32_bf16 v[72:75], v[176:179], v[72:75], v[88:91]
	v_mfma_f32_16x16x32_bf16 v[160:163], v[212:215], v[104:107], v[72:75]
	v_mfma_f32_16x16x32_bf16 v[72:75], v[80:83], v[136:139], v[92:95]
	v_mfma_f32_16x16x32_bf16 v[168:171], v[84:87], v[104:107], v[152:155]
	v_mfma_f32_16x16x32_bf16 v[152:155], v[84:87], v[144:147], v[72:75]
	v_mfma_f32_16x16x32_bf16 v[72:75], v[176:179], v[136:139], v[96:99]
	v_mfma_f32_16x16x32_bf16 v[144:147], v[212:215], v[144:147], v[72:75]
	v_mfma_f32_16x16x32_bf16 v[72:75], v[80:83], v[216:219], v[100:103]
	v_mfma_f32_16x16x32_bf16 v[136:139], v[84:87], v[220:223], v[72:75]
	v_mfma_f32_16x16x32_bf16 v[72:75], v[176:179], v[216:219], v[128:131]
	v_mfma_f32_16x16x32_bf16 v[128:131], v[212:215], v[220:223], v[72:75]
	v_mfma_f32_16x16x32_bf16 v[72:75], v[80:83], v[224:227], v[116:119]
	v_mfma_f32_16x16x32_bf16 v[116:119], v[84:87], v[228:231], v[72:75]
	v_mfma_f32_16x16x32_bf16 v[72:75], v[176:179], v[224:227], v[112:115]
	v_mfma_f32_16x16x32_bf16 v[112:115], v[212:215], v[228:231], v[72:75]
	s_setprio 0
	s_barrier
	s_add_i32 s50, s75, s56
	v_lshl_add_u64 v[104:105], v[232:233], 0, s[22:23]
	s_mov_b32 m0, s50
	s_nop 1
	ds_read_b128 v[72:75], v199 offset:49152
	ds_read_b128 v[88:91], v199 offset:50176
	ds_read_b128 v[92:95], v199 offset:51200
	ds_read_b128 v[96:99], v199 offset:52224
	ds_read_b128 v[100:103], v199 offset:53248
	ds_read_b128 v[216:219], v199 offset:54272
	ds_read_b128 v[220:223], v199 offset:55296
	ds_read_b128 v[224:227], v199 offset:56320
	global_load_lds_dwordx4 v[104:105], off
	s_add_i32 m0, s50, 0x2000
	s_add_u32 s48, s48, 0x80080
	v_lshl_add_u64 v[104:105], v[234:235], 0, s[22:23]
	s_addc_u32 s49, s49, 0
	s_add_i32 s50, s76, s56
	global_load_lds_dwordx4 v[104:105], off
	v_lshl_add_u64 v[104:105], s[48:49], 0, v[182:183]
	s_mov_b32 m0, s50
	s_nop 0
	global_load_lds_dwordx4 v[104:105], off
	v_lshl_add_u64 v[104:105], s[48:49], 0, v[186:187]
	s_add_i32 m0, s50, 0x2000
	s_nop 0
	global_load_lds_dwordx4 v[104:105], off
	v_lshl_add_u64 v[104:105], v[236:237], 0, s[22:23]
	s_mov_b32 m0, s63
	s_nop 0
	global_load_lds_dwordx4 v[104:105], off
	v_lshl_add_u64 v[104:105], v[238:239], 0, s[22:23]
	s_mov_b32 m0, s64
	s_nop 0
	global_load_lds_dwordx4 v[104:105], off
	s_waitcnt vmcnt(8)
	s_waitcnt lgkmcnt(0)
	s_barrier
	s_setprio 1
	s_waitcnt lgkmcnt(0)
	v_mfma_f32_16x16x32_bf16 v[104:107], v[52:55], v[72:75], v[108:111]
	v_mfma_f32_16x16x32_bf16 v[76:79], v[60:63], v[72:75], v[76:79]
	v_mfma_f32_16x16x32_bf16 v[68:71], v[52:55], v[92:95], v[68:71]
	v_mfma_f32_16x16x32_bf16 v[36:39], v[60:63], v[92:95], v[36:39]
	v_mfma_f32_16x16x32_bf16 v[28:31], v[52:55], v[100:103], v[28:31]
	v_mfma_f32_16x16x32_bf16 v[20:23], v[60:63], v[100:103], v[20:23]
	v_mfma_f32_16x16x32_bf16 v[12:15], v[52:55], v[220:223], v[12:15]
	v_mfma_f32_16x16x32_bf16 v[8:11], v[60:63], v[220:223], v[8:11]
	v_mfma_f32_16x16x32_bf16 v[108:111], v[56:59], v[88:91], v[104:107]
	v_mfma_f32_16x16x32_bf16 v[76:79], v[64:67], v[88:91], v[76:79]
	v_mfma_f32_16x16x32_bf16 v[68:71], v[56:59], v[96:99], v[68:71]
	v_mfma_f32_16x16x32_bf16 v[36:39], v[64:67], v[96:99], v[36:39]
	v_mfma_f32_16x16x32_bf16 v[28:31], v[56:59], v[216:219], v[28:31]
	v_mfma_f32_16x16x32_bf16 v[20:23], v[64:67], v[216:219], v[20:23]
	v_mfma_f32_16x16x32_bf16 v[12:15], v[56:59], v[224:227], v[12:15]
	v_mfma_f32_16x16x32_bf16 v[8:11], v[64:67], v[224:227], v[8:11]
	s_setprio 0
	s_setprio 1
	v_mfma_f32_16x16x32_bf16 v[44:47], v[80:83], v[72:75], v[44:47]
	v_mfma_f32_16x16x32_bf16 v[104:107], v[84:87], v[88:91], v[44:47]
	v_mfma_f32_16x16x32_bf16 v[44:47], v[176:179], v[72:75], v[48:51]
	v_mfma_f32_16x16x32_bf16 v[40:43], v[80:83], v[92:95], v[40:43]
	v_mfma_f32_16x16x32_bf16 v[32:35], v[176:179], v[92:95], v[32:35]
	v_mfma_f32_16x16x32_bf16 v[24:27], v[80:83], v[100:103], v[24:27]
	v_mfma_f32_16x16x32_bf16 v[16:19], v[176:179], v[100:103], v[16:19]
	v_mfma_f32_16x16x32_bf16 v[4:7], v[80:83], v[220:223], v[4:7]
	v_mfma_f32_16x16x32_bf16 v[0:3], v[176:179], v[220:223], v[0:3]
	v_mfma_f32_16x16x32_bf16 v[72:75], v[212:215], v[88:91], v[44:47]
	v_mfma_f32_16x16x32_bf16 v[40:43], v[84:87], v[96:99], v[40:43]
	v_mfma_f32_16x16x32_bf16 v[32:35], v[212:215], v[96:99], v[32:35]
	v_mfma_f32_16x16x32_bf16 v[24:27], v[84:87], v[216:219], v[24:27]
	v_mfma_f32_16x16x32_bf16 v[16:19], v[212:215], v[216:219], v[16:19]
	v_mfma_f32_16x16x32_bf16 v[4:7], v[84:87], v[224:227], v[4:7]
	v_mfma_f32_16x16x32_bf16 v[0:3], v[212:215], v[224:227], v[0:3]
	s_setprio 0
	s_barrier
	s_add_i32 s74, s74, 2
	s_add_u32 s46, s46, 0x100
	s_addc_u32 s47, s47, 0
	s_add_u32 s72, s72, 0x100
	s_addc_u32 s73, s73, 0
	s_cmp_gt_u32 s74, 29
	s_cbranch_scc0 .LBB0_1951

; #define PG8_WAIT_V(n) asm volatile("s_waitcnt vmcnt(" #n ")" ::: "memory")
; template <class Epi, class Sched, bool ALIGN_EPI = false, bool SP2 = false>
; __device__ __forceinline__ void gemm_phase(PG8_LAS unsigned char* lds, const Gemm g, const Sched& S, const Epi& E, const int wave_in) {
;     const int lane = lane_id_asm(), wid = __builtin_amdgcn_readfirstlane(wave_in), tid = wid * 64 + lane, wr = wid >> 2, wc = wid & 3, fr = lane & 15, fq = lane >> 4;
;     const int K = g.K, nt = K / BK;
;     unsigned voffA[2], voffB[2];
; #pragma unroll
;     for (int i = 0; i < 2; ++i) { int R, C; stage_rc(tid * 16 + i * 8192, R, C); const int Rb = Epi::PERM ? ((R & ~31) + perm32(R & 31)) : R;
;         voffA[i] = (unsigned)(R * g.lda + C) * 2u; voffB[i] = (unsigned)(Rb * K + C) * 2u; }
;     const size_t kstep = (size_t)(BK * 2);
;     const size_t hstepA = (size_t)HALF * g.lda * 2, hstepB = (size_t)HALF * K * 2;
;     const size_t tstepA = 2 * hstepA, tstepB = 2 * hstepB;
;     const unsigned ldsw = (unsigned)wid * 1024u;
;     const int aoff = lds_byte(wr * 64 + fr, fq * 8), boff = lds_byte(wc * 32 + fr, fq * 8);
;     ...
;     Unit cur, nxt; int ui = 0;
;     if (!S.next(0, cur)) return;
;     f32x4 acc[2][2][4][2];
; #pragma unroll
;     for (int a = 0; a < 2; ++a)
; #pragma unroll
;         for (int b = 0; b < 2; ++b)
; #pragma unroll
;             for (int m = 0; m < 4; ++m)
; #pragma unroll
;                 for (int n = 0; n < 2; ++n) acc[a][b][m][n] = (f32x4){0.f, 0.f, 0.f, 0.f};
;     bf16x8 At[4][2], B0[2][2], B1[2][2];
;     const char* cA = (const char*)g.A + (size_t)cur.pm * tstepA; const char* cB = (const char*)g.Bt + (size_t)cur.pn * tstepB;
;     S.a_ready(cur);
;     if constexpr (SP2) {
;         PG8_STAGE(PG8_SB(0, 0), cB, voffB); PG8_STAGE(PG8_SB(0, 1), cB + hstepB, voffB); PG8_STAGE(PG8_SA(0, 0), cA, voffA); PG8_STAGE(PG8_SA(0, 1), cA + hstepA, voffA);
;         if (wr == 1) PG8_BAR;
;         PG8_WAIT_V(2); PG8_BAR;
;         PG8_STAGE(PG8_SB(1, 0), cB + kstep, voffB); PG8_STAGE(PG8_SA(1, 0), cA + kstep, voffA); PG8_STAGE(PG8_SB(1, 1), cB + hstepB + kstep, voffB);
;         PG8_WAIT_V(6); PG8_BAR;
;     } else {
;         PG8_STAGE(PG8_SB(0, 0), cB, voffB); PG8_STAGE(PG8_SA(0, 0), cA, voffA); PG8_STAGE(PG8_SB(0, 1), cB + hstepB, voffB); PG8_STAGE(PG8_SA(0, 1), cA + hstepA, voffA);
;         if (wr == 1) PG8_BAR;
;         PG8_WAIT_V(4); PG8_BAR;
.LBB0_2093:
	s_cmp_gt_i32 s52, 24
	s_cselect_b64 s[0:1], -1, 0
	s_cmp_lt_i32 s53, 25
	s_cselect_b64 s[2:3], -1, 0
	s_or_b64 s[0:1], s[0:1], s[2:3]
	s_and_b64 vcc, exec, s[0:1]
	s_cbranch_vccnz .LBB0_2164
	s_mov_b32 s99, 0
	s_cmpk_gt_i32 s73, 0x47f
	v_mbcnt_lo_u32_b32 v10, -1, 0
	v_mbcnt_hi_u32_b32 v10, -1, v10
	s_cbranch_scc1 .LBB0_2114
	s_waitcnt lgkmcnt(0)
	s_add_u32 s30, s70, 0xa700000
	s_addc_u32 s31, s71, 0
	s_add_u32 s34, s70, 0x9100000
	s_addc_u32 s35, s71, 0
	s_lshl_b32 s36, s33, 10
	v_lshl_add_u32 v0, v10, 4, s36
	v_add_u32_e32 v1, 0x2000, v0
	v_ashrrev_i32_e32 v2, 31, v1
	v_lshrrev_b32_e32 v2, 22, v2
	v_add_u32_e32 v2, v1, v2
	v_ashrrev_i32_e32 v8, 10, v2
	v_mul_i32_i24_e32 v2, 0x400, v8
	v_sub_u32_e32 v1, v1, v2
	v_lshrrev_b32_e32 v2, 4, v1
	v_bitop3_b32 v1, v2, v1, 32 bitop3:0x6c
	v_ashrrev_i32_e32 v2, 31, v1
	v_lshrrev_b32_e32 v2, 26, v2
	v_add_u32_e32 v2, v1, v2
	v_ashrrev_i32_e32 v9, 6, v2
	v_lshlrev_b32_e32 v3, 3, v8
	v_and_b32_e32 v2, 0xffc0, v2
	v_and_b32_e32 v3, -16, v3
	v_sub_u32_e32 v1, v1, v2
	v_add_u32_e32 v3, v9, v3
	v_lshrrev_b16_e32 v2, 7, v1
	v_and_b32_e32 v4, 3, v9
	s_mov_b32 s0, 0x1ffffe0
	v_lshrrev_b32_e32 v5, 2, v3
	v_lshlrev_b32_e32 v6, 1, v3
	v_and_b32_e32 v2, 1, v2
	v_and_or_b32 v4, v3, s0, v4
	v_and_b32_e32 v5, 4, v5
	v_and_b32_e32 v6, 24, v6
	v_add_u16_e32 v1, v1, v2
	v_mov_b32_e32 v2, 1
	v_or3_b32 v4, v4, v5, v6
	v_lshlrev_b32_e32 v5, 5, v8
	v_ashrrev_i16_sdwa v1, v2, sext(v1) dst_sel:DWORD dst_unused:UNUSED_PAD src0_sel:DWORD src1_sel:BYTE_0
	s_movk_i32 s2, 0x1580
	v_and_b32_e32 v11, 32, v5
	v_bfe_i32 v12, v1, 0, 16
	v_mul_lo_u32 v4, v4, s2
	v_add_u32_e32 v1, v11, v12
	v_mul_lo_u32 v3, v3, s2
	v_add_lshl_u32 v144, v4, v1, 1
	v_add_lshl_u32 v146, v1, v3, 1
	v_ashrrev_i32_e32 v1, 31, v0
	v_lshrrev_b32_e32 v1, 22, v1
	v_add_u32_e32 v1, v0, v1
	v_ashrrev_i32_e32 v13, 10, v1
	v_mul_i32_i24_e32 v1, 0x400, v13
	v_sub_u32_e32 v0, v0, v1
	v_lshrrev_b32_e32 v1, 4, v0
	v_bitop3_b32 v0, v1, v0, 32 bitop3:0x6c
	v_ashrrev_i32_e32 v1, 31, v0
	v_lshrrev_b32_e32 v1, 26, v1
	v_add_u32_e32 v1, v0, v1
	v_lshlrev_b32_e32 v3, 3, v13
	v_ashrrev_i32_e32 v14, 6, v1
	v_and_b32_e32 v3, -16, v3
	v_add_u32_e32 v3, v14, v3
	v_and_b32_e32 v4, 3, v14
	s_ashr_i32 s37, s73, 31
	v_and_or_b32 v4, v3, s0, v4
	s_lshr_b32 s0, s37, 29
	s_add_i32 s0, s73, s0
	s_ashr_i32 s1, s0, 3
	s_and_b32 s0, s0, -8
	s_ashr_i32 s3, s33, 2
	s_sub_i32 s0, s73, s0
	s_cmp_lt_i32 s0, 0
	s_movk_i32 s38, 0x91
	s_cselect_b32 s4, s38, 0x90
	s_mul_i32 s0, s4, s0
	s_add_i32 s0, s0, s1
	s_ashr_i32 s1, s0, 31
	s_lshr_b32 s1, s1, 27
	s_add_i32 s1, s0, s1
	s_ashr_i32 s4, s1, 5
	s_andn2_b32 s1, s1, 31
	s_sub_i32 s0, s0, s1
	s_bfe_i32 s1, s0, 0x80000
	s_bfe_u32 s1, s1, 0x2000d
	s_add_i32 s1, s0, s1
	s_lshl_b32 s5, s4, 2
	s_bfe_i32 s4, s1, 0x80000
	s_and_b32 s1, s1, 0xfc
	s_sub_i32 s0, s0, s1
	v_lshrrev_b32_e32 v5, 2, v3
	v_lshlrev_b32_e32 v6, 1, v3
	v_and_b32_e32 v1, 0xc0, v1
	s_sext_i32_i16 s6, s4
	s_sext_i32_i8 s0, s0
	v_and_b32_e32 v5, 4, v5
	v_and_b32_e32 v6, 24, v6
	v_sub_u32_e32 v0, v0, v1
	s_add_i32 s20, s5, s0
	s_ashr_i32 s0, s6, 2
	v_or3_b32 v4, v4, v5, v6
	v_lshlrev_b32_e32 v5, 5, v13
	v_ashrrev_i16_sdwa v0, v2, sext(v0) dst_sel:DWORD dst_unused:UNUSED_PAD src0_sel:DWORD src1_sel:BYTE_0
	s_lshr_b32 s4, s6, 2
	s_mul_hi_i32 s1, s0, 0x2b0000
	s_mul_i32 s0, s0, 0x2b0000
	v_and_b32_e32 v15, 32, v5
	v_bfe_i32 v16, v0, 0, 16
	s_add_u32 s24, s34, s0
	v_mul_lo_u32 v4, v4, s2
	v_add_u32_e32 v0, v15, v16
	s_addc_u32 s25, s35, s1
	s_add_i32 s39, s36, 0
	v_add_lshl_u32 v148, v4, v0, 1
	s_add_i32 m0, s39, 0x10000
	s_mul_i32 s7, s20, 0x2b0000
	global_load_lds_dwordx4 v148, s[24:25]
	s_add_i32 m0, s39, 0x12000
	s_add_u32 s0, s24, 0x158000
	global_load_lds_dwordx4 v144, s[24:25]
	s_addc_u32 s1, s25, 0
	s_add_i32 m0, s39, 0x14000
	s_mul_hi_i32 s5, s20, 0x2b0000
	global_load_lds_dwordx4 v148, s[0:1]
	s_add_i32 m0, s39, 0x16000
	s_add_u32 s22, s30, s7
	v_mul_lo_u32 v1, v3, s2
	s_addc_u32 s23, s31, s5
	s_add_i32 s40, s39, 0x2000
	v_add_lshl_u32 v150, v0, v1, 1
	global_load_lds_dwordx4 v144, s[0:1]
	s_mov_b32 m0, s39
	s_add_u32 s0, s22, 0x158000
	global_load_lds_dwordx4 v150, s[22:23]
	s_mov_b32 m0, s40
	s_addc_u32 s1, s23, 0
	s_add_i32 s41, s39, 0x4000
	global_load_lds_dwordx4 v146, s[22:23]
	s_mov_b32 m0, s41
	s_add_i32 s42, s39, 0x6000
	global_load_lds_dwordx4 v150, s[0:1]
	s_mov_b32 m0, s42
	v_mov_b32_e32 v149, 0
	global_load_lds_dwordx4 v146, s[0:1]
	v_mov_b32_e32 v145, v149
	v_mov_b32_e32 v151, v149
	v_mov_b32_e32 v147, v149
	s_cmp_eq_u32 s3, 1
	s_mov_b32 s43, 0
	v_lshl_add_u64 v[6:7], s[24:25], 0, v[148:149]
	v_lshl_add_u64 v[4:5], s[24:25], 0, v[144:145]
	v_lshl_add_u64 v[0:1], s[22:23], 0, v[150:151]
	s_cselect_b64 s[0:1], -1, 0
	s_cmp_lg_u32 s3, 1
	v_lshl_add_u64 v[2:3], s[22:23], 0, v[146:147]
	s_cbranch_scc1 .LBB0_2097
	s_barrier

; #define PG8_STAGE(bufoff, gbase, voff) do { _Pragma("unroll") for (int _i = 0; _i < 2; ++_i) \
;         __builtin_amdgcn_global_load_lds((const unsigned*)((const char*)(gbase) + (voff)[_i]), (PG8_LAS unsigned*)(lds + (bufoff) + ldsw + _i * 8192), 16, 0, 0); } while (0)
; #define PG8_LDA(dst, b, h) do { _Pragma("unroll") for (int m = 0; m < 4; ++m) _Pragma("unroll") for (int k = 0; k < 2; ++k) dst[m][k] = *(const PG8_LAS bf16x8*)(lds + PG8_SA(b, h) + aoff + m * 2048 + k * 1024); } while (0)
; #define PG8_LDB(dst, b, h) do { _Pragma("unroll") for (int n = 0; n < 2; ++n) _Pragma("unroll") for (int k = 0; k < 2; ++k) dst[n][k] = *(const PG8_LAS bf16x8*)(lds + PG8_SB(b, h) + boff + n * 2048 + k * 1024); } while (0)
; #define PG8_MMA(ai, bj, At, Bt) do { __builtin_amdgcn_s_setprio(1); _Pragma("unroll") for (int m = 0; m < 4; ++m) _Pragma("unroll") for (int n = 0; n < 2; ++n) _Pragma("unroll") for (int k = 0; k < 2; ++k) \
;         acc[ai][bj][m][n] = __builtin_amdgcn_mfma_f32_16x16x32_bf16(Bt[n][k], At[m][k], acc[ai][bj][m][n], 0, 0, 0); __builtin_amdgcn_s_setprio(0); } while (0)
; #define PG8_WAIT_V(n) asm volatile("s_waitcnt vmcnt(" #n ")" ::: "memory")
; #define PG8_WAIT_L(n) asm volatile("s_waitcnt lgkmcnt(" #n ")" ::: "memory")
; #define PG8_BAR __builtin_amdgcn_s_barrier()
; #define PG8_SCHED __builtin_amdgcn_sched_barrier(0)
; template <class Epi, class Sched, bool ALIGN_EPI = false, bool SP2 = false>
; __device__ __forceinline__ void gemm_phase(PG8_LAS unsigned char* lds, const Gemm g, const Sched& S, const Epi& E, const int wave_in) {
;     ...
;             PG8_LDB(B0, 0, 0); PG8_LDB(B1, 0, 1); PG8_SCHED; PG8_LDA(At, 0, 0); PG8_STAGE(PG8_SA(1, 1), a1 + hstepA, voffA);
;             PG8_WAIT_V(8); PG8_WAIT_L(0); PG8_BAR; PG8_MMA(0, 0, At, B0); PG8_MMA(0, 1, At, B1); PG8_BAR; PG8_SCHED;
;     ...
; #pragma unroll
;         for (int a = 0; a < 2; ++a)
; #pragma unroll
;             for (int b = 0; b < 2; ++b)
; #pragma unroll
;                 for (int m = 0; m < 4; ++m)
; #pragma unroll
;                     for (int n = 0; n < 2; ++n) acc[a][b][m][n] = (f32x4){0.f, 0.f, 0.f, 0.f};
;         cur = nxt; cA = nA; cB = nB; ++ui;
.LBB0_2106:
	s_add_u32 s21, s24, 0x100
	v_mov_b32_e32 v0, 0
	s_addc_u32 s58, s25, 0
	s_mov_b32 s59, -2
	v_mov_b32_e32 v1, v0
	v_mov_b32_e32 v2, v0
	v_mov_b32_e32 v3, v0
	v_mov_b32_e32 v4, v0
	v_mov_b32_e32 v5, v0
	v_mov_b32_e32 v6, v0
	v_mov_b32_e32 v7, v0
	v_mov_b32_e32 v12, v0
	v_mov_b32_e32 v13, v0
	v_mov_b32_e32 v14, v0
	v_mov_b32_e32 v15, v0
	v_mov_b32_e32 v20, v0
	v_mov_b32_e32 v21, v0
	v_mov_b32_e32 v22, v0
	v_mov_b32_e32 v23, v0
	v_mov_b32_e32 v28, v0
	v_mov_b32_e32 v29, v0
	v_mov_b32_e32 v30, v0
	v_mov_b32_e32 v31, v0
	v_mov_b32_e32 v36, v0
	v_mov_b32_e32 v37, v0
	v_mov_b32_e32 v38, v0
	v_mov_b32_e32 v39, v0
	v_mov_b32_e32 v44, v0
	v_mov_b32_e32 v45, v0
	v_mov_b32_e32 v46, v0
	v_mov_b32_e32 v47, v0
	v_mov_b32_e32 v52, v0
	v_mov_b32_e32 v53, v0
	v_mov_b32_e32 v54, v0
	v_mov_b32_e32 v55, v0
	v_mov_b32_e32 v8, v0
	v_mov_b32_e32 v9, v0
	v_mov_b32_e32 v10, v0
	v_mov_b32_e32 v11, v0
	v_mov_b32_e32 v16, v0
	v_mov_b32_e32 v17, v0
	v_mov_b32_e32 v18, v0
	v_mov_b32_e32 v19, v0
	v_mov_b32_e32 v24, v0
	v_mov_b32_e32 v25, v0
	v_mov_b32_e32 v26, v0
	v_mov_b32_e32 v27, v0
	v_mov_b32_e32 v32, v0
	v_mov_b32_e32 v33, v0
	v_mov_b32_e32 v34, v0
	v_mov_b32_e32 v35, v0
	v_mov_b32_e32 v40, v0
	v_mov_b32_e32 v41, v0
	v_mov_b32_e32 v42, v0
	v_mov_b32_e32 v43, v0
	v_mov_b32_e32 v48, v0
	v_mov_b32_e32 v49, v0
	v_mov_b32_e32 v50, v0
	v_mov_b32_e32 v51, v0
	v_mov_b32_e32 v56, v0
	v_mov_b32_e32 v57, v0
	v_mov_b32_e32 v58, v0
	v_mov_b32_e32 v59, v0
	v_mov_b32_e32 v60, v0
	v_mov_b32_e32 v61, v0
	v_mov_b32_e32 v62, v0
	v_mov_b32_e32 v63, v0
	v_mov_b32_e32 v64, v0
	v_mov_b32_e32 v65, v0
	v_mov_b32_e32 v66, v0
	v_mov_b32_e32 v67, v0
	v_mov_b32_e32 v68, v0
	v_mov_b32_e32 v69, v0
	v_mov_b32_e32 v70, v0
	v_mov_b32_e32 v71, v0
	v_mov_b32_e32 v80, v0
	v_mov_b32_e32 v81, v0
	v_mov_b32_e32 v82, v0
	v_mov_b32_e32 v83, v0
	v_mov_b32_e32 v84, v0
	v_mov_b32_e32 v85, v0
	v_mov_b32_e32 v86, v0
	v_mov_b32_e32 v87, v0
	v_mov_b32_e32 v88, v0
	v_mov_b32_e32 v89, v0
	v_mov_b32_e32 v90, v0
	v_mov_b32_e32 v91, v0
	v_mov_b32_e32 v92, v0
	v_mov_b32_e32 v93, v0
	v_mov_b32_e32 v94, v0
	v_mov_b32_e32 v95, v0
	v_mov_b32_e32 v108, v0
	v_mov_b32_e32 v109, v0
	v_mov_b32_e32 v110, v0
	v_mov_b32_e32 v111, v0
	s_waitcnt vmcnt(0)
	v_mov_b32_e32 v116, v0
	v_mov_b32_e32 v117, v0
	v_mov_b32_e32 v118, v0
	v_mov_b32_e32 v119, v0
	v_mov_b32_e32 v72, v0
	v_mov_b32_e32 v73, v0
	v_mov_b32_e32 v74, v0
	v_mov_b32_e32 v75, v0
	v_mov_b32_e32 v76, v0
	v_mov_b32_e32 v77, v0
	v_mov_b32_e32 v78, v0
	v_mov_b32_e32 v79, v0
	v_mov_b32_e32 v96, v0
	v_mov_b32_e32 v97, v0
	v_mov_b32_e32 v98, v0
	v_mov_b32_e32 v99, v0
	v_mov_b32_e32 v100, v0
	v_mov_b32_e32 v101, v0
	v_mov_b32_e32 v102, v0
	v_mov_b32_e32 v103, v0
	v_mov_b32_e32 v104, v0
	v_mov_b32_e32 v105, v0
	v_mov_b32_e32 v106, v0
	v_mov_b32_e32 v107, v0
	v_mov_b32_e32 v112, v0
	v_mov_b32_e32 v113, v0
	v_mov_b32_e32 v114, v0
	v_mov_b32_e32 v115, v0
	v_mov_b32_e32 v120, v0
	v_mov_b32_e32 v121, v0
	v_mov_b32_e32 v122, v0
	v_mov_b32_e32 v123, v0
	v_mov_b32_e32 v124, v0
	v_mov_b32_e32 v125, v0
	v_mov_b32_e32 v126, v0
	v_mov_b32_e32 v127, v0
	s_cmp_lg_u32 s99, 0
	s_cbranch_scc0 .LBB0_2107
	ds_read_b128 v[128:131], v214
	ds_read_b128 v[132:135], v214 offset:1024
	ds_read_b128 v[136:139], v214 offset:2048
	ds_read_b128 v[140:143], v214 offset:3072
	ds_read_b128 v[162:165], v215
	ds_read_b128 v[166:169], v215 offset:1024
	ds_read_b128 v[170:173], v215 offset:2048
	ds_read_b128 v[174:177], v215 offset:3072
	s_add_u32 s24, s22, 0x100
	s_addc_u32 s25, s23, 0
	s_cmpk_eq_i32 s59, 0x52
	s_cselect_b32 s29, s5, s25
	s_cselect_b32 s28, s4, s24
	s_cselect_b32 s27, s19, s58
	s_cselect_b32 s26, s18, s21
	v_lshl_add_u64 v[210:211], s[22:23], 0, v[154:155]
	s_add_i32 m0, s39, 0xc000
	ds_read_b128 v[178:181], v216
	ds_read_b128 v[182:185], v216 offset:1024
	ds_read_b128 v[186:189], v216 offset:2048
	ds_read_b128 v[190:193], v216 offset:3072
	ds_read_b128 v[194:197], v216 offset:4096
	ds_read_b128 v[198:201], v216 offset:5120
	ds_read_b128 v[202:205], v216 offset:6144
	ds_read_b128 v[206:209], v216 offset:7168
	global_load_lds_dwordx4 v[210:211], off
	v_lshl_add_u64 v[210:211], s[22:23], 0, v[156:157]
	s_add_i32 m0, s39, 0xe000
	s_nop 0
	global_load_lds_dwordx4 v[210:211], off
	s_waitcnt vmcnt(24)
	s_waitcnt lgkmcnt(0)
	s_barrier
	s_setprio 1
	s_waitcnt lgkmcnt(0)
	v_mfma_f32_16x16x32_bf16 v[124:127], v[128:131], v[178:181], v[124:127]
	v_mfma_f32_16x16x32_bf16 v[120:123], v[136:139], v[178:181], v[120:123]
	v_mfma_f32_16x16x32_bf16 v[112:115], v[128:131], v[186:189], v[112:115]
	v_mfma_f32_16x16x32_bf16 v[104:107], v[136:139], v[186:189], v[104:107]
	v_mfma_f32_16x16x32_bf16 v[100:103], v[128:131], v[194:197], v[100:103]
	v_mfma_f32_16x16x32_bf16 v[96:99], v[136:139], v[194:197], v[96:99]
	v_mfma_f32_16x16x32_bf16 v[76:79], v[128:131], v[202:205], v[76:79]
	v_mfma_f32_16x16x32_bf16 v[72:75], v[136:139], v[202:205], v[72:75]
	v_mfma_f32_16x16x32_bf16 v[124:127], v[132:135], v[182:185], v[124:127]
	v_mfma_f32_16x16x32_bf16 v[120:123], v[140:143], v[182:185], v[120:123]
	v_mfma_f32_16x16x32_bf16 v[112:115], v[132:135], v[190:193], v[112:115]
	v_mfma_f32_16x16x32_bf16 v[104:107], v[140:143], v[190:193], v[104:107]
	v_mfma_f32_16x16x32_bf16 v[100:103], v[132:135], v[198:201], v[100:103]
	v_mfma_f32_16x16x32_bf16 v[96:99], v[140:143], v[198:201], v[96:99]
	v_mfma_f32_16x16x32_bf16 v[76:79], v[132:135], v[206:209], v[76:79]
	v_mfma_f32_16x16x32_bf16 v[72:75], v[140:143], v[206:209], v[72:75]
	s_setprio 0
	s_setprio 1
	v_mfma_f32_16x16x32_bf16 v[116:119], v[162:165], v[178:181], v[116:119]
	v_mfma_f32_16x16x32_bf16 v[108:111], v[170:173], v[178:181], v[108:111]
	v_mfma_f32_16x16x32_bf16 v[92:95], v[162:165], v[186:189], v[92:95]
	v_mfma_f32_16x16x32_bf16 v[88:91], v[170:173], v[186:189], v[88:91]
	v_mfma_f32_16x16x32_bf16 v[84:87], v[162:165], v[194:197], v[84:87]
	v_mfma_f32_16x16x32_bf16 v[80:83], v[170:173], v[194:197], v[80:83]
	v_mfma_f32_16x16x32_bf16 v[68:71], v[162:165], v[202:205], v[68:71]
	v_mfma_f32_16x16x32_bf16 v[64:67], v[170:173], v[202:205], v[64:67]
	v_mfma_f32_16x16x32_bf16 v[116:119], v[166:169], v[182:185], v[116:119]
	v_mfma_f32_16x16x32_bf16 v[108:111], v[174:177], v[182:185], v[108:111]
	v_mfma_f32_16x16x32_bf16 v[92:95], v[166:169], v[190:193], v[92:95]
	v_mfma_f32_16x16x32_bf16 v[88:91], v[174:177], v[190:193], v[88:91]
	v_mfma_f32_16x16x32_bf16 v[84:87], v[166:169], v[198:201], v[84:87]
	v_mfma_f32_16x16x32_bf16 v[80:83], v[174:177], v[198:201], v[80:83]
	v_mfma_f32_16x16x32_bf16 v[68:71], v[166:169], v[206:209], v[68:71]
	v_mfma_f32_16x16x32_bf16 v[64:67], v[174:177], v[206:209], v[64:67]
	s_setprio 0
	s_barrier
; #define PG8_STAGE(bufoff, gbase, voff) do { _Pragma("unroll") for (int _i = 0; _i < 2; ++_i) \
;         __builtin_amdgcn_global_load_lds((const unsigned*)((const char*)(gbase) + (voff)[_i]), (PG8_LAS unsigned*)(lds + (bufoff) + ldsw + _i * 8192), 16, 0, 0); } while (0)
; #define PG8_LDA(dst, b, h) do { _Pragma("unroll") for (int m = 0; m < 4; ++m) _Pragma("unroll") for (int k = 0; k < 2; ++k) dst[m][k] = *(const PG8_LAS bf16x8*)(lds + PG8_SA(b, h) + aoff + m * 2048 + k * 1024); } while (0)
; #define PG8_LDB(dst, b, h) do { _Pragma("unroll") for (int n = 0; n < 2; ++n) _Pragma("unroll") for (int k = 0; k < 2; ++k) dst[n][k] = *(const PG8_LAS bf16x8*)(lds + PG8_SB(b, h) + boff + n * 2048 + k * 1024); } while (0)
; #define PG8_MMA(ai, bj, At, Bt) do { __builtin_amdgcn_s_setprio(1); _Pragma("unroll") for (int m = 0; m < 4; ++m) _Pragma("unroll") for (int n = 0; n < 2; ++n) _Pragma("unroll") for (int k = 0; k < 2; ++k) \
;         acc[ai][bj][m][n] = __builtin_amdgcn_mfma_f32_16x16x32_bf16(Bt[n][k], At[m][k], acc[ai][bj][m][n], 0, 0, 0); __builtin_amdgcn_s_setprio(0); } while (0)
; #define PG8_WAIT_V(n) asm volatile("s_waitcnt vmcnt(" #n ")" ::: "memory")
; #define PG8_WAIT_L(n) asm volatile("s_waitcnt lgkmcnt(" #n ")" ::: "memory")
; #define PG8_BAR __builtin_amdgcn_s_barrier()
; #define PG8_SCHED __builtin_amdgcn_sched_barrier(0)
; template <class Epi, class Sched, bool ALIGN_EPI = false, bool SP2 = false>
; __device__ __forceinline__ void gemm_phase(PG8_LAS unsigned char* lds, const Gemm g, const Sched& S, const Epi& E, const int wave_in) {
;     ...
;             PG8_LDA(At, 0, 1); PG8_STAGE(PG8_SB(0, 0), b2, voffB); PG8_STAGE(PG8_SB(0, 1), b2 + hstepB, voffB); PG8_STAGE(PG8_SA(0, 0), a2, voffA);
;             PG8_WAIT_V(8); PG8_WAIT_L(0); PG8_BAR; PG8_MMA(1, 0, At, B0); PG8_MMA(1, 1, At, B1); PG8_BAR; PG8_SCHED;
;             PG8_LDB(B0, 1, 0); PG8_LDB(B1, 1, 1); PG8_SCHED; PG8_LDA(At, 1, 0); PG8_STAGE(PG8_SA(0, 1), a2 + hstepA, voffA);
;             PG8_WAIT_V(8); PG8_WAIT_L(0); PG8_BAR; PG8_MMA(0, 0, At, B0); PG8_MMA(0, 1, At, B1); PG8_BAR; PG8_SCHED;
	s_add_i32 s22, s49, s36
	v_lshl_add_u64 v[210:211], s[26:27], 0, v[148:149]
	s_mov_b32 m0, s22
	ds_read_b128 v[178:181], v216 offset:16384
	ds_read_b128 v[182:185], v216 offset:17408
	ds_read_b128 v[186:189], v216 offset:18432
	ds_read_b128 v[190:193], v216 offset:19456
	ds_read_b128 v[194:197], v216 offset:20480
	ds_read_b128 v[198:201], v216 offset:21504
	ds_read_b128 v[202:205], v216 offset:22528
	ds_read_b128 v[206:209], v216 offset:23552
	global_load_lds_dwordx4 v[210:211], off
	s_add_i32 m0, s22, 0x2000
	s_add_u32 s22, s26, 0x158000
	v_lshl_add_u64 v[218:219], s[26:27], 0, v[144:145]
	s_addc_u32 s23, s27, 0
	s_add_i32 s60, s50, s36
	global_load_lds_dwordx4 v[218:219], off
	v_lshl_add_u64 v[220:221], s[22:23], 0, v[148:149]
	s_mov_b32 m0, s60
	v_lshl_add_u64 v[222:223], s[28:29], 0, v[146:147]
	global_load_lds_dwordx4 v[220:221], off
	v_lshl_add_u64 v[220:221], s[22:23], 0, v[144:145]
	s_add_i32 m0, s60, 0x2000
	s_nop 0
	global_load_lds_dwordx4 v[220:221], off
	v_lshl_add_u64 v[220:221], s[28:29], 0, v[150:151]
	s_mov_b32 m0, s39
	s_nop 0
	global_load_lds_dwordx4 v[220:221], off
	s_mov_b32 m0, s40
	s_nop 0
	global_load_lds_dwordx4 v[222:223], off
	s_waitcnt vmcnt(24)
	s_waitcnt lgkmcnt(0)
	s_barrier
	s_setprio 1
	s_waitcnt lgkmcnt(0)
	v_mfma_f32_16x16x32_bf16 v[60:63], v[128:131], v[178:181], v[60:63]
	v_mfma_f32_16x16x32_bf16 v[56:59], v[136:139], v[178:181], v[56:59]
	v_mfma_f32_16x16x32_bf16 v[48:51], v[128:131], v[186:189], v[48:51]
	v_mfma_f32_16x16x32_bf16 v[40:43], v[136:139], v[186:189], v[40:43]
	v_mfma_f32_16x16x32_bf16 v[32:35], v[128:131], v[194:197], v[32:35]
	v_mfma_f32_16x16x32_bf16 v[24:27], v[136:139], v[194:197], v[24:27]
	v_mfma_f32_16x16x32_bf16 v[16:19], v[128:131], v[202:205], v[16:19]
	v_mfma_f32_16x16x32_bf16 v[8:11], v[136:139], v[202:205], v[8:11]
	v_mfma_f32_16x16x32_bf16 v[60:63], v[132:135], v[182:185], v[60:63]
	v_mfma_f32_16x16x32_bf16 v[56:59], v[140:143], v[182:185], v[56:59]
	v_mfma_f32_16x16x32_bf16 v[48:51], v[132:135], v[190:193], v[48:51]
	v_mfma_f32_16x16x32_bf16 v[40:43], v[140:143], v[190:193], v[40:43]
	v_mfma_f32_16x16x32_bf16 v[32:35], v[132:135], v[198:201], v[32:35]
	v_mfma_f32_16x16x32_bf16 v[24:27], v[140:143], v[198:201], v[24:27]
	v_mfma_f32_16x16x32_bf16 v[16:19], v[132:135], v[206:209], v[16:19]
	v_mfma_f32_16x16x32_bf16 v[8:11], v[140:143], v[206:209], v[8:11]
	s_setprio 0
	s_setprio 1
	v_mfma_f32_16x16x32_bf16 v[52:55], v[162:165], v[178:181], v[52:55]
	v_mfma_f32_16x16x32_bf16 v[44:47], v[170:173], v[178:181], v[44:47]
	v_mfma_f32_16x16x32_bf16 v[36:39], v[162:165], v[186:189], v[36:39]
	v_mfma_f32_16x16x32_bf16 v[28:31], v[170:173], v[186:189], v[28:31]
	v_mfma_f32_16x16x32_bf16 v[20:23], v[162:165], v[194:197], v[20:23]
	v_mfma_f32_16x16x32_bf16 v[12:15], v[170:173], v[194:197], v[12:15]
	v_mfma_f32_16x16x32_bf16 v[4:7], v[162:165], v[202:205], v[4:7]
	v_mfma_f32_16x16x32_bf16 v[0:3], v[170:173], v[202:205], v[0:3]
	v_mfma_f32_16x16x32_bf16 v[52:55], v[166:169], v[182:185], v[52:55]
	v_mfma_f32_16x16x32_bf16 v[44:47], v[174:177], v[182:185], v[44:47]
	v_mfma_f32_16x16x32_bf16 v[36:39], v[166:169], v[190:193], v[36:39]
	v_mfma_f32_16x16x32_bf16 v[28:31], v[174:177], v[190:193], v[28:31]
	v_mfma_f32_16x16x32_bf16 v[20:23], v[166:169], v[198:201], v[20:23]
	v_mfma_f32_16x16x32_bf16 v[12:15], v[174:177], v[198:201], v[12:15]
	v_mfma_f32_16x16x32_bf16 v[4:7], v[166:169], v[206:209], v[4:7]
	v_mfma_f32_16x16x32_bf16 v[0:3], v[174:177], v[206:209], v[0:3]
	s_setprio 0
	s_barrier
	s_add_i32 s60, 0, 0x18000
	s_add_i32 s61, 0, 0x1c000
	v_add_u32_e32 v140, s60, v212
	v_add_u32_e32 v174, s61, v212
	ds_read_b128 v[128:131], v140
	ds_read_b128 v[132:135], v140 offset:1024
	ds_read_b128 v[136:139], v140 offset:2048
	ds_read_b128 v[140:143], v140 offset:3072
	ds_read_b128 v[162:165], v174
	ds_read_b128 v[166:169], v174 offset:1024
	ds_read_b128 v[170:173], v174 offset:2048
	ds_read_b128 v[174:177], v174 offset:3072
	s_add_u32 s22, s28, 0x158000
	s_addc_u32 s23, s29, 0
	s_mov_b32 m0, s41
	v_lshl_add_u64 v[224:225], s[22:23], 0, v[150:151]
	ds_read_b128 v[178:181], v216 offset:32768
	ds_read_b128 v[182:185], v216 offset:33792
	ds_read_b128 v[186:189], v216 offset:34816
	ds_read_b128 v[190:193], v216 offset:35840
	ds_read_b128 v[194:197], v216 offset:36864
	ds_read_b128 v[198:201], v216 offset:37888
	ds_read_b128 v[202:205], v216 offset:38912
	ds_read_b128 v[206:209], v216 offset:39936
	global_load_lds_dwordx4 v[224:225], off
	v_lshl_add_u64 v[224:225], s[22:23], 0, v[146:147]
	s_mov_b32 m0, s42
	s_nop 0
	global_load_lds_dwordx4 v[224:225], off
	s_waitcnt vmcnt(8)
	s_waitcnt lgkmcnt(0)
	s_barrier
; #define PG8_STAGE(bufoff, gbase, voff) do { _Pragma("unroll") for (int _i = 0; _i < 2; ++_i) \
;         __builtin_amdgcn_global_load_lds((const unsigned*)((const char*)(gbase) + (voff)[_i]), (PG8_LAS unsigned*)(lds + (bufoff) + ldsw + _i * 8192), 16, 0, 0); } while (0)
; #define PG8_LDA(dst, b, h) do { _Pragma("unroll") for (int m = 0; m < 4; ++m) _Pragma("unroll") for (int k = 0; k < 2; ++k) dst[m][k] = *(const PG8_LAS bf16x8*)(lds + PG8_SA(b, h) + aoff + m * 2048 + k * 1024); } while (0)
; #define PG8_WAIT_V(n) asm volatile("s_waitcnt vmcnt(" #n ")" ::: "memory")
; #define PG8_WAIT_L(n) asm volatile("s_waitcnt lgkmcnt(" #n ")" ::: "memory")
; #define PG8_BAR __builtin_amdgcn_s_barrier()
; template <class Epi, class Sched, bool ALIGN_EPI = false, bool SP2 = false>
; __device__ __forceinline__ void gemm_phase(PG8_LAS unsigned char* lds, const Gemm g, const Sched& S, const Epi& E, const int wave_in) {
;     ...
;         for (int t = 0; t < nt; t += 2) {
;             const bool last = (t == nt - 2);
;             const char* a1 = cA + (size_t)(t + 1) * kstep;
;             const char* a2 = last ? nA : cA + (size_t)(t + 2) * kstep; const char* b2 = last ? nB : cB + (size_t)(t + 2) * kstep;
;             const char* a3 = a2 + kstep; const char* b3 = b2 + kstep;
;             if (last && has_next) S.a_ready(nxt);
;             if constexpr (SP2) {
;             PG8_LDB(B0, 0, 0); PG8_LDB(B1, 0, 1); PG8_SCHED; PG8_LDA(At, 0, 0); PG8_STAGE(PG8_SA(1, 1), a1 + hstepA, voffA);
;             PG8_WAIT_V(8); PG8_WAIT_L(0); PG8_BAR; PG8_MMA(0, 0, At, B0); PG8_MMA(0, 1, At, B1); PG8_BAR; PG8_SCHED;
;             PG8_LDA(At, 0, 1); PG8_STAGE(PG8_SB(0, 0), b2, voffB); PG8_STAGE(PG8_SB(0, 1), b2 + hstepB, voffB); PG8_STAGE(PG8_SA(0, 0), a2, voffA);
;             PG8_WAIT_V(8); PG8_WAIT_L(0); PG8_BAR; PG8_MMA(1, 0, At, B0); PG8_MMA(1, 1, At, B1); PG8_BAR; PG8_SCHED;
;             PG8_LDB(B0, 1, 0); PG8_LDB(B1, 1, 1); PG8_SCHED; PG8_LDA(At, 1, 0); PG8_STAGE(PG8_SA(0, 1), a2 + hstepA, voffA);
;             PG8_WAIT_V(8); PG8_WAIT_L(0); PG8_BAR; PG8_MMA(0, 0, At, B0); PG8_MMA(0, 1, At, B1); PG8_BAR; PG8_SCHED;
;             PG8_LDA(At, 1, 1); PG8_STAGE(PG8_SB(1, 0), b3, voffB); PG8_STAGE(PG8_SB(1, 1), b3 + hstepB, voffB); PG8_STAGE(PG8_SA(1, 0), a3, voffA);
;             PG8_WAIT_V(8); PG8_WAIT_L(0); PG8_BAR; PG8_MMA(1, 0, At, B0); PG8_MMA(1, 1, At, B1); PG8_BAR; PG8_SCHED;
	s_setprio 1
	s_waitcnt lgkmcnt(0)
	v_mfma_f32_16x16x32_bf16 v[124:127], v[128:131], v[178:181], v[124:127]
	v_mfma_f32_16x16x32_bf16 v[120:123], v[136:139], v[178:181], v[120:123]
	v_mfma_f32_16x16x32_bf16 v[112:115], v[128:131], v[186:189], v[112:115]
	v_mfma_f32_16x16x32_bf16 v[104:107], v[136:139], v[186:189], v[104:107]
	v_mfma_f32_16x16x32_bf16 v[100:103], v[128:131], v[194:197], v[100:103]
	v_mfma_f32_16x16x32_bf16 v[96:99], v[136:139], v[194:197], v[96:99]
	v_mfma_f32_16x16x32_bf16 v[76:79], v[128:131], v[202:205], v[76:79]
	v_mfma_f32_16x16x32_bf16 v[72:75], v[136:139], v[202:205], v[72:75]
	v_mfma_f32_16x16x32_bf16 v[124:127], v[132:135], v[182:185], v[124:127]
	v_mfma_f32_16x16x32_bf16 v[120:123], v[140:143], v[182:185], v[120:123]
	v_mfma_f32_16x16x32_bf16 v[112:115], v[132:135], v[190:193], v[112:115]
	v_mfma_f32_16x16x32_bf16 v[104:107], v[140:143], v[190:193], v[104:107]
	v_mfma_f32_16x16x32_bf16 v[100:103], v[132:135], v[198:201], v[100:103]
	v_mfma_f32_16x16x32_bf16 v[96:99], v[140:143], v[198:201], v[96:99]
	v_mfma_f32_16x16x32_bf16 v[76:79], v[132:135], v[206:209], v[76:79]
	v_mfma_f32_16x16x32_bf16 v[72:75], v[140:143], v[206:209], v[72:75]
	s_setprio 0
	s_setprio 1
	v_mfma_f32_16x16x32_bf16 v[116:119], v[162:165], v[178:181], v[116:119]
	v_mfma_f32_16x16x32_bf16 v[108:111], v[170:173], v[178:181], v[108:111]
	v_mfma_f32_16x16x32_bf16 v[92:95], v[162:165], v[186:189], v[92:95]
	v_mfma_f32_16x16x32_bf16 v[88:91], v[170:173], v[186:189], v[88:91]
	v_mfma_f32_16x16x32_bf16 v[84:87], v[162:165], v[194:197], v[84:87]
	v_mfma_f32_16x16x32_bf16 v[80:83], v[170:173], v[194:197], v[80:83]
	v_mfma_f32_16x16x32_bf16 v[68:71], v[162:165], v[202:205], v[68:71]
	v_mfma_f32_16x16x32_bf16 v[64:67], v[170:173], v[202:205], v[64:67]
	v_mfma_f32_16x16x32_bf16 v[116:119], v[166:169], v[182:185], v[116:119]
	v_mfma_f32_16x16x32_bf16 v[108:111], v[174:177], v[182:185], v[108:111]
	v_mfma_f32_16x16x32_bf16 v[92:95], v[166:169], v[190:193], v[92:95]
	v_mfma_f32_16x16x32_bf16 v[88:91], v[174:177], v[190:193], v[88:91]
	v_mfma_f32_16x16x32_bf16 v[84:87], v[166:169], v[198:201], v[84:87]
	v_mfma_f32_16x16x32_bf16 v[80:83], v[174:177], v[198:201], v[80:83]
	v_mfma_f32_16x16x32_bf16 v[68:71], v[166:169], v[206:209], v[68:71]
	v_mfma_f32_16x16x32_bf16 v[64:67], v[174:177], v[206:209], v[64:67]
	s_setprio 0
	s_barrier
	s_add_i32 s22, s60, s36
	v_lshl_add_u64 v[210:211], v[210:211], 0, s[6:7]
	s_mov_b32 m0, s22
	ds_read_b128 v[178:181], v216 offset:49152
	ds_read_b128 v[182:185], v216 offset:50176
	ds_read_b128 v[186:189], v216 offset:51200
	ds_read_b128 v[190:193], v216 offset:52224
	ds_read_b128 v[194:197], v216 offset:53248
	ds_read_b128 v[198:201], v216 offset:54272
	ds_read_b128 v[202:205], v216 offset:55296
	ds_read_b128 v[206:209], v216 offset:56320
	global_load_lds_dwordx4 v[210:211], off
	s_add_i32 m0, s22, 0x2000
	s_add_u32 s22, s26, 0x158080
	v_lshl_add_u64 v[210:211], v[218:219], 0, s[6:7]
	s_addc_u32 s23, s27, 0
	s_add_i32 s26, s61, s36
	global_load_lds_dwordx4 v[210:211], off
	v_lshl_add_u64 v[210:211], s[22:23], 0, v[148:149]
	s_mov_b32 m0, s26
	s_nop 0
	global_load_lds_dwordx4 v[210:211], off
	v_lshl_add_u64 v[210:211], s[22:23], 0, v[144:145]
	s_add_i32 m0, s26, 0x2000
	s_nop 0
	global_load_lds_dwordx4 v[210:211], off
	v_lshl_add_u64 v[210:211], v[220:221], 0, s[6:7]
	s_mov_b32 m0, s46
	s_nop 0
	global_load_lds_dwordx4 v[210:211], off
	v_lshl_add_u64 v[210:211], v[222:223], 0, s[6:7]
	s_mov_b32 m0, s47
	s_nop 0
	global_load_lds_dwordx4 v[210:211], off
	s_waitcnt vmcnt(8)
	s_waitcnt lgkmcnt(0)
	s_barrier
	s_setprio 1
	s_waitcnt lgkmcnt(0)
	v_mfma_f32_16x16x32_bf16 v[60:63], v[128:131], v[178:181], v[60:63]
	v_mfma_f32_16x16x32_bf16 v[56:59], v[136:139], v[178:181], v[56:59]
	v_mfma_f32_16x16x32_bf16 v[48:51], v[128:131], v[186:189], v[48:51]
	v_mfma_f32_16x16x32_bf16 v[40:43], v[136:139], v[186:189], v[40:43]
	v_mfma_f32_16x16x32_bf16 v[32:35], v[128:131], v[194:197], v[32:35]
	v_mfma_f32_16x16x32_bf16 v[24:27], v[136:139], v[194:197], v[24:27]
	v_mfma_f32_16x16x32_bf16 v[16:19], v[128:131], v[202:205], v[16:19]
	v_mfma_f32_16x16x32_bf16 v[8:11], v[136:139], v[202:205], v[8:11]
	v_mfma_f32_16x16x32_bf16 v[60:63], v[132:135], v[182:185], v[60:63]
	v_mfma_f32_16x16x32_bf16 v[56:59], v[140:143], v[182:185], v[56:59]
	v_mfma_f32_16x16x32_bf16 v[48:51], v[132:135], v[190:193], v[48:51]
	v_mfma_f32_16x16x32_bf16 v[40:43], v[140:143], v[190:193], v[40:43]
	v_mfma_f32_16x16x32_bf16 v[32:35], v[132:135], v[198:201], v[32:35]
	v_mfma_f32_16x16x32_bf16 v[24:27], v[140:143], v[198:201], v[24:27]
	v_mfma_f32_16x16x32_bf16 v[16:19], v[132:135], v[206:209], v[16:19]
	v_mfma_f32_16x16x32_bf16 v[8:11], v[140:143], v[206:209], v[8:11]
	s_setprio 0
	s_setprio 1
	v_mfma_f32_16x16x32_bf16 v[52:55], v[162:165], v[178:181], v[52:55]
	v_mfma_f32_16x16x32_bf16 v[44:47], v[170:173], v[178:181], v[44:47]
	v_mfma_f32_16x16x32_bf16 v[36:39], v[162:165], v[186:189], v[36:39]
	v_mfma_f32_16x16x32_bf16 v[28:31], v[170:173], v[186:189], v[28:31]
	v_mfma_f32_16x16x32_bf16 v[20:23], v[162:165], v[194:197], v[20:23]
	v_mfma_f32_16x16x32_bf16 v[12:15], v[170:173], v[194:197], v[12:15]
	v_mfma_f32_16x16x32_bf16 v[4:7], v[162:165], v[202:205], v[4:7]
	v_mfma_f32_16x16x32_bf16 v[0:3], v[170:173], v[202:205], v[0:3]
	v_mfma_f32_16x16x32_bf16 v[52:55], v[166:169], v[182:185], v[52:55]
	v_mfma_f32_16x16x32_bf16 v[44:47], v[174:177], v[182:185], v[44:47]
	v_mfma_f32_16x16x32_bf16 v[36:39], v[166:169], v[190:193], v[36:39]
	v_mfma_f32_16x16x32_bf16 v[28:31], v[174:177], v[190:193], v[28:31]
	v_mfma_f32_16x16x32_bf16 v[20:23], v[166:169], v[198:201], v[20:23]
	v_mfma_f32_16x16x32_bf16 v[12:15], v[174:177], v[198:201], v[12:15]
	v_mfma_f32_16x16x32_bf16 v[4:7], v[166:169], v[206:209], v[4:7]
	v_mfma_f32_16x16x32_bf16 v[0:3], v[174:177], v[206:209], v[0:3]
	s_setprio 0
	s_barrier
	s_add_i32 s59, s59, 2
	s_add_u32 s21, s21, 0x100
	s_addc_u32 s58, s58, 0
	s_cmpk_gt_u32 s59, 0x53
	s_mov_b64 s[22:23], s[24:25]
	s_cbranch_scc0 .LBB0_2107
; #define PG8_STAGE(bufoff, gbase, voff) do { _Pragma("unroll") for (int _i = 0; _i < 2; ++_i) \
;         __builtin_amdgcn_global_load_lds((const unsigned*)((const char*)(gbase) + (voff)[_i]), (PG8_LAS unsigned*)(lds + (bufoff) + ldsw + _i * 8192), 16, 0, 0); } while (0)
; #define PG8_LDA(dst, b, h) do { _Pragma("unroll") for (int m = 0; m < 4; ++m) _Pragma("unroll") for (int k = 0; k < 2; ++k) dst[m][k] = *(const PG8_LAS bf16x8*)(lds + PG8_SA(b, h) + aoff + m * 2048 + k * 1024); } while (0)
; #define PG8_LDB(dst, b, h) do { _Pragma("unroll") for (int n = 0; n < 2; ++n) _Pragma("unroll") for (int k = 0; k < 2; ++k) dst[n][k] = *(const PG8_LAS bf16x8*)(lds + PG8_SB(b, h) + boff + n * 2048 + k * 1024); } while (0)
; #define PG8_MMA(ai, bj, At, Bt) do { __builtin_amdgcn_s_setprio(1); _Pragma("unroll") for (int m = 0; m < 4; ++m) _Pragma("unroll") for (int n = 0; n < 2; ++n) _Pragma("unroll") for (int k = 0; k < 2; ++k) \
;         acc[ai][bj][m][n] = __builtin_amdgcn_mfma_f32_16x16x32_bf16(Bt[n][k], At[m][k], acc[ai][bj][m][n], 0, 0, 0); __builtin_amdgcn_s_setprio(0); } while (0)
; #define PG8_WAIT_V(n) asm volatile("s_waitcnt vmcnt(" #n ")" ::: "memory")
; #define PG8_WAIT_L(n) asm volatile("s_waitcnt lgkmcnt(" #n ")" ::: "memory")
; #define PG8_BAR __builtin_amdgcn_s_barrier()
; #define PG8_SCHED __builtin_amdgcn_sched_barrier(0)
; template <class Epi, class Sched, bool ALIGN_EPI = false, bool SP2 = false>
; __device__ __forceinline__ void gemm_phase(PG8_LAS unsigned char* lds, const Gemm g, const Sched& S, const Epi& E, const int wave_in) {
;     ...
;             PG8_LDB(B0, 0, 0); PG8_LDB(B1, 0, 1); PG8_SCHED; PG8_LDA(At, 0, 0); PG8_STAGE(PG8_SA(1, 1), a1 + hstepA, voffA);
;             PG8_WAIT_V(8); PG8_WAIT_L(0); PG8_BAR; PG8_MMA(0, 0, At, B0); PG8_MMA(0, 1, At, B1); PG8_BAR; PG8_SCHED;
;             PG8_LDA(At, 0, 1); PG8_STAGE(PG8_SB(0, 0), b2, voffB); PG8_STAGE(PG8_SB(0, 1), b2 + hstepB, voffB); PG8_STAGE(PG8_SA(0, 0), a2, voffA);
;             PG8_WAIT_V(8); PG8_WAIT_L(0); PG8_BAR; PG8_MMA(1, 0, At, B0); PG8_MMA(1, 1, At, B1); PG8_BAR; PG8_SCHED;
;             PG8_LDB(B0, 1, 0); PG8_LDB(B1, 1, 1); PG8_SCHED; PG8_LDA(At, 1, 0); PG8_STAGE(PG8_SA(0, 1), a2 + hstepA, voffA);
;             PG8_WAIT_V(8); PG8_WAIT_L(0); PG8_BAR; PG8_MMA(0, 0, At, B0); PG8_MMA(0, 1, At, B1); PG8_BAR; PG8_SCHED;
.LBB0_2107:
	ds_read_b128 v[128:131], v214
	ds_read_b128 v[132:135], v214 offset:1024
	ds_read_b128 v[136:139], v214 offset:2048
	ds_read_b128 v[140:143], v214 offset:3072
	ds_read_b128 v[162:165], v215
	ds_read_b128 v[166:169], v215 offset:1024
	ds_read_b128 v[170:173], v215 offset:2048
	ds_read_b128 v[174:177], v215 offset:3072
	s_add_u32 s24, s22, 0x100
	s_addc_u32 s25, s23, 0
	s_cmpk_eq_i32 s59, 0x52
	s_cselect_b32 s29, s5, s25
	s_cselect_b32 s28, s4, s24
	s_cselect_b32 s27, s19, s58
	s_cselect_b32 s26, s18, s21
	v_lshl_add_u64 v[210:211], s[22:23], 0, v[154:155]
	s_add_i32 m0, s39, 0xc000
	ds_read_b128 v[178:181], v216
	ds_read_b128 v[182:185], v216 offset:1024
	ds_read_b128 v[186:189], v216 offset:2048
	ds_read_b128 v[190:193], v216 offset:3072
	ds_read_b128 v[194:197], v216 offset:4096
	ds_read_b128 v[198:201], v216 offset:5120
	ds_read_b128 v[202:205], v216 offset:6144
	ds_read_b128 v[206:209], v216 offset:7168
	global_load_lds_dwordx4 v[210:211], off
	v_lshl_add_u64 v[210:211], s[22:23], 0, v[156:157]
	s_add_i32 m0, s39, 0xe000
	s_nop 0
	global_load_lds_dwordx4 v[210:211], off
	s_waitcnt vmcnt(8)
	s_waitcnt lgkmcnt(0)
	s_barrier
	s_setprio 1
	s_waitcnt lgkmcnt(0)
	v_mfma_f32_16x16x32_bf16 v[124:127], v[128:131], v[178:181], v[124:127]
	v_mfma_f32_16x16x32_bf16 v[120:123], v[136:139], v[178:181], v[120:123]
	v_mfma_f32_16x16x32_bf16 v[112:115], v[128:131], v[186:189], v[112:115]
	v_mfma_f32_16x16x32_bf16 v[104:107], v[136:139], v[186:189], v[104:107]
	v_mfma_f32_16x16x32_bf16 v[100:103], v[128:131], v[194:197], v[100:103]
	v_mfma_f32_16x16x32_bf16 v[96:99], v[136:139], v[194:197], v[96:99]
	v_mfma_f32_16x16x32_bf16 v[76:79], v[128:131], v[202:205], v[76:79]
	v_mfma_f32_16x16x32_bf16 v[72:75], v[136:139], v[202:205], v[72:75]
	v_mfma_f32_16x16x32_bf16 v[124:127], v[132:135], v[182:185], v[124:127]
	v_mfma_f32_16x16x32_bf16 v[120:123], v[140:143], v[182:185], v[120:123]
	v_mfma_f32_16x16x32_bf16 v[112:115], v[132:135], v[190:193], v[112:115]
	v_mfma_f32_16x16x32_bf16 v[104:107], v[140:143], v[190:193], v[104:107]
	v_mfma_f32_16x16x32_bf16 v[100:103], v[132:135], v[198:201], v[100:103]
	v_mfma_f32_16x16x32_bf16 v[96:99], v[140:143], v[198:201], v[96:99]
	v_mfma_f32_16x16x32_bf16 v[76:79], v[132:135], v[206:209], v[76:79]
	v_mfma_f32_16x16x32_bf16 v[72:75], v[140:143], v[206:209], v[72:75]
	s_setprio 0
	s_setprio 1
	v_mfma_f32_16x16x32_bf16 v[116:119], v[162:165], v[178:181], v[116:119]
	v_mfma_f32_16x16x32_bf16 v[108:111], v[170:173], v[178:181], v[108:111]
	v_mfma_f32_16x16x32_bf16 v[92:95], v[162:165], v[186:189], v[92:95]
	v_mfma_f32_16x16x32_bf16 v[88:91], v[170:173], v[186:189], v[88:91]
	v_mfma_f32_16x16x32_bf16 v[84:87], v[162:165], v[194:197], v[84:87]
	v_mfma_f32_16x16x32_bf16 v[80:83], v[170:173], v[194:197], v[80:83]
	v_mfma_f32_16x16x32_bf16 v[68:71], v[162:165], v[202:205], v[68:71]
	v_mfma_f32_16x16x32_bf16 v[64:67], v[170:173], v[202:205], v[64:67]
	v_mfma_f32_16x16x32_bf16 v[116:119], v[166:169], v[182:185], v[116:119]
	v_mfma_f32_16x16x32_bf16 v[108:111], v[174:177], v[182:185], v[108:111]
	v_mfma_f32_16x16x32_bf16 v[92:95], v[166:169], v[190:193], v[92:95]
	v_mfma_f32_16x16x32_bf16 v[88:91], v[174:177], v[190:193], v[88:91]
	v_mfma_f32_16x16x32_bf16 v[84:87], v[166:169], v[198:201], v[84:87]
	v_mfma_f32_16x16x32_bf16 v[80:83], v[174:177], v[198:201], v[80:83]
	v_mfma_f32_16x16x32_bf16 v[68:71], v[166:169], v[206:209], v[68:71]
	v_mfma_f32_16x16x32_bf16 v[64:67], v[174:177], v[206:209], v[64:67]
	s_setprio 0
	s_barrier
	s_add_i32 s22, s49, s36
	v_lshl_add_u64 v[210:211], s[26:27], 0, v[148:149]
	s_mov_b32 m0, s22
	ds_read_b128 v[178:181], v216 offset:16384
	ds_read_b128 v[182:185], v216 offset:17408
	ds_read_b128 v[186:189], v216 offset:18432
	ds_read_b128 v[190:193], v216 offset:19456
	ds_read_b128 v[194:197], v216 offset:20480
	ds_read_b128 v[198:201], v216 offset:21504
	ds_read_b128 v[202:205], v216 offset:22528
	ds_read_b128 v[206:209], v216 offset:23552
	global_load_lds_dwordx4 v[210:211], off
	s_add_i32 m0, s22, 0x2000
	s_add_u32 s22, s26, 0x158000
	v_lshl_add_u64 v[218:219], s[26:27], 0, v[144:145]
	s_addc_u32 s23, s27, 0
	s_add_i32 s60, s50, s36
	global_load_lds_dwordx4 v[218:219], off
	v_lshl_add_u64 v[220:221], s[22:23], 0, v[148:149]
	s_mov_b32 m0, s60
	v_lshl_add_u64 v[222:223], s[28:29], 0, v[146:147]
	global_load_lds_dwordx4 v[220:221], off
	v_lshl_add_u64 v[220:221], s[22:23], 0, v[144:145]
	s_add_i32 m0, s60, 0x2000
	s_nop 0
	global_load_lds_dwordx4 v[220:221], off
	v_lshl_add_u64 v[220:221], s[28:29], 0, v[150:151]
	s_mov_b32 m0, s39
	s_nop 0
	global_load_lds_dwordx4 v[220:221], off
	s_mov_b32 m0, s40
	s_nop 0
	global_load_lds_dwordx4 v[222:223], off
	s_waitcnt vmcnt(8)
	s_waitcnt lgkmcnt(0)
	s_barrier
; #define PG8_STAGE(bufoff, gbase, voff) do { _Pragma("unroll") for (int _i = 0; _i < 2; ++_i) \
;         __builtin_amdgcn_global_load_lds((const unsigned*)((const char*)(gbase) + (voff)[_i]), (PG8_LAS unsigned*)(lds + (bufoff) + ldsw + _i * 8192), 16, 0, 0); } while (0)
; #define PG8_LDA(dst, b, h) do { _Pragma("unroll") for (int m = 0; m < 4; ++m) _Pragma("unroll") for (int k = 0; k < 2; ++k) dst[m][k] = *(const PG8_LAS bf16x8*)(lds + PG8_SA(b, h) + aoff + m * 2048 + k * 1024); } while (0)
; #define PG8_LDB(dst, b, h) do { _Pragma("unroll") for (int n = 0; n < 2; ++n) _Pragma("unroll") for (int k = 0; k < 2; ++k) dst[n][k] = *(const PG8_LAS bf16x8*)(lds + PG8_SB(b, h) + boff + n * 2048 + k * 1024); } while (0)
; #define PG8_MMA(ai, bj, At, Bt) do { __builtin_amdgcn_s_setprio(1); _Pragma("unroll") for (int m = 0; m < 4; ++m) _Pragma("unroll") for (int n = 0; n < 2; ++n) _Pragma("unroll") for (int k = 0; k < 2; ++k) \
;         acc[ai][bj][m][n] = __builtin_amdgcn_mfma_f32_16x16x32_bf16(Bt[n][k], At[m][k], acc[ai][bj][m][n], 0, 0, 0); __builtin_amdgcn_s_setprio(0); } while (0)
; #define PG8_WAIT_V(n) asm volatile("s_waitcnt vmcnt(" #n ")" ::: "memory")
; #define PG8_WAIT_L(n) asm volatile("s_waitcnt lgkmcnt(" #n ")" ::: "memory")
; #define PG8_BAR __builtin_amdgcn_s_barrier()
; #define PG8_SCHED __builtin_amdgcn_sched_barrier(0)
; template <class Epi, class Sched, bool ALIGN_EPI = false, bool SP2 = false>
; __device__ __forceinline__ void gemm_phase(PG8_LAS unsigned char* lds, const Gemm g, const Sched& S, const Epi& E, const int wave_in) {
;     ...
;             PG8_LDB(B0, 1, 0); PG8_LDB(B1, 1, 1); PG8_SCHED; PG8_LDA(At, 1, 0); PG8_STAGE(PG8_SA(0, 1), a2 + hstepA, voffA);
;             PG8_WAIT_V(8); PG8_WAIT_L(0); PG8_BAR; PG8_MMA(0, 0, At, B0); PG8_MMA(0, 1, At, B1); PG8_BAR; PG8_SCHED;
;             PG8_LDA(At, 1, 1); PG8_STAGE(PG8_SB(1, 0), b3, voffB); PG8_STAGE(PG8_SB(1, 1), b3 + hstepB, voffB); PG8_STAGE(PG8_SA(1, 0), a3, voffA);
;             PG8_WAIT_V(8); PG8_WAIT_L(0); PG8_BAR; PG8_MMA(1, 0, At, B0); PG8_MMA(1, 1, At, B1); PG8_BAR; PG8_SCHED;
	s_setprio 1
	s_waitcnt lgkmcnt(0)
	v_mfma_f32_16x16x32_bf16 v[60:63], v[128:131], v[178:181], v[60:63]
	v_mfma_f32_16x16x32_bf16 v[56:59], v[136:139], v[178:181], v[56:59]
	v_mfma_f32_16x16x32_bf16 v[48:51], v[128:131], v[186:189], v[48:51]
	v_mfma_f32_16x16x32_bf16 v[40:43], v[136:139], v[186:189], v[40:43]
	v_mfma_f32_16x16x32_bf16 v[32:35], v[128:131], v[194:197], v[32:35]
	v_mfma_f32_16x16x32_bf16 v[24:27], v[136:139], v[194:197], v[24:27]
	v_mfma_f32_16x16x32_bf16 v[16:19], v[128:131], v[202:205], v[16:19]
	v_mfma_f32_16x16x32_bf16 v[8:11], v[136:139], v[202:205], v[8:11]
	v_mfma_f32_16x16x32_bf16 v[60:63], v[132:135], v[182:185], v[60:63]
	v_mfma_f32_16x16x32_bf16 v[56:59], v[140:143], v[182:185], v[56:59]
	v_mfma_f32_16x16x32_bf16 v[48:51], v[132:135], v[190:193], v[48:51]
	v_mfma_f32_16x16x32_bf16 v[40:43], v[140:143], v[190:193], v[40:43]
	v_mfma_f32_16x16x32_bf16 v[32:35], v[132:135], v[198:201], v[32:35]
	v_mfma_f32_16x16x32_bf16 v[24:27], v[140:143], v[198:201], v[24:27]
	v_mfma_f32_16x16x32_bf16 v[16:19], v[132:135], v[206:209], v[16:19]
	v_mfma_f32_16x16x32_bf16 v[8:11], v[140:143], v[206:209], v[8:11]
	s_setprio 0
	s_setprio 1
	v_mfma_f32_16x16x32_bf16 v[52:55], v[162:165], v[178:181], v[52:55]
	v_mfma_f32_16x16x32_bf16 v[44:47], v[170:173], v[178:181], v[44:47]
	v_mfma_f32_16x16x32_bf16 v[36:39], v[162:165], v[186:189], v[36:39]
	v_mfma_f32_16x16x32_bf16 v[28:31], v[170:173], v[186:189], v[28:31]
	v_mfma_f32_16x16x32_bf16 v[20:23], v[162:165], v[194:197], v[20:23]
	v_mfma_f32_16x16x32_bf16 v[12:15], v[170:173], v[194:197], v[12:15]
	v_mfma_f32_16x16x32_bf16 v[4:7], v[162:165], v[202:205], v[4:7]
	v_mfma_f32_16x16x32_bf16 v[0:3], v[170:173], v[202:205], v[0:3]
	v_mfma_f32_16x16x32_bf16 v[52:55], v[166:169], v[182:185], v[52:55]
	v_mfma_f32_16x16x32_bf16 v[44:47], v[174:177], v[182:185], v[44:47]
	v_mfma_f32_16x16x32_bf16 v[36:39], v[166:169], v[190:193], v[36:39]
	v_mfma_f32_16x16x32_bf16 v[28:31], v[174:177], v[190:193], v[28:31]
	v_mfma_f32_16x16x32_bf16 v[20:23], v[166:169], v[198:201], v[20:23]
	v_mfma_f32_16x16x32_bf16 v[12:15], v[174:177], v[198:201], v[12:15]
	v_mfma_f32_16x16x32_bf16 v[4:7], v[166:169], v[206:209], v[4:7]
	v_mfma_f32_16x16x32_bf16 v[0:3], v[174:177], v[206:209], v[0:3]
	s_setprio 0
	s_barrier
	s_add_i32 s60, 0, 0x18000
	s_add_i32 s61, 0, 0x1c000
	v_add_u32_e32 v140, s60, v212
	v_add_u32_e32 v174, s61, v212
	ds_read_b128 v[128:131], v140
	ds_read_b128 v[132:135], v140 offset:1024
	ds_read_b128 v[136:139], v140 offset:2048
	ds_read_b128 v[140:143], v140 offset:3072
	ds_read_b128 v[162:165], v174
	ds_read_b128 v[166:169], v174 offset:1024
	ds_read_b128 v[170:173], v174 offset:2048
	ds_read_b128 v[174:177], v174 offset:3072
	s_add_u32 s22, s28, 0x158000
	s_addc_u32 s23, s29, 0
	s_mov_b32 m0, s41
	v_lshl_add_u64 v[224:225], s[22:23], 0, v[150:151]
	ds_read_b128 v[178:181], v216 offset:32768
	ds_read_b128 v[182:185], v216 offset:33792
	ds_read_b128 v[186:189], v216 offset:34816
	ds_read_b128 v[190:193], v216 offset:35840
	ds_read_b128 v[194:197], v216 offset:36864
	ds_read_b128 v[198:201], v216 offset:37888
	ds_read_b128 v[202:205], v216 offset:38912
	ds_read_b128 v[206:209], v216 offset:39936
	global_load_lds_dwordx4 v[224:225], off
	v_lshl_add_u64 v[224:225], s[22:23], 0, v[146:147]
	s_mov_b32 m0, s42
	s_nop 0
	global_load_lds_dwordx4 v[224:225], off
	s_waitcnt vmcnt(8)
	s_waitcnt lgkmcnt(0)
	s_barrier
	s_setprio 1
	s_waitcnt lgkmcnt(0)
	v_mfma_f32_16x16x32_bf16 v[124:127], v[128:131], v[178:181], v[124:127]
	v_mfma_f32_16x16x32_bf16 v[120:123], v[136:139], v[178:181], v[120:123]
	v_mfma_f32_16x16x32_bf16 v[112:115], v[128:131], v[186:189], v[112:115]
	v_mfma_f32_16x16x32_bf16 v[104:107], v[136:139], v[186:189], v[104:107]
	v_mfma_f32_16x16x32_bf16 v[100:103], v[128:131], v[194:197], v[100:103]
	v_mfma_f32_16x16x32_bf16 v[96:99], v[136:139], v[194:197], v[96:99]
	v_mfma_f32_16x16x32_bf16 v[76:79], v[128:131], v[202:205], v[76:79]
	v_mfma_f32_16x16x32_bf16 v[72:75], v[136:139], v[202:205], v[72:75]
	v_mfma_f32_16x16x32_bf16 v[124:127], v[132:135], v[182:185], v[124:127]
	v_mfma_f32_16x16x32_bf16 v[120:123], v[140:143], v[182:185], v[120:123]
	v_mfma_f32_16x16x32_bf16 v[112:115], v[132:135], v[190:193], v[112:115]
	v_mfma_f32_16x16x32_bf16 v[104:107], v[140:143], v[190:193], v[104:107]
	v_mfma_f32_16x16x32_bf16 v[100:103], v[132:135], v[198:201], v[100:103]
	v_mfma_f32_16x16x32_bf16 v[96:99], v[140:143], v[198:201], v[96:99]
	v_mfma_f32_16x16x32_bf16 v[76:79], v[132:135], v[206:209], v[76:79]
	v_mfma_f32_16x16x32_bf16 v[72:75], v[140:143], v[206:209], v[72:75]
	s_setprio 0
	s_setprio 1
	v_mfma_f32_16x16x32_bf16 v[116:119], v[162:165], v[178:181], v[116:119]
	v_mfma_f32_16x16x32_bf16 v[108:111], v[170:173], v[178:181], v[108:111]
	v_mfma_f32_16x16x32_bf16 v[92:95], v[162:165], v[186:189], v[92:95]
	v_mfma_f32_16x16x32_bf16 v[88:91], v[170:173], v[186:189], v[88:91]
	v_mfma_f32_16x16x32_bf16 v[84:87], v[162:165], v[194:197], v[84:87]
	v_mfma_f32_16x16x32_bf16 v[80:83], v[170:173], v[194:197], v[80:83]
	v_mfma_f32_16x16x32_bf16 v[68:71], v[162:165], v[202:205], v[68:71]
	v_mfma_f32_16x16x32_bf16 v[64:67], v[170:173], v[202:205], v[64:67]
	v_mfma_f32_16x16x32_bf16 v[116:119], v[166:169], v[182:185], v[116:119]
	v_mfma_f32_16x16x32_bf16 v[108:111], v[174:177], v[182:185], v[108:111]
	v_mfma_f32_16x16x32_bf16 v[92:95], v[166:169], v[190:193], v[92:95]
	v_mfma_f32_16x16x32_bf16 v[88:91], v[174:177], v[190:193], v[88:91]
	v_mfma_f32_16x16x32_bf16 v[84:87], v[166:169], v[198:201], v[84:87]
	v_mfma_f32_16x16x32_bf16 v[80:83], v[174:177], v[198:201], v[80:83]
	v_mfma_f32_16x16x32_bf16 v[68:71], v[166:169], v[206:209], v[68:71]
	v_mfma_f32_16x16x32_bf16 v[64:67], v[174:177], v[206:209], v[64:67]
	s_setprio 0
	s_barrier
; #define PG8_STAGE(bufoff, gbase, voff) do { _Pragma("unroll") for (int _i = 0; _i < 2; ++_i) \
;         __builtin_amdgcn_global_load_lds((const unsigned*)((const char*)(gbase) + (voff)[_i]), (PG8_LAS unsigned*)(lds + (bufoff) + ldsw + _i * 8192), 16, 0, 0); } while (0)
; #define PG8_LDA(dst, b, h) do { _Pragma("unroll") for (int m = 0; m < 4; ++m) _Pragma("unroll") for (int k = 0; k < 2; ++k) dst[m][k] = *(const PG8_LAS bf16x8*)(lds + PG8_SA(b, h) + aoff + m * 2048 + k * 1024); } while (0)
; #define PG8_WAIT_V(n) asm volatile("s_waitcnt vmcnt(" #n ")" ::: "memory")
; #define PG8_WAIT_L(n) asm volatile("s_waitcnt lgkmcnt(" #n ")" ::: "memory")
; #define PG8_BAR __builtin_amdgcn_s_barrier()
; template <class Epi, class Sched, bool ALIGN_EPI = false, bool SP2 = false>
; __device__ __forceinline__ void gemm_phase(PG8_LAS unsigned char* lds, const Gemm g, const Sched& S, const Epi& E, const int wave_in) {
;     ...
;             PG8_WAIT_V(8); PG8_WAIT_L(0); PG8_BAR; PG8_MMA(1, 0, At, B0); PG8_MMA(1, 1, At, B1); PG8_BAR; PG8_SCHED;
;             } else {
;             PG8_LDB(B0, 0, 0); PG8_SCHED; PG8_LDA(At, 0, 0); PG8_STAGE(PG8_SA(1, 1), a1 + hstepA, voffA);
;             PG8_WAIT_L(8); PG8_BAR; PG8_WAIT_L(0); PG8_MMA(0, 0, At, B0); PG8_BAR; PG8_SCHED;
;             PG8_LDB(B1, 0, 1); PG8_STAGE(PG8_SB(0, 0), b2, voffB);
;             PG8_BAR; PG8_WAIT_L(0); PG8_MMA(0, 1, At, B1); PG8_BAR;
;             PG8_LDA(At, 0, 1); PG8_STAGE(PG8_SA(0, 0), a2, voffA);
;             PG8_BAR; PG8_WAIT_L(0); PG8_MMA(1, 0, At, B0); PG8_BAR; PG8_SCHED;
;             PG8_STAGE(PG8_SB(0, 1), b2 + hstepB, voffB);
;             PG8_WAIT_V(6); PG8_BAR; PG8_MMA(1, 1, At, B1); PG8_BAR;
;             PG8_LDB(B0, 1, 0); PG8_SCHED; PG8_LDA(At, 1, 0); PG8_STAGE(PG8_SA(0, 1), a2 + hstepA, voffA);
;             PG8_WAIT_L(8); PG8_BAR; PG8_WAIT_L(0); PG8_MMA(0, 0, At, B0); PG8_BAR; PG8_SCHED;
;             PG8_LDB(B1, 1, 1); PG8_STAGE(PG8_SB(1, 0), b3, voffB);
;             PG8_BAR; PG8_WAIT_L(0); PG8_MMA(0, 1, At, B1); PG8_BAR;
;             PG8_LDA(At, 1, 1); PG8_STAGE(PG8_SA(1, 0), a3, voffA);
;             PG8_BAR; PG8_WAIT_L(0); PG8_MMA(1, 0, At, B0); PG8_BAR; PG8_SCHED;
;             PG8_STAGE(PG8_SB(1, 1), b3 + hstepB, voffB);
;             PG8_WAIT_V(6); PG8_BAR; PG8_MMA(1, 1, At, B1); PG8_BAR;
;             }
;         }
;         if constexpr (ALIGN_EPI) { if (wr == 0) PG8_BAR; }
	s_add_i32 s22, s60, s36
	v_lshl_add_u64 v[210:211], v[210:211], 0, s[6:7]
	s_mov_b32 m0, s22
	ds_read_b128 v[178:181], v216 offset:49152
	ds_read_b128 v[182:185], v216 offset:50176
	ds_read_b128 v[186:189], v216 offset:51200
	ds_read_b128 v[190:193], v216 offset:52224
	ds_read_b128 v[194:197], v216 offset:53248
	ds_read_b128 v[198:201], v216 offset:54272
	ds_read_b128 v[202:205], v216 offset:55296
	ds_read_b128 v[206:209], v216 offset:56320
	global_load_lds_dwordx4 v[210:211], off
	s_add_i32 m0, s22, 0x2000
	s_add_u32 s22, s26, 0x158080
	v_lshl_add_u64 v[210:211], v[218:219], 0, s[6:7]
	s_addc_u32 s23, s27, 0
	s_add_i32 s26, s61, s36
	global_load_lds_dwordx4 v[210:211], off
	v_lshl_add_u64 v[210:211], s[22:23], 0, v[148:149]
	s_mov_b32 m0, s26
	s_nop 0
	global_load_lds_dwordx4 v[210:211], off
	v_lshl_add_u64 v[210:211], s[22:23], 0, v[144:145]
	s_add_i32 m0, s26, 0x2000
	s_nop 0
	global_load_lds_dwordx4 v[210:211], off
	v_lshl_add_u64 v[210:211], v[220:221], 0, s[6:7]
	s_mov_b32 m0, s46
	s_nop 0
	global_load_lds_dwordx4 v[210:211], off
	v_lshl_add_u64 v[210:211], v[222:223], 0, s[6:7]
	s_mov_b32 m0, s47
	s_nop 0
	global_load_lds_dwordx4 v[210:211], off
	s_waitcnt vmcnt(8)
	s_waitcnt lgkmcnt(0)
	s_barrier
	s_setprio 1
	s_waitcnt lgkmcnt(0)
	v_mfma_f32_16x16x32_bf16 v[60:63], v[128:131], v[178:181], v[60:63]
	v_mfma_f32_16x16x32_bf16 v[56:59], v[136:139], v[178:181], v[56:59]
	v_mfma_f32_16x16x32_bf16 v[48:51], v[128:131], v[186:189], v[48:51]
	v_mfma_f32_16x16x32_bf16 v[40:43], v[136:139], v[186:189], v[40:43]
	v_mfma_f32_16x16x32_bf16 v[32:35], v[128:131], v[194:197], v[32:35]
	v_mfma_f32_16x16x32_bf16 v[24:27], v[136:139], v[194:197], v[24:27]
	v_mfma_f32_16x16x32_bf16 v[16:19], v[128:131], v[202:205], v[16:19]
	v_mfma_f32_16x16x32_bf16 v[8:11], v[136:139], v[202:205], v[8:11]
	v_mfma_f32_16x16x32_bf16 v[60:63], v[132:135], v[182:185], v[60:63]
	v_mfma_f32_16x16x32_bf16 v[56:59], v[140:143], v[182:185], v[56:59]
	v_mfma_f32_16x16x32_bf16 v[48:51], v[132:135], v[190:193], v[48:51]
	v_mfma_f32_16x16x32_bf16 v[40:43], v[140:143], v[190:193], v[40:43]
	v_mfma_f32_16x16x32_bf16 v[32:35], v[132:135], v[198:201], v[32:35]
	v_mfma_f32_16x16x32_bf16 v[24:27], v[140:143], v[198:201], v[24:27]
	v_mfma_f32_16x16x32_bf16 v[16:19], v[132:135], v[206:209], v[16:19]
	v_mfma_f32_16x16x32_bf16 v[8:11], v[140:143], v[206:209], v[8:11]
	s_setprio 0
	s_setprio 1
	v_mfma_f32_16x16x32_bf16 v[52:55], v[162:165], v[178:181], v[52:55]
	v_mfma_f32_16x16x32_bf16 v[44:47], v[170:173], v[178:181], v[44:47]
	v_mfma_f32_16x16x32_bf16 v[36:39], v[162:165], v[186:189], v[36:39]
	v_mfma_f32_16x16x32_bf16 v[28:31], v[170:173], v[186:189], v[28:31]
	v_mfma_f32_16x16x32_bf16 v[20:23], v[162:165], v[194:197], v[20:23]
	v_mfma_f32_16x16x32_bf16 v[12:15], v[170:173], v[194:197], v[12:15]
	v_mfma_f32_16x16x32_bf16 v[4:7], v[162:165], v[202:205], v[4:7]
	v_mfma_f32_16x16x32_bf16 v[0:3], v[170:173], v[202:205], v[0:3]
	v_mfma_f32_16x16x32_bf16 v[52:55], v[166:169], v[182:185], v[52:55]
	v_mfma_f32_16x16x32_bf16 v[44:47], v[174:177], v[182:185], v[44:47]
	v_mfma_f32_16x16x32_bf16 v[36:39], v[166:169], v[190:193], v[36:39]
	v_mfma_f32_16x16x32_bf16 v[28:31], v[174:177], v[190:193], v[28:31]
	v_mfma_f32_16x16x32_bf16 v[20:23], v[166:169], v[198:201], v[20:23]
	v_mfma_f32_16x16x32_bf16 v[12:15], v[174:177], v[198:201], v[12:15]
	v_mfma_f32_16x16x32_bf16 v[4:7], v[166:169], v[206:209], v[4:7]
	v_mfma_f32_16x16x32_bf16 v[0:3], v[174:177], v[206:209], v[0:3]
	s_setprio 0
	s_barrier
	s_add_i32 s59, s59, 2
	s_add_u32 s21, s21, 0x100
	s_addc_u32 s58, s58, 0
	s_cmpk_gt_u32 s59, 0x53
	s_mov_b64 s[22:23], s[24:25]
	s_cbranch_scc0 .LBB0_2107
	s_mov_b32 s99, 1
	s_and_b64 vcc, exec, s[8:9]
	s_cbranch_vccz .LBB0_2110
	s_barrier

;     __host__ __device__ bool next(int i, Unit& u) const {
;         const long L = (long)i * G + c; if (L >= nwg) return false;
;         int wgid = (int)L; { const int q = nwg / NXCD, r = nwg % NXCD, xcd = wgid % NXCD, off = wgid / NXCD; wgid = (xcd < r ? xcd * (q + 1) : r * (q + 1) + (xcd - r) * q) + off; }
;         const int nig = WGM * nN, gid = wgid / nig, fm = gid * WGM, gsz = (nM - fm) < WGM ? (nM - fm) : WGM;
;         u.pm = fm + ((wgid % nig) % gsz); u.pn = (wgid % nig) / gsz; return true;
.LBB0_2235:
	s_cmp_gt_i32 s52, 26
	s_cselect_b64 s[0:1], -1, 0
	s_cmp_lt_i32 s53, 27
	s_cselect_b64 s[2:3], -1, 0
	s_or_b64 s[0:1], s[0:1], s[2:3]
	s_and_b64 vcc, exec, s[0:1]
	s_cbranch_vccnz .LBB0_2336
	s_mov_b32 s99, 0
	s_cmpk_lt_i32 s73, 0x1680
	s_cselect_b64 s[0:1], -1, 0
	s_cmpk_gt_i32 s73, 0x167f
	v_mbcnt_lo_u32_b32 v8, -1, 0
	v_mbcnt_hi_u32_b32 v8, -1, v8
	s_cbranch_scc1 .LBB0_2239
	s_ashr_i32 s2, s73, 31
	s_lshr_b32 s2, s2, 29
	s_add_i32 s2, s73, s2
	s_ashr_i32 s3, s2, 3
	s_and_b32 s2, s2, -8
	s_sub_i32 s2, s73, s2
	s_cmp_lt_i32 s2, 0
	s_movk_i32 s4, 0x2d1
	s_cselect_b32 s4, s4, 0x2d0
	s_mul_i32 s2, s4, s2
	s_add_i32 s2, s2, s3
	s_mul_hi_i32 s3, s2, 0x66666667
	s_lshr_b32 s4, s3, 31
	s_ashr_i32 s3, s3, 6
	s_add_i32 s3, s3, s4
	s_lshl_b32 s4, s3, 2
	s_mulk_i32 s3, 0xa0
	s_sub_i32 s2, s2, s3
	s_sext_i32_i16 s3, s2
	s_bfe_u32 s3, s3, 0x2001d
	s_add_i32 s3, s2, s3
	s_sext_i32_i16 s5, s3
	s_and_b32 s3, s3, 0xfffc
	s_sub_i32 s2, s2, s3
	s_sext_i32_i16 s2, s2
	s_add_i32 s20, s4, s2
	s_ashr_i32 s4, s5, 2
	s_andn2_b64 vcc, exec, s[0:1]
	s_cbranch_vccz .LBB0_2240

;     __host__ __device__ bool next(int i, Unit& u) const { const bool ok = StaticOrder::next(i, u); u.pm = 0; u.pn = 0; return ok; }
; #define PG8_STAGE(bufoff, gbase, voff) do { _Pragma("unroll") for (int _i = 0; _i < 2; ++_i) \
;         __builtin_amdgcn_global_load_lds((const unsigned*)((const char*)(gbase) + (voff)[_i]), (PG8_LAS unsigned*)(lds + (bufoff) + ldsw + _i * 8192), 16, 0, 0); } while (0)
; #define PG8_LDA(dst, b, h) do { _Pragma("unroll") for (int m = 0; m < 4; ++m) _Pragma("unroll") for (int k = 0; k < 2; ++k) dst[m][k] = *(const PG8_LAS bf16x8*)(lds + PG8_SA(b, h) + aoff + m * 2048 + k * 1024); } while (0)
; #define PG8_LDB(dst, b, h) do { _Pragma("unroll") for (int n = 0; n < 2; ++n) _Pragma("unroll") for (int k = 0; k < 2; ++k) dst[n][k] = *(const PG8_LAS bf16x8*)(lds + PG8_SB(b, h) + boff + n * 2048 + k * 1024); } while (0)
; #define PG8_WAIT_V(n) asm volatile("s_waitcnt vmcnt(" #n ")" ::: "memory")
; template <class Epi, class Sched, bool ALIGN_EPI = false, bool SP2 = false>
; __device__ __forceinline__ void gemm_phase(PG8_LAS unsigned char* lds, const Gemm g, const Sched& S, const Epi& E, const int wave_in) {
;     ...
;         const bool has_next = S.next(ui + 1, nxt);
;         const char* nA = has_next ? (const char*)g.A + (size_t)nxt.pm * tstepA : cA; const char* nB = has_next ? (const char*)g.Bt + (size_t)nxt.pn * tstepB : cB;
;         for (int t = 0; t < nt; t += 2) {
;             const bool last = (t == nt - 2);
;             const char* a1 = cA + (size_t)(t + 1) * kstep;
;             const char* a2 = last ? nA : cA + (size_t)(t + 2) * kstep; const char* b2 = last ? nB : cB + (size_t)(t + 2) * kstep;
;             const char* a3 = a2 + kstep; const char* b3 = b2 + kstep;
;             if (last && has_next) S.a_ready(nxt);
;             if constexpr (SP2) {
;             PG8_LDB(B0, 0, 0); PG8_LDB(B1, 0, 1); PG8_SCHED; PG8_LDA(At, 0, 0); PG8_STAGE(PG8_SA(1, 1), a1 + hstepA, voffA);
;             PG8_WAIT_V(8); PG8_WAIT_L(0); PG8_BAR; PG8_MMA(0, 0, At, B0); PG8_MMA(0, 1, At, B1); PG8_BAR; PG8_SCHED;
;     ...
; #pragma unroll
;         for (int a = 0; a < 2; ++a)
; #pragma unroll
;             for (int b = 0; b < 2; ++b)
; #pragma unroll
;                 for (int m = 0; m < 4; ++m)
; #pragma unroll
;                     for (int n = 0; n < 2; ++n) acc[a][b][m][n] = (f32x4){0.f, 0.f, 0.f, 0.f};
;         cur = nxt; cA = nA; cB = nB; ++ui;
.LBB0_2247:
	s_ashr_i32 s15, s14, 31
	s_lshl_b64 s[16:17], s[14:15], 20
	s_add_u32 s16, s28, s16
	s_addc_u32 s17, s29, s17
	s_and_b64 s[18:19], s[2:3], exec
	s_cselect_b32 s5, s17, s23
	s_cselect_b32 s15, s16, s22
	s_ashr_i32 s13, s12, 31
	s_lshl_b64 s[18:19], s[12:13], 20
	s_add_u32 s18, s30, s18
	s_addc_u32 s19, s31, s19
	s_and_b64 s[26:27], s[2:3], exec
	s_cselect_b32 s13, s19, s25
	s_cselect_b32 s47, s18, s24
	s_add_u32 s22, s22, 0x80080
	s_addc_u32 s23, s23, 0
	s_add_u32 s48, s24, 0x100
	v_mov_b32_e32 v0, 0
	s_addc_u32 s49, s25, 0
	s_mov_b32 s50, -2
	v_mov_b32_e32 v1, v0
	v_mov_b32_e32 v2, v0
	v_mov_b32_e32 v3, v0
	v_mov_b32_e32 v4, v0
	v_mov_b32_e32 v5, v0
	v_mov_b32_e32 v6, v0
	v_mov_b32_e32 v7, v0
	v_mov_b32_e32 v16, v0
	v_mov_b32_e32 v17, v0
	v_mov_b32_e32 v18, v0
	v_mov_b32_e32 v19, v0
	v_mov_b32_e32 v20, v0
	v_mov_b32_e32 v21, v0
	v_mov_b32_e32 v22, v0
	v_mov_b32_e32 v23, v0
	v_mov_b32_e32 v32, v0
	v_mov_b32_e32 v33, v0
	v_mov_b32_e32 v34, v0
	v_mov_b32_e32 v35, v0
	v_mov_b32_e32 v36, v0
	v_mov_b32_e32 v37, v0
	v_mov_b32_e32 v38, v0
	v_mov_b32_e32 v39, v0
	v_mov_b32_e32 v48, v0
	v_mov_b32_e32 v49, v0
	v_mov_b32_e32 v50, v0
	v_mov_b32_e32 v51, v0
	v_mov_b32_e32 v52, v0
	v_mov_b32_e32 v53, v0
	v_mov_b32_e32 v54, v0
	v_mov_b32_e32 v55, v0
	v_mov_b32_e32 v8, v0
	v_mov_b32_e32 v9, v0
	v_mov_b32_e32 v10, v0
	v_mov_b32_e32 v11, v0
	v_mov_b32_e32 v12, v0
	v_mov_b32_e32 v13, v0
	v_mov_b32_e32 v14, v0
	v_mov_b32_e32 v15, v0
	v_mov_b32_e32 v24, v0
	v_mov_b32_e32 v25, v0
	v_mov_b32_e32 v26, v0
	v_mov_b32_e32 v27, v0
	v_mov_b32_e32 v28, v0
	v_mov_b32_e32 v29, v0
	v_mov_b32_e32 v30, v0
	v_mov_b32_e32 v31, v0
	v_mov_b32_e32 v40, v0
	v_mov_b32_e32 v41, v0
	v_mov_b32_e32 v42, v0
	v_mov_b32_e32 v43, v0
	v_mov_b32_e32 v44, v0
	v_mov_b32_e32 v45, v0
	v_mov_b32_e32 v46, v0
	v_mov_b32_e32 v47, v0
	v_mov_b32_e32 v56, v0
	v_mov_b32_e32 v57, v0
	v_mov_b32_e32 v58, v0
	v_mov_b32_e32 v59, v0
	v_mov_b32_e32 v60, v0
	v_mov_b32_e32 v61, v0
	v_mov_b32_e32 v62, v0
	v_mov_b32_e32 v63, v0
	v_mov_b32_e32 v64, v0
	v_mov_b32_e32 v65, v0
	v_mov_b32_e32 v66, v0
	v_mov_b32_e32 v67, v0
	v_mov_b32_e32 v68, v0
	v_mov_b32_e32 v69, v0
	v_mov_b32_e32 v70, v0
	v_mov_b32_e32 v71, v0
	v_mov_b32_e32 v80, v0
	v_mov_b32_e32 v81, v0
	v_mov_b32_e32 v82, v0
	v_mov_b32_e32 v83, v0
	v_mov_b32_e32 v84, v0
	v_mov_b32_e32 v85, v0
	v_mov_b32_e32 v86, v0
	v_mov_b32_e32 v87, v0
	v_mov_b32_e32 v96, v0
	v_mov_b32_e32 v97, v0
	v_mov_b32_e32 v98, v0
	v_mov_b32_e32 v99, v0
	v_mov_b32_e32 v100, v0
	v_mov_b32_e32 v101, v0
	v_mov_b32_e32 v102, v0
	v_mov_b32_e32 v103, v0
	v_mov_b32_e32 v112, v0
	v_mov_b32_e32 v113, v0
	v_mov_b32_e32 v114, v0
	v_mov_b32_e32 v115, v0
	v_mov_b32_e32 v116, v0
	v_mov_b32_e32 v117, v0
	v_mov_b32_e32 v118, v0
	v_mov_b32_e32 v119, v0
	v_mov_b32_e32 v72, v0
	v_mov_b32_e32 v73, v0
	v_mov_b32_e32 v74, v0
	v_mov_b32_e32 v75, v0
	v_mov_b32_e32 v76, v0
	v_mov_b32_e32 v77, v0
	v_mov_b32_e32 v78, v0
	v_mov_b32_e32 v79, v0
	v_mov_b32_e32 v88, v0
	v_mov_b32_e32 v89, v0
	v_mov_b32_e32 v90, v0
	v_mov_b32_e32 v91, v0
	v_mov_b32_e32 v92, v0
	v_mov_b32_e32 v93, v0
	v_mov_b32_e32 v94, v0
	v_mov_b32_e32 v95, v0
	v_mov_b32_e32 v104, v0
	v_mov_b32_e32 v105, v0
	v_mov_b32_e32 v106, v0
	v_mov_b32_e32 v107, v0
	v_mov_b32_e32 v108, v0
	v_mov_b32_e32 v109, v0
	v_mov_b32_e32 v110, v0
	v_mov_b32_e32 v111, v0
	v_mov_b32_e32 v120, v0
	v_mov_b32_e32 v121, v0
	v_mov_b32_e32 v122, v0
	v_mov_b32_e32 v123, v0
	v_mov_b32_e32 v124, v0
	v_mov_b32_e32 v125, v0
	v_mov_b32_e32 v126, v0
	v_mov_b32_e32 v127, v0
	s_cmp_lg_u32 s99, 0
	s_cbranch_scc0 .LBB0_2248
	ds_read_b128 v[144:147], v151
	ds_read_b128 v[154:157], v151 offset:1024
	ds_read_b128 v[158:161], v151 offset:2048
	ds_read_b128 v[162:165], v151 offset:3072
	ds_read_b128 v[166:169], v152
	ds_read_b128 v[170:173], v152 offset:1024
	ds_read_b128 v[174:177], v152 offset:2048
	ds_read_b128 v[178:181], v152 offset:3072
	s_add_u32 s24, s22, 0xfff80080
	s_addc_u32 s25, s23, -1
	s_cmp_eq_u32 s50, 28
	s_cselect_b32 s27, s5, s25
	s_cselect_b32 s26, s15, s24
	s_cselect_b32 s25, s13, s49
	s_cselect_b32 s24, s47, s48
	v_lshl_add_u64 v[214:215], s[22:23], 0, v[136:137]
	s_add_i32 m0, s21, 0xc000
	ds_read_b128 v[182:185], v153
	ds_read_b128 v[186:189], v153 offset:1024
	ds_read_b128 v[190:193], v153 offset:2048
	ds_read_b128 v[194:197], v153 offset:3072
	ds_read_b128 v[198:201], v153 offset:4096
	ds_read_b128 v[202:205], v153 offset:5120
	ds_read_b128 v[206:209], v153 offset:6144
	ds_read_b128 v[210:213], v153 offset:7168
	global_load_lds_dwordx4 v[214:215], off
	v_lshl_add_u64 v[214:215], s[22:23], 0, v[138:139]
	s_add_i32 m0, s21, 0xe000
	s_nop 0
	global_load_lds_dwordx4 v[214:215], off
	s_waitcnt vmcnt(24)
	s_waitcnt lgkmcnt(0)
	s_barrier
; #define PG8_STAGE(bufoff, gbase, voff) do { _Pragma("unroll") for (int _i = 0; _i < 2; ++_i) \
;         __builtin_amdgcn_global_load_lds((const unsigned*)((const char*)(gbase) + (voff)[_i]), (PG8_LAS unsigned*)(lds + (bufoff) + ldsw + _i * 8192), 16, 0, 0); } while (0)
; #define PG8_LDA(dst, b, h) do { _Pragma("unroll") for (int m = 0; m < 4; ++m) _Pragma("unroll") for (int k = 0; k < 2; ++k) dst[m][k] = *(const PG8_LAS bf16x8*)(lds + PG8_SA(b, h) + aoff + m * 2048 + k * 1024); } while (0)
; #define PG8_MMA(ai, bj, At, Bt) do { __builtin_amdgcn_s_setprio(1); _Pragma("unroll") for (int m = 0; m < 4; ++m) _Pragma("unroll") for (int n = 0; n < 2; ++n) _Pragma("unroll") for (int k = 0; k < 2; ++k) \
;         acc[ai][bj][m][n] = __builtin_amdgcn_mfma_f32_16x16x32_bf16(Bt[n][k], At[m][k], acc[ai][bj][m][n], 0, 0, 0); __builtin_amdgcn_s_setprio(0); } while (0)
; #define PG8_WAIT_V(n) asm volatile("s_waitcnt vmcnt(" #n ")" ::: "memory")
; #define PG8_WAIT_L(n) asm volatile("s_waitcnt lgkmcnt(" #n ")" ::: "memory")
; #define PG8_BAR __builtin_amdgcn_s_barrier()
; #define PG8_SCHED __builtin_amdgcn_sched_barrier(0)
; template <class Epi, class Sched, bool ALIGN_EPI = false, bool SP2 = false>
; __device__ __forceinline__ void gemm_phase(PG8_LAS unsigned char* lds, const Gemm g, const Sched& S, const Epi& E, const int wave_in) {
;     ...
;             PG8_WAIT_V(8); PG8_WAIT_L(0); PG8_BAR; PG8_MMA(0, 0, At, B0); PG8_MMA(0, 1, At, B1); PG8_BAR; PG8_SCHED;
;             PG8_LDA(At, 0, 1); PG8_STAGE(PG8_SB(0, 0), b2, voffB); PG8_STAGE(PG8_SB(0, 1), b2 + hstepB, voffB); PG8_STAGE(PG8_SA(0, 0), a2, voffA);
;             PG8_WAIT_V(8); PG8_WAIT_L(0); PG8_BAR; PG8_MMA(1, 0, At, B0); PG8_MMA(1, 1, At, B1); PG8_BAR; PG8_SCHED;
	s_setprio 1
	s_waitcnt lgkmcnt(0)
	v_mfma_f32_16x16x32_bf16 v[124:127], v[144:147], v[182:185], v[124:127]
	v_mfma_f32_16x16x32_bf16 v[120:123], v[158:161], v[182:185], v[120:123]
	v_mfma_f32_16x16x32_bf16 v[108:111], v[144:147], v[190:193], v[108:111]
	v_mfma_f32_16x16x32_bf16 v[104:107], v[158:161], v[190:193], v[104:107]
	v_mfma_f32_16x16x32_bf16 v[92:95], v[144:147], v[198:201], v[92:95]
	v_mfma_f32_16x16x32_bf16 v[88:91], v[158:161], v[198:201], v[88:91]
	v_mfma_f32_16x16x32_bf16 v[76:79], v[144:147], v[206:209], v[76:79]
	v_mfma_f32_16x16x32_bf16 v[72:75], v[158:161], v[206:209], v[72:75]
	v_mfma_f32_16x16x32_bf16 v[124:127], v[154:157], v[186:189], v[124:127]
	v_mfma_f32_16x16x32_bf16 v[120:123], v[162:165], v[186:189], v[120:123]
	v_mfma_f32_16x16x32_bf16 v[108:111], v[154:157], v[194:197], v[108:111]
	v_mfma_f32_16x16x32_bf16 v[104:107], v[162:165], v[194:197], v[104:107]
	v_mfma_f32_16x16x32_bf16 v[92:95], v[154:157], v[202:205], v[92:95]
	v_mfma_f32_16x16x32_bf16 v[88:91], v[162:165], v[202:205], v[88:91]
	v_mfma_f32_16x16x32_bf16 v[76:79], v[154:157], v[210:213], v[76:79]
	v_mfma_f32_16x16x32_bf16 v[72:75], v[162:165], v[210:213], v[72:75]
	s_setprio 0
	s_setprio 1
	v_mfma_f32_16x16x32_bf16 v[116:119], v[166:169], v[182:185], v[116:119]
	v_mfma_f32_16x16x32_bf16 v[112:115], v[174:177], v[182:185], v[112:115]
	v_mfma_f32_16x16x32_bf16 v[100:103], v[166:169], v[190:193], v[100:103]
	v_mfma_f32_16x16x32_bf16 v[96:99], v[174:177], v[190:193], v[96:99]
	v_mfma_f32_16x16x32_bf16 v[84:87], v[166:169], v[198:201], v[84:87]
	v_mfma_f32_16x16x32_bf16 v[80:83], v[174:177], v[198:201], v[80:83]
	v_mfma_f32_16x16x32_bf16 v[68:71], v[166:169], v[206:209], v[68:71]
	v_mfma_f32_16x16x32_bf16 v[64:67], v[174:177], v[206:209], v[64:67]
	v_mfma_f32_16x16x32_bf16 v[116:119], v[170:173], v[186:189], v[116:119]
	v_mfma_f32_16x16x32_bf16 v[112:115], v[178:181], v[186:189], v[112:115]
	v_mfma_f32_16x16x32_bf16 v[100:103], v[170:173], v[194:197], v[100:103]
	v_mfma_f32_16x16x32_bf16 v[96:99], v[178:181], v[194:197], v[96:99]
	v_mfma_f32_16x16x32_bf16 v[84:87], v[170:173], v[202:205], v[84:87]
	v_mfma_f32_16x16x32_bf16 v[80:83], v[178:181], v[202:205], v[80:83]
	v_mfma_f32_16x16x32_bf16 v[68:71], v[170:173], v[210:213], v[68:71]
	v_mfma_f32_16x16x32_bf16 v[64:67], v[178:181], v[210:213], v[64:67]
	s_setprio 0
	s_barrier
	s_add_i32 s51, s44, s34
	v_lshl_add_u64 v[214:215], s[24:25], 0, v[130:131]
	s_mov_b32 m0, s51
	ds_read_b128 v[182:185], v153 offset:16384
	ds_read_b128 v[186:189], v153 offset:17408
	ds_read_b128 v[190:193], v153 offset:18432
	ds_read_b128 v[194:197], v153 offset:19456
	ds_read_b128 v[198:201], v153 offset:20480
	ds_read_b128 v[202:205], v153 offset:21504
	ds_read_b128 v[206:209], v153 offset:22528
	ds_read_b128 v[210:213], v153 offset:23552
	global_load_lds_dwordx4 v[214:215], off
	s_add_i32 m0, s51, 0x2000
	s_add_u32 s52, s24, 0x80000
	v_lshl_add_u64 v[216:217], s[24:25], 0, v[134:135]
	s_addc_u32 s53, s25, 0
	s_add_i32 s51, s45, s34
	global_load_lds_dwordx4 v[216:217], off
	v_lshl_add_u64 v[218:219], s[52:53], 0, v[130:131]
	s_mov_b32 m0, s51
	v_lshl_add_u64 v[220:221], s[26:27], 0, v[132:133]
	global_load_lds_dwordx4 v[218:219], off
	v_lshl_add_u64 v[218:219], s[52:53], 0, v[134:135]
	s_add_i32 m0, s51, 0x2000
	s_nop 0
	global_load_lds_dwordx4 v[218:219], off
	v_lshl_add_u64 v[218:219], s[26:27], 0, v[128:129]
	s_mov_b32 m0, s21
	s_nop 0
	global_load_lds_dwordx4 v[218:219], off
	s_mov_b32 m0, s35
	s_nop 0
	global_load_lds_dwordx4 v[220:221], off
	s_waitcnt vmcnt(24)
	s_waitcnt lgkmcnt(0)
	s_barrier
	s_setprio 1
	s_waitcnt lgkmcnt(0)
	v_mfma_f32_16x16x32_bf16 v[60:63], v[144:147], v[182:185], v[60:63]
	v_mfma_f32_16x16x32_bf16 v[56:59], v[158:161], v[182:185], v[56:59]
	v_mfma_f32_16x16x32_bf16 v[44:47], v[144:147], v[190:193], v[44:47]
	v_mfma_f32_16x16x32_bf16 v[40:43], v[158:161], v[190:193], v[40:43]
	v_mfma_f32_16x16x32_bf16 v[28:31], v[144:147], v[198:201], v[28:31]
	v_mfma_f32_16x16x32_bf16 v[24:27], v[158:161], v[198:201], v[24:27]
	v_mfma_f32_16x16x32_bf16 v[12:15], v[144:147], v[206:209], v[12:15]
	v_mfma_f32_16x16x32_bf16 v[8:11], v[158:161], v[206:209], v[8:11]
	v_mfma_f32_16x16x32_bf16 v[60:63], v[154:157], v[186:189], v[60:63]
	v_mfma_f32_16x16x32_bf16 v[56:59], v[162:165], v[186:189], v[56:59]
	v_mfma_f32_16x16x32_bf16 v[44:47], v[154:157], v[194:197], v[44:47]
	v_mfma_f32_16x16x32_bf16 v[40:43], v[162:165], v[194:197], v[40:43]
	v_mfma_f32_16x16x32_bf16 v[28:31], v[154:157], v[202:205], v[28:31]
	v_mfma_f32_16x16x32_bf16 v[24:27], v[162:165], v[202:205], v[24:27]
	v_mfma_f32_16x16x32_bf16 v[12:15], v[154:157], v[210:213], v[12:15]
	v_mfma_f32_16x16x32_bf16 v[8:11], v[162:165], v[210:213], v[8:11]
	s_setprio 0
	s_setprio 1
	v_mfma_f32_16x16x32_bf16 v[52:55], v[166:169], v[182:185], v[52:55]
	v_mfma_f32_16x16x32_bf16 v[48:51], v[174:177], v[182:185], v[48:51]
	v_mfma_f32_16x16x32_bf16 v[36:39], v[166:169], v[190:193], v[36:39]
	v_mfma_f32_16x16x32_bf16 v[32:35], v[174:177], v[190:193], v[32:35]
	v_mfma_f32_16x16x32_bf16 v[20:23], v[166:169], v[198:201], v[20:23]
	v_mfma_f32_16x16x32_bf16 v[16:19], v[174:177], v[198:201], v[16:19]
	v_mfma_f32_16x16x32_bf16 v[4:7], v[166:169], v[206:209], v[4:7]
	v_mfma_f32_16x16x32_bf16 v[0:3], v[174:177], v[206:209], v[0:3]
	v_mfma_f32_16x16x32_bf16 v[52:55], v[170:173], v[186:189], v[52:55]
	v_mfma_f32_16x16x32_bf16 v[48:51], v[178:181], v[186:189], v[48:51]
	v_mfma_f32_16x16x32_bf16 v[36:39], v[170:173], v[194:197], v[36:39]
	v_mfma_f32_16x16x32_bf16 v[32:35], v[178:181], v[194:197], v[32:35]
	v_mfma_f32_16x16x32_bf16 v[20:23], v[170:173], v[202:205], v[20:23]
	v_mfma_f32_16x16x32_bf16 v[16:19], v[178:181], v[202:205], v[16:19]
	v_mfma_f32_16x16x32_bf16 v[4:7], v[170:173], v[210:213], v[4:7]
	v_mfma_f32_16x16x32_bf16 v[0:3], v[178:181], v[210:213], v[0:3]
	s_setprio 0
	s_barrier
; #define PG8_STAGE(bufoff, gbase, voff) do { _Pragma("unroll") for (int _i = 0; _i < 2; ++_i) \
;         __builtin_amdgcn_global_load_lds((const unsigned*)((const char*)(gbase) + (voff)[_i]), (PG8_LAS unsigned*)(lds + (bufoff) + ldsw + _i * 8192), 16, 0, 0); } while (0)
; #define PG8_LDA(dst, b, h) do { _Pragma("unroll") for (int m = 0; m < 4; ++m) _Pragma("unroll") for (int k = 0; k < 2; ++k) dst[m][k] = *(const PG8_LAS bf16x8*)(lds + PG8_SA(b, h) + aoff + m * 2048 + k * 1024); } while (0)
; #define PG8_LDB(dst, b, h) do { _Pragma("unroll") for (int n = 0; n < 2; ++n) _Pragma("unroll") for (int k = 0; k < 2; ++k) dst[n][k] = *(const PG8_LAS bf16x8*)(lds + PG8_SB(b, h) + boff + n * 2048 + k * 1024); } while (0)
; #define PG8_MMA(ai, bj, At, Bt) do { __builtin_amdgcn_s_setprio(1); _Pragma("unroll") for (int m = 0; m < 4; ++m) _Pragma("unroll") for (int n = 0; n < 2; ++n) _Pragma("unroll") for (int k = 0; k < 2; ++k) \
;         acc[ai][bj][m][n] = __builtin_amdgcn_mfma_f32_16x16x32_bf16(Bt[n][k], At[m][k], acc[ai][bj][m][n], 0, 0, 0); __builtin_amdgcn_s_setprio(0); } while (0)
; #define PG8_WAIT_V(n) asm volatile("s_waitcnt vmcnt(" #n ")" ::: "memory")
; #define PG8_WAIT_L(n) asm volatile("s_waitcnt lgkmcnt(" #n ")" ::: "memory")
; #define PG8_BAR __builtin_amdgcn_s_barrier()
; #define PG8_SCHED __builtin_amdgcn_sched_barrier(0)
; template <class Epi, class Sched, bool ALIGN_EPI = false, bool SP2 = false>
; __device__ __forceinline__ void gemm_phase(PG8_LAS unsigned char* lds, const Gemm g, const Sched& S, const Epi& E, const int wave_in) {
;     ...
;             PG8_LDB(B0, 1, 0); PG8_LDB(B1, 1, 1); PG8_SCHED; PG8_LDA(At, 1, 0); PG8_STAGE(PG8_SA(0, 1), a2 + hstepA, voffA);
;             PG8_WAIT_V(8); PG8_WAIT_L(0); PG8_BAR; PG8_MMA(0, 0, At, B0); PG8_MMA(0, 1, At, B1); PG8_BAR; PG8_SCHED;
;             PG8_LDA(At, 1, 1); PG8_STAGE(PG8_SB(1, 0), b3, voffB); PG8_STAGE(PG8_SB(1, 1), b3 + hstepB, voffB); PG8_STAGE(PG8_SA(1, 0), a3, voffA);
;             PG8_WAIT_V(8); PG8_WAIT_L(0); PG8_BAR; PG8_MMA(1, 0, At, B0); PG8_MMA(1, 1, At, B1); PG8_BAR; PG8_SCHED;
	s_add_i32 s51, 0, 0x18000
	s_add_i32 s52, 0, 0x1c000
	v_add_u32_e32 v162, s51, v149
	v_add_u32_e32 v178, s52, v149
	ds_read_b128 v[144:147], v162
	ds_read_b128 v[154:157], v162 offset:1024
	ds_read_b128 v[158:161], v162 offset:2048
	ds_read_b128 v[162:165], v162 offset:3072
	ds_read_b128 v[166:169], v178
	ds_read_b128 v[170:173], v178 offset:1024
	ds_read_b128 v[174:177], v178 offset:2048
	ds_read_b128 v[178:181], v178 offset:3072
	s_add_u32 s26, s26, 0x80000
	s_addc_u32 s27, s27, 0
	s_mov_b32 m0, s36
	v_lshl_add_u64 v[222:223], s[26:27], 0, v[128:129]
	ds_read_b128 v[182:185], v153 offset:32768
	ds_read_b128 v[186:189], v153 offset:33792
	ds_read_b128 v[190:193], v153 offset:34816
	ds_read_b128 v[194:197], v153 offset:35840
	ds_read_b128 v[198:201], v153 offset:36864
	ds_read_b128 v[202:205], v153 offset:37888
	ds_read_b128 v[206:209], v153 offset:38912
	ds_read_b128 v[210:213], v153 offset:39936
	global_load_lds_dwordx4 v[222:223], off
	v_lshl_add_u64 v[222:223], s[26:27], 0, v[132:133]
	s_mov_b32 m0, s37
	s_nop 0
	global_load_lds_dwordx4 v[222:223], off
	s_waitcnt vmcnt(8)
	s_waitcnt lgkmcnt(0)
	s_barrier
	s_setprio 1
	s_waitcnt lgkmcnt(0)
	v_mfma_f32_16x16x32_bf16 v[124:127], v[144:147], v[182:185], v[124:127]
	v_mfma_f32_16x16x32_bf16 v[120:123], v[158:161], v[182:185], v[120:123]
	v_mfma_f32_16x16x32_bf16 v[108:111], v[144:147], v[190:193], v[108:111]
	v_mfma_f32_16x16x32_bf16 v[104:107], v[158:161], v[190:193], v[104:107]
	v_mfma_f32_16x16x32_bf16 v[92:95], v[144:147], v[198:201], v[92:95]
	v_mfma_f32_16x16x32_bf16 v[88:91], v[158:161], v[198:201], v[88:91]
	v_mfma_f32_16x16x32_bf16 v[76:79], v[144:147], v[206:209], v[76:79]
	v_mfma_f32_16x16x32_bf16 v[72:75], v[158:161], v[206:209], v[72:75]
	v_mfma_f32_16x16x32_bf16 v[124:127], v[154:157], v[186:189], v[124:127]
	v_mfma_f32_16x16x32_bf16 v[120:123], v[162:165], v[186:189], v[120:123]
	v_mfma_f32_16x16x32_bf16 v[108:111], v[154:157], v[194:197], v[108:111]
	v_mfma_f32_16x16x32_bf16 v[104:107], v[162:165], v[194:197], v[104:107]
	v_mfma_f32_16x16x32_bf16 v[92:95], v[154:157], v[202:205], v[92:95]
	v_mfma_f32_16x16x32_bf16 v[88:91], v[162:165], v[202:205], v[88:91]
	v_mfma_f32_16x16x32_bf16 v[76:79], v[154:157], v[210:213], v[76:79]
	v_mfma_f32_16x16x32_bf16 v[72:75], v[162:165], v[210:213], v[72:75]
	s_setprio 0
	s_setprio 1
	v_mfma_f32_16x16x32_bf16 v[116:119], v[166:169], v[182:185], v[116:119]
	v_mfma_f32_16x16x32_bf16 v[112:115], v[174:177], v[182:185], v[112:115]
	v_mfma_f32_16x16x32_bf16 v[100:103], v[166:169], v[190:193], v[100:103]
	v_mfma_f32_16x16x32_bf16 v[96:99], v[174:177], v[190:193], v[96:99]
	v_mfma_f32_16x16x32_bf16 v[84:87], v[166:169], v[198:201], v[84:87]
	v_mfma_f32_16x16x32_bf16 v[80:83], v[174:177], v[198:201], v[80:83]
	v_mfma_f32_16x16x32_bf16 v[68:71], v[166:169], v[206:209], v[68:71]
	v_mfma_f32_16x16x32_bf16 v[64:67], v[174:177], v[206:209], v[64:67]
	v_mfma_f32_16x16x32_bf16 v[116:119], v[170:173], v[186:189], v[116:119]
	v_mfma_f32_16x16x32_bf16 v[112:115], v[178:181], v[186:189], v[112:115]
	v_mfma_f32_16x16x32_bf16 v[100:103], v[170:173], v[194:197], v[100:103]
	v_mfma_f32_16x16x32_bf16 v[96:99], v[178:181], v[194:197], v[96:99]
	v_mfma_f32_16x16x32_bf16 v[84:87], v[170:173], v[202:205], v[84:87]
	v_mfma_f32_16x16x32_bf16 v[80:83], v[178:181], v[202:205], v[80:83]
	v_mfma_f32_16x16x32_bf16 v[68:71], v[170:173], v[210:213], v[68:71]
	v_mfma_f32_16x16x32_bf16 v[64:67], v[178:181], v[210:213], v[64:67]
	s_setprio 0
	s_barrier
	s_add_i32 s26, s51, s34
	v_lshl_add_u64 v[214:215], v[214:215], 0, s[8:9]
	s_mov_b32 m0, s26
	ds_read_b128 v[182:185], v153 offset:49152
	ds_read_b128 v[186:189], v153 offset:50176
	ds_read_b128 v[190:193], v153 offset:51200
	ds_read_b128 v[194:197], v153 offset:52224
	ds_read_b128 v[198:201], v153 offset:53248
	ds_read_b128 v[202:205], v153 offset:54272
	ds_read_b128 v[206:209], v153 offset:55296
	ds_read_b128 v[210:213], v153 offset:56320
	global_load_lds_dwordx4 v[214:215], off
	s_add_i32 m0, s26, 0x2000
	s_add_u32 s24, s24, 0x80080
	v_lshl_add_u64 v[214:215], v[216:217], 0, s[8:9]
	s_addc_u32 s25, s25, 0
	s_add_i32 s26, s52, s34
	global_load_lds_dwordx4 v[214:215], off
	v_lshl_add_u64 v[214:215], s[24:25], 0, v[130:131]
	s_mov_b32 m0, s26
	s_nop 0
	global_load_lds_dwordx4 v[214:215], off
	v_lshl_add_u64 v[214:215], s[24:25], 0, v[134:135]
	s_add_i32 m0, s26, 0x2000
	s_nop 0
	global_load_lds_dwordx4 v[214:215], off
	v_lshl_add_u64 v[214:215], v[218:219], 0, s[8:9]
	s_mov_b32 m0, s39
	s_nop 0
	global_load_lds_dwordx4 v[214:215], off
	v_lshl_add_u64 v[214:215], v[220:221], 0, s[8:9]
	s_mov_b32 m0, s40
	s_nop 0
	global_load_lds_dwordx4 v[214:215], off
	s_waitcnt vmcnt(8)
	s_waitcnt lgkmcnt(0)
	s_barrier
; #define PG8_STAGE(bufoff, gbase, voff) do { _Pragma("unroll") for (int _i = 0; _i < 2; ++_i) \
;         __builtin_amdgcn_global_load_lds((const unsigned*)((const char*)(gbase) + (voff)[_i]), (PG8_LAS unsigned*)(lds + (bufoff) + ldsw + _i * 8192), 16, 0, 0); } while (0)
; #define PG8_LDA(dst, b, h) do { _Pragma("unroll") for (int m = 0; m < 4; ++m) _Pragma("unroll") for (int k = 0; k < 2; ++k) dst[m][k] = *(const PG8_LAS bf16x8*)(lds + PG8_SA(b, h) + aoff + m * 2048 + k * 1024); } while (0)
; #define PG8_LDB(dst, b, h) do { _Pragma("unroll") for (int n = 0; n < 2; ++n) _Pragma("unroll") for (int k = 0; k < 2; ++k) dst[n][k] = *(const PG8_LAS bf16x8*)(lds + PG8_SB(b, h) + boff + n * 2048 + k * 1024); } while (0)
; #define PG8_MMA(ai, bj, At, Bt) do { __builtin_amdgcn_s_setprio(1); _Pragma("unroll") for (int m = 0; m < 4; ++m) _Pragma("unroll") for (int n = 0; n < 2; ++n) _Pragma("unroll") for (int k = 0; k < 2; ++k) \
;         acc[ai][bj][m][n] = __builtin_amdgcn_mfma_f32_16x16x32_bf16(Bt[n][k], At[m][k], acc[ai][bj][m][n], 0, 0, 0); __builtin_amdgcn_s_setprio(0); } while (0)
; #define PG8_WAIT_V(n) asm volatile("s_waitcnt vmcnt(" #n ")" ::: "memory")
; #define PG8_WAIT_L(n) asm volatile("s_waitcnt lgkmcnt(" #n ")" ::: "memory")
; #define PG8_BAR __builtin_amdgcn_s_barrier()
; #define PG8_SCHED __builtin_amdgcn_sched_barrier(0)
; template <class Epi, class Sched, bool ALIGN_EPI = false, bool SP2 = false>
; __device__ __forceinline__ void gemm_phase(PG8_LAS unsigned char* lds, const Gemm g, const Sched& S, const Epi& E, const int wave_in) {
;     ...
;         for (int t = 0; t < nt; t += 2) {
;             const bool last = (t == nt - 2);
;             const char* a1 = cA + (size_t)(t + 1) * kstep;
;             const char* a2 = last ? nA : cA + (size_t)(t + 2) * kstep; const char* b2 = last ? nB : cB + (size_t)(t + 2) * kstep;
;             const char* a3 = a2 + kstep; const char* b3 = b2 + kstep;
;             if (last && has_next) S.a_ready(nxt);
;             if constexpr (SP2) {
;             PG8_LDB(B0, 0, 0); PG8_LDB(B1, 0, 1); PG8_SCHED; PG8_LDA(At, 0, 0); PG8_STAGE(PG8_SA(1, 1), a1 + hstepA, voffA);
;             PG8_WAIT_V(8); PG8_WAIT_L(0); PG8_BAR; PG8_MMA(0, 0, At, B0); PG8_MMA(0, 1, At, B1); PG8_BAR; PG8_SCHED;
	s_setprio 1
	s_waitcnt lgkmcnt(0)
	v_mfma_f32_16x16x32_bf16 v[60:63], v[144:147], v[182:185], v[60:63]
	v_mfma_f32_16x16x32_bf16 v[56:59], v[158:161], v[182:185], v[56:59]
	v_mfma_f32_16x16x32_bf16 v[44:47], v[144:147], v[190:193], v[44:47]
	v_mfma_f32_16x16x32_bf16 v[40:43], v[158:161], v[190:193], v[40:43]
	v_mfma_f32_16x16x32_bf16 v[28:31], v[144:147], v[198:201], v[28:31]
	v_mfma_f32_16x16x32_bf16 v[24:27], v[158:161], v[198:201], v[24:27]
	v_mfma_f32_16x16x32_bf16 v[12:15], v[144:147], v[206:209], v[12:15]
	v_mfma_f32_16x16x32_bf16 v[8:11], v[158:161], v[206:209], v[8:11]
	v_mfma_f32_16x16x32_bf16 v[60:63], v[154:157], v[186:189], v[60:63]
	v_mfma_f32_16x16x32_bf16 v[56:59], v[162:165], v[186:189], v[56:59]
	v_mfma_f32_16x16x32_bf16 v[44:47], v[154:157], v[194:197], v[44:47]
	v_mfma_f32_16x16x32_bf16 v[40:43], v[162:165], v[194:197], v[40:43]
	v_mfma_f32_16x16x32_bf16 v[28:31], v[154:157], v[202:205], v[28:31]
	v_mfma_f32_16x16x32_bf16 v[24:27], v[162:165], v[202:205], v[24:27]
	v_mfma_f32_16x16x32_bf16 v[12:15], v[154:157], v[210:213], v[12:15]
	v_mfma_f32_16x16x32_bf16 v[8:11], v[162:165], v[210:213], v[8:11]
	s_setprio 0
	s_setprio 1
	v_mfma_f32_16x16x32_bf16 v[52:55], v[166:169], v[182:185], v[52:55]
	v_mfma_f32_16x16x32_bf16 v[48:51], v[174:177], v[182:185], v[48:51]
	v_mfma_f32_16x16x32_bf16 v[36:39], v[166:169], v[190:193], v[36:39]
	v_mfma_f32_16x16x32_bf16 v[32:35], v[174:177], v[190:193], v[32:35]
	v_mfma_f32_16x16x32_bf16 v[20:23], v[166:169], v[198:201], v[20:23]
	v_mfma_f32_16x16x32_bf16 v[16:19], v[174:177], v[198:201], v[16:19]
	v_mfma_f32_16x16x32_bf16 v[4:7], v[166:169], v[206:209], v[4:7]
	v_mfma_f32_16x16x32_bf16 v[0:3], v[174:177], v[206:209], v[0:3]
	v_mfma_f32_16x16x32_bf16 v[52:55], v[170:173], v[186:189], v[52:55]
	v_mfma_f32_16x16x32_bf16 v[48:51], v[178:181], v[186:189], v[48:51]
	v_mfma_f32_16x16x32_bf16 v[36:39], v[170:173], v[194:197], v[36:39]
	v_mfma_f32_16x16x32_bf16 v[32:35], v[178:181], v[194:197], v[32:35]
	v_mfma_f32_16x16x32_bf16 v[20:23], v[170:173], v[202:205], v[20:23]
	v_mfma_f32_16x16x32_bf16 v[16:19], v[178:181], v[202:205], v[16:19]
	v_mfma_f32_16x16x32_bf16 v[4:7], v[170:173], v[210:213], v[4:7]
	v_mfma_f32_16x16x32_bf16 v[0:3], v[178:181], v[210:213], v[0:3]
	s_setprio 0
	s_barrier
	s_add_i32 s50, s50, 2
	s_add_u32 s22, s22, 0x100
	s_addc_u32 s23, s23, 0
	s_add_u32 s48, s48, 0x100
	s_addc_u32 s49, s49, 0
	s_cmp_gt_u32 s50, 29
	s_cbranch_scc0 .LBB0_2248
.LBB0_2248:
	ds_read_b128 v[144:147], v151
	ds_read_b128 v[154:157], v151 offset:1024
	ds_read_b128 v[158:161], v151 offset:2048
	ds_read_b128 v[162:165], v151 offset:3072
	ds_read_b128 v[166:169], v152
	ds_read_b128 v[170:173], v152 offset:1024
	ds_read_b128 v[174:177], v152 offset:2048
	ds_read_b128 v[178:181], v152 offset:3072
	s_add_u32 s24, s22, 0xfff80080
	s_addc_u32 s25, s23, -1
	s_cmp_eq_u32 s50, 28
	s_cselect_b32 s27, s5, s25
	s_cselect_b32 s26, s15, s24
	s_cselect_b32 s25, s13, s49
	s_cselect_b32 s24, s47, s48
	v_lshl_add_u64 v[214:215], s[22:23], 0, v[136:137]
	s_add_i32 m0, s21, 0xc000
	ds_read_b128 v[182:185], v153
	ds_read_b128 v[186:189], v153 offset:1024
	ds_read_b128 v[190:193], v153 offset:2048
	ds_read_b128 v[194:197], v153 offset:3072
	ds_read_b128 v[198:201], v153 offset:4096
	ds_read_b128 v[202:205], v153 offset:5120
	ds_read_b128 v[206:209], v153 offset:6144
	ds_read_b128 v[210:213], v153 offset:7168
	global_load_lds_dwordx4 v[214:215], off
	v_lshl_add_u64 v[214:215], s[22:23], 0, v[138:139]
	s_add_i32 m0, s21, 0xe000
	s_nop 0
	global_load_lds_dwordx4 v[214:215], off
	s_waitcnt vmcnt(8)
	s_waitcnt lgkmcnt(0)
	s_barrier
	s_setprio 1
	s_waitcnt lgkmcnt(0)
	v_mfma_f32_16x16x32_bf16 v[124:127], v[144:147], v[182:185], v[124:127]
	v_mfma_f32_16x16x32_bf16 v[120:123], v[158:161], v[182:185], v[120:123]
	v_mfma_f32_16x16x32_bf16 v[108:111], v[144:147], v[190:193], v[108:111]
	v_mfma_f32_16x16x32_bf16 v[104:107], v[158:161], v[190:193], v[104:107]
	v_mfma_f32_16x16x32_bf16 v[92:95], v[144:147], v[198:201], v[92:95]
	v_mfma_f32_16x16x32_bf16 v[88:91], v[158:161], v[198:201], v[88:91]
	v_mfma_f32_16x16x32_bf16 v[76:79], v[144:147], v[206:209], v[76:79]
	v_mfma_f32_16x16x32_bf16 v[72:75], v[158:161], v[206:209], v[72:75]
	v_mfma_f32_16x16x32_bf16 v[124:127], v[154:157], v[186:189], v[124:127]
	v_mfma_f32_16x16x32_bf16 v[120:123], v[162:165], v[186:189], v[120:123]
	v_mfma_f32_16x16x32_bf16 v[108:111], v[154:157], v[194:197], v[108:111]
	v_mfma_f32_16x16x32_bf16 v[104:107], v[162:165], v[194:197], v[104:107]
	v_mfma_f32_16x16x32_bf16 v[92:95], v[154:157], v[202:205], v[92:95]
	v_mfma_f32_16x16x32_bf16 v[88:91], v[162:165], v[202:205], v[88:91]
	v_mfma_f32_16x16x32_bf16 v[76:79], v[154:157], v[210:213], v[76:79]
	v_mfma_f32_16x16x32_bf16 v[72:75], v[162:165], v[210:213], v[72:75]
	s_setprio 0
	s_setprio 1
	v_mfma_f32_16x16x32_bf16 v[116:119], v[166:169], v[182:185], v[116:119]
	v_mfma_f32_16x16x32_bf16 v[112:115], v[174:177], v[182:185], v[112:115]
	v_mfma_f32_16x16x32_bf16 v[100:103], v[166:169], v[190:193], v[100:103]
	v_mfma_f32_16x16x32_bf16 v[96:99], v[174:177], v[190:193], v[96:99]
	v_mfma_f32_16x16x32_bf16 v[84:87], v[166:169], v[198:201], v[84:87]
	v_mfma_f32_16x16x32_bf16 v[80:83], v[174:177], v[198:201], v[80:83]
	v_mfma_f32_16x16x32_bf16 v[68:71], v[166:169], v[206:209], v[68:71]
	v_mfma_f32_16x16x32_bf16 v[64:67], v[174:177], v[206:209], v[64:67]
	v_mfma_f32_16x16x32_bf16 v[116:119], v[170:173], v[186:189], v[116:119]
	v_mfma_f32_16x16x32_bf16 v[112:115], v[178:181], v[186:189], v[112:115]
	v_mfma_f32_16x16x32_bf16 v[100:103], v[170:173], v[194:197], v[100:103]
	v_mfma_f32_16x16x32_bf16 v[96:99], v[178:181], v[194:197], v[96:99]
	v_mfma_f32_16x16x32_bf16 v[84:87], v[170:173], v[202:205], v[84:87]
	v_mfma_f32_16x16x32_bf16 v[80:83], v[178:181], v[202:205], v[80:83]
	v_mfma_f32_16x16x32_bf16 v[68:71], v[170:173], v[210:213], v[68:71]
	v_mfma_f32_16x16x32_bf16 v[64:67], v[178:181], v[210:213], v[64:67]
	s_setprio 0
	s_barrier
; #define PG8_STAGE(bufoff, gbase, voff) do { _Pragma("unroll") for (int _i = 0; _i < 2; ++_i) \
;         __builtin_amdgcn_global_load_lds((const unsigned*)((const char*)(gbase) + (voff)[_i]), (PG8_LAS unsigned*)(lds + (bufoff) + ldsw + _i * 8192), 16, 0, 0); } while (0)
; #define PG8_LDA(dst, b, h) do { _Pragma("unroll") for (int m = 0; m < 4; ++m) _Pragma("unroll") for (int k = 0; k < 2; ++k) dst[m][k] = *(const PG8_LAS bf16x8*)(lds + PG8_SA(b, h) + aoff + m * 2048 + k * 1024); } while (0)
; #define PG8_LDB(dst, b, h) do { _Pragma("unroll") for (int n = 0; n < 2; ++n) _Pragma("unroll") for (int k = 0; k < 2; ++k) dst[n][k] = *(const PG8_LAS bf16x8*)(lds + PG8_SB(b, h) + boff + n * 2048 + k * 1024); } while (0)
; #define PG8_MMA(ai, bj, At, Bt) do { __builtin_amdgcn_s_setprio(1); _Pragma("unroll") for (int m = 0; m < 4; ++m) _Pragma("unroll") for (int n = 0; n < 2; ++n) _Pragma("unroll") for (int k = 0; k < 2; ++k) \
;         acc[ai][bj][m][n] = __builtin_amdgcn_mfma_f32_16x16x32_bf16(Bt[n][k], At[m][k], acc[ai][bj][m][n], 0, 0, 0); __builtin_amdgcn_s_setprio(0); } while (0)
; #define PG8_WAIT_V(n) asm volatile("s_waitcnt vmcnt(" #n ")" ::: "memory")
; #define PG8_WAIT_L(n) asm volatile("s_waitcnt lgkmcnt(" #n ")" ::: "memory")
; #define PG8_BAR __builtin_amdgcn_s_barrier()
; #define PG8_SCHED __builtin_amdgcn_sched_barrier(0)
; template <class Epi, class Sched, bool ALIGN_EPI = false, bool SP2 = false>
; __device__ __forceinline__ void gemm_phase(PG8_LAS unsigned char* lds, const Gemm g, const Sched& S, const Epi& E, const int wave_in) {
;     ...
;             PG8_LDA(At, 0, 1); PG8_STAGE(PG8_SB(0, 0), b2, voffB); PG8_STAGE(PG8_SB(0, 1), b2 + hstepB, voffB); PG8_STAGE(PG8_SA(0, 0), a2, voffA);
;             PG8_WAIT_V(8); PG8_WAIT_L(0); PG8_BAR; PG8_MMA(1, 0, At, B0); PG8_MMA(1, 1, At, B1); PG8_BAR; PG8_SCHED;
;             PG8_LDB(B0, 1, 0); PG8_LDB(B1, 1, 1); PG8_SCHED; PG8_LDA(At, 1, 0); PG8_STAGE(PG8_SA(0, 1), a2 + hstepA, voffA);
;             PG8_WAIT_V(8); PG8_WAIT_L(0); PG8_BAR; PG8_MMA(0, 0, At, B0); PG8_MMA(0, 1, At, B1); PG8_BAR; PG8_SCHED;
;             PG8_LDA(At, 1, 1); PG8_STAGE(PG8_SB(1, 0), b3, voffB); PG8_STAGE(PG8_SB(1, 1), b3 + hstepB, voffB); PG8_STAGE(PG8_SA(1, 0), a3, voffA);
	s_add_i32 s51, s44, s34
	v_lshl_add_u64 v[214:215], s[24:25], 0, v[130:131]
	s_mov_b32 m0, s51
	ds_read_b128 v[182:185], v153 offset:16384
	ds_read_b128 v[186:189], v153 offset:17408
	ds_read_b128 v[190:193], v153 offset:18432
	ds_read_b128 v[194:197], v153 offset:19456
	ds_read_b128 v[198:201], v153 offset:20480
	ds_read_b128 v[202:205], v153 offset:21504
	ds_read_b128 v[206:209], v153 offset:22528
	ds_read_b128 v[210:213], v153 offset:23552
	global_load_lds_dwordx4 v[214:215], off
	s_add_i32 m0, s51, 0x2000
	s_add_u32 s52, s24, 0x80000
	v_lshl_add_u64 v[216:217], s[24:25], 0, v[134:135]
	s_addc_u32 s53, s25, 0
	s_add_i32 s51, s45, s34
	global_load_lds_dwordx4 v[216:217], off
	v_lshl_add_u64 v[218:219], s[52:53], 0, v[130:131]
	s_mov_b32 m0, s51
	v_lshl_add_u64 v[220:221], s[26:27], 0, v[132:133]
	global_load_lds_dwordx4 v[218:219], off
	v_lshl_add_u64 v[218:219], s[52:53], 0, v[134:135]
	s_add_i32 m0, s51, 0x2000
	s_nop 0
	global_load_lds_dwordx4 v[218:219], off
	v_lshl_add_u64 v[218:219], s[26:27], 0, v[128:129]
	s_mov_b32 m0, s21
	s_nop 0
	global_load_lds_dwordx4 v[218:219], off
	s_mov_b32 m0, s35
	s_nop 0
	global_load_lds_dwordx4 v[220:221], off
	s_waitcnt vmcnt(8)
	s_waitcnt lgkmcnt(0)
	s_barrier
	s_setprio 1
	s_waitcnt lgkmcnt(0)
	v_mfma_f32_16x16x32_bf16 v[60:63], v[144:147], v[182:185], v[60:63]
	v_mfma_f32_16x16x32_bf16 v[56:59], v[158:161], v[182:185], v[56:59]
	v_mfma_f32_16x16x32_bf16 v[44:47], v[144:147], v[190:193], v[44:47]
	v_mfma_f32_16x16x32_bf16 v[40:43], v[158:161], v[190:193], v[40:43]
	v_mfma_f32_16x16x32_bf16 v[28:31], v[144:147], v[198:201], v[28:31]
	v_mfma_f32_16x16x32_bf16 v[24:27], v[158:161], v[198:201], v[24:27]
	v_mfma_f32_16x16x32_bf16 v[12:15], v[144:147], v[206:209], v[12:15]
	v_mfma_f32_16x16x32_bf16 v[8:11], v[158:161], v[206:209], v[8:11]
	v_mfma_f32_16x16x32_bf16 v[60:63], v[154:157], v[186:189], v[60:63]
	v_mfma_f32_16x16x32_bf16 v[56:59], v[162:165], v[186:189], v[56:59]
	v_mfma_f32_16x16x32_bf16 v[44:47], v[154:157], v[194:197], v[44:47]
	v_mfma_f32_16x16x32_bf16 v[40:43], v[162:165], v[194:197], v[40:43]
	v_mfma_f32_16x16x32_bf16 v[28:31], v[154:157], v[202:205], v[28:31]
	v_mfma_f32_16x16x32_bf16 v[24:27], v[162:165], v[202:205], v[24:27]
	v_mfma_f32_16x16x32_bf16 v[12:15], v[154:157], v[210:213], v[12:15]
	v_mfma_f32_16x16x32_bf16 v[8:11], v[162:165], v[210:213], v[8:11]
	s_setprio 0
	s_setprio 1
	v_mfma_f32_16x16x32_bf16 v[52:55], v[166:169], v[182:185], v[52:55]
	v_mfma_f32_16x16x32_bf16 v[48:51], v[174:177], v[182:185], v[48:51]
	v_mfma_f32_16x16x32_bf16 v[36:39], v[166:169], v[190:193], v[36:39]
	v_mfma_f32_16x16x32_bf16 v[32:35], v[174:177], v[190:193], v[32:35]
	v_mfma_f32_16x16x32_bf16 v[20:23], v[166:169], v[198:201], v[20:23]
	v_mfma_f32_16x16x32_bf16 v[16:19], v[174:177], v[198:201], v[16:19]
	v_mfma_f32_16x16x32_bf16 v[4:7], v[166:169], v[206:209], v[4:7]
	v_mfma_f32_16x16x32_bf16 v[0:3], v[174:177], v[206:209], v[0:3]
	v_mfma_f32_16x16x32_bf16 v[52:55], v[170:173], v[186:189], v[52:55]
	v_mfma_f32_16x16x32_bf16 v[48:51], v[178:181], v[186:189], v[48:51]
	v_mfma_f32_16x16x32_bf16 v[36:39], v[170:173], v[194:197], v[36:39]
	v_mfma_f32_16x16x32_bf16 v[32:35], v[178:181], v[194:197], v[32:35]
	v_mfma_f32_16x16x32_bf16 v[20:23], v[170:173], v[202:205], v[20:23]
	v_mfma_f32_16x16x32_bf16 v[16:19], v[178:181], v[202:205], v[16:19]
	v_mfma_f32_16x16x32_bf16 v[4:7], v[170:173], v[210:213], v[4:7]
	v_mfma_f32_16x16x32_bf16 v[0:3], v[178:181], v[210:213], v[0:3]
	s_setprio 0
	s_barrier
	s_add_i32 s51, 0, 0x18000
	s_add_i32 s52, 0, 0x1c000
	v_add_u32_e32 v162, s51, v149
	v_add_u32_e32 v178, s52, v149
	ds_read_b128 v[144:147], v162
	ds_read_b128 v[154:157], v162 offset:1024
	ds_read_b128 v[158:161], v162 offset:2048
	ds_read_b128 v[162:165], v162 offset:3072
	ds_read_b128 v[166:169], v178
	ds_read_b128 v[170:173], v178 offset:1024
	ds_read_b128 v[174:177], v178 offset:2048
	ds_read_b128 v[178:181], v178 offset:3072
	s_add_u32 s26, s26, 0x80000
	s_addc_u32 s27, s27, 0
	s_mov_b32 m0, s36
	v_lshl_add_u64 v[222:223], s[26:27], 0, v[128:129]
	ds_read_b128 v[182:185], v153 offset:32768
	ds_read_b128 v[186:189], v153 offset:33792
	ds_read_b128 v[190:193], v153 offset:34816
	ds_read_b128 v[194:197], v153 offset:35840
	ds_read_b128 v[198:201], v153 offset:36864
	ds_read_b128 v[202:205], v153 offset:37888
	ds_read_b128 v[206:209], v153 offset:38912
	ds_read_b128 v[210:213], v153 offset:39936
	global_load_lds_dwordx4 v[222:223], off
	v_lshl_add_u64 v[222:223], s[26:27], 0, v[132:133]
	s_mov_b32 m0, s37
	s_nop 0
	global_load_lds_dwordx4 v[222:223], off
	s_waitcnt vmcnt(8)
	s_waitcnt lgkmcnt(0)
	s_barrier
; #define PG8_STAGE(bufoff, gbase, voff) do { _Pragma("unroll") for (int _i = 0; _i < 2; ++_i) \
;         __builtin_amdgcn_global_load_lds((const unsigned*)((const char*)(gbase) + (voff)[_i]), (PG8_LAS unsigned*)(lds + (bufoff) + ldsw + _i * 8192), 16, 0, 0); } while (0)
; #define PG8_LDA(dst, b, h) do { _Pragma("unroll") for (int m = 0; m < 4; ++m) _Pragma("unroll") for (int k = 0; k < 2; ++k) dst[m][k] = *(const PG8_LAS bf16x8*)(lds + PG8_SA(b, h) + aoff + m * 2048 + k * 1024); } while (0)
; #define PG8_BAR __builtin_amdgcn_s_barrier()
; template <class Epi, class Sched, bool ALIGN_EPI = false, bool SP2 = false>
; __device__ __forceinline__ void gemm_phase(PG8_LAS unsigned char* lds, const Gemm g, const Sched& S, const Epi& E, const int wave_in) {
;     ...
;             PG8_LDA(At, 1, 1); PG8_STAGE(PG8_SB(1, 0), b3, voffB); PG8_STAGE(PG8_SB(1, 1), b3 + hstepB, voffB); PG8_STAGE(PG8_SA(1, 0), a3, voffA);
;             PG8_WAIT_V(8); PG8_WAIT_L(0); PG8_BAR; PG8_MMA(1, 0, At, B0); PG8_MMA(1, 1, At, B1); PG8_BAR; PG8_SCHED;
;             } else {
;             PG8_LDB(B0, 0, 0); PG8_SCHED; PG8_LDA(At, 0, 0); PG8_STAGE(PG8_SA(1, 1), a1 + hstepA, voffA);
;             PG8_WAIT_L(8); PG8_BAR; PG8_WAIT_L(0); PG8_MMA(0, 0, At, B0); PG8_BAR; PG8_SCHED;
;             PG8_LDB(B1, 0, 1); PG8_STAGE(PG8_SB(0, 0), b2, voffB);
;             PG8_BAR; PG8_WAIT_L(0); PG8_MMA(0, 1, At, B1); PG8_BAR;
;             PG8_LDA(At, 0, 1); PG8_STAGE(PG8_SA(0, 0), a2, voffA);
;             PG8_BAR; PG8_WAIT_L(0); PG8_MMA(1, 0, At, B0); PG8_BAR; PG8_SCHED;
;             PG8_STAGE(PG8_SB(0, 1), b2 + hstepB, voffB);
;             PG8_WAIT_V(6); PG8_BAR; PG8_MMA(1, 1, At, B1); PG8_BAR;
;             PG8_LDB(B0, 1, 0); PG8_SCHED; PG8_LDA(At, 1, 0); PG8_STAGE(PG8_SA(0, 1), a2 + hstepA, voffA);
;             PG8_WAIT_L(8); PG8_BAR; PG8_WAIT_L(0); PG8_MMA(0, 0, At, B0); PG8_BAR; PG8_SCHED;
;             PG8_LDB(B1, 1, 1); PG8_STAGE(PG8_SB(1, 0), b3, voffB);
;             PG8_BAR; PG8_WAIT_L(0); PG8_MMA(0, 1, At, B1); PG8_BAR;
;             PG8_LDA(At, 1, 1); PG8_STAGE(PG8_SA(1, 0), a3, voffA);
;             PG8_BAR; PG8_WAIT_L(0); PG8_MMA(1, 0, At, B0); PG8_BAR; PG8_SCHED;
;             PG8_STAGE(PG8_SB(1, 1), b3 + hstepB, voffB);
;             PG8_WAIT_V(6); PG8_BAR; PG8_MMA(1, 1, At, B1); PG8_BAR;
;             }
;         }
;         if constexpr (ALIGN_EPI) { if (wr == 0) PG8_BAR; }
	s_setprio 1
	s_waitcnt lgkmcnt(0)
	v_mfma_f32_16x16x32_bf16 v[124:127], v[144:147], v[182:185], v[124:127]
	v_mfma_f32_16x16x32_bf16 v[120:123], v[158:161], v[182:185], v[120:123]
	v_mfma_f32_16x16x32_bf16 v[108:111], v[144:147], v[190:193], v[108:111]
	v_mfma_f32_16x16x32_bf16 v[104:107], v[158:161], v[190:193], v[104:107]
	v_mfma_f32_16x16x32_bf16 v[92:95], v[144:147], v[198:201], v[92:95]
	v_mfma_f32_16x16x32_bf16 v[88:91], v[158:161], v[198:201], v[88:91]
	v_mfma_f32_16x16x32_bf16 v[76:79], v[144:147], v[206:209], v[76:79]
	v_mfma_f32_16x16x32_bf16 v[72:75], v[158:161], v[206:209], v[72:75]
	v_mfma_f32_16x16x32_bf16 v[124:127], v[154:157], v[186:189], v[124:127]
	v_mfma_f32_16x16x32_bf16 v[120:123], v[162:165], v[186:189], v[120:123]
	v_mfma_f32_16x16x32_bf16 v[108:111], v[154:157], v[194:197], v[108:111]
	v_mfma_f32_16x16x32_bf16 v[104:107], v[162:165], v[194:197], v[104:107]
	v_mfma_f32_16x16x32_bf16 v[92:95], v[154:157], v[202:205], v[92:95]
	v_mfma_f32_16x16x32_bf16 v[88:91], v[162:165], v[202:205], v[88:91]
	v_mfma_f32_16x16x32_bf16 v[76:79], v[154:157], v[210:213], v[76:79]
	v_mfma_f32_16x16x32_bf16 v[72:75], v[162:165], v[210:213], v[72:75]
	s_setprio 0
	s_setprio 1
	v_mfma_f32_16x16x32_bf16 v[116:119], v[166:169], v[182:185], v[116:119]
	v_mfma_f32_16x16x32_bf16 v[112:115], v[174:177], v[182:185], v[112:115]
	v_mfma_f32_16x16x32_bf16 v[100:103], v[166:169], v[190:193], v[100:103]
	v_mfma_f32_16x16x32_bf16 v[96:99], v[174:177], v[190:193], v[96:99]
	v_mfma_f32_16x16x32_bf16 v[84:87], v[166:169], v[198:201], v[84:87]
	v_mfma_f32_16x16x32_bf16 v[80:83], v[174:177], v[198:201], v[80:83]
	v_mfma_f32_16x16x32_bf16 v[68:71], v[166:169], v[206:209], v[68:71]
	v_mfma_f32_16x16x32_bf16 v[64:67], v[174:177], v[206:209], v[64:67]
	v_mfma_f32_16x16x32_bf16 v[116:119], v[170:173], v[186:189], v[116:119]
	v_mfma_f32_16x16x32_bf16 v[112:115], v[178:181], v[186:189], v[112:115]
	v_mfma_f32_16x16x32_bf16 v[100:103], v[170:173], v[194:197], v[100:103]
	v_mfma_f32_16x16x32_bf16 v[96:99], v[178:181], v[194:197], v[96:99]
	v_mfma_f32_16x16x32_bf16 v[84:87], v[170:173], v[202:205], v[84:87]
	v_mfma_f32_16x16x32_bf16 v[80:83], v[178:181], v[202:205], v[80:83]
	v_mfma_f32_16x16x32_bf16 v[68:71], v[170:173], v[210:213], v[68:71]
	v_mfma_f32_16x16x32_bf16 v[64:67], v[178:181], v[210:213], v[64:67]
	s_setprio 0
	s_barrier
	s_add_i32 s26, s51, s34
	v_lshl_add_u64 v[214:215], v[214:215], 0, s[8:9]
	s_mov_b32 m0, s26
	ds_read_b128 v[182:185], v153 offset:49152
	ds_read_b128 v[186:189], v153 offset:50176
	ds_read_b128 v[190:193], v153 offset:51200
	ds_read_b128 v[194:197], v153 offset:52224
	ds_read_b128 v[198:201], v153 offset:53248
	ds_read_b128 v[202:205], v153 offset:54272
	ds_read_b128 v[206:209], v153 offset:55296
	ds_read_b128 v[210:213], v153 offset:56320
	global_load_lds_dwordx4 v[214:215], off
	s_add_i32 m0, s26, 0x2000
	s_add_u32 s24, s24, 0x80080
	v_lshl_add_u64 v[214:215], v[216:217], 0, s[8:9]
	s_addc_u32 s25, s25, 0
	s_add_i32 s26, s52, s34
	global_load_lds_dwordx4 v[214:215], off
	v_lshl_add_u64 v[214:215], s[24:25], 0, v[130:131]
	s_mov_b32 m0, s26
	s_nop 0
	global_load_lds_dwordx4 v[214:215], off
	v_lshl_add_u64 v[214:215], s[24:25], 0, v[134:135]
	s_add_i32 m0, s26, 0x2000
	s_nop 0
	global_load_lds_dwordx4 v[214:215], off
	v_lshl_add_u64 v[214:215], v[218:219], 0, s[8:9]
	s_mov_b32 m0, s39
	s_nop 0
	global_load_lds_dwordx4 v[214:215], off
	v_lshl_add_u64 v[214:215], v[220:221], 0, s[8:9]
	s_mov_b32 m0, s40
	s_nop 0
	global_load_lds_dwordx4 v[214:215], off
	s_waitcnt vmcnt(8)
	s_waitcnt lgkmcnt(0)
	s_barrier
	s_setprio 1
	s_waitcnt lgkmcnt(0)
	v_mfma_f32_16x16x32_bf16 v[60:63], v[144:147], v[182:185], v[60:63]
	v_mfma_f32_16x16x32_bf16 v[56:59], v[158:161], v[182:185], v[56:59]
	v_mfma_f32_16x16x32_bf16 v[44:47], v[144:147], v[190:193], v[44:47]
	v_mfma_f32_16x16x32_bf16 v[40:43], v[158:161], v[190:193], v[40:43]
	v_mfma_f32_16x16x32_bf16 v[28:31], v[144:147], v[198:201], v[28:31]
	v_mfma_f32_16x16x32_bf16 v[24:27], v[158:161], v[198:201], v[24:27]
	v_mfma_f32_16x16x32_bf16 v[12:15], v[144:147], v[206:209], v[12:15]
	v_mfma_f32_16x16x32_bf16 v[8:11], v[158:161], v[206:209], v[8:11]
	v_mfma_f32_16x16x32_bf16 v[60:63], v[154:157], v[186:189], v[60:63]
	v_mfma_f32_16x16x32_bf16 v[56:59], v[162:165], v[186:189], v[56:59]
	v_mfma_f32_16x16x32_bf16 v[44:47], v[154:157], v[194:197], v[44:47]
	v_mfma_f32_16x16x32_bf16 v[40:43], v[162:165], v[194:197], v[40:43]
	v_mfma_f32_16x16x32_bf16 v[28:31], v[154:157], v[202:205], v[28:31]
	v_mfma_f32_16x16x32_bf16 v[24:27], v[162:165], v[202:205], v[24:27]
	v_mfma_f32_16x16x32_bf16 v[12:15], v[154:157], v[210:213], v[12:15]
	v_mfma_f32_16x16x32_bf16 v[8:11], v[162:165], v[210:213], v[8:11]
	s_setprio 0
	s_setprio 1
	v_mfma_f32_16x16x32_bf16 v[52:55], v[166:169], v[182:185], v[52:55]
	v_mfma_f32_16x16x32_bf16 v[48:51], v[174:177], v[182:185], v[48:51]
	v_mfma_f32_16x16x32_bf16 v[36:39], v[166:169], v[190:193], v[36:39]
	v_mfma_f32_16x16x32_bf16 v[32:35], v[174:177], v[190:193], v[32:35]
	v_mfma_f32_16x16x32_bf16 v[20:23], v[166:169], v[198:201], v[20:23]
	v_mfma_f32_16x16x32_bf16 v[16:19], v[174:177], v[198:201], v[16:19]
	v_mfma_f32_16x16x32_bf16 v[4:7], v[166:169], v[206:209], v[4:7]
	v_mfma_f32_16x16x32_bf16 v[0:3], v[174:177], v[206:209], v[0:3]
	v_mfma_f32_16x16x32_bf16 v[52:55], v[170:173], v[186:189], v[52:55]
	v_mfma_f32_16x16x32_bf16 v[48:51], v[178:181], v[186:189], v[48:51]
	v_mfma_f32_16x16x32_bf16 v[36:39], v[170:173], v[194:197], v[36:39]
	v_mfma_f32_16x16x32_bf16 v[32:35], v[178:181], v[194:197], v[32:35]
	v_mfma_f32_16x16x32_bf16 v[20:23], v[170:173], v[202:205], v[20:23]
	v_mfma_f32_16x16x32_bf16 v[16:19], v[178:181], v[202:205], v[16:19]
	v_mfma_f32_16x16x32_bf16 v[4:7], v[170:173], v[210:213], v[4:7]
	v_mfma_f32_16x16x32_bf16 v[0:3], v[178:181], v[210:213], v[0:3]
	s_setprio 0
	s_barrier
	s_add_i32 s50, s50, 2
	s_add_u32 s22, s22, 0x100
	s_addc_u32 s23, s23, 0
	s_add_u32 s48, s48, 0x100
	s_addc_u32 s49, s49, 0
	s_cmp_gt_u32 s50, 29
	s_cbranch_scc0 .LBB0_2248
	s_mov_b32 s99, 1
	s_and_b64 vcc, exec, s[10:11]
	s_cbranch_vccz .LBB0_2251
	s_barrier

;     __host__ __device__ bool next(int i, Unit& u) const {
;         const long L = (long)i * G + c; if (L >= nwg) return false;
;         int wgid = (int)L; { const int q = nwg / NXCD, r = nwg % NXCD, xcd = wgid % NXCD, off = wgid / NXCD; wgid = (xcd < r ? xcd * (q + 1) : r * (q + 1) + (xcd - r) * q) + off; }
;         const int nig = WGM * nN, gid = wgid / nig, fm = gid * WGM, gsz = (nM - fm) < WGM ? (nM - fm) : WGM;
;         u.pm = fm + ((wgid % nig) % gsz); u.pn = (wgid % nig) / gsz; return true;
.LBB0_2431:
	s_cmp_gt_i32 s52, 28
	s_cselect_b64 s[0:1], -1, 0
	s_cmp_lt_i32 s53, 29
	s_cselect_b64 s[2:3], -1, 0
	s_or_b64 s[0:1], s[0:1], s[2:3]
	s_and_b64 vcc, exec, s[0:1]
	s_cbranch_vccnz .LBB0_2508
	s_mov_b32 s99, 0
	s_cmpk_gt_i32 s73, 0x3ff
	v_mbcnt_lo_u32_b32 v8, -1, 0
	v_mbcnt_hi_u32_b32 v8, -1, v8
	s_cbranch_scc1 .LBB0_2458
	s_ashr_i32 s34, s73, 31
	s_lshr_b32 s0, s34, 29
	s_add_i32 s3, s73, s0
	s_and_b32 s0, s3, -8
	s_sub_i32 s4, s73, s0
	s_cmp_gt_i32 s4, -1
	s_cbranch_scc0 .LBB0_2435
	s_lshl_b32 s2, s4, 7
	s_cbranch_execz .LBB0_2436
	s_branch .LBB0_2437

;     __host__ __device__ bool next(int i, Unit& u) const { const bool ok = StaticOrder::next(i, u); u.pm = 0; u.pn = 0; return ok; }
; #define PG8_STAGE(bufoff, gbase, voff) do { _Pragma("unroll") for (int _i = 0; _i < 2; ++_i) \
;         __builtin_amdgcn_global_load_lds((const unsigned*)((const char*)(gbase) + (voff)[_i]), (PG8_LAS unsigned*)(lds + (bufoff) + ldsw + _i * 8192), 16, 0, 0); } while (0)
; #define PG8_LDA(dst, b, h) do { _Pragma("unroll") for (int m = 0; m < 4; ++m) _Pragma("unroll") for (int k = 0; k < 2; ++k) dst[m][k] = *(const PG8_LAS bf16x8*)(lds + PG8_SA(b, h) + aoff + m * 2048 + k * 1024); } while (0)
; #define PG8_LDB(dst, b, h) do { _Pragma("unroll") for (int n = 0; n < 2; ++n) _Pragma("unroll") for (int k = 0; k < 2; ++k) dst[n][k] = *(const PG8_LAS bf16x8*)(lds + PG8_SB(b, h) + boff + n * 2048 + k * 1024); } while (0)
; #define PG8_WAIT_V(n) asm volatile("s_waitcnt vmcnt(" #n ")" ::: "memory")
; template <class Epi, class Sched, bool ALIGN_EPI = false, bool SP2 = false>
; __device__ __forceinline__ void gemm_phase(PG8_LAS unsigned char* lds, const Gemm g, const Sched& S, const Epi& E, const int wave_in) {
;     ...
;         const bool has_next = S.next(ui + 1, nxt);
;         const char* nA = has_next ? (const char*)g.A + (size_t)nxt.pm * tstepA : cA; const char* nB = has_next ? (const char*)g.Bt + (size_t)nxt.pn * tstepB : cB;
;         for (int t = 0; t < nt; t += 2) {
;             const bool last = (t == nt - 2);
;             const char* a1 = cA + (size_t)(t + 1) * kstep;
;             const char* a2 = last ? nA : cA + (size_t)(t + 2) * kstep; const char* b2 = last ? nB : cB + (size_t)(t + 2) * kstep;
;             const char* a3 = a2 + kstep; const char* b3 = b2 + kstep;
;             if (last && has_next) S.a_ready(nxt);
;             if constexpr (SP2) {
;             PG8_LDB(B0, 0, 0); PG8_LDB(B1, 0, 1); PG8_SCHED; PG8_LDA(At, 0, 0); PG8_STAGE(PG8_SA(1, 1), a1 + hstepA, voffA);
;             PG8_WAIT_V(8); PG8_WAIT_L(0); PG8_BAR; PG8_MMA(0, 0, At, B0); PG8_MMA(0, 1, At, B1); PG8_BAR; PG8_SCHED;
;     ...
; #pragma unroll
;         for (int a = 0; a < 2; ++a)
; #pragma unroll
;             for (int b = 0; b < 2; ++b)
; #pragma unroll
;                 for (int m = 0; m < 4; ++m)
; #pragma unroll
;                     for (int n = 0; n < 2; ++n) acc[a][b][m][n] = (f32x4){0.f, 0.f, 0.f, 0.f};
;         cur = nxt; cA = nA; cB = nB; ++ui;
.LBB0_2450:
	s_ashr_i32 s19, s18, 31
	s_lshl_b64 s[22:23], s[18:19], 20
	s_add_u32 s22, s37, s22
	s_addc_u32 s23, s38, s23
	s_and_b64 s[4:5], s[4:5], exec
	s_cselect_b32 s19, s23, s29
	s_cselect_b32 s25, s22, s28
	s_add_u32 s58, s28, 0x100
	v_mov_b32_e32 v0, 0
	s_addc_u32 s59, s29, 0
	s_mov_b32 s60, -2
	v_mov_b32_e32 v1, v0
	v_mov_b32_e32 v2, v0
	v_mov_b32_e32 v3, v0
	v_mov_b32_e32 v4, v0
	v_mov_b32_e32 v5, v0
	v_mov_b32_e32 v6, v0
	v_mov_b32_e32 v7, v0
	v_mov_b32_e32 v12, v0
	v_mov_b32_e32 v13, v0
	v_mov_b32_e32 v14, v0
	v_mov_b32_e32 v15, v0
	v_mov_b32_e32 v20, v0
	v_mov_b32_e32 v21, v0
	v_mov_b32_e32 v22, v0
	v_mov_b32_e32 v23, v0
	v_mov_b32_e32 v28, v0
	v_mov_b32_e32 v29, v0
	v_mov_b32_e32 v30, v0
	v_mov_b32_e32 v31, v0
	v_mov_b32_e32 v36, v0
	v_mov_b32_e32 v37, v0
	v_mov_b32_e32 v38, v0
	v_mov_b32_e32 v39, v0
	v_mov_b32_e32 v44, v0
	v_mov_b32_e32 v45, v0
	v_mov_b32_e32 v46, v0
	v_mov_b32_e32 v47, v0
	v_mov_b32_e32 v52, v0
	v_mov_b32_e32 v53, v0
	v_mov_b32_e32 v54, v0
	v_mov_b32_e32 v55, v0
	v_mov_b32_e32 v8, v0
	v_mov_b32_e32 v9, v0
	v_mov_b32_e32 v10, v0
	v_mov_b32_e32 v11, v0
	v_mov_b32_e32 v16, v0
	v_mov_b32_e32 v17, v0
	v_mov_b32_e32 v18, v0
	v_mov_b32_e32 v19, v0
	v_mov_b32_e32 v24, v0
	v_mov_b32_e32 v25, v0
	v_mov_b32_e32 v26, v0
	v_mov_b32_e32 v27, v0
	v_mov_b32_e32 v32, v0
	v_mov_b32_e32 v33, v0
	v_mov_b32_e32 v34, v0
	v_mov_b32_e32 v35, v0
	v_mov_b32_e32 v40, v0
	v_mov_b32_e32 v41, v0
	v_mov_b32_e32 v42, v0
	v_mov_b32_e32 v43, v0
	v_mov_b32_e32 v48, v0
	v_mov_b32_e32 v49, v0
	v_mov_b32_e32 v50, v0
	v_mov_b32_e32 v51, v0
	v_mov_b32_e32 v56, v0
	v_mov_b32_e32 v57, v0
	v_mov_b32_e32 v58, v0
	v_mov_b32_e32 v59, v0
	v_mov_b32_e32 v60, v0
	v_mov_b32_e32 v61, v0
	v_mov_b32_e32 v62, v0
	v_mov_b32_e32 v63, v0
	v_mov_b32_e32 v64, v0
	v_mov_b32_e32 v65, v0
	v_mov_b32_e32 v66, v0
	v_mov_b32_e32 v67, v0
	v_mov_b32_e32 v68, v0
	v_mov_b32_e32 v69, v0
	v_mov_b32_e32 v70, v0
	v_mov_b32_e32 v71, v0
	v_mov_b32_e32 v76, v0
	v_mov_b32_e32 v77, v0
	v_mov_b32_e32 v78, v0
	v_mov_b32_e32 v79, v0
	v_mov_b32_e32 v84, v0
	v_mov_b32_e32 v85, v0
	v_mov_b32_e32 v86, v0
	v_mov_b32_e32 v87, v0
	v_mov_b32_e32 v92, v0
	v_mov_b32_e32 v93, v0
	v_mov_b32_e32 v94, v0
	v_mov_b32_e32 v95, v0
	v_mov_b32_e32 v100, v0
	v_mov_b32_e32 v101, v0
	v_mov_b32_e32 v102, v0
	v_mov_b32_e32 v103, v0
	v_mov_b32_e32 v108, v0
	v_mov_b32_e32 v109, v0
	v_mov_b32_e32 v110, v0
	v_mov_b32_e32 v111, v0
	s_waitcnt vmcnt(0)
	v_mov_b32_e32 v116, v0
	v_mov_b32_e32 v117, v0
	v_mov_b32_e32 v118, v0
	v_mov_b32_e32 v119, v0
	v_mov_b32_e32 v72, v0
	v_mov_b32_e32 v73, v0
	v_mov_b32_e32 v74, v0
	v_mov_b32_e32 v75, v0
	v_mov_b32_e32 v80, v0
	v_mov_b32_e32 v81, v0
	v_mov_b32_e32 v82, v0
	v_mov_b32_e32 v83, v0
	v_mov_b32_e32 v88, v0
	v_mov_b32_e32 v89, v0
	v_mov_b32_e32 v90, v0
	v_mov_b32_e32 v91, v0
	v_mov_b32_e32 v96, v0
	v_mov_b32_e32 v97, v0
	v_mov_b32_e32 v98, v0
	v_mov_b32_e32 v99, v0
	v_mov_b32_e32 v104, v0
	v_mov_b32_e32 v105, v0
	v_mov_b32_e32 v106, v0
	v_mov_b32_e32 v107, v0
	v_mov_b32_e32 v112, v0
	v_mov_b32_e32 v113, v0
	v_mov_b32_e32 v114, v0
	v_mov_b32_e32 v115, v0
	v_mov_b32_e32 v120, v0
	v_mov_b32_e32 v121, v0
	v_mov_b32_e32 v122, v0
	v_mov_b32_e32 v123, v0
	v_mov_b32_e32 v124, v0
	v_mov_b32_e32 v125, v0
	v_mov_b32_e32 v126, v0
	v_mov_b32_e32 v127, v0
	s_cmp_lg_u32 s99, 0
	s_cbranch_scc0 .LBB0_2451
	ds_read_b128 v[128:131], v170
	ds_read_b128 v[132:135], v170 offset:1024
	ds_read_b128 v[136:139], v170 offset:2048
	ds_read_b128 v[140:143], v170 offset:3072
	ds_read_b128 v[162:165], v171
	ds_read_b128 v[174:177], v171 offset:1024
	ds_read_b128 v[178:181], v171 offset:2048
	ds_read_b128 v[182:185], v171 offset:3072
	s_add_u32 s4, s26, 0x100
	s_addc_u32 s5, s27, 0
	s_cmp_eq_u32 s60, 28
	s_cselect_b32 s31, s21, s5
	s_cselect_b32 s30, s20, s4
	s_cselect_b32 s29, s19, s59
	s_cselect_b32 s28, s25, s58
	v_lshl_add_u64 v[166:167], s[26:27], 0, v[154:155]
	s_add_i32 m0, s40, 0xc000
	ds_read_b128 v[186:189], v172
	ds_read_b128 v[190:193], v172 offset:1024
	ds_read_b128 v[194:197], v172 offset:2048
	ds_read_b128 v[198:201], v172 offset:3072
	ds_read_b128 v[202:205], v172 offset:4096
	ds_read_b128 v[206:209], v172 offset:5120
	ds_read_b128 v[210:213], v172 offset:6144
	ds_read_b128 v[214:217], v172 offset:7168
	global_load_lds_dwordx4 v[166:167], off
	v_lshl_add_u64 v[166:167], s[26:27], 0, v[156:157]
	s_add_i32 m0, s40, 0xe000
	s_nop 0
	global_load_lds_dwordx4 v[166:167], off
	s_waitcnt vmcnt(24)
	s_waitcnt lgkmcnt(0)
	s_barrier
	s_setprio 1
	s_waitcnt lgkmcnt(0)
	v_mfma_f32_16x16x32_bf16 v[124:127], v[128:131], v[186:189], v[124:127]
	v_mfma_f32_16x16x32_bf16 v[120:123], v[136:139], v[186:189], v[120:123]
	v_mfma_f32_16x16x32_bf16 v[112:115], v[128:131], v[194:197], v[112:115]
	v_mfma_f32_16x16x32_bf16 v[104:107], v[136:139], v[194:197], v[104:107]
	v_mfma_f32_16x16x32_bf16 v[96:99], v[128:131], v[202:205], v[96:99]
	v_mfma_f32_16x16x32_bf16 v[88:91], v[136:139], v[202:205], v[88:91]
	v_mfma_f32_16x16x32_bf16 v[80:83], v[128:131], v[210:213], v[80:83]
	v_mfma_f32_16x16x32_bf16 v[72:75], v[136:139], v[210:213], v[72:75]
	v_mfma_f32_16x16x32_bf16 v[124:127], v[132:135], v[190:193], v[124:127]
	v_mfma_f32_16x16x32_bf16 v[120:123], v[140:143], v[190:193], v[120:123]
	v_mfma_f32_16x16x32_bf16 v[112:115], v[132:135], v[198:201], v[112:115]
	v_mfma_f32_16x16x32_bf16 v[104:107], v[140:143], v[198:201], v[104:107]
	v_mfma_f32_16x16x32_bf16 v[96:99], v[132:135], v[206:209], v[96:99]
	v_mfma_f32_16x16x32_bf16 v[88:91], v[140:143], v[206:209], v[88:91]
	v_mfma_f32_16x16x32_bf16 v[80:83], v[132:135], v[214:217], v[80:83]
	v_mfma_f32_16x16x32_bf16 v[72:75], v[140:143], v[214:217], v[72:75]
	s_setprio 0
	s_setprio 1
	v_mfma_f32_16x16x32_bf16 v[116:119], v[162:165], v[186:189], v[116:119]
	v_mfma_f32_16x16x32_bf16 v[108:111], v[178:181], v[186:189], v[108:111]
	v_mfma_f32_16x16x32_bf16 v[100:103], v[162:165], v[194:197], v[100:103]
	v_mfma_f32_16x16x32_bf16 v[92:95], v[178:181], v[194:197], v[92:95]
	v_mfma_f32_16x16x32_bf16 v[84:87], v[162:165], v[202:205], v[84:87]
	v_mfma_f32_16x16x32_bf16 v[76:79], v[178:181], v[202:205], v[76:79]
	v_mfma_f32_16x16x32_bf16 v[68:71], v[162:165], v[210:213], v[68:71]
	v_mfma_f32_16x16x32_bf16 v[64:67], v[178:181], v[210:213], v[64:67]
	v_mfma_f32_16x16x32_bf16 v[116:119], v[174:177], v[190:193], v[116:119]
	v_mfma_f32_16x16x32_bf16 v[108:111], v[182:185], v[190:193], v[108:111]
	v_mfma_f32_16x16x32_bf16 v[100:103], v[174:177], v[198:201], v[100:103]
	v_mfma_f32_16x16x32_bf16 v[92:95], v[182:185], v[198:201], v[92:95]
	v_mfma_f32_16x16x32_bf16 v[84:87], v[174:177], v[206:209], v[84:87]
	v_mfma_f32_16x16x32_bf16 v[76:79], v[182:185], v[206:209], v[76:79]
	v_mfma_f32_16x16x32_bf16 v[68:71], v[174:177], v[214:217], v[68:71]
	v_mfma_f32_16x16x32_bf16 v[64:67], v[182:185], v[214:217], v[64:67]
	s_setprio 0
	s_barrier
; #define PG8_STAGE(bufoff, gbase, voff) do { _Pragma("unroll") for (int _i = 0; _i < 2; ++_i) \
;         __builtin_amdgcn_global_load_lds((const unsigned*)((const char*)(gbase) + (voff)[_i]), (PG8_LAS unsigned*)(lds + (bufoff) + ldsw + _i * 8192), 16, 0, 0); } while (0)
; #define PG8_LDA(dst, b, h) do { _Pragma("unroll") for (int m = 0; m < 4; ++m) _Pragma("unroll") for (int k = 0; k < 2; ++k) dst[m][k] = *(const PG8_LAS bf16x8*)(lds + PG8_SA(b, h) + aoff + m * 2048 + k * 1024); } while (0)
; #define PG8_LDB(dst, b, h) do { _Pragma("unroll") for (int n = 0; n < 2; ++n) _Pragma("unroll") for (int k = 0; k < 2; ++k) dst[n][k] = *(const PG8_LAS bf16x8*)(lds + PG8_SB(b, h) + boff + n * 2048 + k * 1024); } while (0)
; #define PG8_MMA(ai, bj, At, Bt) do { __builtin_amdgcn_s_setprio(1); _Pragma("unroll") for (int m = 0; m < 4; ++m) _Pragma("unroll") for (int n = 0; n < 2; ++n) _Pragma("unroll") for (int k = 0; k < 2; ++k) \
;         acc[ai][bj][m][n] = __builtin_amdgcn_mfma_f32_16x16x32_bf16(Bt[n][k], At[m][k], acc[ai][bj][m][n], 0, 0, 0); __builtin_amdgcn_s_setprio(0); } while (0)
; #define PG8_WAIT_V(n) asm volatile("s_waitcnt vmcnt(" #n ")" ::: "memory")
; #define PG8_WAIT_L(n) asm volatile("s_waitcnt lgkmcnt(" #n ")" ::: "memory")
; #define PG8_BAR __builtin_amdgcn_s_barrier()
; #define PG8_SCHED __builtin_amdgcn_sched_barrier(0)
; template <class Epi, class Sched, bool ALIGN_EPI = false, bool SP2 = false>
; __device__ __forceinline__ void gemm_phase(PG8_LAS unsigned char* lds, const Gemm g, const Sched& S, const Epi& E, const int wave_in) {
;     ...
;             PG8_LDA(At, 0, 1); PG8_STAGE(PG8_SB(0, 0), b2, voffB); PG8_STAGE(PG8_SB(0, 1), b2 + hstepB, voffB); PG8_STAGE(PG8_SA(0, 0), a2, voffA);
;             PG8_WAIT_V(8); PG8_WAIT_L(0); PG8_BAR; PG8_MMA(1, 0, At, B0); PG8_MMA(1, 1, At, B1); PG8_BAR; PG8_SCHED;
;             PG8_LDB(B0, 1, 0); PG8_LDB(B1, 1, 1); PG8_SCHED; PG8_LDA(At, 1, 0); PG8_STAGE(PG8_SA(0, 1), a2 + hstepA, voffA);
;             PG8_WAIT_V(8); PG8_WAIT_L(0); PG8_BAR; PG8_MMA(0, 0, At, B0); PG8_MMA(0, 1, At, B1); PG8_BAR; PG8_SCHED;
	s_add_i32 s26, s50, s39
	v_lshl_add_u64 v[166:167], s[28:29], 0, v[146:147]
	s_mov_b32 m0, s26
	ds_read_b128 v[186:189], v172 offset:16384
	ds_read_b128 v[190:193], v172 offset:17408
	ds_read_b128 v[194:197], v172 offset:18432
	ds_read_b128 v[198:201], v172 offset:19456
	ds_read_b128 v[202:205], v172 offset:20480
	ds_read_b128 v[206:209], v172 offset:21504
	ds_read_b128 v[210:213], v172 offset:22528
	ds_read_b128 v[214:217], v172 offset:23552
	global_load_lds_dwordx4 v[166:167], off
	s_add_i32 m0, s26, 0x2000
	s_add_u32 s26, s28, 0x80000
	v_lshl_add_u64 v[218:219], s[28:29], 0, v[150:151]
	s_addc_u32 s27, s29, 0
	s_add_i32 s61, s51, s39
	global_load_lds_dwordx4 v[218:219], off
	v_lshl_add_u64 v[220:221], s[26:27], 0, v[146:147]
	s_mov_b32 m0, s61
	v_lshl_add_u64 v[222:223], s[30:31], 0, v[148:149]
	global_load_lds_dwordx4 v[220:221], off
	v_lshl_add_u64 v[220:221], s[26:27], 0, v[150:151]
	s_add_i32 m0, s61, 0x2000
	s_nop 0
	global_load_lds_dwordx4 v[220:221], off
	v_lshl_add_u64 v[220:221], s[30:31], 0, v[144:145]
	s_mov_b32 m0, s40
	s_nop 0
	global_load_lds_dwordx4 v[220:221], off
	s_mov_b32 m0, s41
	s_nop 0
	global_load_lds_dwordx4 v[222:223], off
	s_waitcnt vmcnt(24)
	s_waitcnt lgkmcnt(0)
	s_barrier
	s_setprio 1
	s_waitcnt lgkmcnt(0)
	v_mfma_f32_16x16x32_bf16 v[60:63], v[128:131], v[186:189], v[60:63]
	v_mfma_f32_16x16x32_bf16 v[56:59], v[136:139], v[186:189], v[56:59]
	v_mfma_f32_16x16x32_bf16 v[48:51], v[128:131], v[194:197], v[48:51]
	v_mfma_f32_16x16x32_bf16 v[40:43], v[136:139], v[194:197], v[40:43]
	v_mfma_f32_16x16x32_bf16 v[32:35], v[128:131], v[202:205], v[32:35]
	v_mfma_f32_16x16x32_bf16 v[24:27], v[136:139], v[202:205], v[24:27]
	v_mfma_f32_16x16x32_bf16 v[16:19], v[128:131], v[210:213], v[16:19]
	v_mfma_f32_16x16x32_bf16 v[8:11], v[136:139], v[210:213], v[8:11]
	v_mfma_f32_16x16x32_bf16 v[60:63], v[132:135], v[190:193], v[60:63]
	v_mfma_f32_16x16x32_bf16 v[56:59], v[140:143], v[190:193], v[56:59]
	v_mfma_f32_16x16x32_bf16 v[48:51], v[132:135], v[198:201], v[48:51]
	v_mfma_f32_16x16x32_bf16 v[40:43], v[140:143], v[198:201], v[40:43]
	v_mfma_f32_16x16x32_bf16 v[32:35], v[132:135], v[206:209], v[32:35]
	v_mfma_f32_16x16x32_bf16 v[24:27], v[140:143], v[206:209], v[24:27]
	v_mfma_f32_16x16x32_bf16 v[16:19], v[132:135], v[214:217], v[16:19]
	v_mfma_f32_16x16x32_bf16 v[8:11], v[140:143], v[214:217], v[8:11]
	s_setprio 0
	s_setprio 1
	v_mfma_f32_16x16x32_bf16 v[52:55], v[162:165], v[186:189], v[52:55]
	v_mfma_f32_16x16x32_bf16 v[44:47], v[178:181], v[186:189], v[44:47]
	v_mfma_f32_16x16x32_bf16 v[36:39], v[162:165], v[194:197], v[36:39]
	v_mfma_f32_16x16x32_bf16 v[28:31], v[178:181], v[194:197], v[28:31]
	v_mfma_f32_16x16x32_bf16 v[20:23], v[162:165], v[202:205], v[20:23]
	v_mfma_f32_16x16x32_bf16 v[12:15], v[178:181], v[202:205], v[12:15]
	v_mfma_f32_16x16x32_bf16 v[4:7], v[162:165], v[210:213], v[4:7]
	v_mfma_f32_16x16x32_bf16 v[0:3], v[178:181], v[210:213], v[0:3]
	v_mfma_f32_16x16x32_bf16 v[52:55], v[174:177], v[190:193], v[52:55]
	v_mfma_f32_16x16x32_bf16 v[44:47], v[182:185], v[190:193], v[44:47]
	v_mfma_f32_16x16x32_bf16 v[36:39], v[174:177], v[198:201], v[36:39]
	v_mfma_f32_16x16x32_bf16 v[28:31], v[182:185], v[198:201], v[28:31]
	v_mfma_f32_16x16x32_bf16 v[20:23], v[174:177], v[206:209], v[20:23]
	v_mfma_f32_16x16x32_bf16 v[12:15], v[182:185], v[206:209], v[12:15]
	v_mfma_f32_16x16x32_bf16 v[4:7], v[174:177], v[214:217], v[4:7]
	v_mfma_f32_16x16x32_bf16 v[0:3], v[182:185], v[214:217], v[0:3]
	s_setprio 0
	s_barrier
	s_add_i32 s61, 0, 0x18000
	s_add_i32 s62, 0, 0x1c000
	v_add_u32_e32 v140, s61, v168
	v_add_u32_e32 v173, s62, v168
	ds_read_b128 v[128:131], v140
	ds_read_b128 v[132:135], v140 offset:1024
	ds_read_b128 v[136:139], v140 offset:2048
	ds_read_b128 v[140:143], v140 offset:3072
	ds_read_b128 v[162:165], v173
	ds_read_b128 v[174:177], v173 offset:1024
	ds_read_b128 v[178:181], v173 offset:2048
	ds_read_b128 v[182:185], v173 offset:3072
	s_add_u32 s26, s30, 0x280000
	s_addc_u32 s27, s31, 0
	s_mov_b32 m0, s42
	v_lshl_add_u64 v[224:225], s[26:27], 0, v[144:145]
	ds_read_b128 v[186:189], v172 offset:32768
	ds_read_b128 v[190:193], v172 offset:33792
	ds_read_b128 v[194:197], v172 offset:34816
	ds_read_b128 v[198:201], v172 offset:35840
	ds_read_b128 v[202:205], v172 offset:36864
	ds_read_b128 v[206:209], v172 offset:37888
	ds_read_b128 v[210:213], v172 offset:38912
	ds_read_b128 v[214:217], v172 offset:39936
	global_load_lds_dwordx4 v[224:225], off
	v_lshl_add_u64 v[224:225], s[26:27], 0, v[148:149]
	s_mov_b32 m0, s43
	s_nop 0
	global_load_lds_dwordx4 v[224:225], off
	s_waitcnt vmcnt(8)
	s_waitcnt lgkmcnt(0)
	s_barrier
; #define PG8_STAGE(bufoff, gbase, voff) do { _Pragma("unroll") for (int _i = 0; _i < 2; ++_i) \
;         __builtin_amdgcn_global_load_lds((const unsigned*)((const char*)(gbase) + (voff)[_i]), (PG8_LAS unsigned*)(lds + (bufoff) + ldsw + _i * 8192), 16, 0, 0); } while (0)
; #define PG8_LDA(dst, b, h) do { _Pragma("unroll") for (int m = 0; m < 4; ++m) _Pragma("unroll") for (int k = 0; k < 2; ++k) dst[m][k] = *(const PG8_LAS bf16x8*)(lds + PG8_SA(b, h) + aoff + m * 2048 + k * 1024); } while (0)
; #define PG8_WAIT_V(n) asm volatile("s_waitcnt vmcnt(" #n ")" ::: "memory")
; #define PG8_WAIT_L(n) asm volatile("s_waitcnt lgkmcnt(" #n ")" ::: "memory")
; #define PG8_BAR __builtin_amdgcn_s_barrier()
; template <class Epi, class Sched, bool ALIGN_EPI = false, bool SP2 = false>
; __device__ __forceinline__ void gemm_phase(PG8_LAS unsigned char* lds, const Gemm g, const Sched& S, const Epi& E, const int wave_in) {
;     ...
;         for (int t = 0; t < nt; t += 2) {
;             const bool last = (t == nt - 2);
;             const char* a1 = cA + (size_t)(t + 1) * kstep;
;             const char* a2 = last ? nA : cA + (size_t)(t + 2) * kstep; const char* b2 = last ? nB : cB + (size_t)(t + 2) * kstep;
;             const char* a3 = a2 + kstep; const char* b3 = b2 + kstep;
;             if (last && has_next) S.a_ready(nxt);
;             if constexpr (SP2) {
;             PG8_LDB(B0, 0, 0); PG8_LDB(B1, 0, 1); PG8_SCHED; PG8_LDA(At, 0, 0); PG8_STAGE(PG8_SA(1, 1), a1 + hstepA, voffA);
;             PG8_WAIT_V(8); PG8_WAIT_L(0); PG8_BAR; PG8_MMA(0, 0, At, B0); PG8_MMA(0, 1, At, B1); PG8_BAR; PG8_SCHED;
;             PG8_LDA(At, 0, 1); PG8_STAGE(PG8_SB(0, 0), b2, voffB); PG8_STAGE(PG8_SB(0, 1), b2 + hstepB, voffB); PG8_STAGE(PG8_SA(0, 0), a2, voffA);
;             PG8_WAIT_V(8); PG8_WAIT_L(0); PG8_BAR; PG8_MMA(1, 0, At, B0); PG8_MMA(1, 1, At, B1); PG8_BAR; PG8_SCHED;
;             PG8_LDB(B0, 1, 0); PG8_LDB(B1, 1, 1); PG8_SCHED; PG8_LDA(At, 1, 0); PG8_STAGE(PG8_SA(0, 1), a2 + hstepA, voffA);
;             PG8_WAIT_V(8); PG8_WAIT_L(0); PG8_BAR; PG8_MMA(0, 0, At, B0); PG8_MMA(0, 1, At, B1); PG8_BAR; PG8_SCHED;
;             PG8_LDA(At, 1, 1); PG8_STAGE(PG8_SB(1, 0), b3, voffB); PG8_STAGE(PG8_SB(1, 1), b3 + hstepB, voffB); PG8_STAGE(PG8_SA(1, 0), a3, voffA);
;             PG8_WAIT_V(8); PG8_WAIT_L(0); PG8_BAR; PG8_MMA(1, 0, At, B0); PG8_MMA(1, 1, At, B1); PG8_BAR; PG8_SCHED;
	s_setprio 1
	s_waitcnt lgkmcnt(0)
	v_mfma_f32_16x16x32_bf16 v[124:127], v[128:131], v[186:189], v[124:127]
	v_mfma_f32_16x16x32_bf16 v[120:123], v[136:139], v[186:189], v[120:123]
	v_mfma_f32_16x16x32_bf16 v[112:115], v[128:131], v[194:197], v[112:115]
	v_mfma_f32_16x16x32_bf16 v[104:107], v[136:139], v[194:197], v[104:107]
	v_mfma_f32_16x16x32_bf16 v[96:99], v[128:131], v[202:205], v[96:99]
	v_mfma_f32_16x16x32_bf16 v[88:91], v[136:139], v[202:205], v[88:91]
	v_mfma_f32_16x16x32_bf16 v[80:83], v[128:131], v[210:213], v[80:83]
	v_mfma_f32_16x16x32_bf16 v[72:75], v[136:139], v[210:213], v[72:75]
	v_mfma_f32_16x16x32_bf16 v[124:127], v[132:135], v[190:193], v[124:127]
	v_mfma_f32_16x16x32_bf16 v[120:123], v[140:143], v[190:193], v[120:123]
	v_mfma_f32_16x16x32_bf16 v[112:115], v[132:135], v[198:201], v[112:115]
	v_mfma_f32_16x16x32_bf16 v[104:107], v[140:143], v[198:201], v[104:107]
	v_mfma_f32_16x16x32_bf16 v[96:99], v[132:135], v[206:209], v[96:99]
	v_mfma_f32_16x16x32_bf16 v[88:91], v[140:143], v[206:209], v[88:91]
	v_mfma_f32_16x16x32_bf16 v[80:83], v[132:135], v[214:217], v[80:83]
	v_mfma_f32_16x16x32_bf16 v[72:75], v[140:143], v[214:217], v[72:75]
	s_setprio 0
	s_setprio 1
	v_mfma_f32_16x16x32_bf16 v[116:119], v[162:165], v[186:189], v[116:119]
	v_mfma_f32_16x16x32_bf16 v[108:111], v[178:181], v[186:189], v[108:111]
	v_mfma_f32_16x16x32_bf16 v[100:103], v[162:165], v[194:197], v[100:103]
	v_mfma_f32_16x16x32_bf16 v[92:95], v[178:181], v[194:197], v[92:95]
	v_mfma_f32_16x16x32_bf16 v[84:87], v[162:165], v[202:205], v[84:87]
	v_mfma_f32_16x16x32_bf16 v[76:79], v[178:181], v[202:205], v[76:79]
	v_mfma_f32_16x16x32_bf16 v[68:71], v[162:165], v[210:213], v[68:71]
	v_mfma_f32_16x16x32_bf16 v[64:67], v[178:181], v[210:213], v[64:67]
	v_mfma_f32_16x16x32_bf16 v[116:119], v[174:177], v[190:193], v[116:119]
	v_mfma_f32_16x16x32_bf16 v[108:111], v[182:185], v[190:193], v[108:111]
	v_mfma_f32_16x16x32_bf16 v[100:103], v[174:177], v[198:201], v[100:103]
	v_mfma_f32_16x16x32_bf16 v[92:95], v[182:185], v[198:201], v[92:95]
	v_mfma_f32_16x16x32_bf16 v[84:87], v[174:177], v[206:209], v[84:87]
	v_mfma_f32_16x16x32_bf16 v[76:79], v[182:185], v[206:209], v[76:79]
	v_mfma_f32_16x16x32_bf16 v[68:71], v[174:177], v[214:217], v[68:71]
	v_mfma_f32_16x16x32_bf16 v[64:67], v[182:185], v[214:217], v[64:67]
	s_setprio 0
	s_barrier
	s_add_i32 s26, s61, s39
	v_lshl_add_u64 v[166:167], v[166:167], 0, s[8:9]
	s_mov_b32 m0, s26
	ds_read_b128 v[186:189], v172 offset:49152
	ds_read_b128 v[190:193], v172 offset:50176
	ds_read_b128 v[194:197], v172 offset:51200
	ds_read_b128 v[198:201], v172 offset:52224
	ds_read_b128 v[202:205], v172 offset:53248
	ds_read_b128 v[206:209], v172 offset:54272
	ds_read_b128 v[210:213], v172 offset:55296
	ds_read_b128 v[214:217], v172 offset:56320
	global_load_lds_dwordx4 v[166:167], off
	s_add_i32 m0, s26, 0x2000
	s_add_u32 s26, s28, 0x80080
	v_lshl_add_u64 v[166:167], v[218:219], 0, s[8:9]
	s_addc_u32 s27, s29, 0
	s_add_i32 s28, s62, s39
	global_load_lds_dwordx4 v[166:167], off
	v_lshl_add_u64 v[166:167], s[26:27], 0, v[146:147]
	s_mov_b32 m0, s28
	s_nop 0
	global_load_lds_dwordx4 v[166:167], off
	v_lshl_add_u64 v[166:167], s[26:27], 0, v[150:151]
	s_add_i32 m0, s28, 0x2000
	s_nop 0
	global_load_lds_dwordx4 v[166:167], off
	v_lshl_add_u64 v[166:167], v[220:221], 0, s[8:9]
	s_mov_b32 m0, s47
	s_nop 0
	global_load_lds_dwordx4 v[166:167], off
	v_lshl_add_u64 v[166:167], v[222:223], 0, s[8:9]
	s_mov_b32 m0, s48
	s_nop 0
	global_load_lds_dwordx4 v[166:167], off
	s_waitcnt vmcnt(8)
	s_waitcnt lgkmcnt(0)
	s_barrier
	s_setprio 1
	s_waitcnt lgkmcnt(0)
	v_mfma_f32_16x16x32_bf16 v[60:63], v[128:131], v[186:189], v[60:63]
	v_mfma_f32_16x16x32_bf16 v[56:59], v[136:139], v[186:189], v[56:59]
	v_mfma_f32_16x16x32_bf16 v[48:51], v[128:131], v[194:197], v[48:51]
	v_mfma_f32_16x16x32_bf16 v[40:43], v[136:139], v[194:197], v[40:43]
	v_mfma_f32_16x16x32_bf16 v[32:35], v[128:131], v[202:205], v[32:35]
	v_mfma_f32_16x16x32_bf16 v[24:27], v[136:139], v[202:205], v[24:27]
	v_mfma_f32_16x16x32_bf16 v[16:19], v[128:131], v[210:213], v[16:19]
	v_mfma_f32_16x16x32_bf16 v[8:11], v[136:139], v[210:213], v[8:11]
	v_mfma_f32_16x16x32_bf16 v[60:63], v[132:135], v[190:193], v[60:63]
	v_mfma_f32_16x16x32_bf16 v[56:59], v[140:143], v[190:193], v[56:59]
	v_mfma_f32_16x16x32_bf16 v[48:51], v[132:135], v[198:201], v[48:51]
	v_mfma_f32_16x16x32_bf16 v[40:43], v[140:143], v[198:201], v[40:43]
	v_mfma_f32_16x16x32_bf16 v[32:35], v[132:135], v[206:209], v[32:35]
	v_mfma_f32_16x16x32_bf16 v[24:27], v[140:143], v[206:209], v[24:27]
	v_mfma_f32_16x16x32_bf16 v[16:19], v[132:135], v[214:217], v[16:19]
	v_mfma_f32_16x16x32_bf16 v[8:11], v[140:143], v[214:217], v[8:11]
	s_setprio 0
	s_setprio 1
	v_mfma_f32_16x16x32_bf16 v[52:55], v[162:165], v[186:189], v[52:55]
	v_mfma_f32_16x16x32_bf16 v[44:47], v[178:181], v[186:189], v[44:47]
	v_mfma_f32_16x16x32_bf16 v[36:39], v[162:165], v[194:197], v[36:39]
	v_mfma_f32_16x16x32_bf16 v[28:31], v[178:181], v[194:197], v[28:31]
	v_mfma_f32_16x16x32_bf16 v[20:23], v[162:165], v[202:205], v[20:23]
	v_mfma_f32_16x16x32_bf16 v[12:15], v[178:181], v[202:205], v[12:15]
	v_mfma_f32_16x16x32_bf16 v[4:7], v[162:165], v[210:213], v[4:7]
	v_mfma_f32_16x16x32_bf16 v[0:3], v[178:181], v[210:213], v[0:3]
	v_mfma_f32_16x16x32_bf16 v[52:55], v[174:177], v[190:193], v[52:55]
	v_mfma_f32_16x16x32_bf16 v[44:47], v[182:185], v[190:193], v[44:47]
	v_mfma_f32_16x16x32_bf16 v[36:39], v[174:177], v[198:201], v[36:39]
	v_mfma_f32_16x16x32_bf16 v[28:31], v[182:185], v[198:201], v[28:31]
	v_mfma_f32_16x16x32_bf16 v[20:23], v[174:177], v[206:209], v[20:23]
	v_mfma_f32_16x16x32_bf16 v[12:15], v[182:185], v[206:209], v[12:15]
	v_mfma_f32_16x16x32_bf16 v[4:7], v[174:177], v[214:217], v[4:7]
	v_mfma_f32_16x16x32_bf16 v[0:3], v[182:185], v[214:217], v[0:3]
	s_setprio 0
	s_barrier
	s_add_i32 s60, s60, 2
	s_add_u32 s58, s58, 0x100
	s_addc_u32 s59, s59, 0
	s_cmp_gt_u32 s60, 29
	s_mov_b64 s[26:27], s[4:5]
	s_cbranch_scc0 .LBB0_2451
; #define PG8_STAGE(bufoff, gbase, voff) do { _Pragma("unroll") for (int _i = 0; _i < 2; ++_i) \
;         __builtin_amdgcn_global_load_lds((const unsigned*)((const char*)(gbase) + (voff)[_i]), (PG8_LAS unsigned*)(lds + (bufoff) + ldsw + _i * 8192), 16, 0, 0); } while (0)
; #define PG8_LDA(dst, b, h) do { _Pragma("unroll") for (int m = 0; m < 4; ++m) _Pragma("unroll") for (int k = 0; k < 2; ++k) dst[m][k] = *(const PG8_LAS bf16x8*)(lds + PG8_SA(b, h) + aoff + m * 2048 + k * 1024); } while (0)
; #define PG8_LDB(dst, b, h) do { _Pragma("unroll") for (int n = 0; n < 2; ++n) _Pragma("unroll") for (int k = 0; k < 2; ++k) dst[n][k] = *(const PG8_LAS bf16x8*)(lds + PG8_SB(b, h) + boff + n * 2048 + k * 1024); } while (0)
; #define PG8_MMA(ai, bj, At, Bt) do { __builtin_amdgcn_s_setprio(1); _Pragma("unroll") for (int m = 0; m < 4; ++m) _Pragma("unroll") for (int n = 0; n < 2; ++n) _Pragma("unroll") for (int k = 0; k < 2; ++k) \
;         acc[ai][bj][m][n] = __builtin_amdgcn_mfma_f32_16x16x32_bf16(Bt[n][k], At[m][k], acc[ai][bj][m][n], 0, 0, 0); __builtin_amdgcn_s_setprio(0); } while (0)
; #define PG8_WAIT_V(n) asm volatile("s_waitcnt vmcnt(" #n ")" ::: "memory")
; #define PG8_WAIT_L(n) asm volatile("s_waitcnt lgkmcnt(" #n ")" ::: "memory")
; #define PG8_BAR __builtin_amdgcn_s_barrier()
; #define PG8_SCHED __builtin_amdgcn_sched_barrier(0)
; template <class Epi, class Sched, bool ALIGN_EPI = false, bool SP2 = false>
; __device__ __forceinline__ void gemm_phase(PG8_LAS unsigned char* lds, const Gemm g, const Sched& S, const Epi& E, const int wave_in) {
;     ...
;             PG8_LDB(B0, 0, 0); PG8_LDB(B1, 0, 1); PG8_SCHED; PG8_LDA(At, 0, 0); PG8_STAGE(PG8_SA(1, 1), a1 + hstepA, voffA);
;             PG8_WAIT_V(8); PG8_WAIT_L(0); PG8_BAR; PG8_MMA(0, 0, At, B0); PG8_MMA(0, 1, At, B1); PG8_BAR; PG8_SCHED;
;             PG8_LDA(At, 0, 1); PG8_STAGE(PG8_SB(0, 0), b2, voffB); PG8_STAGE(PG8_SB(0, 1), b2 + hstepB, voffB); PG8_STAGE(PG8_SA(0, 0), a2, voffA);
;             PG8_WAIT_V(8); PG8_WAIT_L(0); PG8_BAR; PG8_MMA(1, 0, At, B0); PG8_MMA(1, 1, At, B1); PG8_BAR; PG8_SCHED;
;             PG8_LDB(B0, 1, 0); PG8_LDB(B1, 1, 1); PG8_SCHED; PG8_LDA(At, 1, 0); PG8_STAGE(PG8_SA(0, 1), a2 + hstepA, voffA);
;             PG8_WAIT_V(8); PG8_WAIT_L(0); PG8_BAR; PG8_MMA(0, 0, At, B0); PG8_MMA(0, 1, At, B1); PG8_BAR; PG8_SCHED;
.LBB0_2451:
	ds_read_b128 v[128:131], v170
	ds_read_b128 v[132:135], v170 offset:1024
	ds_read_b128 v[136:139], v170 offset:2048
	ds_read_b128 v[140:143], v170 offset:3072
	ds_read_b128 v[162:165], v171
	ds_read_b128 v[174:177], v171 offset:1024
	ds_read_b128 v[178:181], v171 offset:2048
	ds_read_b128 v[182:185], v171 offset:3072
	s_add_u32 s4, s26, 0x100
	s_addc_u32 s5, s27, 0
	s_cmp_eq_u32 s60, 28
	s_cselect_b32 s31, s21, s5
	s_cselect_b32 s30, s20, s4
	s_cselect_b32 s29, s19, s59
	s_cselect_b32 s28, s25, s58
	v_lshl_add_u64 v[166:167], s[26:27], 0, v[154:155]
	s_add_i32 m0, s40, 0xc000
	ds_read_b128 v[186:189], v172
	ds_read_b128 v[190:193], v172 offset:1024
	ds_read_b128 v[194:197], v172 offset:2048
	ds_read_b128 v[198:201], v172 offset:3072
	ds_read_b128 v[202:205], v172 offset:4096
	ds_read_b128 v[206:209], v172 offset:5120
	ds_read_b128 v[210:213], v172 offset:6144
	ds_read_b128 v[214:217], v172 offset:7168
	global_load_lds_dwordx4 v[166:167], off
	v_lshl_add_u64 v[166:167], s[26:27], 0, v[156:157]
	s_add_i32 m0, s40, 0xe000
	s_nop 0
	global_load_lds_dwordx4 v[166:167], off
	s_waitcnt vmcnt(8)
	s_waitcnt lgkmcnt(0)
	s_barrier
	s_setprio 1
	s_waitcnt lgkmcnt(0)
	v_mfma_f32_16x16x32_bf16 v[124:127], v[128:131], v[186:189], v[124:127]
	v_mfma_f32_16x16x32_bf16 v[120:123], v[136:139], v[186:189], v[120:123]
	v_mfma_f32_16x16x32_bf16 v[112:115], v[128:131], v[194:197], v[112:115]
	v_mfma_f32_16x16x32_bf16 v[104:107], v[136:139], v[194:197], v[104:107]
	v_mfma_f32_16x16x32_bf16 v[96:99], v[128:131], v[202:205], v[96:99]
	v_mfma_f32_16x16x32_bf16 v[88:91], v[136:139], v[202:205], v[88:91]
	v_mfma_f32_16x16x32_bf16 v[80:83], v[128:131], v[210:213], v[80:83]
	v_mfma_f32_16x16x32_bf16 v[72:75], v[136:139], v[210:213], v[72:75]
	v_mfma_f32_16x16x32_bf16 v[124:127], v[132:135], v[190:193], v[124:127]
	v_mfma_f32_16x16x32_bf16 v[120:123], v[140:143], v[190:193], v[120:123]
	v_mfma_f32_16x16x32_bf16 v[112:115], v[132:135], v[198:201], v[112:115]
	v_mfma_f32_16x16x32_bf16 v[104:107], v[140:143], v[198:201], v[104:107]
	v_mfma_f32_16x16x32_bf16 v[96:99], v[132:135], v[206:209], v[96:99]
	v_mfma_f32_16x16x32_bf16 v[88:91], v[140:143], v[206:209], v[88:91]
	v_mfma_f32_16x16x32_bf16 v[80:83], v[132:135], v[214:217], v[80:83]
	v_mfma_f32_16x16x32_bf16 v[72:75], v[140:143], v[214:217], v[72:75]
	s_setprio 0
	s_setprio 1
	v_mfma_f32_16x16x32_bf16 v[116:119], v[162:165], v[186:189], v[116:119]
	v_mfma_f32_16x16x32_bf16 v[108:111], v[178:181], v[186:189], v[108:111]
	v_mfma_f32_16x16x32_bf16 v[100:103], v[162:165], v[194:197], v[100:103]
	v_mfma_f32_16x16x32_bf16 v[92:95], v[178:181], v[194:197], v[92:95]
	v_mfma_f32_16x16x32_bf16 v[84:87], v[162:165], v[202:205], v[84:87]
	v_mfma_f32_16x16x32_bf16 v[76:79], v[178:181], v[202:205], v[76:79]
	v_mfma_f32_16x16x32_bf16 v[68:71], v[162:165], v[210:213], v[68:71]
	v_mfma_f32_16x16x32_bf16 v[64:67], v[178:181], v[210:213], v[64:67]
	v_mfma_f32_16x16x32_bf16 v[116:119], v[174:177], v[190:193], v[116:119]
	v_mfma_f32_16x16x32_bf16 v[108:111], v[182:185], v[190:193], v[108:111]
	v_mfma_f32_16x16x32_bf16 v[100:103], v[174:177], v[198:201], v[100:103]
	v_mfma_f32_16x16x32_bf16 v[92:95], v[182:185], v[198:201], v[92:95]
	v_mfma_f32_16x16x32_bf16 v[84:87], v[174:177], v[206:209], v[84:87]
	v_mfma_f32_16x16x32_bf16 v[76:79], v[182:185], v[206:209], v[76:79]
	v_mfma_f32_16x16x32_bf16 v[68:71], v[174:177], v[214:217], v[68:71]
	v_mfma_f32_16x16x32_bf16 v[64:67], v[182:185], v[214:217], v[64:67]
	s_setprio 0
	s_barrier
	s_add_i32 s26, s50, s39
	v_lshl_add_u64 v[166:167], s[28:29], 0, v[146:147]
	s_mov_b32 m0, s26
	ds_read_b128 v[186:189], v172 offset:16384
	ds_read_b128 v[190:193], v172 offset:17408
	ds_read_b128 v[194:197], v172 offset:18432
	ds_read_b128 v[198:201], v172 offset:19456
	ds_read_b128 v[202:205], v172 offset:20480
	ds_read_b128 v[206:209], v172 offset:21504
	ds_read_b128 v[210:213], v172 offset:22528
	ds_read_b128 v[214:217], v172 offset:23552
	global_load_lds_dwordx4 v[166:167], off
	s_add_i32 m0, s26, 0x2000
	s_add_u32 s26, s28, 0x80000
	v_lshl_add_u64 v[218:219], s[28:29], 0, v[150:151]
	s_addc_u32 s27, s29, 0
	s_add_i32 s61, s51, s39
	global_load_lds_dwordx4 v[218:219], off
	v_lshl_add_u64 v[220:221], s[26:27], 0, v[146:147]
	s_mov_b32 m0, s61
	v_lshl_add_u64 v[222:223], s[30:31], 0, v[148:149]
	global_load_lds_dwordx4 v[220:221], off
	v_lshl_add_u64 v[220:221], s[26:27], 0, v[150:151]
	s_add_i32 m0, s61, 0x2000
	s_nop 0
	global_load_lds_dwordx4 v[220:221], off
	v_lshl_add_u64 v[220:221], s[30:31], 0, v[144:145]
	s_mov_b32 m0, s40
	s_nop 0
	global_load_lds_dwordx4 v[220:221], off
	s_mov_b32 m0, s41
	s_nop 0
	global_load_lds_dwordx4 v[222:223], off
	s_waitcnt vmcnt(8)
	s_waitcnt lgkmcnt(0)
	s_barrier
; #define PG8_STAGE(bufoff, gbase, voff) do { _Pragma("unroll") for (int _i = 0; _i < 2; ++_i) \
;         __builtin_amdgcn_global_load_lds((const unsigned*)((const char*)(gbase) + (voff)[_i]), (PG8_LAS unsigned*)(lds + (bufoff) + ldsw + _i * 8192), 16, 0, 0); } while (0)
; #define PG8_LDA(dst, b, h) do { _Pragma("unroll") for (int m = 0; m < 4; ++m) _Pragma("unroll") for (int k = 0; k < 2; ++k) dst[m][k] = *(const PG8_LAS bf16x8*)(lds + PG8_SA(b, h) + aoff + m * 2048 + k * 1024); } while (0)
; #define PG8_LDB(dst, b, h) do { _Pragma("unroll") for (int n = 0; n < 2; ++n) _Pragma("unroll") for (int k = 0; k < 2; ++k) dst[n][k] = *(const PG8_LAS bf16x8*)(lds + PG8_SB(b, h) + boff + n * 2048 + k * 1024); } while (0)
; #define PG8_MMA(ai, bj, At, Bt) do { __builtin_amdgcn_s_setprio(1); _Pragma("unroll") for (int m = 0; m < 4; ++m) _Pragma("unroll") for (int n = 0; n < 2; ++n) _Pragma("unroll") for (int k = 0; k < 2; ++k) \
;         acc[ai][bj][m][n] = __builtin_amdgcn_mfma_f32_16x16x32_bf16(Bt[n][k], At[m][k], acc[ai][bj][m][n], 0, 0, 0); __builtin_amdgcn_s_setprio(0); } while (0)
; #define PG8_WAIT_V(n) asm volatile("s_waitcnt vmcnt(" #n ")" ::: "memory")
; #define PG8_WAIT_L(n) asm volatile("s_waitcnt lgkmcnt(" #n ")" ::: "memory")
; #define PG8_BAR __builtin_amdgcn_s_barrier()
; #define PG8_SCHED __builtin_amdgcn_sched_barrier(0)
; template <class Epi, class Sched, bool ALIGN_EPI = false, bool SP2 = false>
; __device__ __forceinline__ void gemm_phase(PG8_LAS unsigned char* lds, const Gemm g, const Sched& S, const Epi& E, const int wave_in) {
;     ...
;             PG8_LDB(B0, 1, 0); PG8_LDB(B1, 1, 1); PG8_SCHED; PG8_LDA(At, 1, 0); PG8_STAGE(PG8_SA(0, 1), a2 + hstepA, voffA);
;             PG8_WAIT_V(8); PG8_WAIT_L(0); PG8_BAR; PG8_MMA(0, 0, At, B0); PG8_MMA(0, 1, At, B1); PG8_BAR; PG8_SCHED;
;             PG8_LDA(At, 1, 1); PG8_STAGE(PG8_SB(1, 0), b3, voffB); PG8_STAGE(PG8_SB(1, 1), b3 + hstepB, voffB); PG8_STAGE(PG8_SA(1, 0), a3, voffA);
;             PG8_WAIT_V(8); PG8_WAIT_L(0); PG8_BAR; PG8_MMA(1, 0, At, B0); PG8_MMA(1, 1, At, B1); PG8_BAR; PG8_SCHED;
	s_setprio 1
	s_waitcnt lgkmcnt(0)
	v_mfma_f32_16x16x32_bf16 v[60:63], v[128:131], v[186:189], v[60:63]
	v_mfma_f32_16x16x32_bf16 v[56:59], v[136:139], v[186:189], v[56:59]
	v_mfma_f32_16x16x32_bf16 v[48:51], v[128:131], v[194:197], v[48:51]
	v_mfma_f32_16x16x32_bf16 v[40:43], v[136:139], v[194:197], v[40:43]
	v_mfma_f32_16x16x32_bf16 v[32:35], v[128:131], v[202:205], v[32:35]
	v_mfma_f32_16x16x32_bf16 v[24:27], v[136:139], v[202:205], v[24:27]
	v_mfma_f32_16x16x32_bf16 v[16:19], v[128:131], v[210:213], v[16:19]
	v_mfma_f32_16x16x32_bf16 v[8:11], v[136:139], v[210:213], v[8:11]
	v_mfma_f32_16x16x32_bf16 v[60:63], v[132:135], v[190:193], v[60:63]
	v_mfma_f32_16x16x32_bf16 v[56:59], v[140:143], v[190:193], v[56:59]
	v_mfma_f32_16x16x32_bf16 v[48:51], v[132:135], v[198:201], v[48:51]
	v_mfma_f32_16x16x32_bf16 v[40:43], v[140:143], v[198:201], v[40:43]
	v_mfma_f32_16x16x32_bf16 v[32:35], v[132:135], v[206:209], v[32:35]
	v_mfma_f32_16x16x32_bf16 v[24:27], v[140:143], v[206:209], v[24:27]
	v_mfma_f32_16x16x32_bf16 v[16:19], v[132:135], v[214:217], v[16:19]
	v_mfma_f32_16x16x32_bf16 v[8:11], v[140:143], v[214:217], v[8:11]
	s_setprio 0
	s_setprio 1
	v_mfma_f32_16x16x32_bf16 v[52:55], v[162:165], v[186:189], v[52:55]
	v_mfma_f32_16x16x32_bf16 v[44:47], v[178:181], v[186:189], v[44:47]
	v_mfma_f32_16x16x32_bf16 v[36:39], v[162:165], v[194:197], v[36:39]
	v_mfma_f32_16x16x32_bf16 v[28:31], v[178:181], v[194:197], v[28:31]
	v_mfma_f32_16x16x32_bf16 v[20:23], v[162:165], v[202:205], v[20:23]
	v_mfma_f32_16x16x32_bf16 v[12:15], v[178:181], v[202:205], v[12:15]
	v_mfma_f32_16x16x32_bf16 v[4:7], v[162:165], v[210:213], v[4:7]
	v_mfma_f32_16x16x32_bf16 v[0:3], v[178:181], v[210:213], v[0:3]
	v_mfma_f32_16x16x32_bf16 v[52:55], v[174:177], v[190:193], v[52:55]
	v_mfma_f32_16x16x32_bf16 v[44:47], v[182:185], v[190:193], v[44:47]
	v_mfma_f32_16x16x32_bf16 v[36:39], v[174:177], v[198:201], v[36:39]
	v_mfma_f32_16x16x32_bf16 v[28:31], v[182:185], v[198:201], v[28:31]
	v_mfma_f32_16x16x32_bf16 v[20:23], v[174:177], v[206:209], v[20:23]
	v_mfma_f32_16x16x32_bf16 v[12:15], v[182:185], v[206:209], v[12:15]
	v_mfma_f32_16x16x32_bf16 v[4:7], v[174:177], v[214:217], v[4:7]
	v_mfma_f32_16x16x32_bf16 v[0:3], v[182:185], v[214:217], v[0:3]
	s_setprio 0
	s_barrier
	s_add_i32 s61, 0, 0x18000
	s_add_i32 s62, 0, 0x1c000
	v_add_u32_e32 v140, s61, v168
	v_add_u32_e32 v173, s62, v168
	ds_read_b128 v[128:131], v140
	ds_read_b128 v[132:135], v140 offset:1024
	ds_read_b128 v[136:139], v140 offset:2048
	ds_read_b128 v[140:143], v140 offset:3072
	ds_read_b128 v[162:165], v173
	ds_read_b128 v[174:177], v173 offset:1024
	ds_read_b128 v[178:181], v173 offset:2048
	ds_read_b128 v[182:185], v173 offset:3072
	s_add_u32 s26, s30, 0x280000
	s_addc_u32 s27, s31, 0
	s_mov_b32 m0, s42
	v_lshl_add_u64 v[224:225], s[26:27], 0, v[144:145]
	ds_read_b128 v[186:189], v172 offset:32768
	ds_read_b128 v[190:193], v172 offset:33792
	ds_read_b128 v[194:197], v172 offset:34816
	ds_read_b128 v[198:201], v172 offset:35840
	ds_read_b128 v[202:205], v172 offset:36864
	ds_read_b128 v[206:209], v172 offset:37888
	ds_read_b128 v[210:213], v172 offset:38912
	ds_read_b128 v[214:217], v172 offset:39936
	global_load_lds_dwordx4 v[224:225], off
	v_lshl_add_u64 v[224:225], s[26:27], 0, v[148:149]
	s_mov_b32 m0, s43
	s_nop 0
	global_load_lds_dwordx4 v[224:225], off
	s_waitcnt vmcnt(8)
	s_waitcnt lgkmcnt(0)
	s_barrier
	s_setprio 1
	s_waitcnt lgkmcnt(0)
	v_mfma_f32_16x16x32_bf16 v[124:127], v[128:131], v[186:189], v[124:127]
	v_mfma_f32_16x16x32_bf16 v[120:123], v[136:139], v[186:189], v[120:123]
	v_mfma_f32_16x16x32_bf16 v[112:115], v[128:131], v[194:197], v[112:115]
	v_mfma_f32_16x16x32_bf16 v[104:107], v[136:139], v[194:197], v[104:107]
	v_mfma_f32_16x16x32_bf16 v[96:99], v[128:131], v[202:205], v[96:99]
	v_mfma_f32_16x16x32_bf16 v[88:91], v[136:139], v[202:205], v[88:91]
	v_mfma_f32_16x16x32_bf16 v[80:83], v[128:131], v[210:213], v[80:83]
	v_mfma_f32_16x16x32_bf16 v[72:75], v[136:139], v[210:213], v[72:75]
	v_mfma_f32_16x16x32_bf16 v[124:127], v[132:135], v[190:193], v[124:127]
	v_mfma_f32_16x16x32_bf16 v[120:123], v[140:143], v[190:193], v[120:123]
	v_mfma_f32_16x16x32_bf16 v[112:115], v[132:135], v[198:201], v[112:115]
	v_mfma_f32_16x16x32_bf16 v[104:107], v[140:143], v[198:201], v[104:107]
	v_mfma_f32_16x16x32_bf16 v[96:99], v[132:135], v[206:209], v[96:99]
	v_mfma_f32_16x16x32_bf16 v[88:91], v[140:143], v[206:209], v[88:91]
	v_mfma_f32_16x16x32_bf16 v[80:83], v[132:135], v[214:217], v[80:83]
	v_mfma_f32_16x16x32_bf16 v[72:75], v[140:143], v[214:217], v[72:75]
	s_setprio 0
	s_setprio 1
	v_mfma_f32_16x16x32_bf16 v[116:119], v[162:165], v[186:189], v[116:119]
	v_mfma_f32_16x16x32_bf16 v[108:111], v[178:181], v[186:189], v[108:111]
	v_mfma_f32_16x16x32_bf16 v[100:103], v[162:165], v[194:197], v[100:103]
	v_mfma_f32_16x16x32_bf16 v[92:95], v[178:181], v[194:197], v[92:95]
	v_mfma_f32_16x16x32_bf16 v[84:87], v[162:165], v[202:205], v[84:87]
	v_mfma_f32_16x16x32_bf16 v[76:79], v[178:181], v[202:205], v[76:79]
	v_mfma_f32_16x16x32_bf16 v[68:71], v[162:165], v[210:213], v[68:71]
	v_mfma_f32_16x16x32_bf16 v[64:67], v[178:181], v[210:213], v[64:67]
	v_mfma_f32_16x16x32_bf16 v[116:119], v[174:177], v[190:193], v[116:119]
	v_mfma_f32_16x16x32_bf16 v[108:111], v[182:185], v[190:193], v[108:111]
	v_mfma_f32_16x16x32_bf16 v[100:103], v[174:177], v[198:201], v[100:103]
	v_mfma_f32_16x16x32_bf16 v[92:95], v[182:185], v[198:201], v[92:95]
	v_mfma_f32_16x16x32_bf16 v[84:87], v[174:177], v[206:209], v[84:87]
	v_mfma_f32_16x16x32_bf16 v[76:79], v[182:185], v[206:209], v[76:79]
	v_mfma_f32_16x16x32_bf16 v[68:71], v[174:177], v[214:217], v[68:71]
	v_mfma_f32_16x16x32_bf16 v[64:67], v[182:185], v[214:217], v[64:67]
	s_setprio 0
	s_barrier
; #define PG8_STAGE(bufoff, gbase, voff) do { _Pragma("unroll") for (int _i = 0; _i < 2; ++_i) \
;         __builtin_amdgcn_global_load_lds((const unsigned*)((const char*)(gbase) + (voff)[_i]), (PG8_LAS unsigned*)(lds + (bufoff) + ldsw + _i * 8192), 16, 0, 0); } while (0)
; #define PG8_LDA(dst, b, h) do { _Pragma("unroll") for (int m = 0; m < 4; ++m) _Pragma("unroll") for (int k = 0; k < 2; ++k) dst[m][k] = *(const PG8_LAS bf16x8*)(lds + PG8_SA(b, h) + aoff + m * 2048 + k * 1024); } while (0)
; #define PG8_WAIT_V(n) asm volatile("s_waitcnt vmcnt(" #n ")" ::: "memory")
; #define PG8_WAIT_L(n) asm volatile("s_waitcnt lgkmcnt(" #n ")" ::: "memory")
; #define PG8_BAR __builtin_amdgcn_s_barrier()
; template <class Epi, class Sched, bool ALIGN_EPI = false, bool SP2 = false>
; __device__ __forceinline__ void gemm_phase(PG8_LAS unsigned char* lds, const Gemm g, const Sched& S, const Epi& E, const int wave_in) {
;     ...
;             PG8_WAIT_V(8); PG8_WAIT_L(0); PG8_BAR; PG8_MMA(1, 0, At, B0); PG8_MMA(1, 1, At, B1); PG8_BAR; PG8_SCHED;
;             } else {
;             PG8_LDB(B0, 0, 0); PG8_SCHED; PG8_LDA(At, 0, 0); PG8_STAGE(PG8_SA(1, 1), a1 + hstepA, voffA);
;             PG8_WAIT_L(8); PG8_BAR; PG8_WAIT_L(0); PG8_MMA(0, 0, At, B0); PG8_BAR; PG8_SCHED;
;             PG8_LDB(B1, 0, 1); PG8_STAGE(PG8_SB(0, 0), b2, voffB);
;             PG8_BAR; PG8_WAIT_L(0); PG8_MMA(0, 1, At, B1); PG8_BAR;
;             PG8_LDA(At, 0, 1); PG8_STAGE(PG8_SA(0, 0), a2, voffA);
;             PG8_BAR; PG8_WAIT_L(0); PG8_MMA(1, 0, At, B0); PG8_BAR; PG8_SCHED;
;             PG8_STAGE(PG8_SB(0, 1), b2 + hstepB, voffB);
;             PG8_WAIT_V(6); PG8_BAR; PG8_MMA(1, 1, At, B1); PG8_BAR;
;             PG8_LDB(B0, 1, 0); PG8_SCHED; PG8_LDA(At, 1, 0); PG8_STAGE(PG8_SA(0, 1), a2 + hstepA, voffA);
;             PG8_WAIT_L(8); PG8_BAR; PG8_WAIT_L(0); PG8_MMA(0, 0, At, B0); PG8_BAR; PG8_SCHED;
;             PG8_LDB(B1, 1, 1); PG8_STAGE(PG8_SB(1, 0), b3, voffB);
;             PG8_BAR; PG8_WAIT_L(0); PG8_MMA(0, 1, At, B1); PG8_BAR;
;             PG8_LDA(At, 1, 1); PG8_STAGE(PG8_SA(1, 0), a3, voffA);
;             PG8_BAR; PG8_WAIT_L(0); PG8_MMA(1, 0, At, B0); PG8_BAR; PG8_SCHED;
;             PG8_STAGE(PG8_SB(1, 1), b3 + hstepB, voffB);
;             PG8_WAIT_V(6); PG8_BAR; PG8_MMA(1, 1, At, B1); PG8_BAR;
;             }
;         }
;         if constexpr (ALIGN_EPI) { if (wr == 0) PG8_BAR; }
	s_add_i32 s26, s61, s39
	v_lshl_add_u64 v[166:167], v[166:167], 0, s[8:9]
	s_mov_b32 m0, s26
	ds_read_b128 v[186:189], v172 offset:49152
	ds_read_b128 v[190:193], v172 offset:50176
	ds_read_b128 v[194:197], v172 offset:51200
	ds_read_b128 v[198:201], v172 offset:52224
	ds_read_b128 v[202:205], v172 offset:53248
	ds_read_b128 v[206:209], v172 offset:54272
	ds_read_b128 v[210:213], v172 offset:55296
	ds_read_b128 v[214:217], v172 offset:56320
	global_load_lds_dwordx4 v[166:167], off
	s_add_i32 m0, s26, 0x2000
	s_add_u32 s26, s28, 0x80080
	v_lshl_add_u64 v[166:167], v[218:219], 0, s[8:9]
	s_addc_u32 s27, s29, 0
	s_add_i32 s28, s62, s39
	global_load_lds_dwordx4 v[166:167], off
	v_lshl_add_u64 v[166:167], s[26:27], 0, v[146:147]
	s_mov_b32 m0, s28
	s_nop 0
	global_load_lds_dwordx4 v[166:167], off
	v_lshl_add_u64 v[166:167], s[26:27], 0, v[150:151]
	s_add_i32 m0, s28, 0x2000
	s_nop 0
	global_load_lds_dwordx4 v[166:167], off
	v_lshl_add_u64 v[166:167], v[220:221], 0, s[8:9]
	s_mov_b32 m0, s47
	s_nop 0
	global_load_lds_dwordx4 v[166:167], off
	v_lshl_add_u64 v[166:167], v[222:223], 0, s[8:9]
	s_mov_b32 m0, s48
	s_nop 0
	global_load_lds_dwordx4 v[166:167], off
	s_waitcnt vmcnt(8)
	s_waitcnt lgkmcnt(0)
	s_barrier
	s_setprio 1
	s_waitcnt lgkmcnt(0)
	v_mfma_f32_16x16x32_bf16 v[60:63], v[128:131], v[186:189], v[60:63]
	v_mfma_f32_16x16x32_bf16 v[56:59], v[136:139], v[186:189], v[56:59]
	v_mfma_f32_16x16x32_bf16 v[48:51], v[128:131], v[194:197], v[48:51]
	v_mfma_f32_16x16x32_bf16 v[40:43], v[136:139], v[194:197], v[40:43]
	v_mfma_f32_16x16x32_bf16 v[32:35], v[128:131], v[202:205], v[32:35]
	v_mfma_f32_16x16x32_bf16 v[24:27], v[136:139], v[202:205], v[24:27]
	v_mfma_f32_16x16x32_bf16 v[16:19], v[128:131], v[210:213], v[16:19]
	v_mfma_f32_16x16x32_bf16 v[8:11], v[136:139], v[210:213], v[8:11]
	v_mfma_f32_16x16x32_bf16 v[60:63], v[132:135], v[190:193], v[60:63]
	v_mfma_f32_16x16x32_bf16 v[56:59], v[140:143], v[190:193], v[56:59]
	v_mfma_f32_16x16x32_bf16 v[48:51], v[132:135], v[198:201], v[48:51]
	v_mfma_f32_16x16x32_bf16 v[40:43], v[140:143], v[198:201], v[40:43]
	v_mfma_f32_16x16x32_bf16 v[32:35], v[132:135], v[206:209], v[32:35]
	v_mfma_f32_16x16x32_bf16 v[24:27], v[140:143], v[206:209], v[24:27]
	v_mfma_f32_16x16x32_bf16 v[16:19], v[132:135], v[214:217], v[16:19]
	v_mfma_f32_16x16x32_bf16 v[8:11], v[140:143], v[214:217], v[8:11]
	s_setprio 0
	s_setprio 1
	v_mfma_f32_16x16x32_bf16 v[52:55], v[162:165], v[186:189], v[52:55]
	v_mfma_f32_16x16x32_bf16 v[44:47], v[178:181], v[186:189], v[44:47]
	v_mfma_f32_16x16x32_bf16 v[36:39], v[162:165], v[194:197], v[36:39]
	v_mfma_f32_16x16x32_bf16 v[28:31], v[178:181], v[194:197], v[28:31]
	v_mfma_f32_16x16x32_bf16 v[20:23], v[162:165], v[202:205], v[20:23]
	v_mfma_f32_16x16x32_bf16 v[12:15], v[178:181], v[202:205], v[12:15]
	v_mfma_f32_16x16x32_bf16 v[4:7], v[162:165], v[210:213], v[4:7]
	v_mfma_f32_16x16x32_bf16 v[0:3], v[178:181], v[210:213], v[0:3]
	v_mfma_f32_16x16x32_bf16 v[52:55], v[174:177], v[190:193], v[52:55]
	v_mfma_f32_16x16x32_bf16 v[44:47], v[182:185], v[190:193], v[44:47]
	v_mfma_f32_16x16x32_bf16 v[36:39], v[174:177], v[198:201], v[36:39]
	v_mfma_f32_16x16x32_bf16 v[28:31], v[182:185], v[198:201], v[28:31]
	v_mfma_f32_16x16x32_bf16 v[20:23], v[174:177], v[206:209], v[20:23]
	v_mfma_f32_16x16x32_bf16 v[12:15], v[182:185], v[206:209], v[12:15]
	v_mfma_f32_16x16x32_bf16 v[4:7], v[174:177], v[214:217], v[4:7]
	v_mfma_f32_16x16x32_bf16 v[0:3], v[182:185], v[214:217], v[0:3]
	s_setprio 0
	s_barrier
	s_add_i32 s60, s60, 2
	s_add_u32 s58, s58, 0x100
	s_addc_u32 s59, s59, 0
	s_cmp_gt_u32 s60, 29
	s_mov_b64 s[26:27], s[4:5]
	s_cbranch_scc0 .LBB0_2451
	s_mov_b32 s99, 1
	s_and_b64 vcc, exec, s[10:11]
	s_cbranch_vccz .LBB0_2454
	s_barrier

;     __host__ __device__ bool next(int i, Unit& u) const {
;         const long L = (long)i * G + c; if (L >= nwg) return false;
;         int wgid = (int)L; { const int q = nwg / NXCD, r = nwg % NXCD, xcd = wgid % NXCD, off = wgid / NXCD; wgid = (xcd < r ? xcd * (q + 1) : r * (q + 1) + (xcd - r) * q) + off; }
;         const int nig = WGM * nN, gid = wgid / nig, fm = gid * WGM, gsz = (nM - fm) < WGM ? (nM - fm) : WGM;
;         u.pm = fm + ((wgid % nig) % gsz); u.pn = (wgid % nig) / gsz; return true;
.LBB0_2564:
	s_cmp_gt_i32 s52, 30
	s_cselect_b64 s[0:1], -1, 0
	s_cmp_lt_i32 s53, 31
	s_cselect_b64 s[2:3], -1, 0
	s_or_b64 s[0:1], s[0:1], s[2:3]
	s_and_b64 vcc, exec, s[0:1]
	s_cbranch_vccnz .LBB0_2649
	s_mov_b32 s99, 0
	s_cmpk_lt_i32 s73, 0x1580
	s_cselect_b64 s[0:1], -1, 0
	s_cmpk_gt_i32 s73, 0x157f
	v_mbcnt_lo_u32_b32 v10, -1, 0
	v_mbcnt_hi_u32_b32 v10, -1, v10
	s_cbranch_scc1 .LBB0_2568
	s_ashr_i32 s2, s73, 31
	s_lshr_b32 s2, s2, 29
	s_add_i32 s2, s73, s2
	s_ashr_i32 s3, s2, 3
	s_and_b32 s2, s2, -8
	s_sub_i32 s2, s73, s2
	s_cmp_lt_i32 s2, 0
	s_movk_i32 s4, 0x2b1
	s_cselect_b32 s4, s4, 0x2b0
	s_mul_i32 s2, s4, s2
	s_add_i32 s2, s2, s3
	s_mul_hi_i32 s3, s2, 0x2fa0be83
	s_lshr_b32 s4, s3, 31
	s_ashr_i32 s3, s3, 5
	s_add_i32 s3, s3, s4
	s_lshl_b32 s4, s3, 2
	s_mulk_i32 s3, 0xac
	s_sub_i32 s2, s2, s3
	s_sext_i32_i16 s3, s2
	s_bfe_u32 s3, s3, 0x2001d
	s_add_i32 s3, s2, s3
	s_sext_i32_i16 s5, s3
	s_and_b32 s3, s3, 0xfffc
	s_sub_i32 s2, s2, s3
	s_sext_i32_i16 s2, s2
	s_add_i32 s10, s4, s2
	s_ashr_i32 s44, s5, 2
	s_andn2_b64 vcc, exec, s[0:1]
	s_cbranch_vccz .LBB0_2569

; #define PG8_STAGE(bufoff, gbase, voff) do { _Pragma("unroll") for (int _i = 0; _i < 2; ++_i) \
;         __builtin_amdgcn_global_load_lds((const unsigned*)((const char*)(gbase) + (voff)[_i]), (PG8_LAS unsigned*)(lds + (bufoff) + ldsw + _i * 8192), 16, 0, 0); } while (0)
; #define PG8_LDA(dst, b, h) do { _Pragma("unroll") for (int m = 0; m < 4; ++m) _Pragma("unroll") for (int k = 0; k < 2; ++k) dst[m][k] = *(const PG8_LAS bf16x8*)(lds + PG8_SA(b, h) + aoff + m * 2048 + k * 1024); } while (0)
; #define PG8_LDB(dst, b, h) do { _Pragma("unroll") for (int n = 0; n < 2; ++n) _Pragma("unroll") for (int k = 0; k < 2; ++k) dst[n][k] = *(const PG8_LAS bf16x8*)(lds + PG8_SB(b, h) + boff + n * 2048 + k * 1024); } while (0)
; #define PG8_WAIT_V(n) asm volatile("s_waitcnt vmcnt(" #n ")" ::: "memory")
; #define PG8_WAIT_L(n) asm volatile("s_waitcnt lgkmcnt(" #n ")" ::: "memory")
; #define PG8_BAR __builtin_amdgcn_s_barrier()
; #define PG8_SCHED __builtin_amdgcn_sched_barrier(0)
; template <class Epi, class Sched, bool ALIGN_EPI = false, bool SP2 = false>
; __device__ __forceinline__ void gemm_phase(PG8_LAS unsigned char* lds, const Gemm g, const Sched& S, const Epi& E, const int wave_in) {
;     ...
;         const char* nA = has_next ? (const char*)g.A + (size_t)nxt.pm * tstepA : cA; const char* nB = has_next ? (const char*)g.Bt + (size_t)nxt.pn * tstepB : cB;
;         for (int t = 0; t < nt; t += 2) {
;             const bool last = (t == nt - 2);
;             const char* a1 = cA + (size_t)(t + 1) * kstep;
;             const char* a2 = last ? nA : cA + (size_t)(t + 2) * kstep; const char* b2 = last ? nB : cB + (size_t)(t + 2) * kstep;
;             const char* a3 = a2 + kstep; const char* b3 = b2 + kstep;
;             if (last && has_next) S.a_ready(nxt);
;             if constexpr (SP2) {
;             PG8_LDB(B0, 0, 0); PG8_LDB(B1, 0, 1); PG8_SCHED; PG8_LDA(At, 0, 0); PG8_STAGE(PG8_SA(1, 1), a1 + hstepA, voffA);
;             PG8_WAIT_V(8); PG8_WAIT_L(0); PG8_BAR; PG8_MMA(0, 0, At, B0); PG8_MMA(0, 1, At, B1); PG8_BAR; PG8_SCHED;
;     ...
; #pragma unroll
;         for (int a = 0; a < 2; ++a)
; #pragma unroll
;             for (int b = 0; b < 2; ++b)
; #pragma unroll
;                 for (int m = 0; m < 4; ++m)
; #pragma unroll
;                     for (int n = 0; n < 2; ++n) acc[a][b][m][n] = (f32x4){0.f, 0.f, 0.f, 0.f};
;         cur = nxt; cA = nA; cB = nB; ++ui;
.LBB0_2576:
	s_ashr_i32 s39, s38, 31
	s_lshl_b64 s[40:41], s[38:39], 20
	s_add_u32 s40, s52, s40
	s_addc_u32 s41, s53, s41
	s_and_b64 s[42:43], s[8:9], exec
	s_cselect_b32 s11, s41, s47
	s_cselect_b32 s39, s40, s46
	s_ashr_i32 s37, s36, 31
	s_lshl_b64 s[42:43], s[36:37], 20
	s_add_u32 s42, s54, s42
	s_addc_u32 s43, s55, s43
	s_and_b64 s[50:51], s[8:9], exec
	s_cselect_b32 s37, s43, s49
	s_cselect_b32 s45, s42, s48
	s_add_u32 s46, s46, 0x80080
	s_addc_u32 s47, s47, 0
	s_add_u32 s72, s48, 0x100
	v_mov_b32_e32 v0, 0
	s_addc_u32 s73, s49, 0
	s_mov_b32 s75, -2
	v_mov_b32_e32 v1, v0
	v_mov_b32_e32 v2, v0
	v_mov_b32_e32 v3, v0
	v_mov_b32_e32 v4, v0
	v_mov_b32_e32 v5, v0
	v_mov_b32_e32 v6, v0
	v_mov_b32_e32 v7, v0
	v_mov_b32_e32 v16, v0
	v_mov_b32_e32 v17, v0
	v_mov_b32_e32 v18, v0
	v_mov_b32_e32 v19, v0
	v_mov_b32_e32 v24, v0
	v_mov_b32_e32 v25, v0
	v_mov_b32_e32 v26, v0
	v_mov_b32_e32 v27, v0
	v_mov_b32_e32 v32, v0
	v_mov_b32_e32 v33, v0
	v_mov_b32_e32 v34, v0
	v_mov_b32_e32 v35, v0
	v_mov_b32_e32 v40, v0
	v_mov_b32_e32 v41, v0
	v_mov_b32_e32 v42, v0
	v_mov_b32_e32 v43, v0
	v_mov_b32_e32 v48, v0
	v_mov_b32_e32 v49, v0
	v_mov_b32_e32 v50, v0
	v_mov_b32_e32 v51, v0
	v_mov_b32_e32 v56, v0
	v_mov_b32_e32 v57, v0
	v_mov_b32_e32 v58, v0
	v_mov_b32_e32 v59, v0
	v_mov_b32_e32 v8, v0
	v_mov_b32_e32 v9, v0
	v_mov_b32_e32 v10, v0
	v_mov_b32_e32 v11, v0
	v_mov_b32_e32 v12, v0
	v_mov_b32_e32 v13, v0
	v_mov_b32_e32 v14, v0
	v_mov_b32_e32 v15, v0
	v_mov_b32_e32 v20, v0
	v_mov_b32_e32 v21, v0
	v_mov_b32_e32 v22, v0
	v_mov_b32_e32 v23, v0
	v_mov_b32_e32 v28, v0
	v_mov_b32_e32 v29, v0
	v_mov_b32_e32 v30, v0
	v_mov_b32_e32 v31, v0
	v_mov_b32_e32 v36, v0
	v_mov_b32_e32 v37, v0
	v_mov_b32_e32 v38, v0
	v_mov_b32_e32 v39, v0
	v_mov_b32_e32 v44, v0
	v_mov_b32_e32 v45, v0
	v_mov_b32_e32 v46, v0
	v_mov_b32_e32 v47, v0
	v_mov_b32_e32 v52, v0
	v_mov_b32_e32 v53, v0
	v_mov_b32_e32 v54, v0
	v_mov_b32_e32 v55, v0
	v_mov_b32_e32 v60, v0
	v_mov_b32_e32 v61, v0
	v_mov_b32_e32 v62, v0
	v_mov_b32_e32 v63, v0
	v_mov_b32_e32 v112, v0
	v_mov_b32_e32 v113, v0
	s_waitcnt vmcnt(0)
	v_mov_b32_e32 v114, v0
	v_mov_b32_e32 v115, v0
	v_mov_b32_e32 v116, v0
	v_mov_b32_e32 v117, v0
	v_mov_b32_e32 v118, v0
	v_mov_b32_e32 v119, v0
	v_mov_b32_e32 v128, v0
	v_mov_b32_e32 v129, v0
	v_mov_b32_e32 v130, v0
	v_mov_b32_e32 v131, v0
	v_mov_b32_e32 v136, v0
	v_mov_b32_e32 v137, v0
	v_mov_b32_e32 v138, v0
	v_mov_b32_e32 v139, v0
	v_mov_b32_e32 v144, v0
	v_mov_b32_e32 v145, v0
	v_mov_b32_e32 v146, v0
	v_mov_b32_e32 v147, v0
	v_mov_b32_e32 v152, v0
	v_mov_b32_e32 v153, v0
	v_mov_b32_e32 v154, v0
	v_mov_b32_e32 v155, v0
	v_mov_b32_e32 v160, v0
	v_mov_b32_e32 v161, v0
	v_mov_b32_e32 v162, v0
	v_mov_b32_e32 v163, v0
	v_mov_b32_e32 v168, v0
	v_mov_b32_e32 v169, v0
	v_mov_b32_e32 v170, v0
	v_mov_b32_e32 v171, v0
	v_mov_b32_e32 v120, v0
	v_mov_b32_e32 v121, v0
	v_mov_b32_e32 v122, v0
	v_mov_b32_e32 v123, v0
	v_mov_b32_e32 v124, v0
	v_mov_b32_e32 v125, v0
	v_mov_b32_e32 v126, v0
	v_mov_b32_e32 v127, v0
	v_mov_b32_e32 v132, v0
	v_mov_b32_e32 v133, v0
	v_mov_b32_e32 v134, v0
	v_mov_b32_e32 v135, v0
	v_mov_b32_e32 v140, v0
	v_mov_b32_e32 v141, v0
	v_mov_b32_e32 v142, v0
	v_mov_b32_e32 v143, v0
	v_mov_b32_e32 v148, v0
	v_mov_b32_e32 v149, v0
	v_mov_b32_e32 v150, v0
	v_mov_b32_e32 v151, v0
	v_mov_b32_e32 v156, v0
	v_mov_b32_e32 v157, v0
	v_mov_b32_e32 v158, v0
	v_mov_b32_e32 v159, v0
	v_mov_b32_e32 v164, v0
	v_mov_b32_e32 v165, v0
	v_mov_b32_e32 v166, v0
	v_mov_b32_e32 v167, v0
	v_mov_b32_e32 v172, v0
	v_mov_b32_e32 v173, v0
	v_mov_b32_e32 v174, v0
	v_mov_b32_e32 v175, v0
	s_cmp_lg_u32 s99, 0
	s_cbranch_scc0 .LBB0_2577
	ds_read_b128 v[64:67], v189
	ds_read_b128 v[68:71], v189 offset:1024
	ds_read_b128 v[72:75], v189 offset:2048
	ds_read_b128 v[76:79], v189 offset:3072
	ds_read_b128 v[80:83], v197
	ds_read_b128 v[84:87], v197 offset:1024
	ds_read_b128 v[88:91], v197 offset:2048
	ds_read_b128 v[92:95], v197 offset:3072
	s_add_u32 s48, s46, 0xfff80080
	s_addc_u32 s49, s47, -1
	s_cmp_eq_u32 s75, 28
	s_cselect_b32 s51, s11, s49
	s_cselect_b32 s50, s39, s48
	s_cselect_b32 s49, s37, s73
	s_cselect_b32 s48, s45, s72
	v_lshl_add_u64 v[224:225], s[46:47], 0, v[206:207]
	s_add_i32 m0, s57, 0xc000
	ds_read_b128 v[96:99], v199
	ds_read_b128 v[100:103], v199 offset:1024
	ds_read_b128 v[104:107], v199 offset:2048
	ds_read_b128 v[108:111], v199 offset:3072
	ds_read_b128 v[176:179], v199 offset:4096
	ds_read_b128 v[212:215], v199 offset:5120
	ds_read_b128 v[216:219], v199 offset:6144
	ds_read_b128 v[220:223], v199 offset:7168
	global_load_lds_dwordx4 v[224:225], off
	v_lshl_add_u64 v[224:225], s[46:47], 0, v[208:209]
	s_add_i32 m0, s57, 0xe000
	s_nop 0
	global_load_lds_dwordx4 v[224:225], off
	s_waitcnt vmcnt(24)
	s_waitcnt lgkmcnt(0)
	s_barrier
; #define PG8_STAGE(bufoff, gbase, voff) do { _Pragma("unroll") for (int _i = 0; _i < 2; ++_i) \
;         __builtin_amdgcn_global_load_lds((const unsigned*)((const char*)(gbase) + (voff)[_i]), (PG8_LAS unsigned*)(lds + (bufoff) + ldsw + _i * 8192), 16, 0, 0); } while (0)
; #define PG8_LDA(dst, b, h) do { _Pragma("unroll") for (int m = 0; m < 4; ++m) _Pragma("unroll") for (int k = 0; k < 2; ++k) dst[m][k] = *(const PG8_LAS bf16x8*)(lds + PG8_SA(b, h) + aoff + m * 2048 + k * 1024); } while (0)
; #define PG8_MMA(ai, bj, At, Bt) do { __builtin_amdgcn_s_setprio(1); _Pragma("unroll") for (int m = 0; m < 4; ++m) _Pragma("unroll") for (int n = 0; n < 2; ++n) _Pragma("unroll") for (int k = 0; k < 2; ++k) \
;         acc[ai][bj][m][n] = __builtin_amdgcn_mfma_f32_16x16x32_bf16(Bt[n][k], At[m][k], acc[ai][bj][m][n], 0, 0, 0); __builtin_amdgcn_s_setprio(0); } while (0)
; #define PG8_WAIT_V(n) asm volatile("s_waitcnt vmcnt(" #n ")" ::: "memory")
; #define PG8_WAIT_L(n) asm volatile("s_waitcnt lgkmcnt(" #n ")" ::: "memory")
; #define PG8_BAR __builtin_amdgcn_s_barrier()
; #define PG8_SCHED __builtin_amdgcn_sched_barrier(0)
; template <class Epi, class Sched, bool ALIGN_EPI = false, bool SP2 = false>
; __device__ __forceinline__ void gemm_phase(PG8_LAS unsigned char* lds, const Gemm g, const Sched& S, const Epi& E, const int wave_in) {
;     ...
;             PG8_WAIT_V(8); PG8_WAIT_L(0); PG8_BAR; PG8_MMA(0, 0, At, B0); PG8_MMA(0, 1, At, B1); PG8_BAR; PG8_SCHED;
;             PG8_LDA(At, 0, 1); PG8_STAGE(PG8_SB(0, 0), b2, voffB); PG8_STAGE(PG8_SB(0, 1), b2 + hstepB, voffB); PG8_STAGE(PG8_SA(0, 0), a2, voffA);
;             PG8_WAIT_V(8); PG8_WAIT_L(0); PG8_BAR; PG8_MMA(1, 0, At, B0); PG8_MMA(1, 1, At, B1); PG8_BAR; PG8_SCHED;
	s_setprio 1
	s_waitcnt lgkmcnt(0)
	v_mfma_f32_16x16x32_bf16 v[172:175], v[64:67], v[96:99], v[172:175]
	v_mfma_f32_16x16x32_bf16 v[164:167], v[72:75], v[96:99], v[164:167]
	v_mfma_f32_16x16x32_bf16 v[156:159], v[64:67], v[104:107], v[156:159]
	v_mfma_f32_16x16x32_bf16 v[148:151], v[72:75], v[104:107], v[148:151]
	v_mfma_f32_16x16x32_bf16 v[140:143], v[64:67], v[176:179], v[140:143]
	v_mfma_f32_16x16x32_bf16 v[132:135], v[72:75], v[176:179], v[132:135]
	v_mfma_f32_16x16x32_bf16 v[124:127], v[64:67], v[216:219], v[124:127]
	v_mfma_f32_16x16x32_bf16 v[120:123], v[72:75], v[216:219], v[120:123]
	v_mfma_f32_16x16x32_bf16 v[172:175], v[68:71], v[100:103], v[172:175]
	v_mfma_f32_16x16x32_bf16 v[164:167], v[76:79], v[100:103], v[164:167]
	v_mfma_f32_16x16x32_bf16 v[156:159], v[68:71], v[108:111], v[156:159]
	v_mfma_f32_16x16x32_bf16 v[148:151], v[76:79], v[108:111], v[148:151]
	v_mfma_f32_16x16x32_bf16 v[140:143], v[68:71], v[212:215], v[140:143]
	v_mfma_f32_16x16x32_bf16 v[132:135], v[76:79], v[212:215], v[132:135]
	v_mfma_f32_16x16x32_bf16 v[124:127], v[68:71], v[220:223], v[124:127]
	v_mfma_f32_16x16x32_bf16 v[120:123], v[76:79], v[220:223], v[120:123]
	s_setprio 0
	s_setprio 1
	v_mfma_f32_16x16x32_bf16 v[168:171], v[80:83], v[96:99], v[168:171]
	v_mfma_f32_16x16x32_bf16 v[96:99], v[88:91], v[96:99], v[160:163]
	v_mfma_f32_16x16x32_bf16 v[168:171], v[84:87], v[100:103], v[168:171]
	v_mfma_f32_16x16x32_bf16 v[96:99], v[92:95], v[100:103], v[96:99]
	v_mfma_f32_16x16x32_bf16 v[100:103], v[80:83], v[104:107], v[152:155]
	v_mfma_f32_16x16x32_bf16 v[104:107], v[88:91], v[104:107], v[144:147]
	v_mfma_f32_16x16x32_bf16 v[128:131], v[88:91], v[176:179], v[128:131]
	v_mfma_f32_16x16x32_bf16 v[116:119], v[80:83], v[216:219], v[116:119]
	v_mfma_f32_16x16x32_bf16 v[112:115], v[88:91], v[216:219], v[112:115]
	v_mfma_f32_16x16x32_bf16 v[100:103], v[84:87], v[108:111], v[100:103]
	v_mfma_f32_16x16x32_bf16 v[104:107], v[92:95], v[108:111], v[104:107]
	v_mfma_f32_16x16x32_bf16 v[108:111], v[80:83], v[176:179], v[136:139]
	v_mfma_f32_16x16x32_bf16 v[128:131], v[92:95], v[212:215], v[128:131]
	v_mfma_f32_16x16x32_bf16 v[116:119], v[84:87], v[220:223], v[116:119]
	v_mfma_f32_16x16x32_bf16 v[112:115], v[92:95], v[220:223], v[112:115]
	v_mfma_f32_16x16x32_bf16 v[108:111], v[84:87], v[212:215], v[108:111]
	s_setprio 0
	s_barrier
	s_add_i32 s76, s69, s56
	v_lshl_add_u64 v[232:233], s[48:49], 0, v[182:183]
	s_mov_b32 m0, s76
	ds_read_b128 v[136:139], v199 offset:16384
	ds_read_b128 v[144:147], v199 offset:17408
	ds_read_b128 v[152:155], v199 offset:18432
	ds_read_b128 v[160:163], v199 offset:19456
	ds_read_b128 v[176:179], v199 offset:20480
	ds_read_b128 v[212:215], v199 offset:21504
	ds_read_b128 v[216:219], v199 offset:22528
	ds_read_b128 v[220:223], v199 offset:23552
	global_load_lds_dwordx4 v[232:233], off
	s_add_i32 m0, s76, 0x2000
	s_add_u32 s76, s48, 0x80000
	v_lshl_add_u64 v[234:235], s[48:49], 0, v[186:187]
	s_addc_u32 s77, s49, 0
	s_add_i32 s78, s70, s56
	global_load_lds_dwordx4 v[234:235], off
	v_lshl_add_u64 v[224:225], s[76:77], 0, v[182:183]
	s_mov_b32 m0, s78
	v_lshl_add_u64 v[236:237], s[50:51], 0, v[180:181]
	global_load_lds_dwordx4 v[224:225], off
	v_lshl_add_u64 v[224:225], s[76:77], 0, v[186:187]
	s_add_i32 m0, s78, 0x2000
	v_lshl_add_u64 v[238:239], s[50:51], 0, v[184:185]
	global_load_lds_dwordx4 v[224:225], off
	s_mov_b32 m0, s57
	s_nop 0
	global_load_lds_dwordx4 v[236:237], off
	s_mov_b32 m0, s58
	s_nop 0
	global_load_lds_dwordx4 v[238:239], off
	s_waitcnt vmcnt(24)
	s_waitcnt lgkmcnt(0)
	s_barrier
	s_setprio 1
	s_waitcnt lgkmcnt(0)
	v_mfma_f32_16x16x32_bf16 v[60:63], v[64:67], v[136:139], v[60:63]
	v_mfma_f32_16x16x32_bf16 v[52:55], v[72:75], v[136:139], v[52:55]
	v_mfma_f32_16x16x32_bf16 v[44:47], v[64:67], v[152:155], v[44:47]
	v_mfma_f32_16x16x32_bf16 v[36:39], v[72:75], v[152:155], v[36:39]
	v_mfma_f32_16x16x32_bf16 v[28:31], v[64:67], v[176:179], v[28:31]
	v_mfma_f32_16x16x32_bf16 v[20:23], v[72:75], v[176:179], v[20:23]
	v_mfma_f32_16x16x32_bf16 v[12:15], v[64:67], v[216:219], v[12:15]
	v_mfma_f32_16x16x32_bf16 v[8:11], v[72:75], v[216:219], v[8:11]
	v_mfma_f32_16x16x32_bf16 v[60:63], v[68:71], v[144:147], v[60:63]
	v_mfma_f32_16x16x32_bf16 v[52:55], v[76:79], v[144:147], v[52:55]
	v_mfma_f32_16x16x32_bf16 v[44:47], v[68:71], v[160:163], v[44:47]
	v_mfma_f32_16x16x32_bf16 v[36:39], v[76:79], v[160:163], v[36:39]
	v_mfma_f32_16x16x32_bf16 v[28:31], v[68:71], v[212:215], v[28:31]
	v_mfma_f32_16x16x32_bf16 v[20:23], v[76:79], v[212:215], v[20:23]
	v_mfma_f32_16x16x32_bf16 v[12:15], v[68:71], v[220:223], v[12:15]
	v_mfma_f32_16x16x32_bf16 v[8:11], v[76:79], v[220:223], v[8:11]
	s_setprio 0
	s_setprio 1
	v_mfma_f32_16x16x32_bf16 v[56:59], v[80:83], v[136:139], v[56:59]
	v_mfma_f32_16x16x32_bf16 v[48:51], v[88:91], v[136:139], v[48:51]
	v_mfma_f32_16x16x32_bf16 v[40:43], v[80:83], v[152:155], v[40:43]
	v_mfma_f32_16x16x32_bf16 v[32:35], v[88:91], v[152:155], v[32:35]
	v_mfma_f32_16x16x32_bf16 v[24:27], v[80:83], v[176:179], v[24:27]
	v_mfma_f32_16x16x32_bf16 v[16:19], v[88:91], v[176:179], v[16:19]
	v_mfma_f32_16x16x32_bf16 v[4:7], v[80:83], v[216:219], v[4:7]
	v_mfma_f32_16x16x32_bf16 v[0:3], v[88:91], v[216:219], v[0:3]
	v_mfma_f32_16x16x32_bf16 v[56:59], v[84:87], v[144:147], v[56:59]
	v_mfma_f32_16x16x32_bf16 v[48:51], v[92:95], v[144:147], v[48:51]
	v_mfma_f32_16x16x32_bf16 v[40:43], v[84:87], v[160:163], v[40:43]
	v_mfma_f32_16x16x32_bf16 v[32:35], v[92:95], v[160:163], v[32:35]
	v_mfma_f32_16x16x32_bf16 v[24:27], v[84:87], v[212:215], v[24:27]
	v_mfma_f32_16x16x32_bf16 v[16:19], v[92:95], v[212:215], v[16:19]
	v_mfma_f32_16x16x32_bf16 v[4:7], v[84:87], v[220:223], v[4:7]
	v_mfma_f32_16x16x32_bf16 v[0:3], v[92:95], v[220:223], v[0:3]
	s_setprio 0
	s_barrier
; #define PG8_STAGE(bufoff, gbase, voff) do { _Pragma("unroll") for (int _i = 0; _i < 2; ++_i) \
;         __builtin_amdgcn_global_load_lds((const unsigned*)((const char*)(gbase) + (voff)[_i]), (PG8_LAS unsigned*)(lds + (bufoff) + ldsw + _i * 8192), 16, 0, 0); } while (0)
; #define PG8_LDA(dst, b, h) do { _Pragma("unroll") for (int m = 0; m < 4; ++m) _Pragma("unroll") for (int k = 0; k < 2; ++k) dst[m][k] = *(const PG8_LAS bf16x8*)(lds + PG8_SA(b, h) + aoff + m * 2048 + k * 1024); } while (0)
; #define PG8_WAIT_V(n) asm volatile("s_waitcnt vmcnt(" #n ")" ::: "memory")
; #define PG8_WAIT_L(n) asm volatile("s_waitcnt lgkmcnt(" #n ")" ::: "memory")
; #define PG8_BAR __builtin_amdgcn_s_barrier()
; template <class Epi, class Sched, bool ALIGN_EPI = false, bool SP2 = false>
; __device__ __forceinline__ void gemm_phase(PG8_LAS unsigned char* lds, const Gemm g, const Sched& S, const Epi& E, const int wave_in) {
;     ...
;         for (int t = 0; t < nt; t += 2) {
;             const bool last = (t == nt - 2);
;             const char* a1 = cA + (size_t)(t + 1) * kstep;
;             const char* a2 = last ? nA : cA + (size_t)(t + 2) * kstep; const char* b2 = last ? nB : cB + (size_t)(t + 2) * kstep;
;             const char* a3 = a2 + kstep; const char* b3 = b2 + kstep;
;             if (last && has_next) S.a_ready(nxt);
;             if constexpr (SP2) {
;             PG8_LDB(B0, 0, 0); PG8_LDB(B1, 0, 1); PG8_SCHED; PG8_LDA(At, 0, 0); PG8_STAGE(PG8_SA(1, 1), a1 + hstepA, voffA);
;             PG8_WAIT_V(8); PG8_WAIT_L(0); PG8_BAR; PG8_MMA(0, 0, At, B0); PG8_MMA(0, 1, At, B1); PG8_BAR; PG8_SCHED;
;             PG8_LDA(At, 0, 1); PG8_STAGE(PG8_SB(0, 0), b2, voffB); PG8_STAGE(PG8_SB(0, 1), b2 + hstepB, voffB); PG8_STAGE(PG8_SA(0, 0), a2, voffA);
;             PG8_WAIT_V(8); PG8_WAIT_L(0); PG8_BAR; PG8_MMA(1, 0, At, B0); PG8_MMA(1, 1, At, B1); PG8_BAR; PG8_SCHED;
;             PG8_LDB(B0, 1, 0); PG8_LDB(B1, 1, 1); PG8_SCHED; PG8_LDA(At, 1, 0); PG8_STAGE(PG8_SA(0, 1), a2 + hstepA, voffA);
;             PG8_WAIT_V(8); PG8_WAIT_L(0); PG8_BAR; PG8_MMA(0, 0, At, B0); PG8_MMA(0, 1, At, B1); PG8_BAR; PG8_SCHED;
;             PG8_LDA(At, 1, 1); PG8_STAGE(PG8_SB(1, 0), b3, voffB); PG8_STAGE(PG8_SB(1, 1), b3 + hstepB, voffB); PG8_STAGE(PG8_SA(1, 0), a3, voffA);
;             PG8_WAIT_V(8); PG8_WAIT_L(0); PG8_BAR; PG8_MMA(1, 0, At, B0); PG8_MMA(1, 1, At, B1); PG8_BAR; PG8_SCHED;
	s_add_i32 s76, 0, 0x18000
	s_add_i32 s77, 0, 0x1c000
	v_add_u32_e32 v76, s76, v195
	v_add_u32_e32 v92, s77, v195
	ds_read_b128 v[64:67], v76
	ds_read_b128 v[68:71], v76 offset:1024
	ds_read_b128 v[72:75], v76 offset:2048
	ds_read_b128 v[76:79], v76 offset:3072
	ds_read_b128 v[80:83], v92
	ds_read_b128 v[84:87], v92 offset:1024
	ds_read_b128 v[88:91], v92 offset:2048
	ds_read_b128 v[92:95], v92 offset:3072
	s_add_u32 s50, s50, 0x80000
	s_addc_u32 s51, s51, 0
	s_mov_b32 m0, s59
	v_lshl_add_u64 v[152:153], s[50:51], 0, v[180:181]
	ds_read_b128 v[136:139], v199 offset:32768
	ds_read_b128 v[144:147], v199 offset:33792
	ds_read_b128 v[176:179], v199 offset:34816
	ds_read_b128 v[212:215], v199 offset:35840
	ds_read_b128 v[216:219], v199 offset:36864
	ds_read_b128 v[220:223], v199 offset:37888
	ds_read_b128 v[224:227], v199 offset:38912
	ds_read_b128 v[228:231], v199 offset:39936
	global_load_lds_dwordx4 v[152:153], off
	v_lshl_add_u64 v[152:153], s[50:51], 0, v[184:185]
	s_mov_b32 m0, s60
	s_nop 0
	global_load_lds_dwordx4 v[152:153], off
	s_waitcnt vmcnt(8)
	s_waitcnt lgkmcnt(0)
	s_barrier
	s_setprio 1
	s_waitcnt lgkmcnt(0)
	v_mfma_f32_16x16x32_bf16 v[152:155], v[64:67], v[136:139], v[172:175]
	v_mfma_f32_16x16x32_bf16 v[172:175], v[68:71], v[144:147], v[152:155]
	v_mfma_f32_16x16x32_bf16 v[152:155], v[72:75], v[136:139], v[164:167]
	v_mfma_f32_16x16x32_bf16 v[164:167], v[76:79], v[144:147], v[152:155]
	v_mfma_f32_16x16x32_bf16 v[152:155], v[64:67], v[176:179], v[156:159]
	v_mfma_f32_16x16x32_bf16 v[148:151], v[72:75], v[176:179], v[148:151]
	v_mfma_f32_16x16x32_bf16 v[140:143], v[64:67], v[216:219], v[140:143]
	v_mfma_f32_16x16x32_bf16 v[132:135], v[72:75], v[216:219], v[132:135]
	v_mfma_f32_16x16x32_bf16 v[124:127], v[64:67], v[224:227], v[124:127]
	v_mfma_f32_16x16x32_bf16 v[120:123], v[72:75], v[224:227], v[120:123]
	v_mfma_f32_16x16x32_bf16 v[156:159], v[68:71], v[212:215], v[152:155]
	v_mfma_f32_16x16x32_bf16 v[148:151], v[76:79], v[212:215], v[148:151]
	v_mfma_f32_16x16x32_bf16 v[140:143], v[68:71], v[220:223], v[140:143]
	v_mfma_f32_16x16x32_bf16 v[132:135], v[76:79], v[220:223], v[132:135]
	v_mfma_f32_16x16x32_bf16 v[124:127], v[68:71], v[228:231], v[124:127]
	v_mfma_f32_16x16x32_bf16 v[120:123], v[76:79], v[228:231], v[120:123]
	s_setprio 0
	s_setprio 1
	v_mfma_f32_16x16x32_bf16 v[96:99], v[88:91], v[136:139], v[96:99]
	v_mfma_f32_16x16x32_bf16 v[152:155], v[80:83], v[136:139], v[168:171]
	v_mfma_f32_16x16x32_bf16 v[160:163], v[92:95], v[144:147], v[96:99]
	v_mfma_f32_16x16x32_bf16 v[96:99], v[80:83], v[176:179], v[100:103]
	v_mfma_f32_16x16x32_bf16 v[168:171], v[84:87], v[144:147], v[152:155]
	v_mfma_f32_16x16x32_bf16 v[152:155], v[84:87], v[212:215], v[96:99]
	v_mfma_f32_16x16x32_bf16 v[96:99], v[88:91], v[176:179], v[104:107]
	v_mfma_f32_16x16x32_bf16 v[144:147], v[92:95], v[212:215], v[96:99]
	v_mfma_f32_16x16x32_bf16 v[96:99], v[80:83], v[216:219], v[108:111]
	v_mfma_f32_16x16x32_bf16 v[136:139], v[84:87], v[220:223], v[96:99]
	v_mfma_f32_16x16x32_bf16 v[96:99], v[88:91], v[216:219], v[128:131]
	v_mfma_f32_16x16x32_bf16 v[128:131], v[92:95], v[220:223], v[96:99]
	v_mfma_f32_16x16x32_bf16 v[96:99], v[80:83], v[224:227], v[116:119]
	v_mfma_f32_16x16x32_bf16 v[116:119], v[84:87], v[228:231], v[96:99]
	v_mfma_f32_16x16x32_bf16 v[96:99], v[88:91], v[224:227], v[112:115]
	v_mfma_f32_16x16x32_bf16 v[112:115], v[92:95], v[228:231], v[96:99]
	s_setprio 0
	s_barrier
	s_add_i32 s50, s76, s56
	v_lshl_add_u64 v[224:225], v[232:233], 0, s[20:21]
	s_mov_b32 m0, s50
	s_nop 1
	ds_read_b128 v[96:99], v199 offset:49152
	ds_read_b128 v[100:103], v199 offset:50176
	ds_read_b128 v[104:107], v199 offset:51200
	ds_read_b128 v[108:111], v199 offset:52224
	ds_read_b128 v[176:179], v199 offset:53248
	ds_read_b128 v[212:215], v199 offset:54272
	ds_read_b128 v[216:219], v199 offset:55296
	ds_read_b128 v[220:223], v199 offset:56320
	global_load_lds_dwordx4 v[224:225], off
	s_add_i32 m0, s50, 0x2000
	s_add_u32 s48, s48, 0x80080
	v_lshl_add_u64 v[224:225], v[234:235], 0, s[20:21]
	s_addc_u32 s49, s49, 0
	s_add_i32 s50, s77, s56
	global_load_lds_dwordx4 v[224:225], off
	v_lshl_add_u64 v[224:225], s[48:49], 0, v[182:183]
	s_mov_b32 m0, s50
	s_nop 0
	global_load_lds_dwordx4 v[224:225], off
	v_lshl_add_u64 v[224:225], s[48:49], 0, v[186:187]
	s_add_i32 m0, s50, 0x2000
	s_nop 0
	global_load_lds_dwordx4 v[224:225], off
	v_lshl_add_u64 v[224:225], v[236:237], 0, s[20:21]
	s_mov_b32 m0, s63
	s_nop 0
	global_load_lds_dwordx4 v[224:225], off
	v_lshl_add_u64 v[224:225], v[238:239], 0, s[20:21]
	s_mov_b32 m0, s64
	s_nop 0
	global_load_lds_dwordx4 v[224:225], off
	s_waitcnt vmcnt(8)
	s_waitcnt lgkmcnt(0)
	s_barrier
	s_setprio 1
	s_waitcnt lgkmcnt(0)
	v_mfma_f32_16x16x32_bf16 v[60:63], v[64:67], v[96:99], v[60:63]
	v_mfma_f32_16x16x32_bf16 v[52:55], v[72:75], v[96:99], v[52:55]
	v_mfma_f32_16x16x32_bf16 v[44:47], v[64:67], v[104:107], v[44:47]
	v_mfma_f32_16x16x32_bf16 v[36:39], v[72:75], v[104:107], v[36:39]
	v_mfma_f32_16x16x32_bf16 v[28:31], v[64:67], v[176:179], v[28:31]
	v_mfma_f32_16x16x32_bf16 v[20:23], v[72:75], v[176:179], v[20:23]
	v_mfma_f32_16x16x32_bf16 v[12:15], v[64:67], v[216:219], v[12:15]
	v_mfma_f32_16x16x32_bf16 v[8:11], v[72:75], v[216:219], v[8:11]
	v_mfma_f32_16x16x32_bf16 v[60:63], v[68:71], v[100:103], v[60:63]
	v_mfma_f32_16x16x32_bf16 v[52:55], v[76:79], v[100:103], v[52:55]
	v_mfma_f32_16x16x32_bf16 v[44:47], v[68:71], v[108:111], v[44:47]
	v_mfma_f32_16x16x32_bf16 v[36:39], v[76:79], v[108:111], v[36:39]
	v_mfma_f32_16x16x32_bf16 v[28:31], v[68:71], v[212:215], v[28:31]
	v_mfma_f32_16x16x32_bf16 v[20:23], v[76:79], v[212:215], v[20:23]
	v_mfma_f32_16x16x32_bf16 v[12:15], v[68:71], v[220:223], v[12:15]
	v_mfma_f32_16x16x32_bf16 v[8:11], v[76:79], v[220:223], v[8:11]
	s_setprio 0
	s_setprio 1
	v_mfma_f32_16x16x32_bf16 v[56:59], v[80:83], v[96:99], v[56:59]
	v_mfma_f32_16x16x32_bf16 v[48:51], v[88:91], v[96:99], v[48:51]
	v_mfma_f32_16x16x32_bf16 v[40:43], v[80:83], v[104:107], v[40:43]
	v_mfma_f32_16x16x32_bf16 v[32:35], v[88:91], v[104:107], v[32:35]
	v_mfma_f32_16x16x32_bf16 v[24:27], v[80:83], v[176:179], v[24:27]
	v_mfma_f32_16x16x32_bf16 v[16:19], v[88:91], v[176:179], v[16:19]
	v_mfma_f32_16x16x32_bf16 v[4:7], v[80:83], v[216:219], v[4:7]
	v_mfma_f32_16x16x32_bf16 v[0:3], v[88:91], v[216:219], v[0:3]
	v_mfma_f32_16x16x32_bf16 v[56:59], v[84:87], v[100:103], v[56:59]
	v_mfma_f32_16x16x32_bf16 v[48:51], v[92:95], v[100:103], v[48:51]
	v_mfma_f32_16x16x32_bf16 v[40:43], v[84:87], v[108:111], v[40:43]
	v_mfma_f32_16x16x32_bf16 v[32:35], v[92:95], v[108:111], v[32:35]
	v_mfma_f32_16x16x32_bf16 v[24:27], v[84:87], v[212:215], v[24:27]
	v_mfma_f32_16x16x32_bf16 v[16:19], v[92:95], v[212:215], v[16:19]
	v_mfma_f32_16x16x32_bf16 v[4:7], v[84:87], v[220:223], v[4:7]
	v_mfma_f32_16x16x32_bf16 v[0:3], v[92:95], v[220:223], v[0:3]
	s_setprio 0
	s_barrier
	s_add_i32 s75, s75, 2
	s_add_u32 s46, s46, 0x100
	s_addc_u32 s47, s47, 0
	s_add_u32 s72, s72, 0x100
	s_addc_u32 s73, s73, 0
	s_cmp_gt_u32 s75, 29
	s_cbranch_scc0 .LBB0_2577
; #define PG8_STAGE(bufoff, gbase, voff) do { _Pragma("unroll") for (int _i = 0; _i < 2; ++_i) \
;         __builtin_amdgcn_global_load_lds((const unsigned*)((const char*)(gbase) + (voff)[_i]), (PG8_LAS unsigned*)(lds + (bufoff) + ldsw + _i * 8192), 16, 0, 0); } while (0)
; #define PG8_LDA(dst, b, h) do { _Pragma("unroll") for (int m = 0; m < 4; ++m) _Pragma("unroll") for (int k = 0; k < 2; ++k) dst[m][k] = *(const PG8_LAS bf16x8*)(lds + PG8_SA(b, h) + aoff + m * 2048 + k * 1024); } while (0)
; #define PG8_LDB(dst, b, h) do { _Pragma("unroll") for (int n = 0; n < 2; ++n) _Pragma("unroll") for (int k = 0; k < 2; ++k) dst[n][k] = *(const PG8_LAS bf16x8*)(lds + PG8_SB(b, h) + boff + n * 2048 + k * 1024); } while (0)
; #define PG8_MMA(ai, bj, At, Bt) do { __builtin_amdgcn_s_setprio(1); _Pragma("unroll") for (int m = 0; m < 4; ++m) _Pragma("unroll") for (int n = 0; n < 2; ++n) _Pragma("unroll") for (int k = 0; k < 2; ++k) \
;         acc[ai][bj][m][n] = __builtin_amdgcn_mfma_f32_16x16x32_bf16(Bt[n][k], At[m][k], acc[ai][bj][m][n], 0, 0, 0); __builtin_amdgcn_s_setprio(0); } while (0)
; #define PG8_WAIT_V(n) asm volatile("s_waitcnt vmcnt(" #n ")" ::: "memory")
; #define PG8_BAR __builtin_amdgcn_s_barrier()
; template <class Epi, class Sched, bool ALIGN_EPI = false, bool SP2 = false>
; __device__ __forceinline__ void gemm_phase(PG8_LAS unsigned char* lds, const Gemm g, const Sched& S, const Epi& E, const int wave_in) {
;     ...
;         for (int t = 0; t < nt; t += 2) {
;             const bool last = (t == nt - 2);
;             const char* a1 = cA + (size_t)(t + 1) * kstep;
;             const char* a2 = last ? nA : cA + (size_t)(t + 2) * kstep; const char* b2 = last ? nB : cB + (size_t)(t + 2) * kstep;
;             const char* a3 = a2 + kstep; const char* b3 = b2 + kstep;
;             if (last && has_next) S.a_ready(nxt);
;             if constexpr (SP2) {
;             PG8_LDB(B0, 0, 0); PG8_LDB(B1, 0, 1); PG8_SCHED; PG8_LDA(At, 0, 0); PG8_STAGE(PG8_SA(1, 1), a1 + hstepA, voffA);
;             PG8_WAIT_V(8); PG8_WAIT_L(0); PG8_BAR; PG8_MMA(0, 0, At, B0); PG8_MMA(0, 1, At, B1); PG8_BAR; PG8_SCHED;
;             PG8_LDA(At, 0, 1); PG8_STAGE(PG8_SB(0, 0), b2, voffB); PG8_STAGE(PG8_SB(0, 1), b2 + hstepB, voffB); PG8_STAGE(PG8_SA(0, 0), a2, voffA);
;             PG8_WAIT_V(8); PG8_WAIT_L(0); PG8_BAR; PG8_MMA(1, 0, At, B0); PG8_MMA(1, 1, At, B1); PG8_BAR; PG8_SCHED;
.LBB0_2577:
	ds_read_b128 v[64:67], v189
	ds_read_b128 v[68:71], v189 offset:1024
	ds_read_b128 v[72:75], v189 offset:2048
	ds_read_b128 v[76:79], v189 offset:3072
	ds_read_b128 v[80:83], v197
	ds_read_b128 v[84:87], v197 offset:1024
	ds_read_b128 v[88:91], v197 offset:2048
	ds_read_b128 v[92:95], v197 offset:3072
	s_add_u32 s48, s46, 0xfff80080
	s_addc_u32 s49, s47, -1
	s_cmp_eq_u32 s75, 28
	s_cselect_b32 s51, s11, s49
	s_cselect_b32 s50, s39, s48
	s_cselect_b32 s49, s37, s73
	s_cselect_b32 s48, s45, s72
	v_lshl_add_u64 v[224:225], s[46:47], 0, v[206:207]
	s_add_i32 m0, s57, 0xc000
	ds_read_b128 v[96:99], v199
	ds_read_b128 v[100:103], v199 offset:1024
	ds_read_b128 v[104:107], v199 offset:2048
	ds_read_b128 v[108:111], v199 offset:3072
	ds_read_b128 v[176:179], v199 offset:4096
	ds_read_b128 v[212:215], v199 offset:5120
	ds_read_b128 v[216:219], v199 offset:6144
	ds_read_b128 v[220:223], v199 offset:7168
	global_load_lds_dwordx4 v[224:225], off
	v_lshl_add_u64 v[224:225], s[46:47], 0, v[208:209]
	s_add_i32 m0, s57, 0xe000
	s_nop 0
	global_load_lds_dwordx4 v[224:225], off
	s_waitcnt vmcnt(8)
	s_waitcnt lgkmcnt(0)
	s_barrier
	s_setprio 1
	s_waitcnt lgkmcnt(0)
	v_mfma_f32_16x16x32_bf16 v[172:175], v[64:67], v[96:99], v[172:175]
	v_mfma_f32_16x16x32_bf16 v[164:167], v[72:75], v[96:99], v[164:167]
	v_mfma_f32_16x16x32_bf16 v[156:159], v[64:67], v[104:107], v[156:159]
	v_mfma_f32_16x16x32_bf16 v[148:151], v[72:75], v[104:107], v[148:151]
	v_mfma_f32_16x16x32_bf16 v[140:143], v[64:67], v[176:179], v[140:143]
	v_mfma_f32_16x16x32_bf16 v[132:135], v[72:75], v[176:179], v[132:135]
	v_mfma_f32_16x16x32_bf16 v[124:127], v[64:67], v[216:219], v[124:127]
	v_mfma_f32_16x16x32_bf16 v[120:123], v[72:75], v[216:219], v[120:123]
	v_mfma_f32_16x16x32_bf16 v[172:175], v[68:71], v[100:103], v[172:175]
	v_mfma_f32_16x16x32_bf16 v[164:167], v[76:79], v[100:103], v[164:167]
	v_mfma_f32_16x16x32_bf16 v[156:159], v[68:71], v[108:111], v[156:159]
	v_mfma_f32_16x16x32_bf16 v[148:151], v[76:79], v[108:111], v[148:151]
	v_mfma_f32_16x16x32_bf16 v[140:143], v[68:71], v[212:215], v[140:143]
	v_mfma_f32_16x16x32_bf16 v[132:135], v[76:79], v[212:215], v[132:135]
	v_mfma_f32_16x16x32_bf16 v[124:127], v[68:71], v[220:223], v[124:127]
	v_mfma_f32_16x16x32_bf16 v[120:123], v[76:79], v[220:223], v[120:123]
	s_setprio 0
	s_setprio 1
	v_mfma_f32_16x16x32_bf16 v[168:171], v[80:83], v[96:99], v[168:171]
	v_mfma_f32_16x16x32_bf16 v[96:99], v[88:91], v[96:99], v[160:163]
	v_mfma_f32_16x16x32_bf16 v[168:171], v[84:87], v[100:103], v[168:171]
	v_mfma_f32_16x16x32_bf16 v[96:99], v[92:95], v[100:103], v[96:99]
	v_mfma_f32_16x16x32_bf16 v[100:103], v[80:83], v[104:107], v[152:155]
	v_mfma_f32_16x16x32_bf16 v[104:107], v[88:91], v[104:107], v[144:147]
	v_mfma_f32_16x16x32_bf16 v[128:131], v[88:91], v[176:179], v[128:131]
	v_mfma_f32_16x16x32_bf16 v[116:119], v[80:83], v[216:219], v[116:119]
	v_mfma_f32_16x16x32_bf16 v[112:115], v[88:91], v[216:219], v[112:115]
	v_mfma_f32_16x16x32_bf16 v[100:103], v[84:87], v[108:111], v[100:103]
	v_mfma_f32_16x16x32_bf16 v[104:107], v[92:95], v[108:111], v[104:107]
	v_mfma_f32_16x16x32_bf16 v[108:111], v[80:83], v[176:179], v[136:139]
	v_mfma_f32_16x16x32_bf16 v[128:131], v[92:95], v[212:215], v[128:131]
	v_mfma_f32_16x16x32_bf16 v[116:119], v[84:87], v[220:223], v[116:119]
	v_mfma_f32_16x16x32_bf16 v[112:115], v[92:95], v[220:223], v[112:115]
	v_mfma_f32_16x16x32_bf16 v[108:111], v[84:87], v[212:215], v[108:111]
	s_setprio 0
	s_barrier
	s_add_i32 s76, s69, s56
	v_lshl_add_u64 v[232:233], s[48:49], 0, v[182:183]
	s_mov_b32 m0, s76
	ds_read_b128 v[136:139], v199 offset:16384
	ds_read_b128 v[144:147], v199 offset:17408
	ds_read_b128 v[152:155], v199 offset:18432
	ds_read_b128 v[160:163], v199 offset:19456
	ds_read_b128 v[176:179], v199 offset:20480
	ds_read_b128 v[212:215], v199 offset:21504
	ds_read_b128 v[216:219], v199 offset:22528
	ds_read_b128 v[220:223], v199 offset:23552
	global_load_lds_dwordx4 v[232:233], off
	s_add_i32 m0, s76, 0x2000
	s_add_u32 s76, s48, 0x80000
	v_lshl_add_u64 v[234:235], s[48:49], 0, v[186:187]
	s_addc_u32 s77, s49, 0
	s_add_i32 s78, s70, s56
	global_load_lds_dwordx4 v[234:235], off
	v_lshl_add_u64 v[224:225], s[76:77], 0, v[182:183]
	s_mov_b32 m0, s78
	v_lshl_add_u64 v[236:237], s[50:51], 0, v[180:181]
	global_load_lds_dwordx4 v[224:225], off
	v_lshl_add_u64 v[224:225], s[76:77], 0, v[186:187]
	s_add_i32 m0, s78, 0x2000
	v_lshl_add_u64 v[238:239], s[50:51], 0, v[184:185]
	global_load_lds_dwordx4 v[224:225], off
	s_mov_b32 m0, s57
	s_nop 0
	global_load_lds_dwordx4 v[236:237], off
	s_mov_b32 m0, s58
	s_nop 0
	global_load_lds_dwordx4 v[238:239], off
	s_waitcnt vmcnt(8)
	s_waitcnt lgkmcnt(0)
	s_barrier
; #define PG8_STAGE(bufoff, gbase, voff) do { _Pragma("unroll") for (int _i = 0; _i < 2; ++_i) \
;         __builtin_amdgcn_global_load_lds((const unsigned*)((const char*)(gbase) + (voff)[_i]), (PG8_LAS unsigned*)(lds + (bufoff) + ldsw + _i * 8192), 16, 0, 0); } while (0)
; #define PG8_LDA(dst, b, h) do { _Pragma("unroll") for (int m = 0; m < 4; ++m) _Pragma("unroll") for (int k = 0; k < 2; ++k) dst[m][k] = *(const PG8_LAS bf16x8*)(lds + PG8_SA(b, h) + aoff + m * 2048 + k * 1024); } while (0)
; #define PG8_LDB(dst, b, h) do { _Pragma("unroll") for (int n = 0; n < 2; ++n) _Pragma("unroll") for (int k = 0; k < 2; ++k) dst[n][k] = *(const PG8_LAS bf16x8*)(lds + PG8_SB(b, h) + boff + n * 2048 + k * 1024); } while (0)
; #define PG8_MMA(ai, bj, At, Bt) do { __builtin_amdgcn_s_setprio(1); _Pragma("unroll") for (int m = 0; m < 4; ++m) _Pragma("unroll") for (int n = 0; n < 2; ++n) _Pragma("unroll") for (int k = 0; k < 2; ++k) \
;         acc[ai][bj][m][n] = __builtin_amdgcn_mfma_f32_16x16x32_bf16(Bt[n][k], At[m][k], acc[ai][bj][m][n], 0, 0, 0); __builtin_amdgcn_s_setprio(0); } while (0)
; #define PG8_WAIT_V(n) asm volatile("s_waitcnt vmcnt(" #n ")" ::: "memory")
; #define PG8_WAIT_L(n) asm volatile("s_waitcnt lgkmcnt(" #n ")" ::: "memory")
; #define PG8_BAR __builtin_amdgcn_s_barrier()
; #define PG8_SCHED __builtin_amdgcn_sched_barrier(0)
; template <class Epi, class Sched, bool ALIGN_EPI = false, bool SP2 = false>
; __device__ __forceinline__ void gemm_phase(PG8_LAS unsigned char* lds, const Gemm g, const Sched& S, const Epi& E, const int wave_in) {
;     ...
;             PG8_WAIT_V(8); PG8_WAIT_L(0); PG8_BAR; PG8_MMA(1, 0, At, B0); PG8_MMA(1, 1, At, B1); PG8_BAR; PG8_SCHED;
;             PG8_LDB(B0, 1, 0); PG8_LDB(B1, 1, 1); PG8_SCHED; PG8_LDA(At, 1, 0); PG8_STAGE(PG8_SA(0, 1), a2 + hstepA, voffA);
;             PG8_WAIT_V(8); PG8_WAIT_L(0); PG8_BAR; PG8_MMA(0, 0, At, B0); PG8_MMA(0, 1, At, B1); PG8_BAR; PG8_SCHED;
	s_setprio 1
	s_waitcnt lgkmcnt(0)
	v_mfma_f32_16x16x32_bf16 v[60:63], v[64:67], v[136:139], v[60:63]
	v_mfma_f32_16x16x32_bf16 v[52:55], v[72:75], v[136:139], v[52:55]
	v_mfma_f32_16x16x32_bf16 v[44:47], v[64:67], v[152:155], v[44:47]
	v_mfma_f32_16x16x32_bf16 v[36:39], v[72:75], v[152:155], v[36:39]
	v_mfma_f32_16x16x32_bf16 v[28:31], v[64:67], v[176:179], v[28:31]
	v_mfma_f32_16x16x32_bf16 v[20:23], v[72:75], v[176:179], v[20:23]
	v_mfma_f32_16x16x32_bf16 v[12:15], v[64:67], v[216:219], v[12:15]
	v_mfma_f32_16x16x32_bf16 v[8:11], v[72:75], v[216:219], v[8:11]
	v_mfma_f32_16x16x32_bf16 v[60:63], v[68:71], v[144:147], v[60:63]
	v_mfma_f32_16x16x32_bf16 v[52:55], v[76:79], v[144:147], v[52:55]
	v_mfma_f32_16x16x32_bf16 v[44:47], v[68:71], v[160:163], v[44:47]
	v_mfma_f32_16x16x32_bf16 v[36:39], v[76:79], v[160:163], v[36:39]
	v_mfma_f32_16x16x32_bf16 v[28:31], v[68:71], v[212:215], v[28:31]
	v_mfma_f32_16x16x32_bf16 v[20:23], v[76:79], v[212:215], v[20:23]
	v_mfma_f32_16x16x32_bf16 v[12:15], v[68:71], v[220:223], v[12:15]
	v_mfma_f32_16x16x32_bf16 v[8:11], v[76:79], v[220:223], v[8:11]
	s_setprio 0
	s_setprio 1
	v_mfma_f32_16x16x32_bf16 v[56:59], v[80:83], v[136:139], v[56:59]
	v_mfma_f32_16x16x32_bf16 v[48:51], v[88:91], v[136:139], v[48:51]
	v_mfma_f32_16x16x32_bf16 v[40:43], v[80:83], v[152:155], v[40:43]
	v_mfma_f32_16x16x32_bf16 v[32:35], v[88:91], v[152:155], v[32:35]
	v_mfma_f32_16x16x32_bf16 v[24:27], v[80:83], v[176:179], v[24:27]
	v_mfma_f32_16x16x32_bf16 v[16:19], v[88:91], v[176:179], v[16:19]
	v_mfma_f32_16x16x32_bf16 v[4:7], v[80:83], v[216:219], v[4:7]
	v_mfma_f32_16x16x32_bf16 v[0:3], v[88:91], v[216:219], v[0:3]
	v_mfma_f32_16x16x32_bf16 v[56:59], v[84:87], v[144:147], v[56:59]
	v_mfma_f32_16x16x32_bf16 v[48:51], v[92:95], v[144:147], v[48:51]
	v_mfma_f32_16x16x32_bf16 v[40:43], v[84:87], v[160:163], v[40:43]
	v_mfma_f32_16x16x32_bf16 v[32:35], v[92:95], v[160:163], v[32:35]
	v_mfma_f32_16x16x32_bf16 v[24:27], v[84:87], v[212:215], v[24:27]
	v_mfma_f32_16x16x32_bf16 v[16:19], v[92:95], v[212:215], v[16:19]
	v_mfma_f32_16x16x32_bf16 v[4:7], v[84:87], v[220:223], v[4:7]
	v_mfma_f32_16x16x32_bf16 v[0:3], v[92:95], v[220:223], v[0:3]
	s_setprio 0
	s_barrier
	s_add_i32 s76, 0, 0x18000
	s_add_i32 s77, 0, 0x1c000
	v_add_u32_e32 v76, s76, v195
	v_add_u32_e32 v92, s77, v195
	ds_read_b128 v[64:67], v76
	ds_read_b128 v[68:71], v76 offset:1024
	ds_read_b128 v[72:75], v76 offset:2048
	ds_read_b128 v[76:79], v76 offset:3072
	ds_read_b128 v[80:83], v92
	ds_read_b128 v[84:87], v92 offset:1024
	ds_read_b128 v[88:91], v92 offset:2048
	ds_read_b128 v[92:95], v92 offset:3072
	s_add_u32 s50, s50, 0x80000
	s_addc_u32 s51, s51, 0
	s_mov_b32 m0, s59
	v_lshl_add_u64 v[152:153], s[50:51], 0, v[180:181]
	ds_read_b128 v[136:139], v199 offset:32768
	ds_read_b128 v[144:147], v199 offset:33792
	ds_read_b128 v[176:179], v199 offset:34816
	ds_read_b128 v[212:215], v199 offset:35840
	ds_read_b128 v[216:219], v199 offset:36864
	ds_read_b128 v[220:223], v199 offset:37888
	ds_read_b128 v[224:227], v199 offset:38912
	ds_read_b128 v[228:231], v199 offset:39936
	global_load_lds_dwordx4 v[152:153], off
	v_lshl_add_u64 v[152:153], s[50:51], 0, v[184:185]
	s_mov_b32 m0, s60
	s_nop 0
	global_load_lds_dwordx4 v[152:153], off
	s_waitcnt vmcnt(8)
	s_waitcnt lgkmcnt(0)
	s_barrier
	s_setprio 1
	s_waitcnt lgkmcnt(0)
	v_mfma_f32_16x16x32_bf16 v[152:155], v[64:67], v[136:139], v[172:175]
	v_mfma_f32_16x16x32_bf16 v[172:175], v[68:71], v[144:147], v[152:155]
	v_mfma_f32_16x16x32_bf16 v[152:155], v[72:75], v[136:139], v[164:167]
	v_mfma_f32_16x16x32_bf16 v[164:167], v[76:79], v[144:147], v[152:155]
	v_mfma_f32_16x16x32_bf16 v[152:155], v[64:67], v[176:179], v[156:159]
	v_mfma_f32_16x16x32_bf16 v[148:151], v[72:75], v[176:179], v[148:151]
	v_mfma_f32_16x16x32_bf16 v[140:143], v[64:67], v[216:219], v[140:143]
	v_mfma_f32_16x16x32_bf16 v[132:135], v[72:75], v[216:219], v[132:135]
	v_mfma_f32_16x16x32_bf16 v[124:127], v[64:67], v[224:227], v[124:127]
	v_mfma_f32_16x16x32_bf16 v[120:123], v[72:75], v[224:227], v[120:123]
	v_mfma_f32_16x16x32_bf16 v[156:159], v[68:71], v[212:215], v[152:155]
	v_mfma_f32_16x16x32_bf16 v[148:151], v[76:79], v[212:215], v[148:151]
	v_mfma_f32_16x16x32_bf16 v[140:143], v[68:71], v[220:223], v[140:143]
	v_mfma_f32_16x16x32_bf16 v[132:135], v[76:79], v[220:223], v[132:135]
	v_mfma_f32_16x16x32_bf16 v[124:127], v[68:71], v[228:231], v[124:127]
	v_mfma_f32_16x16x32_bf16 v[120:123], v[76:79], v[228:231], v[120:123]
	s_setprio 0
	s_setprio 1
	v_mfma_f32_16x16x32_bf16 v[96:99], v[88:91], v[136:139], v[96:99]
	v_mfma_f32_16x16x32_bf16 v[152:155], v[80:83], v[136:139], v[168:171]
	v_mfma_f32_16x16x32_bf16 v[160:163], v[92:95], v[144:147], v[96:99]
	v_mfma_f32_16x16x32_bf16 v[96:99], v[80:83], v[176:179], v[100:103]
	v_mfma_f32_16x16x32_bf16 v[168:171], v[84:87], v[144:147], v[152:155]
	v_mfma_f32_16x16x32_bf16 v[152:155], v[84:87], v[212:215], v[96:99]
	v_mfma_f32_16x16x32_bf16 v[96:99], v[88:91], v[176:179], v[104:107]
	v_mfma_f32_16x16x32_bf16 v[144:147], v[92:95], v[212:215], v[96:99]
	v_mfma_f32_16x16x32_bf16 v[96:99], v[80:83], v[216:219], v[108:111]
	v_mfma_f32_16x16x32_bf16 v[136:139], v[84:87], v[220:223], v[96:99]
	v_mfma_f32_16x16x32_bf16 v[96:99], v[88:91], v[216:219], v[128:131]
	v_mfma_f32_16x16x32_bf16 v[128:131], v[92:95], v[220:223], v[96:99]
	v_mfma_f32_16x16x32_bf16 v[96:99], v[80:83], v[224:227], v[116:119]
	v_mfma_f32_16x16x32_bf16 v[116:119], v[84:87], v[228:231], v[96:99]
	v_mfma_f32_16x16x32_bf16 v[96:99], v[88:91], v[224:227], v[112:115]
	v_mfma_f32_16x16x32_bf16 v[112:115], v[92:95], v[228:231], v[96:99]
	s_setprio 0
	s_barrier
; #define PG8_STAGE(bufoff, gbase, voff) do { _Pragma("unroll") for (int _i = 0; _i < 2; ++_i) \
;         __builtin_amdgcn_global_load_lds((const unsigned*)((const char*)(gbase) + (voff)[_i]), (PG8_LAS unsigned*)(lds + (bufoff) + ldsw + _i * 8192), 16, 0, 0); } while (0)
; #define PG8_LDA(dst, b, h) do { _Pragma("unroll") for (int m = 0; m < 4; ++m) _Pragma("unroll") for (int k = 0; k < 2; ++k) dst[m][k] = *(const PG8_LAS bf16x8*)(lds + PG8_SA(b, h) + aoff + m * 2048 + k * 1024); } while (0)
; #define PG8_MMA(ai, bj, At, Bt) do { __builtin_amdgcn_s_setprio(1); _Pragma("unroll") for (int m = 0; m < 4; ++m) _Pragma("unroll") for (int n = 0; n < 2; ++n) _Pragma("unroll") for (int k = 0; k < 2; ++k) \
;         acc[ai][bj][m][n] = __builtin_amdgcn_mfma_f32_16x16x32_bf16(Bt[n][k], At[m][k], acc[ai][bj][m][n], 0, 0, 0); __builtin_amdgcn_s_setprio(0); } while (0)
; #define PG8_WAIT_V(n) asm volatile("s_waitcnt vmcnt(" #n ")" ::: "memory")
; #define PG8_WAIT_L(n) asm volatile("s_waitcnt lgkmcnt(" #n ")" ::: "memory")
; #define PG8_BAR __builtin_amdgcn_s_barrier()
; #define PG8_SCHED __builtin_amdgcn_sched_barrier(0)
; template <class Epi, class Sched, bool ALIGN_EPI = false, bool SP2 = false>
; __device__ __forceinline__ void gemm_phase(PG8_LAS unsigned char* lds, const Gemm g, const Sched& S, const Epi& E, const int wave_in) {
;     ...
;             PG8_LDA(At, 1, 1); PG8_STAGE(PG8_SB(1, 0), b3, voffB); PG8_STAGE(PG8_SB(1, 1), b3 + hstepB, voffB); PG8_STAGE(PG8_SA(1, 0), a3, voffA);
;             PG8_WAIT_V(8); PG8_WAIT_L(0); PG8_BAR; PG8_MMA(1, 0, At, B0); PG8_MMA(1, 1, At, B1); PG8_BAR; PG8_SCHED;
;     ...
;         }
;         if constexpr (ALIGN_EPI) { if (wr == 0) PG8_BAR; }
;         if constexpr (!Epi::AFTER_DRAIN) { E(acc, cur, wr, wc, fr, fq); S.done(cur); }
;         if (!has_next) break;
	s_add_i32 s50, s76, s56
	v_lshl_add_u64 v[224:225], v[232:233], 0, s[20:21]
	s_mov_b32 m0, s50
	s_nop 1
	ds_read_b128 v[96:99], v199 offset:49152
	ds_read_b128 v[100:103], v199 offset:50176
	ds_read_b128 v[104:107], v199 offset:51200
	ds_read_b128 v[108:111], v199 offset:52224
	ds_read_b128 v[176:179], v199 offset:53248
	ds_read_b128 v[212:215], v199 offset:54272
	ds_read_b128 v[216:219], v199 offset:55296
	ds_read_b128 v[220:223], v199 offset:56320
	global_load_lds_dwordx4 v[224:225], off
	s_add_i32 m0, s50, 0x2000
	s_add_u32 s48, s48, 0x80080
	v_lshl_add_u64 v[224:225], v[234:235], 0, s[20:21]
	s_addc_u32 s49, s49, 0
	s_add_i32 s50, s77, s56
	global_load_lds_dwordx4 v[224:225], off
	v_lshl_add_u64 v[224:225], s[48:49], 0, v[182:183]
	s_mov_b32 m0, s50
	s_nop 0
	global_load_lds_dwordx4 v[224:225], off
	v_lshl_add_u64 v[224:225], s[48:49], 0, v[186:187]
	s_add_i32 m0, s50, 0x2000
	s_nop 0
	global_load_lds_dwordx4 v[224:225], off
	v_lshl_add_u64 v[224:225], v[236:237], 0, s[20:21]
	s_mov_b32 m0, s63
	s_nop 0
	global_load_lds_dwordx4 v[224:225], off
	v_lshl_add_u64 v[224:225], v[238:239], 0, s[20:21]
	s_mov_b32 m0, s64
	s_nop 0
	global_load_lds_dwordx4 v[224:225], off
	s_waitcnt vmcnt(8)
	s_waitcnt lgkmcnt(0)
	s_barrier
	s_setprio 1
	s_waitcnt lgkmcnt(0)
	v_mfma_f32_16x16x32_bf16 v[60:63], v[64:67], v[96:99], v[60:63]
	v_mfma_f32_16x16x32_bf16 v[52:55], v[72:75], v[96:99], v[52:55]
	v_mfma_f32_16x16x32_bf16 v[44:47], v[64:67], v[104:107], v[44:47]
	v_mfma_f32_16x16x32_bf16 v[36:39], v[72:75], v[104:107], v[36:39]
	v_mfma_f32_16x16x32_bf16 v[28:31], v[64:67], v[176:179], v[28:31]
	v_mfma_f32_16x16x32_bf16 v[20:23], v[72:75], v[176:179], v[20:23]
	v_mfma_f32_16x16x32_bf16 v[12:15], v[64:67], v[216:219], v[12:15]
	v_mfma_f32_16x16x32_bf16 v[8:11], v[72:75], v[216:219], v[8:11]
	v_mfma_f32_16x16x32_bf16 v[60:63], v[68:71], v[100:103], v[60:63]
	v_mfma_f32_16x16x32_bf16 v[52:55], v[76:79], v[100:103], v[52:55]
	v_mfma_f32_16x16x32_bf16 v[44:47], v[68:71], v[108:111], v[44:47]
	v_mfma_f32_16x16x32_bf16 v[36:39], v[76:79], v[108:111], v[36:39]
	v_mfma_f32_16x16x32_bf16 v[28:31], v[68:71], v[212:215], v[28:31]
	v_mfma_f32_16x16x32_bf16 v[20:23], v[76:79], v[212:215], v[20:23]
	v_mfma_f32_16x16x32_bf16 v[12:15], v[68:71], v[220:223], v[12:15]
	v_mfma_f32_16x16x32_bf16 v[8:11], v[76:79], v[220:223], v[8:11]
	s_setprio 0
	s_setprio 1
	v_mfma_f32_16x16x32_bf16 v[56:59], v[80:83], v[96:99], v[56:59]
	v_mfma_f32_16x16x32_bf16 v[48:51], v[88:91], v[96:99], v[48:51]
	v_mfma_f32_16x16x32_bf16 v[40:43], v[80:83], v[104:107], v[40:43]
	v_mfma_f32_16x16x32_bf16 v[32:35], v[88:91], v[104:107], v[32:35]
	v_mfma_f32_16x16x32_bf16 v[24:27], v[80:83], v[176:179], v[24:27]
	v_mfma_f32_16x16x32_bf16 v[16:19], v[88:91], v[176:179], v[16:19]
	v_mfma_f32_16x16x32_bf16 v[4:7], v[80:83], v[216:219], v[4:7]
	v_mfma_f32_16x16x32_bf16 v[0:3], v[88:91], v[216:219], v[0:3]
	v_mfma_f32_16x16x32_bf16 v[56:59], v[84:87], v[100:103], v[56:59]
	v_mfma_f32_16x16x32_bf16 v[48:51], v[92:95], v[100:103], v[48:51]
	v_mfma_f32_16x16x32_bf16 v[40:43], v[84:87], v[108:111], v[40:43]
	v_mfma_f32_16x16x32_bf16 v[32:35], v[92:95], v[108:111], v[32:35]
	v_mfma_f32_16x16x32_bf16 v[24:27], v[84:87], v[212:215], v[24:27]
	v_mfma_f32_16x16x32_bf16 v[16:19], v[92:95], v[212:215], v[16:19]
	v_mfma_f32_16x16x32_bf16 v[4:7], v[84:87], v[220:223], v[4:7]
	v_mfma_f32_16x16x32_bf16 v[0:3], v[92:95], v[220:223], v[0:3]
	s_setprio 0
	s_barrier
	s_add_i32 s75, s75, 2
	s_add_u32 s46, s46, 0x100
	s_addc_u32 s47, s47, 0
	s_add_u32 s72, s72, 0x100
	s_addc_u32 s73, s73, 0
	s_cmp_gt_u32 s75, 29
	s_cbranch_scc0 .LBB0_2577
	s_mov_b32 s99, 1
	s_and_b64 vcc, exec, s[22:23]
	s_cbranch_vccz .LBB0_2580
	s_barrier

;     __host__ __device__ bool next(int i, Unit& u) const { const bool ok = StaticOrder::next(i, u); u.pm = 0; u.pn = 0; return ok; }
;     __host__ __device__ bool next(int i, Unit& u) const {
;         const long L = (long)i * G + c; if (L >= nwg) return false;
;         int wgid = (int)L; { const int q = nwg / NXCD, r = nwg % NXCD, xcd = wgid % NXCD, off = wgid / NXCD; wgid = (xcd < r ? xcd * (q + 1) : r * (q + 1) + (xcd - r) * q) + off; }
;         const int nig = WGM * nN, gid = wgid / nig, fm = gid * WGM, gsz = (nM - fm) < WGM ? (nM - fm) : WGM;
;         u.pm = fm + ((wgid % nig) % gsz); u.pn = (wgid % nig) / gsz; return true;
; template <int L> __device__ __forceinline__ void layer_body(Frame& F, const Args& args, unsigned char* const wsg, const int lo, const int hi, const XcdBarrier& bar) {
;     ...
;         if (IN(base + 7)) {
;             const int Mr = M_ALL - row_lo2;
;             pg8::Gemm g{(const pg8::bf16_t*)(wsg + WS_P) + (size_t)row_lo2 * DFF, (const pg8::bf16_t*)(wsg + WS_WT_DN), Mr, DM, DFF, DFF};
;             pg8::StaticOrder S; S.init(Mr, DM, F.G, (int)blockIdx.x);
;             typedef pg8::EpiResidT<true, !last> EpiD;
;             EpiD E{nullptr, nullptr, X16mid, X16A, args.out, (const float*)(wsg + WS_MOD) + (size_t)L * 17 * NMODC + 5 * DM, pm02, 0};
;             pg8::gemm_phase<EpiD, pg8::StaticOrder, true, true>(F.lds, g, S, E, F.wave);
.LBB0_2719:
	s_cmp_gt_i32 s52, 32
	s_cselect_b64 s[0:1], -1, 0
	s_cmp_lt_i32 s53, 33
	s_cselect_b64 s[2:3], -1, 0
	s_or_b64 s[0:1], s[0:1], s[2:3]
	s_and_b64 vcc, exec, s[0:1]
	s_cbranch_vccnz .LBB0_2798
	s_mov_b32 s99, 0
	s_cmpk_gt_i32 s73, 0x3ff
	v_mbcnt_lo_u32_b32 v8, -1, 0
	v_mbcnt_hi_u32_b32 v8, -1, v8
	s_cbranch_scc1 .LBB0_2748
	s_ashr_i32 s34, s73, 31
	s_lshr_b32 s0, s34, 29
	s_add_i32 s3, s73, s0
	s_and_b32 s0, s3, -8
	s_sub_i32 s4, s73, s0
	s_cmp_gt_i32 s4, -1
	s_cbranch_scc0 .LBB0_2723
	s_lshl_b32 s2, s4, 7
	s_ashr_i32 s3, s3, 3
	s_cbranch_execz .LBB0_2724
	s_branch .LBB0_2725

; #define PG8_STAGE(bufoff, gbase, voff) do { _Pragma("unroll") for (int _i = 0; _i < 2; ++_i) \
;         __builtin_amdgcn_global_load_lds((const unsigned*)((const char*)(gbase) + (voff)[_i]), (PG8_LAS unsigned*)(lds + (bufoff) + ldsw + _i * 8192), 16, 0, 0); } while (0)
; #define PG8_LDA(dst, b, h) do { _Pragma("unroll") for (int m = 0; m < 4; ++m) _Pragma("unroll") for (int k = 0; k < 2; ++k) dst[m][k] = *(const PG8_LAS bf16x8*)(lds + PG8_SA(b, h) + aoff + m * 2048 + k * 1024); } while (0)
; #define PG8_LDB(dst, b, h) do { _Pragma("unroll") for (int n = 0; n < 2; ++n) _Pragma("unroll") for (int k = 0; k < 2; ++k) dst[n][k] = *(const PG8_LAS bf16x8*)(lds + PG8_SB(b, h) + boff + n * 2048 + k * 1024); } while (0)
; #define PG8_MMA(ai, bj, At, Bt) do { __builtin_amdgcn_s_setprio(1); _Pragma("unroll") for (int m = 0; m < 4; ++m) _Pragma("unroll") for (int n = 0; n < 2; ++n) _Pragma("unroll") for (int k = 0; k < 2; ++k) \
;         acc[ai][bj][m][n] = __builtin_amdgcn_mfma_f32_16x16x32_bf16(Bt[n][k], At[m][k], acc[ai][bj][m][n], 0, 0, 0); __builtin_amdgcn_s_setprio(0); } while (0)
; #define PG8_BAR __builtin_amdgcn_s_barrier()
; template <class Epi, class Sched, bool ALIGN_EPI = false, bool SP2 = false>
; __device__ __forceinline__ void gemm_phase(PG8_LAS unsigned char* lds, const Gemm g, const Sched& S, const Epi& E, const int wave_in) {
;     ...
;         for (int t = 0; t < nt; t += 2) {
;             const bool last = (t == nt - 2);
;             const char* a1 = cA + (size_t)(t + 1) * kstep;
;             const char* a2 = last ? nA : cA + (size_t)(t + 2) * kstep; const char* b2 = last ? nB : cB + (size_t)(t + 2) * kstep;
;             const char* a3 = a2 + kstep; const char* b3 = b2 + kstep;
;             if (last && has_next) S.a_ready(nxt);
;             if constexpr (SP2) {
;             PG8_LDB(B0, 0, 0); PG8_LDB(B1, 0, 1); PG8_SCHED; PG8_LDA(At, 0, 0); PG8_STAGE(PG8_SA(1, 1), a1 + hstepA, voffA);
;             PG8_WAIT_V(8); PG8_WAIT_L(0); PG8_BAR; PG8_MMA(0, 0, At, B0); PG8_MMA(0, 1, At, B1); PG8_BAR; PG8_SCHED;
;     ...
; #pragma unroll
;         for (int a = 0; a < 2; ++a)
; #pragma unroll
;             for (int b = 0; b < 2; ++b)
; #pragma unroll
;                 for (int m = 0; m < 4; ++m)
; #pragma unroll
;                     for (int n = 0; n < 2; ++n) acc[a][b][m][n] = (f32x4){0.f, 0.f, 0.f, 0.f};
;         cur = nxt; cA = nA; cB = nB; ++ui;
.LBB0_2740:
	s_add_u32 s25, s28, 0x100
	v_mov_b32_e32 v0, 0
	s_addc_u32 s65, s29, 0
	s_mov_b32 s66, -2
	v_mov_b32_e32 v1, v0
	v_mov_b32_e32 v2, v0
	v_mov_b32_e32 v3, v0
	v_mov_b32_e32 v4, v0
	v_mov_b32_e32 v5, v0
	v_mov_b32_e32 v6, v0
	v_mov_b32_e32 v7, v0
	v_mov_b32_e32 v20, v0
	v_mov_b32_e32 v21, v0
	v_mov_b32_e32 v22, v0
	v_mov_b32_e32 v23, v0
	v_mov_b32_e32 v12, v0
	v_mov_b32_e32 v13, v0
	v_mov_b32_e32 v14, v0
	v_mov_b32_e32 v15, v0
	v_mov_b32_e32 v36, v0
	v_mov_b32_e32 v37, v0
	v_mov_b32_e32 v38, v0
	v_mov_b32_e32 v39, v0
	v_mov_b32_e32 v28, v0
	v_mov_b32_e32 v29, v0
	v_mov_b32_e32 v30, v0
	v_mov_b32_e32 v31, v0
	v_mov_b32_e32 v52, v0
	v_mov_b32_e32 v53, v0
	v_mov_b32_e32 v54, v0
	v_mov_b32_e32 v55, v0
	v_mov_b32_e32 v44, v0
	v_mov_b32_e32 v45, v0
	v_mov_b32_e32 v46, v0
	v_mov_b32_e32 v47, v0
	v_mov_b32_e32 v16, v0
	v_mov_b32_e32 v17, v0
	v_mov_b32_e32 v18, v0
	v_mov_b32_e32 v19, v0
	v_mov_b32_e32 v8, v0
	v_mov_b32_e32 v9, v0
	v_mov_b32_e32 v10, v0
	v_mov_b32_e32 v11, v0
	v_mov_b32_e32 v32, v0
	v_mov_b32_e32 v33, v0
	v_mov_b32_e32 v34, v0
	v_mov_b32_e32 v35, v0
	v_mov_b32_e32 v24, v0
	v_mov_b32_e32 v25, v0
	v_mov_b32_e32 v26, v0
	v_mov_b32_e32 v27, v0
	v_mov_b32_e32 v48, v0
	v_mov_b32_e32 v49, v0
	v_mov_b32_e32 v50, v0
	v_mov_b32_e32 v51, v0
	v_mov_b32_e32 v40, v0
	v_mov_b32_e32 v41, v0
	v_mov_b32_e32 v42, v0
	v_mov_b32_e32 v43, v0
	v_mov_b32_e32 v56, v0
	v_mov_b32_e32 v57, v0
	v_mov_b32_e32 v58, v0
	v_mov_b32_e32 v59, v0
	v_mov_b32_e32 v60, v0
	v_mov_b32_e32 v61, v0
	v_mov_b32_e32 v62, v0
	v_mov_b32_e32 v63, v0
	v_mov_b32_e32 v68, v0
	v_mov_b32_e32 v69, v0
	v_mov_b32_e32 v70, v0
	v_mov_b32_e32 v71, v0
	v_mov_b32_e32 v64, v0
	v_mov_b32_e32 v65, v0
	v_mov_b32_e32 v66, v0
	v_mov_b32_e32 v67, v0
	v_mov_b32_e32 v84, v0
	v_mov_b32_e32 v85, v0
	v_mov_b32_e32 v86, v0
	v_mov_b32_e32 v87, v0
	v_mov_b32_e32 v80, v0
	v_mov_b32_e32 v81, v0
	v_mov_b32_e32 v82, v0
	v_mov_b32_e32 v83, v0
	v_mov_b32_e32 v100, v0
	v_mov_b32_e32 v101, v0
	v_mov_b32_e32 v102, v0
	v_mov_b32_e32 v103, v0
	v_mov_b32_e32 v96, v0
	v_mov_b32_e32 v97, v0
	v_mov_b32_e32 v98, v0
	v_mov_b32_e32 v99, v0
	s_waitcnt vmcnt(0)
	v_mov_b32_e32 v116, v0
	v_mov_b32_e32 v117, v0
	v_mov_b32_e32 v118, v0
	v_mov_b32_e32 v119, v0
	v_mov_b32_e32 v112, v0
	v_mov_b32_e32 v113, v0
	v_mov_b32_e32 v114, v0
	v_mov_b32_e32 v115, v0
	v_mov_b32_e32 v76, v0
	v_mov_b32_e32 v77, v0
	v_mov_b32_e32 v78, v0
	v_mov_b32_e32 v79, v0
	v_mov_b32_e32 v72, v0
	v_mov_b32_e32 v73, v0
	v_mov_b32_e32 v74, v0
	v_mov_b32_e32 v75, v0
	v_mov_b32_e32 v92, v0
	v_mov_b32_e32 v93, v0
	v_mov_b32_e32 v94, v0
	v_mov_b32_e32 v95, v0
	v_mov_b32_e32 v88, v0
	v_mov_b32_e32 v89, v0
	v_mov_b32_e32 v90, v0
	v_mov_b32_e32 v91, v0
	v_mov_b32_e32 v108, v0
	v_mov_b32_e32 v109, v0
	v_mov_b32_e32 v110, v0
	v_mov_b32_e32 v111, v0
	v_mov_b32_e32 v104, v0
	v_mov_b32_e32 v105, v0
	v_mov_b32_e32 v106, v0
	v_mov_b32_e32 v107, v0
	v_mov_b32_e32 v120, v0
	v_mov_b32_e32 v121, v0
	v_mov_b32_e32 v122, v0
	v_mov_b32_e32 v123, v0
	v_mov_b32_e32 v124, v0
	v_mov_b32_e32 v125, v0
	v_mov_b32_e32 v126, v0
	v_mov_b32_e32 v127, v0
	s_cmp_lg_u32 s99, 0
	s_cbranch_scc0 .LBB0_2741
	ds_read_b128 v[128:131], v170
	ds_read_b128 v[132:135], v170 offset:1024
	ds_read_b128 v[136:139], v170 offset:2048
	ds_read_b128 v[140:143], v170 offset:3072
	ds_read_b128 v[162:165], v171
	ds_read_b128 v[174:177], v171 offset:1024
	ds_read_b128 v[178:181], v171 offset:2048
	ds_read_b128 v[182:185], v171 offset:3072
	s_add_u32 s2, s26, 0x100
	s_addc_u32 s3, s27, 0
	s_cmpk_eq_i32 s66, 0x52
	s_cselect_b32 s31, s21, s3
	s_cselect_b32 s30, s20, s2
	s_cselect_b32 s29, s23, s65
	s_cselect_b32 s28, s22, s25
	v_lshl_add_u64 v[166:167], s[26:27], 0, v[154:155]
	s_add_i32 m0, s40, 0xc000
	ds_read_b128 v[186:189], v172
	ds_read_b128 v[190:193], v172 offset:1024
	ds_read_b128 v[194:197], v172 offset:2048
	ds_read_b128 v[198:201], v172 offset:3072
	ds_read_b128 v[202:205], v172 offset:4096
	ds_read_b128 v[206:209], v172 offset:5120
	ds_read_b128 v[210:213], v172 offset:6144
	ds_read_b128 v[214:217], v172 offset:7168
	global_load_lds_dwordx4 v[166:167], off
	v_lshl_add_u64 v[166:167], s[26:27], 0, v[156:157]
	s_add_i32 m0, s40, 0xe000
	s_nop 0
	global_load_lds_dwordx4 v[166:167], off
	s_waitcnt vmcnt(40)
	s_waitcnt lgkmcnt(0)
	s_barrier
	s_setprio 1
	s_waitcnt lgkmcnt(0)
	v_mfma_f32_16x16x32_bf16 v[124:127], v[128:131], v[186:189], v[124:127]
	v_mfma_f32_16x16x32_bf16 v[120:123], v[136:139], v[186:189], v[120:123]
	v_mfma_f32_16x16x32_bf16 v[104:107], v[128:131], v[194:197], v[104:107]
	v_mfma_f32_16x16x32_bf16 v[108:111], v[136:139], v[194:197], v[108:111]
	v_mfma_f32_16x16x32_bf16 v[88:91], v[128:131], v[202:205], v[88:91]
	v_mfma_f32_16x16x32_bf16 v[92:95], v[136:139], v[202:205], v[92:95]
	v_mfma_f32_16x16x32_bf16 v[72:75], v[128:131], v[210:213], v[72:75]
	v_mfma_f32_16x16x32_bf16 v[76:79], v[136:139], v[210:213], v[76:79]
	v_mfma_f32_16x16x32_bf16 v[124:127], v[132:135], v[190:193], v[124:127]
	v_mfma_f32_16x16x32_bf16 v[120:123], v[140:143], v[190:193], v[120:123]
	v_mfma_f32_16x16x32_bf16 v[104:107], v[132:135], v[198:201], v[104:107]
	v_mfma_f32_16x16x32_bf16 v[108:111], v[140:143], v[198:201], v[108:111]
	v_mfma_f32_16x16x32_bf16 v[88:91], v[132:135], v[206:209], v[88:91]
	v_mfma_f32_16x16x32_bf16 v[92:95], v[140:143], v[206:209], v[92:95]
	v_mfma_f32_16x16x32_bf16 v[72:75], v[132:135], v[214:217], v[72:75]
	v_mfma_f32_16x16x32_bf16 v[76:79], v[140:143], v[214:217], v[76:79]
	s_setprio 0
	s_setprio 1
	v_mfma_f32_16x16x32_bf16 v[112:115], v[162:165], v[186:189], v[112:115]
	v_mfma_f32_16x16x32_bf16 v[116:119], v[178:181], v[186:189], v[116:119]
	v_mfma_f32_16x16x32_bf16 v[96:99], v[162:165], v[194:197], v[96:99]
	v_mfma_f32_16x16x32_bf16 v[100:103], v[178:181], v[194:197], v[100:103]
	v_mfma_f32_16x16x32_bf16 v[80:83], v[162:165], v[202:205], v[80:83]
	v_mfma_f32_16x16x32_bf16 v[84:87], v[178:181], v[202:205], v[84:87]
	v_mfma_f32_16x16x32_bf16 v[64:67], v[162:165], v[210:213], v[64:67]
	v_mfma_f32_16x16x32_bf16 v[68:71], v[178:181], v[210:213], v[68:71]
	v_mfma_f32_16x16x32_bf16 v[112:115], v[174:177], v[190:193], v[112:115]
	v_mfma_f32_16x16x32_bf16 v[116:119], v[182:185], v[190:193], v[116:119]
	v_mfma_f32_16x16x32_bf16 v[96:99], v[174:177], v[198:201], v[96:99]
	v_mfma_f32_16x16x32_bf16 v[100:103], v[182:185], v[198:201], v[100:103]
	v_mfma_f32_16x16x32_bf16 v[80:83], v[174:177], v[206:209], v[80:83]
	v_mfma_f32_16x16x32_bf16 v[84:87], v[182:185], v[206:209], v[84:87]
	v_mfma_f32_16x16x32_bf16 v[64:67], v[174:177], v[214:217], v[64:67]
	v_mfma_f32_16x16x32_bf16 v[68:71], v[182:185], v[214:217], v[68:71]
	s_setprio 0
	s_barrier
; #define PG8_STAGE(bufoff, gbase, voff) do { _Pragma("unroll") for (int _i = 0; _i < 2; ++_i) \
;         __builtin_amdgcn_global_load_lds((const unsigned*)((const char*)(gbase) + (voff)[_i]), (PG8_LAS unsigned*)(lds + (bufoff) + ldsw + _i * 8192), 16, 0, 0); } while (0)
; #define PG8_LDA(dst, b, h) do { _Pragma("unroll") for (int m = 0; m < 4; ++m) _Pragma("unroll") for (int k = 0; k < 2; ++k) dst[m][k] = *(const PG8_LAS bf16x8*)(lds + PG8_SA(b, h) + aoff + m * 2048 + k * 1024); } while (0)
; #define PG8_LDB(dst, b, h) do { _Pragma("unroll") for (int n = 0; n < 2; ++n) _Pragma("unroll") for (int k = 0; k < 2; ++k) dst[n][k] = *(const PG8_LAS bf16x8*)(lds + PG8_SB(b, h) + boff + n * 2048 + k * 1024); } while (0)
; #define PG8_MMA(ai, bj, At, Bt) do { __builtin_amdgcn_s_setprio(1); _Pragma("unroll") for (int m = 0; m < 4; ++m) _Pragma("unroll") for (int n = 0; n < 2; ++n) _Pragma("unroll") for (int k = 0; k < 2; ++k) \
;         acc[ai][bj][m][n] = __builtin_amdgcn_mfma_f32_16x16x32_bf16(Bt[n][k], At[m][k], acc[ai][bj][m][n], 0, 0, 0); __builtin_amdgcn_s_setprio(0); } while (0)
; #define PG8_WAIT_V(n) asm volatile("s_waitcnt vmcnt(" #n ")" ::: "memory")
; #define PG8_WAIT_L(n) asm volatile("s_waitcnt lgkmcnt(" #n ")" ::: "memory")
; #define PG8_BAR __builtin_amdgcn_s_barrier()
; #define PG8_SCHED __builtin_amdgcn_sched_barrier(0)
; template <class Epi, class Sched, bool ALIGN_EPI = false, bool SP2 = false>
; __device__ __forceinline__ void gemm_phase(PG8_LAS unsigned char* lds, const Gemm g, const Sched& S, const Epi& E, const int wave_in) {
;     ...
;             PG8_LDA(At, 0, 1); PG8_STAGE(PG8_SB(0, 0), b2, voffB); PG8_STAGE(PG8_SB(0, 1), b2 + hstepB, voffB); PG8_STAGE(PG8_SA(0, 0), a2, voffA);
;             PG8_WAIT_V(8); PG8_WAIT_L(0); PG8_BAR; PG8_MMA(1, 0, At, B0); PG8_MMA(1, 1, At, B1); PG8_BAR; PG8_SCHED;
;             PG8_LDB(B0, 1, 0); PG8_LDB(B1, 1, 1); PG8_SCHED; PG8_LDA(At, 1, 0); PG8_STAGE(PG8_SA(0, 1), a2 + hstepA, voffA);
;             PG8_WAIT_V(8); PG8_WAIT_L(0); PG8_BAR; PG8_MMA(0, 0, At, B0); PG8_MMA(0, 1, At, B1); PG8_BAR; PG8_SCHED;
	s_add_i32 s26, s50, s39
	v_lshl_add_u64 v[166:167], s[28:29], 0, v[146:147]
	s_mov_b32 m0, s26
	ds_read_b128 v[186:189], v172 offset:16384
	ds_read_b128 v[190:193], v172 offset:17408
	ds_read_b128 v[194:197], v172 offset:18432
	ds_read_b128 v[198:201], v172 offset:19456
	ds_read_b128 v[202:205], v172 offset:20480
	ds_read_b128 v[206:209], v172 offset:21504
	ds_read_b128 v[210:213], v172 offset:22528
	ds_read_b128 v[214:217], v172 offset:23552
	global_load_lds_dwordx4 v[166:167], off
	s_add_i32 m0, s26, 0x2000
	s_add_u32 s26, s28, 0x158000
	v_lshl_add_u64 v[218:219], s[28:29], 0, v[150:151]
	s_addc_u32 s27, s29, 0
	s_add_i32 s67, s51, s39
	global_load_lds_dwordx4 v[218:219], off
	v_lshl_add_u64 v[220:221], s[26:27], 0, v[146:147]
	s_mov_b32 m0, s67
	v_lshl_add_u64 v[222:223], s[30:31], 0, v[148:149]
	global_load_lds_dwordx4 v[220:221], off
	v_lshl_add_u64 v[220:221], s[26:27], 0, v[150:151]
	s_add_i32 m0, s67, 0x2000
	s_nop 0
	global_load_lds_dwordx4 v[220:221], off
	v_lshl_add_u64 v[220:221], s[30:31], 0, v[144:145]
	s_mov_b32 m0, s40
	s_nop 0
	global_load_lds_dwordx4 v[220:221], off
	s_mov_b32 m0, s41
	s_nop 0
	global_load_lds_dwordx4 v[222:223], off
	s_waitcnt vmcnt(40)
	s_waitcnt lgkmcnt(0)
	s_barrier
	s_setprio 1
	s_waitcnt lgkmcnt(0)
	v_mfma_f32_16x16x32_bf16 v[60:63], v[128:131], v[186:189], v[60:63]
	v_mfma_f32_16x16x32_bf16 v[56:59], v[136:139], v[186:189], v[56:59]
	v_mfma_f32_16x16x32_bf16 v[40:43], v[128:131], v[194:197], v[40:43]
	v_mfma_f32_16x16x32_bf16 v[48:51], v[136:139], v[194:197], v[48:51]
	v_mfma_f32_16x16x32_bf16 v[24:27], v[128:131], v[202:205], v[24:27]
	v_mfma_f32_16x16x32_bf16 v[32:35], v[136:139], v[202:205], v[32:35]
	v_mfma_f32_16x16x32_bf16 v[8:11], v[128:131], v[210:213], v[8:11]
	v_mfma_f32_16x16x32_bf16 v[16:19], v[136:139], v[210:213], v[16:19]
	v_mfma_f32_16x16x32_bf16 v[60:63], v[132:135], v[190:193], v[60:63]
	v_mfma_f32_16x16x32_bf16 v[56:59], v[140:143], v[190:193], v[56:59]
	v_mfma_f32_16x16x32_bf16 v[40:43], v[132:135], v[198:201], v[40:43]
	v_mfma_f32_16x16x32_bf16 v[48:51], v[140:143], v[198:201], v[48:51]
	v_mfma_f32_16x16x32_bf16 v[24:27], v[132:135], v[206:209], v[24:27]
	v_mfma_f32_16x16x32_bf16 v[32:35], v[140:143], v[206:209], v[32:35]
	v_mfma_f32_16x16x32_bf16 v[8:11], v[132:135], v[214:217], v[8:11]
	v_mfma_f32_16x16x32_bf16 v[16:19], v[140:143], v[214:217], v[16:19]
	s_setprio 0
	s_setprio 1
	v_mfma_f32_16x16x32_bf16 v[44:47], v[162:165], v[186:189], v[44:47]
	v_mfma_f32_16x16x32_bf16 v[52:55], v[178:181], v[186:189], v[52:55]
	v_mfma_f32_16x16x32_bf16 v[28:31], v[162:165], v[194:197], v[28:31]
	v_mfma_f32_16x16x32_bf16 v[36:39], v[178:181], v[194:197], v[36:39]
	v_mfma_f32_16x16x32_bf16 v[12:15], v[162:165], v[202:205], v[12:15]
	v_mfma_f32_16x16x32_bf16 v[20:23], v[178:181], v[202:205], v[20:23]
	v_mfma_f32_16x16x32_bf16 v[4:7], v[162:165], v[210:213], v[4:7]
	v_mfma_f32_16x16x32_bf16 v[0:3], v[178:181], v[210:213], v[0:3]
	v_mfma_f32_16x16x32_bf16 v[44:47], v[174:177], v[190:193], v[44:47]
	v_mfma_f32_16x16x32_bf16 v[52:55], v[182:185], v[190:193], v[52:55]
	v_mfma_f32_16x16x32_bf16 v[28:31], v[174:177], v[198:201], v[28:31]
	v_mfma_f32_16x16x32_bf16 v[36:39], v[182:185], v[198:201], v[36:39]
	v_mfma_f32_16x16x32_bf16 v[12:15], v[174:177], v[206:209], v[12:15]
	v_mfma_f32_16x16x32_bf16 v[20:23], v[182:185], v[206:209], v[20:23]
	v_mfma_f32_16x16x32_bf16 v[4:7], v[174:177], v[214:217], v[4:7]
	v_mfma_f32_16x16x32_bf16 v[0:3], v[182:185], v[214:217], v[0:3]
	s_setprio 0
	s_barrier
	s_add_i32 s67, 0, 0x18000
	s_add_i32 s68, 0, 0x1c000
	v_add_u32_e32 v140, s67, v168
	v_add_u32_e32 v173, s68, v168
	ds_read_b128 v[128:131], v140
	ds_read_b128 v[132:135], v140 offset:1024
	ds_read_b128 v[136:139], v140 offset:2048
	ds_read_b128 v[140:143], v140 offset:3072
	ds_read_b128 v[162:165], v173
	ds_read_b128 v[174:177], v173 offset:1024
	ds_read_b128 v[178:181], v173 offset:2048
	ds_read_b128 v[182:185], v173 offset:3072
	s_add_u32 s26, s30, 0x158000
	s_addc_u32 s27, s31, 0
	s_mov_b32 m0, s42
	v_lshl_add_u64 v[224:225], s[26:27], 0, v[144:145]
	ds_read_b128 v[186:189], v172 offset:32768
	ds_read_b128 v[190:193], v172 offset:33792
	ds_read_b128 v[194:197], v172 offset:34816
	ds_read_b128 v[198:201], v172 offset:35840
	ds_read_b128 v[202:205], v172 offset:36864
	ds_read_b128 v[206:209], v172 offset:37888
	ds_read_b128 v[210:213], v172 offset:38912
	ds_read_b128 v[214:217], v172 offset:39936
	global_load_lds_dwordx4 v[224:225], off
	v_lshl_add_u64 v[224:225], s[26:27], 0, v[148:149]
	s_mov_b32 m0, s43
	s_nop 0
	global_load_lds_dwordx4 v[224:225], off
	s_waitcnt vmcnt(8)
	s_waitcnt lgkmcnt(0)
	s_barrier
; #define PG8_STAGE(bufoff, gbase, voff) do { _Pragma("unroll") for (int _i = 0; _i < 2; ++_i) \
;         __builtin_amdgcn_global_load_lds((const unsigned*)((const char*)(gbase) + (voff)[_i]), (PG8_LAS unsigned*)(lds + (bufoff) + ldsw + _i * 8192), 16, 0, 0); } while (0)
; #define PG8_LDA(dst, b, h) do { _Pragma("unroll") for (int m = 0; m < 4; ++m) _Pragma("unroll") for (int k = 0; k < 2; ++k) dst[m][k] = *(const PG8_LAS bf16x8*)(lds + PG8_SA(b, h) + aoff + m * 2048 + k * 1024); } while (0)
; #define PG8_MMA(ai, bj, At, Bt) do { __builtin_amdgcn_s_setprio(1); _Pragma("unroll") for (int m = 0; m < 4; ++m) _Pragma("unroll") for (int n = 0; n < 2; ++n) _Pragma("unroll") for (int k = 0; k < 2; ++k) \
;         acc[ai][bj][m][n] = __builtin_amdgcn_mfma_f32_16x16x32_bf16(Bt[n][k], At[m][k], acc[ai][bj][m][n], 0, 0, 0); __builtin_amdgcn_s_setprio(0); } while (0)
; #define PG8_WAIT_V(n) asm volatile("s_waitcnt vmcnt(" #n ")" ::: "memory")
; #define PG8_WAIT_L(n) asm volatile("s_waitcnt lgkmcnt(" #n ")" ::: "memory")
; #define PG8_BAR __builtin_amdgcn_s_barrier()
; #define PG8_SCHED __builtin_amdgcn_sched_barrier(0)
; template <class Epi, class Sched, bool ALIGN_EPI = false, bool SP2 = false>
; __device__ __forceinline__ void gemm_phase(PG8_LAS unsigned char* lds, const Gemm g, const Sched& S, const Epi& E, const int wave_in) {
;     ...
;         for (int t = 0; t < nt; t += 2) {
;             const bool last = (t == nt - 2);
;             const char* a1 = cA + (size_t)(t + 1) * kstep;
;     ...
;             PG8_WAIT_V(8); PG8_WAIT_L(0); PG8_BAR; PG8_MMA(0, 0, At, B0); PG8_MMA(0, 1, At, B1); PG8_BAR; PG8_SCHED;
;             PG8_LDA(At, 1, 1); PG8_STAGE(PG8_SB(1, 0), b3, voffB); PG8_STAGE(PG8_SB(1, 1), b3 + hstepB, voffB); PG8_STAGE(PG8_SA(1, 0), a3, voffA);
;             PG8_WAIT_V(8); PG8_WAIT_L(0); PG8_BAR; PG8_MMA(1, 0, At, B0); PG8_MMA(1, 1, At, B1); PG8_BAR; PG8_SCHED;
	s_setprio 1
	s_waitcnt lgkmcnt(0)
	v_mfma_f32_16x16x32_bf16 v[124:127], v[128:131], v[186:189], v[124:127]
	v_mfma_f32_16x16x32_bf16 v[120:123], v[136:139], v[186:189], v[120:123]
	v_mfma_f32_16x16x32_bf16 v[104:107], v[128:131], v[194:197], v[104:107]
	v_mfma_f32_16x16x32_bf16 v[108:111], v[136:139], v[194:197], v[108:111]
	v_mfma_f32_16x16x32_bf16 v[88:91], v[128:131], v[202:205], v[88:91]
	v_mfma_f32_16x16x32_bf16 v[92:95], v[136:139], v[202:205], v[92:95]
	v_mfma_f32_16x16x32_bf16 v[72:75], v[128:131], v[210:213], v[72:75]
	v_mfma_f32_16x16x32_bf16 v[76:79], v[136:139], v[210:213], v[76:79]
	v_mfma_f32_16x16x32_bf16 v[124:127], v[132:135], v[190:193], v[124:127]
	v_mfma_f32_16x16x32_bf16 v[120:123], v[140:143], v[190:193], v[120:123]
	v_mfma_f32_16x16x32_bf16 v[104:107], v[132:135], v[198:201], v[104:107]
	v_mfma_f32_16x16x32_bf16 v[108:111], v[140:143], v[198:201], v[108:111]
	v_mfma_f32_16x16x32_bf16 v[88:91], v[132:135], v[206:209], v[88:91]
	v_mfma_f32_16x16x32_bf16 v[92:95], v[140:143], v[206:209], v[92:95]
	v_mfma_f32_16x16x32_bf16 v[72:75], v[132:135], v[214:217], v[72:75]
	v_mfma_f32_16x16x32_bf16 v[76:79], v[140:143], v[214:217], v[76:79]
	s_setprio 0
	s_setprio 1
	v_mfma_f32_16x16x32_bf16 v[112:115], v[162:165], v[186:189], v[112:115]
	v_mfma_f32_16x16x32_bf16 v[116:119], v[178:181], v[186:189], v[116:119]
	v_mfma_f32_16x16x32_bf16 v[96:99], v[162:165], v[194:197], v[96:99]
	v_mfma_f32_16x16x32_bf16 v[100:103], v[178:181], v[194:197], v[100:103]
	v_mfma_f32_16x16x32_bf16 v[80:83], v[162:165], v[202:205], v[80:83]
	v_mfma_f32_16x16x32_bf16 v[84:87], v[178:181], v[202:205], v[84:87]
	v_mfma_f32_16x16x32_bf16 v[64:67], v[162:165], v[210:213], v[64:67]
	v_mfma_f32_16x16x32_bf16 v[68:71], v[178:181], v[210:213], v[68:71]
	v_mfma_f32_16x16x32_bf16 v[112:115], v[174:177], v[190:193], v[112:115]
	v_mfma_f32_16x16x32_bf16 v[116:119], v[182:185], v[190:193], v[116:119]
	v_mfma_f32_16x16x32_bf16 v[96:99], v[174:177], v[198:201], v[96:99]
	v_mfma_f32_16x16x32_bf16 v[100:103], v[182:185], v[198:201], v[100:103]
	v_mfma_f32_16x16x32_bf16 v[80:83], v[174:177], v[206:209], v[80:83]
	v_mfma_f32_16x16x32_bf16 v[84:87], v[182:185], v[206:209], v[84:87]
	v_mfma_f32_16x16x32_bf16 v[64:67], v[174:177], v[214:217], v[64:67]
	v_mfma_f32_16x16x32_bf16 v[68:71], v[182:185], v[214:217], v[68:71]
	s_setprio 0
	s_barrier
	s_add_i32 s26, s67, s39
	v_lshl_add_u64 v[166:167], v[166:167], 0, s[6:7]
	s_mov_b32 m0, s26
	ds_read_b128 v[186:189], v172 offset:49152
	ds_read_b128 v[190:193], v172 offset:50176
	ds_read_b128 v[194:197], v172 offset:51200
	ds_read_b128 v[198:201], v172 offset:52224
	ds_read_b128 v[202:205], v172 offset:53248
	ds_read_b128 v[206:209], v172 offset:54272
	ds_read_b128 v[210:213], v172 offset:55296
	ds_read_b128 v[214:217], v172 offset:56320
	global_load_lds_dwordx4 v[166:167], off
	s_add_i32 m0, s26, 0x2000
	s_add_u32 s26, s28, 0x158080
	v_lshl_add_u64 v[166:167], v[218:219], 0, s[6:7]
	s_addc_u32 s27, s29, 0
	s_add_i32 s28, s68, s39
	global_load_lds_dwordx4 v[166:167], off
	v_lshl_add_u64 v[166:167], s[26:27], 0, v[146:147]
	s_mov_b32 m0, s28
	s_nop 0
	global_load_lds_dwordx4 v[166:167], off
	v_lshl_add_u64 v[166:167], s[26:27], 0, v[150:151]
	s_add_i32 m0, s28, 0x2000
	s_nop 0
	global_load_lds_dwordx4 v[166:167], off
	v_lshl_add_u64 v[166:167], v[220:221], 0, s[6:7]
	s_mov_b32 m0, s48
	s_nop 0
	global_load_lds_dwordx4 v[166:167], off
	v_lshl_add_u64 v[166:167], v[222:223], 0, s[6:7]
	s_mov_b32 m0, s49
	s_nop 0
	global_load_lds_dwordx4 v[166:167], off
	s_waitcnt vmcnt(8)
	s_waitcnt lgkmcnt(0)
	s_barrier
	s_setprio 1
	s_waitcnt lgkmcnt(0)
	v_mfma_f32_16x16x32_bf16 v[60:63], v[128:131], v[186:189], v[60:63]
	v_mfma_f32_16x16x32_bf16 v[56:59], v[136:139], v[186:189], v[56:59]
	v_mfma_f32_16x16x32_bf16 v[40:43], v[128:131], v[194:197], v[40:43]
	v_mfma_f32_16x16x32_bf16 v[48:51], v[136:139], v[194:197], v[48:51]
	v_mfma_f32_16x16x32_bf16 v[24:27], v[128:131], v[202:205], v[24:27]
	v_mfma_f32_16x16x32_bf16 v[32:35], v[136:139], v[202:205], v[32:35]
	v_mfma_f32_16x16x32_bf16 v[8:11], v[128:131], v[210:213], v[8:11]
	v_mfma_f32_16x16x32_bf16 v[16:19], v[136:139], v[210:213], v[16:19]
	v_mfma_f32_16x16x32_bf16 v[60:63], v[132:135], v[190:193], v[60:63]
	v_mfma_f32_16x16x32_bf16 v[56:59], v[140:143], v[190:193], v[56:59]
	v_mfma_f32_16x16x32_bf16 v[40:43], v[132:135], v[198:201], v[40:43]
	v_mfma_f32_16x16x32_bf16 v[48:51], v[140:143], v[198:201], v[48:51]
	v_mfma_f32_16x16x32_bf16 v[24:27], v[132:135], v[206:209], v[24:27]
	v_mfma_f32_16x16x32_bf16 v[32:35], v[140:143], v[206:209], v[32:35]
	v_mfma_f32_16x16x32_bf16 v[8:11], v[132:135], v[214:217], v[8:11]
	v_mfma_f32_16x16x32_bf16 v[16:19], v[140:143], v[214:217], v[16:19]
	s_setprio 0
	s_setprio 1
	v_mfma_f32_16x16x32_bf16 v[44:47], v[162:165], v[186:189], v[44:47]
	v_mfma_f32_16x16x32_bf16 v[52:55], v[178:181], v[186:189], v[52:55]
	v_mfma_f32_16x16x32_bf16 v[28:31], v[162:165], v[194:197], v[28:31]
	v_mfma_f32_16x16x32_bf16 v[36:39], v[178:181], v[194:197], v[36:39]
	v_mfma_f32_16x16x32_bf16 v[12:15], v[162:165], v[202:205], v[12:15]
	v_mfma_f32_16x16x32_bf16 v[20:23], v[178:181], v[202:205], v[20:23]
	v_mfma_f32_16x16x32_bf16 v[4:7], v[162:165], v[210:213], v[4:7]
	v_mfma_f32_16x16x32_bf16 v[0:3], v[178:181], v[210:213], v[0:3]
	v_mfma_f32_16x16x32_bf16 v[44:47], v[174:177], v[190:193], v[44:47]
	v_mfma_f32_16x16x32_bf16 v[52:55], v[182:185], v[190:193], v[52:55]
	v_mfma_f32_16x16x32_bf16 v[28:31], v[174:177], v[198:201], v[28:31]
	v_mfma_f32_16x16x32_bf16 v[36:39], v[182:185], v[198:201], v[36:39]
	v_mfma_f32_16x16x32_bf16 v[12:15], v[174:177], v[206:209], v[12:15]
	v_mfma_f32_16x16x32_bf16 v[20:23], v[182:185], v[206:209], v[20:23]
	v_mfma_f32_16x16x32_bf16 v[4:7], v[174:177], v[214:217], v[4:7]
	v_mfma_f32_16x16x32_bf16 v[0:3], v[182:185], v[214:217], v[0:3]
	s_setprio 0
	s_barrier
	s_add_i32 s66, s66, 2
	s_add_u32 s25, s25, 0x100
	s_addc_u32 s65, s65, 0
	s_cmpk_gt_u32 s66, 0x53
	s_mov_b64 s[26:27], s[2:3]
	s_cbranch_scc0 .LBB0_2741
; #define PG8_STAGE(bufoff, gbase, voff) do { _Pragma("unroll") for (int _i = 0; _i < 2; ++_i) \
;         __builtin_amdgcn_global_load_lds((const unsigned*)((const char*)(gbase) + (voff)[_i]), (PG8_LAS unsigned*)(lds + (bufoff) + ldsw + _i * 8192), 16, 0, 0); } while (0)
; #define PG8_LDA(dst, b, h) do { _Pragma("unroll") for (int m = 0; m < 4; ++m) _Pragma("unroll") for (int k = 0; k < 2; ++k) dst[m][k] = *(const PG8_LAS bf16x8*)(lds + PG8_SA(b, h) + aoff + m * 2048 + k * 1024); } while (0)
; #define PG8_LDB(dst, b, h) do { _Pragma("unroll") for (int n = 0; n < 2; ++n) _Pragma("unroll") for (int k = 0; k < 2; ++k) dst[n][k] = *(const PG8_LAS bf16x8*)(lds + PG8_SB(b, h) + boff + n * 2048 + k * 1024); } while (0)
; #define PG8_MMA(ai, bj, At, Bt) do { __builtin_amdgcn_s_setprio(1); _Pragma("unroll") for (int m = 0; m < 4; ++m) _Pragma("unroll") for (int n = 0; n < 2; ++n) _Pragma("unroll") for (int k = 0; k < 2; ++k) \
;         acc[ai][bj][m][n] = __builtin_amdgcn_mfma_f32_16x16x32_bf16(Bt[n][k], At[m][k], acc[ai][bj][m][n], 0, 0, 0); __builtin_amdgcn_s_setprio(0); } while (0)
; #define PG8_WAIT_V(n) asm volatile("s_waitcnt vmcnt(" #n ")" ::: "memory")
; #define PG8_WAIT_L(n) asm volatile("s_waitcnt lgkmcnt(" #n ")" ::: "memory")
; #define PG8_BAR __builtin_amdgcn_s_barrier()
; #define PG8_SCHED __builtin_amdgcn_sched_barrier(0)
; template <class Epi, class Sched, bool ALIGN_EPI = false, bool SP2 = false>
; __device__ __forceinline__ void gemm_phase(PG8_LAS unsigned char* lds, const Gemm g, const Sched& S, const Epi& E, const int wave_in) {
;     ...
;             if constexpr (SP2) {
;             PG8_LDB(B0, 0, 0); PG8_LDB(B1, 0, 1); PG8_SCHED; PG8_LDA(At, 0, 0); PG8_STAGE(PG8_SA(1, 1), a1 + hstepA, voffA);
;             PG8_WAIT_V(8); PG8_WAIT_L(0); PG8_BAR; PG8_MMA(0, 0, At, B0); PG8_MMA(0, 1, At, B1); PG8_BAR; PG8_SCHED;
;             PG8_LDA(At, 0, 1); PG8_STAGE(PG8_SB(0, 0), b2, voffB); PG8_STAGE(PG8_SB(0, 1), b2 + hstepB, voffB); PG8_STAGE(PG8_SA(0, 0), a2, voffA);
.LBB0_2741:
	ds_read_b128 v[128:131], v170
	ds_read_b128 v[132:135], v170 offset:1024
	ds_read_b128 v[136:139], v170 offset:2048
	ds_read_b128 v[140:143], v170 offset:3072
	ds_read_b128 v[162:165], v171
	ds_read_b128 v[174:177], v171 offset:1024
	ds_read_b128 v[178:181], v171 offset:2048
	ds_read_b128 v[182:185], v171 offset:3072
	s_add_u32 s2, s26, 0x100
	s_addc_u32 s3, s27, 0
	s_cmpk_eq_i32 s66, 0x52
	s_cselect_b32 s31, s21, s3
	s_cselect_b32 s30, s20, s2
	s_cselect_b32 s29, s23, s65
	s_cselect_b32 s28, s22, s25
	v_lshl_add_u64 v[166:167], s[26:27], 0, v[154:155]
	s_add_i32 m0, s40, 0xc000
	ds_read_b128 v[186:189], v172
	ds_read_b128 v[190:193], v172 offset:1024
	ds_read_b128 v[194:197], v172 offset:2048
	ds_read_b128 v[198:201], v172 offset:3072
	ds_read_b128 v[202:205], v172 offset:4096
	ds_read_b128 v[206:209], v172 offset:5120
	ds_read_b128 v[210:213], v172 offset:6144
	ds_read_b128 v[214:217], v172 offset:7168
	global_load_lds_dwordx4 v[166:167], off
	v_lshl_add_u64 v[166:167], s[26:27], 0, v[156:157]
	s_add_i32 m0, s40, 0xe000
	s_nop 0
	global_load_lds_dwordx4 v[166:167], off
	s_waitcnt vmcnt(8)
	s_waitcnt lgkmcnt(0)
	s_barrier
	s_setprio 1
	s_waitcnt lgkmcnt(0)
	v_mfma_f32_16x16x32_bf16 v[124:127], v[128:131], v[186:189], v[124:127]
	v_mfma_f32_16x16x32_bf16 v[120:123], v[136:139], v[186:189], v[120:123]
	v_mfma_f32_16x16x32_bf16 v[104:107], v[128:131], v[194:197], v[104:107]
	v_mfma_f32_16x16x32_bf16 v[108:111], v[136:139], v[194:197], v[108:111]
	v_mfma_f32_16x16x32_bf16 v[88:91], v[128:131], v[202:205], v[88:91]
	v_mfma_f32_16x16x32_bf16 v[92:95], v[136:139], v[202:205], v[92:95]
	v_mfma_f32_16x16x32_bf16 v[72:75], v[128:131], v[210:213], v[72:75]
	v_mfma_f32_16x16x32_bf16 v[76:79], v[136:139], v[210:213], v[76:79]
	v_mfma_f32_16x16x32_bf16 v[124:127], v[132:135], v[190:193], v[124:127]
	v_mfma_f32_16x16x32_bf16 v[120:123], v[140:143], v[190:193], v[120:123]
	v_mfma_f32_16x16x32_bf16 v[104:107], v[132:135], v[198:201], v[104:107]
	v_mfma_f32_16x16x32_bf16 v[108:111], v[140:143], v[198:201], v[108:111]
	v_mfma_f32_16x16x32_bf16 v[88:91], v[132:135], v[206:209], v[88:91]
	v_mfma_f32_16x16x32_bf16 v[92:95], v[140:143], v[206:209], v[92:95]
	v_mfma_f32_16x16x32_bf16 v[72:75], v[132:135], v[214:217], v[72:75]
	v_mfma_f32_16x16x32_bf16 v[76:79], v[140:143], v[214:217], v[76:79]
	s_setprio 0
	s_setprio 1
	v_mfma_f32_16x16x32_bf16 v[112:115], v[162:165], v[186:189], v[112:115]
	v_mfma_f32_16x16x32_bf16 v[116:119], v[178:181], v[186:189], v[116:119]
	v_mfma_f32_16x16x32_bf16 v[96:99], v[162:165], v[194:197], v[96:99]
	v_mfma_f32_16x16x32_bf16 v[100:103], v[178:181], v[194:197], v[100:103]
	v_mfma_f32_16x16x32_bf16 v[80:83], v[162:165], v[202:205], v[80:83]
	v_mfma_f32_16x16x32_bf16 v[84:87], v[178:181], v[202:205], v[84:87]
	v_mfma_f32_16x16x32_bf16 v[64:67], v[162:165], v[210:213], v[64:67]
	v_mfma_f32_16x16x32_bf16 v[68:71], v[178:181], v[210:213], v[68:71]
	v_mfma_f32_16x16x32_bf16 v[112:115], v[174:177], v[190:193], v[112:115]
	v_mfma_f32_16x16x32_bf16 v[116:119], v[182:185], v[190:193], v[116:119]
	v_mfma_f32_16x16x32_bf16 v[96:99], v[174:177], v[198:201], v[96:99]
	v_mfma_f32_16x16x32_bf16 v[100:103], v[182:185], v[198:201], v[100:103]
	v_mfma_f32_16x16x32_bf16 v[80:83], v[174:177], v[206:209], v[80:83]
	v_mfma_f32_16x16x32_bf16 v[84:87], v[182:185], v[206:209], v[84:87]
	v_mfma_f32_16x16x32_bf16 v[64:67], v[174:177], v[214:217], v[64:67]
	v_mfma_f32_16x16x32_bf16 v[68:71], v[182:185], v[214:217], v[68:71]
	s_setprio 0
	s_barrier
	s_add_i32 s26, s50, s39
	v_lshl_add_u64 v[166:167], s[28:29], 0, v[146:147]
	s_mov_b32 m0, s26
	ds_read_b128 v[186:189], v172 offset:16384
	ds_read_b128 v[190:193], v172 offset:17408
	ds_read_b128 v[194:197], v172 offset:18432
	ds_read_b128 v[198:201], v172 offset:19456
	ds_read_b128 v[202:205], v172 offset:20480
	ds_read_b128 v[206:209], v172 offset:21504
	ds_read_b128 v[210:213], v172 offset:22528
	ds_read_b128 v[214:217], v172 offset:23552
	global_load_lds_dwordx4 v[166:167], off
	s_add_i32 m0, s26, 0x2000
	s_add_u32 s26, s28, 0x158000
	v_lshl_add_u64 v[218:219], s[28:29], 0, v[150:151]
	s_addc_u32 s27, s29, 0
	s_add_i32 s67, s51, s39
	global_load_lds_dwordx4 v[218:219], off
	v_lshl_add_u64 v[220:221], s[26:27], 0, v[146:147]
	s_mov_b32 m0, s67
	v_lshl_add_u64 v[222:223], s[30:31], 0, v[148:149]
	global_load_lds_dwordx4 v[220:221], off
	v_lshl_add_u64 v[220:221], s[26:27], 0, v[150:151]
	s_add_i32 m0, s67, 0x2000
	s_nop 0
	global_load_lds_dwordx4 v[220:221], off
	v_lshl_add_u64 v[220:221], s[30:31], 0, v[144:145]
	s_mov_b32 m0, s40
	s_nop 0
	global_load_lds_dwordx4 v[220:221], off
	s_mov_b32 m0, s41
	s_nop 0
	global_load_lds_dwordx4 v[222:223], off
	s_waitcnt vmcnt(8)
	s_waitcnt lgkmcnt(0)
	s_barrier
; #define PG8_STAGE(bufoff, gbase, voff) do { _Pragma("unroll") for (int _i = 0; _i < 2; ++_i) \
;         __builtin_amdgcn_global_load_lds((const unsigned*)((const char*)(gbase) + (voff)[_i]), (PG8_LAS unsigned*)(lds + (bufoff) + ldsw + _i * 8192), 16, 0, 0); } while (0)
; #define PG8_LDA(dst, b, h) do { _Pragma("unroll") for (int m = 0; m < 4; ++m) _Pragma("unroll") for (int k = 0; k < 2; ++k) dst[m][k] = *(const PG8_LAS bf16x8*)(lds + PG8_SA(b, h) + aoff + m * 2048 + k * 1024); } while (0)
; #define PG8_LDB(dst, b, h) do { _Pragma("unroll") for (int n = 0; n < 2; ++n) _Pragma("unroll") for (int k = 0; k < 2; ++k) dst[n][k] = *(const PG8_LAS bf16x8*)(lds + PG8_SB(b, h) + boff + n * 2048 + k * 1024); } while (0)
; #define PG8_MMA(ai, bj, At, Bt) do { __builtin_amdgcn_s_setprio(1); _Pragma("unroll") for (int m = 0; m < 4; ++m) _Pragma("unroll") for (int n = 0; n < 2; ++n) _Pragma("unroll") for (int k = 0; k < 2; ++k) \
;         acc[ai][bj][m][n] = __builtin_amdgcn_mfma_f32_16x16x32_bf16(Bt[n][k], At[m][k], acc[ai][bj][m][n], 0, 0, 0); __builtin_amdgcn_s_setprio(0); } while (0)
; #define PG8_WAIT_V(n) asm volatile("s_waitcnt vmcnt(" #n ")" ::: "memory")
; #define PG8_WAIT_L(n) asm volatile("s_waitcnt lgkmcnt(" #n ")" ::: "memory")
; #define PG8_BAR __builtin_amdgcn_s_barrier()
; #define PG8_SCHED __builtin_amdgcn_sched_barrier(0)
; template <class Epi, class Sched, bool ALIGN_EPI = false, bool SP2 = false>
; __device__ __forceinline__ void gemm_phase(PG8_LAS unsigned char* lds, const Gemm g, const Sched& S, const Epi& E, const int wave_in) {
;     ...
;             PG8_WAIT_V(8); PG8_WAIT_L(0); PG8_BAR; PG8_MMA(1, 0, At, B0); PG8_MMA(1, 1, At, B1); PG8_BAR; PG8_SCHED;
;             PG8_LDB(B0, 1, 0); PG8_LDB(B1, 1, 1); PG8_SCHED; PG8_LDA(At, 1, 0); PG8_STAGE(PG8_SA(0, 1), a2 + hstepA, voffA);
;             PG8_WAIT_V(8); PG8_WAIT_L(0); PG8_BAR; PG8_MMA(0, 0, At, B0); PG8_MMA(0, 1, At, B1); PG8_BAR; PG8_SCHED;
	s_setprio 1
	s_waitcnt lgkmcnt(0)
	v_mfma_f32_16x16x32_bf16 v[60:63], v[128:131], v[186:189], v[60:63]
	v_mfma_f32_16x16x32_bf16 v[56:59], v[136:139], v[186:189], v[56:59]
	v_mfma_f32_16x16x32_bf16 v[40:43], v[128:131], v[194:197], v[40:43]
	v_mfma_f32_16x16x32_bf16 v[48:51], v[136:139], v[194:197], v[48:51]
	v_mfma_f32_16x16x32_bf16 v[24:27], v[128:131], v[202:205], v[24:27]
	v_mfma_f32_16x16x32_bf16 v[32:35], v[136:139], v[202:205], v[32:35]
	v_mfma_f32_16x16x32_bf16 v[8:11], v[128:131], v[210:213], v[8:11]
	v_mfma_f32_16x16x32_bf16 v[16:19], v[136:139], v[210:213], v[16:19]
	v_mfma_f32_16x16x32_bf16 v[60:63], v[132:135], v[190:193], v[60:63]
	v_mfma_f32_16x16x32_bf16 v[56:59], v[140:143], v[190:193], v[56:59]
	v_mfma_f32_16x16x32_bf16 v[40:43], v[132:135], v[198:201], v[40:43]
	v_mfma_f32_16x16x32_bf16 v[48:51], v[140:143], v[198:201], v[48:51]
	v_mfma_f32_16x16x32_bf16 v[24:27], v[132:135], v[206:209], v[24:27]
	v_mfma_f32_16x16x32_bf16 v[32:35], v[140:143], v[206:209], v[32:35]
	v_mfma_f32_16x16x32_bf16 v[8:11], v[132:135], v[214:217], v[8:11]
	v_mfma_f32_16x16x32_bf16 v[16:19], v[140:143], v[214:217], v[16:19]
	s_setprio 0
	s_setprio 1
	v_mfma_f32_16x16x32_bf16 v[44:47], v[162:165], v[186:189], v[44:47]
	v_mfma_f32_16x16x32_bf16 v[52:55], v[178:181], v[186:189], v[52:55]
	v_mfma_f32_16x16x32_bf16 v[28:31], v[162:165], v[194:197], v[28:31]
	v_mfma_f32_16x16x32_bf16 v[36:39], v[178:181], v[194:197], v[36:39]
	v_mfma_f32_16x16x32_bf16 v[12:15], v[162:165], v[202:205], v[12:15]
	v_mfma_f32_16x16x32_bf16 v[20:23], v[178:181], v[202:205], v[20:23]
	v_mfma_f32_16x16x32_bf16 v[4:7], v[162:165], v[210:213], v[4:7]
	v_mfma_f32_16x16x32_bf16 v[0:3], v[178:181], v[210:213], v[0:3]
	v_mfma_f32_16x16x32_bf16 v[44:47], v[174:177], v[190:193], v[44:47]
	v_mfma_f32_16x16x32_bf16 v[52:55], v[182:185], v[190:193], v[52:55]
	v_mfma_f32_16x16x32_bf16 v[28:31], v[174:177], v[198:201], v[28:31]
	v_mfma_f32_16x16x32_bf16 v[36:39], v[182:185], v[198:201], v[36:39]
	v_mfma_f32_16x16x32_bf16 v[12:15], v[174:177], v[206:209], v[12:15]
	v_mfma_f32_16x16x32_bf16 v[20:23], v[182:185], v[206:209], v[20:23]
	v_mfma_f32_16x16x32_bf16 v[4:7], v[174:177], v[214:217], v[4:7]
	v_mfma_f32_16x16x32_bf16 v[0:3], v[182:185], v[214:217], v[0:3]
	s_setprio 0
	s_barrier
	s_add_i32 s67, 0, 0x18000
	s_add_i32 s68, 0, 0x1c000
	v_add_u32_e32 v140, s67, v168
	v_add_u32_e32 v173, s68, v168
	ds_read_b128 v[128:131], v140
	ds_read_b128 v[132:135], v140 offset:1024
	ds_read_b128 v[136:139], v140 offset:2048
	ds_read_b128 v[140:143], v140 offset:3072
	ds_read_b128 v[162:165], v173
	ds_read_b128 v[174:177], v173 offset:1024
	ds_read_b128 v[178:181], v173 offset:2048
	ds_read_b128 v[182:185], v173 offset:3072
	s_add_u32 s26, s30, 0x158000
	s_addc_u32 s27, s31, 0
	s_mov_b32 m0, s42
	v_lshl_add_u64 v[224:225], s[26:27], 0, v[144:145]
	ds_read_b128 v[186:189], v172 offset:32768
	ds_read_b128 v[190:193], v172 offset:33792
	ds_read_b128 v[194:197], v172 offset:34816
	ds_read_b128 v[198:201], v172 offset:35840
	ds_read_b128 v[202:205], v172 offset:36864
	ds_read_b128 v[206:209], v172 offset:37888
	ds_read_b128 v[210:213], v172 offset:38912
	ds_read_b128 v[214:217], v172 offset:39936
	global_load_lds_dwordx4 v[224:225], off
	v_lshl_add_u64 v[224:225], s[26:27], 0, v[148:149]
	s_mov_b32 m0, s43
	s_nop 0
	global_load_lds_dwordx4 v[224:225], off
	s_waitcnt vmcnt(8)
	s_waitcnt lgkmcnt(0)
	s_barrier
	s_setprio 1
	s_waitcnt lgkmcnt(0)
	v_mfma_f32_16x16x32_bf16 v[124:127], v[128:131], v[186:189], v[124:127]
	v_mfma_f32_16x16x32_bf16 v[120:123], v[136:139], v[186:189], v[120:123]
	v_mfma_f32_16x16x32_bf16 v[104:107], v[128:131], v[194:197], v[104:107]
	v_mfma_f32_16x16x32_bf16 v[108:111], v[136:139], v[194:197], v[108:111]
	v_mfma_f32_16x16x32_bf16 v[88:91], v[128:131], v[202:205], v[88:91]
	v_mfma_f32_16x16x32_bf16 v[92:95], v[136:139], v[202:205], v[92:95]
	v_mfma_f32_16x16x32_bf16 v[72:75], v[128:131], v[210:213], v[72:75]
	v_mfma_f32_16x16x32_bf16 v[76:79], v[136:139], v[210:213], v[76:79]
	v_mfma_f32_16x16x32_bf16 v[124:127], v[132:135], v[190:193], v[124:127]
	v_mfma_f32_16x16x32_bf16 v[120:123], v[140:143], v[190:193], v[120:123]
	v_mfma_f32_16x16x32_bf16 v[104:107], v[132:135], v[198:201], v[104:107]
	v_mfma_f32_16x16x32_bf16 v[108:111], v[140:143], v[198:201], v[108:111]
	v_mfma_f32_16x16x32_bf16 v[88:91], v[132:135], v[206:209], v[88:91]
	v_mfma_f32_16x16x32_bf16 v[92:95], v[140:143], v[206:209], v[92:95]
	v_mfma_f32_16x16x32_bf16 v[72:75], v[132:135], v[214:217], v[72:75]
	v_mfma_f32_16x16x32_bf16 v[76:79], v[140:143], v[214:217], v[76:79]
	s_setprio 0
	s_setprio 1
	v_mfma_f32_16x16x32_bf16 v[112:115], v[162:165], v[186:189], v[112:115]
	v_mfma_f32_16x16x32_bf16 v[116:119], v[178:181], v[186:189], v[116:119]
	v_mfma_f32_16x16x32_bf16 v[96:99], v[162:165], v[194:197], v[96:99]
	v_mfma_f32_16x16x32_bf16 v[100:103], v[178:181], v[194:197], v[100:103]
	v_mfma_f32_16x16x32_bf16 v[80:83], v[162:165], v[202:205], v[80:83]
	v_mfma_f32_16x16x32_bf16 v[84:87], v[178:181], v[202:205], v[84:87]
	v_mfma_f32_16x16x32_bf16 v[64:67], v[162:165], v[210:213], v[64:67]
	v_mfma_f32_16x16x32_bf16 v[68:71], v[178:181], v[210:213], v[68:71]
	v_mfma_f32_16x16x32_bf16 v[112:115], v[174:177], v[190:193], v[112:115]
	v_mfma_f32_16x16x32_bf16 v[116:119], v[182:185], v[190:193], v[116:119]
	v_mfma_f32_16x16x32_bf16 v[96:99], v[174:177], v[198:201], v[96:99]
	v_mfma_f32_16x16x32_bf16 v[100:103], v[182:185], v[198:201], v[100:103]
	v_mfma_f32_16x16x32_bf16 v[80:83], v[174:177], v[206:209], v[80:83]
	v_mfma_f32_16x16x32_bf16 v[84:87], v[182:185], v[206:209], v[84:87]
	v_mfma_f32_16x16x32_bf16 v[64:67], v[174:177], v[214:217], v[64:67]
	v_mfma_f32_16x16x32_bf16 v[68:71], v[182:185], v[214:217], v[68:71]
	s_setprio 0
	s_barrier
; #define PG8_STAGE(bufoff, gbase, voff) do { _Pragma("unroll") for (int _i = 0; _i < 2; ++_i) \
;         __builtin_amdgcn_global_load_lds((const unsigned*)((const char*)(gbase) + (voff)[_i]), (PG8_LAS unsigned*)(lds + (bufoff) + ldsw + _i * 8192), 16, 0, 0); } while (0)
; #define PG8_LDA(dst, b, h) do { _Pragma("unroll") for (int m = 0; m < 4; ++m) _Pragma("unroll") for (int k = 0; k < 2; ++k) dst[m][k] = *(const PG8_LAS bf16x8*)(lds + PG8_SA(b, h) + aoff + m * 2048 + k * 1024); } while (0)
; #define PG8_MMA(ai, bj, At, Bt) do { __builtin_amdgcn_s_setprio(1); _Pragma("unroll") for (int m = 0; m < 4; ++m) _Pragma("unroll") for (int n = 0; n < 2; ++n) _Pragma("unroll") for (int k = 0; k < 2; ++k) \
;         acc[ai][bj][m][n] = __builtin_amdgcn_mfma_f32_16x16x32_bf16(Bt[n][k], At[m][k], acc[ai][bj][m][n], 0, 0, 0); __builtin_amdgcn_s_setprio(0); } while (0)
; #define PG8_WAIT_V(n) asm volatile("s_waitcnt vmcnt(" #n ")" ::: "memory")
; #define PG8_WAIT_L(n) asm volatile("s_waitcnt lgkmcnt(" #n ")" ::: "memory")
; #define PG8_BAR __builtin_amdgcn_s_barrier()
; #define PG8_SCHED __builtin_amdgcn_sched_barrier(0)
; template <class Epi, class Sched, bool ALIGN_EPI = false, bool SP2 = false>
; __device__ __forceinline__ void gemm_phase(PG8_LAS unsigned char* lds, const Gemm g, const Sched& S, const Epi& E, const int wave_in) {
;     ...
;             PG8_LDA(At, 1, 1); PG8_STAGE(PG8_SB(1, 0), b3, voffB); PG8_STAGE(PG8_SB(1, 1), b3 + hstepB, voffB); PG8_STAGE(PG8_SA(1, 0), a3, voffA);
;             PG8_WAIT_V(8); PG8_WAIT_L(0); PG8_BAR; PG8_MMA(1, 0, At, B0); PG8_MMA(1, 1, At, B1); PG8_BAR; PG8_SCHED;
;     ...
;         }
;         if constexpr (ALIGN_EPI) { if (wr == 0) PG8_BAR; }
;         if constexpr (!Epi::AFTER_DRAIN) { E(acc, cur, wr, wc, fr, fq); S.done(cur); }
;         if (!has_next) break;
	s_add_i32 s26, s67, s39
	v_lshl_add_u64 v[166:167], v[166:167], 0, s[6:7]
	s_mov_b32 m0, s26
	ds_read_b128 v[186:189], v172 offset:49152
	ds_read_b128 v[190:193], v172 offset:50176
	ds_read_b128 v[194:197], v172 offset:51200
	ds_read_b128 v[198:201], v172 offset:52224
	ds_read_b128 v[202:205], v172 offset:53248
	ds_read_b128 v[206:209], v172 offset:54272
	ds_read_b128 v[210:213], v172 offset:55296
	ds_read_b128 v[214:217], v172 offset:56320
	global_load_lds_dwordx4 v[166:167], off
	s_add_i32 m0, s26, 0x2000
	s_add_u32 s26, s28, 0x158080
	v_lshl_add_u64 v[166:167], v[218:219], 0, s[6:7]
	s_addc_u32 s27, s29, 0
	s_add_i32 s28, s68, s39
	global_load_lds_dwordx4 v[166:167], off
	v_lshl_add_u64 v[166:167], s[26:27], 0, v[146:147]
	s_mov_b32 m0, s28
	s_nop 0
	global_load_lds_dwordx4 v[166:167], off
	v_lshl_add_u64 v[166:167], s[26:27], 0, v[150:151]
	s_add_i32 m0, s28, 0x2000
	s_nop 0
	global_load_lds_dwordx4 v[166:167], off
	v_lshl_add_u64 v[166:167], v[220:221], 0, s[6:7]
	s_mov_b32 m0, s48
	s_nop 0
	global_load_lds_dwordx4 v[166:167], off
	v_lshl_add_u64 v[166:167], v[222:223], 0, s[6:7]
	s_mov_b32 m0, s49
	s_nop 0
	global_load_lds_dwordx4 v[166:167], off
	s_waitcnt vmcnt(8)
	s_waitcnt lgkmcnt(0)
	s_barrier
	s_setprio 1
	s_waitcnt lgkmcnt(0)
	v_mfma_f32_16x16x32_bf16 v[60:63], v[128:131], v[186:189], v[60:63]
	v_mfma_f32_16x16x32_bf16 v[56:59], v[136:139], v[186:189], v[56:59]
	v_mfma_f32_16x16x32_bf16 v[40:43], v[128:131], v[194:197], v[40:43]
	v_mfma_f32_16x16x32_bf16 v[48:51], v[136:139], v[194:197], v[48:51]
	v_mfma_f32_16x16x32_bf16 v[24:27], v[128:131], v[202:205], v[24:27]
	v_mfma_f32_16x16x32_bf16 v[32:35], v[136:139], v[202:205], v[32:35]
	v_mfma_f32_16x16x32_bf16 v[8:11], v[128:131], v[210:213], v[8:11]
	v_mfma_f32_16x16x32_bf16 v[16:19], v[136:139], v[210:213], v[16:19]
	v_mfma_f32_16x16x32_bf16 v[60:63], v[132:135], v[190:193], v[60:63]
	v_mfma_f32_16x16x32_bf16 v[56:59], v[140:143], v[190:193], v[56:59]
	v_mfma_f32_16x16x32_bf16 v[40:43], v[132:135], v[198:201], v[40:43]
	v_mfma_f32_16x16x32_bf16 v[48:51], v[140:143], v[198:201], v[48:51]
	v_mfma_f32_16x16x32_bf16 v[24:27], v[132:135], v[206:209], v[24:27]
	v_mfma_f32_16x16x32_bf16 v[32:35], v[140:143], v[206:209], v[32:35]
	v_mfma_f32_16x16x32_bf16 v[8:11], v[132:135], v[214:217], v[8:11]
	v_mfma_f32_16x16x32_bf16 v[16:19], v[140:143], v[214:217], v[16:19]
	s_setprio 0
	s_setprio 1
	v_mfma_f32_16x16x32_bf16 v[44:47], v[162:165], v[186:189], v[44:47]
	v_mfma_f32_16x16x32_bf16 v[52:55], v[178:181], v[186:189], v[52:55]
	v_mfma_f32_16x16x32_bf16 v[28:31], v[162:165], v[194:197], v[28:31]
	v_mfma_f32_16x16x32_bf16 v[36:39], v[178:181], v[194:197], v[36:39]
	v_mfma_f32_16x16x32_bf16 v[12:15], v[162:165], v[202:205], v[12:15]
	v_mfma_f32_16x16x32_bf16 v[20:23], v[178:181], v[202:205], v[20:23]
	v_mfma_f32_16x16x32_bf16 v[4:7], v[162:165], v[210:213], v[4:7]
	v_mfma_f32_16x16x32_bf16 v[0:3], v[178:181], v[210:213], v[0:3]
	v_mfma_f32_16x16x32_bf16 v[44:47], v[174:177], v[190:193], v[44:47]
	v_mfma_f32_16x16x32_bf16 v[52:55], v[182:185], v[190:193], v[52:55]
	v_mfma_f32_16x16x32_bf16 v[28:31], v[174:177], v[198:201], v[28:31]
	v_mfma_f32_16x16x32_bf16 v[36:39], v[182:185], v[198:201], v[36:39]
	v_mfma_f32_16x16x32_bf16 v[12:15], v[174:177], v[206:209], v[12:15]
	v_mfma_f32_16x16x32_bf16 v[20:23], v[182:185], v[206:209], v[20:23]
	v_mfma_f32_16x16x32_bf16 v[4:7], v[174:177], v[214:217], v[4:7]
	v_mfma_f32_16x16x32_bf16 v[0:3], v[182:185], v[214:217], v[0:3]
	s_setprio 0
	s_barrier
	s_add_i32 s66, s66, 2
	s_add_u32 s25, s25, 0x100
	s_addc_u32 s65, s65, 0
	s_cmpk_gt_u32 s66, 0x53
	s_mov_b64 s[26:27], s[2:3]
	s_cbranch_scc0 .LBB0_2741
	s_mov_b32 s99, 1
	s_and_b64 vcc, exec, s[8:9]
	s_cbranch_vccz .LBB0_2744
	s_barrier
